# remove per-phase s_setprio flips from all 14 GEMM main loops
# speedup vs baseline: 1.0304x; 1.0127x over previous
; #define PG8_STAGE(bufoff, gbase, voff) do { _Pragma("unroll") for (int _i = 0; _i < 2; ++_i) \
;         __builtin_amdgcn_global_load_lds((const unsigned*)((const char*)(gbase) + (voff)[_i]), (LAS unsigned*)(lds + (bufoff) + ldsw + _i * 8192), 16, 0, 0); } while (0)
; #define PG8_LDA(dst, b, h) do { _Pragma("unroll") for (int m = 0; m < 4; ++m) _Pragma("unroll") for (int k = 0; k < 2; ++k) dst[m][k] = *(const LAS bf16x8*)(lds + PG8_SA(b, h) + aoff + m * 2048 + k * 1024); } while (0)
; #define PG8_WAIT_V(n) asm volatile("s_waitcnt vmcnt(" #n ")" ::: "memory")
; #define PG8_WAIT_L(n) asm volatile("s_waitcnt lgkmcnt(" #n ")" ::: "memory")
; template <class Epi>
; __device__ __forceinline__ void gemm_phase(LAS unsigned char* lds, const Gemm g, const StaticOrder& S, const Epi& E) {
;     ...
;         for (int t = 0; t < nt; t += 2) {
;             const bool last = (t == nt - 2);
;             const char* a1 = cA + (size_t)(t + 1) * kstep;
;             const char* a2 = last ? nA : cA + (size_t)(t + 2) * kstep; const char* b2 = last ? nB : cB + (size_t)(t + 2) * kstep;
;             const char* a3 = a2 + kstep; const char* b3 = b2 + kstep;
;             PG8_LDB(B0, 0, 0); PG8_SCHED; PG8_LDA(At, 0, 0); PG8_STAGE(PG8_SA(1, 1), a1 + hstep, voffA);
;             PG8_WAIT_L(8); PG8_BAR; PG8_WAIT_L(0); PG8_MMA(0, 0, At, B0); PG8_BAR; PG8_SCHED;
;             PG8_LDB(B1, 0, 1); PG8_STAGE(PG8_SB(0, 0), b2, voffB0);
;             PG8_BAR; PG8_WAIT_L(0); PG8_MMA(0, 1, At, B1); PG8_BAR;
;             PG8_LDA(At, 0, 1); PG8_STAGE(PG8_SA(0, 0), a2, voffA);
;             PG8_BAR; PG8_WAIT_L(0); PG8_MMA(1, 0, At, B0); PG8_BAR; PG8_SCHED;
;             PG8_STAGE(PG8_SB(0, 1), b2, voffB1);
;             PG8_WAIT_V(6); PG8_BAR; PG8_MMA(1, 1, At, B1); PG8_BAR;
;             PG8_LDB(B0, 1, 0); PG8_SCHED; PG8_LDA(At, 1, 0); PG8_STAGE(PG8_SA(0, 1), a2 + hstep, voffA);
;             PG8_WAIT_L(8); PG8_BAR; PG8_WAIT_L(0); PG8_MMA(0, 0, At, B0); PG8_BAR; PG8_SCHED;
;             PG8_LDB(B1, 1, 1); PG8_STAGE(PG8_SB(1, 0), b3, voffB0);
;             PG8_BAR; PG8_WAIT_L(0); PG8_MMA(0, 1, At, B1); PG8_BAR;
;             PG8_LDA(At, 1, 1); PG8_STAGE(PG8_SA(1, 0), a3, voffA);
;             PG8_BAR; PG8_WAIT_L(0); PG8_MMA(1, 0, At, B0); PG8_BAR; PG8_SCHED;
;             PG8_STAGE(PG8_SB(1, 1), b3, voffB1);
;             PG8_WAIT_V(6); PG8_BAR; PG8_MMA(1, 1, At, B1); PG8_BAR;
.LBB0_107:
	ds_read_b128 v[162:165], v158
	ds_read_b128 v[166:169], v158 offset:1024
	ds_read_b128 v[170:173], v158 offset:2048
	ds_read_b128 v[174:177], v158 offset:3072
	s_add_u32 s33, s34, 0xfff80080
	s_addc_u32 s36, s35, -1
	s_cmp_eq_u32 s63, 28
	s_cselect_b32 s37, s13, s36
	s_cselect_b32 s36, s59, s33
	s_cselect_b32 s39, s11, s62
	s_cselect_b32 s38, s60, s61
	v_lshl_add_u64 v[212:213], s[34:35], 0, v[140:141]
	s_add_i32 m0, s31, 0xc000
	ds_read_b128 v[178:181], v159
	ds_read_b128 v[182:185], v159 offset:1024
	ds_read_b128 v[186:189], v159 offset:2048
	ds_read_b128 v[190:193], v159 offset:3072
	ds_read_b128 v[194:197], v159 offset:4096
	ds_read_b128 v[198:201], v159 offset:5120
	ds_read_b128 v[204:207], v159 offset:6144
	ds_read_b128 v[208:211], v159 offset:7168
	global_load_lds_dwordx4 v[212:213], off
	v_lshl_add_u64 v[212:213], s[34:35], 0, v[142:143]
	s_add_i32 m0, s31, 0xe000
	s_nop 0
	global_load_lds_dwordx4 v[212:213], off
	s_waitcnt lgkmcnt(8)
	s_barrier
	s_waitcnt lgkmcnt(0)
	s_waitcnt lgkmcnt(0)
	v_mfma_f32_16x16x32_bf16 v[124:127], v[162:165], v[178:181], v[124:127]
	v_mfma_f32_16x16x32_bf16 v[120:123], v[170:173], v[178:181], v[120:123]
	v_mfma_f32_16x16x32_bf16 v[108:111], v[162:165], v[186:189], v[108:111]
	v_mfma_f32_16x16x32_bf16 v[104:107], v[170:173], v[186:189], v[104:107]
	v_mfma_f32_16x16x32_bf16 v[92:95], v[162:165], v[194:197], v[92:95]
	v_mfma_f32_16x16x32_bf16 v[88:91], v[170:173], v[194:197], v[88:91]
	v_mfma_f32_16x16x32_bf16 v[76:79], v[162:165], v[204:207], v[76:79]
	v_mfma_f32_16x16x32_bf16 v[72:75], v[170:173], v[204:207], v[72:75]
	v_mfma_f32_16x16x32_bf16 v[124:127], v[166:169], v[182:185], v[124:127]
	v_mfma_f32_16x16x32_bf16 v[120:123], v[174:177], v[182:185], v[120:123]
	v_mfma_f32_16x16x32_bf16 v[108:111], v[166:169], v[190:193], v[108:111]
	v_mfma_f32_16x16x32_bf16 v[104:107], v[174:177], v[190:193], v[104:107]
	v_mfma_f32_16x16x32_bf16 v[92:95], v[166:169], v[198:201], v[92:95]
	v_mfma_f32_16x16x32_bf16 v[88:91], v[174:177], v[198:201], v[88:91]
	v_mfma_f32_16x16x32_bf16 v[76:79], v[166:169], v[208:211], v[76:79]
	v_mfma_f32_16x16x32_bf16 v[72:75], v[174:177], v[208:211], v[72:75]
	s_barrier
	s_add_i32 s33, s56, s44
	v_lshl_add_u64 v[228:229], s[38:39], 0, v[134:135]
	s_mov_b32 m0, s33
	ds_read_b128 v[212:215], v160
	ds_read_b128 v[216:219], v160 offset:1024
	ds_read_b128 v[220:223], v160 offset:2048
	ds_read_b128 v[224:227], v160 offset:3072
	global_load_lds_dwordx4 v[228:229], off
	v_lshl_add_u64 v[230:231], s[38:39], 0, v[128:129]
	s_add_i32 m0, s33, 0x2000
	s_nop 0
	global_load_lds_dwordx4 v[230:231], off
	s_barrier
	s_waitcnt lgkmcnt(0)
	s_waitcnt lgkmcnt(0)
	v_mfma_f32_16x16x32_bf16 v[116:119], v[212:215], v[178:181], v[116:119]
	v_mfma_f32_16x16x32_bf16 v[112:115], v[220:223], v[178:181], v[112:115]
	v_mfma_f32_16x16x32_bf16 v[100:103], v[212:215], v[186:189], v[100:103]
	v_mfma_f32_16x16x32_bf16 v[96:99], v[220:223], v[186:189], v[96:99]
	v_mfma_f32_16x16x32_bf16 v[84:87], v[212:215], v[194:197], v[84:87]
	v_mfma_f32_16x16x32_bf16 v[80:83], v[220:223], v[194:197], v[80:83]
	v_mfma_f32_16x16x32_bf16 v[68:71], v[212:215], v[204:207], v[68:71]
	v_mfma_f32_16x16x32_bf16 v[64:67], v[220:223], v[204:207], v[64:67]
	v_mfma_f32_16x16x32_bf16 v[116:119], v[216:219], v[182:185], v[116:119]
	v_mfma_f32_16x16x32_bf16 v[112:115], v[224:227], v[182:185], v[112:115]
	v_mfma_f32_16x16x32_bf16 v[100:103], v[216:219], v[190:193], v[100:103]
	v_mfma_f32_16x16x32_bf16 v[96:99], v[224:227], v[190:193], v[96:99]
	v_mfma_f32_16x16x32_bf16 v[84:87], v[216:219], v[198:201], v[84:87]
	v_mfma_f32_16x16x32_bf16 v[80:83], v[224:227], v[198:201], v[80:83]
	v_mfma_f32_16x16x32_bf16 v[68:71], v[216:219], v[208:211], v[68:71]
	v_mfma_f32_16x16x32_bf16 v[64:67], v[224:227], v[208:211], v[64:67]
	s_mov_b32 m0, s31
	v_lshl_add_u64 v[232:233], s[36:37], 0, v[138:139]
	s_barrier
	ds_read_b128 v[178:181], v159 offset:16384
	ds_read_b128 v[182:185], v159 offset:17408
	ds_read_b128 v[186:189], v159 offset:18432
	ds_read_b128 v[190:193], v159 offset:19456
	ds_read_b128 v[194:197], v159 offset:20480
	ds_read_b128 v[198:201], v159 offset:21504
	ds_read_b128 v[204:207], v159 offset:22528
	ds_read_b128 v[208:211], v159 offset:23552
	global_load_lds_dwordx4 v[232:233], off
	v_lshl_add_u64 v[234:235], s[36:37], 0, v[132:133]
	s_mov_b32 m0, s46
	s_nop 0
	global_load_lds_dwordx4 v[234:235], off
	s_barrier
	s_waitcnt lgkmcnt(0)
	s_waitcnt lgkmcnt(0)
	v_mfma_f32_16x16x32_bf16 v[60:63], v[162:165], v[178:181], v[60:63]
	v_mfma_f32_16x16x32_bf16 v[56:59], v[170:173], v[178:181], v[56:59]
	v_mfma_f32_16x16x32_bf16 v[44:47], v[162:165], v[186:189], v[44:47]
	v_mfma_f32_16x16x32_bf16 v[40:43], v[170:173], v[186:189], v[40:43]
	v_mfma_f32_16x16x32_bf16 v[28:31], v[162:165], v[194:197], v[28:31]
	v_mfma_f32_16x16x32_bf16 v[24:27], v[170:173], v[194:197], v[24:27]
	v_mfma_f32_16x16x32_bf16 v[12:15], v[162:165], v[204:207], v[12:15]
	v_mfma_f32_16x16x32_bf16 v[8:11], v[170:173], v[204:207], v[8:11]
	v_mfma_f32_16x16x32_bf16 v[60:63], v[166:169], v[182:185], v[60:63]
	v_mfma_f32_16x16x32_bf16 v[56:59], v[174:177], v[182:185], v[56:59]
	v_mfma_f32_16x16x32_bf16 v[44:47], v[166:169], v[190:193], v[44:47]
	v_mfma_f32_16x16x32_bf16 v[40:43], v[174:177], v[190:193], v[40:43]
	v_mfma_f32_16x16x32_bf16 v[28:31], v[166:169], v[198:201], v[28:31]
	v_mfma_f32_16x16x32_bf16 v[24:27], v[174:177], v[198:201], v[24:27]
	v_mfma_f32_16x16x32_bf16 v[12:15], v[166:169], v[208:211], v[12:15]
	v_mfma_f32_16x16x32_bf16 v[8:11], v[174:177], v[208:211], v[8:11]
	s_barrier
; #define PG8_STAGE(bufoff, gbase, voff) do { _Pragma("unroll") for (int _i = 0; _i < 2; ++_i) \
;         __builtin_amdgcn_global_load_lds((const unsigned*)((const char*)(gbase) + (voff)[_i]), (LAS unsigned*)(lds + (bufoff) + ldsw + _i * 8192), 16, 0, 0); } while (0)
; #define PG8_LDA(dst, b, h) do { _Pragma("unroll") for (int m = 0; m < 4; ++m) _Pragma("unroll") for (int k = 0; k < 2; ++k) dst[m][k] = *(const LAS bf16x8*)(lds + PG8_SA(b, h) + aoff + m * 2048 + k * 1024); } while (0)
; #define PG8_LDB(dst, b, h) do { _Pragma("unroll") for (int n = 0; n < 2; ++n) _Pragma("unroll") for (int k = 0; k < 2; ++k) dst[n][k] = *(const LAS bf16x8*)(lds + PG8_SB(b, h) + boff + n * 2048 + k * 1024); } while (0)
; #define PG8_MMA(ai, bj, At, Bt) do { __builtin_amdgcn_s_setprio(1); _Pragma("unroll") for (int m = 0; m < 4; ++m) _Pragma("unroll") for (int n = 0; n < 2; ++n) _Pragma("unroll") for (int k = 0; k < 2; ++k) \
;         acc[ai][bj][m][n] = __builtin_amdgcn_mfma_f32_16x16x32_bf16(Bt[n][k], At[m][k], acc[ai][bj][m][n], 0, 0, 0); __builtin_amdgcn_s_setprio(0); } while (0)
; #define PG8_WAIT_V(n) asm volatile("s_waitcnt vmcnt(" #n ")" ::: "memory")
; #define PG8_WAIT_L(n) asm volatile("s_waitcnt lgkmcnt(" #n ")" ::: "memory")
; #define PG8_BAR __builtin_amdgcn_s_barrier()
; #define PG8_SCHED __builtin_amdgcn_sched_barrier(0)
; template <class Epi>
; __device__ __forceinline__ void gemm_phase(LAS unsigned char* lds, const Gemm g, const StaticOrder& S, const Epi& E) {
;     ...
;             PG8_STAGE(PG8_SB(0, 1), b2, voffB1);
;             PG8_WAIT_V(6); PG8_BAR; PG8_MMA(1, 1, At, B1); PG8_BAR;
;             PG8_LDB(B0, 1, 0); PG8_SCHED; PG8_LDA(At, 1, 0); PG8_STAGE(PG8_SA(0, 1), a2 + hstep, voffA);
;             PG8_WAIT_L(8); PG8_BAR; PG8_WAIT_L(0); PG8_MMA(0, 0, At, B0); PG8_BAR; PG8_SCHED;
;             PG8_LDB(B1, 1, 1); PG8_STAGE(PG8_SB(1, 0), b3, voffB0);
;             PG8_BAR; PG8_WAIT_L(0); PG8_MMA(0, 1, At, B1); PG8_BAR;
;             PG8_LDA(At, 1, 1); PG8_STAGE(PG8_SA(1, 0), a3, voffA);
;             PG8_BAR; PG8_WAIT_L(0); PG8_MMA(1, 0, At, B0); PG8_BAR; PG8_SCHED;
	s_add_i32 s33, s57, s44
	v_lshl_add_u64 v[236:237], s[38:39], 0, v[136:137]
	s_mov_b32 m0, s33
	v_lshl_add_u64 v[238:239], s[38:39], 0, v[130:131]
	global_load_lds_dwordx4 v[236:237], off
	s_add_i32 m0, s33, 0x2000
	s_nop 0
	global_load_lds_dwordx4 v[238:239], off
	s_waitcnt vmcnt(6)
	s_barrier
	v_mfma_f32_16x16x32_bf16 v[52:55], v[212:215], v[178:181], v[52:55]
	v_mfma_f32_16x16x32_bf16 v[48:51], v[220:223], v[178:181], v[48:51]
	v_mfma_f32_16x16x32_bf16 v[36:39], v[212:215], v[186:189], v[36:39]
	v_mfma_f32_16x16x32_bf16 v[32:35], v[220:223], v[186:189], v[32:35]
	v_mfma_f32_16x16x32_bf16 v[20:23], v[212:215], v[194:197], v[20:23]
	v_mfma_f32_16x16x32_bf16 v[16:19], v[220:223], v[194:197], v[16:19]
	v_mfma_f32_16x16x32_bf16 v[4:7], v[212:215], v[204:207], v[4:7]
	v_mfma_f32_16x16x32_bf16 v[0:3], v[220:223], v[204:207], v[0:3]
	v_mfma_f32_16x16x32_bf16 v[52:55], v[216:219], v[182:185], v[52:55]
	v_mfma_f32_16x16x32_bf16 v[48:51], v[224:227], v[182:185], v[48:51]
	v_mfma_f32_16x16x32_bf16 v[36:39], v[216:219], v[190:193], v[36:39]
	v_mfma_f32_16x16x32_bf16 v[32:35], v[224:227], v[190:193], v[32:35]
	v_mfma_f32_16x16x32_bf16 v[20:23], v[216:219], v[198:201], v[20:23]
	v_mfma_f32_16x16x32_bf16 v[16:19], v[224:227], v[198:201], v[16:19]
	v_mfma_f32_16x16x32_bf16 v[4:7], v[216:219], v[208:211], v[4:7]
	v_mfma_f32_16x16x32_bf16 v[0:3], v[224:227], v[208:211], v[0:3]
	s_add_i32 s33, 0, 0x18000
	v_add_u32_e32 v161, s33, v148
	s_barrier
	ds_read_b128 v[162:165], v161
	ds_read_b128 v[166:169], v161 offset:1024
	ds_read_b128 v[170:173], v161 offset:2048
	ds_read_b128 v[174:177], v161 offset:3072
	s_add_u32 s36, s36, 0x80000
	s_addc_u32 s37, s37, 0
	s_mov_b32 m0, s47
	v_lshl_add_u64 v[212:213], s[36:37], 0, v[138:139]
	ds_read_b128 v[178:181], v159 offset:32768
	ds_read_b128 v[182:185], v159 offset:33792
	ds_read_b128 v[186:189], v159 offset:34816
	ds_read_b128 v[190:193], v159 offset:35840
	ds_read_b128 v[194:197], v159 offset:36864
	ds_read_b128 v[198:201], v159 offset:37888
	ds_read_b128 v[204:207], v159 offset:38912
	ds_read_b128 v[208:211], v159 offset:39936
	global_load_lds_dwordx4 v[212:213], off
	v_lshl_add_u64 v[212:213], s[36:37], 0, v[132:133]
	s_mov_b32 m0, s48
	s_nop 0
	global_load_lds_dwordx4 v[212:213], off
	s_waitcnt lgkmcnt(8)
	s_barrier
	s_waitcnt lgkmcnt(0)
	s_waitcnt lgkmcnt(0)
	v_mfma_f32_16x16x32_bf16 v[124:127], v[162:165], v[178:181], v[124:127]
	v_mfma_f32_16x16x32_bf16 v[120:123], v[170:173], v[178:181], v[120:123]
	v_mfma_f32_16x16x32_bf16 v[108:111], v[162:165], v[186:189], v[108:111]
	v_mfma_f32_16x16x32_bf16 v[104:107], v[170:173], v[186:189], v[104:107]
	v_mfma_f32_16x16x32_bf16 v[92:95], v[162:165], v[194:197], v[92:95]
	v_mfma_f32_16x16x32_bf16 v[88:91], v[170:173], v[194:197], v[88:91]
	v_mfma_f32_16x16x32_bf16 v[76:79], v[162:165], v[204:207], v[76:79]
	v_mfma_f32_16x16x32_bf16 v[72:75], v[170:173], v[204:207], v[72:75]
	v_mfma_f32_16x16x32_bf16 v[124:127], v[166:169], v[182:185], v[124:127]
	v_mfma_f32_16x16x32_bf16 v[120:123], v[174:177], v[182:185], v[120:123]
	v_mfma_f32_16x16x32_bf16 v[108:111], v[166:169], v[190:193], v[108:111]
	v_mfma_f32_16x16x32_bf16 v[104:107], v[174:177], v[190:193], v[104:107]
	v_mfma_f32_16x16x32_bf16 v[92:95], v[166:169], v[198:201], v[92:95]
	v_mfma_f32_16x16x32_bf16 v[88:91], v[174:177], v[198:201], v[88:91]
	v_mfma_f32_16x16x32_bf16 v[76:79], v[166:169], v[208:211], v[76:79]
	v_mfma_f32_16x16x32_bf16 v[72:75], v[174:177], v[208:211], v[72:75]
	s_barrier
	s_add_i32 s36, 0, 0x1c000
	s_add_i32 s33, s33, s44
	v_add_u32_e32 v161, s36, v148
	v_lshl_add_u64 v[228:229], v[228:229], 0, s[8:9]
	s_mov_b32 m0, s33
	ds_read_b128 v[212:215], v161
	ds_read_b128 v[216:219], v161 offset:1024
	ds_read_b128 v[220:223], v161 offset:2048
	ds_read_b128 v[224:227], v161 offset:3072
	global_load_lds_dwordx4 v[228:229], off
	v_lshl_add_u64 v[228:229], v[230:231], 0, s[8:9]
	s_add_i32 m0, s33, 0x2000
	s_nop 0
	global_load_lds_dwordx4 v[228:229], off
	s_barrier
	s_waitcnt lgkmcnt(0)
	s_waitcnt lgkmcnt(0)
	v_mfma_f32_16x16x32_bf16 v[116:119], v[212:215], v[178:181], v[116:119]
	v_mfma_f32_16x16x32_bf16 v[112:115], v[220:223], v[178:181], v[112:115]
	v_mfma_f32_16x16x32_bf16 v[100:103], v[212:215], v[186:189], v[100:103]
	v_mfma_f32_16x16x32_bf16 v[96:99], v[220:223], v[186:189], v[96:99]
	v_mfma_f32_16x16x32_bf16 v[84:87], v[212:215], v[194:197], v[84:87]
	v_mfma_f32_16x16x32_bf16 v[80:83], v[220:223], v[194:197], v[80:83]
	v_mfma_f32_16x16x32_bf16 v[68:71], v[212:215], v[204:207], v[68:71]
	v_mfma_f32_16x16x32_bf16 v[64:67], v[220:223], v[204:207], v[64:67]
	v_mfma_f32_16x16x32_bf16 v[116:119], v[216:219], v[182:185], v[116:119]
	v_mfma_f32_16x16x32_bf16 v[112:115], v[224:227], v[182:185], v[112:115]
	v_mfma_f32_16x16x32_bf16 v[100:103], v[216:219], v[190:193], v[100:103]
	v_mfma_f32_16x16x32_bf16 v[96:99], v[224:227], v[190:193], v[96:99]
	v_mfma_f32_16x16x32_bf16 v[84:87], v[216:219], v[198:201], v[84:87]
	v_mfma_f32_16x16x32_bf16 v[80:83], v[224:227], v[198:201], v[80:83]
	v_mfma_f32_16x16x32_bf16 v[68:71], v[216:219], v[208:211], v[68:71]
	v_mfma_f32_16x16x32_bf16 v[64:67], v[224:227], v[208:211], v[64:67]
	s_mov_b32 m0, s51
	v_lshl_add_u64 v[228:229], v[232:233], 0, s[8:9]
	s_barrier
	ds_read_b128 v[178:181], v159 offset:49152
	ds_read_b128 v[182:185], v159 offset:50176
	ds_read_b128 v[186:189], v159 offset:51200
	ds_read_b128 v[190:193], v159 offset:52224
	ds_read_b128 v[194:197], v159 offset:53248
	ds_read_b128 v[198:201], v159 offset:54272
	ds_read_b128 v[204:207], v159 offset:55296
	ds_read_b128 v[208:211], v159 offset:56320
	global_load_lds_dwordx4 v[228:229], off
	v_lshl_add_u64 v[228:229], v[234:235], 0, s[8:9]
	s_mov_b32 m0, s52
	s_nop 0
	global_load_lds_dwordx4 v[228:229], off
	s_barrier
; __device__ __forceinline__ unsigned cvt_pk_bf16(float lo, float hi) { unsigned r; asm volatile("v_cvt_pk_bf16_f32 %0, %1, %2" : "=v"(r) : "v"(lo), "v"(hi)); return r; }
; #define PG8_STAGE(bufoff, gbase, voff) do { _Pragma("unroll") for (int _i = 0; _i < 2; ++_i) \
;         __builtin_amdgcn_global_load_lds((const unsigned*)((const char*)(gbase) + (voff)[_i]), (LAS unsigned*)(lds + (bufoff) + ldsw + _i * 8192), 16, 0, 0); } while (0)
; #define PG8_WAIT_V(n) asm volatile("s_waitcnt vmcnt(" #n ")" ::: "memory")
; #define PG8_WAIT_L(n) asm volatile("s_waitcnt lgkmcnt(" #n ")" ::: "memory")
; #define PG8_BAR __builtin_amdgcn_s_barrier()
; #define PG8_SCHED __builtin_amdgcn_sched_barrier(0)
;     __device__ __forceinline__ void operator()(const f32x4 (&acc)[2][2][4][2], const Unit& u, int wr, int wc, int fr, int fq) const {
;         const int row0 = u.pm * BM + wr * 64 + fr; const int col0 = u.pn * BM + wc * 64 + 16 * fq;
; #pragma unroll
;         for (int ai = 0; ai < 2; ++ai)
; #pragma unroll
;             for (int m = 0; m < 4; ++m) { const int row = row0 + ai * HALF + m * 16;
;                 const float rs = ssin ? __builtin_amdgcn_rsqf(ssin[row] * (1.f / D) + EPS) : 1.0f; float sq = 0.f; u32x4 w[2];
; #pragma unroll
;                 for (int bj = 0; bj < 2; ++bj) { f32x4 v0 = acc[ai][bj][m][0] * rs, v1 = acc[ai][bj][m][1] * rs;
;                     if (ACT == 1) {
; #pragma unroll
;                         for (int j = 0; j < 4; ++j) { const float a = fmaxf(v0[j], 0.f), b = fmaxf(v1[j], 0.f); v0[j] = a * a; v1[j] = b * b; } }
;                     sq += (v0[0] * v0[0] + v0[1] * v0[1]) + (v0[2] * v0[2] + v0[3] * v0[3]) + (v1[0] * v1[0] + v1[1] * v1[1]) + (v1[2] * v1[2] + v1[3] * v1[3]);
;                     w[bj].x = cvt_pk_bf16(v0[0], v0[1]); w[bj].y = cvt_pk_bf16(v0[2], v0[3]); w[bj].z = cvt_pk_bf16(v1[0], v1[1]); w[bj].w = cvt_pk_bf16(v1[2], v1[3]); }
;                 store_pair_lines(O, ldc, row, fr, col0, w[0], w[1]);
; template <class Epi>
; __device__ __forceinline__ void gemm_phase(LAS unsigned char* lds, const Gemm g, const StaticOrder& S, const Epi& E) {
;     ...
;             PG8_BAR; PG8_WAIT_L(0); PG8_MMA(1, 0, At, B0); PG8_BAR; PG8_SCHED;
;             PG8_STAGE(PG8_SB(1, 1), b3, voffB1);
;             PG8_WAIT_V(6); PG8_BAR; PG8_MMA(1, 1, At, B1); PG8_BAR;
	s_waitcnt lgkmcnt(0)
	s_waitcnt lgkmcnt(0)
	v_mfma_f32_16x16x32_bf16 v[60:63], v[162:165], v[178:181], v[60:63]
	v_mfma_f32_16x16x32_bf16 v[56:59], v[170:173], v[178:181], v[56:59]
	v_mfma_f32_16x16x32_bf16 v[44:47], v[162:165], v[186:189], v[44:47]
	v_mfma_f32_16x16x32_bf16 v[40:43], v[170:173], v[186:189], v[40:43]
	v_mfma_f32_16x16x32_bf16 v[28:31], v[162:165], v[194:197], v[28:31]
	v_mfma_f32_16x16x32_bf16 v[24:27], v[170:173], v[194:197], v[24:27]
	v_mfma_f32_16x16x32_bf16 v[12:15], v[162:165], v[204:207], v[12:15]
	v_mfma_f32_16x16x32_bf16 v[8:11], v[170:173], v[204:207], v[8:11]
	v_mfma_f32_16x16x32_bf16 v[60:63], v[166:169], v[182:185], v[60:63]
	v_mfma_f32_16x16x32_bf16 v[56:59], v[174:177], v[182:185], v[56:59]
	v_mfma_f32_16x16x32_bf16 v[44:47], v[166:169], v[190:193], v[44:47]
	v_mfma_f32_16x16x32_bf16 v[40:43], v[174:177], v[190:193], v[40:43]
	v_mfma_f32_16x16x32_bf16 v[28:31], v[166:169], v[198:201], v[28:31]
	v_mfma_f32_16x16x32_bf16 v[24:27], v[174:177], v[198:201], v[24:27]
	v_mfma_f32_16x16x32_bf16 v[12:15], v[166:169], v[208:211], v[12:15]
	v_mfma_f32_16x16x32_bf16 v[8:11], v[174:177], v[208:211], v[8:11]
	s_barrier
	s_add_i32 s33, s36, s44
	v_lshl_add_u64 v[162:163], v[236:237], 0, s[8:9]
	s_mov_b32 m0, s33
	s_nop 0
	global_load_lds_dwordx4 v[162:163], off
	v_lshl_add_u64 v[162:163], v[238:239], 0, s[8:9]
	s_add_i32 m0, s33, 0x2000
	s_nop 0
	global_load_lds_dwordx4 v[162:163], off
	s_waitcnt vmcnt(6)
	s_barrier
	v_mfma_f32_16x16x32_bf16 v[52:55], v[212:215], v[178:181], v[52:55]
	v_mfma_f32_16x16x32_bf16 v[48:51], v[220:223], v[178:181], v[48:51]
	v_mfma_f32_16x16x32_bf16 v[36:39], v[212:215], v[186:189], v[36:39]
	v_mfma_f32_16x16x32_bf16 v[32:35], v[220:223], v[186:189], v[32:35]
	v_mfma_f32_16x16x32_bf16 v[20:23], v[212:215], v[194:197], v[20:23]
	v_mfma_f32_16x16x32_bf16 v[16:19], v[220:223], v[194:197], v[16:19]
	v_mfma_f32_16x16x32_bf16 v[4:7], v[212:215], v[204:207], v[4:7]
	v_mfma_f32_16x16x32_bf16 v[0:3], v[220:223], v[204:207], v[0:3]
	v_mfma_f32_16x16x32_bf16 v[52:55], v[216:219], v[182:185], v[52:55]
	v_mfma_f32_16x16x32_bf16 v[48:51], v[224:227], v[182:185], v[48:51]
	v_mfma_f32_16x16x32_bf16 v[36:39], v[216:219], v[190:193], v[36:39]
	v_mfma_f32_16x16x32_bf16 v[32:35], v[224:227], v[190:193], v[32:35]
	v_mfma_f32_16x16x32_bf16 v[20:23], v[216:219], v[198:201], v[20:23]
	v_mfma_f32_16x16x32_bf16 v[16:19], v[224:227], v[198:201], v[16:19]
	v_mfma_f32_16x16x32_bf16 v[4:7], v[216:219], v[208:211], v[4:7]
	v_mfma_f32_16x16x32_bf16 v[0:3], v[224:227], v[208:211], v[0:3]
	s_add_i32 s63, s63, 2
	s_add_u32 s34, s34, 0x100
	s_addc_u32 s35, s35, 0
	s_add_u32 s61, s61, 0x100
	s_addc_u32 s62, s62, 0
	s_cmp_gt_u32 s63, 29
	s_barrier
	s_cbranch_scc0 .LBB0_107
	s_lshl_b32 s11, s30, 8
	v_cvt_pk_bf16_f32 v124, v124, v125
	v_cvt_pk_bf16_f32 v125, v126, v127
	v_cvt_pk_bf16_f32 v120, v120, v121
	v_cvt_pk_bf16_f32 v121, v122, v123
	v_cvt_pk_bf16_f32 v122, v116, v117
	v_cvt_pk_bf16_f32 v119, v118, v119
	v_mov_b32_e32 v118, 0
	s_add_i32 s11, s11, s53
	v_cvt_pk_bf16_f32 v112, v112, v113
	v_cvt_pk_bf16_f32 v113, v114, v115
	v_mov_b32_e32 v123, 0
	v_mov_b32_dpp v118, v124 row_ror:8 row_mask:0xf bank_mask:0xf
	v_mov_b32_e32 v114, 0
	v_mov_b32_dpp v123, v125 row_ror:8 row_mask:0xf bank_mask:0xf
	v_mov_b32_e32 v126, 0
	v_mov_b32_e32 v127, 0
	v_mov_b32_dpp v114, v122 row_ror:8 row_mask:0xf bank_mask:0xf
	v_mov_b32_e32 v115, 0
	v_mov_b32_e32 v116, 0
	v_mov_b32_e32 v117, 0
	v_cndmask_b32_e64 v118, v122, v118, s[4:5]
	v_or_b32_e32 v122, s11, v149
	v_lshl_or_b32 v162, s58, 8, v157
	v_mov_b32_dpp v126, v120 row_ror:8 row_mask:0xf bank_mask:0xf
	v_mov_b32_dpp v127, v121 row_ror:8 row_mask:0xf bank_mask:0xf
	v_mov_b32_dpp v115, v119 row_ror:8 row_mask:0xf bank_mask:0xf
	v_mov_b32_dpp v116, v112 row_ror:8 row_mask:0xf bank_mask:0xf
	v_mov_b32_dpp v117, v113 row_ror:8 row_mask:0xf bank_mask:0xf
	v_cndmask_b32_e64 v119, v119, v123, s[4:5]
	v_ashrrev_i32_e32 v123, 31, v122
	v_ashrrev_i32_e32 v163, 31, v162
	v_cndmask_b32_e64 v116, v116, v120, s[4:5]
	v_cndmask_b32_e64 v117, v117, v121, s[4:5]
	v_cndmask_b32_e64 v120, v112, v126, s[4:5]
	v_cndmask_b32_e64 v121, v113, v127, s[4:5]
	v_lshlrev_b64 v[112:113], 13, v[122:123]
	v_cndmask_b32_e64 v114, v114, v124, s[4:5]
	v_cndmask_b32_e64 v115, v115, v125, s[4:5]
	v_lshl_add_u64 v[124:125], s[6:7], 0, v[112:113]
	v_lshlrev_b64 v[112:113], 1, v[162:163]
	v_lshl_add_u64 v[124:125], v[124:125], 0, v[112:113]
	global_store_dwordx4 v[124:125], v[114:117], off
	v_or_b32_e32 v161, s11, v147
	s_mov_b32 s58, s10
	v_or_b32_e32 v114, 8, v122
	v_ashrrev_i32_e32 v115, 31, v114
	v_lshlrev_b64 v[114:115], 13, v[114:115]
	v_lshl_add_u64 v[114:115], s[6:7], 0, v[114:115]
	v_lshl_add_u64 v[114:115], v[114:115], 0, v[112:113]
	global_store_dwordx4 v[114:115], v[118:121], off
	v_cvt_pk_bf16_f32 v108, v108, v109
	v_cvt_pk_bf16_f32 v109, v110, v111
	v_cvt_pk_bf16_f32 v104, v104, v105
	v_cvt_pk_bf16_f32 v105, v106, v107
	v_cvt_pk_bf16_f32 v100, v100, v101
	v_cvt_pk_bf16_f32 v101, v102, v103
	v_cvt_pk_bf16_f32 v102, v96, v97
	v_cvt_pk_bf16_f32 v103, v98, v99
	v_mov_b32_e32 v98, 0
	v_mov_b32_e32 v110, 0
	v_mov_b32_e32 v99, 0
	v_mov_b32_dpp v98, v102 row_ror:8 row_mask:0xf bank_mask:0xf
	v_mov_b32_dpp v110, v104 row_ror:8 row_mask:0xf bank_mask:0xf
	v_mov_b32_e32 v111, 0
	v_mov_b32_dpp v99, v103 row_ror:8 row_mask:0xf bank_mask:0xf
	v_cndmask_b32_e64 v98, v98, v104, s[4:5]
	v_add_u32_e32 v104, v150, v161
	v_mov_b32_dpp v111, v105 row_ror:8 row_mask:0xf bank_mask:0xf
	v_cndmask_b32_e64 v99, v99, v105, s[4:5]
	v_ashrrev_i32_e32 v105, 31, v104
	v_mov_b32_e32 v96, 0
	v_mov_b32_e32 v97, 0
	v_lshlrev_b64 v[104:105], 13, v[104:105]
; __device__ __forceinline__ unsigned cvt_pk_bf16(float lo, float hi) { unsigned r; asm volatile("v_cvt_pk_bf16_f32 %0, %1, %2" : "=v"(r) : "v"(lo), "v"(hi)); return r; }
; __device__ __forceinline__ unsigned dpp_ror8(unsigned x) { return (unsigned)__builtin_amdgcn_update_dpp(0, (int)x, 0x128, 0xf, 0xf, false); }
; __device__ __forceinline__ void store_pair_lines(bf16_t* O, int ldc, int row, int fr, int col0, u32x4 wA, u32x4 wB) {
;     const u32x4 sA = {dpp_ror8(wA.x), dpp_ror8(wA.y), dpp_ror8(wA.z), dpp_ror8(wA.w)}, sB = {dpp_ror8(wB.x), dpp_ror8(wB.y), dpp_ror8(wB.z), dpp_ror8(wB.w)};
;     const bool lo = fr < 8;
;     const u32x4 o1 = lo ? wA : sB, o2 = lo ? sA : wB;
;     const int r1 = row - fr + (fr & 7), cb = col0 + (lo ? 0 : 8);
;     *(u32x4*)(O + (size_t)r1 * ldc + cb) = o1;
;     *(u32x4*)(O + (size_t)(r1 + 8) * ldc + cb) = o2;
;     __device__ __forceinline__ void operator()(const f32x4 (&acc)[2][2][4][2], const Unit& u, int wr, int wc, int fr, int fq) const {
;         const int row0 = u.pm * BM + wr * 64 + fr; const int col0 = u.pn * BM + wc * 64 + 16 * fq;
; #pragma unroll
;         for (int ai = 0; ai < 2; ++ai)
; #pragma unroll
;             for (int m = 0; m < 4; ++m) { const int row = row0 + ai * HALF + m * 16;
;                 const float rs = ssin ? __builtin_amdgcn_rsqf(ssin[row] * (1.f / D) + EPS) : 1.0f; float sq = 0.f; u32x4 w[2];
; #pragma unroll
;                 for (int bj = 0; bj < 2; ++bj) { f32x4 v0 = acc[ai][bj][m][0] * rs, v1 = acc[ai][bj][m][1] * rs;
;                     if (ACT == 1) {
; #pragma unroll
;                         for (int j = 0; j < 4; ++j) { const float a = fmaxf(v0[j], 0.f), b = fmaxf(v1[j], 0.f); v0[j] = a * a; v1[j] = b * b; } }
;                     sq += (v0[0] * v0[0] + v0[1] * v0[1]) + (v0[2] * v0[2] + v0[3] * v0[3]) + (v1[0] * v1[0] + v1[1] * v1[1]) + (v1[2] * v1[2] + v1[3] * v1[3]);
;                     w[bj].x = cvt_pk_bf16(v0[0], v0[1]); w[bj].y = cvt_pk_bf16(v0[2], v0[3]); w[bj].z = cvt_pk_bf16(v1[0], v1[1]); w[bj].w = cvt_pk_bf16(v1[2], v1[3]); }
;                 store_pair_lines(O, ldc, row, fr, col0, w[0], w[1]);
	v_mov_b32_dpp v96, v100 row_ror:8 row_mask:0xf bank_mask:0xf
	v_mov_b32_dpp v97, v101 row_ror:8 row_mask:0xf bank_mask:0xf
	v_lshl_add_u64 v[104:105], s[6:7], 0, v[104:105]
	v_mov_b32_e32 v106, 0
	v_mov_b32_e32 v107, 0
	v_cndmask_b32_e64 v96, v96, v108, s[4:5]
	v_cndmask_b32_e64 v97, v97, v109, s[4:5]
	v_lshl_add_u64 v[104:105], v[104:105], 0, v[112:113]
	v_mov_b32_dpp v106, v108 row_ror:8 row_mask:0xf bank_mask:0xf
	v_mov_b32_dpp v107, v109 row_ror:8 row_mask:0xf bank_mask:0xf
	global_store_dwordx4 v[104:105], v[96:99], off
	v_cndmask_b32_e64 v100, v100, v106, s[4:5]
	v_cndmask_b32_e64 v101, v101, v107, s[4:5]
	v_add_co_u32_e32 v96, vcc, s49, v104
	v_cndmask_b32_e64 v102, v102, v110, s[4:5]
	v_cndmask_b32_e64 v103, v103, v111, s[4:5]
	v_addc_co_u32_e32 v97, vcc, 0, v105, vcc
	global_store_dwordx4 v[96:97], v[100:103], off
	v_cvt_pk_bf16_f32 v92, v92, v93
	v_cvt_pk_bf16_f32 v93, v94, v95
	v_cvt_pk_bf16_f32 v88, v88, v89
	v_cvt_pk_bf16_f32 v89, v90, v91
	v_cvt_pk_bf16_f32 v84, v84, v85
	v_cvt_pk_bf16_f32 v85, v86, v87
	v_cvt_pk_bf16_f32 v86, v80, v81
	v_cvt_pk_bf16_f32 v87, v82, v83
	v_mov_b32_e32 v82, 0
	v_mov_b32_e32 v94, 0
	v_mov_b32_e32 v83, 0
	v_mov_b32_dpp v82, v86 row_ror:8 row_mask:0xf bank_mask:0xf
	v_mov_b32_dpp v94, v88 row_ror:8 row_mask:0xf bank_mask:0xf
	v_mov_b32_e32 v95, 0
	v_mov_b32_dpp v83, v87 row_ror:8 row_mask:0xf bank_mask:0xf
	v_cndmask_b32_e64 v82, v82, v88, s[4:5]
	v_add_u32_e32 v88, v151, v161
	v_mov_b32_dpp v95, v89 row_ror:8 row_mask:0xf bank_mask:0xf
	v_cndmask_b32_e64 v83, v83, v89, s[4:5]
	v_ashrrev_i32_e32 v89, 31, v88
	v_mov_b32_e32 v80, 0
	v_mov_b32_e32 v81, 0
	v_lshlrev_b64 v[88:89], 13, v[88:89]
	v_mov_b32_dpp v80, v84 row_ror:8 row_mask:0xf bank_mask:0xf
	v_mov_b32_dpp v81, v85 row_ror:8 row_mask:0xf bank_mask:0xf
	v_lshl_add_u64 v[88:89], s[6:7], 0, v[88:89]
	v_mov_b32_e32 v90, 0
	v_mov_b32_e32 v91, 0
	v_cndmask_b32_e64 v80, v80, v92, s[4:5]
	v_cndmask_b32_e64 v81, v81, v93, s[4:5]
	v_lshl_add_u64 v[88:89], v[88:89], 0, v[112:113]
	v_mov_b32_dpp v90, v92 row_ror:8 row_mask:0xf bank_mask:0xf
	v_mov_b32_dpp v91, v93 row_ror:8 row_mask:0xf bank_mask:0xf
	global_store_dwordx4 v[88:89], v[80:83], off
	v_cndmask_b32_e64 v84, v84, v90, s[4:5]
	v_cndmask_b32_e64 v85, v85, v91, s[4:5]
	v_add_co_u32_e32 v80, vcc, s49, v88
	v_cndmask_b32_e64 v86, v86, v94, s[4:5]
	v_cndmask_b32_e64 v87, v87, v95, s[4:5]
	v_addc_co_u32_e32 v81, vcc, 0, v89, vcc
	global_store_dwordx4 v[80:81], v[84:87], off
	v_cvt_pk_bf16_f32 v76, v76, v77
	v_cvt_pk_bf16_f32 v77, v78, v79
	v_cvt_pk_bf16_f32 v72, v72, v73
	v_cvt_pk_bf16_f32 v73, v74, v75
	v_cvt_pk_bf16_f32 v68, v68, v69
	v_cvt_pk_bf16_f32 v69, v70, v71
	v_cvt_pk_bf16_f32 v70, v64, v65
	v_cvt_pk_bf16_f32 v71, v66, v67
	v_mov_b32_e32 v66, 0
	v_mov_b32_e32 v78, 0
	v_mov_b32_e32 v67, 0
	v_mov_b32_dpp v66, v70 row_ror:8 row_mask:0xf bank_mask:0xf
	v_mov_b32_dpp v78, v72 row_ror:8 row_mask:0xf bank_mask:0xf
	v_mov_b32_e32 v79, 0
	v_mov_b32_dpp v67, v71 row_ror:8 row_mask:0xf bank_mask:0xf
	v_cndmask_b32_e64 v66, v66, v72, s[4:5]
	v_add_u32_e32 v72, v152, v161
	v_mov_b32_dpp v79, v73 row_ror:8 row_mask:0xf bank_mask:0xf
	v_cndmask_b32_e64 v67, v67, v73, s[4:5]
	v_ashrrev_i32_e32 v73, 31, v72
	v_mov_b32_e32 v64, 0
	v_mov_b32_e32 v65, 0
	v_lshlrev_b64 v[72:73], 13, v[72:73]
	v_mov_b32_dpp v64, v68 row_ror:8 row_mask:0xf bank_mask:0xf
	v_mov_b32_dpp v65, v69 row_ror:8 row_mask:0xf bank_mask:0xf
	v_lshl_add_u64 v[72:73], s[6:7], 0, v[72:73]
	v_mov_b32_e32 v74, 0
	v_mov_b32_e32 v75, 0
	v_cndmask_b32_e64 v64, v64, v76, s[4:5]
	v_cndmask_b32_e64 v65, v65, v77, s[4:5]
	v_lshl_add_u64 v[72:73], v[72:73], 0, v[112:113]
	v_mov_b32_dpp v74, v76 row_ror:8 row_mask:0xf bank_mask:0xf
	v_mov_b32_dpp v75, v77 row_ror:8 row_mask:0xf bank_mask:0xf
	global_store_dwordx4 v[72:73], v[64:67], off
	v_cndmask_b32_e64 v68, v68, v74, s[4:5]
	v_cndmask_b32_e64 v69, v69, v75, s[4:5]
	v_add_co_u32_e32 v64, vcc, s49, v72
	v_cndmask_b32_e64 v70, v70, v78, s[4:5]
	v_cndmask_b32_e64 v71, v71, v79, s[4:5]
	v_addc_co_u32_e32 v65, vcc, 0, v73, vcc
	global_store_dwordx4 v[64:65], v[68:71], off
	v_cvt_pk_bf16_f32 v60, v60, v61
	v_cvt_pk_bf16_f32 v61, v62, v63
	v_cvt_pk_bf16_f32 v56, v56, v57
	v_cvt_pk_bf16_f32 v57, v58, v59
	v_cvt_pk_bf16_f32 v52, v52, v53
	v_cvt_pk_bf16_f32 v53, v54, v55
	v_cvt_pk_bf16_f32 v54, v48, v49
	v_cvt_pk_bf16_f32 v55, v50, v51
	v_mov_b32_e32 v50, 0
	v_mov_b32_e32 v62, 0
	v_mov_b32_e32 v51, 0
	v_mov_b32_dpp v50, v54 row_ror:8 row_mask:0xf bank_mask:0xf
	v_mov_b32_dpp v62, v56 row_ror:8 row_mask:0xf bank_mask:0xf
	v_mov_b32_e32 v63, 0
	v_mov_b32_dpp v51, v55 row_ror:8 row_mask:0xf bank_mask:0xf
	v_cndmask_b32_e64 v50, v50, v56, s[4:5]
	v_add_u32_e32 v56, v153, v161
	v_mov_b32_dpp v63, v57 row_ror:8 row_mask:0xf bank_mask:0xf
	v_cndmask_b32_e64 v51, v51, v57, s[4:5]
	v_ashrrev_i32_e32 v57, 31, v56
	v_mov_b32_e32 v48, 0
	v_mov_b32_e32 v49, 0
	v_lshlrev_b64 v[56:57], 13, v[56:57]
	v_mov_b32_dpp v48, v52 row_ror:8 row_mask:0xf bank_mask:0xf
	v_mov_b32_dpp v49, v53 row_ror:8 row_mask:0xf bank_mask:0xf
	v_lshl_add_u64 v[56:57], s[6:7], 0, v[56:57]
	v_mov_b32_e32 v58, 0
	v_mov_b32_e32 v59, 0
	v_cndmask_b32_e64 v48, v48, v60, s[4:5]
	v_cndmask_b32_e64 v49, v49, v61, s[4:5]
	v_lshl_add_u64 v[56:57], v[56:57], 0, v[112:113]
	v_mov_b32_dpp v58, v60 row_ror:8 row_mask:0xf bank_mask:0xf
	v_mov_b32_dpp v59, v61 row_ror:8 row_mask:0xf bank_mask:0xf
; __device__ __forceinline__ unsigned cvt_pk_bf16(float lo, float hi) { unsigned r; asm volatile("v_cvt_pk_bf16_f32 %0, %1, %2" : "=v"(r) : "v"(lo), "v"(hi)); return r; }
; __device__ __forceinline__ unsigned dpp_ror8(unsigned x) { return (unsigned)__builtin_amdgcn_update_dpp(0, (int)x, 0x128, 0xf, 0xf, false); }
; __device__ __forceinline__ void store_pair_lines(bf16_t* O, int ldc, int row, int fr, int col0, u32x4 wA, u32x4 wB) {
;     const u32x4 sA = {dpp_ror8(wA.x), dpp_ror8(wA.y), dpp_ror8(wA.z), dpp_ror8(wA.w)}, sB = {dpp_ror8(wB.x), dpp_ror8(wB.y), dpp_ror8(wB.z), dpp_ror8(wB.w)};
;     const bool lo = fr < 8;
;     const u32x4 o1 = lo ? wA : sB, o2 = lo ? sA : wB;
;     const int r1 = row - fr + (fr & 7), cb = col0 + (lo ? 0 : 8);
;     *(u32x4*)(O + (size_t)r1 * ldc + cb) = o1;
;     *(u32x4*)(O + (size_t)(r1 + 8) * ldc + cb) = o2;
;     __device__ __forceinline__ void operator()(const f32x4 (&acc)[2][2][4][2], const Unit& u, int wr, int wc, int fr, int fq) const {
;         const int row0 = u.pm * BM + wr * 64 + fr; const int col0 = u.pn * BM + wc * 64 + 16 * fq;
; #pragma unroll
;         for (int ai = 0; ai < 2; ++ai)
; #pragma unroll
;             for (int m = 0; m < 4; ++m) { const int row = row0 + ai * HALF + m * 16;
;                 const float rs = ssin ? __builtin_amdgcn_rsqf(ssin[row] * (1.f / D) + EPS) : 1.0f; float sq = 0.f; u32x4 w[2];
; #pragma unroll
;                 for (int bj = 0; bj < 2; ++bj) { f32x4 v0 = acc[ai][bj][m][0] * rs, v1 = acc[ai][bj][m][1] * rs;
;                     if (ACT == 1) {
; #pragma unroll
;                         for (int j = 0; j < 4; ++j) { const float a = fmaxf(v0[j], 0.f), b = fmaxf(v1[j], 0.f); v0[j] = a * a; v1[j] = b * b; } }
;                     sq += (v0[0] * v0[0] + v0[1] * v0[1]) + (v0[2] * v0[2] + v0[3] * v0[3]) + (v1[0] * v1[0] + v1[1] * v1[1]) + (v1[2] * v1[2] + v1[3] * v1[3]);
;                     w[bj].x = cvt_pk_bf16(v0[0], v0[1]); w[bj].y = cvt_pk_bf16(v0[2], v0[3]); w[bj].z = cvt_pk_bf16(v1[0], v1[1]); w[bj].w = cvt_pk_bf16(v1[2], v1[3]); }
;                 store_pair_lines(O, ldc, row, fr, col0, w[0], w[1]);
;                 if (ssout) { sq += __shfl_xor(sq, 16); sq += __shfl_xor(sq, 32); if (fq == 0) unsafeAtomicAdd(ssout + row, sq); } }
	global_store_dwordx4 v[56:57], v[48:51], off
	v_cndmask_b32_e64 v52, v52, v58, s[4:5]
	v_cndmask_b32_e64 v53, v53, v59, s[4:5]
	v_add_co_u32_e32 v48, vcc, s49, v56
	v_cndmask_b32_e64 v54, v54, v62, s[4:5]
	v_cndmask_b32_e64 v55, v55, v63, s[4:5]
	v_addc_co_u32_e32 v49, vcc, 0, v57, vcc
	global_store_dwordx4 v[48:49], v[52:55], off
	v_cvt_pk_bf16_f32 v44, v44, v45
	v_cvt_pk_bf16_f32 v45, v46, v47
	v_cvt_pk_bf16_f32 v40, v40, v41
	v_cvt_pk_bf16_f32 v41, v42, v43
	v_cvt_pk_bf16_f32 v36, v36, v37
	v_cvt_pk_bf16_f32 v37, v38, v39
	v_cvt_pk_bf16_f32 v38, v32, v33
	v_cvt_pk_bf16_f32 v39, v34, v35
	v_mov_b32_e32 v34, 0
	v_mov_b32_e32 v46, 0
	v_mov_b32_e32 v35, 0
	v_mov_b32_dpp v34, v38 row_ror:8 row_mask:0xf bank_mask:0xf
	v_mov_b32_dpp v46, v40 row_ror:8 row_mask:0xf bank_mask:0xf
	v_mov_b32_e32 v47, 0
	v_mov_b32_dpp v35, v39 row_ror:8 row_mask:0xf bank_mask:0xf
	v_cndmask_b32_e64 v34, v34, v40, s[4:5]
	v_add_u32_e32 v40, v154, v161
	v_mov_b32_dpp v47, v41 row_ror:8 row_mask:0xf bank_mask:0xf
	v_cndmask_b32_e64 v35, v35, v41, s[4:5]
	v_ashrrev_i32_e32 v41, 31, v40
	v_mov_b32_e32 v32, 0
	v_mov_b32_e32 v33, 0
	v_lshlrev_b64 v[40:41], 13, v[40:41]
	v_mov_b32_dpp v32, v36 row_ror:8 row_mask:0xf bank_mask:0xf
	v_mov_b32_dpp v33, v37 row_ror:8 row_mask:0xf bank_mask:0xf
	v_lshl_add_u64 v[40:41], s[6:7], 0, v[40:41]
	v_mov_b32_e32 v42, 0
	v_mov_b32_e32 v43, 0
	v_cndmask_b32_e64 v32, v32, v44, s[4:5]
	v_cndmask_b32_e64 v33, v33, v45, s[4:5]
	v_lshl_add_u64 v[40:41], v[40:41], 0, v[112:113]
	v_mov_b32_dpp v42, v44 row_ror:8 row_mask:0xf bank_mask:0xf
	v_mov_b32_dpp v43, v45 row_ror:8 row_mask:0xf bank_mask:0xf
	global_store_dwordx4 v[40:41], v[32:35], off
	v_cndmask_b32_e64 v36, v36, v42, s[4:5]
	v_cndmask_b32_e64 v37, v37, v43, s[4:5]
	v_add_co_u32_e32 v32, vcc, s49, v40
	v_cndmask_b32_e64 v38, v38, v46, s[4:5]
	v_cndmask_b32_e64 v39, v39, v47, s[4:5]
	v_addc_co_u32_e32 v33, vcc, 0, v41, vcc
	global_store_dwordx4 v[32:33], v[36:39], off
	v_cvt_pk_bf16_f32 v28, v28, v29
	v_cvt_pk_bf16_f32 v29, v30, v31
	v_cvt_pk_bf16_f32 v24, v24, v25
	v_cvt_pk_bf16_f32 v25, v26, v27
	v_cvt_pk_bf16_f32 v20, v20, v21
	v_cvt_pk_bf16_f32 v21, v22, v23
	v_cvt_pk_bf16_f32 v22, v16, v17
	v_cvt_pk_bf16_f32 v23, v18, v19
	v_mov_b32_e32 v18, 0
	v_mov_b32_e32 v30, 0
	v_mov_b32_e32 v19, 0
	v_mov_b32_dpp v18, v22 row_ror:8 row_mask:0xf bank_mask:0xf
	v_mov_b32_dpp v30, v24 row_ror:8 row_mask:0xf bank_mask:0xf
	v_mov_b32_e32 v31, 0
	v_mov_b32_dpp v19, v23 row_ror:8 row_mask:0xf bank_mask:0xf
	v_cndmask_b32_e64 v18, v18, v24, s[4:5]
	v_add_u32_e32 v24, v155, v161
	v_mov_b32_dpp v31, v25 row_ror:8 row_mask:0xf bank_mask:0xf
	v_cndmask_b32_e64 v19, v19, v25, s[4:5]
	v_ashrrev_i32_e32 v25, 31, v24
	v_mov_b32_e32 v16, 0
	v_mov_b32_e32 v17, 0
	v_lshlrev_b64 v[24:25], 13, v[24:25]
	v_mov_b32_dpp v16, v20 row_ror:8 row_mask:0xf bank_mask:0xf
	v_mov_b32_dpp v17, v21 row_ror:8 row_mask:0xf bank_mask:0xf
	v_lshl_add_u64 v[24:25], s[6:7], 0, v[24:25]
	v_mov_b32_e32 v26, 0
	v_mov_b32_e32 v27, 0
	v_cndmask_b32_e64 v16, v16, v28, s[4:5]
	v_cndmask_b32_e64 v17, v17, v29, s[4:5]
	v_lshl_add_u64 v[24:25], v[24:25], 0, v[112:113]
	v_mov_b32_dpp v26, v28 row_ror:8 row_mask:0xf bank_mask:0xf
	v_mov_b32_dpp v27, v29 row_ror:8 row_mask:0xf bank_mask:0xf
	global_store_dwordx4 v[24:25], v[16:19], off
	v_cndmask_b32_e64 v20, v20, v26, s[4:5]
	v_cndmask_b32_e64 v21, v21, v27, s[4:5]
	v_add_co_u32_e32 v16, vcc, s49, v24
	v_cndmask_b32_e64 v22, v22, v30, s[4:5]
	v_cndmask_b32_e64 v23, v23, v31, s[4:5]
	v_addc_co_u32_e32 v17, vcc, 0, v25, vcc
	global_store_dwordx4 v[16:17], v[20:23], off
	v_cvt_pk_bf16_f32 v12, v12, v13
	v_cvt_pk_bf16_f32 v13, v14, v15
	v_cvt_pk_bf16_f32 v8, v8, v9
	v_cvt_pk_bf16_f32 v9, v10, v11
	v_cvt_pk_bf16_f32 v4, v4, v5
	v_cvt_pk_bf16_f32 v5, v6, v7
	v_cvt_pk_bf16_f32 v6, v0, v1
	v_cvt_pk_bf16_f32 v7, v2, v3
	v_mov_b32_e32 v2, 0
	v_mov_b32_e32 v14, 0
	v_mov_b32_e32 v3, 0
	v_mov_b32_dpp v2, v6 row_ror:8 row_mask:0xf bank_mask:0xf
	v_mov_b32_dpp v14, v8 row_ror:8 row_mask:0xf bank_mask:0xf
	v_mov_b32_e32 v15, 0
	v_mov_b32_dpp v3, v7 row_ror:8 row_mask:0xf bank_mask:0xf
	v_cndmask_b32_e64 v2, v2, v8, s[4:5]
	v_add_u32_e32 v8, v156, v161
	v_mov_b32_dpp v15, v9 row_ror:8 row_mask:0xf bank_mask:0xf
	v_cndmask_b32_e64 v3, v3, v9, s[4:5]
	v_ashrrev_i32_e32 v9, 31, v8
	v_mov_b32_e32 v0, 0
	v_mov_b32_e32 v1, 0
	v_lshlrev_b64 v[8:9], 13, v[8:9]
	v_mov_b32_dpp v0, v4 row_ror:8 row_mask:0xf bank_mask:0xf
	v_mov_b32_dpp v1, v5 row_ror:8 row_mask:0xf bank_mask:0xf
	v_lshl_add_u64 v[8:9], s[6:7], 0, v[8:9]
	v_cndmask_b32_e64 v0, v0, v12, s[4:5]
	v_cndmask_b32_e64 v1, v1, v13, s[4:5]
	v_lshl_add_u64 v[8:9], v[8:9], 0, v[112:113]
	v_mov_b32_e32 v10, 0
	v_mov_b32_e32 v11, 0
	global_store_dwordx4 v[8:9], v[0:3], off
	v_mov_b32_dpp v10, v12 row_ror:8 row_mask:0xf bank_mask:0xf
	v_mov_b32_dpp v11, v13 row_ror:8 row_mask:0xf bank_mask:0xf
	v_add_co_u32_e32 v0, vcc, 0x10000, v8
	v_cndmask_b32_e64 v4, v4, v10, s[4:5]
	s_nop 0
	v_addc_co_u32_e32 v1, vcc, 0, v9, vcc
	v_cndmask_b32_e64 v5, v5, v11, s[4:5]
	v_cndmask_b32_e64 v6, v6, v14, s[4:5]
	v_cndmask_b32_e64 v7, v7, v15, s[4:5]
	s_and_b64 vcc, exec, s[18:19]
	s_mov_b32 s30, s12
	s_mov_b64 s[36:37], s[28:29]
	s_mov_b64 s[34:35], s[16:17]
	global_store_dwordx4 v[0:1], v[4:7], off
	s_cbranch_vccz .LBB0_103
	s_waitcnt vmcnt(0)
	s_cmpk_gt_u32 s27, 0xff
	s_cbranch_scc1 .LBB0_111
	s_barrier

; #define PG8_STAGE(bufoff, gbase, voff) do { _Pragma("unroll") for (int _i = 0; _i < 2; ++_i) \
;         __builtin_amdgcn_global_load_lds((const unsigned*)((const char*)(gbase) + (voff)[_i]), (LAS unsigned*)(lds + (bufoff) + ldsw + _i * 8192), 16, 0, 0); } while (0)
; #define PG8_LDA(dst, b, h) do { _Pragma("unroll") for (int m = 0; m < 4; ++m) _Pragma("unroll") for (int k = 0; k < 2; ++k) dst[m][k] = *(const LAS bf16x8*)(lds + PG8_SA(b, h) + aoff + m * 2048 + k * 1024); } while (0)
; #define PG8_LDB(dst, b, h) do { _Pragma("unroll") for (int n = 0; n < 2; ++n) _Pragma("unroll") for (int k = 0; k < 2; ++k) dst[n][k] = *(const LAS bf16x8*)(lds + PG8_SB(b, h) + boff + n * 2048 + k * 1024); } while (0)
; #define PG8_MMA(ai, bj, At, Bt) do { __builtin_amdgcn_s_setprio(1); _Pragma("unroll") for (int m = 0; m < 4; ++m) _Pragma("unroll") for (int n = 0; n < 2; ++n) _Pragma("unroll") for (int k = 0; k < 2; ++k) \
;         acc[ai][bj][m][n] = __builtin_amdgcn_mfma_f32_16x16x32_bf16(Bt[n][k], At[m][k], acc[ai][bj][m][n], 0, 0, 0); __builtin_amdgcn_s_setprio(0); } while (0)
; template <class Epi>
; __device__ __forceinline__ void gemm_phase(LAS unsigned char* lds, const Gemm g, const StaticOrder& S, const Epi& E) {
;     ...
;         for (int t = 0; t < nt; t += 2) {
;             const bool last = (t == nt - 2);
;             const char* a1 = cA + (size_t)(t + 1) * kstep;
;             const char* a2 = last ? nA : cA + (size_t)(t + 2) * kstep; const char* b2 = last ? nB : cB + (size_t)(t + 2) * kstep;
;             const char* a3 = a2 + kstep; const char* b3 = b2 + kstep;
;             PG8_LDB(B0, 0, 0); PG8_SCHED; PG8_LDA(At, 0, 0); PG8_STAGE(PG8_SA(1, 1), a1 + hstep, voffA);
;             PG8_WAIT_L(8); PG8_BAR; PG8_WAIT_L(0); PG8_MMA(0, 0, At, B0); PG8_BAR; PG8_SCHED;
;             PG8_LDB(B1, 0, 1); PG8_STAGE(PG8_SB(0, 0), b2, voffB0);
;             PG8_BAR; PG8_WAIT_L(0); PG8_MMA(0, 1, At, B1); PG8_BAR;
;             PG8_LDA(At, 0, 1); PG8_STAGE(PG8_SA(0, 0), a2, voffA);
;             PG8_BAR; PG8_WAIT_L(0); PG8_MMA(1, 0, At, B0); PG8_BAR; PG8_SCHED;
;             PG8_STAGE(PG8_SB(0, 1), b2, voffB1);
;             PG8_WAIT_V(6); PG8_BAR; PG8_MMA(1, 1, At, B1); PG8_BAR;
;             PG8_LDB(B0, 1, 0); PG8_SCHED; PG8_LDA(At, 1, 0); PG8_STAGE(PG8_SA(0, 1), a2 + hstep, voffA);
;             PG8_WAIT_L(8); PG8_BAR; PG8_WAIT_L(0); PG8_MMA(0, 0, At, B0); PG8_BAR; PG8_SCHED;
.LBB0_234:
	ds_read_b128 v[160:163], v157
	ds_read_b128 v[164:167], v157 offset:1024
	ds_read_b128 v[168:171], v157 offset:2048
	ds_read_b128 v[172:175], v157 offset:3072
	s_add_u32 s33, s38, 0xfffe0080
	s_addc_u32 s40, s39, -1
	s_cmp_eq_u32 s68, 4
	s_cselect_b32 s41, s17, s40
	s_cselect_b32 s40, s64, s33
	s_cselect_b32 s43, s11, s67
	s_cselect_b32 s42, s65, s66
	v_lshl_add_u64 v[200:201], s[38:39], 0, v[140:141]
	s_add_i32 m0, s37, 0xc000
	ds_read_b128 v[176:179], v158
	ds_read_b128 v[180:183], v158 offset:1024
	ds_read_b128 v[184:187], v158 offset:2048
	ds_read_b128 v[188:191], v158 offset:3072
	ds_read_b128 v[192:195], v158 offset:4096
	ds_read_b128 v[196:199], v158 offset:5120
	ds_read_b128 v[204:207], v158 offset:6144
	ds_read_b128 v[208:211], v158 offset:7168
	global_load_lds_dwordx4 v[200:201], off
	v_lshl_add_u64 v[200:201], s[38:39], 0, v[142:143]
	s_add_i32 m0, s37, 0xe000
	s_nop 0
	global_load_lds_dwordx4 v[200:201], off
	s_waitcnt lgkmcnt(8)
	s_barrier
	s_waitcnt lgkmcnt(0)
	s_waitcnt lgkmcnt(0)
	v_mfma_f32_16x16x32_bf16 v[124:127], v[160:163], v[176:179], v[124:127]
	v_mfma_f32_16x16x32_bf16 v[120:123], v[168:171], v[176:179], v[120:123]
	v_mfma_f32_16x16x32_bf16 v[108:111], v[160:163], v[184:187], v[108:111]
	v_mfma_f32_16x16x32_bf16 v[104:107], v[168:171], v[184:187], v[104:107]
	v_mfma_f32_16x16x32_bf16 v[92:95], v[160:163], v[192:195], v[92:95]
	v_mfma_f32_16x16x32_bf16 v[88:91], v[168:171], v[192:195], v[88:91]
	v_mfma_f32_16x16x32_bf16 v[76:79], v[160:163], v[204:207], v[76:79]
	v_mfma_f32_16x16x32_bf16 v[72:75], v[168:171], v[204:207], v[72:75]
	v_mfma_f32_16x16x32_bf16 v[124:127], v[164:167], v[180:183], v[124:127]
	v_mfma_f32_16x16x32_bf16 v[120:123], v[172:175], v[180:183], v[120:123]
	v_mfma_f32_16x16x32_bf16 v[108:111], v[164:167], v[188:191], v[108:111]
	v_mfma_f32_16x16x32_bf16 v[104:107], v[172:175], v[188:191], v[104:107]
	v_mfma_f32_16x16x32_bf16 v[92:95], v[164:167], v[196:199], v[92:95]
	v_mfma_f32_16x16x32_bf16 v[88:91], v[172:175], v[196:199], v[88:91]
	v_mfma_f32_16x16x32_bf16 v[76:79], v[164:167], v[208:211], v[76:79]
	v_mfma_f32_16x16x32_bf16 v[72:75], v[172:175], v[208:211], v[72:75]
	s_barrier
	s_add_i32 s33, s60, s49
	v_lshl_add_u64 v[200:201], s[42:43], 0, v[134:135]
	s_mov_b32 m0, s33
	ds_read_b128 v[212:215], v159
	ds_read_b128 v[216:219], v159 offset:1024
	ds_read_b128 v[220:223], v159 offset:2048
	ds_read_b128 v[224:227], v159 offset:3072
	global_load_lds_dwordx4 v[200:201], off
	v_lshl_add_u64 v[228:229], s[42:43], 0, v[128:129]
	s_add_i32 m0, s33, 0x2000
	s_nop 0
	global_load_lds_dwordx4 v[228:229], off
	s_barrier
	s_waitcnt lgkmcnt(0)
	s_waitcnt lgkmcnt(0)
	v_mfma_f32_16x16x32_bf16 v[116:119], v[212:215], v[176:179], v[116:119]
	v_mfma_f32_16x16x32_bf16 v[112:115], v[220:223], v[176:179], v[112:115]
	v_mfma_f32_16x16x32_bf16 v[100:103], v[212:215], v[184:187], v[100:103]
	v_mfma_f32_16x16x32_bf16 v[96:99], v[220:223], v[184:187], v[96:99]
	v_mfma_f32_16x16x32_bf16 v[84:87], v[212:215], v[192:195], v[84:87]
	v_mfma_f32_16x16x32_bf16 v[80:83], v[220:223], v[192:195], v[80:83]
	v_mfma_f32_16x16x32_bf16 v[68:71], v[212:215], v[204:207], v[68:71]
	v_mfma_f32_16x16x32_bf16 v[64:67], v[220:223], v[204:207], v[64:67]
	v_mfma_f32_16x16x32_bf16 v[116:119], v[216:219], v[180:183], v[116:119]
	v_mfma_f32_16x16x32_bf16 v[112:115], v[224:227], v[180:183], v[112:115]
	v_mfma_f32_16x16x32_bf16 v[100:103], v[216:219], v[188:191], v[100:103]
	v_mfma_f32_16x16x32_bf16 v[96:99], v[224:227], v[188:191], v[96:99]
	v_mfma_f32_16x16x32_bf16 v[84:87], v[216:219], v[196:199], v[84:87]
	v_mfma_f32_16x16x32_bf16 v[80:83], v[224:227], v[196:199], v[80:83]
	v_mfma_f32_16x16x32_bf16 v[68:71], v[216:219], v[208:211], v[68:71]
	v_mfma_f32_16x16x32_bf16 v[64:67], v[224:227], v[208:211], v[64:67]
	s_mov_b32 m0, s37
	v_lshl_add_u64 v[230:231], s[40:41], 0, v[138:139]
	s_barrier
	ds_read_b128 v[176:179], v158 offset:16384
	ds_read_b128 v[180:183], v158 offset:17408
	ds_read_b128 v[184:187], v158 offset:18432
	ds_read_b128 v[188:191], v158 offset:19456
	ds_read_b128 v[192:195], v158 offset:20480
	ds_read_b128 v[196:199], v158 offset:21504
	ds_read_b128 v[204:207], v158 offset:22528
	ds_read_b128 v[208:211], v158 offset:23552
	global_load_lds_dwordx4 v[230:231], off
	v_lshl_add_u64 v[232:233], s[40:41], 0, v[132:133]
	s_mov_b32 m0, s51
	s_nop 0
	global_load_lds_dwordx4 v[232:233], off
	s_barrier
	s_waitcnt lgkmcnt(0)
	s_waitcnt lgkmcnt(0)
	v_mfma_f32_16x16x32_bf16 v[60:63], v[160:163], v[176:179], v[60:63]
	v_mfma_f32_16x16x32_bf16 v[56:59], v[168:171], v[176:179], v[56:59]
	v_mfma_f32_16x16x32_bf16 v[44:47], v[160:163], v[184:187], v[44:47]
	v_mfma_f32_16x16x32_bf16 v[40:43], v[168:171], v[184:187], v[40:43]
	v_mfma_f32_16x16x32_bf16 v[28:31], v[160:163], v[192:195], v[28:31]
	v_mfma_f32_16x16x32_bf16 v[24:27], v[168:171], v[192:195], v[24:27]
	v_mfma_f32_16x16x32_bf16 v[12:15], v[160:163], v[204:207], v[12:15]
	v_mfma_f32_16x16x32_bf16 v[8:11], v[168:171], v[204:207], v[8:11]
	v_mfma_f32_16x16x32_bf16 v[60:63], v[164:167], v[180:183], v[60:63]
	v_mfma_f32_16x16x32_bf16 v[56:59], v[172:175], v[180:183], v[56:59]
	v_mfma_f32_16x16x32_bf16 v[44:47], v[164:167], v[188:191], v[44:47]
	v_mfma_f32_16x16x32_bf16 v[40:43], v[172:175], v[188:191], v[40:43]
	v_mfma_f32_16x16x32_bf16 v[28:31], v[164:167], v[196:199], v[28:31]
	v_mfma_f32_16x16x32_bf16 v[24:27], v[172:175], v[196:199], v[24:27]
	v_mfma_f32_16x16x32_bf16 v[12:15], v[164:167], v[208:211], v[12:15]
	v_mfma_f32_16x16x32_bf16 v[8:11], v[172:175], v[208:211], v[8:11]
	s_barrier
; #define PG8_STAGE(bufoff, gbase, voff) do { _Pragma("unroll") for (int _i = 0; _i < 2; ++_i) \
;         __builtin_amdgcn_global_load_lds((const unsigned*)((const char*)(gbase) + (voff)[_i]), (LAS unsigned*)(lds + (bufoff) + ldsw + _i * 8192), 16, 0, 0); } while (0)
; #define PG8_LDA(dst, b, h) do { _Pragma("unroll") for (int m = 0; m < 4; ++m) _Pragma("unroll") for (int k = 0; k < 2; ++k) dst[m][k] = *(const LAS bf16x8*)(lds + PG8_SA(b, h) + aoff + m * 2048 + k * 1024); } while (0)
; #define PG8_LDB(dst, b, h) do { _Pragma("unroll") for (int n = 0; n < 2; ++n) _Pragma("unroll") for (int k = 0; k < 2; ++k) dst[n][k] = *(const LAS bf16x8*)(lds + PG8_SB(b, h) + boff + n * 2048 + k * 1024); } while (0)
; #define PG8_MMA(ai, bj, At, Bt) do { __builtin_amdgcn_s_setprio(1); _Pragma("unroll") for (int m = 0; m < 4; ++m) _Pragma("unroll") for (int n = 0; n < 2; ++n) _Pragma("unroll") for (int k = 0; k < 2; ++k) \
;         acc[ai][bj][m][n] = __builtin_amdgcn_mfma_f32_16x16x32_bf16(Bt[n][k], At[m][k], acc[ai][bj][m][n], 0, 0, 0); __builtin_amdgcn_s_setprio(0); } while (0)
; #define PG8_WAIT_V(n) asm volatile("s_waitcnt vmcnt(" #n ")" ::: "memory")
; #define PG8_WAIT_L(n) asm volatile("s_waitcnt lgkmcnt(" #n ")" ::: "memory")
; #define PG8_BAR __builtin_amdgcn_s_barrier()
; #define PG8_SCHED __builtin_amdgcn_sched_barrier(0)
; template <class Epi>
; __device__ __forceinline__ void gemm_phase(LAS unsigned char* lds, const Gemm g, const StaticOrder& S, const Epi& E) {
;     ...
;             PG8_STAGE(PG8_SB(0, 1), b2, voffB1);
;             PG8_WAIT_V(6); PG8_BAR; PG8_MMA(1, 1, At, B1); PG8_BAR;
;             PG8_LDB(B0, 1, 0); PG8_SCHED; PG8_LDA(At, 1, 0); PG8_STAGE(PG8_SA(0, 1), a2 + hstep, voffA);
;             PG8_WAIT_L(8); PG8_BAR; PG8_WAIT_L(0); PG8_MMA(0, 0, At, B0); PG8_BAR; PG8_SCHED;
;             PG8_LDB(B1, 1, 1); PG8_STAGE(PG8_SB(1, 0), b3, voffB0);
;             PG8_BAR; PG8_WAIT_L(0); PG8_MMA(0, 1, At, B1); PG8_BAR;
;             PG8_LDA(At, 1, 1); PG8_STAGE(PG8_SA(1, 0), a3, voffA);
;             PG8_BAR; PG8_WAIT_L(0); PG8_MMA(1, 0, At, B0); PG8_BAR; PG8_SCHED;
	s_add_i32 s33, s61, s49
	v_lshl_add_u64 v[234:235], s[42:43], 0, v[136:137]
	s_mov_b32 m0, s33
	v_lshl_add_u64 v[236:237], s[42:43], 0, v[130:131]
	global_load_lds_dwordx4 v[234:235], off
	s_add_i32 m0, s33, 0x2000
	s_nop 0
	global_load_lds_dwordx4 v[236:237], off
	s_waitcnt vmcnt(6)
	s_barrier
	v_mfma_f32_16x16x32_bf16 v[52:55], v[212:215], v[176:179], v[52:55]
	v_mfma_f32_16x16x32_bf16 v[48:51], v[220:223], v[176:179], v[48:51]
	v_mfma_f32_16x16x32_bf16 v[36:39], v[212:215], v[184:187], v[36:39]
	v_mfma_f32_16x16x32_bf16 v[32:35], v[220:223], v[184:187], v[32:35]
	v_mfma_f32_16x16x32_bf16 v[20:23], v[212:215], v[192:195], v[20:23]
	v_mfma_f32_16x16x32_bf16 v[16:19], v[220:223], v[192:195], v[16:19]
	v_mfma_f32_16x16x32_bf16 v[4:7], v[212:215], v[204:207], v[4:7]
	v_mfma_f32_16x16x32_bf16 v[0:3], v[220:223], v[204:207], v[0:3]
	v_mfma_f32_16x16x32_bf16 v[52:55], v[216:219], v[180:183], v[52:55]
	v_mfma_f32_16x16x32_bf16 v[48:51], v[224:227], v[180:183], v[48:51]
	v_mfma_f32_16x16x32_bf16 v[36:39], v[216:219], v[188:191], v[36:39]
	v_mfma_f32_16x16x32_bf16 v[32:35], v[224:227], v[188:191], v[32:35]
	v_mfma_f32_16x16x32_bf16 v[20:23], v[216:219], v[196:199], v[20:23]
	v_mfma_f32_16x16x32_bf16 v[16:19], v[224:227], v[196:199], v[16:19]
	v_mfma_f32_16x16x32_bf16 v[4:7], v[216:219], v[208:211], v[4:7]
	v_mfma_f32_16x16x32_bf16 v[0:3], v[224:227], v[208:211], v[0:3]
	s_add_i32 s33, 0, 0x18000
	v_add_u32_e32 v172, s33, v147
	s_barrier
	ds_read_b128 v[160:163], v172
	ds_read_b128 v[164:167], v172 offset:1024
	ds_read_b128 v[168:171], v172 offset:2048
	ds_read_b128 v[172:175], v172 offset:3072
	s_add_u32 s40, s40, 0x20000
	s_addc_u32 s41, s41, 0
	s_mov_b32 m0, s52
	v_lshl_add_u64 v[212:213], s[40:41], 0, v[138:139]
	ds_read_b128 v[176:179], v158 offset:32768
	ds_read_b128 v[180:183], v158 offset:33792
	ds_read_b128 v[184:187], v158 offset:34816
	ds_read_b128 v[188:191], v158 offset:35840
	ds_read_b128 v[192:195], v158 offset:36864
	ds_read_b128 v[196:199], v158 offset:37888
	ds_read_b128 v[204:207], v158 offset:38912
	ds_read_b128 v[208:211], v158 offset:39936
	global_load_lds_dwordx4 v[212:213], off
	v_lshl_add_u64 v[212:213], s[40:41], 0, v[132:133]
	s_mov_b32 m0, s53
	s_nop 0
	global_load_lds_dwordx4 v[212:213], off
	s_waitcnt lgkmcnt(8)
	s_barrier
	s_waitcnt lgkmcnt(0)
	s_waitcnt lgkmcnt(0)
	v_mfma_f32_16x16x32_bf16 v[124:127], v[160:163], v[176:179], v[124:127]
	v_mfma_f32_16x16x32_bf16 v[120:123], v[168:171], v[176:179], v[120:123]
	v_mfma_f32_16x16x32_bf16 v[108:111], v[160:163], v[184:187], v[108:111]
	v_mfma_f32_16x16x32_bf16 v[104:107], v[168:171], v[184:187], v[104:107]
	v_mfma_f32_16x16x32_bf16 v[92:95], v[160:163], v[192:195], v[92:95]
	v_mfma_f32_16x16x32_bf16 v[88:91], v[168:171], v[192:195], v[88:91]
	v_mfma_f32_16x16x32_bf16 v[76:79], v[160:163], v[204:207], v[76:79]
	v_mfma_f32_16x16x32_bf16 v[72:75], v[168:171], v[204:207], v[72:75]
	v_mfma_f32_16x16x32_bf16 v[124:127], v[164:167], v[180:183], v[124:127]
	v_mfma_f32_16x16x32_bf16 v[120:123], v[172:175], v[180:183], v[120:123]
	v_mfma_f32_16x16x32_bf16 v[108:111], v[164:167], v[188:191], v[108:111]
	v_mfma_f32_16x16x32_bf16 v[104:107], v[172:175], v[188:191], v[104:107]
	v_mfma_f32_16x16x32_bf16 v[92:95], v[164:167], v[196:199], v[92:95]
	v_mfma_f32_16x16x32_bf16 v[88:91], v[172:175], v[196:199], v[88:91]
	v_mfma_f32_16x16x32_bf16 v[76:79], v[164:167], v[208:211], v[76:79]
	v_mfma_f32_16x16x32_bf16 v[72:75], v[172:175], v[208:211], v[72:75]
	s_barrier
	s_add_i32 s40, 0, 0x1c000
	s_add_i32 s33, s33, s49
	v_add_u32_e32 v224, s40, v147
	v_lshl_add_u64 v[200:201], v[200:201], 0, s[8:9]
	s_mov_b32 m0, s33
	ds_read_b128 v[212:215], v224
	ds_read_b128 v[216:219], v224 offset:1024
	ds_read_b128 v[220:223], v224 offset:2048
	ds_read_b128 v[224:227], v224 offset:3072
	global_load_lds_dwordx4 v[200:201], off
	v_lshl_add_u64 v[200:201], v[228:229], 0, s[8:9]
	s_add_i32 m0, s33, 0x2000
	s_nop 0
	global_load_lds_dwordx4 v[200:201], off
	s_barrier
	s_waitcnt lgkmcnt(0)
	s_waitcnt lgkmcnt(0)
	v_mfma_f32_16x16x32_bf16 v[116:119], v[212:215], v[176:179], v[116:119]
	v_mfma_f32_16x16x32_bf16 v[112:115], v[220:223], v[176:179], v[112:115]
	v_mfma_f32_16x16x32_bf16 v[100:103], v[212:215], v[184:187], v[100:103]
	v_mfma_f32_16x16x32_bf16 v[96:99], v[220:223], v[184:187], v[96:99]
	v_mfma_f32_16x16x32_bf16 v[84:87], v[212:215], v[192:195], v[84:87]
	v_mfma_f32_16x16x32_bf16 v[80:83], v[220:223], v[192:195], v[80:83]
	v_mfma_f32_16x16x32_bf16 v[68:71], v[212:215], v[204:207], v[68:71]
	v_mfma_f32_16x16x32_bf16 v[64:67], v[220:223], v[204:207], v[64:67]
	v_mfma_f32_16x16x32_bf16 v[116:119], v[216:219], v[180:183], v[116:119]
	v_mfma_f32_16x16x32_bf16 v[112:115], v[224:227], v[180:183], v[112:115]
	v_mfma_f32_16x16x32_bf16 v[100:103], v[216:219], v[188:191], v[100:103]
	v_mfma_f32_16x16x32_bf16 v[96:99], v[224:227], v[188:191], v[96:99]
	v_mfma_f32_16x16x32_bf16 v[84:87], v[216:219], v[196:199], v[84:87]
	v_mfma_f32_16x16x32_bf16 v[80:83], v[224:227], v[196:199], v[80:83]
	v_mfma_f32_16x16x32_bf16 v[68:71], v[216:219], v[208:211], v[68:71]
	v_mfma_f32_16x16x32_bf16 v[64:67], v[224:227], v[208:211], v[64:67]
	s_mov_b32 m0, s55
	v_lshl_add_u64 v[200:201], v[230:231], 0, s[8:9]
	s_barrier
	ds_read_b128 v[176:179], v158 offset:49152
	ds_read_b128 v[180:183], v158 offset:50176
	ds_read_b128 v[184:187], v158 offset:51200
	ds_read_b128 v[188:191], v158 offset:52224
	ds_read_b128 v[192:195], v158 offset:53248
	ds_read_b128 v[196:199], v158 offset:54272
	ds_read_b128 v[204:207], v158 offset:55296
	ds_read_b128 v[208:211], v158 offset:56320
	global_load_lds_dwordx4 v[200:201], off
	v_lshl_add_u64 v[200:201], v[232:233], 0, s[8:9]
	s_mov_b32 m0, s56
	s_nop 0
	global_load_lds_dwordx4 v[200:201], off
	s_barrier
; __device__ __forceinline__ unsigned cvt_pk_bf16(float lo, float hi) { unsigned r; asm volatile("v_cvt_pk_bf16_f32 %0, %1, %2" : "=v"(r) : "v"(lo), "v"(hi)); return r; }
; #define PG8_STAGE(bufoff, gbase, voff) do { _Pragma("unroll") for (int _i = 0; _i < 2; ++_i) \
;         __builtin_amdgcn_global_load_lds((const unsigned*)((const char*)(gbase) + (voff)[_i]), (LAS unsigned*)(lds + (bufoff) + ldsw + _i * 8192), 16, 0, 0); } while (0)
; #define PG8_WAIT_V(n) asm volatile("s_waitcnt vmcnt(" #n ")" ::: "memory")
; #define PG8_WAIT_L(n) asm volatile("s_waitcnt lgkmcnt(" #n ")" ::: "memory")
; #define PG8_BAR __builtin_amdgcn_s_barrier()
; #define PG8_SCHED __builtin_amdgcn_sched_barrier(0)
;     __device__ __forceinline__ void operator()(const f32x4 (&acc)[2][2][4][2], const Unit& u, int wr, int wc, int fr, int fq) const {
;         const int row0 = u.pm * BM + wr * 64 + fr; const int col0 = u.pn * BM + wc * 64 + 16 * fq;
; #pragma unroll
;         for (int ai = 0; ai < 2; ++ai)
; #pragma unroll
;             for (int m = 0; m < 4; ++m) { const int row = row0 + ai * HALF + m * 16;
;                 const float rs = ssin ? __builtin_amdgcn_rsqf(ssin[row] * (1.f / D) + EPS) : 1.0f; float sq = 0.f; u32x4 w[2];
; #pragma unroll
;                 for (int bj = 0; bj < 2; ++bj) { f32x4 v0 = acc[ai][bj][m][0] * rs, v1 = acc[ai][bj][m][1] * rs;
;                     if (ACT == 1) {
; #pragma unroll
;                         for (int j = 0; j < 4; ++j) { const float a = fmaxf(v0[j], 0.f), b = fmaxf(v1[j], 0.f); v0[j] = a * a; v1[j] = b * b; } }
;                     sq += (v0[0] * v0[0] + v0[1] * v0[1]) + (v0[2] * v0[2] + v0[3] * v0[3]) + (v1[0] * v1[0] + v1[1] * v1[1]) + (v1[2] * v1[2] + v1[3] * v1[3]);
;                     w[bj].x = cvt_pk_bf16(v0[0], v0[1]); w[bj].y = cvt_pk_bf16(v0[2], v0[3]); w[bj].z = cvt_pk_bf16(v1[0], v1[1]); w[bj].w = cvt_pk_bf16(v1[2], v1[3]); }
;                 store_pair_lines(O, ldc, row, fr, col0, w[0], w[1]);
; template <class Epi>
; __device__ __forceinline__ void gemm_phase(LAS unsigned char* lds, const Gemm g, const StaticOrder& S, const Epi& E) {
;     ...
;             PG8_BAR; PG8_WAIT_L(0); PG8_MMA(1, 0, At, B0); PG8_BAR; PG8_SCHED;
;             PG8_STAGE(PG8_SB(1, 1), b3, voffB1);
;             PG8_WAIT_V(6); PG8_BAR; PG8_MMA(1, 1, At, B1); PG8_BAR;
	s_waitcnt lgkmcnt(0)
	s_waitcnt lgkmcnt(0)
	v_mfma_f32_16x16x32_bf16 v[60:63], v[160:163], v[176:179], v[60:63]
	v_mfma_f32_16x16x32_bf16 v[56:59], v[168:171], v[176:179], v[56:59]
	v_mfma_f32_16x16x32_bf16 v[44:47], v[160:163], v[184:187], v[44:47]
	v_mfma_f32_16x16x32_bf16 v[40:43], v[168:171], v[184:187], v[40:43]
	v_mfma_f32_16x16x32_bf16 v[28:31], v[160:163], v[192:195], v[28:31]
	v_mfma_f32_16x16x32_bf16 v[24:27], v[168:171], v[192:195], v[24:27]
	v_mfma_f32_16x16x32_bf16 v[12:15], v[160:163], v[204:207], v[12:15]
	v_mfma_f32_16x16x32_bf16 v[8:11], v[168:171], v[204:207], v[8:11]
	v_mfma_f32_16x16x32_bf16 v[60:63], v[164:167], v[180:183], v[60:63]
	v_mfma_f32_16x16x32_bf16 v[56:59], v[172:175], v[180:183], v[56:59]
	v_mfma_f32_16x16x32_bf16 v[44:47], v[164:167], v[188:191], v[44:47]
	v_mfma_f32_16x16x32_bf16 v[40:43], v[172:175], v[188:191], v[40:43]
	v_mfma_f32_16x16x32_bf16 v[28:31], v[164:167], v[196:199], v[28:31]
	v_mfma_f32_16x16x32_bf16 v[24:27], v[172:175], v[196:199], v[24:27]
	v_mfma_f32_16x16x32_bf16 v[12:15], v[164:167], v[208:211], v[12:15]
	v_mfma_f32_16x16x32_bf16 v[8:11], v[172:175], v[208:211], v[8:11]
	s_barrier
	s_add_i32 s33, s40, s49
	v_lshl_add_u64 v[160:161], v[234:235], 0, s[8:9]
	s_mov_b32 m0, s33
	s_nop 0
	global_load_lds_dwordx4 v[160:161], off
	v_lshl_add_u64 v[160:161], v[236:237], 0, s[8:9]
	s_add_i32 m0, s33, 0x2000
	s_nop 0
	global_load_lds_dwordx4 v[160:161], off
	s_waitcnt vmcnt(6)
	s_barrier
	v_mfma_f32_16x16x32_bf16 v[52:55], v[212:215], v[176:179], v[52:55]
	v_mfma_f32_16x16x32_bf16 v[48:51], v[220:223], v[176:179], v[48:51]
	v_mfma_f32_16x16x32_bf16 v[36:39], v[212:215], v[184:187], v[36:39]
	v_mfma_f32_16x16x32_bf16 v[32:35], v[220:223], v[184:187], v[32:35]
	v_mfma_f32_16x16x32_bf16 v[20:23], v[212:215], v[192:195], v[20:23]
	v_mfma_f32_16x16x32_bf16 v[16:19], v[220:223], v[192:195], v[16:19]
	v_mfma_f32_16x16x32_bf16 v[4:7], v[212:215], v[204:207], v[4:7]
	v_mfma_f32_16x16x32_bf16 v[0:3], v[220:223], v[204:207], v[0:3]
	v_mfma_f32_16x16x32_bf16 v[52:55], v[216:219], v[180:183], v[52:55]
	v_mfma_f32_16x16x32_bf16 v[48:51], v[224:227], v[180:183], v[48:51]
	v_mfma_f32_16x16x32_bf16 v[36:39], v[216:219], v[188:191], v[36:39]
	v_mfma_f32_16x16x32_bf16 v[32:35], v[224:227], v[188:191], v[32:35]
	v_mfma_f32_16x16x32_bf16 v[20:23], v[216:219], v[196:199], v[20:23]
	v_mfma_f32_16x16x32_bf16 v[16:19], v[224:227], v[196:199], v[16:19]
	v_mfma_f32_16x16x32_bf16 v[4:7], v[216:219], v[208:211], v[4:7]
	v_mfma_f32_16x16x32_bf16 v[0:3], v[224:227], v[208:211], v[0:3]
	s_add_i32 s68, s68, 2
	s_add_u32 s38, s38, 0x100
	s_addc_u32 s39, s39, 0
	s_add_u32 s66, s66, 0x100
	s_addc_u32 s67, s67, 0
	s_cmp_gt_u32 s68, 5
	s_barrier
	s_cbranch_scc0 .LBB0_234
	s_lshl_b32 s11, s36, 8
	v_cvt_pk_bf16_f32 v124, v124, v125
	v_cvt_pk_bf16_f32 v125, v126, v127
	v_cvt_pk_bf16_f32 v120, v120, v121
	v_cvt_pk_bf16_f32 v121, v122, v123
	v_cvt_pk_bf16_f32 v122, v116, v117
	v_cvt_pk_bf16_f32 v123, v118, v119
	v_cvt_pk_bf16_f32 v112, v112, v113
	v_cvt_pk_bf16_f32 v113, v114, v115
	v_mov_b32_e32 v114, 0
	v_mov_b32_e32 v115, 0
	v_mov_b32_e32 v126, 0
	v_mov_b32_e32 v127, 0
	v_mov_b32_e32 v118, 0
	v_mov_b32_e32 v119, 0
	s_add_i32 s11, s11, s57
	v_lshl_or_b32 v162, s63, 8, v156
	v_mov_b32_dpp v114, v124 row_ror:8 row_mask:0xf bank_mask:0xf
	v_mov_b32_dpp v115, v125 row_ror:8 row_mask:0xf bank_mask:0xf
	v_mov_b32_dpp v126, v120 row_ror:8 row_mask:0xf bank_mask:0xf
	v_mov_b32_dpp v127, v121 row_ror:8 row_mask:0xf bank_mask:0xf
	v_mov_b32_e32 v116, 0
	v_mov_b32_e32 v117, 0
	v_mov_b32_dpp v118, v112 row_ror:8 row_mask:0xf bank_mask:0xf
	v_mov_b32_dpp v119, v113 row_ror:8 row_mask:0xf bank_mask:0xf
	v_ashrrev_i32_e32 v163, 31, v162
	v_mov_b32_dpp v116, v122 row_ror:8 row_mask:0xf bank_mask:0xf
	v_mov_b32_dpp v117, v123 row_ror:8 row_mask:0xf bank_mask:0xf
	v_cndmask_b32_e64 v118, v118, v120, s[4:5]
	v_cndmask_b32_e64 v119, v119, v121, s[4:5]
	v_cndmask_b32_e64 v120, v122, v114, s[4:5]
	v_cndmask_b32_e64 v121, v123, v115, s[4:5]
	v_cndmask_b32_e64 v122, v112, v126, s[4:5]
	v_cndmask_b32_e64 v123, v113, v127, s[4:5]
	v_or_b32_e32 v126, s11, v148
	v_mov_b64_e32 v[112:113], s[6:7]
	v_cndmask_b32_e64 v116, v116, v124, s[4:5]
	v_cndmask_b32_e64 v117, v117, v125, s[4:5]
	v_mad_i64_i32 v[124:125], s[38:39], v126, s62, v[112:113]
	v_lshlrev_b64 v[114:115], 1, v[162:163]
	v_lshl_add_u64 v[124:125], v[124:125], 0, v[114:115]
	global_store_dwordx4 v[124:125], v[116:119], off
	v_or_b32_e32 v160, s11, v146
	s_and_b64 vcc, exec, s[30:31]
	v_or_b32_e32 v116, 8, v126
	v_mad_i64_i32 v[116:117], s[38:39], v116, s62, v[112:113]
	v_lshl_add_u64 v[116:117], v[116:117], 0, v[114:115]
	global_store_dwordx4 v[116:117], v[120:123], off
	v_cvt_pk_bf16_f32 v108, v108, v109
	v_cvt_pk_bf16_f32 v109, v110, v111
	v_cvt_pk_bf16_f32 v104, v104, v105
	v_cvt_pk_bf16_f32 v105, v106, v107
	v_mov_b32_e32 v106, 0
	v_cvt_pk_bf16_f32 v100, v100, v101
	v_cvt_pk_bf16_f32 v101, v102, v103
	v_cvt_pk_bf16_f32 v102, v96, v97
	v_cvt_pk_bf16_f32 v103, v98, v99
	v_mov_b32_e32 v96, 0
	s_nop 0
	v_mov_b32_dpp v106, v108 row_ror:8 row_mask:0xf bank_mask:0xf
	v_mov_b32_e32 v98, 0
	v_mov_b32_e32 v99, 0
	v_mov_b32_e32 v110, 0
	v_mov_b32_e32 v111, 0
	v_mov_b32_dpp v96, v100 row_ror:8 row_mask:0xf bank_mask:0xf
	v_mov_b32_e32 v97, 0
	v_mov_b32_dpp v98, v102 row_ror:8 row_mask:0xf bank_mask:0xf
	v_mov_b32_dpp v99, v103 row_ror:8 row_mask:0xf bank_mask:0xf
	v_cndmask_b32_e64 v100, v100, v106, s[4:5]
	v_add_u32_e32 v106, v149, v160
	v_mov_b32_dpp v110, v104 row_ror:8 row_mask:0xf bank_mask:0xf
	v_mov_b32_dpp v111, v105 row_ror:8 row_mask:0xf bank_mask:0xf
	v_mov_b32_dpp v97, v101 row_ror:8 row_mask:0xf bank_mask:0xf
; __device__ __forceinline__ unsigned cvt_pk_bf16(float lo, float hi) { unsigned r; asm volatile("v_cvt_pk_bf16_f32 %0, %1, %2" : "=v"(r) : "v"(lo), "v"(hi)); return r; }
; __device__ __forceinline__ unsigned dpp_ror8(unsigned x) { return (unsigned)__builtin_amdgcn_update_dpp(0, (int)x, 0x128, 0xf, 0xf, false); }
; __device__ __forceinline__ void store_pair_lines(bf16_t* O, int ldc, int row, int fr, int col0, u32x4 wA, u32x4 wB) {
;     const u32x4 sA = {dpp_ror8(wA.x), dpp_ror8(wA.y), dpp_ror8(wA.z), dpp_ror8(wA.w)}, sB = {dpp_ror8(wB.x), dpp_ror8(wB.y), dpp_ror8(wB.z), dpp_ror8(wB.w)};
;     const bool lo = fr < 8;
;     const u32x4 o1 = lo ? wA : sB, o2 = lo ? sA : wB;
;     const int r1 = row - fr + (fr & 7), cb = col0 + (lo ? 0 : 8);
;     *(u32x4*)(O + (size_t)r1 * ldc + cb) = o1;
;     *(u32x4*)(O + (size_t)(r1 + 8) * ldc + cb) = o2;
;     __device__ __forceinline__ void operator()(const f32x4 (&acc)[2][2][4][2], const Unit& u, int wr, int wc, int fr, int fq) const {
;         const int row0 = u.pm * BM + wr * 64 + fr; const int col0 = u.pn * BM + wc * 64 + 16 * fq;
; #pragma unroll
;         for (int ai = 0; ai < 2; ++ai)
; #pragma unroll
;             for (int m = 0; m < 4; ++m) { const int row = row0 + ai * HALF + m * 16;
;                 const float rs = ssin ? __builtin_amdgcn_rsqf(ssin[row] * (1.f / D) + EPS) : 1.0f; float sq = 0.f; u32x4 w[2];
; #pragma unroll
;                 for (int bj = 0; bj < 2; ++bj) { f32x4 v0 = acc[ai][bj][m][0] * rs, v1 = acc[ai][bj][m][1] * rs;
;                     if (ACT == 1) {
; #pragma unroll
;                         for (int j = 0; j < 4; ++j) { const float a = fmaxf(v0[j], 0.f), b = fmaxf(v1[j], 0.f); v0[j] = a * a; v1[j] = b * b; } }
;                     sq += (v0[0] * v0[0] + v0[1] * v0[1]) + (v0[2] * v0[2] + v0[3] * v0[3]) + (v1[0] * v1[0] + v1[1] * v1[1]) + (v1[2] * v1[2] + v1[3] * v1[3]);
;                     w[bj].x = cvt_pk_bf16(v0[0], v0[1]); w[bj].y = cvt_pk_bf16(v0[2], v0[3]); w[bj].z = cvt_pk_bf16(v1[0], v1[1]); w[bj].w = cvt_pk_bf16(v1[2], v1[3]); }
;                 store_pair_lines(O, ldc, row, fr, col0, w[0], w[1]);
	v_cndmask_b32_e64 v98, v98, v104, s[4:5]
	v_cndmask_b32_e64 v99, v99, v105, s[4:5]
	v_mad_i64_i32 v[104:105], s[38:39], v106, s62, v[112:113]
	v_cndmask_b32_e64 v96, v96, v108, s[4:5]
	v_cndmask_b32_e64 v97, v97, v109, s[4:5]
	v_lshl_add_u64 v[104:105], v[104:105], 0, v[114:115]
	v_mov_b32_e32 v107, 0
	global_store_dwordx4 v[104:105], v[96:99], off
	v_cndmask_b32_e64 v102, v102, v110, s[4:5]
	v_mov_b32_dpp v107, v109 row_ror:8 row_mask:0xf bank_mask:0xf
	v_add_u32_e32 v96, 8, v106
	v_mad_i64_i32 v[96:97], s[38:39], v96, s62, v[112:113]
	v_cndmask_b32_e64 v101, v101, v107, s[4:5]
	v_cndmask_b32_e64 v103, v103, v111, s[4:5]
	v_lshl_add_u64 v[96:97], v[96:97], 0, v[114:115]
	global_store_dwordx4 v[96:97], v[100:103], off
	v_cvt_pk_bf16_f32 v92, v92, v93
	v_cvt_pk_bf16_f32 v93, v94, v95
	v_cvt_pk_bf16_f32 v88, v88, v89
	v_cvt_pk_bf16_f32 v89, v90, v91
	v_mov_b32_e32 v90, 0
	v_cvt_pk_bf16_f32 v84, v84, v85
	v_cvt_pk_bf16_f32 v85, v86, v87
	v_cvt_pk_bf16_f32 v86, v80, v81
	v_cvt_pk_bf16_f32 v87, v82, v83
	v_mov_b32_e32 v80, 0
	s_nop 0
	v_mov_b32_dpp v90, v92 row_ror:8 row_mask:0xf bank_mask:0xf
	v_mov_b32_e32 v82, 0
	v_mov_b32_e32 v83, 0
	v_mov_b32_e32 v94, 0
	v_mov_b32_e32 v95, 0
	v_mov_b32_dpp v80, v84 row_ror:8 row_mask:0xf bank_mask:0xf
	v_mov_b32_e32 v81, 0
	v_mov_b32_dpp v82, v86 row_ror:8 row_mask:0xf bank_mask:0xf
	v_mov_b32_dpp v83, v87 row_ror:8 row_mask:0xf bank_mask:0xf
	v_cndmask_b32_e64 v84, v84, v90, s[4:5]
	v_add_u32_e32 v90, v150, v160
	v_mov_b32_dpp v94, v88 row_ror:8 row_mask:0xf bank_mask:0xf
	v_mov_b32_dpp v95, v89 row_ror:8 row_mask:0xf bank_mask:0xf
	v_mov_b32_dpp v81, v85 row_ror:8 row_mask:0xf bank_mask:0xf
	v_cndmask_b32_e64 v82, v82, v88, s[4:5]
	v_cndmask_b32_e64 v83, v83, v89, s[4:5]
	v_mad_i64_i32 v[88:89], s[38:39], v90, s62, v[112:113]
	v_cndmask_b32_e64 v80, v80, v92, s[4:5]
	v_cndmask_b32_e64 v81, v81, v93, s[4:5]
	v_lshl_add_u64 v[88:89], v[88:89], 0, v[114:115]
	v_mov_b32_e32 v91, 0
	global_store_dwordx4 v[88:89], v[80:83], off
	v_cndmask_b32_e64 v86, v86, v94, s[4:5]
	v_mov_b32_dpp v91, v93 row_ror:8 row_mask:0xf bank_mask:0xf
	v_add_u32_e32 v80, 8, v90
	v_mad_i64_i32 v[80:81], s[38:39], v80, s62, v[112:113]
	v_cndmask_b32_e64 v85, v85, v91, s[4:5]
	v_cndmask_b32_e64 v87, v87, v95, s[4:5]
	v_lshl_add_u64 v[80:81], v[80:81], 0, v[114:115]
	global_store_dwordx4 v[80:81], v[84:87], off
	v_cvt_pk_bf16_f32 v76, v76, v77
	v_cvt_pk_bf16_f32 v77, v78, v79
	v_cvt_pk_bf16_f32 v72, v72, v73
	v_cvt_pk_bf16_f32 v73, v74, v75
	v_mov_b32_e32 v74, 0
	v_cvt_pk_bf16_f32 v68, v68, v69
	v_cvt_pk_bf16_f32 v69, v70, v71
	v_cvt_pk_bf16_f32 v70, v64, v65
	v_cvt_pk_bf16_f32 v71, v66, v67
	v_mov_b32_e32 v64, 0
	s_nop 0
	v_mov_b32_dpp v74, v76 row_ror:8 row_mask:0xf bank_mask:0xf
	v_mov_b32_e32 v66, 0
	v_mov_b32_e32 v67, 0
	v_mov_b32_e32 v78, 0
	v_mov_b32_e32 v79, 0
	v_mov_b32_dpp v64, v68 row_ror:8 row_mask:0xf bank_mask:0xf
	v_mov_b32_e32 v65, 0
	v_mov_b32_dpp v66, v70 row_ror:8 row_mask:0xf bank_mask:0xf
	v_mov_b32_dpp v67, v71 row_ror:8 row_mask:0xf bank_mask:0xf
	v_cndmask_b32_e64 v68, v68, v74, s[4:5]
	v_add_u32_e32 v74, v151, v160
	v_mov_b32_dpp v78, v72 row_ror:8 row_mask:0xf bank_mask:0xf
	v_mov_b32_dpp v79, v73 row_ror:8 row_mask:0xf bank_mask:0xf
	v_mov_b32_dpp v65, v69 row_ror:8 row_mask:0xf bank_mask:0xf
	v_cndmask_b32_e64 v66, v66, v72, s[4:5]
	v_cndmask_b32_e64 v67, v67, v73, s[4:5]
	v_mad_i64_i32 v[72:73], s[38:39], v74, s62, v[112:113]
	v_cndmask_b32_e64 v64, v64, v76, s[4:5]
	v_cndmask_b32_e64 v65, v65, v77, s[4:5]
	v_lshl_add_u64 v[72:73], v[72:73], 0, v[114:115]
	v_mov_b32_e32 v75, 0
	global_store_dwordx4 v[72:73], v[64:67], off
	v_cndmask_b32_e64 v70, v70, v78, s[4:5]
	v_mov_b32_dpp v75, v77 row_ror:8 row_mask:0xf bank_mask:0xf
	v_add_u32_e32 v64, 8, v74
	v_mad_i64_i32 v[64:65], s[38:39], v64, s62, v[112:113]
	v_cndmask_b32_e64 v69, v69, v75, s[4:5]
	v_cndmask_b32_e64 v71, v71, v79, s[4:5]
	v_lshl_add_u64 v[64:65], v[64:65], 0, v[114:115]
	global_store_dwordx4 v[64:65], v[68:71], off
	v_cvt_pk_bf16_f32 v60, v60, v61
	v_cvt_pk_bf16_f32 v61, v62, v63
	v_cvt_pk_bf16_f32 v56, v56, v57
	v_cvt_pk_bf16_f32 v57, v58, v59
	v_mov_b32_e32 v58, 0
	v_cvt_pk_bf16_f32 v52, v52, v53
	v_cvt_pk_bf16_f32 v53, v54, v55
	v_cvt_pk_bf16_f32 v54, v48, v49
	v_cvt_pk_bf16_f32 v55, v50, v51
	v_mov_b32_e32 v48, 0
	s_nop 0
	v_mov_b32_dpp v58, v60 row_ror:8 row_mask:0xf bank_mask:0xf
	v_mov_b32_e32 v50, 0
	v_mov_b32_e32 v51, 0
	v_mov_b32_e32 v62, 0
	v_mov_b32_e32 v63, 0
	v_mov_b32_dpp v48, v52 row_ror:8 row_mask:0xf bank_mask:0xf
	v_mov_b32_e32 v49, 0
	v_mov_b32_dpp v50, v54 row_ror:8 row_mask:0xf bank_mask:0xf
	v_mov_b32_dpp v51, v55 row_ror:8 row_mask:0xf bank_mask:0xf
	v_cndmask_b32_e64 v52, v52, v58, s[4:5]
	v_add_u32_e32 v58, v152, v160
	v_mov_b32_dpp v62, v56 row_ror:8 row_mask:0xf bank_mask:0xf
	v_mov_b32_dpp v63, v57 row_ror:8 row_mask:0xf bank_mask:0xf
	v_mov_b32_dpp v49, v53 row_ror:8 row_mask:0xf bank_mask:0xf
	v_cndmask_b32_e64 v50, v50, v56, s[4:5]
	v_cndmask_b32_e64 v51, v51, v57, s[4:5]
	v_mad_i64_i32 v[56:57], s[38:39], v58, s62, v[112:113]
	v_cndmask_b32_e64 v48, v48, v60, s[4:5]
	v_cndmask_b32_e64 v49, v49, v61, s[4:5]
	v_lshl_add_u64 v[56:57], v[56:57], 0, v[114:115]
	v_mov_b32_e32 v59, 0
	global_store_dwordx4 v[56:57], v[48:51], off
	v_cndmask_b32_e64 v54, v54, v62, s[4:5]
; __device__ __forceinline__ unsigned cvt_pk_bf16(float lo, float hi) { unsigned r; asm volatile("v_cvt_pk_bf16_f32 %0, %1, %2" : "=v"(r) : "v"(lo), "v"(hi)); return r; }
; __device__ __forceinline__ unsigned dpp_ror8(unsigned x) { return (unsigned)__builtin_amdgcn_update_dpp(0, (int)x, 0x128, 0xf, 0xf, false); }
; __device__ __forceinline__ void store_pair_lines(bf16_t* O, int ldc, int row, int fr, int col0, u32x4 wA, u32x4 wB) {
;     const u32x4 sA = {dpp_ror8(wA.x), dpp_ror8(wA.y), dpp_ror8(wA.z), dpp_ror8(wA.w)}, sB = {dpp_ror8(wB.x), dpp_ror8(wB.y), dpp_ror8(wB.z), dpp_ror8(wB.w)};
;     const bool lo = fr < 8;
;     const u32x4 o1 = lo ? wA : sB, o2 = lo ? sA : wB;
;     const int r1 = row - fr + (fr & 7), cb = col0 + (lo ? 0 : 8);
;     *(u32x4*)(O + (size_t)r1 * ldc + cb) = o1;
;     *(u32x4*)(O + (size_t)(r1 + 8) * ldc + cb) = o2;
;     __device__ __forceinline__ void operator()(const f32x4 (&acc)[2][2][4][2], const Unit& u, int wr, int wc, int fr, int fq) const {
;         const int row0 = u.pm * BM + wr * 64 + fr; const int col0 = u.pn * BM + wc * 64 + 16 * fq;
; #pragma unroll
;         for (int ai = 0; ai < 2; ++ai)
; #pragma unroll
;             for (int m = 0; m < 4; ++m) { const int row = row0 + ai * HALF + m * 16;
;                 const float rs = ssin ? __builtin_amdgcn_rsqf(ssin[row] * (1.f / D) + EPS) : 1.0f; float sq = 0.f; u32x4 w[2];
; #pragma unroll
;                 for (int bj = 0; bj < 2; ++bj) { f32x4 v0 = acc[ai][bj][m][0] * rs, v1 = acc[ai][bj][m][1] * rs;
;                     if (ACT == 1) {
; #pragma unroll
;                         for (int j = 0; j < 4; ++j) { const float a = fmaxf(v0[j], 0.f), b = fmaxf(v1[j], 0.f); v0[j] = a * a; v1[j] = b * b; } }
;                     sq += (v0[0] * v0[0] + v0[1] * v0[1]) + (v0[2] * v0[2] + v0[3] * v0[3]) + (v1[0] * v1[0] + v1[1] * v1[1]) + (v1[2] * v1[2] + v1[3] * v1[3]);
;                     w[bj].x = cvt_pk_bf16(v0[0], v0[1]); w[bj].y = cvt_pk_bf16(v0[2], v0[3]); w[bj].z = cvt_pk_bf16(v1[0], v1[1]); w[bj].w = cvt_pk_bf16(v1[2], v1[3]); }
;                 store_pair_lines(O, ldc, row, fr, col0, w[0], w[1]);
;                 if (ssout) { sq += __shfl_xor(sq, 16); sq += __shfl_xor(sq, 32); if (fq == 0) unsafeAtomicAdd(ssout + row, sq); } }
	v_mov_b32_dpp v59, v61 row_ror:8 row_mask:0xf bank_mask:0xf
	v_add_u32_e32 v48, 8, v58
	v_mad_i64_i32 v[48:49], s[38:39], v48, s62, v[112:113]
	v_cndmask_b32_e64 v53, v53, v59, s[4:5]
	v_cndmask_b32_e64 v55, v55, v63, s[4:5]
	v_lshl_add_u64 v[48:49], v[48:49], 0, v[114:115]
	global_store_dwordx4 v[48:49], v[52:55], off
	v_cvt_pk_bf16_f32 v44, v44, v45
	v_cvt_pk_bf16_f32 v45, v46, v47
	v_cvt_pk_bf16_f32 v40, v40, v41
	v_cvt_pk_bf16_f32 v41, v42, v43
	v_mov_b32_e32 v42, 0
	v_cvt_pk_bf16_f32 v36, v36, v37
	v_cvt_pk_bf16_f32 v37, v38, v39
	v_cvt_pk_bf16_f32 v38, v32, v33
	v_cvt_pk_bf16_f32 v39, v34, v35
	v_mov_b32_e32 v32, 0
	s_nop 0
	v_mov_b32_dpp v42, v44 row_ror:8 row_mask:0xf bank_mask:0xf
	v_mov_b32_e32 v34, 0
	v_mov_b32_e32 v35, 0
	v_mov_b32_e32 v46, 0
	v_mov_b32_e32 v47, 0
	v_mov_b32_dpp v32, v36 row_ror:8 row_mask:0xf bank_mask:0xf
	v_mov_b32_e32 v33, 0
	v_mov_b32_dpp v34, v38 row_ror:8 row_mask:0xf bank_mask:0xf
	v_mov_b32_dpp v35, v39 row_ror:8 row_mask:0xf bank_mask:0xf
	v_cndmask_b32_e64 v36, v36, v42, s[4:5]
	v_add_u32_e32 v42, v153, v160
	v_mov_b32_dpp v46, v40 row_ror:8 row_mask:0xf bank_mask:0xf
	v_mov_b32_dpp v47, v41 row_ror:8 row_mask:0xf bank_mask:0xf
	v_mov_b32_dpp v33, v37 row_ror:8 row_mask:0xf bank_mask:0xf
	v_cndmask_b32_e64 v34, v34, v40, s[4:5]
	v_cndmask_b32_e64 v35, v35, v41, s[4:5]
	v_mad_i64_i32 v[40:41], s[38:39], v42, s62, v[112:113]
	v_cndmask_b32_e64 v32, v32, v44, s[4:5]
	v_cndmask_b32_e64 v33, v33, v45, s[4:5]
	v_lshl_add_u64 v[40:41], v[40:41], 0, v[114:115]
	v_mov_b32_e32 v43, 0
	global_store_dwordx4 v[40:41], v[32:35], off
	v_cndmask_b32_e64 v38, v38, v46, s[4:5]
	v_mov_b32_dpp v43, v45 row_ror:8 row_mask:0xf bank_mask:0xf
	v_add_u32_e32 v32, 8, v42
	v_mad_i64_i32 v[32:33], s[38:39], v32, s62, v[112:113]
	v_cndmask_b32_e64 v37, v37, v43, s[4:5]
	v_cndmask_b32_e64 v39, v39, v47, s[4:5]
	v_lshl_add_u64 v[32:33], v[32:33], 0, v[114:115]
	global_store_dwordx4 v[32:33], v[36:39], off
	v_cvt_pk_bf16_f32 v28, v28, v29
	v_cvt_pk_bf16_f32 v29, v30, v31
	v_cvt_pk_bf16_f32 v24, v24, v25
	v_cvt_pk_bf16_f32 v25, v26, v27
	v_mov_b32_e32 v26, 0
	v_cvt_pk_bf16_f32 v20, v20, v21
	v_cvt_pk_bf16_f32 v21, v22, v23
	v_cvt_pk_bf16_f32 v22, v16, v17
	v_cvt_pk_bf16_f32 v23, v18, v19
	v_mov_b32_e32 v16, 0
	s_nop 0
	v_mov_b32_dpp v26, v28 row_ror:8 row_mask:0xf bank_mask:0xf
	v_mov_b32_e32 v18, 0
	v_mov_b32_e32 v19, 0
	v_mov_b32_e32 v30, 0
	v_mov_b32_e32 v31, 0
	v_mov_b32_dpp v16, v20 row_ror:8 row_mask:0xf bank_mask:0xf
	v_mov_b32_e32 v17, 0
	v_mov_b32_dpp v18, v22 row_ror:8 row_mask:0xf bank_mask:0xf
	v_mov_b32_dpp v19, v23 row_ror:8 row_mask:0xf bank_mask:0xf
	v_cndmask_b32_e64 v20, v20, v26, s[4:5]
	v_add_u32_e32 v26, v154, v160
	v_mov_b32_dpp v30, v24 row_ror:8 row_mask:0xf bank_mask:0xf
	v_mov_b32_dpp v31, v25 row_ror:8 row_mask:0xf bank_mask:0xf
	v_mov_b32_dpp v17, v21 row_ror:8 row_mask:0xf bank_mask:0xf
	v_cndmask_b32_e64 v18, v18, v24, s[4:5]
	v_cndmask_b32_e64 v19, v19, v25, s[4:5]
	v_mad_i64_i32 v[24:25], s[38:39], v26, s62, v[112:113]
	v_cndmask_b32_e64 v16, v16, v28, s[4:5]
	v_cndmask_b32_e64 v17, v17, v29, s[4:5]
	v_lshl_add_u64 v[24:25], v[24:25], 0, v[114:115]
	v_mov_b32_e32 v27, 0
	global_store_dwordx4 v[24:25], v[16:19], off
	v_cndmask_b32_e64 v22, v22, v30, s[4:5]
	v_mov_b32_dpp v27, v29 row_ror:8 row_mask:0xf bank_mask:0xf
	v_add_u32_e32 v16, 8, v26
	v_mad_i64_i32 v[16:17], s[38:39], v16, s62, v[112:113]
	v_cndmask_b32_e64 v21, v21, v27, s[4:5]
	v_cndmask_b32_e64 v23, v23, v31, s[4:5]
	v_lshl_add_u64 v[16:17], v[16:17], 0, v[114:115]
	global_store_dwordx4 v[16:17], v[20:23], off
	v_cvt_pk_bf16_f32 v12, v12, v13
	v_cvt_pk_bf16_f32 v13, v14, v15
	v_cvt_pk_bf16_f32 v8, v8, v9
	v_cvt_pk_bf16_f32 v9, v10, v11
	v_mov_b32_e32 v10, 0
	v_cvt_pk_bf16_f32 v4, v4, v5
	v_cvt_pk_bf16_f32 v5, v6, v7
	v_cvt_pk_bf16_f32 v6, v0, v1
	v_cvt_pk_bf16_f32 v7, v2, v3
	v_mov_b32_e32 v0, 0
	s_nop 0
	v_mov_b32_dpp v10, v12 row_ror:8 row_mask:0xf bank_mask:0xf
	v_mov_b32_e32 v2, 0
	v_mov_b32_e32 v3, 0
	v_mov_b32_e32 v14, 0
	v_mov_b32_e32 v15, 0
	v_mov_b32_dpp v0, v4 row_ror:8 row_mask:0xf bank_mask:0xf
	v_mov_b32_e32 v1, 0
	v_mov_b32_dpp v2, v6 row_ror:8 row_mask:0xf bank_mask:0xf
	v_mov_b32_dpp v3, v7 row_ror:8 row_mask:0xf bank_mask:0xf
	v_cndmask_b32_e64 v4, v4, v10, s[4:5]
	v_add_u32_e32 v10, v155, v160
	v_mov_b32_dpp v14, v8 row_ror:8 row_mask:0xf bank_mask:0xf
	v_mov_b32_dpp v15, v9 row_ror:8 row_mask:0xf bank_mask:0xf
	v_mov_b32_dpp v1, v5 row_ror:8 row_mask:0xf bank_mask:0xf
	v_cndmask_b32_e64 v2, v2, v8, s[4:5]
	v_cndmask_b32_e64 v3, v3, v9, s[4:5]
	v_mad_i64_i32 v[8:9], s[38:39], v10, s62, v[112:113]
	v_cndmask_b32_e64 v0, v0, v12, s[4:5]
	v_cndmask_b32_e64 v1, v1, v13, s[4:5]
	v_lshl_add_u64 v[8:9], v[8:9], 0, v[114:115]
	v_mov_b32_e32 v11, 0
	global_store_dwordx4 v[8:9], v[0:3], off
	v_cndmask_b32_e64 v6, v6, v14, s[4:5]
	v_mov_b32_dpp v11, v13 row_ror:8 row_mask:0xf bank_mask:0xf
	v_add_u32_e32 v0, 8, v10
	v_mad_i64_i32 v[0:1], s[38:39], v0, s62, v[112:113]
	v_cndmask_b32_e64 v5, v5, v11, s[4:5]
	v_cndmask_b32_e64 v7, v7, v15, s[4:5]
	v_lshl_add_u64 v[0:1], v[0:1], 0, v[114:115]
	s_mov_b32 s63, s10
	s_mov_b32 s36, s16
	s_mov_b64 s[40:41], s[34:35]
	s_mov_b64 s[38:39], s[18:19]
	global_store_dwordx4 v[0:1], v[4:7], off
	s_cbranch_vccz .LBB0_230
	s_waitcnt vmcnt(0)
	s_cmpk_gt_u32 s44, 0xff
	s_cbranch_scc1 .LBB0_238
	s_barrier

; #define PG8_STAGE(bufoff, gbase, voff) do { _Pragma("unroll") for (int _i = 0; _i < 2; ++_i) \
;         __builtin_amdgcn_global_load_lds((const unsigned*)((const char*)(gbase) + (voff)[_i]), (LAS unsigned*)(lds + (bufoff) + ldsw + _i * 8192), 16, 0, 0); } while (0)
; #define PG8_LDA(dst, b, h) do { _Pragma("unroll") for (int m = 0; m < 4; ++m) _Pragma("unroll") for (int k = 0; k < 2; ++k) dst[m][k] = *(const LAS bf16x8*)(lds + PG8_SA(b, h) + aoff + m * 2048 + k * 1024); } while (0)
; #define PG8_LDB(dst, b, h) do { _Pragma("unroll") for (int n = 0; n < 2; ++n) _Pragma("unroll") for (int k = 0; k < 2; ++k) dst[n][k] = *(const LAS bf16x8*)(lds + PG8_SB(b, h) + boff + n * 2048 + k * 1024); } while (0)
; #define PG8_WAIT_V(n) asm volatile("s_waitcnt vmcnt(" #n ")" ::: "memory")
; #define PG8_WAIT_L(n) asm volatile("s_waitcnt lgkmcnt(" #n ")" ::: "memory")
; template <class Epi>
; __device__ __forceinline__ void gemm_phase(LAS unsigned char* lds, const Gemm g, const StaticOrder& S, const Epi& E) {
;     ...
;         const bool has_next = S.next(ui + 1, nxt);
;         const char* nA = has_next ? (const char*)g.A + (size_t)nxt.pm * tstep : cA; const char* nB = has_next ? (const char*)g.Bt + (size_t)nxt.pn * tstep : cB;
;         for (int t = 0; t < nt; t += 2) {
;             const bool last = (t == nt - 2);
;             const char* a1 = cA + (size_t)(t + 1) * kstep;
;             const char* a2 = last ? nA : cA + (size_t)(t + 2) * kstep; const char* b2 = last ? nB : cB + (size_t)(t + 2) * kstep;
;             const char* a3 = a2 + kstep; const char* b3 = b2 + kstep;
;             PG8_LDB(B0, 0, 0); PG8_SCHED; PG8_LDA(At, 0, 0); PG8_STAGE(PG8_SA(1, 1), a1 + hstep, voffA);
;             PG8_WAIT_L(8); PG8_BAR; PG8_WAIT_L(0); PG8_MMA(0, 0, At, B0); PG8_BAR; PG8_SCHED;
;             PG8_LDB(B1, 0, 1); PG8_STAGE(PG8_SB(0, 0), b2, voffB0);
;             PG8_BAR; PG8_WAIT_L(0); PG8_MMA(0, 1, At, B1); PG8_BAR;
;             PG8_LDA(At, 0, 1); PG8_STAGE(PG8_SA(0, 0), a2, voffA);
;             PG8_BAR; PG8_WAIT_L(0); PG8_MMA(1, 0, At, B0); PG8_BAR; PG8_SCHED;
;             PG8_STAGE(PG8_SB(0, 1), b2, voffB1);
;             PG8_WAIT_V(6); PG8_BAR; PG8_MMA(1, 1, At, B1); PG8_BAR;
;             PG8_LDB(B0, 1, 0); PG8_SCHED; PG8_LDA(At, 1, 0); PG8_STAGE(PG8_SA(0, 1), a2 + hstep, voffA);
;             PG8_WAIT_L(8); PG8_BAR; PG8_WAIT_L(0); PG8_MMA(0, 0, At, B0); PG8_BAR; PG8_SCHED;
.LBB0_248:
	s_add_u32 s16, s42, s50
	s_addc_u32 s17, s43, 0
	s_add_u32 s33, s16, 0x100
	s_addc_u32 s48, s17, 0
	v_cndmask_b32_e64 v172, 0, 1, s[46:47]
	s_and_b64 s[46:47], s[44:45], exec
	s_cselect_b32 s49, s19, s48
	s_cselect_b32 s48, s72, s33
	s_add_u32 s33, s40, s50
	s_addc_u32 s46, s41, 0
	s_add_u32 s33, s33, 0x100
	s_addc_u32 s47, s46, 0
	s_and_b64 s[44:45], s[44:45], exec
	ds_read_b128 v[156:159], v153
	ds_read_b128 v[160:163], v153 offset:1024
	ds_read_b128 v[164:167], v153 offset:2048
	ds_read_b128 v[168:171], v153 offset:3072
	s_cselect_b32 s46, s73, s33
	s_cselect_b32 s47, s11, s47
	s_add_u32 s50, s16, 0x10080
	s_addc_u32 s51, s17, 0
	s_add_i32 s17, s69, s57
	s_add_i32 s79, s70, s57
	s_add_i32 m0, s39, 0xc000
	s_add_i32 s16, s39, 0xe000
	s_add_i32 s82, s17, 0x2000
	s_add_i32 s78, s79, 0x2000
	s_add_i32 s77, 0, 0x18000
	s_add_u32 s44, s48, 0x10000
	s_addc_u32 s45, s49, 0
	s_add_i32 s74, 0, 0x1c000
	s_add_i32 s75, s77, s57
	s_add_i32 s81, s74, s57
	s_add_i32 s33, s75, 0x2000
	s_add_i32 s80, s81, 0x2000
	v_cmp_ne_u32_e32 vcc, 1, v172
	v_lshl_add_u64 v[200:201], s[50:51], 0, v[138:139]
	ds_read_b128 v[172:175], v154
	ds_read_b128 v[176:179], v154 offset:1024
	ds_read_b128 v[180:183], v154 offset:2048
	ds_read_b128 v[184:187], v154 offset:3072
	ds_read_b128 v[188:191], v154 offset:4096
	ds_read_b128 v[192:195], v154 offset:5120
	ds_read_b128 v[196:199], v154 offset:6144
	ds_read_b128 v[204:207], v154 offset:7168
	global_load_lds_dwordx4 v[200:201], off
	v_lshl_add_u64 v[200:201], s[50:51], 0, v[132:133]
	s_mov_b32 m0, s16
	s_nop 0
	global_load_lds_dwordx4 v[200:201], off
	s_waitcnt lgkmcnt(8)
	s_barrier
	s_waitcnt lgkmcnt(0)
	s_waitcnt lgkmcnt(0)
	v_mfma_f32_16x16x32_bf16 v[124:127], v[156:159], v[172:175], v[124:127]
	v_mfma_f32_16x16x32_bf16 v[120:123], v[164:167], v[172:175], v[120:123]
	v_mfma_f32_16x16x32_bf16 v[108:111], v[156:159], v[180:183], v[108:111]
	v_mfma_f32_16x16x32_bf16 v[104:107], v[164:167], v[180:183], v[104:107]
	v_mfma_f32_16x16x32_bf16 v[92:95], v[156:159], v[188:191], v[92:95]
	v_mfma_f32_16x16x32_bf16 v[88:91], v[164:167], v[188:191], v[88:91]
	v_mfma_f32_16x16x32_bf16 v[76:79], v[156:159], v[196:199], v[76:79]
	v_mfma_f32_16x16x32_bf16 v[72:75], v[164:167], v[196:199], v[72:75]
	v_mfma_f32_16x16x32_bf16 v[124:127], v[160:163], v[176:179], v[124:127]
	v_mfma_f32_16x16x32_bf16 v[120:123], v[168:171], v[176:179], v[120:123]
	v_mfma_f32_16x16x32_bf16 v[108:111], v[160:163], v[184:187], v[108:111]
	v_mfma_f32_16x16x32_bf16 v[104:107], v[168:171], v[184:187], v[104:107]
	v_mfma_f32_16x16x32_bf16 v[92:95], v[160:163], v[192:195], v[92:95]
	v_mfma_f32_16x16x32_bf16 v[88:91], v[168:171], v[192:195], v[88:91]
	v_mfma_f32_16x16x32_bf16 v[76:79], v[160:163], v[204:207], v[76:79]
	v_mfma_f32_16x16x32_bf16 v[72:75], v[168:171], v[204:207], v[72:75]
	s_barrier
	s_mov_b32 m0, s17
	v_lshl_add_u64 v[200:201], s[46:47], 0, v[134:135]
	ds_read_b128 v[208:211], v155
	ds_read_b128 v[212:215], v155 offset:1024
	ds_read_b128 v[216:219], v155 offset:2048
	ds_read_b128 v[220:223], v155 offset:3072
	global_load_lds_dwordx4 v[200:201], off
	v_lshl_add_u64 v[224:225], s[46:47], 0, v[128:129]
	s_mov_b32 m0, s82
	s_nop 0
	global_load_lds_dwordx4 v[224:225], off
	s_barrier
	s_waitcnt lgkmcnt(0)
	s_waitcnt lgkmcnt(0)
	v_mfma_f32_16x16x32_bf16 v[116:119], v[208:211], v[172:175], v[116:119]
	v_mfma_f32_16x16x32_bf16 v[112:115], v[216:219], v[172:175], v[112:115]
	v_mfma_f32_16x16x32_bf16 v[100:103], v[208:211], v[180:183], v[100:103]
	v_mfma_f32_16x16x32_bf16 v[96:99], v[216:219], v[180:183], v[96:99]
	v_mfma_f32_16x16x32_bf16 v[84:87], v[208:211], v[188:191], v[84:87]
	v_mfma_f32_16x16x32_bf16 v[80:83], v[216:219], v[188:191], v[80:83]
	v_mfma_f32_16x16x32_bf16 v[68:71], v[208:211], v[196:199], v[68:71]
	v_mfma_f32_16x16x32_bf16 v[64:67], v[216:219], v[196:199], v[64:67]
	v_mfma_f32_16x16x32_bf16 v[116:119], v[212:215], v[176:179], v[116:119]
	v_mfma_f32_16x16x32_bf16 v[112:115], v[220:223], v[176:179], v[112:115]
	v_mfma_f32_16x16x32_bf16 v[100:103], v[212:215], v[184:187], v[100:103]
	v_mfma_f32_16x16x32_bf16 v[96:99], v[220:223], v[184:187], v[96:99]
	v_mfma_f32_16x16x32_bf16 v[84:87], v[212:215], v[192:195], v[84:87]
	v_mfma_f32_16x16x32_bf16 v[80:83], v[220:223], v[192:195], v[80:83]
	v_mfma_f32_16x16x32_bf16 v[68:71], v[212:215], v[204:207], v[68:71]
	v_mfma_f32_16x16x32_bf16 v[64:67], v[220:223], v[204:207], v[64:67]
	s_mov_b32 m0, s39
	v_lshl_add_u64 v[226:227], s[48:49], 0, v[138:139]
	s_barrier
	ds_read_b128 v[172:175], v154 offset:16384
	ds_read_b128 v[176:179], v154 offset:17408
	ds_read_b128 v[180:183], v154 offset:18432
	ds_read_b128 v[184:187], v154 offset:19456
	ds_read_b128 v[188:191], v154 offset:20480
	ds_read_b128 v[192:195], v154 offset:21504
	ds_read_b128 v[196:199], v154 offset:22528
	ds_read_b128 v[204:207], v154 offset:23552
	global_load_lds_dwordx4 v[226:227], off
	v_lshl_add_u64 v[228:229], s[48:49], 0, v[132:133]
	s_mov_b32 m0, s59
	s_nop 0
	global_load_lds_dwordx4 v[228:229], off
	s_barrier
	s_waitcnt lgkmcnt(0)
	s_waitcnt lgkmcnt(0)
	v_mfma_f32_16x16x32_bf16 v[60:63], v[156:159], v[172:175], v[60:63]
	v_mfma_f32_16x16x32_bf16 v[56:59], v[164:167], v[172:175], v[56:59]
	v_mfma_f32_16x16x32_bf16 v[44:47], v[156:159], v[180:183], v[44:47]
	v_mfma_f32_16x16x32_bf16 v[40:43], v[164:167], v[180:183], v[40:43]
	v_mfma_f32_16x16x32_bf16 v[28:31], v[156:159], v[188:191], v[28:31]
	v_mfma_f32_16x16x32_bf16 v[24:27], v[164:167], v[188:191], v[24:27]
	v_mfma_f32_16x16x32_bf16 v[12:15], v[156:159], v[196:199], v[12:15]
	v_mfma_f32_16x16x32_bf16 v[8:11], v[164:167], v[196:199], v[8:11]
	v_mfma_f32_16x16x32_bf16 v[60:63], v[160:163], v[176:179], v[60:63]
	v_mfma_f32_16x16x32_bf16 v[56:59], v[168:171], v[176:179], v[56:59]
	v_mfma_f32_16x16x32_bf16 v[44:47], v[160:163], v[184:187], v[44:47]
	v_mfma_f32_16x16x32_bf16 v[40:43], v[168:171], v[184:187], v[40:43]
	v_mfma_f32_16x16x32_bf16 v[28:31], v[160:163], v[192:195], v[28:31]
	v_mfma_f32_16x16x32_bf16 v[24:27], v[168:171], v[192:195], v[24:27]
	v_mfma_f32_16x16x32_bf16 v[12:15], v[160:163], v[204:207], v[12:15]
	v_mfma_f32_16x16x32_bf16 v[8:11], v[168:171], v[204:207], v[8:11]
	s_barrier
; #define PG8_STAGE(bufoff, gbase, voff) do { _Pragma("unroll") for (int _i = 0; _i < 2; ++_i) \
;         __builtin_amdgcn_global_load_lds((const unsigned*)((const char*)(gbase) + (voff)[_i]), (LAS unsigned*)(lds + (bufoff) + ldsw + _i * 8192), 16, 0, 0); } while (0)
; #define PG8_LDA(dst, b, h) do { _Pragma("unroll") for (int m = 0; m < 4; ++m) _Pragma("unroll") for (int k = 0; k < 2; ++k) dst[m][k] = *(const LAS bf16x8*)(lds + PG8_SA(b, h) + aoff + m * 2048 + k * 1024); } while (0)
; #define PG8_LDB(dst, b, h) do { _Pragma("unroll") for (int n = 0; n < 2; ++n) _Pragma("unroll") for (int k = 0; k < 2; ++k) dst[n][k] = *(const LAS bf16x8*)(lds + PG8_SB(b, h) + boff + n * 2048 + k * 1024); } while (0)
; #define PG8_MMA(ai, bj, At, Bt) do { __builtin_amdgcn_s_setprio(1); _Pragma("unroll") for (int m = 0; m < 4; ++m) _Pragma("unroll") for (int n = 0; n < 2; ++n) _Pragma("unroll") for (int k = 0; k < 2; ++k) \
;         acc[ai][bj][m][n] = __builtin_amdgcn_mfma_f32_16x16x32_bf16(Bt[n][k], At[m][k], acc[ai][bj][m][n], 0, 0, 0); __builtin_amdgcn_s_setprio(0); } while (0)
; #define PG8_WAIT_V(n) asm volatile("s_waitcnt vmcnt(" #n ")" ::: "memory")
; #define PG8_WAIT_L(n) asm volatile("s_waitcnt lgkmcnt(" #n ")" ::: "memory")
; #define PG8_BAR __builtin_amdgcn_s_barrier()
; #define PG8_SCHED __builtin_amdgcn_sched_barrier(0)
; template <class Epi>
; __device__ __forceinline__ void gemm_phase(LAS unsigned char* lds, const Gemm g, const StaticOrder& S, const Epi& E) {
;     ...
;             PG8_STAGE(PG8_SB(0, 1), b2, voffB1);
;             PG8_WAIT_V(6); PG8_BAR; PG8_MMA(1, 1, At, B1); PG8_BAR;
;             PG8_LDB(B0, 1, 0); PG8_SCHED; PG8_LDA(At, 1, 0); PG8_STAGE(PG8_SA(0, 1), a2 + hstep, voffA);
;             PG8_WAIT_L(8); PG8_BAR; PG8_WAIT_L(0); PG8_MMA(0, 0, At, B0); PG8_BAR; PG8_SCHED;
;             PG8_LDB(B1, 1, 1); PG8_STAGE(PG8_SB(1, 0), b3, voffB0);
;             PG8_BAR; PG8_WAIT_L(0); PG8_MMA(0, 1, At, B1); PG8_BAR;
;             PG8_LDA(At, 1, 1); PG8_STAGE(PG8_SA(1, 0), a3, voffA);
;             PG8_BAR; PG8_WAIT_L(0); PG8_MMA(1, 0, At, B0); PG8_BAR; PG8_SCHED;
	s_mov_b32 m0, s79
	v_lshl_add_u64 v[230:231], s[46:47], 0, v[136:137]
	global_load_lds_dwordx4 v[230:231], off
	v_lshl_add_u64 v[232:233], s[46:47], 0, v[130:131]
	s_mov_b32 m0, s78
	s_nop 0
	global_load_lds_dwordx4 v[232:233], off
	s_waitcnt vmcnt(6)
	s_barrier
	v_mfma_f32_16x16x32_bf16 v[52:55], v[208:211], v[172:175], v[52:55]
	v_mfma_f32_16x16x32_bf16 v[48:51], v[216:219], v[172:175], v[48:51]
	v_mfma_f32_16x16x32_bf16 v[36:39], v[208:211], v[180:183], v[36:39]
	v_mfma_f32_16x16x32_bf16 v[32:35], v[216:219], v[180:183], v[32:35]
	v_mfma_f32_16x16x32_bf16 v[20:23], v[208:211], v[188:191], v[20:23]
	v_mfma_f32_16x16x32_bf16 v[16:19], v[216:219], v[188:191], v[16:19]
	v_mfma_f32_16x16x32_bf16 v[4:7], v[208:211], v[196:199], v[4:7]
	v_mfma_f32_16x16x32_bf16 v[0:3], v[216:219], v[196:199], v[0:3]
	v_mfma_f32_16x16x32_bf16 v[52:55], v[212:215], v[176:179], v[52:55]
	v_mfma_f32_16x16x32_bf16 v[48:51], v[220:223], v[176:179], v[48:51]
	v_mfma_f32_16x16x32_bf16 v[36:39], v[212:215], v[184:187], v[36:39]
	v_mfma_f32_16x16x32_bf16 v[32:35], v[220:223], v[184:187], v[32:35]
	v_mfma_f32_16x16x32_bf16 v[20:23], v[212:215], v[192:195], v[20:23]
	v_mfma_f32_16x16x32_bf16 v[16:19], v[220:223], v[192:195], v[16:19]
	v_mfma_f32_16x16x32_bf16 v[4:7], v[212:215], v[204:207], v[4:7]
	v_mfma_f32_16x16x32_bf16 v[0:3], v[220:223], v[204:207], v[0:3]
	v_add_u32_e32 v168, s77, v143
	s_barrier
	ds_read_b128 v[156:159], v168
	ds_read_b128 v[160:163], v168 offset:1024
	ds_read_b128 v[164:167], v168 offset:2048
	ds_read_b128 v[168:171], v168 offset:3072
	s_mov_b32 m0, s60
	v_lshl_add_u64 v[208:209], s[44:45], 0, v[138:139]
	ds_read_b128 v[172:175], v154 offset:32768
	ds_read_b128 v[176:179], v154 offset:33792
	ds_read_b128 v[180:183], v154 offset:34816
	ds_read_b128 v[184:187], v154 offset:35840
	ds_read_b128 v[188:191], v154 offset:36864
	ds_read_b128 v[192:195], v154 offset:37888
	ds_read_b128 v[196:199], v154 offset:38912
	ds_read_b128 v[204:207], v154 offset:39936
	global_load_lds_dwordx4 v[208:209], off
	v_lshl_add_u64 v[208:209], s[44:45], 0, v[132:133]
	s_mov_b32 m0, s61
	s_nop 0
	global_load_lds_dwordx4 v[208:209], off
	s_waitcnt lgkmcnt(8)
	s_barrier
	s_waitcnt lgkmcnt(0)
	s_waitcnt lgkmcnt(0)
	v_mfma_f32_16x16x32_bf16 v[124:127], v[156:159], v[172:175], v[124:127]
	v_mfma_f32_16x16x32_bf16 v[120:123], v[164:167], v[172:175], v[120:123]
	v_mfma_f32_16x16x32_bf16 v[108:111], v[156:159], v[180:183], v[108:111]
	v_mfma_f32_16x16x32_bf16 v[104:107], v[164:167], v[180:183], v[104:107]
	v_mfma_f32_16x16x32_bf16 v[92:95], v[156:159], v[188:191], v[92:95]
	v_mfma_f32_16x16x32_bf16 v[88:91], v[164:167], v[188:191], v[88:91]
	v_mfma_f32_16x16x32_bf16 v[76:79], v[156:159], v[196:199], v[76:79]
	v_mfma_f32_16x16x32_bf16 v[72:75], v[164:167], v[196:199], v[72:75]
	v_mfma_f32_16x16x32_bf16 v[124:127], v[160:163], v[176:179], v[124:127]
	v_mfma_f32_16x16x32_bf16 v[120:123], v[168:171], v[176:179], v[120:123]
	v_mfma_f32_16x16x32_bf16 v[108:111], v[160:163], v[184:187], v[108:111]
	v_mfma_f32_16x16x32_bf16 v[104:107], v[168:171], v[184:187], v[104:107]
	v_mfma_f32_16x16x32_bf16 v[92:95], v[160:163], v[192:195], v[92:95]
	v_mfma_f32_16x16x32_bf16 v[88:91], v[168:171], v[192:195], v[88:91]
	v_mfma_f32_16x16x32_bf16 v[76:79], v[160:163], v[204:207], v[76:79]
	v_mfma_f32_16x16x32_bf16 v[72:75], v[168:171], v[204:207], v[72:75]
	s_barrier
	s_mov_b32 m0, s75
	v_add_u32_e32 v220, s74, v143
	v_lshl_add_u64 v[200:201], v[200:201], 0, s[8:9]
	ds_read_b128 v[208:211], v220
	ds_read_b128 v[212:215], v220 offset:1024
	ds_read_b128 v[216:219], v220 offset:2048
	ds_read_b128 v[220:223], v220 offset:3072
	global_load_lds_dwordx4 v[200:201], off
	v_lshl_add_u64 v[200:201], v[224:225], 0, s[8:9]
	s_mov_b32 m0, s33
	s_nop 0
	global_load_lds_dwordx4 v[200:201], off
	s_barrier
	s_waitcnt lgkmcnt(0)
	s_waitcnt lgkmcnt(0)
	v_mfma_f32_16x16x32_bf16 v[116:119], v[208:211], v[172:175], v[116:119]
	v_mfma_f32_16x16x32_bf16 v[112:115], v[216:219], v[172:175], v[112:115]
	v_mfma_f32_16x16x32_bf16 v[100:103], v[208:211], v[180:183], v[100:103]
	v_mfma_f32_16x16x32_bf16 v[96:99], v[216:219], v[180:183], v[96:99]
	v_mfma_f32_16x16x32_bf16 v[84:87], v[208:211], v[188:191], v[84:87]
	v_mfma_f32_16x16x32_bf16 v[80:83], v[216:219], v[188:191], v[80:83]
	v_mfma_f32_16x16x32_bf16 v[68:71], v[208:211], v[196:199], v[68:71]
	v_mfma_f32_16x16x32_bf16 v[64:67], v[216:219], v[196:199], v[64:67]
	v_mfma_f32_16x16x32_bf16 v[116:119], v[212:215], v[176:179], v[116:119]
	v_mfma_f32_16x16x32_bf16 v[112:115], v[220:223], v[176:179], v[112:115]
	v_mfma_f32_16x16x32_bf16 v[100:103], v[212:215], v[184:187], v[100:103]
	v_mfma_f32_16x16x32_bf16 v[96:99], v[220:223], v[184:187], v[96:99]
	v_mfma_f32_16x16x32_bf16 v[84:87], v[212:215], v[192:195], v[84:87]
	v_mfma_f32_16x16x32_bf16 v[80:83], v[220:223], v[192:195], v[80:83]
	v_mfma_f32_16x16x32_bf16 v[68:71], v[212:215], v[204:207], v[68:71]
	v_mfma_f32_16x16x32_bf16 v[64:67], v[220:223], v[204:207], v[64:67]
	s_mov_b32 m0, s63
	v_lshl_add_u64 v[200:201], v[226:227], 0, s[8:9]
	s_barrier
	ds_read_b128 v[172:175], v154 offset:49152
	ds_read_b128 v[176:179], v154 offset:50176
	ds_read_b128 v[180:183], v154 offset:51200
	ds_read_b128 v[184:187], v154 offset:52224
	ds_read_b128 v[188:191], v154 offset:53248
	ds_read_b128 v[192:195], v154 offset:54272
	ds_read_b128 v[196:199], v154 offset:55296
	ds_read_b128 v[204:207], v154 offset:56320
	global_load_lds_dwordx4 v[200:201], off
	v_lshl_add_u64 v[200:201], v[228:229], 0, s[8:9]
	s_mov_b32 m0, s64
	s_nop 0
	global_load_lds_dwordx4 v[200:201], off
	s_barrier
; __device__ __forceinline__ unsigned cvt_pk_bf16(float lo, float hi) { unsigned r; asm volatile("v_cvt_pk_bf16_f32 %0, %1, %2" : "=v"(r) : "v"(lo), "v"(hi)); return r; }
; #define PG8_STAGE(bufoff, gbase, voff) do { _Pragma("unroll") for (int _i = 0; _i < 2; ++_i) \
;         __builtin_amdgcn_global_load_lds((const unsigned*)((const char*)(gbase) + (voff)[_i]), (LAS unsigned*)(lds + (bufoff) + ldsw + _i * 8192), 16, 0, 0); } while (0)
; #define PG8_WAIT_V(n) asm volatile("s_waitcnt vmcnt(" #n ")" ::: "memory")
; #define PG8_WAIT_L(n) asm volatile("s_waitcnt lgkmcnt(" #n ")" ::: "memory")
; #define PG8_BAR __builtin_amdgcn_s_barrier()
; #define PG8_SCHED __builtin_amdgcn_sched_barrier(0)
;     __device__ __forceinline__ void operator()(const f32x4 (&acc)[2][2][4][2], const Unit& u, int wr, int wc, int fr, int fq) const {
;         const int row0 = u.pm * BM + wr * 64 + fr; const int col0 = u.pn * BM + wc * 64 + 16 * fq;
; #pragma unroll
;         for (int ai = 0; ai < 2; ++ai)
; #pragma unroll
;             for (int m = 0; m < 4; ++m) { const int row = row0 + ai * HALF + m * 16;
;                 const float rs = ssin ? __builtin_amdgcn_rsqf(ssin[row] * (1.f / D) + EPS) : 1.0f; float sq = 0.f; u32x4 w[2];
; #pragma unroll
;                 for (int bj = 0; bj < 2; ++bj) { f32x4 v0 = acc[ai][bj][m][0] * rs, v1 = acc[ai][bj][m][1] * rs;
;                     if (ACT == 1) {
; #pragma unroll
;                         for (int j = 0; j < 4; ++j) { const float a = fmaxf(v0[j], 0.f), b = fmaxf(v1[j], 0.f); v0[j] = a * a; v1[j] = b * b; } }
;                     sq += (v0[0] * v0[0] + v0[1] * v0[1]) + (v0[2] * v0[2] + v0[3] * v0[3]) + (v1[0] * v1[0] + v1[1] * v1[1]) + (v1[2] * v1[2] + v1[3] * v1[3]);
;                     w[bj].x = cvt_pk_bf16(v0[0], v0[1]); w[bj].y = cvt_pk_bf16(v0[2], v0[3]); w[bj].z = cvt_pk_bf16(v1[0], v1[1]); w[bj].w = cvt_pk_bf16(v1[2], v1[3]); }
;                 store_pair_lines(O, ldc, row, fr, col0, w[0], w[1]);
; template <class Epi>
; __device__ __forceinline__ void gemm_phase(LAS unsigned char* lds, const Gemm g, const StaticOrder& S, const Epi& E) {
;     ...
;             PG8_BAR; PG8_WAIT_L(0); PG8_MMA(1, 0, At, B0); PG8_BAR; PG8_SCHED;
;             PG8_STAGE(PG8_SB(1, 1), b3, voffB1);
;             PG8_WAIT_V(6); PG8_BAR; PG8_MMA(1, 1, At, B1); PG8_BAR;
	s_waitcnt lgkmcnt(0)
	s_waitcnt lgkmcnt(0)
	v_mfma_f32_16x16x32_bf16 v[60:63], v[156:159], v[172:175], v[60:63]
	v_mfma_f32_16x16x32_bf16 v[56:59], v[164:167], v[172:175], v[56:59]
	v_mfma_f32_16x16x32_bf16 v[44:47], v[156:159], v[180:183], v[44:47]
	v_mfma_f32_16x16x32_bf16 v[40:43], v[164:167], v[180:183], v[40:43]
	v_mfma_f32_16x16x32_bf16 v[28:31], v[156:159], v[188:191], v[28:31]
	v_mfma_f32_16x16x32_bf16 v[24:27], v[164:167], v[188:191], v[24:27]
	v_mfma_f32_16x16x32_bf16 v[12:15], v[156:159], v[196:199], v[12:15]
	v_mfma_f32_16x16x32_bf16 v[8:11], v[164:167], v[196:199], v[8:11]
	v_mfma_f32_16x16x32_bf16 v[60:63], v[160:163], v[176:179], v[60:63]
	v_mfma_f32_16x16x32_bf16 v[56:59], v[168:171], v[176:179], v[56:59]
	v_mfma_f32_16x16x32_bf16 v[44:47], v[160:163], v[184:187], v[44:47]
	v_mfma_f32_16x16x32_bf16 v[40:43], v[168:171], v[184:187], v[40:43]
	v_mfma_f32_16x16x32_bf16 v[28:31], v[160:163], v[192:195], v[28:31]
	v_mfma_f32_16x16x32_bf16 v[24:27], v[168:171], v[192:195], v[24:27]
	v_mfma_f32_16x16x32_bf16 v[12:15], v[160:163], v[204:207], v[12:15]
	v_mfma_f32_16x16x32_bf16 v[8:11], v[168:171], v[204:207], v[8:11]
	s_barrier
	s_mov_b32 m0, s81
	v_lshl_add_u64 v[156:157], v[230:231], 0, s[8:9]
	global_load_lds_dwordx4 v[156:157], off
	v_lshl_add_u64 v[156:157], v[232:233], 0, s[8:9]
	s_mov_b32 m0, s80
	s_nop 0
	global_load_lds_dwordx4 v[156:157], off
	s_waitcnt vmcnt(6)
	s_barrier
	v_mfma_f32_16x16x32_bf16 v[52:55], v[208:211], v[172:175], v[52:55]
	v_mfma_f32_16x16x32_bf16 v[48:51], v[216:219], v[172:175], v[48:51]
	v_mfma_f32_16x16x32_bf16 v[36:39], v[208:211], v[180:183], v[36:39]
	v_mfma_f32_16x16x32_bf16 v[32:35], v[216:219], v[180:183], v[32:35]
	v_mfma_f32_16x16x32_bf16 v[20:23], v[208:211], v[188:191], v[20:23]
	v_mfma_f32_16x16x32_bf16 v[16:19], v[216:219], v[188:191], v[16:19]
	v_mfma_f32_16x16x32_bf16 v[4:7], v[208:211], v[196:199], v[4:7]
	v_mfma_f32_16x16x32_bf16 v[0:3], v[216:219], v[196:199], v[0:3]
	v_mfma_f32_16x16x32_bf16 v[52:55], v[212:215], v[176:179], v[52:55]
	v_mfma_f32_16x16x32_bf16 v[48:51], v[220:223], v[176:179], v[48:51]
	v_mfma_f32_16x16x32_bf16 v[36:39], v[212:215], v[184:187], v[36:39]
	v_mfma_f32_16x16x32_bf16 v[32:35], v[220:223], v[184:187], v[32:35]
	v_mfma_f32_16x16x32_bf16 v[20:23], v[212:215], v[192:195], v[20:23]
	v_mfma_f32_16x16x32_bf16 v[16:19], v[220:223], v[192:195], v[16:19]
	v_mfma_f32_16x16x32_bf16 v[4:7], v[212:215], v[204:207], v[4:7]
	v_mfma_f32_16x16x32_bf16 v[0:3], v[220:223], v[204:207], v[0:3]
	s_movk_i32 s50, 0x100
	s_mov_b64 s[46:47], 0
	s_mov_b64 s[44:45], -1
	s_barrier
	s_cbranch_vccz .LBB0_248
	s_lshl_b32 s11, s38, 8
	v_cvt_pk_bf16_f32 v124, v124, v125
	v_cvt_pk_bf16_f32 v125, v126, v127
	v_cvt_pk_bf16_f32 v120, v120, v121
	v_cvt_pk_bf16_f32 v121, v122, v123
	v_cvt_pk_bf16_f32 v122, v116, v117
	v_cvt_pk_bf16_f32 v119, v118, v119
	v_mov_b32_e32 v118, 0
	s_add_i32 s11, s11, s65
	v_cvt_pk_bf16_f32 v112, v112, v113
	v_cvt_pk_bf16_f32 v113, v114, v115
	v_mov_b32_e32 v123, 0
	v_mov_b32_dpp v118, v124 row_ror:8 row_mask:0xf bank_mask:0xf
	v_mov_b32_e32 v114, 0
	v_mov_b32_dpp v123, v125 row_ror:8 row_mask:0xf bank_mask:0xf
	v_mov_b32_e32 v126, 0
	v_mov_b32_e32 v127, 0
	v_mov_b32_dpp v114, v122 row_ror:8 row_mask:0xf bank_mask:0xf
	v_mov_b32_e32 v115, 0
	v_mov_b32_e32 v116, 0
	v_mov_b32_e32 v117, 0
	v_cndmask_b32_e64 v118, v122, v118, s[4:5]
	v_or_b32_e32 v122, s11, v144
	v_lshl_or_b32 v158, s71, 8, v152
	v_mov_b32_dpp v126, v120 row_ror:8 row_mask:0xf bank_mask:0xf
	v_mov_b32_dpp v127, v121 row_ror:8 row_mask:0xf bank_mask:0xf
	v_mov_b32_dpp v115, v119 row_ror:8 row_mask:0xf bank_mask:0xf
	v_mov_b32_dpp v116, v112 row_ror:8 row_mask:0xf bank_mask:0xf
	v_mov_b32_dpp v117, v113 row_ror:8 row_mask:0xf bank_mask:0xf
	v_cndmask_b32_e64 v119, v119, v123, s[4:5]
	v_ashrrev_i32_e32 v123, 31, v122
	v_ashrrev_i32_e32 v159, 31, v158
	v_cndmask_b32_e64 v116, v116, v120, s[4:5]
	v_cndmask_b32_e64 v117, v117, v121, s[4:5]
	v_cndmask_b32_e64 v120, v112, v126, s[4:5]
	v_cndmask_b32_e64 v121, v113, v127, s[4:5]
	v_lshlrev_b64 v[112:113], 12, v[122:123]
	v_cndmask_b32_e64 v114, v114, v124, s[4:5]
	v_cndmask_b32_e64 v115, v115, v125, s[4:5]
	v_lshl_add_u64 v[124:125], s[6:7], 0, v[112:113]
	v_lshlrev_b64 v[112:113], 1, v[158:159]
	v_lshl_add_u64 v[124:125], v[124:125], 0, v[112:113]
	global_store_dwordx4 v[124:125], v[114:117], off
	v_or_b32_e32 v156, s11, v142
	s_mov_b32 s71, s10
	v_or_b32_e32 v114, 8, v122
	v_ashrrev_i32_e32 v115, 31, v114
	v_lshlrev_b64 v[114:115], 12, v[114:115]
	v_lshl_add_u64 v[114:115], s[6:7], 0, v[114:115]
	v_lshl_add_u64 v[114:115], v[114:115], 0, v[112:113]
	global_store_dwordx4 v[114:115], v[118:121], off
	v_cvt_pk_bf16_f32 v108, v108, v109
	v_cvt_pk_bf16_f32 v109, v110, v111
	v_cvt_pk_bf16_f32 v104, v104, v105
	v_cvt_pk_bf16_f32 v105, v106, v107
	v_cvt_pk_bf16_f32 v100, v100, v101
	v_cvt_pk_bf16_f32 v101, v102, v103
	v_cvt_pk_bf16_f32 v102, v96, v97
	v_cvt_pk_bf16_f32 v103, v98, v99
	v_mov_b32_e32 v98, 0
	v_mov_b32_e32 v110, 0
	v_mov_b32_e32 v99, 0
	v_mov_b32_dpp v98, v102 row_ror:8 row_mask:0xf bank_mask:0xf
	v_mov_b32_dpp v110, v104 row_ror:8 row_mask:0xf bank_mask:0xf
	v_mov_b32_e32 v111, 0
	v_mov_b32_dpp v99, v103 row_ror:8 row_mask:0xf bank_mask:0xf
	v_cndmask_b32_e64 v98, v98, v104, s[4:5]
	v_add_u32_e32 v104, v145, v156
	v_mov_b32_dpp v111, v105 row_ror:8 row_mask:0xf bank_mask:0xf
	v_cndmask_b32_e64 v99, v99, v105, s[4:5]
	v_ashrrev_i32_e32 v105, 31, v104
	v_mov_b32_e32 v96, 0
	v_mov_b32_e32 v97, 0
	v_lshlrev_b64 v[104:105], 12, v[104:105]
	v_mov_b32_dpp v96, v100 row_ror:8 row_mask:0xf bank_mask:0xf
	v_mov_b32_dpp v97, v101 row_ror:8 row_mask:0xf bank_mask:0xf
; __device__ __forceinline__ unsigned cvt_pk_bf16(float lo, float hi) { unsigned r; asm volatile("v_cvt_pk_bf16_f32 %0, %1, %2" : "=v"(r) : "v"(lo), "v"(hi)); return r; }
; __device__ __forceinline__ unsigned dpp_ror8(unsigned x) { return (unsigned)__builtin_amdgcn_update_dpp(0, (int)x, 0x128, 0xf, 0xf, false); }
; __device__ __forceinline__ void store_pair_lines(bf16_t* O, int ldc, int row, int fr, int col0, u32x4 wA, u32x4 wB) {
;     const u32x4 sA = {dpp_ror8(wA.x), dpp_ror8(wA.y), dpp_ror8(wA.z), dpp_ror8(wA.w)}, sB = {dpp_ror8(wB.x), dpp_ror8(wB.y), dpp_ror8(wB.z), dpp_ror8(wB.w)};
;     const bool lo = fr < 8;
;     const u32x4 o1 = lo ? wA : sB, o2 = lo ? sA : wB;
;     const int r1 = row - fr + (fr & 7), cb = col0 + (lo ? 0 : 8);
;     *(u32x4*)(O + (size_t)r1 * ldc + cb) = o1;
;     *(u32x4*)(O + (size_t)(r1 + 8) * ldc + cb) = o2;
;     __device__ __forceinline__ void operator()(const f32x4 (&acc)[2][2][4][2], const Unit& u, int wr, int wc, int fr, int fq) const {
;         const int row0 = u.pm * BM + wr * 64 + fr; const int col0 = u.pn * BM + wc * 64 + 16 * fq;
; #pragma unroll
;         for (int ai = 0; ai < 2; ++ai)
; #pragma unroll
;             for (int m = 0; m < 4; ++m) { const int row = row0 + ai * HALF + m * 16;
;                 const float rs = ssin ? __builtin_amdgcn_rsqf(ssin[row] * (1.f / D) + EPS) : 1.0f; float sq = 0.f; u32x4 w[2];
; #pragma unroll
;                 for (int bj = 0; bj < 2; ++bj) { f32x4 v0 = acc[ai][bj][m][0] * rs, v1 = acc[ai][bj][m][1] * rs;
;                     if (ACT == 1) {
; #pragma unroll
;                         for (int j = 0; j < 4; ++j) { const float a = fmaxf(v0[j], 0.f), b = fmaxf(v1[j], 0.f); v0[j] = a * a; v1[j] = b * b; } }
;                     sq += (v0[0] * v0[0] + v0[1] * v0[1]) + (v0[2] * v0[2] + v0[3] * v0[3]) + (v1[0] * v1[0] + v1[1] * v1[1]) + (v1[2] * v1[2] + v1[3] * v1[3]);
;                     w[bj].x = cvt_pk_bf16(v0[0], v0[1]); w[bj].y = cvt_pk_bf16(v0[2], v0[3]); w[bj].z = cvt_pk_bf16(v1[0], v1[1]); w[bj].w = cvt_pk_bf16(v1[2], v1[3]); }
;                 store_pair_lines(O, ldc, row, fr, col0, w[0], w[1]);
	v_lshl_add_u64 v[104:105], s[6:7], 0, v[104:105]
	v_mov_b32_e32 v106, 0
	v_mov_b32_e32 v107, 0
	v_cndmask_b32_e64 v96, v96, v108, s[4:5]
	v_cndmask_b32_e64 v97, v97, v109, s[4:5]
	v_lshl_add_u64 v[104:105], v[104:105], 0, v[112:113]
	v_mov_b32_dpp v106, v108 row_ror:8 row_mask:0xf bank_mask:0xf
	v_mov_b32_dpp v107, v109 row_ror:8 row_mask:0xf bank_mask:0xf
	global_store_dwordx4 v[104:105], v[96:99], off
	v_cndmask_b32_e64 v100, v100, v106, s[4:5]
	v_cndmask_b32_e64 v101, v101, v107, s[4:5]
	v_add_co_u32_e32 v96, vcc, s66, v104
	v_cndmask_b32_e64 v102, v102, v110, s[4:5]
	v_cndmask_b32_e64 v103, v103, v111, s[4:5]
	v_addc_co_u32_e32 v97, vcc, 0, v105, vcc
	global_store_dwordx4 v[96:97], v[100:103], off
	v_cvt_pk_bf16_f32 v92, v92, v93
	v_cvt_pk_bf16_f32 v93, v94, v95
	v_cvt_pk_bf16_f32 v88, v88, v89
	v_cvt_pk_bf16_f32 v89, v90, v91
	v_cvt_pk_bf16_f32 v84, v84, v85
	v_cvt_pk_bf16_f32 v85, v86, v87
	v_cvt_pk_bf16_f32 v86, v80, v81
	v_cvt_pk_bf16_f32 v87, v82, v83
	v_mov_b32_e32 v82, 0
	v_mov_b32_e32 v94, 0
	v_mov_b32_e32 v83, 0
	v_mov_b32_dpp v82, v86 row_ror:8 row_mask:0xf bank_mask:0xf
	v_mov_b32_dpp v94, v88 row_ror:8 row_mask:0xf bank_mask:0xf
	v_mov_b32_e32 v95, 0
	v_mov_b32_dpp v83, v87 row_ror:8 row_mask:0xf bank_mask:0xf
	v_cndmask_b32_e64 v82, v82, v88, s[4:5]
	v_add_u32_e32 v88, v146, v156
	v_mov_b32_dpp v95, v89 row_ror:8 row_mask:0xf bank_mask:0xf
	v_cndmask_b32_e64 v83, v83, v89, s[4:5]
	v_ashrrev_i32_e32 v89, 31, v88
	v_mov_b32_e32 v80, 0
	v_mov_b32_e32 v81, 0
	v_lshlrev_b64 v[88:89], 12, v[88:89]
	v_mov_b32_dpp v80, v84 row_ror:8 row_mask:0xf bank_mask:0xf
	v_mov_b32_dpp v81, v85 row_ror:8 row_mask:0xf bank_mask:0xf
	v_lshl_add_u64 v[88:89], s[6:7], 0, v[88:89]
	v_mov_b32_e32 v90, 0
	v_mov_b32_e32 v91, 0
	v_cndmask_b32_e64 v80, v80, v92, s[4:5]
	v_cndmask_b32_e64 v81, v81, v93, s[4:5]
	v_lshl_add_u64 v[88:89], v[88:89], 0, v[112:113]
	v_mov_b32_dpp v90, v92 row_ror:8 row_mask:0xf bank_mask:0xf
	v_mov_b32_dpp v91, v93 row_ror:8 row_mask:0xf bank_mask:0xf
	global_store_dwordx4 v[88:89], v[80:83], off
	v_cndmask_b32_e64 v84, v84, v90, s[4:5]
	v_cndmask_b32_e64 v85, v85, v91, s[4:5]
	v_add_co_u32_e32 v80, vcc, s66, v88
	v_cndmask_b32_e64 v86, v86, v94, s[4:5]
	v_cndmask_b32_e64 v87, v87, v95, s[4:5]
	v_addc_co_u32_e32 v81, vcc, 0, v89, vcc
	global_store_dwordx4 v[80:81], v[84:87], off
	v_cvt_pk_bf16_f32 v76, v76, v77
	v_cvt_pk_bf16_f32 v77, v78, v79
	v_cvt_pk_bf16_f32 v72, v72, v73
	v_cvt_pk_bf16_f32 v73, v74, v75
	v_cvt_pk_bf16_f32 v68, v68, v69
	v_cvt_pk_bf16_f32 v69, v70, v71
	v_cvt_pk_bf16_f32 v70, v64, v65
	v_cvt_pk_bf16_f32 v71, v66, v67
	v_mov_b32_e32 v66, 0
	v_mov_b32_e32 v78, 0
	v_mov_b32_e32 v67, 0
	v_mov_b32_dpp v66, v70 row_ror:8 row_mask:0xf bank_mask:0xf
	v_mov_b32_dpp v78, v72 row_ror:8 row_mask:0xf bank_mask:0xf
	v_mov_b32_e32 v79, 0
	v_mov_b32_dpp v67, v71 row_ror:8 row_mask:0xf bank_mask:0xf
	v_cndmask_b32_e64 v66, v66, v72, s[4:5]
	v_add_u32_e32 v72, v147, v156
	v_mov_b32_dpp v79, v73 row_ror:8 row_mask:0xf bank_mask:0xf
	v_cndmask_b32_e64 v67, v67, v73, s[4:5]
	v_ashrrev_i32_e32 v73, 31, v72
	v_mov_b32_e32 v64, 0
	v_mov_b32_e32 v65, 0
	v_lshlrev_b64 v[72:73], 12, v[72:73]
	v_mov_b32_dpp v64, v68 row_ror:8 row_mask:0xf bank_mask:0xf
	v_mov_b32_dpp v65, v69 row_ror:8 row_mask:0xf bank_mask:0xf
	v_lshl_add_u64 v[72:73], s[6:7], 0, v[72:73]
	v_mov_b32_e32 v74, 0
	v_mov_b32_e32 v75, 0
	v_cndmask_b32_e64 v64, v64, v76, s[4:5]
	v_cndmask_b32_e64 v65, v65, v77, s[4:5]
	v_lshl_add_u64 v[72:73], v[72:73], 0, v[112:113]
	v_mov_b32_dpp v74, v76 row_ror:8 row_mask:0xf bank_mask:0xf
	v_mov_b32_dpp v75, v77 row_ror:8 row_mask:0xf bank_mask:0xf
	global_store_dwordx4 v[72:73], v[64:67], off
	v_cndmask_b32_e64 v68, v68, v74, s[4:5]
	v_cndmask_b32_e64 v69, v69, v75, s[4:5]
	v_add_co_u32_e32 v64, vcc, s66, v72
	v_cndmask_b32_e64 v70, v70, v78, s[4:5]
	v_cndmask_b32_e64 v71, v71, v79, s[4:5]
	v_addc_co_u32_e32 v65, vcc, 0, v73, vcc
	global_store_dwordx4 v[64:65], v[68:71], off
	v_cvt_pk_bf16_f32 v60, v60, v61
	v_cvt_pk_bf16_f32 v61, v62, v63
	v_cvt_pk_bf16_f32 v56, v56, v57
	v_cvt_pk_bf16_f32 v57, v58, v59
	v_cvt_pk_bf16_f32 v52, v52, v53
	v_cvt_pk_bf16_f32 v53, v54, v55
	v_cvt_pk_bf16_f32 v54, v48, v49
	v_cvt_pk_bf16_f32 v55, v50, v51
	v_mov_b32_e32 v50, 0
	v_mov_b32_e32 v62, 0
	v_mov_b32_e32 v51, 0
	v_mov_b32_dpp v50, v54 row_ror:8 row_mask:0xf bank_mask:0xf
	v_mov_b32_dpp v62, v56 row_ror:8 row_mask:0xf bank_mask:0xf
	v_mov_b32_e32 v63, 0
	v_mov_b32_dpp v51, v55 row_ror:8 row_mask:0xf bank_mask:0xf
	v_cndmask_b32_e64 v50, v50, v56, s[4:5]
	v_add_u32_e32 v56, v148, v156
	v_mov_b32_dpp v63, v57 row_ror:8 row_mask:0xf bank_mask:0xf
	v_cndmask_b32_e64 v51, v51, v57, s[4:5]
	v_ashrrev_i32_e32 v57, 31, v56
	v_mov_b32_e32 v48, 0
	v_mov_b32_e32 v49, 0
	v_lshlrev_b64 v[56:57], 12, v[56:57]
	v_mov_b32_dpp v48, v52 row_ror:8 row_mask:0xf bank_mask:0xf
	v_mov_b32_dpp v49, v53 row_ror:8 row_mask:0xf bank_mask:0xf
	v_lshl_add_u64 v[56:57], s[6:7], 0, v[56:57]
	v_mov_b32_e32 v58, 0
	v_mov_b32_e32 v59, 0
	v_cndmask_b32_e64 v48, v48, v60, s[4:5]
	v_cndmask_b32_e64 v49, v49, v61, s[4:5]
	v_lshl_add_u64 v[56:57], v[56:57], 0, v[112:113]
	v_mov_b32_dpp v58, v60 row_ror:8 row_mask:0xf bank_mask:0xf
	v_mov_b32_dpp v59, v61 row_ror:8 row_mask:0xf bank_mask:0xf
	global_store_dwordx4 v[56:57], v[48:51], off
; __device__ __forceinline__ unsigned cvt_pk_bf16(float lo, float hi) { unsigned r; asm volatile("v_cvt_pk_bf16_f32 %0, %1, %2" : "=v"(r) : "v"(lo), "v"(hi)); return r; }
; __device__ __forceinline__ unsigned dpp_ror8(unsigned x) { return (unsigned)__builtin_amdgcn_update_dpp(0, (int)x, 0x128, 0xf, 0xf, false); }
; __device__ __forceinline__ void store_pair_lines(bf16_t* O, int ldc, int row, int fr, int col0, u32x4 wA, u32x4 wB) {
;     const u32x4 sA = {dpp_ror8(wA.x), dpp_ror8(wA.y), dpp_ror8(wA.z), dpp_ror8(wA.w)}, sB = {dpp_ror8(wB.x), dpp_ror8(wB.y), dpp_ror8(wB.z), dpp_ror8(wB.w)};
;     const bool lo = fr < 8;
;     const u32x4 o1 = lo ? wA : sB, o2 = lo ? sA : wB;
;     const int r1 = row - fr + (fr & 7), cb = col0 + (lo ? 0 : 8);
;     *(u32x4*)(O + (size_t)r1 * ldc + cb) = o1;
;     *(u32x4*)(O + (size_t)(r1 + 8) * ldc + cb) = o2;
;     __device__ __forceinline__ void operator()(const f32x4 (&acc)[2][2][4][2], const Unit& u, int wr, int wc, int fr, int fq) const {
;         const int row0 = u.pm * BM + wr * 64 + fr; const int col0 = u.pn * BM + wc * 64 + 16 * fq;
; #pragma unroll
;         for (int ai = 0; ai < 2; ++ai)
; #pragma unroll
;             for (int m = 0; m < 4; ++m) { const int row = row0 + ai * HALF + m * 16;
;                 const float rs = ssin ? __builtin_amdgcn_rsqf(ssin[row] * (1.f / D) + EPS) : 1.0f; float sq = 0.f; u32x4 w[2];
; #pragma unroll
;                 for (int bj = 0; bj < 2; ++bj) { f32x4 v0 = acc[ai][bj][m][0] * rs, v1 = acc[ai][bj][m][1] * rs;
;                     if (ACT == 1) {
; #pragma unroll
;                         for (int j = 0; j < 4; ++j) { const float a = fmaxf(v0[j], 0.f), b = fmaxf(v1[j], 0.f); v0[j] = a * a; v1[j] = b * b; } }
;                     sq += (v0[0] * v0[0] + v0[1] * v0[1]) + (v0[2] * v0[2] + v0[3] * v0[3]) + (v1[0] * v1[0] + v1[1] * v1[1]) + (v1[2] * v1[2] + v1[3] * v1[3]);
;                     w[bj].x = cvt_pk_bf16(v0[0], v0[1]); w[bj].y = cvt_pk_bf16(v0[2], v0[3]); w[bj].z = cvt_pk_bf16(v1[0], v1[1]); w[bj].w = cvt_pk_bf16(v1[2], v1[3]); }
;                 store_pair_lines(O, ldc, row, fr, col0, w[0], w[1]);
;                 if (ssout) { sq += __shfl_xor(sq, 16); sq += __shfl_xor(sq, 32); if (fq == 0) unsafeAtomicAdd(ssout + row, sq); } }
	v_cndmask_b32_e64 v52, v52, v58, s[4:5]
	v_cndmask_b32_e64 v53, v53, v59, s[4:5]
	v_add_co_u32_e32 v48, vcc, s66, v56
	v_cndmask_b32_e64 v54, v54, v62, s[4:5]
	v_cndmask_b32_e64 v55, v55, v63, s[4:5]
	v_addc_co_u32_e32 v49, vcc, 0, v57, vcc
	global_store_dwordx4 v[48:49], v[52:55], off
	v_cvt_pk_bf16_f32 v44, v44, v45
	v_cvt_pk_bf16_f32 v45, v46, v47
	v_cvt_pk_bf16_f32 v40, v40, v41
	v_cvt_pk_bf16_f32 v41, v42, v43
	v_cvt_pk_bf16_f32 v36, v36, v37
	v_cvt_pk_bf16_f32 v37, v38, v39
	v_cvt_pk_bf16_f32 v38, v32, v33
	v_cvt_pk_bf16_f32 v39, v34, v35
	v_mov_b32_e32 v34, 0
	v_mov_b32_e32 v46, 0
	v_mov_b32_e32 v35, 0
	v_mov_b32_dpp v34, v38 row_ror:8 row_mask:0xf bank_mask:0xf
	v_mov_b32_dpp v46, v40 row_ror:8 row_mask:0xf bank_mask:0xf
	v_mov_b32_e32 v47, 0
	v_mov_b32_dpp v35, v39 row_ror:8 row_mask:0xf bank_mask:0xf
	v_cndmask_b32_e64 v34, v34, v40, s[4:5]
	v_add_u32_e32 v40, v149, v156
	v_mov_b32_dpp v47, v41 row_ror:8 row_mask:0xf bank_mask:0xf
	v_cndmask_b32_e64 v35, v35, v41, s[4:5]
	v_ashrrev_i32_e32 v41, 31, v40
	v_mov_b32_e32 v32, 0
	v_mov_b32_e32 v33, 0
	v_lshlrev_b64 v[40:41], 12, v[40:41]
	v_mov_b32_dpp v32, v36 row_ror:8 row_mask:0xf bank_mask:0xf
	v_mov_b32_dpp v33, v37 row_ror:8 row_mask:0xf bank_mask:0xf
	v_lshl_add_u64 v[40:41], s[6:7], 0, v[40:41]
	v_mov_b32_e32 v42, 0
	v_mov_b32_e32 v43, 0
	v_cndmask_b32_e64 v32, v32, v44, s[4:5]
	v_cndmask_b32_e64 v33, v33, v45, s[4:5]
	v_lshl_add_u64 v[40:41], v[40:41], 0, v[112:113]
	v_mov_b32_dpp v42, v44 row_ror:8 row_mask:0xf bank_mask:0xf
	v_mov_b32_dpp v43, v45 row_ror:8 row_mask:0xf bank_mask:0xf
	global_store_dwordx4 v[40:41], v[32:35], off
	v_cndmask_b32_e64 v36, v36, v42, s[4:5]
	v_cndmask_b32_e64 v37, v37, v43, s[4:5]
	v_add_co_u32_e32 v32, vcc, s66, v40
	v_cndmask_b32_e64 v38, v38, v46, s[4:5]
	v_cndmask_b32_e64 v39, v39, v47, s[4:5]
	v_addc_co_u32_e32 v33, vcc, 0, v41, vcc
	global_store_dwordx4 v[32:33], v[36:39], off
	v_cvt_pk_bf16_f32 v28, v28, v29
	v_cvt_pk_bf16_f32 v29, v30, v31
	v_cvt_pk_bf16_f32 v24, v24, v25
	v_cvt_pk_bf16_f32 v25, v26, v27
	v_cvt_pk_bf16_f32 v20, v20, v21
	v_cvt_pk_bf16_f32 v21, v22, v23
	v_cvt_pk_bf16_f32 v22, v16, v17
	v_cvt_pk_bf16_f32 v23, v18, v19
	v_mov_b32_e32 v18, 0
	v_mov_b32_e32 v30, 0
	v_mov_b32_e32 v19, 0
	v_mov_b32_dpp v18, v22 row_ror:8 row_mask:0xf bank_mask:0xf
	v_mov_b32_dpp v30, v24 row_ror:8 row_mask:0xf bank_mask:0xf
	v_mov_b32_e32 v31, 0
	v_mov_b32_dpp v19, v23 row_ror:8 row_mask:0xf bank_mask:0xf
	v_cndmask_b32_e64 v18, v18, v24, s[4:5]
	v_add_u32_e32 v24, v150, v156
	v_mov_b32_dpp v31, v25 row_ror:8 row_mask:0xf bank_mask:0xf
	v_cndmask_b32_e64 v19, v19, v25, s[4:5]
	v_ashrrev_i32_e32 v25, 31, v24
	v_mov_b32_e32 v16, 0
	v_mov_b32_e32 v17, 0
	v_lshlrev_b64 v[24:25], 12, v[24:25]
	v_mov_b32_dpp v16, v20 row_ror:8 row_mask:0xf bank_mask:0xf
	v_mov_b32_dpp v17, v21 row_ror:8 row_mask:0xf bank_mask:0xf
	v_lshl_add_u64 v[24:25], s[6:7], 0, v[24:25]
	v_mov_b32_e32 v26, 0
	v_mov_b32_e32 v27, 0
	v_cndmask_b32_e64 v16, v16, v28, s[4:5]
	v_cndmask_b32_e64 v17, v17, v29, s[4:5]
	v_lshl_add_u64 v[24:25], v[24:25], 0, v[112:113]
	v_mov_b32_dpp v26, v28 row_ror:8 row_mask:0xf bank_mask:0xf
	v_mov_b32_dpp v27, v29 row_ror:8 row_mask:0xf bank_mask:0xf
	global_store_dwordx4 v[24:25], v[16:19], off
	v_cndmask_b32_e64 v20, v20, v26, s[4:5]
	v_cndmask_b32_e64 v21, v21, v27, s[4:5]
	v_add_co_u32_e32 v16, vcc, s66, v24
	v_cndmask_b32_e64 v22, v22, v30, s[4:5]
	v_cndmask_b32_e64 v23, v23, v31, s[4:5]
	v_addc_co_u32_e32 v17, vcc, 0, v25, vcc
	global_store_dwordx4 v[16:17], v[20:23], off
	v_cvt_pk_bf16_f32 v12, v12, v13
	v_cvt_pk_bf16_f32 v13, v14, v15
	v_cvt_pk_bf16_f32 v8, v8, v9
	v_cvt_pk_bf16_f32 v9, v10, v11
	v_cvt_pk_bf16_f32 v4, v4, v5
	v_cvt_pk_bf16_f32 v5, v6, v7
	v_cvt_pk_bf16_f32 v6, v0, v1
	v_cvt_pk_bf16_f32 v7, v2, v3
	v_mov_b32_e32 v2, 0
	v_mov_b32_e32 v14, 0
	v_mov_b32_e32 v3, 0
	v_mov_b32_dpp v2, v6 row_ror:8 row_mask:0xf bank_mask:0xf
	v_mov_b32_dpp v14, v8 row_ror:8 row_mask:0xf bank_mask:0xf
	v_mov_b32_e32 v15, 0
	v_mov_b32_dpp v3, v7 row_ror:8 row_mask:0xf bank_mask:0xf
	v_cndmask_b32_e64 v2, v2, v8, s[4:5]
	v_add_u32_e32 v8, v151, v156
	v_mov_b32_dpp v15, v9 row_ror:8 row_mask:0xf bank_mask:0xf
	v_cndmask_b32_e64 v3, v3, v9, s[4:5]
	v_ashrrev_i32_e32 v9, 31, v8
	v_mov_b32_e32 v0, 0
	v_mov_b32_e32 v1, 0
	v_lshlrev_b64 v[8:9], 12, v[8:9]
	v_mov_b32_dpp v0, v4 row_ror:8 row_mask:0xf bank_mask:0xf
	v_mov_b32_dpp v1, v5 row_ror:8 row_mask:0xf bank_mask:0xf
	v_lshl_add_u64 v[8:9], s[6:7], 0, v[8:9]
	v_cndmask_b32_e64 v0, v0, v12, s[4:5]
	v_cndmask_b32_e64 v1, v1, v13, s[4:5]
	v_lshl_add_u64 v[8:9], v[8:9], 0, v[112:113]
	v_mov_b32_e32 v10, 0
	v_mov_b32_e32 v11, 0
	global_store_dwordx4 v[8:9], v[0:3], off
	v_mov_b32_dpp v10, v12 row_ror:8 row_mask:0xf bank_mask:0xf
	v_mov_b32_dpp v11, v13 row_ror:8 row_mask:0xf bank_mask:0xf
	v_add_co_u32_e32 v0, vcc, 0x8000, v8
	v_cndmask_b32_e64 v4, v4, v10, s[4:5]
	s_nop 0
	v_addc_co_u32_e32 v1, vcc, 0, v9, vcc
	v_cndmask_b32_e64 v5, v5, v11, s[4:5]
	v_cndmask_b32_e64 v6, v6, v14, s[4:5]
	v_cndmask_b32_e64 v7, v7, v15, s[4:5]
	s_and_b64 vcc, exec, s[34:35]
	s_mov_b32 s38, s18
	s_mov_b64 s[40:41], s[36:37]
	s_mov_b64 s[42:43], s[30:31]
	global_store_dwordx4 v[0:1], v[4:7], off
	s_cbranch_vccz .LBB0_243
	s_waitcnt vmcnt(0)
	s_cmpk_gt_u32 s52, 0xff
	s_cbranch_scc1 .LBB0_252
	s_barrier

; #define PG8_STAGE(bufoff, gbase, voff) do { _Pragma("unroll") for (int _i = 0; _i < 2; ++_i) \
;         __builtin_amdgcn_global_load_lds((const unsigned*)((const char*)(gbase) + (voff)[_i]), (LAS unsigned*)(lds + (bufoff) + ldsw + _i * 8192), 16, 0, 0); } while (0)
; #define PG8_LDA(dst, b, h) do { _Pragma("unroll") for (int m = 0; m < 4; ++m) _Pragma("unroll") for (int k = 0; k < 2; ++k) dst[m][k] = *(const LAS bf16x8*)(lds + PG8_SA(b, h) + aoff + m * 2048 + k * 1024); } while (0)
; #define PG8_LDB(dst, b, h) do { _Pragma("unroll") for (int n = 0; n < 2; ++n) _Pragma("unroll") for (int k = 0; k < 2; ++k) dst[n][k] = *(const LAS bf16x8*)(lds + PG8_SB(b, h) + boff + n * 2048 + k * 1024); } while (0)
; #define PG8_MMA(ai, bj, At, Bt) do { __builtin_amdgcn_s_setprio(1); _Pragma("unroll") for (int m = 0; m < 4; ++m) _Pragma("unroll") for (int n = 0; n < 2; ++n) _Pragma("unroll") for (int k = 0; k < 2; ++k) \
;         acc[ai][bj][m][n] = __builtin_amdgcn_mfma_f32_16x16x32_bf16(Bt[n][k], At[m][k], acc[ai][bj][m][n], 0, 0, 0); __builtin_amdgcn_s_setprio(0); } while (0)
; template <class Epi>
; __device__ __forceinline__ void gemm_phase(LAS unsigned char* lds, const Gemm g, const StaticOrder& S, const Epi& E) {
;     ...
;         for (int t = 0; t < nt; t += 2) {
;             const bool last = (t == nt - 2);
;             const char* a1 = cA + (size_t)(t + 1) * kstep;
;             const char* a2 = last ? nA : cA + (size_t)(t + 2) * kstep; const char* b2 = last ? nB : cB + (size_t)(t + 2) * kstep;
;             const char* a3 = a2 + kstep; const char* b3 = b2 + kstep;
;             PG8_LDB(B0, 0, 0); PG8_SCHED; PG8_LDA(At, 0, 0); PG8_STAGE(PG8_SA(1, 1), a1 + hstep, voffA);
;             PG8_WAIT_L(8); PG8_BAR; PG8_WAIT_L(0); PG8_MMA(0, 0, At, B0); PG8_BAR; PG8_SCHED;
;             PG8_LDB(B1, 0, 1); PG8_STAGE(PG8_SB(0, 0), b2, voffB0);
;             PG8_BAR; PG8_WAIT_L(0); PG8_MMA(0, 1, At, B1); PG8_BAR;
;             PG8_LDA(At, 0, 1); PG8_STAGE(PG8_SA(0, 0), a2, voffA);
;             PG8_BAR; PG8_WAIT_L(0); PG8_MMA(1, 0, At, B0); PG8_BAR; PG8_SCHED;
;             PG8_STAGE(PG8_SB(0, 1), b2, voffB1);
;             PG8_WAIT_V(6); PG8_BAR; PG8_MMA(1, 1, At, B1); PG8_BAR;
;             PG8_LDB(B0, 1, 0); PG8_SCHED; PG8_LDA(At, 1, 0); PG8_STAGE(PG8_SA(0, 1), a2 + hstep, voffA);
;             PG8_WAIT_L(8); PG8_BAR; PG8_WAIT_L(0); PG8_MMA(0, 0, At, B0); PG8_BAR; PG8_SCHED;
.LBB0_613:
	ds_read_b128 v[146:149], v155
	ds_read_b128 v[158:161], v155 offset:1024
	ds_read_b128 v[162:165], v155 offset:2048
	ds_read_b128 v[166:169], v155 offset:3072
	s_add_u32 s33, s54, 0xfff80080
	s_addc_u32 s56, s55, -1
	s_cmp_eq_u32 s88, 28
	s_cselect_b32 s57, s43, s56
	s_cselect_b32 s56, s51, s33
	s_cselect_b32 s59, s41, s87
	s_cselect_b32 s58, s85, s86
	v_lshl_add_u64 v[204:205], s[54:55], 0, v[140:141]
	s_add_i32 m0, s53, 0xc000
	ds_read_b128 v[170:173], v156
	ds_read_b128 v[174:177], v156 offset:1024
	ds_read_b128 v[178:181], v156 offset:2048
	ds_read_b128 v[182:185], v156 offset:3072
	ds_read_b128 v[186:189], v156 offset:4096
	ds_read_b128 v[190:193], v156 offset:5120
	ds_read_b128 v[194:197], v156 offset:6144
	ds_read_b128 v[198:201], v156 offset:7168
	global_load_lds_dwordx4 v[204:205], off
	v_lshl_add_u64 v[204:205], s[54:55], 0, v[142:143]
	s_add_i32 m0, s53, 0xe000
	s_nop 0
	global_load_lds_dwordx4 v[204:205], off
	s_waitcnt lgkmcnt(8)
	s_barrier
	s_waitcnt lgkmcnt(0)
	s_waitcnt lgkmcnt(0)
	v_mfma_f32_16x16x32_bf16 v[124:127], v[146:149], v[170:173], v[124:127]
	v_mfma_f32_16x16x32_bf16 v[120:123], v[162:165], v[170:173], v[120:123]
	v_mfma_f32_16x16x32_bf16 v[108:111], v[146:149], v[178:181], v[108:111]
	v_mfma_f32_16x16x32_bf16 v[104:107], v[162:165], v[178:181], v[104:107]
	v_mfma_f32_16x16x32_bf16 v[92:95], v[146:149], v[186:189], v[92:95]
	v_mfma_f32_16x16x32_bf16 v[88:91], v[162:165], v[186:189], v[88:91]
	v_mfma_f32_16x16x32_bf16 v[76:79], v[146:149], v[194:197], v[76:79]
	v_mfma_f32_16x16x32_bf16 v[72:75], v[162:165], v[194:197], v[72:75]
	v_mfma_f32_16x16x32_bf16 v[124:127], v[158:161], v[174:177], v[124:127]
	v_mfma_f32_16x16x32_bf16 v[120:123], v[166:169], v[174:177], v[120:123]
	v_mfma_f32_16x16x32_bf16 v[108:111], v[158:161], v[182:185], v[108:111]
	v_mfma_f32_16x16x32_bf16 v[104:107], v[166:169], v[182:185], v[104:107]
	v_mfma_f32_16x16x32_bf16 v[92:95], v[158:161], v[190:193], v[92:95]
	v_mfma_f32_16x16x32_bf16 v[88:91], v[166:169], v[190:193], v[88:91]
	v_mfma_f32_16x16x32_bf16 v[76:79], v[158:161], v[198:201], v[76:79]
	v_mfma_f32_16x16x32_bf16 v[72:75], v[166:169], v[198:201], v[72:75]
	s_barrier
	s_add_i32 s33, s79, s65
	v_lshl_add_u64 v[220:221], s[58:59], 0, v[130:131]
	s_mov_b32 m0, s33
	ds_read_b128 v[204:207], v157
	ds_read_b128 v[208:211], v157 offset:1024
	ds_read_b128 v[212:215], v157 offset:2048
	ds_read_b128 v[216:219], v157 offset:3072
	global_load_lds_dwordx4 v[220:221], off
	v_lshl_add_u64 v[222:223], s[58:59], 0, v[136:137]
	s_add_i32 m0, s33, 0x2000
	s_nop 0
	global_load_lds_dwordx4 v[222:223], off
	s_barrier
	s_waitcnt lgkmcnt(0)
	s_waitcnt lgkmcnt(0)
	v_mfma_f32_16x16x32_bf16 v[116:119], v[204:207], v[170:173], v[116:119]
	v_mfma_f32_16x16x32_bf16 v[112:115], v[212:215], v[170:173], v[112:115]
	v_mfma_f32_16x16x32_bf16 v[100:103], v[204:207], v[178:181], v[100:103]
	v_mfma_f32_16x16x32_bf16 v[96:99], v[212:215], v[178:181], v[96:99]
	v_mfma_f32_16x16x32_bf16 v[84:87], v[204:207], v[186:189], v[84:87]
	v_mfma_f32_16x16x32_bf16 v[80:83], v[212:215], v[186:189], v[80:83]
	v_mfma_f32_16x16x32_bf16 v[68:71], v[204:207], v[194:197], v[68:71]
	v_mfma_f32_16x16x32_bf16 v[64:67], v[212:215], v[194:197], v[64:67]
	v_mfma_f32_16x16x32_bf16 v[116:119], v[208:211], v[174:177], v[116:119]
	v_mfma_f32_16x16x32_bf16 v[112:115], v[216:219], v[174:177], v[112:115]
	v_mfma_f32_16x16x32_bf16 v[100:103], v[208:211], v[182:185], v[100:103]
	v_mfma_f32_16x16x32_bf16 v[96:99], v[216:219], v[182:185], v[96:99]
	v_mfma_f32_16x16x32_bf16 v[84:87], v[208:211], v[190:193], v[84:87]
	v_mfma_f32_16x16x32_bf16 v[80:83], v[216:219], v[190:193], v[80:83]
	v_mfma_f32_16x16x32_bf16 v[68:71], v[208:211], v[198:201], v[68:71]
	v_mfma_f32_16x16x32_bf16 v[64:67], v[216:219], v[198:201], v[64:67]
	s_mov_b32 m0, s53
	v_lshl_add_u64 v[224:225], s[56:57], 0, v[128:129]
	s_barrier
	ds_read_b128 v[170:173], v156 offset:16384
	ds_read_b128 v[174:177], v156 offset:17408
	ds_read_b128 v[178:181], v156 offset:18432
	ds_read_b128 v[182:185], v156 offset:19456
	ds_read_b128 v[186:189], v156 offset:20480
	ds_read_b128 v[190:193], v156 offset:21504
	ds_read_b128 v[194:197], v156 offset:22528
	ds_read_b128 v[198:201], v156 offset:23552
	global_load_lds_dwordx4 v[224:225], off
	v_lshl_add_u64 v[226:227], s[56:57], 0, v[134:135]
	s_mov_b32 m0, s66
	s_nop 0
	global_load_lds_dwordx4 v[226:227], off
	s_barrier
	s_waitcnt lgkmcnt(0)
	s_waitcnt lgkmcnt(0)
	v_mfma_f32_16x16x32_bf16 v[60:63], v[146:149], v[170:173], v[60:63]
	v_mfma_f32_16x16x32_bf16 v[56:59], v[162:165], v[170:173], v[56:59]
	v_mfma_f32_16x16x32_bf16 v[44:47], v[146:149], v[178:181], v[44:47]
	v_mfma_f32_16x16x32_bf16 v[40:43], v[162:165], v[178:181], v[40:43]
	v_mfma_f32_16x16x32_bf16 v[28:31], v[146:149], v[186:189], v[28:31]
	v_mfma_f32_16x16x32_bf16 v[24:27], v[162:165], v[186:189], v[24:27]
	v_mfma_f32_16x16x32_bf16 v[12:15], v[146:149], v[194:197], v[12:15]
	v_mfma_f32_16x16x32_bf16 v[8:11], v[162:165], v[194:197], v[8:11]
	v_mfma_f32_16x16x32_bf16 v[60:63], v[158:161], v[174:177], v[60:63]
	v_mfma_f32_16x16x32_bf16 v[56:59], v[166:169], v[174:177], v[56:59]
	v_mfma_f32_16x16x32_bf16 v[44:47], v[158:161], v[182:185], v[44:47]
	v_mfma_f32_16x16x32_bf16 v[40:43], v[166:169], v[182:185], v[40:43]
	v_mfma_f32_16x16x32_bf16 v[28:31], v[158:161], v[190:193], v[28:31]
	v_mfma_f32_16x16x32_bf16 v[24:27], v[166:169], v[190:193], v[24:27]
	v_mfma_f32_16x16x32_bf16 v[12:15], v[158:161], v[198:201], v[12:15]
	v_mfma_f32_16x16x32_bf16 v[8:11], v[166:169], v[198:201], v[8:11]
	s_barrier
; #define PG8_STAGE(bufoff, gbase, voff) do { _Pragma("unroll") for (int _i = 0; _i < 2; ++_i) \
;         __builtin_amdgcn_global_load_lds((const unsigned*)((const char*)(gbase) + (voff)[_i]), (LAS unsigned*)(lds + (bufoff) + ldsw + _i * 8192), 16, 0, 0); } while (0)
; #define PG8_LDA(dst, b, h) do { _Pragma("unroll") for (int m = 0; m < 4; ++m) _Pragma("unroll") for (int k = 0; k < 2; ++k) dst[m][k] = *(const LAS bf16x8*)(lds + PG8_SA(b, h) + aoff + m * 2048 + k * 1024); } while (0)
; #define PG8_LDB(dst, b, h) do { _Pragma("unroll") for (int n = 0; n < 2; ++n) _Pragma("unroll") for (int k = 0; k < 2; ++k) dst[n][k] = *(const LAS bf16x8*)(lds + PG8_SB(b, h) + boff + n * 2048 + k * 1024); } while (0)
; #define PG8_MMA(ai, bj, At, Bt) do { __builtin_amdgcn_s_setprio(1); _Pragma("unroll") for (int m = 0; m < 4; ++m) _Pragma("unroll") for (int n = 0; n < 2; ++n) _Pragma("unroll") for (int k = 0; k < 2; ++k) \
;         acc[ai][bj][m][n] = __builtin_amdgcn_mfma_f32_16x16x32_bf16(Bt[n][k], At[m][k], acc[ai][bj][m][n], 0, 0, 0); __builtin_amdgcn_s_setprio(0); } while (0)
; #define PG8_WAIT_V(n) asm volatile("s_waitcnt vmcnt(" #n ")" ::: "memory")
; #define PG8_WAIT_L(n) asm volatile("s_waitcnt lgkmcnt(" #n ")" ::: "memory")
; #define PG8_BAR __builtin_amdgcn_s_barrier()
; #define PG8_SCHED __builtin_amdgcn_sched_barrier(0)
; template <class Epi>
; __device__ __forceinline__ void gemm_phase(LAS unsigned char* lds, const Gemm g, const StaticOrder& S, const Epi& E) {
;     ...
;             PG8_STAGE(PG8_SB(0, 1), b2, voffB1);
;             PG8_WAIT_V(6); PG8_BAR; PG8_MMA(1, 1, At, B1); PG8_BAR;
;             PG8_LDB(B0, 1, 0); PG8_SCHED; PG8_LDA(At, 1, 0); PG8_STAGE(PG8_SA(0, 1), a2 + hstep, voffA);
;             PG8_WAIT_L(8); PG8_BAR; PG8_WAIT_L(0); PG8_MMA(0, 0, At, B0); PG8_BAR; PG8_SCHED;
;             PG8_LDB(B1, 1, 1); PG8_STAGE(PG8_SB(1, 0), b3, voffB0);
;             PG8_BAR; PG8_WAIT_L(0); PG8_MMA(0, 1, At, B1); PG8_BAR;
;             PG8_LDA(At, 1, 1); PG8_STAGE(PG8_SA(1, 0), a3, voffA);
;             PG8_BAR; PG8_WAIT_L(0); PG8_MMA(1, 0, At, B0); PG8_BAR; PG8_SCHED;
	s_add_i32 s33, s80, s65
	v_lshl_add_u64 v[228:229], s[58:59], 0, v[132:133]
	s_mov_b32 m0, s33
	v_lshl_add_u64 v[230:231], s[58:59], 0, v[138:139]
	global_load_lds_dwordx4 v[228:229], off
	s_add_i32 m0, s33, 0x2000
	s_nop 0
	global_load_lds_dwordx4 v[230:231], off
	s_waitcnt vmcnt(6)
	s_barrier
	v_mfma_f32_16x16x32_bf16 v[52:55], v[204:207], v[170:173], v[52:55]
	v_mfma_f32_16x16x32_bf16 v[48:51], v[212:215], v[170:173], v[48:51]
	v_mfma_f32_16x16x32_bf16 v[36:39], v[204:207], v[178:181], v[36:39]
	v_mfma_f32_16x16x32_bf16 v[32:35], v[212:215], v[178:181], v[32:35]
	v_mfma_f32_16x16x32_bf16 v[20:23], v[204:207], v[186:189], v[20:23]
	v_mfma_f32_16x16x32_bf16 v[16:19], v[212:215], v[186:189], v[16:19]
	v_mfma_f32_16x16x32_bf16 v[4:7], v[204:207], v[194:197], v[4:7]
	v_mfma_f32_16x16x32_bf16 v[0:3], v[212:215], v[194:197], v[0:3]
	v_mfma_f32_16x16x32_bf16 v[52:55], v[208:211], v[174:177], v[52:55]
	v_mfma_f32_16x16x32_bf16 v[48:51], v[216:219], v[174:177], v[48:51]
	v_mfma_f32_16x16x32_bf16 v[36:39], v[208:211], v[182:185], v[36:39]
	v_mfma_f32_16x16x32_bf16 v[32:35], v[216:219], v[182:185], v[32:35]
	v_mfma_f32_16x16x32_bf16 v[20:23], v[208:211], v[190:193], v[20:23]
	v_mfma_f32_16x16x32_bf16 v[16:19], v[216:219], v[190:193], v[16:19]
	v_mfma_f32_16x16x32_bf16 v[4:7], v[208:211], v[198:201], v[4:7]
	v_mfma_f32_16x16x32_bf16 v[0:3], v[216:219], v[198:201], v[0:3]
	s_add_i32 s33, 0, 0x18000
	v_add_u32_e32 v166, s33, v151
	s_barrier
	ds_read_b128 v[146:149], v166
	ds_read_b128 v[158:161], v166 offset:1024
	ds_read_b128 v[162:165], v166 offset:2048
	ds_read_b128 v[166:169], v166 offset:3072
	s_add_u32 s56, s56, 0x80000
	s_addc_u32 s57, s57, 0
	s_mov_b32 m0, s67
	v_lshl_add_u64 v[204:205], s[56:57], 0, v[128:129]
	ds_read_b128 v[170:173], v156 offset:32768
	ds_read_b128 v[174:177], v156 offset:33792
	ds_read_b128 v[178:181], v156 offset:34816
	ds_read_b128 v[182:185], v156 offset:35840
	ds_read_b128 v[186:189], v156 offset:36864
	ds_read_b128 v[190:193], v156 offset:37888
	ds_read_b128 v[194:197], v156 offset:38912
	ds_read_b128 v[198:201], v156 offset:39936
	global_load_lds_dwordx4 v[204:205], off
	v_lshl_add_u64 v[204:205], s[56:57], 0, v[134:135]
	s_mov_b32 m0, s68
	s_nop 0
	global_load_lds_dwordx4 v[204:205], off
	s_waitcnt lgkmcnt(8)
	s_barrier
	s_waitcnt lgkmcnt(0)
	s_waitcnt lgkmcnt(0)
	v_mfma_f32_16x16x32_bf16 v[124:127], v[146:149], v[170:173], v[124:127]
	v_mfma_f32_16x16x32_bf16 v[120:123], v[162:165], v[170:173], v[120:123]
	v_mfma_f32_16x16x32_bf16 v[108:111], v[146:149], v[178:181], v[108:111]
	v_mfma_f32_16x16x32_bf16 v[104:107], v[162:165], v[178:181], v[104:107]
	v_mfma_f32_16x16x32_bf16 v[92:95], v[146:149], v[186:189], v[92:95]
	v_mfma_f32_16x16x32_bf16 v[88:91], v[162:165], v[186:189], v[88:91]
	v_mfma_f32_16x16x32_bf16 v[76:79], v[146:149], v[194:197], v[76:79]
	v_mfma_f32_16x16x32_bf16 v[72:75], v[162:165], v[194:197], v[72:75]
	v_mfma_f32_16x16x32_bf16 v[124:127], v[158:161], v[174:177], v[124:127]
	v_mfma_f32_16x16x32_bf16 v[120:123], v[166:169], v[174:177], v[120:123]
	v_mfma_f32_16x16x32_bf16 v[108:111], v[158:161], v[182:185], v[108:111]
	v_mfma_f32_16x16x32_bf16 v[104:107], v[166:169], v[182:185], v[104:107]
	v_mfma_f32_16x16x32_bf16 v[92:95], v[158:161], v[190:193], v[92:95]
	v_mfma_f32_16x16x32_bf16 v[88:91], v[166:169], v[190:193], v[88:91]
	v_mfma_f32_16x16x32_bf16 v[76:79], v[158:161], v[198:201], v[76:79]
	v_mfma_f32_16x16x32_bf16 v[72:75], v[166:169], v[198:201], v[72:75]
	s_barrier
	s_add_i32 s56, 0, 0x1c000
	s_add_i32 s33, s33, s65
	v_add_u32_e32 v216, s56, v151
	v_lshl_add_u64 v[220:221], v[220:221], 0, s[36:37]
	s_mov_b32 m0, s33
	ds_read_b128 v[204:207], v216
	ds_read_b128 v[208:211], v216 offset:1024
	ds_read_b128 v[212:215], v216 offset:2048
	ds_read_b128 v[216:219], v216 offset:3072
	global_load_lds_dwordx4 v[220:221], off
	v_lshl_add_u64 v[220:221], v[222:223], 0, s[36:37]
	s_add_i32 m0, s33, 0x2000
	s_nop 0
	global_load_lds_dwordx4 v[220:221], off
	s_barrier
	s_waitcnt lgkmcnt(0)
	s_waitcnt lgkmcnt(0)
	v_mfma_f32_16x16x32_bf16 v[116:119], v[204:207], v[170:173], v[116:119]
	v_mfma_f32_16x16x32_bf16 v[112:115], v[212:215], v[170:173], v[112:115]
	v_mfma_f32_16x16x32_bf16 v[100:103], v[204:207], v[178:181], v[100:103]
	v_mfma_f32_16x16x32_bf16 v[96:99], v[212:215], v[178:181], v[96:99]
	v_mfma_f32_16x16x32_bf16 v[84:87], v[204:207], v[186:189], v[84:87]
	v_mfma_f32_16x16x32_bf16 v[80:83], v[212:215], v[186:189], v[80:83]
	v_mfma_f32_16x16x32_bf16 v[68:71], v[204:207], v[194:197], v[68:71]
	v_mfma_f32_16x16x32_bf16 v[64:67], v[212:215], v[194:197], v[64:67]
	v_mfma_f32_16x16x32_bf16 v[116:119], v[208:211], v[174:177], v[116:119]
	v_mfma_f32_16x16x32_bf16 v[112:115], v[216:219], v[174:177], v[112:115]
	v_mfma_f32_16x16x32_bf16 v[100:103], v[208:211], v[182:185], v[100:103]
	v_mfma_f32_16x16x32_bf16 v[96:99], v[216:219], v[182:185], v[96:99]
	v_mfma_f32_16x16x32_bf16 v[84:87], v[208:211], v[190:193], v[84:87]
	v_mfma_f32_16x16x32_bf16 v[80:83], v[216:219], v[190:193], v[80:83]
	v_mfma_f32_16x16x32_bf16 v[68:71], v[208:211], v[198:201], v[68:71]
	v_mfma_f32_16x16x32_bf16 v[64:67], v[216:219], v[198:201], v[64:67]
	s_mov_b32 m0, s72
	v_lshl_add_u64 v[220:221], v[224:225], 0, s[36:37]
	s_barrier
	ds_read_b128 v[170:173], v156 offset:49152
	ds_read_b128 v[174:177], v156 offset:50176
	ds_read_b128 v[178:181], v156 offset:51200
	ds_read_b128 v[182:185], v156 offset:52224
	ds_read_b128 v[186:189], v156 offset:53248
	ds_read_b128 v[190:193], v156 offset:54272
	ds_read_b128 v[194:197], v156 offset:55296
	ds_read_b128 v[198:201], v156 offset:56320
	global_load_lds_dwordx4 v[220:221], off
	v_lshl_add_u64 v[220:221], v[226:227], 0, s[36:37]
	s_mov_b32 m0, s73
	s_nop 0
	global_load_lds_dwordx4 v[220:221], off
	s_barrier
; #define PG8_STAGE(bufoff, gbase, voff) do { _Pragma("unroll") for (int _i = 0; _i < 2; ++_i) \
;         __builtin_amdgcn_global_load_lds((const unsigned*)((const char*)(gbase) + (voff)[_i]), (LAS unsigned*)(lds + (bufoff) + ldsw + _i * 8192), 16, 0, 0); } while (0)
; #define PG8_MMA(ai, bj, At, Bt) do { __builtin_amdgcn_s_setprio(1); _Pragma("unroll") for (int m = 0; m < 4; ++m) _Pragma("unroll") for (int n = 0; n < 2; ++n) _Pragma("unroll") for (int k = 0; k < 2; ++k) \
;         acc[ai][bj][m][n] = __builtin_amdgcn_mfma_f32_16x16x32_bf16(Bt[n][k], At[m][k], acc[ai][bj][m][n], 0, 0, 0); __builtin_amdgcn_s_setprio(0); } while (0)
; #define PG8_WAIT_V(n) asm volatile("s_waitcnt vmcnt(" #n ")" ::: "memory")
; #define PG8_WAIT_L(n) asm volatile("s_waitcnt lgkmcnt(" #n ")" ::: "memory")
; #define PG8_BAR __builtin_amdgcn_s_barrier()
; #define PG8_SCHED __builtin_amdgcn_sched_barrier(0)
; template <class Epi>
; __device__ __forceinline__ void gemm_phase(LAS unsigned char* lds, const Gemm g, const StaticOrder& S, const Epi& E) {
;     ...
;             PG8_BAR; PG8_WAIT_L(0); PG8_MMA(1, 0, At, B0); PG8_BAR; PG8_SCHED;
;             PG8_STAGE(PG8_SB(1, 1), b3, voffB1);
;             PG8_WAIT_V(6); PG8_BAR; PG8_MMA(1, 1, At, B1); PG8_BAR;
	s_waitcnt lgkmcnt(0)
	s_waitcnt lgkmcnt(0)
	v_mfma_f32_16x16x32_bf16 v[60:63], v[146:149], v[170:173], v[60:63]
	v_mfma_f32_16x16x32_bf16 v[56:59], v[162:165], v[170:173], v[56:59]
	v_mfma_f32_16x16x32_bf16 v[44:47], v[146:149], v[178:181], v[44:47]
	v_mfma_f32_16x16x32_bf16 v[40:43], v[162:165], v[178:181], v[40:43]
	v_mfma_f32_16x16x32_bf16 v[28:31], v[146:149], v[186:189], v[28:31]
	v_mfma_f32_16x16x32_bf16 v[24:27], v[162:165], v[186:189], v[24:27]
	v_mfma_f32_16x16x32_bf16 v[12:15], v[146:149], v[194:197], v[12:15]
	v_mfma_f32_16x16x32_bf16 v[8:11], v[162:165], v[194:197], v[8:11]
	v_mfma_f32_16x16x32_bf16 v[60:63], v[158:161], v[174:177], v[60:63]
	v_mfma_f32_16x16x32_bf16 v[56:59], v[166:169], v[174:177], v[56:59]
	v_mfma_f32_16x16x32_bf16 v[44:47], v[158:161], v[182:185], v[44:47]
	v_mfma_f32_16x16x32_bf16 v[40:43], v[166:169], v[182:185], v[40:43]
	v_mfma_f32_16x16x32_bf16 v[28:31], v[158:161], v[190:193], v[28:31]
	v_mfma_f32_16x16x32_bf16 v[24:27], v[166:169], v[190:193], v[24:27]
	v_mfma_f32_16x16x32_bf16 v[12:15], v[158:161], v[198:201], v[12:15]
	v_mfma_f32_16x16x32_bf16 v[8:11], v[166:169], v[198:201], v[8:11]
	s_barrier
	s_add_i32 s33, s56, s65
	v_lshl_add_u64 v[146:147], v[228:229], 0, s[36:37]
	s_mov_b32 m0, s33
	s_nop 0
	global_load_lds_dwordx4 v[146:147], off
	v_lshl_add_u64 v[146:147], v[230:231], 0, s[36:37]
	s_add_i32 m0, s33, 0x2000
	s_nop 0
	global_load_lds_dwordx4 v[146:147], off
	s_waitcnt vmcnt(6)
	s_barrier
	v_mfma_f32_16x16x32_bf16 v[52:55], v[204:207], v[170:173], v[52:55]
	v_mfma_f32_16x16x32_bf16 v[48:51], v[212:215], v[170:173], v[48:51]
	v_mfma_f32_16x16x32_bf16 v[36:39], v[204:207], v[178:181], v[36:39]
	v_mfma_f32_16x16x32_bf16 v[32:35], v[212:215], v[178:181], v[32:35]
	v_mfma_f32_16x16x32_bf16 v[20:23], v[204:207], v[186:189], v[20:23]
	v_mfma_f32_16x16x32_bf16 v[16:19], v[212:215], v[186:189], v[16:19]
	v_mfma_f32_16x16x32_bf16 v[4:7], v[204:207], v[194:197], v[4:7]
	v_mfma_f32_16x16x32_bf16 v[0:3], v[212:215], v[194:197], v[0:3]
	v_mfma_f32_16x16x32_bf16 v[52:55], v[208:211], v[174:177], v[52:55]
	v_mfma_f32_16x16x32_bf16 v[48:51], v[216:219], v[174:177], v[48:51]
	v_mfma_f32_16x16x32_bf16 v[36:39], v[208:211], v[182:185], v[36:39]
	v_mfma_f32_16x16x32_bf16 v[32:35], v[216:219], v[182:185], v[32:35]
	v_mfma_f32_16x16x32_bf16 v[20:23], v[208:211], v[190:193], v[20:23]
	v_mfma_f32_16x16x32_bf16 v[16:19], v[216:219], v[190:193], v[16:19]
	v_mfma_f32_16x16x32_bf16 v[4:7], v[208:211], v[198:201], v[4:7]
	v_mfma_f32_16x16x32_bf16 v[0:3], v[216:219], v[198:201], v[0:3]
	s_add_i32 s88, s88, 2
	s_add_u32 s54, s54, 0x100
	s_addc_u32 s55, s55, 0
	s_add_u32 s86, s86, 0x100
	s_addc_u32 s87, s87, 0
	s_cmp_gt_u32 s88, 29
	s_barrier
	s_cbranch_scc0 .LBB0_613
; __device__ __forceinline__ unsigned cvt_pk_bf16(float lo, float hi) { unsigned r; asm volatile("v_cvt_pk_bf16_f32 %0, %1, %2" : "=v"(r) : "v"(lo), "v"(hi)); return r; }
; __device__ __forceinline__ float bflo(unsigned w) { return __uint_as_float(w << 16); }
; __device__ __forceinline__ float bfhi(unsigned w) { return __uint_as_float(w & 0xffff0000u); }
;     __device__ __forceinline__ void operator()(const f32x4 (&acc)[2][2][4][2], const Unit& u, int wr, int wc, int fr, int fq) const {
;         const int row0 = u.pm * BM + wr * 64 + fr, col0 = u.pn * BM + wc * 64 + 16 * fq;
; #pragma unroll
;         for (int ai = 0; ai < 2; ++ai)
; #pragma unroll
;             for (int m = 0; m < 4; ++m) { const int row = row0 + ai * HALF + m * 16; const size_t off = (size_t)row * D + col0; float sq = 0.f; u32x4 w[2];
;                 const float sc = rsin ? __builtin_amdgcn_rcpf(rsin[row] * (1.f / D) + EPS) : 1.0f;
;                 u32x4 rr[2]; if (R) load_pair_lines(R, D, row, fr, col0, rr[0], rr[1]);
; #pragma unroll
;                 for (int bj = 0; bj < 2; ++bj) { f32x4 r0, r1;
;                     if (R) { const u32x4 rw = rr[bj]; r0 = (f32x4){bflo(rw.x), bfhi(rw.x), bflo(rw.y), bfhi(rw.y)}; r1 = (f32x4){bflo(rw.z), bfhi(rw.z), bflo(rw.w), bfhi(rw.w)}; }
;                     else { const float* rp = (row < 8192 ? src_p + off : src_s + (off - (size_t)8192 * D)) + 8 * bj; r0 = *(const f32x4*)rp; r1 = *(const f32x4*)(rp + 4); }
;                     const f32x4 o0 = r0 + acc[ai][bj][m][0] * sc, o1 = r1 + acc[ai][bj][m][1] * sc;
;                     sq += (o0[0] * o0[0] + o0[1] * o0[1]) + (o0[2] * o0[2] + o0[3] * o0[3]) + (o1[0] * o1[0] + o1[1] * o1[1]) + (o1[2] * o1[2] + o1[3] * o1[3]);
;                     w[bj].x = cvt_pk_bf16(o0[0], o0[1]); w[bj].y = cvt_pk_bf16(o0[2], o0[3]); w[bj].z = cvt_pk_bf16(o1[0], o1[1]); w[bj].w = cvt_pk_bf16(o1[2], o1[3]); }
;                 store_pair_lines(O, D, row, fr, col0, w[0], w[1]);
;                 if (ssout) { sq += __shfl_xor(sq, 16); sq += __shfl_xor(sq, 32); if (fq == 0) unsafeAtomicAdd(ssout + row, sq); } }
	s_lshl_b32 s33, s52, 8
	s_add_i32 s33, s33, s74
	v_or_b32_e32 v146, s33, v150
	v_lshl_or_b32 v148, s50, 8, v154
	v_ashrrev_i32_e32 v147, 31, v146
	v_ashrrev_i32_e32 v149, 31, v148
	v_lshlrev_b64 v[158:159], 11, v[146:147]
	v_lshl_add_u64 v[158:159], v[158:159], 0, v[148:149]
	v_lshlrev_b64 v[158:159], 2, v[158:159]
	v_lshl_add_u64 v[160:161], s[16:17], 0, v[158:159]
	v_lshl_add_u64 v[158:159], s[18:19], 0, v[158:159]
	v_lshl_add_u64 v[158:159], v[158:159], 0, s[38:39]
	v_cmp_gt_i32_e32 vcc, s70, v146
	v_mov_b32_e32 v183, 0
	v_mov_b32_e32 v184, 0
	v_cndmask_b32_e32 v167, v159, v161, vcc
	v_cndmask_b32_e32 v166, v158, v160, vcc
	global_load_dwordx4 v[158:161], v[166:167], off
	global_load_dwordx4 v[162:165], v[166:167], off offset:16
	v_or_b32_e32 v188, 16, v146
	v_ashrrev_i32_e32 v189, 31, v188
	v_lshlrev_b64 v[190:191], 11, v[188:189]
	v_lshl_add_u64 v[190:191], v[190:191], 0, v[148:149]
	v_lshlrev_b64 v[190:191], 2, v[190:191]
	v_lshl_add_u64 v[192:193], s[16:17], 0, v[190:191]
	v_lshl_add_u64 v[190:191], s[18:19], 0, v[190:191]
	v_lshl_add_u64 v[190:191], v[190:191], 0, s[38:39]
	v_cmp_gt_i32_e32 vcc, s70, v188
	s_nop 1
	v_cndmask_b32_e32 v195, v191, v193, vcc
	v_cndmask_b32_e32 v194, v190, v192, vcc
	global_load_dwordx4 v[196:199], v[194:195], off
	global_load_dwordx4 v[204:207], v[194:195], off offset:16
	global_load_dwordx4 v[208:211], v[194:195], off offset:32
	global_load_dwordx4 v[212:215], v[194:195], off offset:48
	v_or_b32_e32 v188, 32, v146
	v_ashrrev_i32_e32 v189, 31, v188
	v_lshlrev_b64 v[190:191], 11, v[188:189]
	v_lshl_add_u64 v[190:191], v[190:191], 0, v[148:149]
	v_lshlrev_b64 v[190:191], 2, v[190:191]
	v_lshl_add_u64 v[192:193], s[16:17], 0, v[190:191]
	v_lshl_add_u64 v[190:191], s[18:19], 0, v[190:191]
	v_lshl_add_u64 v[190:191], v[190:191], 0, s[38:39]
	v_cmp_gt_i32_e32 vcc, s70, v188
	s_nop 1
	v_cndmask_b32_e32 v195, v191, v193, vcc
	v_cndmask_b32_e32 v194, v190, v192, vcc
	global_load_dwordx4 v[216:219], v[194:195], off
	global_load_dwordx4 v[220:223], v[194:195], off offset:16
	global_load_dwordx4 v[224:227], v[194:195], off offset:32
	global_load_dwordx4 v[228:231], v[194:195], off offset:48
	v_or_b32_e32 v188, 48, v146
	v_ashrrev_i32_e32 v189, 31, v188
	v_lshlrev_b64 v[190:191], 11, v[188:189]
	v_lshl_add_u64 v[190:191], v[190:191], 0, v[148:149]
	v_lshlrev_b64 v[190:191], 2, v[190:191]
	v_lshl_add_u64 v[192:193], s[16:17], 0, v[190:191]
	v_lshl_add_u64 v[190:191], s[18:19], 0, v[190:191]
	v_lshl_add_u64 v[190:191], v[190:191], 0, s[38:39]
	v_cmp_gt_i32_e32 vcc, s70, v188
	s_nop 1
	v_cndmask_b32_e32 v195, v191, v193, vcc
	v_cndmask_b32_e32 v194, v190, v192, vcc
	global_load_dwordx4 v[232:235], v[194:195], off
	global_load_dwordx4 v[236:239], v[194:195], off offset:16
	global_load_dwordx4 v[240:243], v[194:195], off offset:32
	global_load_dwordx4 v[244:247], v[194:195], off offset:48
	v_mov_b32_e32 v185, 0
	v_mov_b32_e32 v186, 0
	v_mov_b32_e32 v179, 0
	v_mov_b32_e32 v180, 0
	v_mov_b32_e32 v181, 0
	v_mov_b32_e32 v182, 0
	s_waitcnt vmcnt(12)
	v_pk_add_f32 v[168:169], v[126:127], v[160:161]
	v_pk_add_f32 v[170:171], v[124:125], v[158:159]
	v_pk_add_f32 v[164:165], v[122:123], v[164:165]
	v_pk_add_f32 v[162:163], v[120:121], v[162:163]
	v_cvt_pk_bf16_f32 v123, v170, v171
	v_cvt_pk_bf16_f32 v176, v168, v169
	v_mul_f32_e32 v171, v171, v171
	v_cvt_pk_bf16_f32 v177, v162, v163
	v_cvt_pk_bf16_f32 v178, v164, v165
	global_load_dwordx4 v[124:127], v[166:167], off offset:32
	global_load_dwordx4 v[158:161], v[166:167], off offset:48
	v_mul_f32_e32 v169, v169, v169
	v_and_b32_e32 v121, 64, v203
	v_mul_f32_e32 v163, v163, v163
	v_fmac_f32_e32 v171, v170, v170
	v_fmac_f32_e32 v169, v168, v168
	v_xor_b32_e32 v122, 16, v203
	v_add_u32_e32 v172, 64, v121
	v_mul_f32_e32 v165, v165, v165
	v_fmac_f32_e32 v163, v162, v162
	v_add_f32_e32 v162, v171, v169
	v_cmp_lt_i32_e32 vcc, v122, v172
	v_fmac_f32_e32 v165, v164, v164
	v_add_f32_e32 v162, v163, v162
	v_cndmask_b32_e32 v122, v203, v122, vcc
	v_add_f32_e32 v162, v165, v162
	v_xor_b32_e32 v167, 32, v203
	v_lshlrev_b32_e32 v122, 2, v122
	v_or_b32_e32 v166, s33, v152
	v_cmp_lt_i32_e32 vcc, v167, v172
	v_or_b32_e32 v120, v148, v153
	v_ashrrev_i32_e32 v121, 31, v120
	v_cndmask_b32_e32 v187, v203, v167, vcc
	v_ashrrev_i32_e32 v167, 31, v166
	v_or_b32_e32 v174, 8, v166
	v_lshlrev_b64 v[166:167], 12, v[166:167]
	v_lshlrev_b64 v[172:173], 1, v[120:121]
	v_lshl_add_u64 v[166:167], s[10:11], 0, v[166:167]
	v_lshl_add_u64 v[166:167], v[166:167], 0, v[172:173]
	v_ashrrev_i32_e32 v175, 31, v174
	v_mov_b32_dpp v179, v123 row_ror:8 row_mask:0xf bank_mask:0xf
	v_mov_b32_dpp v180, v176 row_ror:8 row_mask:0xf bank_mask:0xf
	v_mov_b32_dpp v181, v177 row_ror:8 row_mask:0xf bank_mask:0xf
	v_mov_b32_dpp v182, v178 row_ror:8 row_mask:0xf bank_mask:0xf
	s_waitcnt vmcnt(0)
	v_pk_add_f32 v[126:127], v[118:119], v[126:127]
	v_pk_add_f32 v[124:125], v[116:117], v[124:125]
	v_pk_add_f32 v[112:113], v[112:113], v[158:159]
	v_cvt_pk_bf16_f32 v116, v124, v125
	v_cvt_pk_bf16_f32 v117, v126, v127
	v_mul_f32_e32 v125, v125, v125
	v_mul_f32_e32 v127, v127, v127
	v_pk_add_f32 v[114:115], v[114:115], v[160:161]
	v_mul_f32_e32 v158, v113, v113
	v_fmac_f32_e32 v125, v124, v124
	v_fmac_f32_e32 v127, v126, v126
	v_cvt_pk_bf16_f32 v118, v112, v113
	v_cvt_pk_bf16_f32 v119, v114, v115
	v_mul_f32_e32 v115, v115, v115
	v_fmac_f32_e32 v158, v112, v112
	v_add_f32_e32 v112, v125, v127
	v_fmac_f32_e32 v115, v114, v114
	v_add_f32_e32 v112, v158, v112
	v_add_f32_e32 v112, v115, v112
	v_add_f32_e32 v124, v162, v112
	ds_bpermute_b32 v125, v122, v124
	v_mov_b32_dpp v183, v116 row_ror:8 row_mask:0xf bank_mask:0xf
	v_mov_b32_dpp v184, v117 row_ror:8 row_mask:0xf bank_mask:0xf
	v_mov_b32_dpp v185, v118 row_ror:8 row_mask:0xf bank_mask:0xf
	v_mov_b32_dpp v186, v119 row_ror:8 row_mask:0xf bank_mask:0xf
	v_cndmask_b32_e64 v113, v184, v176, s[6:7]
	v_cndmask_b32_e64 v115, v186, v178, s[6:7]
	v_cndmask_b32_e64 v112, v183, v123, s[6:7]
	v_cndmask_b32_e64 v114, v185, v177, s[6:7]
	global_store_dwordx4 v[166:167], v[112:115], off
	v_cndmask_b32_e64 v117, v117, v180, s[6:7]
	v_cndmask_b32_e64 v119, v119, v182, s[6:7]
	s_waitcnt lgkmcnt(0)
	v_add_f32_e32 v112, v124, v125
	v_lshlrev_b32_e32 v114, 2, v187
	ds_bpermute_b32 v113, v114, v112
	v_lshlrev_b64 v[124:125], 12, v[174:175]
	v_lshl_add_u64 v[124:125], s[10:11], 0, v[124:125]
	v_cndmask_b32_e64 v116, v116, v179, s[6:7]
	v_cndmask_b32_e64 v118, v118, v181, s[6:7]
	v_lshl_add_u64 v[124:125], v[124:125], 0, v[172:173]
	global_store_dwordx4 v[124:125], v[116:119], off
	s_and_saveexec_b64 s[50:51], s[8:9]
	s_cbranch_execz .LBB0_616
	s_waitcnt lgkmcnt(0)
	v_add_f32_e32 v115, v112, v113
	v_lshl_add_u64 v[112:113], v[146:147], 2, s[12:13]
	global_atomic_add_f32 v[112:113], v115, off

; #define PG8_STAGE(bufoff, gbase, voff) do { _Pragma("unroll") for (int _i = 0; _i < 2; ++_i) \
;         __builtin_amdgcn_global_load_lds((const unsigned*)((const char*)(gbase) + (voff)[_i]), (LAS unsigned*)(lds + (bufoff) + ldsw + _i * 8192), 16, 0, 0); } while (0)
; #define PG8_LDA(dst, b, h) do { _Pragma("unroll") for (int m = 0; m < 4; ++m) _Pragma("unroll") for (int k = 0; k < 2; ++k) dst[m][k] = *(const LAS bf16x8*)(lds + PG8_SA(b, h) + aoff + m * 2048 + k * 1024); } while (0)
; #define PG8_LDB(dst, b, h) do { _Pragma("unroll") for (int n = 0; n < 2; ++n) _Pragma("unroll") for (int k = 0; k < 2; ++k) dst[n][k] = *(const LAS bf16x8*)(lds + PG8_SB(b, h) + boff + n * 2048 + k * 1024); } while (0)
; #define PG8_WAIT_V(n) asm volatile("s_waitcnt vmcnt(" #n ")" ::: "memory")
; #define PG8_WAIT_L(n) asm volatile("s_waitcnt lgkmcnt(" #n ")" ::: "memory")
; template <class Epi>
; __device__ __forceinline__ void gemm_phase(LAS unsigned char* lds, const Gemm g, const StaticOrder& S, const Epi& E) {
;     ...
;         const bool has_next = S.next(ui + 1, nxt);
;         const char* nA = has_next ? (const char*)g.A + (size_t)nxt.pm * tstep : cA; const char* nB = has_next ? (const char*)g.Bt + (size_t)nxt.pn * tstep : cB;
;         for (int t = 0; t < nt; t += 2) {
;             const bool last = (t == nt - 2);
;             const char* a1 = cA + (size_t)(t + 1) * kstep;
;             const char* a2 = last ? nA : cA + (size_t)(t + 2) * kstep; const char* b2 = last ? nB : cB + (size_t)(t + 2) * kstep;
;             const char* a3 = a2 + kstep; const char* b3 = b2 + kstep;
;             PG8_LDB(B0, 0, 0); PG8_SCHED; PG8_LDA(At, 0, 0); PG8_STAGE(PG8_SA(1, 1), a1 + hstep, voffA);
;             PG8_WAIT_L(8); PG8_BAR; PG8_WAIT_L(0); PG8_MMA(0, 0, At, B0); PG8_BAR; PG8_SCHED;
;             PG8_LDB(B1, 0, 1); PG8_STAGE(PG8_SB(0, 0), b2, voffB0);
;             PG8_BAR; PG8_WAIT_L(0); PG8_MMA(0, 1, At, B1); PG8_BAR;
;             PG8_LDA(At, 0, 1); PG8_STAGE(PG8_SA(0, 0), a2, voffA);
;             PG8_BAR; PG8_WAIT_L(0); PG8_MMA(1, 0, At, B0); PG8_BAR; PG8_SCHED;
;             PG8_STAGE(PG8_SB(0, 1), b2, voffB1);
;             PG8_WAIT_V(6); PG8_BAR; PG8_MMA(1, 1, At, B1); PG8_BAR;
;             PG8_LDB(B0, 1, 0); PG8_SCHED; PG8_LDA(At, 1, 0); PG8_STAGE(PG8_SA(0, 1), a2 + hstep, voffA);
;             PG8_WAIT_L(8); PG8_BAR; PG8_WAIT_L(0); PG8_MMA(0, 0, At, B0); PG8_BAR; PG8_SCHED;
.LBB0_645:
	s_add_u32 s33, s50, s58
	s_addc_u32 s59, s51, 0
	s_add_u32 s56, s33, 0x100
	s_addc_u32 s57, s59, 0
	v_cndmask_b32_e64 v153, 0, 1, s[54:55]
	s_and_b64 s[54:55], s[52:53], exec
	s_cselect_b32 s57, s37, s57
	s_cselect_b32 s56, s45, s56
	s_add_u32 s54, s48, s58
	s_addc_u32 s55, s49, 0
	s_add_u32 s54, s54, 0x100
	s_addc_u32 s55, s55, 0
	s_and_b64 s[52:53], s[52:53], exec
	ds_read_b128 v[142:145], v150
	ds_read_b128 v[154:157], v150 offset:1024
	ds_read_b128 v[158:161], v150 offset:2048
	ds_read_b128 v[162:165], v150 offset:3072
	s_cselect_b32 s54, s80, s54
	s_cselect_b32 s55, s19, s55
	s_add_u32 s58, s33, 0x10080
	s_addc_u32 s59, s59, 0
	s_add_i32 s89, s78, s65
	s_add_i32 s85, s79, s65
	s_add_i32 m0, s47, 0xc000
	s_add_i32 s33, s47, 0xe000
	s_add_i32 s88, s89, 0x2000
	s_add_i32 s84, s85, 0x2000
	s_add_i32 s83, 0, 0x18000
	s_add_u32 s52, s56, 0x10000
	s_addc_u32 s53, s57, 0
	s_add_i32 s81, 0, 0x1c000
	s_add_i32 s82, s83, s65
	s_add_i32 s87, s81, s65
	s_add_i32 s90, s82, 0x2000
	s_add_i32 s86, s87, 0x2000
	v_cmp_ne_u32_e32 vcc, 1, v153
	v_lshl_add_u64 v[198:199], s[58:59], 0, v[128:129]
	ds_read_b128 v[166:169], v151
	ds_read_b128 v[170:173], v151 offset:1024
	ds_read_b128 v[174:177], v151 offset:2048
	ds_read_b128 v[178:181], v151 offset:3072
	ds_read_b128 v[182:185], v151 offset:4096
	ds_read_b128 v[186:189], v151 offset:5120
	ds_read_b128 v[190:193], v151 offset:6144
	ds_read_b128 v[194:197], v151 offset:7168
	global_load_lds_dwordx4 v[198:199], off
	v_lshl_add_u64 v[198:199], s[58:59], 0, v[134:135]
	s_mov_b32 m0, s33
	s_nop 0
	global_load_lds_dwordx4 v[198:199], off
	s_waitcnt lgkmcnt(8)
	s_barrier
	s_waitcnt lgkmcnt(0)
	s_waitcnt lgkmcnt(0)
	v_mfma_f32_16x16x32_bf16 v[124:127], v[142:145], v[166:169], v[124:127]
	v_mfma_f32_16x16x32_bf16 v[120:123], v[158:161], v[166:169], v[120:123]
	v_mfma_f32_16x16x32_bf16 v[108:111], v[142:145], v[174:177], v[108:111]
	v_mfma_f32_16x16x32_bf16 v[104:107], v[158:161], v[174:177], v[104:107]
	v_mfma_f32_16x16x32_bf16 v[92:95], v[142:145], v[182:185], v[92:95]
	v_mfma_f32_16x16x32_bf16 v[88:91], v[158:161], v[182:185], v[88:91]
	v_mfma_f32_16x16x32_bf16 v[76:79], v[142:145], v[190:193], v[76:79]
	v_mfma_f32_16x16x32_bf16 v[72:75], v[158:161], v[190:193], v[72:75]
	v_mfma_f32_16x16x32_bf16 v[124:127], v[154:157], v[170:173], v[124:127]
	v_mfma_f32_16x16x32_bf16 v[120:123], v[162:165], v[170:173], v[120:123]
	v_mfma_f32_16x16x32_bf16 v[108:111], v[154:157], v[178:181], v[108:111]
	v_mfma_f32_16x16x32_bf16 v[104:107], v[162:165], v[178:181], v[104:107]
	v_mfma_f32_16x16x32_bf16 v[92:95], v[154:157], v[186:189], v[92:95]
	v_mfma_f32_16x16x32_bf16 v[88:91], v[162:165], v[186:189], v[88:91]
	v_mfma_f32_16x16x32_bf16 v[76:79], v[154:157], v[194:197], v[76:79]
	v_mfma_f32_16x16x32_bf16 v[72:75], v[162:165], v[194:197], v[72:75]
	s_barrier
	s_mov_b32 m0, s89
	v_lshl_add_u64 v[216:217], s[54:55], 0, v[130:131]
	ds_read_b128 v[198:201], v152
	ds_read_b128 v[204:207], v152 offset:1024
	ds_read_b128 v[208:211], v152 offset:2048
	ds_read_b128 v[212:215], v152 offset:3072
	global_load_lds_dwordx4 v[216:217], off
	v_lshl_add_u64 v[218:219], s[54:55], 0, v[136:137]
	s_mov_b32 m0, s88
	s_nop 0
	global_load_lds_dwordx4 v[218:219], off
	s_barrier
	s_waitcnt lgkmcnt(0)
	s_waitcnt lgkmcnt(0)
	v_mfma_f32_16x16x32_bf16 v[116:119], v[198:201], v[166:169], v[116:119]
	v_mfma_f32_16x16x32_bf16 v[112:115], v[208:211], v[166:169], v[112:115]
	v_mfma_f32_16x16x32_bf16 v[100:103], v[198:201], v[174:177], v[100:103]
	v_mfma_f32_16x16x32_bf16 v[96:99], v[208:211], v[174:177], v[96:99]
	v_mfma_f32_16x16x32_bf16 v[84:87], v[198:201], v[182:185], v[84:87]
	v_mfma_f32_16x16x32_bf16 v[80:83], v[208:211], v[182:185], v[80:83]
	v_mfma_f32_16x16x32_bf16 v[68:71], v[198:201], v[190:193], v[68:71]
	v_mfma_f32_16x16x32_bf16 v[64:67], v[208:211], v[190:193], v[64:67]
	v_mfma_f32_16x16x32_bf16 v[116:119], v[204:207], v[170:173], v[116:119]
	v_mfma_f32_16x16x32_bf16 v[112:115], v[212:215], v[170:173], v[112:115]
	v_mfma_f32_16x16x32_bf16 v[100:103], v[204:207], v[178:181], v[100:103]
	v_mfma_f32_16x16x32_bf16 v[96:99], v[212:215], v[178:181], v[96:99]
	v_mfma_f32_16x16x32_bf16 v[84:87], v[204:207], v[186:189], v[84:87]
	v_mfma_f32_16x16x32_bf16 v[80:83], v[212:215], v[186:189], v[80:83]
	v_mfma_f32_16x16x32_bf16 v[68:71], v[204:207], v[194:197], v[68:71]
	v_mfma_f32_16x16x32_bf16 v[64:67], v[212:215], v[194:197], v[64:67]
	s_mov_b32 m0, s47
	v_lshl_add_u64 v[220:221], s[56:57], 0, v[128:129]
	s_barrier
	ds_read_b128 v[166:169], v151 offset:16384
	ds_read_b128 v[170:173], v151 offset:17408
	ds_read_b128 v[174:177], v151 offset:18432
	ds_read_b128 v[178:181], v151 offset:19456
	ds_read_b128 v[182:185], v151 offset:20480
	ds_read_b128 v[186:189], v151 offset:21504
	ds_read_b128 v[190:193], v151 offset:22528
	ds_read_b128 v[194:197], v151 offset:23552
	global_load_lds_dwordx4 v[220:221], off
	v_lshl_add_u64 v[222:223], s[56:57], 0, v[134:135]
	s_mov_b32 m0, s66
	s_nop 0
	global_load_lds_dwordx4 v[222:223], off
	s_barrier
	s_waitcnt lgkmcnt(0)
	s_waitcnt lgkmcnt(0)
	v_mfma_f32_16x16x32_bf16 v[60:63], v[142:145], v[166:169], v[60:63]
	v_mfma_f32_16x16x32_bf16 v[56:59], v[158:161], v[166:169], v[56:59]
	v_mfma_f32_16x16x32_bf16 v[44:47], v[142:145], v[174:177], v[44:47]
	v_mfma_f32_16x16x32_bf16 v[40:43], v[158:161], v[174:177], v[40:43]
	v_mfma_f32_16x16x32_bf16 v[28:31], v[142:145], v[182:185], v[28:31]
	v_mfma_f32_16x16x32_bf16 v[24:27], v[158:161], v[182:185], v[24:27]
	v_mfma_f32_16x16x32_bf16 v[12:15], v[142:145], v[190:193], v[12:15]
	v_mfma_f32_16x16x32_bf16 v[8:11], v[158:161], v[190:193], v[8:11]
	v_mfma_f32_16x16x32_bf16 v[60:63], v[154:157], v[170:173], v[60:63]
	v_mfma_f32_16x16x32_bf16 v[56:59], v[162:165], v[170:173], v[56:59]
	v_mfma_f32_16x16x32_bf16 v[44:47], v[154:157], v[178:181], v[44:47]
	v_mfma_f32_16x16x32_bf16 v[40:43], v[162:165], v[178:181], v[40:43]
	v_mfma_f32_16x16x32_bf16 v[28:31], v[154:157], v[186:189], v[28:31]
	v_mfma_f32_16x16x32_bf16 v[24:27], v[162:165], v[186:189], v[24:27]
	v_mfma_f32_16x16x32_bf16 v[12:15], v[154:157], v[194:197], v[12:15]
	v_mfma_f32_16x16x32_bf16 v[8:11], v[162:165], v[194:197], v[8:11]
	s_barrier
; #define PG8_STAGE(bufoff, gbase, voff) do { _Pragma("unroll") for (int _i = 0; _i < 2; ++_i) \
;         __builtin_amdgcn_global_load_lds((const unsigned*)((const char*)(gbase) + (voff)[_i]), (LAS unsigned*)(lds + (bufoff) + ldsw + _i * 8192), 16, 0, 0); } while (0)
; #define PG8_LDA(dst, b, h) do { _Pragma("unroll") for (int m = 0; m < 4; ++m) _Pragma("unroll") for (int k = 0; k < 2; ++k) dst[m][k] = *(const LAS bf16x8*)(lds + PG8_SA(b, h) + aoff + m * 2048 + k * 1024); } while (0)
; #define PG8_LDB(dst, b, h) do { _Pragma("unroll") for (int n = 0; n < 2; ++n) _Pragma("unroll") for (int k = 0; k < 2; ++k) dst[n][k] = *(const LAS bf16x8*)(lds + PG8_SB(b, h) + boff + n * 2048 + k * 1024); } while (0)
; #define PG8_MMA(ai, bj, At, Bt) do { __builtin_amdgcn_s_setprio(1); _Pragma("unroll") for (int m = 0; m < 4; ++m) _Pragma("unroll") for (int n = 0; n < 2; ++n) _Pragma("unroll") for (int k = 0; k < 2; ++k) \
;         acc[ai][bj][m][n] = __builtin_amdgcn_mfma_f32_16x16x32_bf16(Bt[n][k], At[m][k], acc[ai][bj][m][n], 0, 0, 0); __builtin_amdgcn_s_setprio(0); } while (0)
; #define PG8_WAIT_V(n) asm volatile("s_waitcnt vmcnt(" #n ")" ::: "memory")
; #define PG8_WAIT_L(n) asm volatile("s_waitcnt lgkmcnt(" #n ")" ::: "memory")
; #define PG8_BAR __builtin_amdgcn_s_barrier()
; #define PG8_SCHED __builtin_amdgcn_sched_barrier(0)
; template <class Epi>
; __device__ __forceinline__ void gemm_phase(LAS unsigned char* lds, const Gemm g, const StaticOrder& S, const Epi& E) {
;     ...
;             PG8_STAGE(PG8_SB(0, 1), b2, voffB1);
;             PG8_WAIT_V(6); PG8_BAR; PG8_MMA(1, 1, At, B1); PG8_BAR;
;             PG8_LDB(B0, 1, 0); PG8_SCHED; PG8_LDA(At, 1, 0); PG8_STAGE(PG8_SA(0, 1), a2 + hstep, voffA);
;             PG8_WAIT_L(8); PG8_BAR; PG8_WAIT_L(0); PG8_MMA(0, 0, At, B0); PG8_BAR; PG8_SCHED;
;             PG8_LDB(B1, 1, 1); PG8_STAGE(PG8_SB(1, 0), b3, voffB0);
;             PG8_BAR; PG8_WAIT_L(0); PG8_MMA(0, 1, At, B1); PG8_BAR;
;             PG8_LDA(At, 1, 1); PG8_STAGE(PG8_SA(1, 0), a3, voffA);
;             PG8_BAR; PG8_WAIT_L(0); PG8_MMA(1, 0, At, B0); PG8_BAR; PG8_SCHED;
	s_mov_b32 m0, s85
	v_lshl_add_u64 v[224:225], s[54:55], 0, v[132:133]
	global_load_lds_dwordx4 v[224:225], off
	v_lshl_add_u64 v[226:227], s[54:55], 0, v[138:139]
	s_mov_b32 m0, s84
	s_nop 0
	global_load_lds_dwordx4 v[226:227], off
	s_waitcnt vmcnt(6)
	s_barrier
	v_mfma_f32_16x16x32_bf16 v[52:55], v[198:201], v[166:169], v[52:55]
	v_mfma_f32_16x16x32_bf16 v[48:51], v[208:211], v[166:169], v[48:51]
	v_mfma_f32_16x16x32_bf16 v[36:39], v[198:201], v[174:177], v[36:39]
	v_mfma_f32_16x16x32_bf16 v[32:35], v[208:211], v[174:177], v[32:35]
	v_mfma_f32_16x16x32_bf16 v[20:23], v[198:201], v[182:185], v[20:23]
	v_mfma_f32_16x16x32_bf16 v[16:19], v[208:211], v[182:185], v[16:19]
	v_mfma_f32_16x16x32_bf16 v[4:7], v[198:201], v[190:193], v[4:7]
	v_mfma_f32_16x16x32_bf16 v[0:3], v[208:211], v[190:193], v[0:3]
	v_mfma_f32_16x16x32_bf16 v[52:55], v[204:207], v[170:173], v[52:55]
	v_mfma_f32_16x16x32_bf16 v[48:51], v[212:215], v[170:173], v[48:51]
	v_mfma_f32_16x16x32_bf16 v[36:39], v[204:207], v[178:181], v[36:39]
	v_mfma_f32_16x16x32_bf16 v[32:35], v[212:215], v[178:181], v[32:35]
	v_mfma_f32_16x16x32_bf16 v[20:23], v[204:207], v[186:189], v[20:23]
	v_mfma_f32_16x16x32_bf16 v[16:19], v[212:215], v[186:189], v[16:19]
	v_mfma_f32_16x16x32_bf16 v[4:7], v[204:207], v[194:197], v[4:7]
	v_mfma_f32_16x16x32_bf16 v[0:3], v[212:215], v[194:197], v[0:3]
	v_add_u32_e32 v153, s83, v147
	s_barrier
	ds_read_b128 v[142:145], v153
	ds_read_b128 v[154:157], v153 offset:1024
	ds_read_b128 v[158:161], v153 offset:2048
	ds_read_b128 v[162:165], v153 offset:3072
	s_mov_b32 m0, s67
	v_lshl_add_u64 v[198:199], s[52:53], 0, v[128:129]
	ds_read_b128 v[166:169], v151 offset:32768
	ds_read_b128 v[170:173], v151 offset:33792
	ds_read_b128 v[174:177], v151 offset:34816
	ds_read_b128 v[178:181], v151 offset:35840
	ds_read_b128 v[182:185], v151 offset:36864
	ds_read_b128 v[186:189], v151 offset:37888
	ds_read_b128 v[190:193], v151 offset:38912
	ds_read_b128 v[194:197], v151 offset:39936
	global_load_lds_dwordx4 v[198:199], off
	v_lshl_add_u64 v[198:199], s[52:53], 0, v[134:135]
	s_mov_b32 m0, s68
	s_nop 0
	global_load_lds_dwordx4 v[198:199], off
	s_waitcnt lgkmcnt(8)
	s_barrier
	s_waitcnt lgkmcnt(0)
	s_waitcnt lgkmcnt(0)
	v_mfma_f32_16x16x32_bf16 v[124:127], v[142:145], v[166:169], v[124:127]
	v_mfma_f32_16x16x32_bf16 v[120:123], v[158:161], v[166:169], v[120:123]
	v_mfma_f32_16x16x32_bf16 v[108:111], v[142:145], v[174:177], v[108:111]
	v_mfma_f32_16x16x32_bf16 v[104:107], v[158:161], v[174:177], v[104:107]
	v_mfma_f32_16x16x32_bf16 v[92:95], v[142:145], v[182:185], v[92:95]
	v_mfma_f32_16x16x32_bf16 v[88:91], v[158:161], v[182:185], v[88:91]
	v_mfma_f32_16x16x32_bf16 v[76:79], v[142:145], v[190:193], v[76:79]
	v_mfma_f32_16x16x32_bf16 v[72:75], v[158:161], v[190:193], v[72:75]
	v_mfma_f32_16x16x32_bf16 v[124:127], v[154:157], v[170:173], v[124:127]
	v_mfma_f32_16x16x32_bf16 v[120:123], v[162:165], v[170:173], v[120:123]
	v_mfma_f32_16x16x32_bf16 v[108:111], v[154:157], v[178:181], v[108:111]
	v_mfma_f32_16x16x32_bf16 v[104:107], v[162:165], v[178:181], v[104:107]
	v_mfma_f32_16x16x32_bf16 v[92:95], v[154:157], v[186:189], v[92:95]
	v_mfma_f32_16x16x32_bf16 v[88:91], v[162:165], v[186:189], v[88:91]
	v_mfma_f32_16x16x32_bf16 v[76:79], v[154:157], v[194:197], v[76:79]
	v_mfma_f32_16x16x32_bf16 v[72:75], v[162:165], v[194:197], v[72:75]
	s_barrier
	s_mov_b32 m0, s82
	v_add_u32_e32 v153, s81, v147
	v_lshl_add_u64 v[216:217], v[216:217], 0, s[16:17]
	ds_read_b128 v[198:201], v153
	ds_read_b128 v[204:207], v153 offset:1024
	ds_read_b128 v[208:211], v153 offset:2048
	ds_read_b128 v[212:215], v153 offset:3072
	global_load_lds_dwordx4 v[216:217], off
	v_lshl_add_u64 v[216:217], v[218:219], 0, s[16:17]
	s_mov_b32 m0, s90
	s_nop 0
	global_load_lds_dwordx4 v[216:217], off
	s_barrier
	s_waitcnt lgkmcnt(0)
	s_waitcnt lgkmcnt(0)
	v_mfma_f32_16x16x32_bf16 v[116:119], v[198:201], v[166:169], v[116:119]
	v_mfma_f32_16x16x32_bf16 v[112:115], v[208:211], v[166:169], v[112:115]
	v_mfma_f32_16x16x32_bf16 v[100:103], v[198:201], v[174:177], v[100:103]
	v_mfma_f32_16x16x32_bf16 v[96:99], v[208:211], v[174:177], v[96:99]
	v_mfma_f32_16x16x32_bf16 v[84:87], v[198:201], v[182:185], v[84:87]
	v_mfma_f32_16x16x32_bf16 v[80:83], v[208:211], v[182:185], v[80:83]
	v_mfma_f32_16x16x32_bf16 v[68:71], v[198:201], v[190:193], v[68:71]
	v_mfma_f32_16x16x32_bf16 v[64:67], v[208:211], v[190:193], v[64:67]
	v_mfma_f32_16x16x32_bf16 v[116:119], v[204:207], v[170:173], v[116:119]
	v_mfma_f32_16x16x32_bf16 v[112:115], v[212:215], v[170:173], v[112:115]
	v_mfma_f32_16x16x32_bf16 v[100:103], v[204:207], v[178:181], v[100:103]
	v_mfma_f32_16x16x32_bf16 v[96:99], v[212:215], v[178:181], v[96:99]
	v_mfma_f32_16x16x32_bf16 v[84:87], v[204:207], v[186:189], v[84:87]
	v_mfma_f32_16x16x32_bf16 v[80:83], v[212:215], v[186:189], v[80:83]
	v_mfma_f32_16x16x32_bf16 v[68:71], v[204:207], v[194:197], v[68:71]
	v_mfma_f32_16x16x32_bf16 v[64:67], v[212:215], v[194:197], v[64:67]
	s_mov_b32 m0, s70
	v_lshl_add_u64 v[216:217], v[220:221], 0, s[16:17]
	s_barrier
	ds_read_b128 v[166:169], v151 offset:49152
	ds_read_b128 v[170:173], v151 offset:50176
	ds_read_b128 v[174:177], v151 offset:51200
	ds_read_b128 v[178:181], v151 offset:52224
	ds_read_b128 v[182:185], v151 offset:53248
	ds_read_b128 v[186:189], v151 offset:54272
	ds_read_b128 v[190:193], v151 offset:55296
	ds_read_b128 v[194:197], v151 offset:56320
	global_load_lds_dwordx4 v[216:217], off
	v_lshl_add_u64 v[216:217], v[222:223], 0, s[16:17]
	s_mov_b32 m0, s71
	s_nop 0
	global_load_lds_dwordx4 v[216:217], off
	s_barrier
; __device__ __forceinline__ unsigned cvt_pk_bf16(float lo, float hi) { unsigned r; asm volatile("v_cvt_pk_bf16_f32 %0, %1, %2" : "=v"(r) : "v"(lo), "v"(hi)); return r; }
; #define PG8_STAGE(bufoff, gbase, voff) do { _Pragma("unroll") for (int _i = 0; _i < 2; ++_i) \
;         __builtin_amdgcn_global_load_lds((const unsigned*)((const char*)(gbase) + (voff)[_i]), (LAS unsigned*)(lds + (bufoff) + ldsw + _i * 8192), 16, 0, 0); } while (0)
; #define PG8_WAIT_V(n) asm volatile("s_waitcnt vmcnt(" #n ")" ::: "memory")
; #define PG8_WAIT_L(n) asm volatile("s_waitcnt lgkmcnt(" #n ")" ::: "memory")
; #define PG8_BAR __builtin_amdgcn_s_barrier()
;     __device__ __forceinline__ void operator()(const f32x4 (&acc)[2][2][4][2], const Unit& u, int wr, int wc, int fr, int fq) const {
;         const int row0 = u.pm * BM + wr * 64 + fr; const int col0 = u.pn * BM + wc * 64 + 16 * fq;
; #pragma unroll
;         for (int ai = 0; ai < 2; ++ai)
; #pragma unroll
;             for (int m = 0; m < 4; ++m) { const int row = row0 + ai * HALF + m * 16;
;                 const float rs = ssin ? __builtin_amdgcn_rsqf(ssin[row] * (1.f / D) + EPS) : 1.0f; float sq = 0.f; u32x4 w[2];
; #pragma unroll
;                 for (int bj = 0; bj < 2; ++bj) { f32x4 v0 = acc[ai][bj][m][0] * rs, v1 = acc[ai][bj][m][1] * rs;
;                     if (ACT == 1) {
; #pragma unroll
;                         for (int j = 0; j < 4; ++j) { const float a = fmaxf(v0[j], 0.f), b = fmaxf(v1[j], 0.f); v0[j] = a * a; v1[j] = b * b; } }
;                     sq += (v0[0] * v0[0] + v0[1] * v0[1]) + (v0[2] * v0[2] + v0[3] * v0[3]) + (v1[0] * v1[0] + v1[1] * v1[1]) + (v1[2] * v1[2] + v1[3] * v1[3]);
;                     w[bj].x = cvt_pk_bf16(v0[0], v0[1]); w[bj].y = cvt_pk_bf16(v0[2], v0[3]); w[bj].z = cvt_pk_bf16(v1[0], v1[1]); w[bj].w = cvt_pk_bf16(v1[2], v1[3]); }
;                 store_pair_lines(O, ldc, row, fr, col0, w[0], w[1]);
;                 if (ssout) { sq += __shfl_xor(sq, 16); sq += __shfl_xor(sq, 32); if (fq == 0) unsafeAtomicAdd(ssout + row, sq); } }
; template <class Epi>
; __device__ __forceinline__ void gemm_phase(LAS unsigned char* lds, const Gemm g, const StaticOrder& S, const Epi& E) {
;     ...
;             PG8_BAR; PG8_WAIT_L(0); PG8_MMA(1, 0, At, B0); PG8_BAR; PG8_SCHED;
;             PG8_STAGE(PG8_SB(1, 1), b3, voffB1);
;             PG8_WAIT_V(6); PG8_BAR; PG8_MMA(1, 1, At, B1); PG8_BAR;
	s_waitcnt lgkmcnt(0)
	s_waitcnt lgkmcnt(0)
	v_mfma_f32_16x16x32_bf16 v[60:63], v[142:145], v[166:169], v[60:63]
	v_mfma_f32_16x16x32_bf16 v[56:59], v[158:161], v[166:169], v[56:59]
	v_mfma_f32_16x16x32_bf16 v[44:47], v[142:145], v[174:177], v[44:47]
	v_mfma_f32_16x16x32_bf16 v[40:43], v[158:161], v[174:177], v[40:43]
	v_mfma_f32_16x16x32_bf16 v[28:31], v[142:145], v[182:185], v[28:31]
	v_mfma_f32_16x16x32_bf16 v[24:27], v[158:161], v[182:185], v[24:27]
	v_mfma_f32_16x16x32_bf16 v[12:15], v[142:145], v[190:193], v[12:15]
	v_mfma_f32_16x16x32_bf16 v[8:11], v[158:161], v[190:193], v[8:11]
	v_mfma_f32_16x16x32_bf16 v[60:63], v[154:157], v[170:173], v[60:63]
	v_mfma_f32_16x16x32_bf16 v[56:59], v[162:165], v[170:173], v[56:59]
	v_mfma_f32_16x16x32_bf16 v[44:47], v[154:157], v[178:181], v[44:47]
	v_mfma_f32_16x16x32_bf16 v[40:43], v[162:165], v[178:181], v[40:43]
	v_mfma_f32_16x16x32_bf16 v[28:31], v[154:157], v[186:189], v[28:31]
	v_mfma_f32_16x16x32_bf16 v[24:27], v[162:165], v[186:189], v[24:27]
	v_mfma_f32_16x16x32_bf16 v[12:15], v[154:157], v[194:197], v[12:15]
	v_mfma_f32_16x16x32_bf16 v[8:11], v[162:165], v[194:197], v[8:11]
	s_barrier
	s_mov_b32 m0, s87
	v_lshl_add_u64 v[142:143], v[224:225], 0, s[16:17]
	global_load_lds_dwordx4 v[142:143], off
	v_lshl_add_u64 v[142:143], v[226:227], 0, s[16:17]
	s_mov_b32 m0, s86
	s_nop 0
	global_load_lds_dwordx4 v[142:143], off
	s_waitcnt vmcnt(6)
	s_barrier
	v_mfma_f32_16x16x32_bf16 v[52:55], v[198:201], v[166:169], v[52:55]
	v_mfma_f32_16x16x32_bf16 v[48:51], v[208:211], v[166:169], v[48:51]
	v_mfma_f32_16x16x32_bf16 v[36:39], v[198:201], v[174:177], v[36:39]
	v_mfma_f32_16x16x32_bf16 v[32:35], v[208:211], v[174:177], v[32:35]
	v_mfma_f32_16x16x32_bf16 v[20:23], v[198:201], v[182:185], v[20:23]
	v_mfma_f32_16x16x32_bf16 v[16:19], v[208:211], v[182:185], v[16:19]
	v_mfma_f32_16x16x32_bf16 v[4:7], v[198:201], v[190:193], v[4:7]
	v_mfma_f32_16x16x32_bf16 v[0:3], v[208:211], v[190:193], v[0:3]
	v_mfma_f32_16x16x32_bf16 v[52:55], v[204:207], v[170:173], v[52:55]
	v_mfma_f32_16x16x32_bf16 v[48:51], v[212:215], v[170:173], v[48:51]
	v_mfma_f32_16x16x32_bf16 v[36:39], v[204:207], v[178:181], v[36:39]
	v_mfma_f32_16x16x32_bf16 v[32:35], v[212:215], v[178:181], v[32:35]
	v_mfma_f32_16x16x32_bf16 v[20:23], v[204:207], v[186:189], v[20:23]
	v_mfma_f32_16x16x32_bf16 v[16:19], v[212:215], v[186:189], v[16:19]
	v_mfma_f32_16x16x32_bf16 v[4:7], v[204:207], v[194:197], v[4:7]
	v_mfma_f32_16x16x32_bf16 v[0:3], v[212:215], v[194:197], v[0:3]
	s_movk_i32 s58, 0x100
	s_mov_b64 s[54:55], 0
	s_mov_b64 s[52:53], -1
	s_barrier
	s_cbranch_vccz .LBB0_645
	v_cvt_pk_bf16_f32 v145, v124, v125
	v_cvt_pk_bf16_f32 v153, v126, v127
	v_cvt_pk_bf16_f32 v156, v120, v121
	v_cvt_pk_bf16_f32 v157, v122, v123
	v_cvt_pk_bf16_f32 v158, v116, v117
	v_cvt_pk_bf16_f32 v159, v118, v119
	v_cvt_pk_bf16_f32 v160, v112, v113
	v_cvt_pk_bf16_f32 v161, v114, v115
	v_mul_f32_e32 v123, v123, v123
	v_mul_f32_e32 v115, v115, v115
	v_fmac_f32_e32 v123, v122, v122
	v_mul_f32_e32 v122, v125, v125
	v_fmac_f32_e32 v115, v114, v114
	v_mul_f32_e32 v114, v117, v117
	v_fmac_f32_e32 v122, v124, v124
	v_mul_f32_e32 v124, v127, v127
	v_fmac_f32_e32 v114, v116, v116
	v_mul_f32_e32 v116, v119, v119
	v_fmac_f32_e32 v124, v126, v126
	v_mul_f32_e32 v121, v121, v121
	v_fmac_f32_e32 v116, v118, v118
	v_mul_f32_e32 v113, v113, v113
	v_add_f32_e32 v122, v122, v124
	v_fmac_f32_e32 v121, v120, v120
	v_add_f32_e32 v114, v114, v116
	v_fmac_f32_e32 v113, v112, v112
	v_add_f32_e32 v120, v122, v121
	v_add_f32_e32 v112, v114, v113
	s_lshl_b32 s19, s46, 8
	v_mov_b32_e32 v162, 0
	v_add_f32_e32 v120, v123, v120
	v_add_f32_e32 v112, v115, v112
	v_and_b32_e32 v113, 64, v203
	s_add_i32 s19, s19, s72
	v_mov_b32_dpp v162, v145 row_ror:8 row_mask:0xf bank_mask:0xf
	v_mov_b32_e32 v163, 0
	v_mov_b32_e32 v154, 0
	v_add_f32_e32 v115, v120, v112
	v_xor_b32_e32 v112, 16, v203
	v_add_u32_e32 v118, 64, v113
	v_mov_b32_dpp v163, v153 row_ror:8 row_mask:0xf bank_mask:0xf
	v_mov_b32_e32 v164, 0
	v_mov_b32_e32 v165, 0
	v_mov_b32_dpp v154, v158 row_ror:8 row_mask:0xf bank_mask:0xf
	v_mov_b32_e32 v155, 0
	v_cndmask_b32_e64 v158, v158, v162, s[6:7]
	v_or_b32_e32 v162, s19, v148
	v_cmp_lt_i32_e32 vcc, v112, v118
	v_lshl_or_b32 v142, s44, 8, v149
	v_mov_b32_dpp v164, v156 row_ror:8 row_mask:0xf bank_mask:0xf
	v_mov_b32_dpp v165, v157 row_ror:8 row_mask:0xf bank_mask:0xf
	v_mov_b32_dpp v155, v159 row_ror:8 row_mask:0xf bank_mask:0xf
	v_mov_b32_e32 v166, 0
	v_mov_b32_e32 v167, 0
	v_cndmask_b32_e64 v159, v159, v163, s[6:7]
	v_ashrrev_i32_e32 v163, 31, v162
	v_cndmask_b32_e32 v112, v203, v112, vcc
	v_ashrrev_i32_e32 v143, 31, v142
	v_mov_b32_dpp v166, v160 row_ror:8 row_mask:0xf bank_mask:0xf
	v_mov_b32_dpp v167, v161 row_ror:8 row_mask:0xf bank_mask:0xf
	v_cndmask_b32_e64 v160, v160, v164, s[6:7]
	v_cndmask_b32_e64 v161, v161, v165, s[6:7]
	v_lshlrev_b64 v[164:165], 12, v[162:163]
	v_lshlrev_b32_e32 v114, 2, v112
	v_cndmask_b32_e64 v156, v166, v156, s[6:7]
	v_cndmask_b32_e64 v157, v167, v157, s[6:7]
	v_lshl_add_u64 v[164:165], s[10:11], 0, v[164:165]
	v_lshlrev_b64 v[166:167], 1, v[142:143]
	ds_bpermute_b32 v119, v114, v115
	v_cndmask_b32_e64 v154, v154, v145, s[6:7]
	v_cndmask_b32_e64 v155, v155, v153, s[6:7]
	v_lshl_add_u64 v[112:113], v[164:165], 0, v[166:167]
	global_store_dwordx4 v[112:113], v[154:157], off
	v_xor_b32_e32 v113, 32, v203
	v_cmp_lt_i32_e32 vcc, v113, v118
	s_waitcnt lgkmcnt(0)
	v_add_f32_e32 v112, v115, v119
	v_or_b32_e32 v116, 8, v162
	v_cndmask_b32_e32 v113, v203, v113, vcc
	v_lshlrev_b32_e32 v115, 2, v113
	ds_bpermute_b32 v113, v115, v112
	v_ashrrev_i32_e32 v117, 31, v116
	v_lshlrev_b64 v[116:117], 12, v[116:117]
	v_lshl_add_u64 v[116:117], s[10:11], 0, v[116:117]
	v_or_b32_e32 v144, s19, v146
	v_lshl_add_u64 v[116:117], v[116:117], 0, v[166:167]
	global_store_dwordx4 v[116:117], v[158:161], off
	s_and_saveexec_b64 s[44:45], s[8:9]
	s_cbranch_execz .LBB0_648
	v_ashrrev_i32_e32 v145, 31, v144
	s_waitcnt lgkmcnt(0)
	v_add_f32_e32 v116, v112, v113
	v_lshl_add_u64 v[112:113], v[144:145], 2, s[12:13]
	global_atomic_add_f32 v[112:113], v116, off

; #define PG8_STAGE(bufoff, gbase, voff) do { _Pragma("unroll") for (int _i = 0; _i < 2; ++_i) \
;         __builtin_amdgcn_global_load_lds((const unsigned*)((const char*)(gbase) + (voff)[_i]), (LAS unsigned*)(lds + (bufoff) + ldsw + _i * 8192), 16, 0, 0); } while (0)
; #define PG8_LDA(dst, b, h) do { _Pragma("unroll") for (int m = 0; m < 4; ++m) _Pragma("unroll") for (int k = 0; k < 2; ++k) dst[m][k] = *(const LAS bf16x8*)(lds + PG8_SA(b, h) + aoff + m * 2048 + k * 1024); } while (0)
; #define PG8_LDB(dst, b, h) do { _Pragma("unroll") for (int n = 0; n < 2; ++n) _Pragma("unroll") for (int k = 0; k < 2; ++k) dst[n][k] = *(const LAS bf16x8*)(lds + PG8_SB(b, h) + boff + n * 2048 + k * 1024); } while (0)
; #define PG8_MMA(ai, bj, At, Bt) do { __builtin_amdgcn_s_setprio(1); _Pragma("unroll") for (int m = 0; m < 4; ++m) _Pragma("unroll") for (int n = 0; n < 2; ++n) _Pragma("unroll") for (int k = 0; k < 2; ++k) \
;         acc[ai][bj][m][n] = __builtin_amdgcn_mfma_f32_16x16x32_bf16(Bt[n][k], At[m][k], acc[ai][bj][m][n], 0, 0, 0); __builtin_amdgcn_s_setprio(0); } while (0)
; #define PG8_WAIT_L(n) asm volatile("s_waitcnt lgkmcnt(" #n ")" ::: "memory")
; #define PG8_BAR __builtin_amdgcn_s_barrier()
; template <class Epi>
; __device__ __forceinline__ void gemm_phase(LAS unsigned char* lds, const Gemm g, const StaticOrder& S, const Epi& E) {
;     ...
;         const char* nA = has_next ? (const char*)g.A + (size_t)nxt.pm * tstep : cA; const char* nB = has_next ? (const char*)g.Bt + (size_t)nxt.pn * tstep : cB;
;         for (int t = 0; t < nt; t += 2) {
;             const bool last = (t == nt - 2);
;             const char* a1 = cA + (size_t)(t + 1) * kstep;
;             const char* a2 = last ? nA : cA + (size_t)(t + 2) * kstep; const char* b2 = last ? nB : cB + (size_t)(t + 2) * kstep;
;             const char* a3 = a2 + kstep; const char* b3 = b2 + kstep;
;             PG8_LDB(B0, 0, 0); PG8_SCHED; PG8_LDA(At, 0, 0); PG8_STAGE(PG8_SA(1, 1), a1 + hstep, voffA);
;             PG8_WAIT_L(8); PG8_BAR; PG8_WAIT_L(0); PG8_MMA(0, 0, At, B0); PG8_BAR; PG8_SCHED;
;             PG8_LDB(B1, 0, 1); PG8_STAGE(PG8_SB(0, 0), b2, voffB0);
;             PG8_BAR; PG8_WAIT_L(0); PG8_MMA(0, 1, At, B1); PG8_BAR;
;             PG8_LDA(At, 0, 1); PG8_STAGE(PG8_SA(0, 0), a2, voffA);
;             PG8_BAR; PG8_WAIT_L(0); PG8_MMA(1, 0, At, B0); PG8_BAR; PG8_SCHED;
.LBB0_733:
	ds_read_b128 v[160:163], v157
	ds_read_b128 v[164:167], v157 offset:1024
	ds_read_b128 v[168:171], v157 offset:2048
	ds_read_b128 v[172:175], v157 offset:3072
	s_add_u32 s33, s46, 0xfff80080
	s_addc_u32 s48, s47, -1
	s_cmp_eq_u32 s74, 28
	s_cselect_b32 s49, s37, s48
	s_cselect_b32 s48, s70, s33
	s_cselect_b32 s51, s19, s73
	s_cselect_b32 s50, s71, s72
	v_lshl_add_u64 v[200:201], s[46:47], 0, v[140:141]
	s_add_i32 m0, s45, 0xc000
	ds_read_b128 v[176:179], v158
	ds_read_b128 v[180:183], v158 offset:1024
	ds_read_b128 v[184:187], v158 offset:2048
	ds_read_b128 v[188:191], v158 offset:3072
	ds_read_b128 v[192:195], v158 offset:4096
	ds_read_b128 v[196:199], v158 offset:5120
	ds_read_b128 v[204:207], v158 offset:6144
	ds_read_b128 v[208:211], v158 offset:7168
	global_load_lds_dwordx4 v[200:201], off
	v_lshl_add_u64 v[200:201], s[46:47], 0, v[142:143]
	s_add_i32 m0, s45, 0xe000
	s_nop 0
	global_load_lds_dwordx4 v[200:201], off
	s_waitcnt lgkmcnt(8)
	s_barrier
	s_waitcnt lgkmcnt(0)
	s_waitcnt lgkmcnt(0)
	v_mfma_f32_16x16x32_bf16 v[124:127], v[160:163], v[176:179], v[124:127]
	v_mfma_f32_16x16x32_bf16 v[120:123], v[168:171], v[176:179], v[120:123]
	v_mfma_f32_16x16x32_bf16 v[108:111], v[160:163], v[184:187], v[108:111]
	v_mfma_f32_16x16x32_bf16 v[104:107], v[168:171], v[184:187], v[104:107]
	v_mfma_f32_16x16x32_bf16 v[92:95], v[160:163], v[192:195], v[92:95]
	v_mfma_f32_16x16x32_bf16 v[88:91], v[168:171], v[192:195], v[88:91]
	v_mfma_f32_16x16x32_bf16 v[76:79], v[160:163], v[204:207], v[76:79]
	v_mfma_f32_16x16x32_bf16 v[72:75], v[168:171], v[204:207], v[72:75]
	v_mfma_f32_16x16x32_bf16 v[124:127], v[164:167], v[180:183], v[124:127]
	v_mfma_f32_16x16x32_bf16 v[120:123], v[172:175], v[180:183], v[120:123]
	v_mfma_f32_16x16x32_bf16 v[108:111], v[164:167], v[188:191], v[108:111]
	v_mfma_f32_16x16x32_bf16 v[104:107], v[172:175], v[188:191], v[104:107]
	v_mfma_f32_16x16x32_bf16 v[92:95], v[164:167], v[196:199], v[92:95]
	v_mfma_f32_16x16x32_bf16 v[88:91], v[172:175], v[196:199], v[88:91]
	v_mfma_f32_16x16x32_bf16 v[76:79], v[164:167], v[208:211], v[76:79]
	v_mfma_f32_16x16x32_bf16 v[72:75], v[172:175], v[208:211], v[72:75]
	s_barrier
	s_add_i32 s33, s66, s56
	v_lshl_add_u64 v[200:201], s[50:51], 0, v[130:131]
	s_mov_b32 m0, s33
	ds_read_b128 v[212:215], v159
	ds_read_b128 v[216:219], v159 offset:1024
	ds_read_b128 v[220:223], v159 offset:2048
	ds_read_b128 v[224:227], v159 offset:3072
	global_load_lds_dwordx4 v[200:201], off
	v_lshl_add_u64 v[228:229], s[50:51], 0, v[136:137]
	s_add_i32 m0, s33, 0x2000
	s_nop 0
	global_load_lds_dwordx4 v[228:229], off
	s_barrier
	s_waitcnt lgkmcnt(0)
	s_waitcnt lgkmcnt(0)
	v_mfma_f32_16x16x32_bf16 v[116:119], v[212:215], v[176:179], v[116:119]
	v_mfma_f32_16x16x32_bf16 v[112:115], v[220:223], v[176:179], v[112:115]
	v_mfma_f32_16x16x32_bf16 v[100:103], v[212:215], v[184:187], v[100:103]
	v_mfma_f32_16x16x32_bf16 v[96:99], v[220:223], v[184:187], v[96:99]
	v_mfma_f32_16x16x32_bf16 v[84:87], v[212:215], v[192:195], v[84:87]
	v_mfma_f32_16x16x32_bf16 v[80:83], v[220:223], v[192:195], v[80:83]
	v_mfma_f32_16x16x32_bf16 v[68:71], v[212:215], v[204:207], v[68:71]
	v_mfma_f32_16x16x32_bf16 v[64:67], v[220:223], v[204:207], v[64:67]
	v_mfma_f32_16x16x32_bf16 v[116:119], v[216:219], v[180:183], v[116:119]
	v_mfma_f32_16x16x32_bf16 v[112:115], v[224:227], v[180:183], v[112:115]
	v_mfma_f32_16x16x32_bf16 v[100:103], v[216:219], v[188:191], v[100:103]
	v_mfma_f32_16x16x32_bf16 v[96:99], v[224:227], v[188:191], v[96:99]
	v_mfma_f32_16x16x32_bf16 v[84:87], v[216:219], v[196:199], v[84:87]
	v_mfma_f32_16x16x32_bf16 v[80:83], v[224:227], v[196:199], v[80:83]
	v_mfma_f32_16x16x32_bf16 v[68:71], v[216:219], v[208:211], v[68:71]
	v_mfma_f32_16x16x32_bf16 v[64:67], v[224:227], v[208:211], v[64:67]
	s_mov_b32 m0, s45
	v_lshl_add_u64 v[230:231], s[48:49], 0, v[128:129]
	s_barrier
	ds_read_b128 v[176:179], v158 offset:16384
	ds_read_b128 v[180:183], v158 offset:17408
	ds_read_b128 v[184:187], v158 offset:18432
	ds_read_b128 v[188:191], v158 offset:19456
	ds_read_b128 v[192:195], v158 offset:20480
	ds_read_b128 v[196:199], v158 offset:21504
	ds_read_b128 v[204:207], v158 offset:22528
	ds_read_b128 v[208:211], v158 offset:23552
	global_load_lds_dwordx4 v[230:231], off
	v_lshl_add_u64 v[232:233], s[48:49], 0, v[134:135]
	s_mov_b32 m0, s57
	s_nop 0
	global_load_lds_dwordx4 v[232:233], off
	s_barrier
	s_waitcnt lgkmcnt(0)
	s_waitcnt lgkmcnt(0)
	v_mfma_f32_16x16x32_bf16 v[60:63], v[160:163], v[176:179], v[60:63]
	v_mfma_f32_16x16x32_bf16 v[56:59], v[168:171], v[176:179], v[56:59]
	v_mfma_f32_16x16x32_bf16 v[44:47], v[160:163], v[184:187], v[44:47]
	v_mfma_f32_16x16x32_bf16 v[40:43], v[168:171], v[184:187], v[40:43]
	v_mfma_f32_16x16x32_bf16 v[28:31], v[160:163], v[192:195], v[28:31]
	v_mfma_f32_16x16x32_bf16 v[24:27], v[168:171], v[192:195], v[24:27]
	v_mfma_f32_16x16x32_bf16 v[12:15], v[160:163], v[204:207], v[12:15]
	v_mfma_f32_16x16x32_bf16 v[8:11], v[168:171], v[204:207], v[8:11]
	v_mfma_f32_16x16x32_bf16 v[60:63], v[164:167], v[180:183], v[60:63]
	v_mfma_f32_16x16x32_bf16 v[56:59], v[172:175], v[180:183], v[56:59]
	v_mfma_f32_16x16x32_bf16 v[44:47], v[164:167], v[188:191], v[44:47]
	v_mfma_f32_16x16x32_bf16 v[40:43], v[172:175], v[188:191], v[40:43]
	v_mfma_f32_16x16x32_bf16 v[28:31], v[164:167], v[196:199], v[28:31]
	v_mfma_f32_16x16x32_bf16 v[24:27], v[172:175], v[196:199], v[24:27]
	v_mfma_f32_16x16x32_bf16 v[12:15], v[164:167], v[208:211], v[12:15]
	v_mfma_f32_16x16x32_bf16 v[8:11], v[172:175], v[208:211], v[8:11]
	s_barrier
; #define PG8_STAGE(bufoff, gbase, voff) do { _Pragma("unroll") for (int _i = 0; _i < 2; ++_i) \
;         __builtin_amdgcn_global_load_lds((const unsigned*)((const char*)(gbase) + (voff)[_i]), (LAS unsigned*)(lds + (bufoff) + ldsw + _i * 8192), 16, 0, 0); } while (0)
; #define PG8_LDA(dst, b, h) do { _Pragma("unroll") for (int m = 0; m < 4; ++m) _Pragma("unroll") for (int k = 0; k < 2; ++k) dst[m][k] = *(const LAS bf16x8*)(lds + PG8_SA(b, h) + aoff + m * 2048 + k * 1024); } while (0)
; #define PG8_LDB(dst, b, h) do { _Pragma("unroll") for (int n = 0; n < 2; ++n) _Pragma("unroll") for (int k = 0; k < 2; ++k) dst[n][k] = *(const LAS bf16x8*)(lds + PG8_SB(b, h) + boff + n * 2048 + k * 1024); } while (0)
; #define PG8_MMA(ai, bj, At, Bt) do { __builtin_amdgcn_s_setprio(1); _Pragma("unroll") for (int m = 0; m < 4; ++m) _Pragma("unroll") for (int n = 0; n < 2; ++n) _Pragma("unroll") for (int k = 0; k < 2; ++k) \
;         acc[ai][bj][m][n] = __builtin_amdgcn_mfma_f32_16x16x32_bf16(Bt[n][k], At[m][k], acc[ai][bj][m][n], 0, 0, 0); __builtin_amdgcn_s_setprio(0); } while (0)
; #define PG8_WAIT_V(n) asm volatile("s_waitcnt vmcnt(" #n ")" ::: "memory")
; #define PG8_WAIT_L(n) asm volatile("s_waitcnt lgkmcnt(" #n ")" ::: "memory")
; #define PG8_BAR __builtin_amdgcn_s_barrier()
; #define PG8_SCHED __builtin_amdgcn_sched_barrier(0)
; template <class Epi>
; __device__ __forceinline__ void gemm_phase(LAS unsigned char* lds, const Gemm g, const StaticOrder& S, const Epi& E) {
;     ...
;             PG8_STAGE(PG8_SB(0, 1), b2, voffB1);
;             PG8_WAIT_V(6); PG8_BAR; PG8_MMA(1, 1, At, B1); PG8_BAR;
;             PG8_LDB(B0, 1, 0); PG8_SCHED; PG8_LDA(At, 1, 0); PG8_STAGE(PG8_SA(0, 1), a2 + hstep, voffA);
;             PG8_WAIT_L(8); PG8_BAR; PG8_WAIT_L(0); PG8_MMA(0, 0, At, B0); PG8_BAR; PG8_SCHED;
;             PG8_LDB(B1, 1, 1); PG8_STAGE(PG8_SB(1, 0), b3, voffB0);
;             PG8_BAR; PG8_WAIT_L(0); PG8_MMA(0, 1, At, B1); PG8_BAR;
;             PG8_LDA(At, 1, 1); PG8_STAGE(PG8_SA(1, 0), a3, voffA);
;             PG8_BAR; PG8_WAIT_L(0); PG8_MMA(1, 0, At, B0); PG8_BAR; PG8_SCHED;
	s_add_i32 s33, s67, s56
	v_lshl_add_u64 v[234:235], s[50:51], 0, v[132:133]
	s_mov_b32 m0, s33
	v_lshl_add_u64 v[236:237], s[50:51], 0, v[138:139]
	global_load_lds_dwordx4 v[234:235], off
	s_add_i32 m0, s33, 0x2000
	s_nop 0
	global_load_lds_dwordx4 v[236:237], off
	s_waitcnt vmcnt(6)
	s_barrier
	v_mfma_f32_16x16x32_bf16 v[52:55], v[212:215], v[176:179], v[52:55]
	v_mfma_f32_16x16x32_bf16 v[48:51], v[220:223], v[176:179], v[48:51]
	v_mfma_f32_16x16x32_bf16 v[36:39], v[212:215], v[184:187], v[36:39]
	v_mfma_f32_16x16x32_bf16 v[32:35], v[220:223], v[184:187], v[32:35]
	v_mfma_f32_16x16x32_bf16 v[20:23], v[212:215], v[192:195], v[20:23]
	v_mfma_f32_16x16x32_bf16 v[16:19], v[220:223], v[192:195], v[16:19]
	v_mfma_f32_16x16x32_bf16 v[4:7], v[212:215], v[204:207], v[4:7]
	v_mfma_f32_16x16x32_bf16 v[0:3], v[220:223], v[204:207], v[0:3]
	v_mfma_f32_16x16x32_bf16 v[52:55], v[216:219], v[180:183], v[52:55]
	v_mfma_f32_16x16x32_bf16 v[48:51], v[224:227], v[180:183], v[48:51]
	v_mfma_f32_16x16x32_bf16 v[36:39], v[216:219], v[188:191], v[36:39]
	v_mfma_f32_16x16x32_bf16 v[32:35], v[224:227], v[188:191], v[32:35]
	v_mfma_f32_16x16x32_bf16 v[20:23], v[216:219], v[196:199], v[20:23]
	v_mfma_f32_16x16x32_bf16 v[16:19], v[224:227], v[196:199], v[16:19]
	v_mfma_f32_16x16x32_bf16 v[4:7], v[216:219], v[208:211], v[4:7]
	v_mfma_f32_16x16x32_bf16 v[0:3], v[224:227], v[208:211], v[0:3]
	s_add_i32 s33, 0, 0x18000
	v_add_u32_e32 v172, s33, v147
	s_barrier
	ds_read_b128 v[160:163], v172
	ds_read_b128 v[164:167], v172 offset:1024
	ds_read_b128 v[168:171], v172 offset:2048
	ds_read_b128 v[172:175], v172 offset:3072
	s_add_u32 s48, s48, 0x80000
	s_addc_u32 s49, s49, 0
	s_mov_b32 m0, s58
	v_lshl_add_u64 v[212:213], s[48:49], 0, v[128:129]
	ds_read_b128 v[176:179], v158 offset:32768
	ds_read_b128 v[180:183], v158 offset:33792
	ds_read_b128 v[184:187], v158 offset:34816
	ds_read_b128 v[188:191], v158 offset:35840
	ds_read_b128 v[192:195], v158 offset:36864
	ds_read_b128 v[196:199], v158 offset:37888
	ds_read_b128 v[204:207], v158 offset:38912
	ds_read_b128 v[208:211], v158 offset:39936
	global_load_lds_dwordx4 v[212:213], off
	v_lshl_add_u64 v[212:213], s[48:49], 0, v[134:135]
	s_mov_b32 m0, s59
	s_nop 0
	global_load_lds_dwordx4 v[212:213], off
	s_waitcnt lgkmcnt(8)
	s_barrier
	s_waitcnt lgkmcnt(0)
	s_waitcnt lgkmcnt(0)
	v_mfma_f32_16x16x32_bf16 v[124:127], v[160:163], v[176:179], v[124:127]
	v_mfma_f32_16x16x32_bf16 v[120:123], v[168:171], v[176:179], v[120:123]
	v_mfma_f32_16x16x32_bf16 v[108:111], v[160:163], v[184:187], v[108:111]
	v_mfma_f32_16x16x32_bf16 v[104:107], v[168:171], v[184:187], v[104:107]
	v_mfma_f32_16x16x32_bf16 v[92:95], v[160:163], v[192:195], v[92:95]
	v_mfma_f32_16x16x32_bf16 v[88:91], v[168:171], v[192:195], v[88:91]
	v_mfma_f32_16x16x32_bf16 v[76:79], v[160:163], v[204:207], v[76:79]
	v_mfma_f32_16x16x32_bf16 v[72:75], v[168:171], v[204:207], v[72:75]
	v_mfma_f32_16x16x32_bf16 v[124:127], v[164:167], v[180:183], v[124:127]
	v_mfma_f32_16x16x32_bf16 v[120:123], v[172:175], v[180:183], v[120:123]
	v_mfma_f32_16x16x32_bf16 v[108:111], v[164:167], v[188:191], v[108:111]
	v_mfma_f32_16x16x32_bf16 v[104:107], v[172:175], v[188:191], v[104:107]
	v_mfma_f32_16x16x32_bf16 v[92:95], v[164:167], v[196:199], v[92:95]
	v_mfma_f32_16x16x32_bf16 v[88:91], v[172:175], v[196:199], v[88:91]
	v_mfma_f32_16x16x32_bf16 v[76:79], v[164:167], v[208:211], v[76:79]
	v_mfma_f32_16x16x32_bf16 v[72:75], v[172:175], v[208:211], v[72:75]
	s_barrier
	s_add_i32 s48, 0, 0x1c000
	s_add_i32 s33, s33, s56
	v_add_u32_e32 v224, s48, v147
	v_lshl_add_u64 v[200:201], v[200:201], 0, s[16:17]
	s_mov_b32 m0, s33
	ds_read_b128 v[212:215], v224
	ds_read_b128 v[216:219], v224 offset:1024
	ds_read_b128 v[220:223], v224 offset:2048
	ds_read_b128 v[224:227], v224 offset:3072
	global_load_lds_dwordx4 v[200:201], off
	v_lshl_add_u64 v[200:201], v[228:229], 0, s[16:17]
	s_add_i32 m0, s33, 0x2000
	s_nop 0
	global_load_lds_dwordx4 v[200:201], off
	s_barrier
	s_waitcnt lgkmcnt(0)
	s_waitcnt lgkmcnt(0)
	v_mfma_f32_16x16x32_bf16 v[116:119], v[212:215], v[176:179], v[116:119]
	v_mfma_f32_16x16x32_bf16 v[112:115], v[220:223], v[176:179], v[112:115]
	v_mfma_f32_16x16x32_bf16 v[100:103], v[212:215], v[184:187], v[100:103]
	v_mfma_f32_16x16x32_bf16 v[96:99], v[220:223], v[184:187], v[96:99]
	v_mfma_f32_16x16x32_bf16 v[84:87], v[212:215], v[192:195], v[84:87]
	v_mfma_f32_16x16x32_bf16 v[80:83], v[220:223], v[192:195], v[80:83]
	v_mfma_f32_16x16x32_bf16 v[68:71], v[212:215], v[204:207], v[68:71]
	v_mfma_f32_16x16x32_bf16 v[64:67], v[220:223], v[204:207], v[64:67]
	v_mfma_f32_16x16x32_bf16 v[116:119], v[216:219], v[180:183], v[116:119]
	v_mfma_f32_16x16x32_bf16 v[112:115], v[224:227], v[180:183], v[112:115]
	v_mfma_f32_16x16x32_bf16 v[100:103], v[216:219], v[188:191], v[100:103]
	v_mfma_f32_16x16x32_bf16 v[96:99], v[224:227], v[188:191], v[96:99]
	v_mfma_f32_16x16x32_bf16 v[84:87], v[216:219], v[196:199], v[84:87]
	v_mfma_f32_16x16x32_bf16 v[80:83], v[224:227], v[196:199], v[80:83]
	v_mfma_f32_16x16x32_bf16 v[68:71], v[216:219], v[208:211], v[68:71]
	v_mfma_f32_16x16x32_bf16 v[64:67], v[224:227], v[208:211], v[64:67]
	s_mov_b32 m0, s61
	v_lshl_add_u64 v[200:201], v[230:231], 0, s[16:17]
	s_barrier
	ds_read_b128 v[176:179], v158 offset:49152
	ds_read_b128 v[180:183], v158 offset:50176
	ds_read_b128 v[184:187], v158 offset:51200
	ds_read_b128 v[188:191], v158 offset:52224
	ds_read_b128 v[192:195], v158 offset:53248
	ds_read_b128 v[196:199], v158 offset:54272
	ds_read_b128 v[204:207], v158 offset:55296
	ds_read_b128 v[208:211], v158 offset:56320
	global_load_lds_dwordx4 v[200:201], off
	v_lshl_add_u64 v[200:201], v[232:233], 0, s[16:17]
	s_mov_b32 m0, s62
	s_nop 0
	global_load_lds_dwordx4 v[200:201], off
	s_barrier
; __device__ __forceinline__ unsigned cvt_pk_bf16(float lo, float hi) { unsigned r; asm volatile("v_cvt_pk_bf16_f32 %0, %1, %2" : "=v"(r) : "v"(lo), "v"(hi)); return r; }
; #define PG8_STAGE(bufoff, gbase, voff) do { _Pragma("unroll") for (int _i = 0; _i < 2; ++_i) \
;         __builtin_amdgcn_global_load_lds((const unsigned*)((const char*)(gbase) + (voff)[_i]), (LAS unsigned*)(lds + (bufoff) + ldsw + _i * 8192), 16, 0, 0); } while (0)
; #define PG8_MMA(ai, bj, At, Bt) do { __builtin_amdgcn_s_setprio(1); _Pragma("unroll") for (int m = 0; m < 4; ++m) _Pragma("unroll") for (int n = 0; n < 2; ++n) _Pragma("unroll") for (int k = 0; k < 2; ++k) \
;         acc[ai][bj][m][n] = __builtin_amdgcn_mfma_f32_16x16x32_bf16(Bt[n][k], At[m][k], acc[ai][bj][m][n], 0, 0, 0); __builtin_amdgcn_s_setprio(0); } while (0)
; #define PG8_WAIT_V(n) asm volatile("s_waitcnt vmcnt(" #n ")" ::: "memory")
; #define PG8_BAR __builtin_amdgcn_s_barrier()
;     __device__ __forceinline__ void operator()(const f32x4 (&acc)[2][2][4][2], const Unit& u, int wr, int wc, int fr, int fq) const {
;     ...
;             for (int m = 0; m < 4; ++m) { const int row = row0 + ai * HALF + m * 16;
;                 const float rs = ssin ? __builtin_amdgcn_rsqf(ssin[row] * (1.f / D) + EPS) : 1.0f; float sq = 0.f; u32x4 w[2];
; #pragma unroll
;                 for (int bj = 0; bj < 2; ++bj) { f32x4 v0 = acc[ai][bj][m][0] * rs, v1 = acc[ai][bj][m][1] * rs;
;                     if (ACT == 1) {
; #pragma unroll
;                         for (int j = 0; j < 4; ++j) { const float a = fmaxf(v0[j], 0.f), b = fmaxf(v1[j], 0.f); v0[j] = a * a; v1[j] = b * b; } }
;                     sq += (v0[0] * v0[0] + v0[1] * v0[1]) + (v0[2] * v0[2] + v0[3] * v0[3]) + (v1[0] * v1[0] + v1[1] * v1[1]) + (v1[2] * v1[2] + v1[3] * v1[3]);
;                     w[bj].x = cvt_pk_bf16(v0[0], v0[1]); w[bj].y = cvt_pk_bf16(v0[2], v0[3]); w[bj].z = cvt_pk_bf16(v1[0], v1[1]); w[bj].w = cvt_pk_bf16(v1[2], v1[3]); }
;                 store_pair_lines(O, ldc, row, fr, col0, w[0], w[1]);
; template <class Epi>
; __device__ __forceinline__ void gemm_phase(LAS unsigned char* lds, const Gemm g, const StaticOrder& S, const Epi& E) {
;     ...
;             PG8_BAR; PG8_WAIT_L(0); PG8_MMA(1, 0, At, B0); PG8_BAR; PG8_SCHED;
;             PG8_STAGE(PG8_SB(1, 1), b3, voffB1);
;             PG8_WAIT_V(6); PG8_BAR; PG8_MMA(1, 1, At, B1); PG8_BAR;
	s_waitcnt lgkmcnt(0)
	s_waitcnt lgkmcnt(0)
	v_mfma_f32_16x16x32_bf16 v[60:63], v[160:163], v[176:179], v[60:63]
	v_mfma_f32_16x16x32_bf16 v[56:59], v[168:171], v[176:179], v[56:59]
	v_mfma_f32_16x16x32_bf16 v[44:47], v[160:163], v[184:187], v[44:47]
	v_mfma_f32_16x16x32_bf16 v[40:43], v[168:171], v[184:187], v[40:43]
	v_mfma_f32_16x16x32_bf16 v[28:31], v[160:163], v[192:195], v[28:31]
	v_mfma_f32_16x16x32_bf16 v[24:27], v[168:171], v[192:195], v[24:27]
	v_mfma_f32_16x16x32_bf16 v[12:15], v[160:163], v[204:207], v[12:15]
	v_mfma_f32_16x16x32_bf16 v[8:11], v[168:171], v[204:207], v[8:11]
	v_mfma_f32_16x16x32_bf16 v[60:63], v[164:167], v[180:183], v[60:63]
	v_mfma_f32_16x16x32_bf16 v[56:59], v[172:175], v[180:183], v[56:59]
	v_mfma_f32_16x16x32_bf16 v[44:47], v[164:167], v[188:191], v[44:47]
	v_mfma_f32_16x16x32_bf16 v[40:43], v[172:175], v[188:191], v[40:43]
	v_mfma_f32_16x16x32_bf16 v[28:31], v[164:167], v[196:199], v[28:31]
	v_mfma_f32_16x16x32_bf16 v[24:27], v[172:175], v[196:199], v[24:27]
	v_mfma_f32_16x16x32_bf16 v[12:15], v[164:167], v[208:211], v[12:15]
	v_mfma_f32_16x16x32_bf16 v[8:11], v[172:175], v[208:211], v[8:11]
	s_barrier
	s_add_i32 s33, s48, s56
	v_lshl_add_u64 v[160:161], v[234:235], 0, s[16:17]
	s_mov_b32 m0, s33
	s_nop 0
	global_load_lds_dwordx4 v[160:161], off
	v_lshl_add_u64 v[160:161], v[236:237], 0, s[16:17]
	s_add_i32 m0, s33, 0x2000
	s_nop 0
	global_load_lds_dwordx4 v[160:161], off
	s_waitcnt vmcnt(6)
	s_barrier
	v_mfma_f32_16x16x32_bf16 v[52:55], v[212:215], v[176:179], v[52:55]
	v_mfma_f32_16x16x32_bf16 v[48:51], v[220:223], v[176:179], v[48:51]
	v_mfma_f32_16x16x32_bf16 v[36:39], v[212:215], v[184:187], v[36:39]
	v_mfma_f32_16x16x32_bf16 v[32:35], v[220:223], v[184:187], v[32:35]
	v_mfma_f32_16x16x32_bf16 v[20:23], v[212:215], v[192:195], v[20:23]
	v_mfma_f32_16x16x32_bf16 v[16:19], v[220:223], v[192:195], v[16:19]
	v_mfma_f32_16x16x32_bf16 v[4:7], v[212:215], v[204:207], v[4:7]
	v_mfma_f32_16x16x32_bf16 v[0:3], v[220:223], v[204:207], v[0:3]
	v_mfma_f32_16x16x32_bf16 v[52:55], v[216:219], v[180:183], v[52:55]
	v_mfma_f32_16x16x32_bf16 v[48:51], v[224:227], v[180:183], v[48:51]
	v_mfma_f32_16x16x32_bf16 v[36:39], v[216:219], v[188:191], v[36:39]
	v_mfma_f32_16x16x32_bf16 v[32:35], v[224:227], v[188:191], v[32:35]
	v_mfma_f32_16x16x32_bf16 v[20:23], v[216:219], v[196:199], v[20:23]
	v_mfma_f32_16x16x32_bf16 v[16:19], v[224:227], v[196:199], v[16:19]
	v_mfma_f32_16x16x32_bf16 v[4:7], v[216:219], v[208:211], v[4:7]
	v_mfma_f32_16x16x32_bf16 v[0:3], v[224:227], v[208:211], v[0:3]
	s_add_i32 s74, s74, 2
	s_add_u32 s46, s46, 0x100
	s_addc_u32 s47, s47, 0
	s_add_u32 s72, s72, 0x100
	s_addc_u32 s73, s73, 0
	s_cmp_gt_u32 s74, 29
	s_barrier
	s_cbranch_scc0 .LBB0_733
	v_max_f32_e32 v124, v124, v124
	v_max_f32_e32 v120, v120, v120
	v_max_f32_e32 v125, v125, v125
	v_max_f32_e32 v121, v121, v121
	v_max_f32_e32 v122, v122, v122
	v_max_f32_e32 v118, v118, v118
	v_max_f32_e32 v119, v119, v119
	v_max_f32_e32 v124, 0, v124
	v_max_f32_e32 v120, 0, v120
	v_max_f32_e32 v125, 0, v125
	v_max_f32_e32 v121, 0, v121
	v_max_f32_e32 v126, v126, v126
	v_max_f32_e32 v122, 0, v122
	v_max_f32_e32 v127, v127, v127
	v_max_f32_e32 v123, v123, v123
	v_max_f32_e32 v116, v116, v116
	v_max_f32_e32 v112, v112, v112
	v_max_f32_e32 v117, v117, v117
	v_max_f32_e32 v113, v113, v113
	v_max_f32_e32 v118, 0, v118
	v_max_f32_e32 v114, v114, v114
	v_max_f32_e32 v119, 0, v119
	v_mul_f32_e32 v124, v124, v124
	v_mul_f32_e32 v120, v120, v120
	v_mul_f32_e32 v125, v125, v125
	v_mul_f32_e32 v121, v121, v121
	v_max_f32_e32 v126, 0, v126
	v_mul_f32_e32 v122, v122, v122
	v_max_f32_e32 v127, 0, v127
	v_max_f32_e32 v123, 0, v123
	v_max_f32_e32 v116, 0, v116
	v_max_f32_e32 v112, 0, v112
	v_max_f32_e32 v117, 0, v117
	v_max_f32_e32 v113, 0, v113
	v_max_f32_e32 v114, 0, v114
	v_mul_f32_e32 v118, v118, v118
	v_max_f32_e32 v115, v115, v115
	v_mul_f32_e32 v119, v119, v119
	s_lshl_b32 s19, s44, 8
	v_mul_f32_e32 v126, v126, v126
	v_mul_f32_e32 v127, v127, v127
	v_mul_f32_e32 v123, v123, v123
	v_cvt_pk_bf16_f32 v124, v124, v125
	v_cvt_pk_bf16_f32 v125, v126, v127
	v_cvt_pk_bf16_f32 v120, v120, v121
	v_cvt_pk_bf16_f32 v121, v122, v123
	v_mul_f32_e32 v116, v116, v116
	v_mul_f32_e32 v112, v112, v112
	v_mul_f32_e32 v117, v117, v117
	v_mul_f32_e32 v113, v113, v113
	v_mul_f32_e32 v114, v114, v114
	v_max_f32_e32 v115, 0, v115
	v_cvt_pk_bf16_f32 v122, v116, v117
	v_cvt_pk_bf16_f32 v119, v118, v119
	v_mov_b32_e32 v118, 0
	s_add_i32 s19, s19, s63
	v_mul_f32_e32 v115, v115, v115
	v_cvt_pk_bf16_f32 v112, v112, v113
	v_cvt_pk_bf16_f32 v113, v114, v115
	v_mov_b32_dpp v118, v124 row_ror:8 row_mask:0xf bank_mask:0xf
	v_mov_b32_e32 v123, 0
	v_mov_b32_e32 v114, 0
	v_mov_b32_e32 v126, 0
	v_mov_b32_dpp v123, v125 row_ror:8 row_mask:0xf bank_mask:0xf
	v_mov_b32_e32 v127, 0
	v_mov_b32_dpp v114, v122 row_ror:8 row_mask:0xf bank_mask:0xf
	v_mov_b32_e32 v115, 0
	v_mov_b32_e32 v116, 0
	v_mov_b32_e32 v117, 0
	v_cndmask_b32_e64 v118, v122, v118, s[6:7]
	v_or_b32_e32 v122, s19, v148
	v_lshl_or_b32 v162, s69, 8, v156
	v_mov_b32_dpp v126, v120 row_ror:8 row_mask:0xf bank_mask:0xf
	v_mov_b32_dpp v127, v121 row_ror:8 row_mask:0xf bank_mask:0xf
	v_mov_b32_dpp v115, v119 row_ror:8 row_mask:0xf bank_mask:0xf
	v_mov_b32_dpp v116, v112 row_ror:8 row_mask:0xf bank_mask:0xf
	v_mov_b32_dpp v117, v113 row_ror:8 row_mask:0xf bank_mask:0xf
	v_cndmask_b32_e64 v119, v119, v123, s[6:7]
	v_ashrrev_i32_e32 v123, 31, v122
	v_ashrrev_i32_e32 v163, 31, v162
	v_cndmask_b32_e64 v116, v116, v120, s[6:7]
	v_cndmask_b32_e64 v117, v117, v121, s[6:7]
	v_cndmask_b32_e64 v120, v112, v126, s[6:7]
	v_cndmask_b32_e64 v121, v113, v127, s[6:7]
; __device__ __forceinline__ unsigned cvt_pk_bf16(float lo, float hi) { unsigned r; asm volatile("v_cvt_pk_bf16_f32 %0, %1, %2" : "=v"(r) : "v"(lo), "v"(hi)); return r; }
;     __device__ __forceinline__ void operator()(const f32x4 (&acc)[2][2][4][2], const Unit& u, int wr, int wc, int fr, int fq) const {
;     ...
;             for (int m = 0; m < 4; ++m) { const int row = row0 + ai * HALF + m * 16;
;                 const float rs = ssin ? __builtin_amdgcn_rsqf(ssin[row] * (1.f / D) + EPS) : 1.0f; float sq = 0.f; u32x4 w[2];
; #pragma unroll
;                 for (int bj = 0; bj < 2; ++bj) { f32x4 v0 = acc[ai][bj][m][0] * rs, v1 = acc[ai][bj][m][1] * rs;
;                     if (ACT == 1) {
; #pragma unroll
;                         for (int j = 0; j < 4; ++j) { const float a = fmaxf(v0[j], 0.f), b = fmaxf(v1[j], 0.f); v0[j] = a * a; v1[j] = b * b; } }
;                     sq += (v0[0] * v0[0] + v0[1] * v0[1]) + (v0[2] * v0[2] + v0[3] * v0[3]) + (v1[0] * v1[0] + v1[1] * v1[1]) + (v1[2] * v1[2] + v1[3] * v1[3]);
;                     w[bj].x = cvt_pk_bf16(v0[0], v0[1]); w[bj].y = cvt_pk_bf16(v0[2], v0[3]); w[bj].z = cvt_pk_bf16(v1[0], v1[1]); w[bj].w = cvt_pk_bf16(v1[2], v1[3]); }
;                 store_pair_lines(O, ldc, row, fr, col0, w[0], w[1]);
	v_lshlrev_b64 v[112:113], 14, v[122:123]
	v_cndmask_b32_e64 v114, v114, v124, s[6:7]
	v_cndmask_b32_e64 v115, v115, v125, s[6:7]
	v_lshl_add_u64 v[124:125], s[10:11], 0, v[112:113]
	v_lshlrev_b64 v[112:113], 1, v[162:163]
	v_lshl_add_u64 v[124:125], v[124:125], 0, v[112:113]
	global_store_dwordx4 v[124:125], v[114:117], off
	v_max_f32_e32 v108, v108, v108
	v_max_f32_e32 v104, v104, v104
	v_or_b32_e32 v114, 8, v122
	v_ashrrev_i32_e32 v115, 31, v114
	v_lshlrev_b64 v[114:115], 14, v[114:115]
	v_max_f32_e32 v109, v109, v109
	v_max_f32_e32 v105, v105, v105
	v_max_f32_e32 v100, v100, v100
	v_max_f32_e32 v101, v101, v101
	v_max_f32_e32 v102, v102, v102
	v_max_f32_e32 v98, v98, v98
	v_max_f32_e32 v103, v103, v103
	v_lshl_add_u64 v[114:115], s[10:11], 0, v[114:115]
	v_max_f32_e32 v108, 0, v108
	v_max_f32_e32 v104, 0, v104
	v_max_f32_e32 v109, 0, v109
	v_max_f32_e32 v105, 0, v105
	v_max_f32_e32 v110, v110, v110
	v_max_f32_e32 v106, v106, v106
	v_max_f32_e32 v111, v111, v111
	v_max_f32_e32 v107, v107, v107
	v_max_f32_e32 v100, 0, v100
	v_max_f32_e32 v96, v96, v96
	v_max_f32_e32 v101, 0, v101
	v_max_f32_e32 v97, v97, v97
	v_max_f32_e32 v102, 0, v102
	v_max_f32_e32 v98, 0, v98
	v_max_f32_e32 v103, 0, v103
	v_max_f32_e32 v99, v99, v99
	v_lshl_add_u64 v[114:115], v[114:115], 0, v[112:113]
	v_mul_f32_e32 v108, v108, v108
	v_mul_f32_e32 v104, v104, v104
	v_mul_f32_e32 v109, v109, v109
	v_mul_f32_e32 v105, v105, v105
	v_max_f32_e32 v110, 0, v110
	v_max_f32_e32 v106, 0, v106
	v_max_f32_e32 v111, 0, v111
	v_max_f32_e32 v107, 0, v107
	v_max_f32_e32 v96, 0, v96
	v_mul_f32_e32 v100, v100, v100
	v_max_f32_e32 v97, 0, v97
	v_mul_f32_e32 v101, v101, v101
	v_mul_f32_e32 v102, v102, v102
	v_mul_f32_e32 v98, v98, v98
	v_max_f32_e32 v99, 0, v99
	v_mul_f32_e32 v103, v103, v103
	global_store_dwordx4 v[114:115], v[118:121], off
	v_mul_f32_e32 v110, v110, v110
	v_mul_f32_e32 v106, v106, v106
	v_mul_f32_e32 v111, v111, v111
	v_mul_f32_e32 v107, v107, v107
	v_cvt_pk_bf16_f32 v108, v108, v109
	v_cvt_pk_bf16_f32 v109, v110, v111
	v_cvt_pk_bf16_f32 v104, v104, v105
	v_cvt_pk_bf16_f32 v105, v106, v107
	v_mul_f32_e32 v96, v96, v96
	v_mul_f32_e32 v97, v97, v97
	v_mul_f32_e32 v99, v99, v99
	v_cvt_pk_bf16_f32 v100, v100, v101
	v_cvt_pk_bf16_f32 v101, v102, v103
	v_cvt_pk_bf16_f32 v102, v96, v97
	v_cvt_pk_bf16_f32 v103, v98, v99
	v_mov_b32_e32 v98, 0
	v_or_b32_e32 v160, s19, v146
	v_mov_b32_e32 v110, 0
	v_mov_b32_dpp v98, v102 row_ror:8 row_mask:0xf bank_mask:0xf
	v_mov_b32_e32 v99, 0
	v_mov_b32_dpp v110, v104 row_ror:8 row_mask:0xf bank_mask:0xf
	v_mov_b32_e32 v111, 0
	v_mov_b32_dpp v99, v103 row_ror:8 row_mask:0xf bank_mask:0xf
	v_cndmask_b32_e64 v98, v98, v104, s[6:7]
	v_add_u32_e32 v104, v149, v160
	v_mov_b32_dpp v111, v105 row_ror:8 row_mask:0xf bank_mask:0xf
	v_cndmask_b32_e64 v99, v99, v105, s[6:7]
	v_ashrrev_i32_e32 v105, 31, v104
	v_mov_b32_e32 v96, 0
	v_mov_b32_e32 v97, 0
	v_lshlrev_b64 v[104:105], 14, v[104:105]
	v_mov_b32_dpp v96, v100 row_ror:8 row_mask:0xf bank_mask:0xf
	v_mov_b32_dpp v97, v101 row_ror:8 row_mask:0xf bank_mask:0xf
	v_lshl_add_u64 v[104:105], s[10:11], 0, v[104:105]
	v_mov_b32_e32 v106, 0
	v_mov_b32_e32 v107, 0
	v_cndmask_b32_e64 v96, v96, v108, s[6:7]
	v_cndmask_b32_e64 v97, v97, v109, s[6:7]
	v_lshl_add_u64 v[104:105], v[104:105], 0, v[112:113]
	v_max_f32_e32 v92, v92, v92
	v_max_f32_e32 v88, v88, v88
	v_max_f32_e32 v93, v93, v93
	v_max_f32_e32 v89, v89, v89
	v_max_f32_e32 v84, v84, v84
	v_max_f32_e32 v85, v85, v85
	v_max_f32_e32 v86, v86, v86
	v_max_f32_e32 v82, v82, v82
	v_max_f32_e32 v87, v87, v87
	v_mov_b32_dpp v106, v108 row_ror:8 row_mask:0xf bank_mask:0xf
	v_mov_b32_dpp v107, v109 row_ror:8 row_mask:0xf bank_mask:0xf
	global_store_dwordx4 v[104:105], v[96:99], off
	v_max_f32_e32 v92, 0, v92
	v_max_f32_e32 v88, 0, v88
	v_add_co_u32_e32 v96, vcc, s68, v104
	v_max_f32_e32 v93, 0, v93
	v_max_f32_e32 v89, 0, v89
	v_max_f32_e32 v94, v94, v94
	v_max_f32_e32 v90, v90, v90
	v_max_f32_e32 v95, v95, v95
	v_max_f32_e32 v91, v91, v91
	v_max_f32_e32 v84, 0, v84
	v_max_f32_e32 v80, v80, v80
	v_max_f32_e32 v85, 0, v85
	v_max_f32_e32 v81, v81, v81
	v_max_f32_e32 v86, 0, v86
	v_max_f32_e32 v82, 0, v82
	v_max_f32_e32 v87, 0, v87
	v_max_f32_e32 v83, v83, v83
	v_cndmask_b32_e64 v100, v100, v106, s[6:7]
	v_cndmask_b32_e64 v101, v101, v107, s[6:7]
	v_cndmask_b32_e64 v102, v102, v110, s[6:7]
	v_cndmask_b32_e64 v103, v103, v111, s[6:7]
	v_addc_co_u32_e32 v97, vcc, 0, v105, vcc
	v_mul_f32_e32 v92, v92, v92
	v_mul_f32_e32 v88, v88, v88
	v_mul_f32_e32 v93, v93, v93
	v_mul_f32_e32 v89, v89, v89
	v_max_f32_e32 v94, 0, v94
	v_max_f32_e32 v90, 0, v90
	v_max_f32_e32 v95, 0, v95
	v_max_f32_e32 v91, 0, v91
	v_max_f32_e32 v80, 0, v80
	v_mul_f32_e32 v84, v84, v84
	v_max_f32_e32 v81, 0, v81
	v_mul_f32_e32 v85, v85, v85
	v_mul_f32_e32 v86, v86, v86
	v_mul_f32_e32 v82, v82, v82
	v_max_f32_e32 v83, 0, v83
	v_mul_f32_e32 v87, v87, v87
	global_store_dwordx4 v[96:97], v[100:103], off
	v_mul_f32_e32 v94, v94, v94
	v_mul_f32_e32 v90, v90, v90
	v_mul_f32_e32 v95, v95, v95
	v_mul_f32_e32 v91, v91, v91
	v_cvt_pk_bf16_f32 v92, v92, v93
	v_cvt_pk_bf16_f32 v93, v94, v95
	v_cvt_pk_bf16_f32 v88, v88, v89
	v_cvt_pk_bf16_f32 v89, v90, v91
	v_mul_f32_e32 v80, v80, v80
	v_mul_f32_e32 v81, v81, v81
	v_mul_f32_e32 v83, v83, v83
	v_cvt_pk_bf16_f32 v84, v84, v85
	v_cvt_pk_bf16_f32 v85, v86, v87
	v_cvt_pk_bf16_f32 v86, v80, v81
	v_cvt_pk_bf16_f32 v87, v82, v83
	v_mov_b32_e32 v82, 0
	v_mov_b32_e32 v94, 0
	v_mov_b32_e32 v83, 0
	v_mov_b32_dpp v82, v86 row_ror:8 row_mask:0xf bank_mask:0xf
	v_mov_b32_dpp v94, v88 row_ror:8 row_mask:0xf bank_mask:0xf
	v_mov_b32_e32 v95, 0
	v_mov_b32_dpp v83, v87 row_ror:8 row_mask:0xf bank_mask:0xf
; __device__ __forceinline__ unsigned cvt_pk_bf16(float lo, float hi) { unsigned r; asm volatile("v_cvt_pk_bf16_f32 %0, %1, %2" : "=v"(r) : "v"(lo), "v"(hi)); return r; }
;     __device__ __forceinline__ void operator()(const f32x4 (&acc)[2][2][4][2], const Unit& u, int wr, int wc, int fr, int fq) const {
;     ...
;             for (int m = 0; m < 4; ++m) { const int row = row0 + ai * HALF + m * 16;
;                 const float rs = ssin ? __builtin_amdgcn_rsqf(ssin[row] * (1.f / D) + EPS) : 1.0f; float sq = 0.f; u32x4 w[2];
; #pragma unroll
;                 for (int bj = 0; bj < 2; ++bj) { f32x4 v0 = acc[ai][bj][m][0] * rs, v1 = acc[ai][bj][m][1] * rs;
;                     if (ACT == 1) {
; #pragma unroll
;                         for (int j = 0; j < 4; ++j) { const float a = fmaxf(v0[j], 0.f), b = fmaxf(v1[j], 0.f); v0[j] = a * a; v1[j] = b * b; } }
;                     sq += (v0[0] * v0[0] + v0[1] * v0[1]) + (v0[2] * v0[2] + v0[3] * v0[3]) + (v1[0] * v1[0] + v1[1] * v1[1]) + (v1[2] * v1[2] + v1[3] * v1[3]);
;                     w[bj].x = cvt_pk_bf16(v0[0], v0[1]); w[bj].y = cvt_pk_bf16(v0[2], v0[3]); w[bj].z = cvt_pk_bf16(v1[0], v1[1]); w[bj].w = cvt_pk_bf16(v1[2], v1[3]); }
;                 store_pair_lines(O, ldc, row, fr, col0, w[0], w[1]);
	v_cndmask_b32_e64 v82, v82, v88, s[6:7]
	v_add_u32_e32 v88, v150, v160
	v_mov_b32_dpp v95, v89 row_ror:8 row_mask:0xf bank_mask:0xf
	v_cndmask_b32_e64 v83, v83, v89, s[6:7]
	v_ashrrev_i32_e32 v89, 31, v88
	v_mov_b32_e32 v80, 0
	v_mov_b32_e32 v81, 0
	v_lshlrev_b64 v[88:89], 14, v[88:89]
	v_mov_b32_dpp v80, v84 row_ror:8 row_mask:0xf bank_mask:0xf
	v_mov_b32_dpp v81, v85 row_ror:8 row_mask:0xf bank_mask:0xf
	v_lshl_add_u64 v[88:89], s[10:11], 0, v[88:89]
	v_mov_b32_e32 v90, 0
	v_mov_b32_e32 v91, 0
	v_cndmask_b32_e64 v80, v80, v92, s[6:7]
	v_cndmask_b32_e64 v81, v81, v93, s[6:7]
	v_lshl_add_u64 v[88:89], v[88:89], 0, v[112:113]
	v_max_f32_e32 v76, v76, v76
	v_max_f32_e32 v72, v72, v72
	v_max_f32_e32 v77, v77, v77
	v_max_f32_e32 v73, v73, v73
	v_max_f32_e32 v68, v68, v68
	v_max_f32_e32 v69, v69, v69
	v_max_f32_e32 v70, v70, v70
	v_max_f32_e32 v66, v66, v66
	v_max_f32_e32 v71, v71, v71
	v_mov_b32_dpp v90, v92 row_ror:8 row_mask:0xf bank_mask:0xf
	v_mov_b32_dpp v91, v93 row_ror:8 row_mask:0xf bank_mask:0xf
	global_store_dwordx4 v[88:89], v[80:83], off
	v_max_f32_e32 v76, 0, v76
	v_max_f32_e32 v72, 0, v72
	v_add_co_u32_e32 v80, vcc, s68, v88
	v_max_f32_e32 v77, 0, v77
	v_max_f32_e32 v73, 0, v73
	v_max_f32_e32 v78, v78, v78
	v_max_f32_e32 v74, v74, v74
	v_max_f32_e32 v79, v79, v79
	v_max_f32_e32 v75, v75, v75
	v_max_f32_e32 v68, 0, v68
	v_max_f32_e32 v64, v64, v64
	v_max_f32_e32 v69, 0, v69
	v_max_f32_e32 v65, v65, v65
	v_max_f32_e32 v70, 0, v70
	v_max_f32_e32 v66, 0, v66
	v_max_f32_e32 v71, 0, v71
	v_max_f32_e32 v67, v67, v67
	v_cndmask_b32_e64 v84, v84, v90, s[6:7]
	v_cndmask_b32_e64 v85, v85, v91, s[6:7]
	v_cndmask_b32_e64 v86, v86, v94, s[6:7]
	v_cndmask_b32_e64 v87, v87, v95, s[6:7]
	v_addc_co_u32_e32 v81, vcc, 0, v89, vcc
	v_mul_f32_e32 v76, v76, v76
	v_mul_f32_e32 v72, v72, v72
	v_mul_f32_e32 v77, v77, v77
	v_mul_f32_e32 v73, v73, v73
	v_max_f32_e32 v78, 0, v78
	v_max_f32_e32 v74, 0, v74
	v_max_f32_e32 v79, 0, v79
	v_max_f32_e32 v75, 0, v75
	v_max_f32_e32 v64, 0, v64
	v_mul_f32_e32 v68, v68, v68
	v_max_f32_e32 v65, 0, v65
	v_mul_f32_e32 v69, v69, v69
	v_mul_f32_e32 v70, v70, v70
	v_mul_f32_e32 v66, v66, v66
	v_max_f32_e32 v67, 0, v67
	v_mul_f32_e32 v71, v71, v71
	global_store_dwordx4 v[80:81], v[84:87], off
	v_mul_f32_e32 v78, v78, v78
	v_mul_f32_e32 v74, v74, v74
	v_mul_f32_e32 v79, v79, v79
	v_mul_f32_e32 v75, v75, v75
	v_cvt_pk_bf16_f32 v76, v76, v77
	v_cvt_pk_bf16_f32 v77, v78, v79
	v_cvt_pk_bf16_f32 v72, v72, v73
	v_cvt_pk_bf16_f32 v73, v74, v75
	v_mul_f32_e32 v64, v64, v64
	v_mul_f32_e32 v65, v65, v65
	v_mul_f32_e32 v67, v67, v67
	v_cvt_pk_bf16_f32 v68, v68, v69
	v_cvt_pk_bf16_f32 v69, v70, v71
	v_cvt_pk_bf16_f32 v70, v64, v65
	v_cvt_pk_bf16_f32 v71, v66, v67
	v_mov_b32_e32 v66, 0
	v_mov_b32_e32 v78, 0
	v_mov_b32_e32 v67, 0
	v_mov_b32_dpp v66, v70 row_ror:8 row_mask:0xf bank_mask:0xf
	v_mov_b32_dpp v78, v72 row_ror:8 row_mask:0xf bank_mask:0xf
	v_mov_b32_e32 v79, 0
	v_mov_b32_dpp v67, v71 row_ror:8 row_mask:0xf bank_mask:0xf
	v_cndmask_b32_e64 v66, v66, v72, s[6:7]
	v_add_u32_e32 v72, v151, v160
	v_mov_b32_dpp v79, v73 row_ror:8 row_mask:0xf bank_mask:0xf
	v_cndmask_b32_e64 v67, v67, v73, s[6:7]
	v_ashrrev_i32_e32 v73, 31, v72
	v_mov_b32_e32 v64, 0
	v_mov_b32_e32 v65, 0
	v_lshlrev_b64 v[72:73], 14, v[72:73]
	v_mov_b32_dpp v64, v68 row_ror:8 row_mask:0xf bank_mask:0xf
	v_mov_b32_dpp v65, v69 row_ror:8 row_mask:0xf bank_mask:0xf
	v_lshl_add_u64 v[72:73], s[10:11], 0, v[72:73]
	v_mov_b32_e32 v74, 0
	v_mov_b32_e32 v75, 0
	v_cndmask_b32_e64 v64, v64, v76, s[6:7]
	v_cndmask_b32_e64 v65, v65, v77, s[6:7]
	v_lshl_add_u64 v[72:73], v[72:73], 0, v[112:113]
	v_max_f32_e32 v60, v60, v60
	v_max_f32_e32 v56, v56, v56
	v_max_f32_e32 v61, v61, v61
	v_max_f32_e32 v57, v57, v57
	v_max_f32_e32 v52, v52, v52
	v_max_f32_e32 v53, v53, v53
	v_max_f32_e32 v54, v54, v54
	v_max_f32_e32 v50, v50, v50
	v_max_f32_e32 v55, v55, v55
	v_mov_b32_dpp v74, v76 row_ror:8 row_mask:0xf bank_mask:0xf
	v_mov_b32_dpp v75, v77 row_ror:8 row_mask:0xf bank_mask:0xf
	global_store_dwordx4 v[72:73], v[64:67], off
	v_max_f32_e32 v60, 0, v60
	v_max_f32_e32 v56, 0, v56
	v_add_co_u32_e32 v64, vcc, s68, v72
	v_max_f32_e32 v61, 0, v61
	v_max_f32_e32 v57, 0, v57
	v_max_f32_e32 v62, v62, v62
	v_max_f32_e32 v58, v58, v58
	v_max_f32_e32 v63, v63, v63
	v_max_f32_e32 v59, v59, v59
	v_max_f32_e32 v52, 0, v52
	v_max_f32_e32 v48, v48, v48
	v_max_f32_e32 v53, 0, v53
	v_max_f32_e32 v49, v49, v49
	v_max_f32_e32 v54, 0, v54
	v_max_f32_e32 v50, 0, v50
	v_max_f32_e32 v55, 0, v55
	v_max_f32_e32 v51, v51, v51
	v_cndmask_b32_e64 v68, v68, v74, s[6:7]
	v_cndmask_b32_e64 v69, v69, v75, s[6:7]
	v_cndmask_b32_e64 v70, v70, v78, s[6:7]
	v_cndmask_b32_e64 v71, v71, v79, s[6:7]
	v_addc_co_u32_e32 v65, vcc, 0, v73, vcc
	v_mul_f32_e32 v60, v60, v60
	v_mul_f32_e32 v56, v56, v56
	v_mul_f32_e32 v61, v61, v61
	v_mul_f32_e32 v57, v57, v57
	v_max_f32_e32 v62, 0, v62
	v_max_f32_e32 v58, 0, v58
	v_max_f32_e32 v63, 0, v63
	v_max_f32_e32 v59, 0, v59
	v_max_f32_e32 v48, 0, v48
	v_mul_f32_e32 v52, v52, v52
	v_max_f32_e32 v49, 0, v49
	v_mul_f32_e32 v53, v53, v53
	v_mul_f32_e32 v54, v54, v54
	v_mul_f32_e32 v50, v50, v50
	v_max_f32_e32 v51, 0, v51
	v_mul_f32_e32 v55, v55, v55
	global_store_dwordx4 v[64:65], v[68:71], off
	v_mul_f32_e32 v62, v62, v62
	v_mul_f32_e32 v58, v58, v58
	v_mul_f32_e32 v63, v63, v63
	v_mul_f32_e32 v59, v59, v59
	v_cvt_pk_bf16_f32 v60, v60, v61
	v_cvt_pk_bf16_f32 v61, v62, v63
	v_cvt_pk_bf16_f32 v56, v56, v57
	v_cvt_pk_bf16_f32 v57, v58, v59
	v_mul_f32_e32 v48, v48, v48
	v_mul_f32_e32 v49, v49, v49
	v_mul_f32_e32 v51, v51, v51
	v_cvt_pk_bf16_f32 v52, v52, v53
	v_cvt_pk_bf16_f32 v53, v54, v55
; __device__ __forceinline__ unsigned cvt_pk_bf16(float lo, float hi) { unsigned r; asm volatile("v_cvt_pk_bf16_f32 %0, %1, %2" : "=v"(r) : "v"(lo), "v"(hi)); return r; }
;     __device__ __forceinline__ void operator()(const f32x4 (&acc)[2][2][4][2], const Unit& u, int wr, int wc, int fr, int fq) const {
;     ...
;             for (int m = 0; m < 4; ++m) { const int row = row0 + ai * HALF + m * 16;
;                 const float rs = ssin ? __builtin_amdgcn_rsqf(ssin[row] * (1.f / D) + EPS) : 1.0f; float sq = 0.f; u32x4 w[2];
; #pragma unroll
;                 for (int bj = 0; bj < 2; ++bj) { f32x4 v0 = acc[ai][bj][m][0] * rs, v1 = acc[ai][bj][m][1] * rs;
;                     if (ACT == 1) {
; #pragma unroll
;                         for (int j = 0; j < 4; ++j) { const float a = fmaxf(v0[j], 0.f), b = fmaxf(v1[j], 0.f); v0[j] = a * a; v1[j] = b * b; } }
;                     sq += (v0[0] * v0[0] + v0[1] * v0[1]) + (v0[2] * v0[2] + v0[3] * v0[3]) + (v1[0] * v1[0] + v1[1] * v1[1]) + (v1[2] * v1[2] + v1[3] * v1[3]);
;                     w[bj].x = cvt_pk_bf16(v0[0], v0[1]); w[bj].y = cvt_pk_bf16(v0[2], v0[3]); w[bj].z = cvt_pk_bf16(v1[0], v1[1]); w[bj].w = cvt_pk_bf16(v1[2], v1[3]); }
;                 store_pair_lines(O, ldc, row, fr, col0, w[0], w[1]);
	v_cvt_pk_bf16_f32 v54, v48, v49
	v_cvt_pk_bf16_f32 v55, v50, v51
	v_mov_b32_e32 v50, 0
	v_mov_b32_e32 v62, 0
	v_mov_b32_e32 v51, 0
	v_mov_b32_dpp v50, v54 row_ror:8 row_mask:0xf bank_mask:0xf
	v_mov_b32_dpp v62, v56 row_ror:8 row_mask:0xf bank_mask:0xf
	v_mov_b32_e32 v63, 0
	v_mov_b32_dpp v51, v55 row_ror:8 row_mask:0xf bank_mask:0xf
	v_cndmask_b32_e64 v50, v50, v56, s[6:7]
	v_add_u32_e32 v56, v152, v160
	v_mov_b32_dpp v63, v57 row_ror:8 row_mask:0xf bank_mask:0xf
	v_cndmask_b32_e64 v51, v51, v57, s[6:7]
	v_ashrrev_i32_e32 v57, 31, v56
	v_mov_b32_e32 v48, 0
	v_mov_b32_e32 v49, 0
	v_lshlrev_b64 v[56:57], 14, v[56:57]
	v_mov_b32_dpp v48, v52 row_ror:8 row_mask:0xf bank_mask:0xf
	v_mov_b32_dpp v49, v53 row_ror:8 row_mask:0xf bank_mask:0xf
	v_lshl_add_u64 v[56:57], s[10:11], 0, v[56:57]
	v_mov_b32_e32 v58, 0
	v_mov_b32_e32 v59, 0
	v_cndmask_b32_e64 v48, v48, v60, s[6:7]
	v_cndmask_b32_e64 v49, v49, v61, s[6:7]
	v_lshl_add_u64 v[56:57], v[56:57], 0, v[112:113]
	v_max_f32_e32 v44, v44, v44
	v_max_f32_e32 v40, v40, v40
	v_max_f32_e32 v45, v45, v45
	v_max_f32_e32 v41, v41, v41
	v_max_f32_e32 v36, v36, v36
	v_max_f32_e32 v37, v37, v37
	v_max_f32_e32 v38, v38, v38
	v_max_f32_e32 v34, v34, v34
	v_max_f32_e32 v39, v39, v39
	v_mov_b32_dpp v58, v60 row_ror:8 row_mask:0xf bank_mask:0xf
	v_mov_b32_dpp v59, v61 row_ror:8 row_mask:0xf bank_mask:0xf
	global_store_dwordx4 v[56:57], v[48:51], off
	v_max_f32_e32 v44, 0, v44
	v_max_f32_e32 v40, 0, v40
	v_add_co_u32_e32 v48, vcc, s68, v56
	v_max_f32_e32 v45, 0, v45
	v_max_f32_e32 v41, 0, v41
	v_max_f32_e32 v46, v46, v46
	v_max_f32_e32 v42, v42, v42
	v_max_f32_e32 v47, v47, v47
	v_max_f32_e32 v43, v43, v43
	v_max_f32_e32 v36, 0, v36
	v_max_f32_e32 v32, v32, v32
	v_max_f32_e32 v37, 0, v37
	v_max_f32_e32 v33, v33, v33
	v_max_f32_e32 v38, 0, v38
	v_max_f32_e32 v34, 0, v34
	v_max_f32_e32 v39, 0, v39
	v_max_f32_e32 v35, v35, v35
	v_cndmask_b32_e64 v52, v52, v58, s[6:7]
	v_cndmask_b32_e64 v53, v53, v59, s[6:7]
	v_cndmask_b32_e64 v54, v54, v62, s[6:7]
	v_cndmask_b32_e64 v55, v55, v63, s[6:7]
	v_addc_co_u32_e32 v49, vcc, 0, v57, vcc
	v_mul_f32_e32 v44, v44, v44
	v_mul_f32_e32 v40, v40, v40
	v_mul_f32_e32 v45, v45, v45
	v_mul_f32_e32 v41, v41, v41
	v_max_f32_e32 v46, 0, v46
	v_max_f32_e32 v42, 0, v42
	v_max_f32_e32 v47, 0, v47
	v_max_f32_e32 v43, 0, v43
	v_max_f32_e32 v32, 0, v32
	v_mul_f32_e32 v36, v36, v36
	v_max_f32_e32 v33, 0, v33
	v_mul_f32_e32 v37, v37, v37
	v_mul_f32_e32 v38, v38, v38
	v_mul_f32_e32 v34, v34, v34
	v_max_f32_e32 v35, 0, v35
	v_mul_f32_e32 v39, v39, v39
	global_store_dwordx4 v[48:49], v[52:55], off
	v_mul_f32_e32 v46, v46, v46
	v_mul_f32_e32 v42, v42, v42
	v_mul_f32_e32 v47, v47, v47
	v_mul_f32_e32 v43, v43, v43
	v_cvt_pk_bf16_f32 v44, v44, v45
	v_cvt_pk_bf16_f32 v45, v46, v47
	v_cvt_pk_bf16_f32 v40, v40, v41
	v_cvt_pk_bf16_f32 v41, v42, v43
	v_mul_f32_e32 v32, v32, v32
	v_mul_f32_e32 v33, v33, v33
	v_mul_f32_e32 v35, v35, v35
	v_cvt_pk_bf16_f32 v36, v36, v37
	v_cvt_pk_bf16_f32 v37, v38, v39
	v_cvt_pk_bf16_f32 v38, v32, v33
	v_cvt_pk_bf16_f32 v39, v34, v35
	v_mov_b32_e32 v34, 0
	v_mov_b32_e32 v46, 0
	v_mov_b32_e32 v35, 0
	v_mov_b32_dpp v34, v38 row_ror:8 row_mask:0xf bank_mask:0xf
	v_mov_b32_dpp v46, v40 row_ror:8 row_mask:0xf bank_mask:0xf
	v_mov_b32_e32 v47, 0
	v_mov_b32_dpp v35, v39 row_ror:8 row_mask:0xf bank_mask:0xf
	v_cndmask_b32_e64 v34, v34, v40, s[6:7]
	v_add_u32_e32 v40, v153, v160
	v_mov_b32_dpp v47, v41 row_ror:8 row_mask:0xf bank_mask:0xf
	v_cndmask_b32_e64 v35, v35, v41, s[6:7]
	v_ashrrev_i32_e32 v41, 31, v40
	v_mov_b32_e32 v32, 0
	v_mov_b32_e32 v33, 0
	v_lshlrev_b64 v[40:41], 14, v[40:41]
	v_mov_b32_dpp v32, v36 row_ror:8 row_mask:0xf bank_mask:0xf
	v_mov_b32_dpp v33, v37 row_ror:8 row_mask:0xf bank_mask:0xf
	v_lshl_add_u64 v[40:41], s[10:11], 0, v[40:41]
	v_mov_b32_e32 v42, 0
	v_mov_b32_e32 v43, 0
	v_cndmask_b32_e64 v32, v32, v44, s[6:7]
	v_cndmask_b32_e64 v33, v33, v45, s[6:7]
	v_lshl_add_u64 v[40:41], v[40:41], 0, v[112:113]
	v_max_f32_e32 v28, v28, v28
	v_max_f32_e32 v24, v24, v24
	v_max_f32_e32 v29, v29, v29
	v_max_f32_e32 v25, v25, v25
	v_max_f32_e32 v20, v20, v20
	v_max_f32_e32 v21, v21, v21
	v_max_f32_e32 v22, v22, v22
	v_max_f32_e32 v18, v18, v18
	v_max_f32_e32 v23, v23, v23
	v_mov_b32_dpp v42, v44 row_ror:8 row_mask:0xf bank_mask:0xf
	v_mov_b32_dpp v43, v45 row_ror:8 row_mask:0xf bank_mask:0xf
	global_store_dwordx4 v[40:41], v[32:35], off
	v_max_f32_e32 v28, 0, v28
	v_max_f32_e32 v24, 0, v24
	v_add_co_u32_e32 v32, vcc, s68, v40
	v_max_f32_e32 v29, 0, v29
	v_max_f32_e32 v25, 0, v25
	v_max_f32_e32 v30, v30, v30
	v_max_f32_e32 v26, v26, v26
	v_max_f32_e32 v31, v31, v31
	v_max_f32_e32 v27, v27, v27
	v_max_f32_e32 v20, 0, v20
	v_max_f32_e32 v16, v16, v16
	v_max_f32_e32 v21, 0, v21
	v_max_f32_e32 v17, v17, v17
	v_max_f32_e32 v22, 0, v22
	v_max_f32_e32 v18, 0, v18
	v_max_f32_e32 v23, 0, v23
	v_max_f32_e32 v19, v19, v19
	v_cndmask_b32_e64 v36, v36, v42, s[6:7]
	v_cndmask_b32_e64 v37, v37, v43, s[6:7]
	v_cndmask_b32_e64 v38, v38, v46, s[6:7]
	v_cndmask_b32_e64 v39, v39, v47, s[6:7]
	v_addc_co_u32_e32 v33, vcc, 0, v41, vcc
	v_mul_f32_e32 v28, v28, v28
	v_mul_f32_e32 v24, v24, v24
	v_mul_f32_e32 v29, v29, v29
	v_mul_f32_e32 v25, v25, v25
	v_max_f32_e32 v30, 0, v30
	v_max_f32_e32 v26, 0, v26
; __device__ __forceinline__ unsigned cvt_pk_bf16(float lo, float hi) { unsigned r; asm volatile("v_cvt_pk_bf16_f32 %0, %1, %2" : "=v"(r) : "v"(lo), "v"(hi)); return r; }
;     __device__ __forceinline__ void operator()(const f32x4 (&acc)[2][2][4][2], const Unit& u, int wr, int wc, int fr, int fq) const {
;     ...
;             for (int m = 0; m < 4; ++m) { const int row = row0 + ai * HALF + m * 16;
;                 const float rs = ssin ? __builtin_amdgcn_rsqf(ssin[row] * (1.f / D) + EPS) : 1.0f; float sq = 0.f; u32x4 w[2];
; #pragma unroll
;                 for (int bj = 0; bj < 2; ++bj) { f32x4 v0 = acc[ai][bj][m][0] * rs, v1 = acc[ai][bj][m][1] * rs;
;                     if (ACT == 1) {
; #pragma unroll
;                         for (int j = 0; j < 4; ++j) { const float a = fmaxf(v0[j], 0.f), b = fmaxf(v1[j], 0.f); v0[j] = a * a; v1[j] = b * b; } }
;                     sq += (v0[0] * v0[0] + v0[1] * v0[1]) + (v0[2] * v0[2] + v0[3] * v0[3]) + (v1[0] * v1[0] + v1[1] * v1[1]) + (v1[2] * v1[2] + v1[3] * v1[3]);
;                     w[bj].x = cvt_pk_bf16(v0[0], v0[1]); w[bj].y = cvt_pk_bf16(v0[2], v0[3]); w[bj].z = cvt_pk_bf16(v1[0], v1[1]); w[bj].w = cvt_pk_bf16(v1[2], v1[3]); }
;                 store_pair_lines(O, ldc, row, fr, col0, w[0], w[1]);
	v_max_f32_e32 v31, 0, v31
	v_max_f32_e32 v27, 0, v27
	v_max_f32_e32 v16, 0, v16
	v_mul_f32_e32 v20, v20, v20
	v_max_f32_e32 v17, 0, v17
	v_mul_f32_e32 v21, v21, v21
	v_mul_f32_e32 v22, v22, v22
	v_mul_f32_e32 v18, v18, v18
	v_max_f32_e32 v19, 0, v19
	v_mul_f32_e32 v23, v23, v23
	global_store_dwordx4 v[32:33], v[36:39], off
	v_mul_f32_e32 v30, v30, v30
	v_mul_f32_e32 v26, v26, v26
	v_mul_f32_e32 v31, v31, v31
	v_mul_f32_e32 v27, v27, v27
	v_cvt_pk_bf16_f32 v28, v28, v29
	v_cvt_pk_bf16_f32 v29, v30, v31
	v_cvt_pk_bf16_f32 v24, v24, v25
	v_cvt_pk_bf16_f32 v25, v26, v27
	v_mul_f32_e32 v16, v16, v16
	v_mul_f32_e32 v17, v17, v17
	v_mul_f32_e32 v19, v19, v19
	v_cvt_pk_bf16_f32 v20, v20, v21
	v_cvt_pk_bf16_f32 v21, v22, v23
	v_cvt_pk_bf16_f32 v22, v16, v17
	v_cvt_pk_bf16_f32 v23, v18, v19
	v_mov_b32_e32 v18, 0
	v_mov_b32_e32 v30, 0
	v_mov_b32_e32 v19, 0
	v_mov_b32_dpp v18, v22 row_ror:8 row_mask:0xf bank_mask:0xf
	v_mov_b32_dpp v30, v24 row_ror:8 row_mask:0xf bank_mask:0xf
	v_mov_b32_e32 v31, 0
	v_mov_b32_dpp v19, v23 row_ror:8 row_mask:0xf bank_mask:0xf
	v_cndmask_b32_e64 v18, v18, v24, s[6:7]
	v_add_u32_e32 v24, v154, v160
	v_mov_b32_dpp v31, v25 row_ror:8 row_mask:0xf bank_mask:0xf
	v_cndmask_b32_e64 v19, v19, v25, s[6:7]
	v_ashrrev_i32_e32 v25, 31, v24
	v_mov_b32_e32 v16, 0
	v_mov_b32_e32 v17, 0
	v_lshlrev_b64 v[24:25], 14, v[24:25]
	v_mov_b32_dpp v16, v20 row_ror:8 row_mask:0xf bank_mask:0xf
	v_mov_b32_dpp v17, v21 row_ror:8 row_mask:0xf bank_mask:0xf
	v_lshl_add_u64 v[24:25], s[10:11], 0, v[24:25]
	v_mov_b32_e32 v26, 0
	v_mov_b32_e32 v27, 0
	v_cndmask_b32_e64 v16, v16, v28, s[6:7]
	v_cndmask_b32_e64 v17, v17, v29, s[6:7]
	v_lshl_add_u64 v[24:25], v[24:25], 0, v[112:113]
	v_max_f32_e32 v12, v12, v12
	v_max_f32_e32 v8, v8, v8
	v_max_f32_e32 v13, v13, v13
	v_max_f32_e32 v9, v9, v9
	v_max_f32_e32 v4, v4, v4
	v_max_f32_e32 v5, v5, v5
	v_max_f32_e32 v6, v6, v6
	v_max_f32_e32 v2, v2, v2
	v_max_f32_e32 v7, v7, v7
	v_mov_b32_dpp v26, v28 row_ror:8 row_mask:0xf bank_mask:0xf
	v_mov_b32_dpp v27, v29 row_ror:8 row_mask:0xf bank_mask:0xf
	global_store_dwordx4 v[24:25], v[16:19], off
	v_max_f32_e32 v12, 0, v12
	v_max_f32_e32 v8, 0, v8
	v_add_co_u32_e32 v16, vcc, s68, v24
	v_max_f32_e32 v13, 0, v13
	v_max_f32_e32 v9, 0, v9
	v_max_f32_e32 v14, v14, v14
	v_max_f32_e32 v10, v10, v10
	v_max_f32_e32 v15, v15, v15
	v_max_f32_e32 v11, v11, v11
	v_max_f32_e32 v4, 0, v4
	v_max_f32_e32 v0, v0, v0
	v_max_f32_e32 v5, 0, v5
	v_max_f32_e32 v1, v1, v1
	v_max_f32_e32 v6, 0, v6
	v_max_f32_e32 v2, 0, v2
	v_max_f32_e32 v7, 0, v7
	v_max_f32_e32 v3, v3, v3
	v_cndmask_b32_e64 v20, v20, v26, s[6:7]
	v_cndmask_b32_e64 v21, v21, v27, s[6:7]
	v_cndmask_b32_e64 v22, v22, v30, s[6:7]
	v_cndmask_b32_e64 v23, v23, v31, s[6:7]
	v_addc_co_u32_e32 v17, vcc, 0, v25, vcc
	v_mul_f32_e32 v12, v12, v12
	v_mul_f32_e32 v8, v8, v8
	v_mul_f32_e32 v13, v13, v13
	v_mul_f32_e32 v9, v9, v9
	v_max_f32_e32 v14, 0, v14
	v_max_f32_e32 v10, 0, v10
	v_max_f32_e32 v15, 0, v15
	v_max_f32_e32 v11, 0, v11
	v_max_f32_e32 v0, 0, v0
	v_mul_f32_e32 v4, v4, v4
	v_max_f32_e32 v1, 0, v1
	v_mul_f32_e32 v5, v5, v5
	v_mul_f32_e32 v6, v6, v6
	v_mul_f32_e32 v2, v2, v2
	v_max_f32_e32 v3, 0, v3
	v_mul_f32_e32 v7, v7, v7
	global_store_dwordx4 v[16:17], v[20:23], off
	v_mul_f32_e32 v14, v14, v14
	v_mul_f32_e32 v10, v10, v10
	v_mul_f32_e32 v15, v15, v15
	v_mul_f32_e32 v11, v11, v11
	v_cvt_pk_bf16_f32 v12, v12, v13
	v_cvt_pk_bf16_f32 v13, v14, v15
	v_cvt_pk_bf16_f32 v8, v8, v9
	v_cvt_pk_bf16_f32 v9, v10, v11
	v_mul_f32_e32 v0, v0, v0
	v_mul_f32_e32 v1, v1, v1
	v_mul_f32_e32 v3, v3, v3
	v_cvt_pk_bf16_f32 v4, v4, v5
	v_cvt_pk_bf16_f32 v5, v6, v7
	v_cvt_pk_bf16_f32 v6, v0, v1
	v_cvt_pk_bf16_f32 v7, v2, v3
	v_mov_b32_e32 v2, 0
	v_mov_b32_e32 v14, 0
	v_mov_b32_e32 v3, 0
	v_mov_b32_dpp v2, v6 row_ror:8 row_mask:0xf bank_mask:0xf
	v_mov_b32_dpp v14, v8 row_ror:8 row_mask:0xf bank_mask:0xf
	v_mov_b32_e32 v15, 0
	v_mov_b32_dpp v3, v7 row_ror:8 row_mask:0xf bank_mask:0xf
	v_cndmask_b32_e64 v2, v2, v8, s[6:7]
	v_add_u32_e32 v8, v155, v160
	v_mov_b32_dpp v15, v9 row_ror:8 row_mask:0xf bank_mask:0xf
	v_cndmask_b32_e64 v3, v3, v9, s[6:7]
	v_ashrrev_i32_e32 v9, 31, v8
	v_mov_b32_e32 v0, 0
	v_mov_b32_e32 v1, 0
	v_lshlrev_b64 v[8:9], 14, v[8:9]
	v_mov_b32_dpp v0, v4 row_ror:8 row_mask:0xf bank_mask:0xf
	v_mov_b32_dpp v1, v5 row_ror:8 row_mask:0xf bank_mask:0xf
	v_lshl_add_u64 v[8:9], s[10:11], 0, v[8:9]
	v_cndmask_b32_e64 v0, v0, v12, s[6:7]
	v_cndmask_b32_e64 v1, v1, v13, s[6:7]
	v_lshl_add_u64 v[8:9], v[8:9], 0, v[112:113]
	v_mov_b32_e32 v10, 0
	v_mov_b32_e32 v11, 0
	global_store_dwordx4 v[8:9], v[0:3], off
	v_mov_b32_dpp v10, v12 row_ror:8 row_mask:0xf bank_mask:0xf
	v_mov_b32_dpp v11, v13 row_ror:8 row_mask:0xf bank_mask:0xf
	v_add_co_u32_e32 v0, vcc, 0x20000, v8
	v_cndmask_b32_e64 v4, v4, v10, s[6:7]
	s_nop 0
	v_addc_co_u32_e32 v1, vcc, 0, v9, vcc
	v_cndmask_b32_e64 v5, v5, v11, s[6:7]
	v_cndmask_b32_e64 v6, v6, v14, s[6:7]
	v_cndmask_b32_e64 v7, v7, v15, s[6:7]
	s_and_b64 vcc, exec, s[40:41]
	s_mov_b32 s69, s18
	s_mov_b32 s44, s36
	s_mov_b64 s[48:49], s[42:43]
	s_mov_b64 s[46:47], s[38:39]
	global_store_dwordx4 v[0:1], v[4:7], off
	s_cbranch_vccz .LBB0_725
	s_waitcnt vmcnt(0)
	s_cmpk_gt_u32 s52, 0xff
	s_cbranch_scc1 .LBB0_737
	s_barrier

; #define PG8_STAGE(bufoff, gbase, voff) do { _Pragma("unroll") for (int _i = 0; _i < 2; ++_i) \
;         __builtin_amdgcn_global_load_lds((const unsigned*)((const char*)(gbase) + (voff)[_i]), (LAS unsigned*)(lds + (bufoff) + ldsw + _i * 8192), 16, 0, 0); } while (0)
; #define PG8_LDA(dst, b, h) do { _Pragma("unroll") for (int m = 0; m < 4; ++m) _Pragma("unroll") for (int k = 0; k < 2; ++k) dst[m][k] = *(const LAS bf16x8*)(lds + PG8_SA(b, h) + aoff + m * 2048 + k * 1024); } while (0)
; #define PG8_LDB(dst, b, h) do { _Pragma("unroll") for (int n = 0; n < 2; ++n) _Pragma("unroll") for (int k = 0; k < 2; ++k) dst[n][k] = *(const LAS bf16x8*)(lds + PG8_SB(b, h) + boff + n * 2048 + k * 1024); } while (0)
; #define PG8_MMA(ai, bj, At, Bt) do { __builtin_amdgcn_s_setprio(1); _Pragma("unroll") for (int m = 0; m < 4; ++m) _Pragma("unroll") for (int n = 0; n < 2; ++n) _Pragma("unroll") for (int k = 0; k < 2; ++k) \
;         acc[ai][bj][m][n] = __builtin_amdgcn_mfma_f32_16x16x32_bf16(Bt[n][k], At[m][k], acc[ai][bj][m][n], 0, 0, 0); __builtin_amdgcn_s_setprio(0); } while (0)
; #define PG8_WAIT_L(n) asm volatile("s_waitcnt lgkmcnt(" #n ")" ::: "memory")
; #define PG8_BAR __builtin_amdgcn_s_barrier()
; template <class Epi>
; __device__ __forceinline__ void gemm_phase(LAS unsigned char* lds, const Gemm g, const StaticOrder& S, const Epi& E) {
;     ...
;         const char* nA = has_next ? (const char*)g.A + (size_t)nxt.pm * tstep : cA; const char* nB = has_next ? (const char*)g.Bt + (size_t)nxt.pn * tstep : cB;
;         for (int t = 0; t < nt; t += 2) {
;             const bool last = (t == nt - 2);
;             const char* a1 = cA + (size_t)(t + 1) * kstep;
;             const char* a2 = last ? nA : cA + (size_t)(t + 2) * kstep; const char* b2 = last ? nB : cB + (size_t)(t + 2) * kstep;
;             const char* a3 = a2 + kstep; const char* b3 = b2 + kstep;
;             PG8_LDB(B0, 0, 0); PG8_SCHED; PG8_LDA(At, 0, 0); PG8_STAGE(PG8_SA(1, 1), a1 + hstep, voffA);
;             PG8_WAIT_L(8); PG8_BAR; PG8_WAIT_L(0); PG8_MMA(0, 0, At, B0); PG8_BAR; PG8_SCHED;
;             PG8_LDB(B1, 0, 1); PG8_STAGE(PG8_SB(0, 0), b2, voffB0);
;             PG8_BAR; PG8_WAIT_L(0); PG8_MMA(0, 1, At, B1); PG8_BAR;
;             PG8_LDA(At, 0, 1); PG8_STAGE(PG8_SA(0, 0), a2, voffA);
;             PG8_BAR; PG8_WAIT_L(0); PG8_MMA(1, 0, At, B0); PG8_BAR; PG8_SCHED;
.LBB0_806:
	ds_read_b128 v[146:149], v156
	ds_read_b128 v[160:163], v156 offset:1024
	ds_read_b128 v[164:167], v156 offset:2048
	ds_read_b128 v[168:171], v156 offset:3072
	s_add_u32 s33, s50, 0xffe00080
	s_addc_u32 s52, s51, -1
	s_cmpk_eq_i32 s80, 0x7c
	s_cselect_b32 s53, s41, s52
	s_cselect_b32 s52, s75, s33
	s_cselect_b32 s55, s39, s79
	s_cselect_b32 s54, s77, s78
	v_lshl_add_u64 v[150:151], s[50:51], 0, v[140:141]
	s_add_i32 m0, s49, 0xc000
	ds_read_b128 v[172:175], v157
	ds_read_b128 v[176:179], v157 offset:1024
	ds_read_b128 v[180:183], v157 offset:2048
	ds_read_b128 v[184:187], v157 offset:3072
	ds_read_b128 v[188:191], v157 offset:4096
	ds_read_b128 v[192:195], v157 offset:5120
	ds_read_b128 v[196:199], v157 offset:6144
	ds_read_b128 v[204:207], v157 offset:7168
	global_load_lds_dwordx4 v[150:151], off
	v_lshl_add_u64 v[150:151], s[50:51], 0, v[142:143]
	s_add_i32 m0, s49, 0xe000
	s_nop 0
	global_load_lds_dwordx4 v[150:151], off
	s_waitcnt lgkmcnt(8)
	s_barrier
	s_waitcnt lgkmcnt(0)
	s_waitcnt lgkmcnt(0)
	v_mfma_f32_16x16x32_bf16 v[124:127], v[146:149], v[172:175], v[124:127]
	v_mfma_f32_16x16x32_bf16 v[120:123], v[164:167], v[172:175], v[120:123]
	v_mfma_f32_16x16x32_bf16 v[108:111], v[146:149], v[180:183], v[108:111]
	v_mfma_f32_16x16x32_bf16 v[104:107], v[164:167], v[180:183], v[104:107]
	v_mfma_f32_16x16x32_bf16 v[92:95], v[146:149], v[188:191], v[92:95]
	v_mfma_f32_16x16x32_bf16 v[88:91], v[164:167], v[188:191], v[88:91]
	v_mfma_f32_16x16x32_bf16 v[76:79], v[146:149], v[196:199], v[76:79]
	v_mfma_f32_16x16x32_bf16 v[72:75], v[164:167], v[196:199], v[72:75]
	v_mfma_f32_16x16x32_bf16 v[124:127], v[160:163], v[176:179], v[124:127]
	v_mfma_f32_16x16x32_bf16 v[120:123], v[168:171], v[176:179], v[120:123]
	v_mfma_f32_16x16x32_bf16 v[108:111], v[160:163], v[184:187], v[108:111]
	v_mfma_f32_16x16x32_bf16 v[104:107], v[168:171], v[184:187], v[104:107]
	v_mfma_f32_16x16x32_bf16 v[92:95], v[160:163], v[192:195], v[92:95]
	v_mfma_f32_16x16x32_bf16 v[88:91], v[168:171], v[192:195], v[88:91]
	v_mfma_f32_16x16x32_bf16 v[76:79], v[160:163], v[204:207], v[76:79]
	v_mfma_f32_16x16x32_bf16 v[72:75], v[168:171], v[204:207], v[72:75]
	s_barrier
	s_add_i32 s33, s72, s62
	v_lshl_add_u64 v[150:151], s[54:55], 0, v[130:131]
	s_mov_b32 m0, s33
	ds_read_b128 v[208:211], v158
	ds_read_b128 v[212:215], v158 offset:1024
	ds_read_b128 v[216:219], v158 offset:2048
	ds_read_b128 v[220:223], v158 offset:3072
	global_load_lds_dwordx4 v[150:151], off
	v_lshl_add_u64 v[200:201], s[54:55], 0, v[136:137]
	s_add_i32 m0, s33, 0x2000
	s_nop 0
	global_load_lds_dwordx4 v[200:201], off
	s_barrier
	s_waitcnt lgkmcnt(0)
	s_waitcnt lgkmcnt(0)
	v_mfma_f32_16x16x32_bf16 v[116:119], v[208:211], v[172:175], v[116:119]
	v_mfma_f32_16x16x32_bf16 v[112:115], v[216:219], v[172:175], v[112:115]
	v_mfma_f32_16x16x32_bf16 v[100:103], v[208:211], v[180:183], v[100:103]
	v_mfma_f32_16x16x32_bf16 v[96:99], v[216:219], v[180:183], v[96:99]
	v_mfma_f32_16x16x32_bf16 v[84:87], v[208:211], v[188:191], v[84:87]
	v_mfma_f32_16x16x32_bf16 v[80:83], v[216:219], v[188:191], v[80:83]
	v_mfma_f32_16x16x32_bf16 v[68:71], v[208:211], v[196:199], v[68:71]
	v_mfma_f32_16x16x32_bf16 v[64:67], v[216:219], v[196:199], v[64:67]
	v_mfma_f32_16x16x32_bf16 v[116:119], v[212:215], v[176:179], v[116:119]
	v_mfma_f32_16x16x32_bf16 v[112:115], v[220:223], v[176:179], v[112:115]
	v_mfma_f32_16x16x32_bf16 v[100:103], v[212:215], v[184:187], v[100:103]
	v_mfma_f32_16x16x32_bf16 v[96:99], v[220:223], v[184:187], v[96:99]
	v_mfma_f32_16x16x32_bf16 v[84:87], v[212:215], v[192:195], v[84:87]
	v_mfma_f32_16x16x32_bf16 v[80:83], v[220:223], v[192:195], v[80:83]
	v_mfma_f32_16x16x32_bf16 v[68:71], v[212:215], v[204:207], v[68:71]
	v_mfma_f32_16x16x32_bf16 v[64:67], v[220:223], v[204:207], v[64:67]
	s_mov_b32 m0, s49
	v_lshl_add_u64 v[224:225], s[52:53], 0, v[128:129]
	s_barrier
	ds_read_b128 v[172:175], v157 offset:16384
	ds_read_b128 v[176:179], v157 offset:17408
	ds_read_b128 v[180:183], v157 offset:18432
	ds_read_b128 v[184:187], v157 offset:19456
	ds_read_b128 v[188:191], v157 offset:20480
	ds_read_b128 v[192:195], v157 offset:21504
	ds_read_b128 v[196:199], v157 offset:22528
	ds_read_b128 v[204:207], v157 offset:23552
	global_load_lds_dwordx4 v[224:225], off
	v_lshl_add_u64 v[226:227], s[52:53], 0, v[134:135]
	s_mov_b32 m0, s63
	s_nop 0
	global_load_lds_dwordx4 v[226:227], off
	s_barrier
	s_waitcnt lgkmcnt(0)
	s_waitcnt lgkmcnt(0)
	v_mfma_f32_16x16x32_bf16 v[60:63], v[146:149], v[172:175], v[60:63]
	v_mfma_f32_16x16x32_bf16 v[56:59], v[164:167], v[172:175], v[56:59]
	v_mfma_f32_16x16x32_bf16 v[44:47], v[146:149], v[180:183], v[44:47]
	v_mfma_f32_16x16x32_bf16 v[40:43], v[164:167], v[180:183], v[40:43]
	v_mfma_f32_16x16x32_bf16 v[28:31], v[146:149], v[188:191], v[28:31]
	v_mfma_f32_16x16x32_bf16 v[24:27], v[164:167], v[188:191], v[24:27]
	v_mfma_f32_16x16x32_bf16 v[12:15], v[146:149], v[196:199], v[12:15]
	v_mfma_f32_16x16x32_bf16 v[8:11], v[164:167], v[196:199], v[8:11]
	v_mfma_f32_16x16x32_bf16 v[60:63], v[160:163], v[176:179], v[60:63]
	v_mfma_f32_16x16x32_bf16 v[56:59], v[168:171], v[176:179], v[56:59]
	v_mfma_f32_16x16x32_bf16 v[44:47], v[160:163], v[184:187], v[44:47]
	v_mfma_f32_16x16x32_bf16 v[40:43], v[168:171], v[184:187], v[40:43]
	v_mfma_f32_16x16x32_bf16 v[28:31], v[160:163], v[192:195], v[28:31]
	v_mfma_f32_16x16x32_bf16 v[24:27], v[168:171], v[192:195], v[24:27]
	v_mfma_f32_16x16x32_bf16 v[12:15], v[160:163], v[204:207], v[12:15]
	v_mfma_f32_16x16x32_bf16 v[8:11], v[168:171], v[204:207], v[8:11]
	s_barrier
; #define PG8_STAGE(bufoff, gbase, voff) do { _Pragma("unroll") for (int _i = 0; _i < 2; ++_i) \
;         __builtin_amdgcn_global_load_lds((const unsigned*)((const char*)(gbase) + (voff)[_i]), (LAS unsigned*)(lds + (bufoff) + ldsw + _i * 8192), 16, 0, 0); } while (0)
; #define PG8_LDA(dst, b, h) do { _Pragma("unroll") for (int m = 0; m < 4; ++m) _Pragma("unroll") for (int k = 0; k < 2; ++k) dst[m][k] = *(const LAS bf16x8*)(lds + PG8_SA(b, h) + aoff + m * 2048 + k * 1024); } while (0)
; #define PG8_LDB(dst, b, h) do { _Pragma("unroll") for (int n = 0; n < 2; ++n) _Pragma("unroll") for (int k = 0; k < 2; ++k) dst[n][k] = *(const LAS bf16x8*)(lds + PG8_SB(b, h) + boff + n * 2048 + k * 1024); } while (0)
; #define PG8_MMA(ai, bj, At, Bt) do { __builtin_amdgcn_s_setprio(1); _Pragma("unroll") for (int m = 0; m < 4; ++m) _Pragma("unroll") for (int n = 0; n < 2; ++n) _Pragma("unroll") for (int k = 0; k < 2; ++k) \
;         acc[ai][bj][m][n] = __builtin_amdgcn_mfma_f32_16x16x32_bf16(Bt[n][k], At[m][k], acc[ai][bj][m][n], 0, 0, 0); __builtin_amdgcn_s_setprio(0); } while (0)
; #define PG8_WAIT_V(n) asm volatile("s_waitcnt vmcnt(" #n ")" ::: "memory")
; #define PG8_WAIT_L(n) asm volatile("s_waitcnt lgkmcnt(" #n ")" ::: "memory")
; #define PG8_BAR __builtin_amdgcn_s_barrier()
; #define PG8_SCHED __builtin_amdgcn_sched_barrier(0)
; template <class Epi>
; __device__ __forceinline__ void gemm_phase(LAS unsigned char* lds, const Gemm g, const StaticOrder& S, const Epi& E) {
;     ...
;             PG8_STAGE(PG8_SB(0, 1), b2, voffB1);
;             PG8_WAIT_V(6); PG8_BAR; PG8_MMA(1, 1, At, B1); PG8_BAR;
;             PG8_LDB(B0, 1, 0); PG8_SCHED; PG8_LDA(At, 1, 0); PG8_STAGE(PG8_SA(0, 1), a2 + hstep, voffA);
;             PG8_WAIT_L(8); PG8_BAR; PG8_WAIT_L(0); PG8_MMA(0, 0, At, B0); PG8_BAR; PG8_SCHED;
;             PG8_LDB(B1, 1, 1); PG8_STAGE(PG8_SB(1, 0), b3, voffB0);
;             PG8_BAR; PG8_WAIT_L(0); PG8_MMA(0, 1, At, B1); PG8_BAR;
;             PG8_LDA(At, 1, 1); PG8_STAGE(PG8_SA(1, 0), a3, voffA);
;             PG8_BAR; PG8_WAIT_L(0); PG8_MMA(1, 0, At, B0); PG8_BAR; PG8_SCHED;
	s_add_i32 s33, s73, s62
	v_lshl_add_u64 v[228:229], s[54:55], 0, v[132:133]
	s_mov_b32 m0, s33
	v_lshl_add_u64 v[230:231], s[54:55], 0, v[138:139]
	global_load_lds_dwordx4 v[228:229], off
	s_add_i32 m0, s33, 0x2000
	s_nop 0
	global_load_lds_dwordx4 v[230:231], off
	s_waitcnt vmcnt(6)
	s_barrier
	v_mfma_f32_16x16x32_bf16 v[52:55], v[208:211], v[172:175], v[52:55]
	v_mfma_f32_16x16x32_bf16 v[48:51], v[216:219], v[172:175], v[48:51]
	v_mfma_f32_16x16x32_bf16 v[36:39], v[208:211], v[180:183], v[36:39]
	v_mfma_f32_16x16x32_bf16 v[32:35], v[216:219], v[180:183], v[32:35]
	v_mfma_f32_16x16x32_bf16 v[20:23], v[208:211], v[188:191], v[20:23]
	v_mfma_f32_16x16x32_bf16 v[16:19], v[216:219], v[188:191], v[16:19]
	v_mfma_f32_16x16x32_bf16 v[4:7], v[208:211], v[196:199], v[4:7]
	v_mfma_f32_16x16x32_bf16 v[0:3], v[216:219], v[196:199], v[0:3]
	v_mfma_f32_16x16x32_bf16 v[52:55], v[212:215], v[176:179], v[52:55]
	v_mfma_f32_16x16x32_bf16 v[48:51], v[220:223], v[176:179], v[48:51]
	v_mfma_f32_16x16x32_bf16 v[36:39], v[212:215], v[184:187], v[36:39]
	v_mfma_f32_16x16x32_bf16 v[32:35], v[220:223], v[184:187], v[32:35]
	v_mfma_f32_16x16x32_bf16 v[20:23], v[212:215], v[192:195], v[20:23]
	v_mfma_f32_16x16x32_bf16 v[16:19], v[220:223], v[192:195], v[16:19]
	v_mfma_f32_16x16x32_bf16 v[4:7], v[212:215], v[204:207], v[4:7]
	v_mfma_f32_16x16x32_bf16 v[0:3], v[220:223], v[204:207], v[0:3]
	s_add_i32 s33, 0, 0x18000
	v_add_u32_e32 v168, s33, v153
	s_barrier
	ds_read_b128 v[146:149], v168
	ds_read_b128 v[160:163], v168 offset:1024
	ds_read_b128 v[164:167], v168 offset:2048
	ds_read_b128 v[168:171], v168 offset:3072
	s_add_u32 s52, s52, 0x200000
	s_addc_u32 s53, s53, 0
	s_mov_b32 m0, s64
	v_lshl_add_u64 v[208:209], s[52:53], 0, v[128:129]
	ds_read_b128 v[172:175], v157 offset:32768
	ds_read_b128 v[176:179], v157 offset:33792
	ds_read_b128 v[180:183], v157 offset:34816
	ds_read_b128 v[184:187], v157 offset:35840
	ds_read_b128 v[188:191], v157 offset:36864
	ds_read_b128 v[192:195], v157 offset:37888
	ds_read_b128 v[196:199], v157 offset:38912
	ds_read_b128 v[204:207], v157 offset:39936
	global_load_lds_dwordx4 v[208:209], off
	v_lshl_add_u64 v[208:209], s[52:53], 0, v[134:135]
	s_mov_b32 m0, s65
	s_nop 0
	global_load_lds_dwordx4 v[208:209], off
	s_waitcnt lgkmcnt(8)
	s_barrier
	s_waitcnt lgkmcnt(0)
	s_waitcnt lgkmcnt(0)
	v_mfma_f32_16x16x32_bf16 v[124:127], v[146:149], v[172:175], v[124:127]
	v_mfma_f32_16x16x32_bf16 v[120:123], v[164:167], v[172:175], v[120:123]
	v_mfma_f32_16x16x32_bf16 v[108:111], v[146:149], v[180:183], v[108:111]
	v_mfma_f32_16x16x32_bf16 v[104:107], v[164:167], v[180:183], v[104:107]
	v_mfma_f32_16x16x32_bf16 v[92:95], v[146:149], v[188:191], v[92:95]
	v_mfma_f32_16x16x32_bf16 v[88:91], v[164:167], v[188:191], v[88:91]
	v_mfma_f32_16x16x32_bf16 v[76:79], v[146:149], v[196:199], v[76:79]
	v_mfma_f32_16x16x32_bf16 v[72:75], v[164:167], v[196:199], v[72:75]
	v_mfma_f32_16x16x32_bf16 v[124:127], v[160:163], v[176:179], v[124:127]
	v_mfma_f32_16x16x32_bf16 v[120:123], v[168:171], v[176:179], v[120:123]
	v_mfma_f32_16x16x32_bf16 v[108:111], v[160:163], v[184:187], v[108:111]
	v_mfma_f32_16x16x32_bf16 v[104:107], v[168:171], v[184:187], v[104:107]
	v_mfma_f32_16x16x32_bf16 v[92:95], v[160:163], v[192:195], v[92:95]
	v_mfma_f32_16x16x32_bf16 v[88:91], v[168:171], v[192:195], v[88:91]
	v_mfma_f32_16x16x32_bf16 v[76:79], v[160:163], v[204:207], v[76:79]
	v_mfma_f32_16x16x32_bf16 v[72:75], v[168:171], v[204:207], v[72:75]
	s_barrier
	s_add_i32 s52, 0, 0x1c000
	s_add_i32 s33, s33, s62
	v_add_u32_e32 v220, s52, v153
	v_lshl_add_u64 v[150:151], v[150:151], 0, s[18:19]
	s_mov_b32 m0, s33
	ds_read_b128 v[208:211], v220
	ds_read_b128 v[212:215], v220 offset:1024
	ds_read_b128 v[216:219], v220 offset:2048
	ds_read_b128 v[220:223], v220 offset:3072
	global_load_lds_dwordx4 v[150:151], off
	v_lshl_add_u64 v[150:151], v[200:201], 0, s[18:19]
	s_add_i32 m0, s33, 0x2000
	s_nop 0
	global_load_lds_dwordx4 v[150:151], off
	s_barrier
	s_waitcnt lgkmcnt(0)
	s_waitcnt lgkmcnt(0)
	v_mfma_f32_16x16x32_bf16 v[116:119], v[208:211], v[172:175], v[116:119]
	v_mfma_f32_16x16x32_bf16 v[112:115], v[216:219], v[172:175], v[112:115]
	v_mfma_f32_16x16x32_bf16 v[100:103], v[208:211], v[180:183], v[100:103]
	v_mfma_f32_16x16x32_bf16 v[96:99], v[216:219], v[180:183], v[96:99]
	v_mfma_f32_16x16x32_bf16 v[84:87], v[208:211], v[188:191], v[84:87]
	v_mfma_f32_16x16x32_bf16 v[80:83], v[216:219], v[188:191], v[80:83]
	v_mfma_f32_16x16x32_bf16 v[68:71], v[208:211], v[196:199], v[68:71]
	v_mfma_f32_16x16x32_bf16 v[64:67], v[216:219], v[196:199], v[64:67]
	v_mfma_f32_16x16x32_bf16 v[116:119], v[212:215], v[176:179], v[116:119]
	v_mfma_f32_16x16x32_bf16 v[112:115], v[220:223], v[176:179], v[112:115]
	v_mfma_f32_16x16x32_bf16 v[100:103], v[212:215], v[184:187], v[100:103]
	v_mfma_f32_16x16x32_bf16 v[96:99], v[220:223], v[184:187], v[96:99]
	v_mfma_f32_16x16x32_bf16 v[84:87], v[212:215], v[192:195], v[84:87]
	v_mfma_f32_16x16x32_bf16 v[80:83], v[220:223], v[192:195], v[80:83]
	v_mfma_f32_16x16x32_bf16 v[68:71], v[212:215], v[204:207], v[68:71]
	v_mfma_f32_16x16x32_bf16 v[64:67], v[220:223], v[204:207], v[64:67]
	s_mov_b32 m0, s67
	v_lshl_add_u64 v[150:151], v[224:225], 0, s[18:19]
	s_barrier
	ds_read_b128 v[172:175], v157 offset:49152
	ds_read_b128 v[176:179], v157 offset:50176
	ds_read_b128 v[180:183], v157 offset:51200
	ds_read_b128 v[184:187], v157 offset:52224
	ds_read_b128 v[188:191], v157 offset:53248
	ds_read_b128 v[192:195], v157 offset:54272
	ds_read_b128 v[196:199], v157 offset:55296
	ds_read_b128 v[204:207], v157 offset:56320
	global_load_lds_dwordx4 v[150:151], off
	v_lshl_add_u64 v[150:151], v[226:227], 0, s[18:19]
	s_mov_b32 m0, s68
	s_nop 0
	global_load_lds_dwordx4 v[150:151], off
	s_barrier
; #define PG8_STAGE(bufoff, gbase, voff) do { _Pragma("unroll") for (int _i = 0; _i < 2; ++_i) \
;         __builtin_amdgcn_global_load_lds((const unsigned*)((const char*)(gbase) + (voff)[_i]), (LAS unsigned*)(lds + (bufoff) + ldsw + _i * 8192), 16, 0, 0); } while (0)
; #define PG8_LDA(dst, b, h) do { _Pragma("unroll") for (int m = 0; m < 4; ++m) _Pragma("unroll") for (int k = 0; k < 2; ++k) dst[m][k] = *(const LAS bf16x8*)(lds + PG8_SA(b, h) + aoff + m * 2048 + k * 1024); } while (0)
; #define PG8_LDB(dst, b, h) do { _Pragma("unroll") for (int n = 0; n < 2; ++n) _Pragma("unroll") for (int k = 0; k < 2; ++k) dst[n][k] = *(const LAS bf16x8*)(lds + PG8_SB(b, h) + boff + n * 2048 + k * 1024); } while (0)
; #define PG8_MMA(ai, bj, At, Bt) do { __builtin_amdgcn_s_setprio(1); _Pragma("unroll") for (int m = 0; m < 4; ++m) _Pragma("unroll") for (int n = 0; n < 2; ++n) _Pragma("unroll") for (int k = 0; k < 2; ++k) \
;         acc[ai][bj][m][n] = __builtin_amdgcn_mfma_f32_16x16x32_bf16(Bt[n][k], At[m][k], acc[ai][bj][m][n], 0, 0, 0); __builtin_amdgcn_s_setprio(0); } while (0)
;     __device__ __forceinline__ void operator()(const f32x4 (&acc)[2][2][4][2], const Unit& u, int wr, int wc, int fr, int fq) const {
;     ...
;             for (int m = 0; m < 4; ++m) { const int row = row0 + ai * HALF + m * 16; const size_t off = (size_t)row * D + col0; float sq = 0.f; u32x4 w[2];
;                 const float sc = rsin ? __builtin_amdgcn_rcpf(rsin[row] * (1.f / D) + EPS) : 1.0f;
;                 u32x4 rr[2]; if (R) load_pair_lines(R, D, row, fr, col0, rr[0], rr[1]);
; template <class Epi>
; __device__ __forceinline__ void gemm_phase(LAS unsigned char* lds, const Gemm g, const StaticOrder& S, const Epi& E) {
;     ...
;             PG8_WAIT_V(6); PG8_BAR; PG8_MMA(1, 1, At, B1); PG8_BAR;
;             PG8_LDB(B0, 1, 0); PG8_SCHED; PG8_LDA(At, 1, 0); PG8_STAGE(PG8_SA(0, 1), a2 + hstep, voffA);
;             PG8_WAIT_L(8); PG8_BAR; PG8_WAIT_L(0); PG8_MMA(0, 0, At, B0); PG8_BAR; PG8_SCHED;
;             PG8_LDB(B1, 1, 1); PG8_STAGE(PG8_SB(1, 0), b3, voffB0);
;             PG8_BAR; PG8_WAIT_L(0); PG8_MMA(0, 1, At, B1); PG8_BAR;
;             PG8_LDA(At, 1, 1); PG8_STAGE(PG8_SA(1, 0), a3, voffA);
;             PG8_BAR; PG8_WAIT_L(0); PG8_MMA(1, 0, At, B0); PG8_BAR; PG8_SCHED;
;             PG8_STAGE(PG8_SB(1, 1), b3, voffB1);
;             PG8_WAIT_V(6); PG8_BAR; PG8_MMA(1, 1, At, B1); PG8_BAR;
	s_waitcnt lgkmcnt(0)
	s_waitcnt lgkmcnt(0)
	v_mfma_f32_16x16x32_bf16 v[60:63], v[146:149], v[172:175], v[60:63]
	v_mfma_f32_16x16x32_bf16 v[56:59], v[164:167], v[172:175], v[56:59]
	v_mfma_f32_16x16x32_bf16 v[44:47], v[146:149], v[180:183], v[44:47]
	v_mfma_f32_16x16x32_bf16 v[40:43], v[164:167], v[180:183], v[40:43]
	v_mfma_f32_16x16x32_bf16 v[28:31], v[146:149], v[188:191], v[28:31]
	v_mfma_f32_16x16x32_bf16 v[24:27], v[164:167], v[188:191], v[24:27]
	v_mfma_f32_16x16x32_bf16 v[12:15], v[146:149], v[196:199], v[12:15]
	v_mfma_f32_16x16x32_bf16 v[8:11], v[164:167], v[196:199], v[8:11]
	v_mfma_f32_16x16x32_bf16 v[60:63], v[160:163], v[176:179], v[60:63]
	v_mfma_f32_16x16x32_bf16 v[56:59], v[168:171], v[176:179], v[56:59]
	v_mfma_f32_16x16x32_bf16 v[44:47], v[160:163], v[184:187], v[44:47]
	v_mfma_f32_16x16x32_bf16 v[40:43], v[168:171], v[184:187], v[40:43]
	v_mfma_f32_16x16x32_bf16 v[28:31], v[160:163], v[192:195], v[28:31]
	v_mfma_f32_16x16x32_bf16 v[24:27], v[168:171], v[192:195], v[24:27]
	v_mfma_f32_16x16x32_bf16 v[12:15], v[160:163], v[204:207], v[12:15]
	v_mfma_f32_16x16x32_bf16 v[8:11], v[168:171], v[204:207], v[8:11]
	s_barrier
	s_add_i32 s33, s52, s62
	v_lshl_add_u64 v[146:147], v[228:229], 0, s[18:19]
	s_mov_b32 m0, s33
	s_nop 0
	global_load_lds_dwordx4 v[146:147], off
	v_lshl_add_u64 v[146:147], v[230:231], 0, s[18:19]
	s_add_i32 m0, s33, 0x2000
	s_nop 0
	global_load_lds_dwordx4 v[146:147], off
	s_waitcnt vmcnt(6)
	s_barrier
	v_mfma_f32_16x16x32_bf16 v[52:55], v[208:211], v[172:175], v[52:55]
	v_mfma_f32_16x16x32_bf16 v[48:51], v[216:219], v[172:175], v[48:51]
	v_mfma_f32_16x16x32_bf16 v[36:39], v[208:211], v[180:183], v[36:39]
	v_mfma_f32_16x16x32_bf16 v[32:35], v[216:219], v[180:183], v[32:35]
	v_mfma_f32_16x16x32_bf16 v[20:23], v[208:211], v[188:191], v[20:23]
	v_mfma_f32_16x16x32_bf16 v[16:19], v[216:219], v[188:191], v[16:19]
	v_mfma_f32_16x16x32_bf16 v[4:7], v[208:211], v[196:199], v[4:7]
	v_mfma_f32_16x16x32_bf16 v[0:3], v[216:219], v[196:199], v[0:3]
	v_mfma_f32_16x16x32_bf16 v[52:55], v[212:215], v[176:179], v[52:55]
	v_mfma_f32_16x16x32_bf16 v[48:51], v[220:223], v[176:179], v[48:51]
	v_mfma_f32_16x16x32_bf16 v[36:39], v[212:215], v[184:187], v[36:39]
	v_mfma_f32_16x16x32_bf16 v[32:35], v[220:223], v[184:187], v[32:35]
	v_mfma_f32_16x16x32_bf16 v[20:23], v[212:215], v[192:195], v[20:23]
	v_mfma_f32_16x16x32_bf16 v[16:19], v[220:223], v[192:195], v[16:19]
	v_mfma_f32_16x16x32_bf16 v[4:7], v[212:215], v[204:207], v[4:7]
	v_mfma_f32_16x16x32_bf16 v[0:3], v[220:223], v[204:207], v[0:3]
	s_add_i32 s80, s80, 2
	s_add_u32 s50, s50, 0x100
	s_addc_u32 s51, s51, 0
	s_add_u32 s78, s78, 0x100
	s_addc_u32 s79, s79, 0
	s_cmpk_gt_u32 s80, 0x7d
	s_barrier
	s_cbranch_scc0 .LBB0_806
	s_lshl_b32 s33, s48, 8
	s_add_i32 s33, s33, s69
	v_or_b32_e32 v164, s33, v154
	v_ashrrev_i32_e32 v165, 31, v164
	v_lshl_or_b32 v146, s74, 8, v155
	v_lshlrev_b64 v[168:169], 12, v[164:165]
	v_or_b32_e32 v164, 8, v164
	v_or_b32_e32 v150, s33, v152
	v_ashrrev_i32_e32 v147, 31, v146
	v_ashrrev_i32_e32 v165, 31, v164
	v_ashrrev_i32_e32 v151, 31, v150
	v_lshl_add_u64 v[160:161], s[16:17], 0, v[168:169]
	v_lshlrev_b64 v[146:147], 1, v[146:147]
	v_lshlrev_b64 v[170:171], 12, v[164:165]
	v_lshl_add_u64 v[148:149], v[150:151], 2, s[10:11]
	v_lshl_add_u64 v[160:161], v[160:161], 0, v[146:147]
	v_lshl_add_u64 v[164:165], s[16:17], 0, v[170:171]
	global_load_dword v151, v[148:149], off
	s_nop 0
	global_load_dwordx4 v[160:163], v[160:161], off
	v_lshl_add_u64 v[164:165], v[164:165], 0, v[146:147]
	global_load_dwordx4 v[164:167], v[164:165], off
	v_or_b32_e32 v190, 16, v150
	v_ashrrev_i32_e32 v191, 31, v190
	v_lshl_add_u64 v[192:193], v[190:191], 2, s[10:11]
	v_sub_u32_e32 v190, v190, v152
	v_add_u32_e32 v190, v190, v154
	v_ashrrev_i32_e32 v191, 31, v190
	v_lshlrev_b64 v[196:197], 12, v[190:191]
	v_lshl_add_u64 v[190:191], s[16:17], 0, v[196:197]
	v_lshl_add_u64 v[198:199], v[196:197], 0, s[36:37]
	v_lshl_add_u64 v[190:191], v[190:191], 0, v[146:147]
	v_lshl_add_u64 v[194:195], s[16:17], 0, v[198:199]
	global_load_dword v204, v[192:193], off
	global_load_dwordx4 v[208:211], v[190:191], off
	v_lshl_add_u64 v[194:195], v[194:195], 0, v[146:147]
	global_load_dwordx4 v[212:215], v[194:195], off
	v_or_b32_e32 v190, 32, v150
	v_ashrrev_i32_e32 v191, 31, v190
	v_lshl_add_u64 v[192:193], v[190:191], 2, s[10:11]
	v_sub_u32_e32 v190, v190, v152
	v_add_u32_e32 v190, v190, v154
	v_ashrrev_i32_e32 v191, 31, v190
	v_lshlrev_b64 v[196:197], 12, v[190:191]
	v_lshl_add_u64 v[190:191], s[16:17], 0, v[196:197]
	v_lshl_add_u64 v[198:199], v[196:197], 0, s[36:37]
	v_lshl_add_u64 v[190:191], v[190:191], 0, v[146:147]
	v_lshl_add_u64 v[194:195], s[16:17], 0, v[198:199]
	global_load_dword v205, v[192:193], off
	global_load_dwordx4 v[216:219], v[190:191], off
	v_lshl_add_u64 v[194:195], v[194:195], 0, v[146:147]
	global_load_dwordx4 v[220:223], v[194:195], off
	v_or_b32_e32 v190, 48, v150
	v_ashrrev_i32_e32 v191, 31, v190
	v_lshl_add_u64 v[192:193], v[190:191], 2, s[10:11]
	v_sub_u32_e32 v190, v190, v152
	v_add_u32_e32 v190, v190, v154
	v_ashrrev_i32_e32 v191, 31, v190
	v_lshlrev_b64 v[196:197], 12, v[190:191]
	v_lshl_add_u64 v[190:191], s[16:17], 0, v[196:197]
	v_lshl_add_u64 v[198:199], v[196:197], 0, s[36:37]
	v_lshl_add_u64 v[190:191], v[190:191], 0, v[146:147]
	v_lshl_add_u64 v[194:195], s[16:17], 0, v[198:199]
	global_load_dword v206, v[192:193], off
	global_load_dwordx4 v[224:227], v[190:191], off
	v_lshl_add_u64 v[194:195], v[194:195], 0, v[146:147]
	global_load_dwordx4 v[228:231], v[194:195], off
	v_sub_u32_e32 v190, v150, v152
	v_add_u32_e32 v199, v190, v154
	v_add_u32_e32 v190, 0x80, v199
; __device__ __forceinline__ unsigned cvt_pk_bf16(float lo, float hi) { unsigned r; asm volatile("v_cvt_pk_bf16_f32 %0, %1, %2" : "=v"(r) : "v"(lo), "v"(hi)); return r; }
; __device__ __forceinline__ float bflo(unsigned w) { return __uint_as_float(w << 16); }
; __device__ __forceinline__ float bfhi(unsigned w) { return __uint_as_float(w & 0xffff0000u); }
;     __device__ __forceinline__ void operator()(const f32x4 (&acc)[2][2][4][2], const Unit& u, int wr, int wc, int fr, int fq) const {
;     ...
;             for (int m = 0; m < 4; ++m) { const int row = row0 + ai * HALF + m * 16; const size_t off = (size_t)row * D + col0; float sq = 0.f; u32x4 w[2];
;                 const float sc = rsin ? __builtin_amdgcn_rcpf(rsin[row] * (1.f / D) + EPS) : 1.0f;
;                 u32x4 rr[2]; if (R) load_pair_lines(R, D, row, fr, col0, rr[0], rr[1]);
; #pragma unroll
;                 for (int bj = 0; bj < 2; ++bj) { f32x4 r0, r1;
;                     if (R) { const u32x4 rw = rr[bj]; r0 = (f32x4){bflo(rw.x), bfhi(rw.x), bflo(rw.y), bfhi(rw.y)}; r1 = (f32x4){bflo(rw.z), bfhi(rw.z), bflo(rw.w), bfhi(rw.w)}; }
;                     else { const float* rp = (row < 8192 ? src_p + off : src_s + (off - (size_t)8192 * D)) + 8 * bj; r0 = *(const f32x4*)rp; r1 = *(const f32x4*)(rp + 4); }
;                     const f32x4 o0 = r0 + acc[ai][bj][m][0] * sc, o1 = r1 + acc[ai][bj][m][1] * sc;
;                     sq += (o0[0] * o0[0] + o0[1] * o0[1]) + (o0[2] * o0[2] + o0[3] * o0[3]) + (o1[0] * o1[0] + o1[1] * o1[1]) + (o1[2] * o1[2] + o1[3] * o1[3]);
;                     w[bj].x = cvt_pk_bf16(o0[0], o0[1]); w[bj].y = cvt_pk_bf16(o0[2], o0[3]); w[bj].z = cvt_pk_bf16(o1[0], o1[1]); w[bj].w = cvt_pk_bf16(o1[2], o1[3]); }
;                 store_pair_lines(O, D, row, fr, col0, w[0], w[1]);
	v_ashrrev_i32_e32 v191, 31, v190
	v_lshlrev_b64 v[194:195], 12, v[190:191]
	v_lshl_add_u64 v[190:191], s[16:17], 0, v[194:195]
	v_lshl_add_u64 v[196:197], v[194:195], 0, s[36:37]
	v_lshl_add_u64 v[190:191], v[190:191], 0, v[146:147]
	v_lshl_add_u64 v[192:193], s[16:17], 0, v[196:197]
	global_load_dword v207, v[148:149], off offset:512
	global_load_dwordx4 v[232:235], v[190:191], off
	v_lshl_add_u64 v[192:193], v[192:193], 0, v[146:147]
	global_load_dwordx4 v[236:239], v[192:193], off
	v_sub_u32_e32 v198, v150, v152
	v_add_u32_e32 v201, v198, v154
	v_add_u32_e32 v190, 0x90, v201
	v_ashrrev_i32_e32 v191, 31, v190
	v_lshlrev_b64 v[194:195], 12, v[190:191]
	v_lshl_add_u64 v[190:191], s[16:17], 0, v[194:195]
	v_lshl_add_u64 v[196:197], v[194:195], 0, s[36:37]
	v_lshl_add_u64 v[190:191], v[190:191], 0, v[146:147]
	v_lshl_add_u64 v[192:193], s[16:17], 0, v[196:197]
	global_load_dword v240, v[148:149], off offset:576
	global_load_dwordx4 v[244:247], v[190:191], off
	v_lshl_add_u64 v[192:193], v[192:193], 0, v[146:147]
	global_load_dwordx4 v[248:251], v[192:193], off
	v_mov_b32_e32 v173, 0
	v_mov_b32_e32 v174, 0
	v_mov_b32_e32 v175, 0
	v_mov_b32_e32 v177, 0
	v_mov_b32_e32 v178, 0
	v_mov_b32_e32 v179, 0
	v_mov_b32_e32 v176, 0
	v_mov_b32_e32 v180, 0
	v_mov_b32_e32 v188, 0
	v_mov_b32_e32 v189, 0
	v_mov_b32_e32 v184, 0
	v_mov_b32_e32 v185, 0
	v_mov_b32_e32 v186, 0
	v_mov_b32_e32 v187, 0
	v_mov_b32_e32 v182, 0
	v_mov_b32_e32 v183, 0
	s_and_b64 vcc, exec, s[44:45]
	s_mov_b32 s74, s38
	s_mov_b32 s48, s40
	s_mov_b64 s[52:53], s[46:47]
	s_mov_b64 s[50:51], s[42:43]
	s_waitcnt vmcnt(15)
	v_fmamk_f32 v151, v151, 0x3a000000, v159
	v_rcp_f32_e32 v172, v151
	v_mov_b32_dpp v173, v160 row_ror:8 row_mask:0xf bank_mask:0xf
	v_mov_b32_dpp v174, v161 row_ror:8 row_mask:0xf bank_mask:0xf
	v_mov_b32_dpp v175, v162 row_ror:8 row_mask:0xf bank_mask:0xf
	v_mov_b32_dpp v177, v164 row_ror:8 row_mask:0xf bank_mask:0xf
	v_mov_b32_dpp v178, v165 row_ror:8 row_mask:0xf bank_mask:0xf
	v_mov_b32_dpp v179, v166 row_ror:8 row_mask:0xf bank_mask:0xf
	v_mov_b32_dpp v176, v163 row_ror:8 row_mask:0xf bank_mask:0xf
	v_mov_b32_dpp v180, v167 row_ror:8 row_mask:0xf bank_mask:0xf
	v_cndmask_b32_e64 v166, v166, v175, s[6:7]
	v_cndmask_b32_e64 v165, v165, v174, s[6:7]
	v_cndmask_b32_e64 v164, v164, v173, s[6:7]
	v_cndmask_b32_e64 v179, v179, v162, s[6:7]
	v_cndmask_b32_e64 v178, v178, v161, s[6:7]
	v_cndmask_b32_e64 v175, v177, v160, s[6:7]
	v_cndmask_b32_e64 v151, v167, v176, s[6:7]
	v_cndmask_b32_e64 v173, v180, v163, s[6:7]
	v_lshlrev_b32_e32 v160, 16, v164
	v_and_b32_e32 v161, 0xffff0000, v164
	v_lshlrev_b32_e32 v162, 16, v165
	v_and_b32_e32 v163, 0xffff0000, v165
	v_lshlrev_b32_e32 v174, 16, v175
	v_and_b32_e32 v175, 0xffff0000, v175
	v_lshlrev_b32_e32 v176, 16, v178
	v_and_b32_e32 v177, 0xffff0000, v178
	v_lshlrev_b32_e32 v178, 16, v179
	v_and_b32_e32 v179, 0xffff0000, v179
	v_lshlrev_b32_e32 v164, 16, v166
	v_and_b32_e32 v165, 0xffff0000, v166
	v_lshlrev_b32_e32 v166, 16, v151
	v_and_b32_e32 v167, 0xffff0000, v151
	v_lshlrev_b32_e32 v180, 16, v173
	v_and_b32_e32 v181, 0xffff0000, v173
	v_pk_fma_f32 v[118:119], v[118:119], v[172:173], v[162:163] op_sel_hi:[1,0,1]
	v_pk_fma_f32 v[116:117], v[116:117], v[172:173], v[160:161] op_sel_hi:[1,0,1]
	v_pk_fma_f32 v[124:125], v[124:125], v[172:173], v[174:175] op_sel_hi:[1,0,1]
	v_pk_fma_f32 v[120:121], v[120:121], v[172:173], v[178:179] op_sel_hi:[1,0,1]
	v_pk_fma_f32 v[114:115], v[114:115], v[172:173], v[166:167] op_sel_hi:[1,0,1]
	v_pk_fma_f32 v[112:113], v[112:113], v[172:173], v[164:165] op_sel_hi:[1,0,1]
	v_pk_fma_f32 v[126:127], v[126:127], v[172:173], v[176:177] op_sel_hi:[1,0,1]
	v_pk_fma_f32 v[122:123], v[122:123], v[172:173], v[180:181] op_sel_hi:[1,0,1]
	v_cvt_pk_bf16_f32 v124, v124, v125
	v_cvt_pk_bf16_f32 v125, v126, v127
	v_cvt_pk_bf16_f32 v120, v120, v121
	v_mov_b32_e32 v126, 0
	v_cvt_pk_bf16_f32 v121, v122, v123
	v_cvt_pk_bf16_f32 v116, v116, v117
	v_cvt_pk_bf16_f32 v117, v118, v119
	v_cvt_pk_bf16_f32 v118, v112, v113
	v_cvt_pk_bf16_f32 v119, v114, v115
	s_nop 0
	v_mov_b32_dpp v184, v120 row_ror:8 row_mask:0xf bank_mask:0xf
	v_mov_b32_dpp v185, v121 row_ror:8 row_mask:0xf bank_mask:0xf
	v_mov_b32_dpp v188, v118 row_ror:8 row_mask:0xf bank_mask:0xf
	v_mov_b32_dpp v189, v119 row_ror:8 row_mask:0xf bank_mask:0xf
	v_mov_b32_dpp v186, v116 row_ror:8 row_mask:0xf bank_mask:0xf
	v_mov_b32_dpp v187, v117 row_ror:8 row_mask:0xf bank_mask:0xf
	v_cndmask_b32_e64 v114, v188, v120, s[6:7]
	v_cndmask_b32_e64 v115, v189, v121, s[6:7]
	v_lshl_add_u64 v[120:121], s[8:9], 0, v[168:169]
	v_cndmask_b32_e64 v112, v186, v124, s[6:7]
	v_cndmask_b32_e64 v113, v187, v125, s[6:7]
	v_lshl_add_u64 v[120:121], v[120:121], 0, v[146:147]
	v_mov_b32_dpp v182, v124 row_ror:8 row_mask:0xf bank_mask:0xf
	v_mov_b32_dpp v183, v125 row_ror:8 row_mask:0xf bank_mask:0xf
	global_store_dwordx4 v[120:121], v[112:115], off
	v_cndmask_b32_e64 v116, v116, v182, s[6:7]
	v_cndmask_b32_e64 v117, v117, v183, s[6:7]
	v_lshl_add_u64 v[112:113], s[8:9], 0, v[170:171]
	v_cndmask_b32_e64 v118, v118, v184, s[6:7]
	v_cndmask_b32_e64 v119, v119, v185, s[6:7]
	v_lshl_add_u64 v[112:113], v[112:113], 0, v[146:147]
	global_store_dwordx4 v[112:113], v[116:119], off
	v_or_b32_e32 v112, 16, v150
	v_ashrrev_i32_e32 v113, 31, v112
	v_lshl_add_u64 v[114:115], v[112:113], 2, s[10:11]
	v_sub_u32_e32 v112, v112, v152
	v_add_u32_e32 v112, v112, v154
	v_ashrrev_i32_e32 v113, 31, v112
	v_lshlrev_b64 v[120:121], 12, v[112:113]
	v_lshl_add_u64 v[112:113], s[16:17], 0, v[120:121]
	v_lshl_add_u64 v[122:123], v[120:121], 0, s[36:37]
	v_lshl_add_u64 v[112:113], v[112:113], 0, v[146:147]
	v_lshl_add_u64 v[116:117], s[16:17], 0, v[122:123]
	s_waitcnt vmcnt(14)
; __device__ __forceinline__ unsigned cvt_pk_bf16(float lo, float hi) { unsigned r; asm volatile("v_cvt_pk_bf16_f32 %0, %1, %2" : "=v"(r) : "v"(lo), "v"(hi)); return r; }
; __device__ __forceinline__ float bflo(unsigned w) { return __uint_as_float(w << 16); }
; __device__ __forceinline__ float bfhi(unsigned w) { return __uint_as_float(w & 0xffff0000u); }
;     __device__ __forceinline__ void operator()(const f32x4 (&acc)[2][2][4][2], const Unit& u, int wr, int wc, int fr, int fq) const {
;     ...
;             for (int m = 0; m < 4; ++m) { const int row = row0 + ai * HALF + m * 16; const size_t off = (size_t)row * D + col0; float sq = 0.f; u32x4 w[2];
;                 const float sc = rsin ? __builtin_amdgcn_rcpf(rsin[row] * (1.f / D) + EPS) : 1.0f;
;                 u32x4 rr[2]; if (R) load_pair_lines(R, D, row, fr, col0, rr[0], rr[1]);
; #pragma unroll
;                 for (int bj = 0; bj < 2; ++bj) { f32x4 r0, r1;
;                     if (R) { const u32x4 rw = rr[bj]; r0 = (f32x4){bflo(rw.x), bfhi(rw.x), bflo(rw.y), bfhi(rw.y)}; r1 = (f32x4){bflo(rw.z), bfhi(rw.z), bflo(rw.w), bfhi(rw.w)}; }
;                     else { const float* rp = (row < 8192 ? src_p + off : src_s + (off - (size_t)8192 * D)) + 8 * bj; r0 = *(const f32x4*)rp; r1 = *(const f32x4*)(rp + 4); }
;                     const f32x4 o0 = r0 + acc[ai][bj][m][0] * sc, o1 = r1 + acc[ai][bj][m][1] * sc;
;                     sq += (o0[0] * o0[0] + o0[1] * o0[1]) + (o0[2] * o0[2] + o0[3] * o0[3]) + (o1[0] * o1[0] + o1[1] * o1[1]) + (o1[2] * o1[2] + o1[3] * o1[3]);
;                     w[bj].x = cvt_pk_bf16(o0[0], o0[1]); w[bj].y = cvt_pk_bf16(o0[2], o0[3]); w[bj].z = cvt_pk_bf16(o1[0], o1[1]); w[bj].w = cvt_pk_bf16(o1[2], o1[3]); }
;                 store_pair_lines(O, D, row, fr, col0, w[0], w[1]);
	s_nop 0
	v_mov_b32_e32 v124, v204
	s_nop 0
	v_mov_b64_e32 v[112:113], v[208:209]
	v_mov_b64_e32 v[114:115], v[210:211]
	v_lshl_add_u64 v[116:117], v[116:117], 0, v[146:147]
	v_mov_b64_e32 v[116:117], v[212:213]
	v_mov_b64_e32 v[118:119], v[214:215]
	s_nop 1
	v_sub_u32_e32 v198, v150, v152
	v_add_u32_e32 v201, v198, v154
	v_add_u32_e32 v190, 0xa0, v201
	v_ashrrev_i32_e32 v191, 31, v190
	v_lshlrev_b64 v[194:195], 12, v[190:191]
	v_lshl_add_u64 v[196:197], v[194:195], 0, s[36:37]
	global_load_dword v204, v[148:149], off offset:640
	v_lshl_add_u64 v[190:191], s[16:17], 0, v[194:195]
	v_lshl_add_u64 v[192:193], s[16:17], 0, v[196:197]
	v_lshl_add_u64 v[190:191], v[190:191], 0, v[146:147]
	v_lshl_add_u64 v[192:193], v[192:193], 0, v[146:147]
	global_load_dwordx4 v[208:211], v[190:191], off
	global_load_dwordx4 v[212:215], v[192:193], off
	v_mov_b32_e32 v125, 0
	v_mov_b32_e32 v127, 0
	v_mov_b32_e32 v151, 0
	v_mov_b32_e32 v160, 0
	v_mov_b32_e32 v161, 0
	v_mov_b32_e32 v162, 0
	v_mov_b32_e32 v163, 0
	v_mov_b32_e32 v166, 0
	v_fmamk_f32 v124, v124, 0x3a000000, v159
	v_rcp_f32_e32 v124, v124
	v_mov_b32_dpp v125, v112 row_ror:8 row_mask:0xf bank_mask:0xf
	v_mov_b32_dpp v126, v113 row_ror:8 row_mask:0xf bank_mask:0xf
	v_mov_b32_dpp v127, v114 row_ror:8 row_mask:0xf bank_mask:0xf
	v_mov_b32_dpp v151, v115 row_ror:8 row_mask:0xf bank_mask:0xf
	v_mov_b32_dpp v160, v116 row_ror:8 row_mask:0xf bank_mask:0xf
	v_mov_b32_dpp v161, v117 row_ror:8 row_mask:0xf bank_mask:0xf
	v_mov_b32_dpp v162, v118 row_ror:8 row_mask:0xf bank_mask:0xf
	v_mov_b32_dpp v163, v119 row_ror:8 row_mask:0xf bank_mask:0xf
	v_cndmask_b32_e64 v163, v163, v115, s[6:7]
	v_cndmask_b32_e64 v162, v162, v114, s[6:7]
	v_cndmask_b32_e64 v115, v161, v113, s[6:7]
	v_cndmask_b32_e64 v113, v160, v112, s[6:7]
	v_cndmask_b32_e64 v151, v119, v151, s[6:7]
	v_cndmask_b32_e64 v164, v118, v127, s[6:7]
	v_cndmask_b32_e64 v161, v117, v126, s[6:7]
	v_cndmask_b32_e64 v125, v116, v125, s[6:7]
	v_lshlrev_b32_e32 v112, 16, v113
	v_and_b32_e32 v113, 0xffff0000, v113
	v_lshlrev_b32_e32 v116, 16, v162
	v_and_b32_e32 v117, 0xffff0000, v162
	v_lshlrev_b32_e32 v118, 16, v163
	v_and_b32_e32 v119, 0xffff0000, v163
	v_lshlrev_b32_e32 v126, 16, v125
	v_and_b32_e32 v127, 0xffff0000, v125
	v_lshlrev_b32_e32 v160, 16, v161
	v_and_b32_e32 v161, 0xffff0000, v161
	v_lshlrev_b32_e32 v162, 16, v164
	v_and_b32_e32 v163, 0xffff0000, v164
	v_lshlrev_b32_e32 v164, 16, v151
	v_and_b32_e32 v165, 0xffff0000, v151
	v_lshlrev_b32_e32 v114, 16, v115
	v_and_b32_e32 v115, 0xffff0000, v115
	v_pk_fma_f32 v[108:109], v[108:109], v[124:125], v[112:113] op_sel_hi:[1,0,1]
	v_pk_fma_f32 v[104:105], v[104:105], v[124:125], v[116:117] op_sel_hi:[1,0,1]
	v_pk_fma_f32 v[102:103], v[102:103], v[124:125], v[160:161] op_sel_hi:[1,0,1]
	v_pk_fma_f32 v[100:101], v[100:101], v[124:125], v[126:127] op_sel_hi:[1,0,1]
	v_pk_fma_f32 v[98:99], v[98:99], v[124:125], v[164:165] op_sel_hi:[1,0,1]
	v_pk_fma_f32 v[110:111], v[110:111], v[124:125], v[114:115] op_sel_hi:[1,0,1]
	v_pk_fma_f32 v[106:107], v[106:107], v[124:125], v[118:119] op_sel_hi:[1,0,1]
	v_pk_fma_f32 v[96:97], v[96:97], v[124:125], v[162:163] op_sel_hi:[1,0,1]
	v_cvt_pk_bf16_f32 v108, v108, v109
	v_cvt_pk_bf16_f32 v109, v110, v111
	v_cvt_pk_bf16_f32 v104, v104, v105
	v_cvt_pk_bf16_f32 v105, v106, v107
	v_cvt_pk_bf16_f32 v100, v100, v101
	v_cvt_pk_bf16_f32 v101, v102, v103
	s_nop 0
	v_cvt_pk_bf16_f32 v102, v96, v97
	v_cvt_pk_bf16_f32 v103, v98, v99
	v_mov_b32_e32 v98, 0
	v_mov_b32_e32 v99, 0
	v_mov_b32_e32 v107, 0
	v_mov_b32_e32 v110, 0
	v_mov_b32_e32 v96, 0
	v_mov_b32_e32 v97, 0
	v_mov_b32_dpp v98, v102 row_ror:8 row_mask:0xf bank_mask:0xf
	v_mov_b32_dpp v99, v103 row_ror:8 row_mask:0xf bank_mask:0xf
	v_mov_b32_dpp v107, v104 row_ror:8 row_mask:0xf bank_mask:0xf
	v_mov_b32_dpp v110, v105 row_ror:8 row_mask:0xf bank_mask:0xf
	v_mov_b32_dpp v96, v100 row_ror:8 row_mask:0xf bank_mask:0xf
	v_mov_b32_dpp v97, v101 row_ror:8 row_mask:0xf bank_mask:0xf
	v_cndmask_b32_e64 v98, v98, v104, s[6:7]
	v_cndmask_b32_e64 v99, v99, v105, s[6:7]
	v_lshl_add_u64 v[104:105], s[8:9], 0, v[120:121]
	v_mov_b32_e32 v106, 0
	v_cndmask_b32_e64 v96, v96, v108, s[6:7]
	v_cndmask_b32_e64 v97, v97, v109, s[6:7]
	v_lshl_add_u64 v[104:105], v[104:105], 0, v[146:147]
	v_mov_b32_dpp v166, v108 row_ror:8 row_mask:0xf bank_mask:0xf
	v_mov_b32_dpp v106, v109 row_ror:8 row_mask:0xf bank_mask:0xf
	global_store_dwordx4 v[104:105], v[96:99], off
	v_cndmask_b32_e64 v100, v100, v166, s[6:7]
	v_cndmask_b32_e64 v101, v101, v106, s[6:7]
	v_lshl_add_u64 v[96:97], s[8:9], 0, v[122:123]
	v_cndmask_b32_e64 v102, v102, v107, s[6:7]
	v_cndmask_b32_e64 v103, v103, v110, s[6:7]
	v_lshl_add_u64 v[96:97], v[96:97], 0, v[146:147]
	global_store_dwordx4 v[96:97], v[100:103], off
	v_or_b32_e32 v96, 32, v150
	v_ashrrev_i32_e32 v97, 31, v96
	v_lshl_add_u64 v[98:99], v[96:97], 2, s[10:11]
	v_sub_u32_e32 v96, v96, v152
	v_add_u32_e32 v96, v96, v154
	v_ashrrev_i32_e32 v97, 31, v96
	v_lshlrev_b64 v[104:105], 12, v[96:97]
	v_lshl_add_u64 v[96:97], s[16:17], 0, v[104:105]
	v_lshl_add_u64 v[106:107], v[104:105], 0, s[36:37]
	v_lshl_add_u64 v[96:97], v[96:97], 0, v[146:147]
	v_lshl_add_u64 v[100:101], s[16:17], 0, v[106:107]
	s_waitcnt vmcnt(16)
; __device__ __forceinline__ unsigned cvt_pk_bf16(float lo, float hi) { unsigned r; asm volatile("v_cvt_pk_bf16_f32 %0, %1, %2" : "=v"(r) : "v"(lo), "v"(hi)); return r; }
; __device__ __forceinline__ float bflo(unsigned w) { return __uint_as_float(w << 16); }
; __device__ __forceinline__ float bfhi(unsigned w) { return __uint_as_float(w & 0xffff0000u); }
;     __device__ __forceinline__ void operator()(const f32x4 (&acc)[2][2][4][2], const Unit& u, int wr, int wc, int fr, int fq) const {
;     ...
;             for (int m = 0; m < 4; ++m) { const int row = row0 + ai * HALF + m * 16; const size_t off = (size_t)row * D + col0; float sq = 0.f; u32x4 w[2];
;                 const float sc = rsin ? __builtin_amdgcn_rcpf(rsin[row] * (1.f / D) + EPS) : 1.0f;
;                 u32x4 rr[2]; if (R) load_pair_lines(R, D, row, fr, col0, rr[0], rr[1]);
; #pragma unroll
;                 for (int bj = 0; bj < 2; ++bj) { f32x4 r0, r1;
;                     if (R) { const u32x4 rw = rr[bj]; r0 = (f32x4){bflo(rw.x), bfhi(rw.x), bflo(rw.y), bfhi(rw.y)}; r1 = (f32x4){bflo(rw.z), bfhi(rw.z), bflo(rw.w), bfhi(rw.w)}; }
;                     else { const float* rp = (row < 8192 ? src_p + off : src_s + (off - (size_t)8192 * D)) + 8 * bj; r0 = *(const f32x4*)rp; r1 = *(const f32x4*)(rp + 4); }
;                     const f32x4 o0 = r0 + acc[ai][bj][m][0] * sc, o1 = r1 + acc[ai][bj][m][1] * sc;
;                     sq += (o0[0] * o0[0] + o0[1] * o0[1]) + (o0[2] * o0[2] + o0[3] * o0[3]) + (o1[0] * o1[0] + o1[1] * o1[1]) + (o1[2] * o1[2] + o1[3] * o1[3]);
;                     w[bj].x = cvt_pk_bf16(o0[0], o0[1]); w[bj].y = cvt_pk_bf16(o0[2], o0[3]); w[bj].z = cvt_pk_bf16(o1[0], o1[1]); w[bj].w = cvt_pk_bf16(o1[2], o1[3]); }
;                 store_pair_lines(O, D, row, fr, col0, w[0], w[1]);
	s_nop 0
	v_mov_b32_e32 v108, v205
	s_nop 0
	v_mov_b64_e32 v[96:97], v[216:217]
	v_mov_b64_e32 v[98:99], v[218:219]
	v_lshl_add_u64 v[100:101], v[100:101], 0, v[146:147]
	v_mov_b64_e32 v[100:101], v[220:221]
	v_mov_b64_e32 v[102:103], v[222:223]
	s_nop 1
	v_sub_u32_e32 v198, v150, v152
	v_add_u32_e32 v201, v198, v154
	v_add_u32_e32 v190, 0xb0, v201
	v_ashrrev_i32_e32 v191, 31, v190
	v_lshlrev_b64 v[194:195], 12, v[190:191]
	v_lshl_add_u64 v[196:197], v[194:195], 0, s[36:37]
	global_load_dword v205, v[148:149], off offset:704
	v_lshl_add_u64 v[190:191], s[16:17], 0, v[194:195]
	v_lshl_add_u64 v[192:193], s[16:17], 0, v[196:197]
	v_lshl_add_u64 v[190:191], v[190:191], 0, v[146:147]
	v_lshl_add_u64 v[192:193], v[192:193], 0, v[146:147]
	global_load_dwordx4 v[216:219], v[190:191], off
	global_load_dwordx4 v[220:223], v[192:193], off
	v_mov_b32_e32 v113, 0
	v_mov_b32_e32 v114, 0
	v_mov_b32_e32 v115, 0
	v_mov_b32_e32 v116, 0
	v_mov_b32_e32 v109, 0
	v_mov_b32_e32 v110, 0
	v_mov_b32_e32 v111, 0
	v_mov_b32_e32 v112, 0
	v_fmamk_f32 v108, v108, 0x3a000000, v159
	v_rcp_f32_e32 v108, v108
	v_mov_b32_dpp v109, v96 row_ror:8 row_mask:0xf bank_mask:0xf
	v_mov_b32_dpp v113, v100 row_ror:8 row_mask:0xf bank_mask:0xf
	v_mov_b32_dpp v114, v101 row_ror:8 row_mask:0xf bank_mask:0xf
	v_mov_b32_dpp v115, v102 row_ror:8 row_mask:0xf bank_mask:0xf
	v_mov_b32_dpp v116, v103 row_ror:8 row_mask:0xf bank_mask:0xf
	v_mov_b32_dpp v110, v97 row_ror:8 row_mask:0xf bank_mask:0xf
	v_mov_b32_dpp v111, v98 row_ror:8 row_mask:0xf bank_mask:0xf
	v_mov_b32_dpp v112, v99 row_ror:8 row_mask:0xf bank_mask:0xf
	v_cndmask_b32_e64 v116, v116, v99, s[6:7]
	v_cndmask_b32_e64 v115, v115, v98, s[6:7]
	v_cndmask_b32_e64 v99, v114, v97, s[6:7]
	v_cndmask_b32_e64 v97, v113, v96, s[6:7]
	v_cndmask_b32_e64 v114, v103, v112, s[6:7]
	v_cndmask_b32_e64 v117, v102, v111, s[6:7]
	v_cndmask_b32_e64 v113, v101, v110, s[6:7]
	v_cndmask_b32_e64 v109, v100, v109, s[6:7]
	v_lshlrev_b32_e32 v96, 16, v97
	v_and_b32_e32 v97, 0xffff0000, v97
	v_lshlrev_b32_e32 v98, 16, v99
	v_and_b32_e32 v99, 0xffff0000, v99
	v_lshlrev_b32_e32 v100, 16, v115
	v_and_b32_e32 v101, 0xffff0000, v115
	v_lshlrev_b32_e32 v102, 16, v116
	v_and_b32_e32 v103, 0xffff0000, v116
	v_pk_fma_f32 v[94:95], v[94:95], v[108:109], v[98:99] op_sel_hi:[1,0,1]
	v_pk_fma_f32 v[92:93], v[92:93], v[108:109], v[96:97] op_sel_hi:[1,0,1]
	v_pk_fma_f32 v[90:91], v[90:91], v[108:109], v[102:103] op_sel_hi:[1,0,1]
	v_pk_fma_f32 v[88:89], v[88:89], v[108:109], v[100:101] op_sel_hi:[1,0,1]
	v_lshlrev_b32_e32 v110, 16, v109
	v_and_b32_e32 v111, 0xffff0000, v109
	v_lshlrev_b32_e32 v112, 16, v113
	v_and_b32_e32 v113, 0xffff0000, v113
	v_cvt_pk_bf16_f32 v92, v92, v93
	v_cvt_pk_bf16_f32 v93, v94, v95
	v_cvt_pk_bf16_f32 v94, v88, v89
	v_cvt_pk_bf16_f32 v95, v90, v91
	v_lshlrev_b32_e32 v88, 16, v117
	v_and_b32_e32 v89, 0xffff0000, v117
	v_lshlrev_b32_e32 v90, 16, v114
	v_and_b32_e32 v91, 0xffff0000, v114
	v_pk_fma_f32 v[86:87], v[86:87], v[108:109], v[112:113] op_sel_hi:[1,0,1]
	v_pk_fma_f32 v[84:85], v[84:85], v[108:109], v[110:111] op_sel_hi:[1,0,1]
	v_pk_fma_f32 v[82:83], v[82:83], v[108:109], v[90:91] op_sel_hi:[1,0,1]
	v_pk_fma_f32 v[80:81], v[80:81], v[108:109], v[88:89] op_sel_hi:[1,0,1]
	v_mov_b32_e32 v88, 0
	v_mov_b32_e32 v89, 0
	v_cvt_pk_bf16_f32 v84, v84, v85
	v_cvt_pk_bf16_f32 v85, v86, v87
	v_cvt_pk_bf16_f32 v86, v80, v81
	v_cvt_pk_bf16_f32 v87, v82, v83
	s_nop 0
	v_mov_b32_dpp v88, v92 row_ror:8 row_mask:0xf bank_mask:0xf
	v_mov_b32_dpp v89, v93 row_ror:8 row_mask:0xf bank_mask:0xf
	v_mov_b32_e32 v80, 0
	v_mov_b32_e32 v81, 0
	v_mov_b32_e32 v82, 0
	v_mov_b32_e32 v83, 0
	v_mov_b32_dpp v80, v84 row_ror:8 row_mask:0xf bank_mask:0xf
	v_mov_b32_dpp v81, v85 row_ror:8 row_mask:0xf bank_mask:0xf
	v_mov_b32_dpp v82, v86 row_ror:8 row_mask:0xf bank_mask:0xf
	v_mov_b32_dpp v83, v87 row_ror:8 row_mask:0xf bank_mask:0xf
	v_cndmask_b32_e64 v84, v84, v88, s[6:7]
	v_cndmask_b32_e64 v85, v85, v89, s[6:7]
	v_lshl_add_u64 v[88:89], s[8:9], 0, v[104:105]
	v_mov_b32_e32 v90, 0
	v_mov_b32_e32 v91, 0
	v_cndmask_b32_e64 v80, v80, v92, s[6:7]
	v_cndmask_b32_e64 v81, v81, v93, s[6:7]
	v_cndmask_b32_e64 v82, v82, v94, s[6:7]
	v_cndmask_b32_e64 v83, v83, v95, s[6:7]
	v_lshl_add_u64 v[88:89], v[88:89], 0, v[146:147]
	v_mov_b32_dpp v90, v94 row_ror:8 row_mask:0xf bank_mask:0xf
	v_mov_b32_dpp v91, v95 row_ror:8 row_mask:0xf bank_mask:0xf
	global_store_dwordx4 v[88:89], v[80:83], off
	v_cndmask_b32_e64 v86, v86, v90, s[6:7]
	v_cndmask_b32_e64 v87, v87, v91, s[6:7]
	v_lshl_add_u64 v[80:81], s[8:9], 0, v[106:107]
	v_lshl_add_u64 v[80:81], v[80:81], 0, v[146:147]
	global_store_dwordx4 v[80:81], v[84:87], off
	v_or_b32_e32 v80, 48, v150
	v_ashrrev_i32_e32 v81, 31, v80
	v_lshl_add_u64 v[82:83], v[80:81], 2, s[10:11]
	v_sub_u32_e32 v80, v80, v152
	v_add_u32_e32 v80, v80, v154
	v_ashrrev_i32_e32 v81, 31, v80
	v_lshlrev_b64 v[88:89], 12, v[80:81]
	v_lshl_add_u64 v[80:81], s[16:17], 0, v[88:89]
	v_lshl_add_u64 v[90:91], v[88:89], 0, s[36:37]
	v_lshl_add_u64 v[80:81], v[80:81], 0, v[146:147]
	v_lshl_add_u64 v[84:85], s[16:17], 0, v[90:91]
	s_waitcnt vmcnt(18)
; __device__ __forceinline__ unsigned cvt_pk_bf16(float lo, float hi) { unsigned r; asm volatile("v_cvt_pk_bf16_f32 %0, %1, %2" : "=v"(r) : "v"(lo), "v"(hi)); return r; }
; __device__ __forceinline__ float bflo(unsigned w) { return __uint_as_float(w << 16); }
; __device__ __forceinline__ float bfhi(unsigned w) { return __uint_as_float(w & 0xffff0000u); }
;     __device__ __forceinline__ void operator()(const f32x4 (&acc)[2][2][4][2], const Unit& u, int wr, int wc, int fr, int fq) const {
;     ...
;             for (int m = 0; m < 4; ++m) { const int row = row0 + ai * HALF + m * 16; const size_t off = (size_t)row * D + col0; float sq = 0.f; u32x4 w[2];
;                 const float sc = rsin ? __builtin_amdgcn_rcpf(rsin[row] * (1.f / D) + EPS) : 1.0f;
;                 u32x4 rr[2]; if (R) load_pair_lines(R, D, row, fr, col0, rr[0], rr[1]);
; #pragma unroll
;                 for (int bj = 0; bj < 2; ++bj) { f32x4 r0, r1;
;                     if (R) { const u32x4 rw = rr[bj]; r0 = (f32x4){bflo(rw.x), bfhi(rw.x), bflo(rw.y), bfhi(rw.y)}; r1 = (f32x4){bflo(rw.z), bfhi(rw.z), bflo(rw.w), bfhi(rw.w)}; }
;                     else { const float* rp = (row < 8192 ? src_p + off : src_s + (off - (size_t)8192 * D)) + 8 * bj; r0 = *(const f32x4*)rp; r1 = *(const f32x4*)(rp + 4); }
;                     const f32x4 o0 = r0 + acc[ai][bj][m][0] * sc, o1 = r1 + acc[ai][bj][m][1] * sc;
;                     sq += (o0[0] * o0[0] + o0[1] * o0[1]) + (o0[2] * o0[2] + o0[3] * o0[3]) + (o1[0] * o1[0] + o1[1] * o1[1]) + (o1[2] * o1[2] + o1[3] * o1[3]);
;                     w[bj].x = cvt_pk_bf16(o0[0], o0[1]); w[bj].y = cvt_pk_bf16(o0[2], o0[3]); w[bj].z = cvt_pk_bf16(o1[0], o1[1]); w[bj].w = cvt_pk_bf16(o1[2], o1[3]); }
;                 store_pair_lines(O, D, row, fr, col0, w[0], w[1]);
	s_nop 0
	v_mov_b32_e32 v92, v206
	s_nop 0
	v_mov_b64_e32 v[80:81], v[224:225]
	v_mov_b64_e32 v[82:83], v[226:227]
	v_lshl_add_u64 v[84:85], v[84:85], 0, v[146:147]
	v_mov_b64_e32 v[84:85], v[228:229]
	v_mov_b64_e32 v[86:87], v[230:231]
	s_nop 1
	v_mov_b32_e32 v97, 0
	v_mov_b32_e32 v98, 0
	v_mov_b32_e32 v99, 0
	v_mov_b32_e32 v100, 0
	v_mov_b32_e32 v93, 0
	v_mov_b32_e32 v94, 0
	v_mov_b32_e32 v95, 0
	v_mov_b32_e32 v96, 0
	v_fmamk_f32 v92, v92, 0x3a000000, v159
	v_rcp_f32_e32 v92, v92
	v_mov_b32_dpp v93, v80 row_ror:8 row_mask:0xf bank_mask:0xf
	v_mov_b32_dpp v97, v84 row_ror:8 row_mask:0xf bank_mask:0xf
	v_mov_b32_dpp v98, v85 row_ror:8 row_mask:0xf bank_mask:0xf
	v_mov_b32_dpp v99, v86 row_ror:8 row_mask:0xf bank_mask:0xf
	v_mov_b32_dpp v100, v87 row_ror:8 row_mask:0xf bank_mask:0xf
	v_mov_b32_dpp v94, v81 row_ror:8 row_mask:0xf bank_mask:0xf
	v_mov_b32_dpp v95, v82 row_ror:8 row_mask:0xf bank_mask:0xf
	v_mov_b32_dpp v96, v83 row_ror:8 row_mask:0xf bank_mask:0xf
	v_cndmask_b32_e64 v100, v100, v83, s[6:7]
	v_cndmask_b32_e64 v99, v99, v82, s[6:7]
	v_cndmask_b32_e64 v83, v98, v81, s[6:7]
	v_cndmask_b32_e64 v81, v97, v80, s[6:7]
	v_cndmask_b32_e64 v96, v87, v96, s[6:7]
	v_cndmask_b32_e64 v95, v86, v95, s[6:7]
	v_cndmask_b32_e64 v94, v85, v94, s[6:7]
	v_cndmask_b32_e64 v93, v84, v93, s[6:7]
	v_lshlrev_b32_e32 v80, 16, v81
	v_and_b32_e32 v81, 0xffff0000, v81
	v_lshlrev_b32_e32 v82, 16, v83
	v_and_b32_e32 v83, 0xffff0000, v83
	v_lshlrev_b32_e32 v84, 16, v99
	v_and_b32_e32 v85, 0xffff0000, v99
	v_lshlrev_b32_e32 v86, 16, v100
	v_and_b32_e32 v87, 0xffff0000, v100
	v_pk_fma_f32 v[78:79], v[78:79], v[92:93], v[82:83] op_sel_hi:[1,0,1]
	v_pk_fma_f32 v[76:77], v[76:77], v[92:93], v[80:81] op_sel_hi:[1,0,1]
	v_pk_fma_f32 v[74:75], v[74:75], v[92:93], v[86:87] op_sel_hi:[1,0,1]
	v_pk_fma_f32 v[72:73], v[72:73], v[92:93], v[84:85] op_sel_hi:[1,0,1]
	v_cvt_pk_bf16_f32 v80, v76, v77
	v_cvt_pk_bf16_f32 v81, v78, v79
	v_lshlrev_b32_e32 v76, 16, v95
	v_cvt_pk_bf16_f32 v82, v72, v73
	v_cvt_pk_bf16_f32 v83, v74, v75
	v_lshlrev_b32_e32 v72, 16, v93
	v_and_b32_e32 v73, 0xffff0000, v93
	v_lshlrev_b32_e32 v74, 16, v94
	v_and_b32_e32 v75, 0xffff0000, v94
	v_and_b32_e32 v77, 0xffff0000, v95
	v_lshlrev_b32_e32 v78, 16, v96
	v_and_b32_e32 v79, 0xffff0000, v96
	v_pk_fma_f32 v[70:71], v[70:71], v[92:93], v[74:75] op_sel_hi:[1,0,1]
	v_pk_fma_f32 v[68:69], v[68:69], v[92:93], v[72:73] op_sel_hi:[1,0,1]
	v_pk_fma_f32 v[66:67], v[66:67], v[92:93], v[78:79] op_sel_hi:[1,0,1]
	v_pk_fma_f32 v[64:65], v[64:65], v[92:93], v[76:77] op_sel_hi:[1,0,1]
	v_mov_b32_e32 v72, 0
	v_mov_b32_e32 v73, 0
	v_cvt_pk_bf16_f32 v68, v68, v69
	v_cvt_pk_bf16_f32 v69, v70, v71
	v_cvt_pk_bf16_f32 v70, v64, v65
	v_cvt_pk_bf16_f32 v71, v66, v67
	s_nop 0
	v_mov_b32_dpp v72, v80 row_ror:8 row_mask:0xf bank_mask:0xf
	v_mov_b32_dpp v73, v81 row_ror:8 row_mask:0xf bank_mask:0xf
	v_mov_b32_e32 v64, 0
	v_mov_b32_e32 v65, 0
	v_mov_b32_e32 v66, 0
	v_mov_b32_e32 v67, 0
	v_mov_b32_dpp v64, v68 row_ror:8 row_mask:0xf bank_mask:0xf
	v_mov_b32_dpp v65, v69 row_ror:8 row_mask:0xf bank_mask:0xf
	v_mov_b32_dpp v66, v70 row_ror:8 row_mask:0xf bank_mask:0xf
	v_mov_b32_dpp v67, v71 row_ror:8 row_mask:0xf bank_mask:0xf
	v_cndmask_b32_e64 v68, v68, v72, s[6:7]
	v_cndmask_b32_e64 v69, v69, v73, s[6:7]
	v_lshl_add_u64 v[72:73], s[8:9], 0, v[88:89]
	v_mov_b32_e32 v74, 0
	v_mov_b32_e32 v75, 0
	v_cndmask_b32_e64 v64, v64, v80, s[6:7]
	v_cndmask_b32_e64 v65, v65, v81, s[6:7]
	v_cndmask_b32_e64 v66, v66, v82, s[6:7]
	v_cndmask_b32_e64 v67, v67, v83, s[6:7]
	v_lshl_add_u64 v[72:73], v[72:73], 0, v[146:147]
	v_mov_b32_dpp v74, v82 row_ror:8 row_mask:0xf bank_mask:0xf
	v_mov_b32_dpp v75, v83 row_ror:8 row_mask:0xf bank_mask:0xf
	global_store_dwordx4 v[72:73], v[64:67], off
	v_cndmask_b32_e64 v70, v70, v74, s[6:7]
	v_cndmask_b32_e64 v71, v71, v75, s[6:7]
	v_lshl_add_u64 v[64:65], s[8:9], 0, v[90:91]
	v_lshl_add_u64 v[64:65], v[64:65], 0, v[146:147]
	global_store_dwordx4 v[64:65], v[68:71], off
	v_sub_u32_e32 v64, v150, v152
	v_add_u32_e32 v77, v64, v154
	v_add_u32_e32 v64, 0x80, v77
	v_ashrrev_i32_e32 v65, 31, v64
	v_lshlrev_b64 v[72:73], 12, v[64:65]
	v_lshl_add_u64 v[64:65], s[16:17], 0, v[72:73]
	v_lshl_add_u64 v[74:75], v[72:73], 0, s[36:37]
	v_lshl_add_u64 v[64:65], v[64:65], 0, v[146:147]
	v_lshl_add_u64 v[68:69], s[16:17], 0, v[74:75]
	s_waitcnt vmcnt(17)
; __device__ __forceinline__ unsigned cvt_pk_bf16(float lo, float hi) { unsigned r; asm volatile("v_cvt_pk_bf16_f32 %0, %1, %2" : "=v"(r) : "v"(lo), "v"(hi)); return r; }
; __device__ __forceinline__ float bflo(unsigned w) { return __uint_as_float(w << 16); }
; __device__ __forceinline__ float bfhi(unsigned w) { return __uint_as_float(w & 0xffff0000u); }
;     __device__ __forceinline__ void operator()(const f32x4 (&acc)[2][2][4][2], const Unit& u, int wr, int wc, int fr, int fq) const {
;     ...
;             for (int m = 0; m < 4; ++m) { const int row = row0 + ai * HALF + m * 16; const size_t off = (size_t)row * D + col0; float sq = 0.f; u32x4 w[2];
;                 const float sc = rsin ? __builtin_amdgcn_rcpf(rsin[row] * (1.f / D) + EPS) : 1.0f;
;                 u32x4 rr[2]; if (R) load_pair_lines(R, D, row, fr, col0, rr[0], rr[1]);
; #pragma unroll
;                 for (int bj = 0; bj < 2; ++bj) { f32x4 r0, r1;
;                     if (R) { const u32x4 rw = rr[bj]; r0 = (f32x4){bflo(rw.x), bfhi(rw.x), bflo(rw.y), bfhi(rw.y)}; r1 = (f32x4){bflo(rw.z), bfhi(rw.z), bflo(rw.w), bfhi(rw.w)}; }
;                     else { const float* rp = (row < 8192 ? src_p + off : src_s + (off - (size_t)8192 * D)) + 8 * bj; r0 = *(const f32x4*)rp; r1 = *(const f32x4*)(rp + 4); }
;                     const f32x4 o0 = r0 + acc[ai][bj][m][0] * sc, o1 = r1 + acc[ai][bj][m][1] * sc;
;                     sq += (o0[0] * o0[0] + o0[1] * o0[1]) + (o0[2] * o0[2] + o0[3] * o0[3]) + (o1[0] * o1[0] + o1[1] * o1[1]) + (o1[2] * o1[2] + o1[3] * o1[3]);
;                     w[bj].x = cvt_pk_bf16(o0[0], o0[1]); w[bj].y = cvt_pk_bf16(o0[2], o0[3]); w[bj].z = cvt_pk_bf16(o1[0], o1[1]); w[bj].w = cvt_pk_bf16(o1[2], o1[3]); }
;                 store_pair_lines(O, D, row, fr, col0, w[0], w[1]);
	s_nop 0
	v_mov_b32_e32 v76, v207
	s_nop 0
	v_mov_b64_e32 v[64:65], v[232:233]
	v_mov_b64_e32 v[66:67], v[234:235]
	v_lshl_add_u64 v[68:69], v[68:69], 0, v[146:147]
	v_mov_b64_e32 v[68:69], v[236:237]
	v_mov_b64_e32 v[70:71], v[238:239]
	s_nop 1
	v_mov_b32_e32 v82, 0
	v_mov_b32_e32 v83, 0
	v_mov_b32_e32 v84, 0
	v_mov_b32_e32 v85, 0
	v_mov_b32_e32 v78, 0
	v_mov_b32_e32 v79, 0
	v_mov_b32_e32 v80, 0
	v_mov_b32_e32 v81, 0
	v_fmamk_f32 v76, v76, 0x3a000000, v159
	v_rcp_f32_e32 v76, v76
	v_mov_b32_dpp v78, v64 row_ror:8 row_mask:0xf bank_mask:0xf
	v_mov_b32_dpp v82, v68 row_ror:8 row_mask:0xf bank_mask:0xf
	v_mov_b32_dpp v83, v69 row_ror:8 row_mask:0xf bank_mask:0xf
	v_mov_b32_dpp v84, v70 row_ror:8 row_mask:0xf bank_mask:0xf
	v_mov_b32_dpp v85, v71 row_ror:8 row_mask:0xf bank_mask:0xf
	v_mov_b32_dpp v79, v65 row_ror:8 row_mask:0xf bank_mask:0xf
	v_mov_b32_dpp v80, v66 row_ror:8 row_mask:0xf bank_mask:0xf
	v_mov_b32_dpp v81, v67 row_ror:8 row_mask:0xf bank_mask:0xf
	v_cndmask_b32_e64 v85, v85, v67, s[6:7]
	v_cndmask_b32_e64 v84, v84, v66, s[6:7]
	v_cndmask_b32_e64 v67, v83, v65, s[6:7]
	v_cndmask_b32_e64 v65, v82, v64, s[6:7]
	v_cndmask_b32_e64 v81, v71, v81, s[6:7]
	v_cndmask_b32_e64 v80, v70, v80, s[6:7]
	v_cndmask_b32_e64 v79, v69, v79, s[6:7]
	v_cndmask_b32_e64 v78, v68, v78, s[6:7]
	v_lshlrev_b32_e32 v64, 16, v65
	v_and_b32_e32 v65, 0xffff0000, v65
	v_lshlrev_b32_e32 v66, 16, v67
	v_and_b32_e32 v67, 0xffff0000, v67
	v_lshlrev_b32_e32 v68, 16, v84
	v_and_b32_e32 v69, 0xffff0000, v84
	v_lshlrev_b32_e32 v70, 16, v85
	v_and_b32_e32 v71, 0xffff0000, v85
	v_pk_fma_f32 v[62:63], v[62:63], v[76:77], v[66:67] op_sel_hi:[1,0,1]
	v_pk_fma_f32 v[60:61], v[60:61], v[76:77], v[64:65] op_sel_hi:[1,0,1]
	v_pk_fma_f32 v[58:59], v[58:59], v[76:77], v[70:71] op_sel_hi:[1,0,1]
	v_pk_fma_f32 v[56:57], v[56:57], v[76:77], v[68:69] op_sel_hi:[1,0,1]
	v_cvt_pk_bf16_f32 v64, v60, v61
	v_cvt_pk_bf16_f32 v65, v62, v63
	v_lshlrev_b32_e32 v60, 16, v80
	v_cvt_pk_bf16_f32 v66, v56, v57
	v_cvt_pk_bf16_f32 v67, v58, v59
	v_lshlrev_b32_e32 v56, 16, v78
	v_and_b32_e32 v57, 0xffff0000, v78
	v_lshlrev_b32_e32 v58, 16, v79
	v_and_b32_e32 v59, 0xffff0000, v79
	v_and_b32_e32 v61, 0xffff0000, v80
	v_lshlrev_b32_e32 v62, 16, v81
	v_and_b32_e32 v63, 0xffff0000, v81
	v_pk_fma_f32 v[54:55], v[54:55], v[76:77], v[58:59] op_sel_hi:[1,0,1]
	v_pk_fma_f32 v[52:53], v[52:53], v[76:77], v[56:57] op_sel_hi:[1,0,1]
	v_pk_fma_f32 v[50:51], v[50:51], v[76:77], v[62:63] op_sel_hi:[1,0,1]
	v_pk_fma_f32 v[48:49], v[48:49], v[76:77], v[60:61] op_sel_hi:[1,0,1]
	v_mov_b32_e32 v56, 0
	v_mov_b32_e32 v57, 0
	v_cvt_pk_bf16_f32 v52, v52, v53
	v_cvt_pk_bf16_f32 v53, v54, v55
	v_cvt_pk_bf16_f32 v54, v48, v49
	v_cvt_pk_bf16_f32 v55, v50, v51
	s_nop 0
	v_mov_b32_dpp v56, v64 row_ror:8 row_mask:0xf bank_mask:0xf
	v_mov_b32_dpp v57, v65 row_ror:8 row_mask:0xf bank_mask:0xf
	v_mov_b32_e32 v48, 0
	v_mov_b32_e32 v49, 0
	v_mov_b32_e32 v50, 0
	v_mov_b32_e32 v51, 0
	v_mov_b32_dpp v48, v52 row_ror:8 row_mask:0xf bank_mask:0xf
	v_mov_b32_dpp v49, v53 row_ror:8 row_mask:0xf bank_mask:0xf
	v_mov_b32_dpp v50, v54 row_ror:8 row_mask:0xf bank_mask:0xf
	v_mov_b32_dpp v51, v55 row_ror:8 row_mask:0xf bank_mask:0xf
	v_cndmask_b32_e64 v52, v52, v56, s[6:7]
	v_cndmask_b32_e64 v53, v53, v57, s[6:7]
	v_lshl_add_u64 v[56:57], s[8:9], 0, v[72:73]
	v_mov_b32_e32 v58, 0
	v_mov_b32_e32 v59, 0
	v_cndmask_b32_e64 v48, v48, v64, s[6:7]
	v_cndmask_b32_e64 v49, v49, v65, s[6:7]
	v_cndmask_b32_e64 v50, v50, v66, s[6:7]
	v_cndmask_b32_e64 v51, v51, v67, s[6:7]
	v_lshl_add_u64 v[56:57], v[56:57], 0, v[146:147]
	v_mov_b32_dpp v58, v66 row_ror:8 row_mask:0xf bank_mask:0xf
	v_mov_b32_dpp v59, v67 row_ror:8 row_mask:0xf bank_mask:0xf
	global_store_dwordx4 v[56:57], v[48:51], off
	v_cndmask_b32_e64 v54, v54, v58, s[6:7]
	v_cndmask_b32_e64 v55, v55, v59, s[6:7]
	v_lshl_add_u64 v[48:49], s[8:9], 0, v[74:75]
	v_lshl_add_u64 v[48:49], v[48:49], 0, v[146:147]
	global_store_dwordx4 v[48:49], v[52:55], off
	v_add_u32_e32 v48, 0x90, v77
	v_ashrrev_i32_e32 v49, 31, v48
	v_lshlrev_b64 v[56:57], 12, v[48:49]
	v_lshl_add_u64 v[48:49], s[16:17], 0, v[56:57]
	v_lshl_add_u64 v[58:59], v[56:57], 0, s[36:37]
	v_lshl_add_u64 v[48:49], v[48:49], 0, v[146:147]
	v_lshl_add_u64 v[52:53], s[16:17], 0, v[58:59]
	s_waitcnt vmcnt(16)
; __device__ __forceinline__ unsigned cvt_pk_bf16(float lo, float hi) { unsigned r; asm volatile("v_cvt_pk_bf16_f32 %0, %1, %2" : "=v"(r) : "v"(lo), "v"(hi)); return r; }
; __device__ __forceinline__ float bflo(unsigned w) { return __uint_as_float(w << 16); }
; __device__ __forceinline__ float bfhi(unsigned w) { return __uint_as_float(w & 0xffff0000u); }
;     __device__ __forceinline__ void operator()(const f32x4 (&acc)[2][2][4][2], const Unit& u, int wr, int wc, int fr, int fq) const {
;     ...
;             for (int m = 0; m < 4; ++m) { const int row = row0 + ai * HALF + m * 16; const size_t off = (size_t)row * D + col0; float sq = 0.f; u32x4 w[2];
;                 const float sc = rsin ? __builtin_amdgcn_rcpf(rsin[row] * (1.f / D) + EPS) : 1.0f;
;                 u32x4 rr[2]; if (R) load_pair_lines(R, D, row, fr, col0, rr[0], rr[1]);
; #pragma unroll
;                 for (int bj = 0; bj < 2; ++bj) { f32x4 r0, r1;
;                     if (R) { const u32x4 rw = rr[bj]; r0 = (f32x4){bflo(rw.x), bfhi(rw.x), bflo(rw.y), bfhi(rw.y)}; r1 = (f32x4){bflo(rw.z), bfhi(rw.z), bflo(rw.w), bfhi(rw.w)}; }
;                     else { const float* rp = (row < 8192 ? src_p + off : src_s + (off - (size_t)8192 * D)) + 8 * bj; r0 = *(const f32x4*)rp; r1 = *(const f32x4*)(rp + 4); }
;                     const f32x4 o0 = r0 + acc[ai][bj][m][0] * sc, o1 = r1 + acc[ai][bj][m][1] * sc;
;                     sq += (o0[0] * o0[0] + o0[1] * o0[1]) + (o0[2] * o0[2] + o0[3] * o0[3]) + (o1[0] * o1[0] + o1[1] * o1[1]) + (o1[2] * o1[2] + o1[3] * o1[3]);
;                     w[bj].x = cvt_pk_bf16(o0[0], o0[1]); w[bj].y = cvt_pk_bf16(o0[2], o0[3]); w[bj].z = cvt_pk_bf16(o1[0], o1[1]); w[bj].w = cvt_pk_bf16(o1[2], o1[3]); }
;                 store_pair_lines(O, D, row, fr, col0, w[0], w[1]);
	s_nop 0
	v_mov_b32_e32 v60, v240
	s_nop 0
	v_mov_b64_e32 v[48:49], v[244:245]
	v_mov_b64_e32 v[50:51], v[246:247]
	v_lshl_add_u64 v[52:53], v[52:53], 0, v[146:147]
	v_mov_b64_e32 v[52:53], v[248:249]
	v_mov_b64_e32 v[54:55], v[250:251]
	s_nop 1
	v_mov_b32_e32 v65, 0
	v_mov_b32_e32 v66, 0
	v_mov_b32_e32 v67, 0
	v_mov_b32_e32 v68, 0
	v_mov_b32_e32 v61, 0
	v_mov_b32_e32 v62, 0
	v_mov_b32_e32 v63, 0
	v_mov_b32_e32 v64, 0
	v_fmamk_f32 v60, v60, 0x3a000000, v159
	v_rcp_f32_e32 v60, v60
	v_mov_b32_dpp v61, v48 row_ror:8 row_mask:0xf bank_mask:0xf
	v_mov_b32_dpp v65, v52 row_ror:8 row_mask:0xf bank_mask:0xf
	v_mov_b32_dpp v66, v53 row_ror:8 row_mask:0xf bank_mask:0xf
	v_mov_b32_dpp v67, v54 row_ror:8 row_mask:0xf bank_mask:0xf
	v_mov_b32_dpp v68, v55 row_ror:8 row_mask:0xf bank_mask:0xf
	v_mov_b32_dpp v62, v49 row_ror:8 row_mask:0xf bank_mask:0xf
	v_mov_b32_dpp v63, v50 row_ror:8 row_mask:0xf bank_mask:0xf
	v_mov_b32_dpp v64, v51 row_ror:8 row_mask:0xf bank_mask:0xf
	v_cndmask_b32_e64 v68, v68, v51, s[6:7]
	v_cndmask_b32_e64 v67, v67, v50, s[6:7]
	v_cndmask_b32_e64 v51, v66, v49, s[6:7]
	v_cndmask_b32_e64 v49, v65, v48, s[6:7]
	v_cndmask_b32_e64 v64, v55, v64, s[6:7]
	v_cndmask_b32_e64 v63, v54, v63, s[6:7]
	v_cndmask_b32_e64 v62, v53, v62, s[6:7]
	v_cndmask_b32_e64 v61, v52, v61, s[6:7]
	v_lshlrev_b32_e32 v48, 16, v49
	v_and_b32_e32 v49, 0xffff0000, v49
	v_lshlrev_b32_e32 v50, 16, v51
	v_and_b32_e32 v51, 0xffff0000, v51
	v_lshlrev_b32_e32 v52, 16, v67
	v_and_b32_e32 v53, 0xffff0000, v67
	v_lshlrev_b32_e32 v54, 16, v68
	v_and_b32_e32 v55, 0xffff0000, v68
	v_pk_fma_f32 v[46:47], v[46:47], v[60:61], v[50:51] op_sel_hi:[1,0,1]
	v_pk_fma_f32 v[44:45], v[44:45], v[60:61], v[48:49] op_sel_hi:[1,0,1]
	v_pk_fma_f32 v[42:43], v[42:43], v[60:61], v[54:55] op_sel_hi:[1,0,1]
	v_pk_fma_f32 v[40:41], v[40:41], v[60:61], v[52:53] op_sel_hi:[1,0,1]
	v_cvt_pk_bf16_f32 v48, v44, v45
	v_cvt_pk_bf16_f32 v49, v46, v47
	v_lshlrev_b32_e32 v44, 16, v63
	v_cvt_pk_bf16_f32 v50, v40, v41
	v_cvt_pk_bf16_f32 v51, v42, v43
	v_lshlrev_b32_e32 v40, 16, v61
	v_and_b32_e32 v41, 0xffff0000, v61
	v_lshlrev_b32_e32 v42, 16, v62
	v_and_b32_e32 v43, 0xffff0000, v62
	v_and_b32_e32 v45, 0xffff0000, v63
	v_lshlrev_b32_e32 v46, 16, v64
	v_and_b32_e32 v47, 0xffff0000, v64
	v_pk_fma_f32 v[38:39], v[38:39], v[60:61], v[42:43] op_sel_hi:[1,0,1]
	v_pk_fma_f32 v[36:37], v[36:37], v[60:61], v[40:41] op_sel_hi:[1,0,1]
	v_pk_fma_f32 v[34:35], v[34:35], v[60:61], v[46:47] op_sel_hi:[1,0,1]
	v_pk_fma_f32 v[32:33], v[32:33], v[60:61], v[44:45] op_sel_hi:[1,0,1]
	v_mov_b32_e32 v40, 0
	v_mov_b32_e32 v41, 0
	v_cvt_pk_bf16_f32 v36, v36, v37
	v_cvt_pk_bf16_f32 v37, v38, v39
	v_cvt_pk_bf16_f32 v38, v32, v33
	v_cvt_pk_bf16_f32 v39, v34, v35
	s_nop 0
	v_mov_b32_dpp v40, v48 row_ror:8 row_mask:0xf bank_mask:0xf
	v_mov_b32_dpp v41, v49 row_ror:8 row_mask:0xf bank_mask:0xf
	v_mov_b32_e32 v32, 0
	v_mov_b32_e32 v33, 0
	v_mov_b32_e32 v34, 0
	v_mov_b32_e32 v35, 0
	v_mov_b32_dpp v32, v36 row_ror:8 row_mask:0xf bank_mask:0xf
	v_mov_b32_dpp v33, v37 row_ror:8 row_mask:0xf bank_mask:0xf
	v_mov_b32_dpp v34, v38 row_ror:8 row_mask:0xf bank_mask:0xf
	v_mov_b32_dpp v35, v39 row_ror:8 row_mask:0xf bank_mask:0xf
	v_cndmask_b32_e64 v36, v36, v40, s[6:7]
	v_cndmask_b32_e64 v37, v37, v41, s[6:7]
	v_lshl_add_u64 v[40:41], s[8:9], 0, v[56:57]
	v_mov_b32_e32 v42, 0
	v_mov_b32_e32 v43, 0
	v_cndmask_b32_e64 v32, v32, v48, s[6:7]
	v_cndmask_b32_e64 v33, v33, v49, s[6:7]
	v_cndmask_b32_e64 v34, v34, v50, s[6:7]
	v_cndmask_b32_e64 v35, v35, v51, s[6:7]
	v_lshl_add_u64 v[40:41], v[40:41], 0, v[146:147]
	v_mov_b32_dpp v42, v50 row_ror:8 row_mask:0xf bank_mask:0xf
	v_mov_b32_dpp v43, v51 row_ror:8 row_mask:0xf bank_mask:0xf
	global_store_dwordx4 v[40:41], v[32:35], off
	v_cndmask_b32_e64 v38, v38, v42, s[6:7]
	v_cndmask_b32_e64 v39, v39, v43, s[6:7]
	v_lshl_add_u64 v[32:33], s[8:9], 0, v[58:59]
	v_lshl_add_u64 v[32:33], v[32:33], 0, v[146:147]
	global_store_dwordx4 v[32:33], v[36:39], off
	v_add_u32_e32 v32, 0xa0, v77
	v_ashrrev_i32_e32 v33, 31, v32
	v_lshlrev_b64 v[40:41], 12, v[32:33]
	v_lshl_add_u64 v[42:43], v[40:41], 0, s[36:37]
	s_waitcnt vmcnt(13)
	s_nop 0
	v_mov_b32_e32 v44, v204
	v_lshl_add_u64 v[32:33], s[16:17], 0, v[40:41]
	v_lshl_add_u64 v[36:37], s[16:17], 0, v[42:43]
	v_lshl_add_u64 v[32:33], v[32:33], 0, v[146:147]
	v_lshl_add_u64 v[36:37], v[36:37], 0, v[146:147]
	v_mov_b64_e32 v[32:33], v[208:209]
	v_mov_b64_e32 v[34:35], v[210:211]
	v_mov_b32_e32 v49, 0
	v_mov_b64_e32 v[36:37], v[212:213]
	v_mov_b64_e32 v[38:39], v[214:215]
	s_nop 1
	v_mov_b32_e32 v50, 0
	v_mov_b32_e32 v51, 0
	v_mov_b32_e32 v52, 0
	v_mov_b32_e32 v45, 0
	v_mov_b32_e32 v46, 0
	v_mov_b32_e32 v47, 0
	v_mov_b32_e32 v48, 0
	v_fmamk_f32 v44, v44, 0x3a000000, v159
	v_rcp_f32_e32 v44, v44
	v_mov_b32_dpp v45, v32 row_ror:8 row_mask:0xf bank_mask:0xf
	v_mov_b32_dpp v46, v33 row_ror:8 row_mask:0xf bank_mask:0xf
	v_mov_b32_dpp v49, v36 row_ror:8 row_mask:0xf bank_mask:0xf
	v_mov_b32_dpp v50, v37 row_ror:8 row_mask:0xf bank_mask:0xf
	v_mov_b32_dpp v51, v38 row_ror:8 row_mask:0xf bank_mask:0xf
	v_mov_b32_dpp v52, v39 row_ror:8 row_mask:0xf bank_mask:0xf
	v_mov_b32_dpp v47, v34 row_ror:8 row_mask:0xf bank_mask:0xf
	v_mov_b32_dpp v48, v35 row_ror:8 row_mask:0xf bank_mask:0xf
	v_cndmask_b32_e64 v52, v52, v35, s[6:7]
	v_cndmask_b32_e64 v51, v51, v34, s[6:7]
	v_cndmask_b32_e64 v35, v50, v33, s[6:7]
	v_cndmask_b32_e64 v33, v49, v32, s[6:7]
	v_cndmask_b32_e64 v48, v39, v48, s[6:7]
	v_cndmask_b32_e64 v47, v38, v47, s[6:7]
	v_cndmask_b32_e64 v46, v37, v46, s[6:7]
	v_cndmask_b32_e64 v45, v36, v45, s[6:7]
	v_lshlrev_b32_e32 v32, 16, v33
	v_and_b32_e32 v33, 0xffff0000, v33
; __device__ __forceinline__ unsigned cvt_pk_bf16(float lo, float hi) { unsigned r; asm volatile("v_cvt_pk_bf16_f32 %0, %1, %2" : "=v"(r) : "v"(lo), "v"(hi)); return r; }
; __device__ __forceinline__ float bflo(unsigned w) { return __uint_as_float(w << 16); }
; __device__ __forceinline__ float bfhi(unsigned w) { return __uint_as_float(w & 0xffff0000u); }
;     __device__ __forceinline__ void operator()(const f32x4 (&acc)[2][2][4][2], const Unit& u, int wr, int wc, int fr, int fq) const {
;     ...
;             for (int m = 0; m < 4; ++m) { const int row = row0 + ai * HALF + m * 16; const size_t off = (size_t)row * D + col0; float sq = 0.f; u32x4 w[2];
;                 const float sc = rsin ? __builtin_amdgcn_rcpf(rsin[row] * (1.f / D) + EPS) : 1.0f;
;                 u32x4 rr[2]; if (R) load_pair_lines(R, D, row, fr, col0, rr[0], rr[1]);
; #pragma unroll
;                 for (int bj = 0; bj < 2; ++bj) { f32x4 r0, r1;
;                     if (R) { const u32x4 rw = rr[bj]; r0 = (f32x4){bflo(rw.x), bfhi(rw.x), bflo(rw.y), bfhi(rw.y)}; r1 = (f32x4){bflo(rw.z), bfhi(rw.z), bflo(rw.w), bfhi(rw.w)}; }
;                     else { const float* rp = (row < 8192 ? src_p + off : src_s + (off - (size_t)8192 * D)) + 8 * bj; r0 = *(const f32x4*)rp; r1 = *(const f32x4*)(rp + 4); }
;                     const f32x4 o0 = r0 + acc[ai][bj][m][0] * sc, o1 = r1 + acc[ai][bj][m][1] * sc;
;                     sq += (o0[0] * o0[0] + o0[1] * o0[1]) + (o0[2] * o0[2] + o0[3] * o0[3]) + (o1[0] * o1[0] + o1[1] * o1[1]) + (o1[2] * o1[2] + o1[3] * o1[3]);
;                     w[bj].x = cvt_pk_bf16(o0[0], o0[1]); w[bj].y = cvt_pk_bf16(o0[2], o0[3]); w[bj].z = cvt_pk_bf16(o1[0], o1[1]); w[bj].w = cvt_pk_bf16(o1[2], o1[3]); }
;                 store_pair_lines(O, D, row, fr, col0, w[0], w[1]);
	v_lshlrev_b32_e32 v34, 16, v35
	v_and_b32_e32 v35, 0xffff0000, v35
	v_lshlrev_b32_e32 v36, 16, v51
	v_and_b32_e32 v37, 0xffff0000, v51
	v_lshlrev_b32_e32 v38, 16, v52
	v_and_b32_e32 v39, 0xffff0000, v52
	v_pk_fma_f32 v[30:31], v[30:31], v[44:45], v[34:35] op_sel_hi:[1,0,1]
	v_pk_fma_f32 v[28:29], v[28:29], v[44:45], v[32:33] op_sel_hi:[1,0,1]
	v_pk_fma_f32 v[26:27], v[26:27], v[44:45], v[38:39] op_sel_hi:[1,0,1]
	v_pk_fma_f32 v[24:25], v[24:25], v[44:45], v[36:37] op_sel_hi:[1,0,1]
	v_cvt_pk_bf16_f32 v32, v28, v29
	v_cvt_pk_bf16_f32 v33, v30, v31
	v_lshlrev_b32_e32 v28, 16, v47
	v_cvt_pk_bf16_f32 v34, v24, v25
	v_cvt_pk_bf16_f32 v35, v26, v27
	v_lshlrev_b32_e32 v24, 16, v45
	v_and_b32_e32 v25, 0xffff0000, v45
	v_lshlrev_b32_e32 v26, 16, v46
	v_and_b32_e32 v27, 0xffff0000, v46
	v_and_b32_e32 v29, 0xffff0000, v47
	v_lshlrev_b32_e32 v30, 16, v48
	v_and_b32_e32 v31, 0xffff0000, v48
	v_pk_fma_f32 v[22:23], v[22:23], v[44:45], v[26:27] op_sel_hi:[1,0,1]
	v_pk_fma_f32 v[20:21], v[20:21], v[44:45], v[24:25] op_sel_hi:[1,0,1]
	v_pk_fma_f32 v[18:19], v[18:19], v[44:45], v[30:31] op_sel_hi:[1,0,1]
	v_pk_fma_f32 v[16:17], v[16:17], v[44:45], v[28:29] op_sel_hi:[1,0,1]
	v_mov_b32_e32 v24, 0
	v_mov_b32_e32 v25, 0
	v_cvt_pk_bf16_f32 v20, v20, v21
	v_cvt_pk_bf16_f32 v21, v22, v23
	v_cvt_pk_bf16_f32 v22, v16, v17
	v_cvt_pk_bf16_f32 v23, v18, v19
	s_nop 0
	v_mov_b32_dpp v24, v32 row_ror:8 row_mask:0xf bank_mask:0xf
	v_mov_b32_dpp v25, v33 row_ror:8 row_mask:0xf bank_mask:0xf
	v_mov_b32_e32 v16, 0
	v_mov_b32_e32 v17, 0
	v_mov_b32_e32 v18, 0
	v_mov_b32_e32 v19, 0
	v_mov_b32_dpp v16, v20 row_ror:8 row_mask:0xf bank_mask:0xf
	v_mov_b32_dpp v17, v21 row_ror:8 row_mask:0xf bank_mask:0xf
	v_mov_b32_dpp v18, v22 row_ror:8 row_mask:0xf bank_mask:0xf
	v_mov_b32_dpp v19, v23 row_ror:8 row_mask:0xf bank_mask:0xf
	v_cndmask_b32_e64 v20, v20, v24, s[6:7]
	v_cndmask_b32_e64 v21, v21, v25, s[6:7]
	v_lshl_add_u64 v[24:25], s[8:9], 0, v[40:41]
	v_mov_b32_e32 v26, 0
	v_mov_b32_e32 v27, 0
	v_cndmask_b32_e64 v16, v16, v32, s[6:7]
	v_cndmask_b32_e64 v17, v17, v33, s[6:7]
	v_cndmask_b32_e64 v18, v18, v34, s[6:7]
	v_cndmask_b32_e64 v19, v19, v35, s[6:7]
	v_lshl_add_u64 v[24:25], v[24:25], 0, v[146:147]
	v_mov_b32_dpp v26, v34 row_ror:8 row_mask:0xf bank_mask:0xf
	v_mov_b32_dpp v27, v35 row_ror:8 row_mask:0xf bank_mask:0xf
	global_store_dwordx4 v[24:25], v[16:19], off
	v_cndmask_b32_e64 v22, v22, v26, s[6:7]
	v_cndmask_b32_e64 v23, v23, v27, s[6:7]
	v_lshl_add_u64 v[16:17], s[8:9], 0, v[42:43]
	v_lshl_add_u64 v[16:17], v[16:17], 0, v[146:147]
	global_store_dwordx4 v[16:17], v[20:23], off
	v_add_u32_e32 v16, 0xb0, v77
	v_ashrrev_i32_e32 v17, 31, v16
	v_lshlrev_b64 v[24:25], 12, v[16:17]
	v_lshl_add_u64 v[26:27], v[24:25], 0, s[36:37]
	s_waitcnt vmcnt(10)
	s_nop 0
	v_mov_b32_e32 v28, v205
	v_lshl_add_u64 v[16:17], s[16:17], 0, v[24:25]
	v_lshl_add_u64 v[20:21], s[16:17], 0, v[26:27]
	v_lshl_add_u64 v[16:17], v[16:17], 0, v[146:147]
	v_lshl_add_u64 v[20:21], v[20:21], 0, v[146:147]
	v_mov_b64_e32 v[16:17], v[216:217]
	v_mov_b64_e32 v[18:19], v[218:219]
	v_mov_b32_e32 v33, 0
	v_mov_b64_e32 v[20:21], v[220:221]
	v_mov_b64_e32 v[22:23], v[222:223]
	s_nop 1
	v_mov_b32_e32 v34, 0
	v_mov_b32_e32 v35, 0
	v_mov_b32_e32 v36, 0
	v_mov_b32_e32 v29, 0
	v_mov_b32_e32 v30, 0
	v_mov_b32_e32 v31, 0
	v_mov_b32_e32 v32, 0
	v_fmamk_f32 v28, v28, 0x3a000000, v159
	v_rcp_f32_e32 v28, v28
	v_mov_b32_dpp v29, v16 row_ror:8 row_mask:0xf bank_mask:0xf
	v_mov_b32_dpp v30, v17 row_ror:8 row_mask:0xf bank_mask:0xf
	v_mov_b32_dpp v33, v20 row_ror:8 row_mask:0xf bank_mask:0xf
	v_mov_b32_dpp v34, v21 row_ror:8 row_mask:0xf bank_mask:0xf
	v_mov_b32_dpp v35, v22 row_ror:8 row_mask:0xf bank_mask:0xf
	v_mov_b32_dpp v36, v23 row_ror:8 row_mask:0xf bank_mask:0xf
	v_mov_b32_dpp v31, v18 row_ror:8 row_mask:0xf bank_mask:0xf
	v_mov_b32_dpp v32, v19 row_ror:8 row_mask:0xf bank_mask:0xf
	v_cndmask_b32_e64 v36, v36, v19, s[6:7]
	v_cndmask_b32_e64 v35, v35, v18, s[6:7]
	v_cndmask_b32_e64 v19, v34, v17, s[6:7]
	v_cndmask_b32_e64 v17, v33, v16, s[6:7]
	v_cndmask_b32_e64 v32, v23, v32, s[6:7]
	v_cndmask_b32_e64 v31, v22, v31, s[6:7]
	v_cndmask_b32_e64 v30, v21, v30, s[6:7]
	v_cndmask_b32_e64 v29, v20, v29, s[6:7]
	v_lshlrev_b32_e32 v16, 16, v17
	v_and_b32_e32 v17, 0xffff0000, v17
	v_lshlrev_b32_e32 v18, 16, v19
	v_and_b32_e32 v19, 0xffff0000, v19
	v_lshlrev_b32_e32 v20, 16, v35
	v_and_b32_e32 v21, 0xffff0000, v35
	v_lshlrev_b32_e32 v22, 16, v36
	v_and_b32_e32 v23, 0xffff0000, v36
	v_pk_fma_f32 v[14:15], v[14:15], v[28:29], v[18:19] op_sel_hi:[1,0,1]
	v_pk_fma_f32 v[12:13], v[12:13], v[28:29], v[16:17] op_sel_hi:[1,0,1]
	v_pk_fma_f32 v[10:11], v[10:11], v[28:29], v[22:23] op_sel_hi:[1,0,1]
	v_pk_fma_f32 v[8:9], v[8:9], v[28:29], v[20:21] op_sel_hi:[1,0,1]
	v_cvt_pk_bf16_f32 v16, v12, v13
	v_cvt_pk_bf16_f32 v17, v14, v15
	v_lshlrev_b32_e32 v12, 16, v31
	v_cvt_pk_bf16_f32 v18, v8, v9
	v_cvt_pk_bf16_f32 v19, v10, v11
	v_lshlrev_b32_e32 v8, 16, v29
	v_and_b32_e32 v9, 0xffff0000, v29
	v_lshlrev_b32_e32 v10, 16, v30
	v_and_b32_e32 v11, 0xffff0000, v30
	v_and_b32_e32 v13, 0xffff0000, v31
	v_lshlrev_b32_e32 v14, 16, v32
	v_and_b32_e32 v15, 0xffff0000, v32
	v_pk_fma_f32 v[6:7], v[6:7], v[28:29], v[10:11] op_sel_hi:[1,0,1]
	v_pk_fma_f32 v[4:5], v[4:5], v[28:29], v[8:9] op_sel_hi:[1,0,1]
	v_pk_fma_f32 v[2:3], v[2:3], v[28:29], v[14:15] op_sel_hi:[1,0,1]
	v_pk_fma_f32 v[0:1], v[0:1], v[28:29], v[12:13] op_sel_hi:[1,0,1]
	v_mov_b32_e32 v8, 0
	v_mov_b32_e32 v9, 0
	v_cvt_pk_bf16_f32 v4, v4, v5
	v_cvt_pk_bf16_f32 v5, v6, v7
	v_cvt_pk_bf16_f32 v6, v0, v1
	v_cvt_pk_bf16_f32 v7, v2, v3
	s_nop 0
	v_mov_b32_dpp v8, v16 row_ror:8 row_mask:0xf bank_mask:0xf
	v_mov_b32_dpp v9, v17 row_ror:8 row_mask:0xf bank_mask:0xf
	v_mov_b32_e32 v0, 0
	v_mov_b32_e32 v1, 0
	v_mov_b32_e32 v2, 0
	v_mov_b32_e32 v3, 0
	v_mov_b32_dpp v0, v4 row_ror:8 row_mask:0xf bank_mask:0xf
	v_mov_b32_dpp v1, v5 row_ror:8 row_mask:0xf bank_mask:0xf
	v_mov_b32_dpp v2, v6 row_ror:8 row_mask:0xf bank_mask:0xf
	v_mov_b32_dpp v3, v7 row_ror:8 row_mask:0xf bank_mask:0xf
	v_cndmask_b32_e64 v4, v4, v8, s[6:7]
	v_cndmask_b32_e64 v5, v5, v9, s[6:7]
	v_lshl_add_u64 v[8:9], s[8:9], 0, v[24:25]
	v_mov_b32_e32 v10, 0
	v_mov_b32_e32 v11, 0
	v_cndmask_b32_e64 v0, v0, v16, s[6:7]
	v_cndmask_b32_e64 v1, v1, v17, s[6:7]
	v_cndmask_b32_e64 v2, v2, v18, s[6:7]
	v_cndmask_b32_e64 v3, v3, v19, s[6:7]
	v_lshl_add_u64 v[8:9], v[8:9], 0, v[146:147]
	v_mov_b32_dpp v10, v18 row_ror:8 row_mask:0xf bank_mask:0xf
	v_mov_b32_dpp v11, v19 row_ror:8 row_mask:0xf bank_mask:0xf
	global_store_dwordx4 v[8:9], v[0:3], off
	v_cndmask_b32_e64 v6, v6, v10, s[6:7]
	v_cndmask_b32_e64 v7, v7, v11, s[6:7]
	v_lshl_add_u64 v[0:1], s[8:9], 0, v[26:27]
	v_lshl_add_u64 v[0:1], v[0:1], 0, v[146:147]
	global_store_dwordx4 v[0:1], v[4:7], off
	s_cbranch_vccz .LBB0_798
	s_waitcnt vmcnt(0)
	s_cmpk_gt_u32 s56, 0xff
	s_cbranch_scc1 .LBB0_810
	s_barrier

; #define PG8_STAGE(bufoff, gbase, voff) do { _Pragma("unroll") for (int _i = 0; _i < 2; ++_i) \
;         __builtin_amdgcn_global_load_lds((const unsigned*)((const char*)(gbase) + (voff)[_i]), (LAS unsigned*)(lds + (bufoff) + ldsw + _i * 8192), 16, 0, 0); } while (0)
; #define PG8_LDA(dst, b, h) do { _Pragma("unroll") for (int m = 0; m < 4; ++m) _Pragma("unroll") for (int k = 0; k < 2; ++k) dst[m][k] = *(const LAS bf16x8*)(lds + PG8_SA(b, h) + aoff + m * 2048 + k * 1024); } while (0)
; #define PG8_LDB(dst, b, h) do { _Pragma("unroll") for (int n = 0; n < 2; ++n) _Pragma("unroll") for (int k = 0; k < 2; ++k) dst[n][k] = *(const LAS bf16x8*)(lds + PG8_SB(b, h) + boff + n * 2048 + k * 1024); } while (0)
; #define PG8_MMA(ai, bj, At, Bt) do { __builtin_amdgcn_s_setprio(1); _Pragma("unroll") for (int m = 0; m < 4; ++m) _Pragma("unroll") for (int n = 0; n < 2; ++n) _Pragma("unroll") for (int k = 0; k < 2; ++k) \
;         acc[ai][bj][m][n] = __builtin_amdgcn_mfma_f32_16x16x32_bf16(Bt[n][k], At[m][k], acc[ai][bj][m][n], 0, 0, 0); __builtin_amdgcn_s_setprio(0); } while (0)
; #define PG8_WAIT_L(n) asm volatile("s_waitcnt lgkmcnt(" #n ")" ::: "memory")
; #define PG8_BAR __builtin_amdgcn_s_barrier()
; template <class Epi>
; __device__ __forceinline__ void gemm_phase(LAS unsigned char* lds, const Gemm g, const StaticOrder& S, const Epi& E) {
;     ...
;         const char* nA = has_next ? (const char*)g.A + (size_t)nxt.pm * tstep : cA; const char* nB = has_next ? (const char*)g.Bt + (size_t)nxt.pn * tstep : cB;
;         for (int t = 0; t < nt; t += 2) {
;             const bool last = (t == nt - 2);
;             const char* a1 = cA + (size_t)(t + 1) * kstep;
;             const char* a2 = last ? nA : cA + (size_t)(t + 2) * kstep; const char* b2 = last ? nB : cB + (size_t)(t + 2) * kstep;
;             const char* a3 = a2 + kstep; const char* b3 = b2 + kstep;
;             PG8_LDB(B0, 0, 0); PG8_SCHED; PG8_LDA(At, 0, 0); PG8_STAGE(PG8_SA(1, 1), a1 + hstep, voffA);
;             PG8_WAIT_L(8); PG8_BAR; PG8_WAIT_L(0); PG8_MMA(0, 0, At, B0); PG8_BAR; PG8_SCHED;
;             PG8_LDB(B1, 0, 1); PG8_STAGE(PG8_SB(0, 0), b2, voffB0);
;             PG8_BAR; PG8_WAIT_L(0); PG8_MMA(0, 1, At, B1); PG8_BAR;
;             PG8_LDA(At, 0, 1); PG8_STAGE(PG8_SA(0, 0), a2, voffA);
;             PG8_BAR; PG8_WAIT_L(0); PG8_MMA(1, 0, At, B0); PG8_BAR; PG8_SCHED;
.LBB0_882:
	ds_read_b128 v[32:35], v177
	ds_read_b128 v[40:43], v177 offset:1024
	ds_read_b128 v[48:51], v177 offset:2048
	ds_read_b128 v[52:55], v177 offset:3072
	s_add_u32 s33, s60, 0xfff80080
	s_addc_u32 s62, s61, -1
	s_cmp_eq_u32 s86, 28
	s_cselect_b32 s63, s49, s62
	s_cselect_b32 s62, s57, s33
	s_cselect_b32 s65, s47, s85
	s_cselect_b32 s64, s83, s84
	v_lshl_add_u64 v[170:171], s[60:61], 0, v[156:157]
	s_add_i32 m0, s59, 0xc000
	ds_read_b128 v[162:165], v178
	ds_read_b128 v[166:169], v178 offset:1024
	ds_read_b128 v[182:185], v178 offset:2048
	ds_read_b128 v[186:189], v178 offset:3072
	ds_read_b128 v[190:193], v178 offset:4096
	ds_read_b128 v[194:197], v178 offset:5120
	ds_read_b128 v[198:201], v178 offset:6144
	ds_read_b128 v[204:207], v178 offset:7168
	global_load_lds_dwordx4 v[170:171], off
	v_lshl_add_u64 v[170:171], s[60:61], 0, v[158:159]
	s_add_i32 m0, s59, 0xe000
	s_nop 0
	global_load_lds_dwordx4 v[170:171], off
	s_waitcnt lgkmcnt(8)
	s_barrier
	s_waitcnt lgkmcnt(0)
	s_waitcnt lgkmcnt(0)
	v_mfma_f32_16x16x32_bf16 v[140:143], v[32:35], v[162:165], v[140:143]
	v_mfma_f32_16x16x32_bf16 v[136:139], v[48:51], v[162:165], v[136:139]
	v_mfma_f32_16x16x32_bf16 v[124:127], v[32:35], v[182:185], v[124:127]
	v_mfma_f32_16x16x32_bf16 v[120:123], v[48:51], v[182:185], v[120:123]
	v_mfma_f32_16x16x32_bf16 v[108:111], v[32:35], v[190:193], v[108:111]
	v_mfma_f32_16x16x32_bf16 v[104:107], v[48:51], v[190:193], v[104:107]
	v_mfma_f32_16x16x32_bf16 v[92:95], v[32:35], v[198:201], v[92:95]
	v_mfma_f32_16x16x32_bf16 v[88:91], v[48:51], v[198:201], v[88:91]
	v_mfma_f32_16x16x32_bf16 v[140:143], v[40:43], v[166:169], v[140:143]
	v_mfma_f32_16x16x32_bf16 v[136:139], v[52:55], v[166:169], v[136:139]
	v_mfma_f32_16x16x32_bf16 v[124:127], v[40:43], v[186:189], v[124:127]
	v_mfma_f32_16x16x32_bf16 v[120:123], v[52:55], v[186:189], v[120:123]
	v_mfma_f32_16x16x32_bf16 v[108:111], v[40:43], v[194:197], v[108:111]
	v_mfma_f32_16x16x32_bf16 v[104:107], v[52:55], v[194:197], v[104:107]
	v_mfma_f32_16x16x32_bf16 v[92:95], v[40:43], v[204:207], v[92:95]
	v_mfma_f32_16x16x32_bf16 v[88:91], v[52:55], v[204:207], v[88:91]
	s_barrier
	s_add_i32 s33, s81, s69
	v_lshl_add_u64 v[170:171], s[64:65], 0, v[146:147]
	s_mov_b32 m0, s33
	ds_read_b128 v[208:211], v179
	ds_read_b128 v[212:215], v179 offset:1024
	ds_read_b128 v[216:219], v179 offset:2048
	ds_read_b128 v[220:223], v179 offset:3072
	global_load_lds_dwordx4 v[170:171], off
	v_lshl_add_u64 v[224:225], s[64:65], 0, v[152:153]
	s_add_i32 m0, s33, 0x2000
	s_nop 0
	global_load_lds_dwordx4 v[224:225], off
	s_barrier
	s_waitcnt lgkmcnt(0)
	s_waitcnt lgkmcnt(0)
	v_mfma_f32_16x16x32_bf16 v[132:135], v[208:211], v[162:165], v[132:135]
	v_mfma_f32_16x16x32_bf16 v[128:131], v[216:219], v[162:165], v[128:131]
	v_mfma_f32_16x16x32_bf16 v[116:119], v[208:211], v[182:185], v[116:119]
	v_mfma_f32_16x16x32_bf16 v[112:115], v[216:219], v[182:185], v[112:115]
	v_mfma_f32_16x16x32_bf16 v[100:103], v[208:211], v[190:193], v[100:103]
	v_mfma_f32_16x16x32_bf16 v[96:99], v[216:219], v[190:193], v[96:99]
	v_mfma_f32_16x16x32_bf16 v[84:87], v[208:211], v[198:201], v[84:87]
	v_mfma_f32_16x16x32_bf16 v[80:83], v[216:219], v[198:201], v[80:83]
	v_mfma_f32_16x16x32_bf16 v[132:135], v[212:215], v[166:169], v[132:135]
	v_mfma_f32_16x16x32_bf16 v[128:131], v[220:223], v[166:169], v[128:131]
	v_mfma_f32_16x16x32_bf16 v[116:119], v[212:215], v[186:189], v[116:119]
	v_mfma_f32_16x16x32_bf16 v[112:115], v[220:223], v[186:189], v[112:115]
	v_mfma_f32_16x16x32_bf16 v[100:103], v[212:215], v[194:197], v[100:103]
	v_mfma_f32_16x16x32_bf16 v[96:99], v[220:223], v[194:197], v[96:99]
	v_mfma_f32_16x16x32_bf16 v[84:87], v[212:215], v[204:207], v[84:87]
	v_mfma_f32_16x16x32_bf16 v[80:83], v[220:223], v[204:207], v[80:83]
	s_mov_b32 m0, s59
	v_lshl_add_u64 v[226:227], s[62:63], 0, v[144:145]
	s_barrier
	ds_read_b128 v[162:165], v178 offset:16384
	ds_read_b128 v[166:169], v178 offset:17408
	ds_read_b128 v[182:185], v178 offset:18432
	ds_read_b128 v[186:189], v178 offset:19456
	ds_read_b128 v[190:193], v178 offset:20480
	ds_read_b128 v[194:197], v178 offset:21504
	ds_read_b128 v[198:201], v178 offset:22528
	ds_read_b128 v[204:207], v178 offset:23552
	global_load_lds_dwordx4 v[226:227], off
	v_lshl_add_u64 v[228:229], s[62:63], 0, v[150:151]
	s_mov_b32 m0, s70
	s_nop 0
	global_load_lds_dwordx4 v[228:229], off
	s_barrier
	s_waitcnt lgkmcnt(0)
	s_waitcnt lgkmcnt(0)
	v_mfma_f32_16x16x32_bf16 v[76:79], v[32:35], v[162:165], v[76:79]
	v_mfma_f32_16x16x32_bf16 v[72:75], v[48:51], v[162:165], v[72:75]
	v_mfma_f32_16x16x32_bf16 v[60:63], v[32:35], v[182:185], v[60:63]
	v_mfma_f32_16x16x32_bf16 v[56:59], v[48:51], v[182:185], v[56:59]
	v_mfma_f32_16x16x32_bf16 v[28:31], v[32:35], v[190:193], v[28:31]
	v_mfma_f32_16x16x32_bf16 v[24:27], v[48:51], v[190:193], v[24:27]
	v_mfma_f32_16x16x32_bf16 v[12:15], v[32:35], v[198:201], v[12:15]
	v_mfma_f32_16x16x32_bf16 v[8:11], v[48:51], v[198:201], v[8:11]
	v_mfma_f32_16x16x32_bf16 v[76:79], v[40:43], v[166:169], v[76:79]
	v_mfma_f32_16x16x32_bf16 v[72:75], v[52:55], v[166:169], v[72:75]
	v_mfma_f32_16x16x32_bf16 v[60:63], v[40:43], v[186:189], v[60:63]
	v_mfma_f32_16x16x32_bf16 v[56:59], v[52:55], v[186:189], v[56:59]
	v_mfma_f32_16x16x32_bf16 v[28:31], v[40:43], v[194:197], v[28:31]
	v_mfma_f32_16x16x32_bf16 v[24:27], v[52:55], v[194:197], v[24:27]
	v_mfma_f32_16x16x32_bf16 v[12:15], v[40:43], v[204:207], v[12:15]
	v_mfma_f32_16x16x32_bf16 v[8:11], v[52:55], v[204:207], v[8:11]
	s_barrier
; #define PG8_STAGE(bufoff, gbase, voff) do { _Pragma("unroll") for (int _i = 0; _i < 2; ++_i) \
;         __builtin_amdgcn_global_load_lds((const unsigned*)((const char*)(gbase) + (voff)[_i]), (LAS unsigned*)(lds + (bufoff) + ldsw + _i * 8192), 16, 0, 0); } while (0)
; #define PG8_LDA(dst, b, h) do { _Pragma("unroll") for (int m = 0; m < 4; ++m) _Pragma("unroll") for (int k = 0; k < 2; ++k) dst[m][k] = *(const LAS bf16x8*)(lds + PG8_SA(b, h) + aoff + m * 2048 + k * 1024); } while (0)
; #define PG8_LDB(dst, b, h) do { _Pragma("unroll") for (int n = 0; n < 2; ++n) _Pragma("unroll") for (int k = 0; k < 2; ++k) dst[n][k] = *(const LAS bf16x8*)(lds + PG8_SB(b, h) + boff + n * 2048 + k * 1024); } while (0)
; #define PG8_MMA(ai, bj, At, Bt) do { __builtin_amdgcn_s_setprio(1); _Pragma("unroll") for (int m = 0; m < 4; ++m) _Pragma("unroll") for (int n = 0; n < 2; ++n) _Pragma("unroll") for (int k = 0; k < 2; ++k) \
;         acc[ai][bj][m][n] = __builtin_amdgcn_mfma_f32_16x16x32_bf16(Bt[n][k], At[m][k], acc[ai][bj][m][n], 0, 0, 0); __builtin_amdgcn_s_setprio(0); } while (0)
; #define PG8_WAIT_V(n) asm volatile("s_waitcnt vmcnt(" #n ")" ::: "memory")
; #define PG8_WAIT_L(n) asm volatile("s_waitcnt lgkmcnt(" #n ")" ::: "memory")
; #define PG8_BAR __builtin_amdgcn_s_barrier()
; #define PG8_SCHED __builtin_amdgcn_sched_barrier(0)
; template <class Epi>
; __device__ __forceinline__ void gemm_phase(LAS unsigned char* lds, const Gemm g, const StaticOrder& S, const Epi& E) {
;     ...
;             PG8_STAGE(PG8_SB(0, 1), b2, voffB1);
;             PG8_WAIT_V(6); PG8_BAR; PG8_MMA(1, 1, At, B1); PG8_BAR;
;             PG8_LDB(B0, 1, 0); PG8_SCHED; PG8_LDA(At, 1, 0); PG8_STAGE(PG8_SA(0, 1), a2 + hstep, voffA);
;             PG8_WAIT_L(8); PG8_BAR; PG8_WAIT_L(0); PG8_MMA(0, 0, At, B0); PG8_BAR; PG8_SCHED;
;             PG8_LDB(B1, 1, 1); PG8_STAGE(PG8_SB(1, 0), b3, voffB0);
;             PG8_BAR; PG8_WAIT_L(0); PG8_MMA(0, 1, At, B1); PG8_BAR;
;             PG8_LDA(At, 1, 1); PG8_STAGE(PG8_SA(1, 0), a3, voffA);
;             PG8_BAR; PG8_WAIT_L(0); PG8_MMA(1, 0, At, B0); PG8_BAR; PG8_SCHED;
	s_add_i32 s33, s82, s69
	v_lshl_add_u64 v[230:231], s[64:65], 0, v[148:149]
	s_mov_b32 m0, s33
	v_lshl_add_u64 v[232:233], s[64:65], 0, v[154:155]
	global_load_lds_dwordx4 v[230:231], off
	s_add_i32 m0, s33, 0x2000
	s_nop 0
	global_load_lds_dwordx4 v[232:233], off
	s_waitcnt vmcnt(6)
	s_barrier
	v_mfma_f32_16x16x32_bf16 v[44:47], v[208:211], v[182:185], v[44:47]
	v_mfma_f32_16x16x32_bf16 v[36:39], v[216:219], v[182:185], v[36:39]
	v_mfma_f32_16x16x32_bf16 v[20:23], v[208:211], v[190:193], v[20:23]
	v_mfma_f32_16x16x32_bf16 v[16:19], v[216:219], v[190:193], v[16:19]
	v_mfma_f32_16x16x32_bf16 v[4:7], v[208:211], v[198:201], v[4:7]
	v_mfma_f32_16x16x32_bf16 v[0:3], v[216:219], v[198:201], v[0:3]
	v_mfma_f32_16x16x32_bf16 v[32:35], v[208:211], v[162:165], v[68:71]
	v_mfma_f32_16x16x32_bf16 v[40:43], v[216:219], v[162:165], v[64:67]
	v_mfma_f32_16x16x32_bf16 v[44:47], v[212:215], v[186:189], v[44:47]
	v_mfma_f32_16x16x32_bf16 v[36:39], v[220:223], v[186:189], v[36:39]
	v_mfma_f32_16x16x32_bf16 v[20:23], v[212:215], v[194:197], v[20:23]
	v_mfma_f32_16x16x32_bf16 v[16:19], v[220:223], v[194:197], v[16:19]
	v_mfma_f32_16x16x32_bf16 v[4:7], v[212:215], v[204:207], v[4:7]
	v_mfma_f32_16x16x32_bf16 v[0:3], v[220:223], v[204:207], v[0:3]
	v_mfma_f32_16x16x32_bf16 v[32:35], v[212:215], v[166:169], v[32:35]
	v_mfma_f32_16x16x32_bf16 v[40:43], v[220:223], v[166:169], v[40:43]
	s_add_i32 s33, 0, 0x18000
	v_add_u32_e32 v68, s33, v173
	s_barrier
	ds_read_b128 v[48:51], v68
	ds_read_b128 v[52:55], v68 offset:1024
	ds_read_b128 v[64:67], v68 offset:2048
	ds_read_b128 v[68:71], v68 offset:3072
	s_add_u32 s62, s62, 0x80000
	s_addc_u32 s63, s63, 0
	s_mov_b32 m0, s71
	v_lshl_add_u64 v[208:209], s[62:63], 0, v[144:145]
	ds_read_b128 v[162:165], v178 offset:32768
	ds_read_b128 v[166:169], v178 offset:33792
	ds_read_b128 v[182:185], v178 offset:34816
	ds_read_b128 v[186:189], v178 offset:35840
	ds_read_b128 v[190:193], v178 offset:36864
	ds_read_b128 v[194:197], v178 offset:37888
	ds_read_b128 v[198:201], v178 offset:38912
	ds_read_b128 v[204:207], v178 offset:39936
	global_load_lds_dwordx4 v[208:209], off
	v_lshl_add_u64 v[208:209], s[62:63], 0, v[150:151]
	s_mov_b32 m0, s72
	s_nop 0
	global_load_lds_dwordx4 v[208:209], off
	s_waitcnt lgkmcnt(8)
	s_barrier
	s_waitcnt lgkmcnt(0)
	s_waitcnt lgkmcnt(0)
	v_mfma_f32_16x16x32_bf16 v[140:143], v[48:51], v[162:165], v[140:143]
	v_mfma_f32_16x16x32_bf16 v[136:139], v[64:67], v[162:165], v[136:139]
	v_mfma_f32_16x16x32_bf16 v[124:127], v[48:51], v[182:185], v[124:127]
	v_mfma_f32_16x16x32_bf16 v[120:123], v[64:67], v[182:185], v[120:123]
	v_mfma_f32_16x16x32_bf16 v[108:111], v[48:51], v[190:193], v[108:111]
	v_mfma_f32_16x16x32_bf16 v[104:107], v[64:67], v[190:193], v[104:107]
	v_mfma_f32_16x16x32_bf16 v[92:95], v[48:51], v[198:201], v[92:95]
	v_mfma_f32_16x16x32_bf16 v[88:91], v[64:67], v[198:201], v[88:91]
	v_mfma_f32_16x16x32_bf16 v[140:143], v[52:55], v[166:169], v[140:143]
	v_mfma_f32_16x16x32_bf16 v[136:139], v[68:71], v[166:169], v[136:139]
	v_mfma_f32_16x16x32_bf16 v[124:127], v[52:55], v[186:189], v[124:127]
	v_mfma_f32_16x16x32_bf16 v[120:123], v[68:71], v[186:189], v[120:123]
	v_mfma_f32_16x16x32_bf16 v[108:111], v[52:55], v[194:197], v[108:111]
	v_mfma_f32_16x16x32_bf16 v[104:107], v[68:71], v[194:197], v[104:107]
	v_mfma_f32_16x16x32_bf16 v[92:95], v[52:55], v[204:207], v[92:95]
	v_mfma_f32_16x16x32_bf16 v[88:91], v[68:71], v[204:207], v[88:91]
	s_barrier
	s_add_i32 s62, 0, 0x1c000
	s_add_i32 s33, s33, s69
	v_add_u32_e32 v181, s62, v173
	v_lshl_add_u64 v[170:171], v[170:171], 0, s[42:43]
	s_mov_b32 m0, s33
	ds_read_b128 v[208:211], v181
	ds_read_b128 v[212:215], v181 offset:1024
	ds_read_b128 v[216:219], v181 offset:2048
	ds_read_b128 v[220:223], v181 offset:3072
	global_load_lds_dwordx4 v[170:171], off
	v_lshl_add_u64 v[170:171], v[224:225], 0, s[42:43]
	s_add_i32 m0, s33, 0x2000
	s_nop 0
	global_load_lds_dwordx4 v[170:171], off
	s_barrier
	s_waitcnt lgkmcnt(0)
	s_waitcnt lgkmcnt(0)
	v_mfma_f32_16x16x32_bf16 v[132:135], v[208:211], v[162:165], v[132:135]
	v_mfma_f32_16x16x32_bf16 v[128:131], v[216:219], v[162:165], v[128:131]
	v_mfma_f32_16x16x32_bf16 v[116:119], v[208:211], v[182:185], v[116:119]
	v_mfma_f32_16x16x32_bf16 v[112:115], v[216:219], v[182:185], v[112:115]
	v_mfma_f32_16x16x32_bf16 v[100:103], v[208:211], v[190:193], v[100:103]
	v_mfma_f32_16x16x32_bf16 v[96:99], v[216:219], v[190:193], v[96:99]
	v_mfma_f32_16x16x32_bf16 v[84:87], v[208:211], v[198:201], v[84:87]
	v_mfma_f32_16x16x32_bf16 v[80:83], v[216:219], v[198:201], v[80:83]
	v_mfma_f32_16x16x32_bf16 v[132:135], v[212:215], v[166:169], v[132:135]
	v_mfma_f32_16x16x32_bf16 v[128:131], v[220:223], v[166:169], v[128:131]
	v_mfma_f32_16x16x32_bf16 v[116:119], v[212:215], v[186:189], v[116:119]
	v_mfma_f32_16x16x32_bf16 v[112:115], v[220:223], v[186:189], v[112:115]
	v_mfma_f32_16x16x32_bf16 v[100:103], v[212:215], v[194:197], v[100:103]
	v_mfma_f32_16x16x32_bf16 v[96:99], v[220:223], v[194:197], v[96:99]
	v_mfma_f32_16x16x32_bf16 v[84:87], v[212:215], v[204:207], v[84:87]
	v_mfma_f32_16x16x32_bf16 v[80:83], v[220:223], v[204:207], v[80:83]
	s_mov_b32 m0, s74
	v_lshl_add_u64 v[170:171], v[226:227], 0, s[42:43]
	s_barrier
	ds_read_b128 v[162:165], v178 offset:49152
	ds_read_b128 v[166:169], v178 offset:50176
	ds_read_b128 v[182:185], v178 offset:51200
	ds_read_b128 v[186:189], v178 offset:52224
	ds_read_b128 v[190:193], v178 offset:53248
	ds_read_b128 v[194:197], v178 offset:54272
	ds_read_b128 v[198:201], v178 offset:55296
	ds_read_b128 v[204:207], v178 offset:56320
	global_load_lds_dwordx4 v[170:171], off
	v_lshl_add_u64 v[170:171], v[228:229], 0, s[42:43]
	s_mov_b32 m0, s75
	s_nop 0
	global_load_lds_dwordx4 v[170:171], off
	s_barrier
; __device__ __forceinline__ float bflo(unsigned w) { return __uint_as_float(w << 16); }
; __device__ __forceinline__ float bfhi(unsigned w) { return __uint_as_float(w & 0xffff0000u); }
; #define PG8_STAGE(bufoff, gbase, voff) do { _Pragma("unroll") for (int _i = 0; _i < 2; ++_i) \
;         __builtin_amdgcn_global_load_lds((const unsigned*)((const char*)(gbase) + (voff)[_i]), (LAS unsigned*)(lds + (bufoff) + ldsw + _i * 8192), 16, 0, 0); } while (0)
;     __device__ __forceinline__ void operator()(const f32x4 (&acc)[2][2][4][2], const Unit& u, int wr, int wc, int fr, int fq) const {
;         const int row0 = u.pm * BM + wr * 64 + fr, col0 = u.pn * BM + wc * 64 + 16 * fq;
;         f32x4 gv[2][2];
; #pragma unroll
;         for (int bj = 0; bj < 2; ++bj) { gv[bj][0] = *(const f32x4*)(g + col0 + 8 * bj); gv[bj][1] = *(const f32x4*)(g + col0 + 8 * bj + 4); }
; #pragma unroll
;         for (int ai = 0; ai < 2; ++ai)
; #pragma unroll
;             for (int m = 0; m < 4; ++m) { const int row = row0 + ai * HALF + m * 16; const size_t off = (size_t)row * D + col0; const float ri = __builtin_amdgcn_rsqf(sse[row] * (1.f / D) + EPS); float sq = 0.f; u32x4 w[2];
;                 u32x4 rr[2], ee[2]; load_pair_lines(R, D, row, fr, col0, rr[0], rr[1]); load_pair_lines(E, D, row, fr, col0, ee[0], ee[1]);
; #pragma unroll
;                 for (int bj = 0; bj < 2; ++bj) { const u32x4 rw = rr[bj], ew = ee[bj];
;                     const float r[8] = {bflo(rw.x), bfhi(rw.x), bflo(rw.y), bfhi(rw.y), bflo(rw.z), bfhi(rw.z), bflo(rw.w), bfhi(rw.w)};
;                     const float e[8] = {bflo(ew.x), bfhi(ew.x), bflo(ew.y), bfhi(ew.y), bflo(ew.z), bfhi(ew.z), bflo(ew.w), bfhi(ew.w)};
;                     float o[8];
; #pragma unroll
;                     for (int j = 0; j < 8; ++j) { const float a = acc[ai][bj][m][j >> 2][j & 3]; const float gg = gv[bj][j >> 2][j & 3];
;                         o[j] = r[j] + e[j] * ri * gg * __builtin_amdgcn_rcpf(1.f + __builtin_amdgcn_exp2f(-a * LOG2E)); }
; template <class Epi>
; __device__ __forceinline__ void gemm_phase(LAS unsigned char* lds, const Gemm g, const StaticOrder& S, const Epi& E) {
;     ...
;             PG8_BAR; PG8_WAIT_L(0); PG8_MMA(1, 0, At, B0); PG8_BAR; PG8_SCHED;
;             PG8_STAGE(PG8_SB(1, 1), b3, voffB1);
;             PG8_WAIT_V(6); PG8_BAR; PG8_MMA(1, 1, At, B1); PG8_BAR;
	s_waitcnt lgkmcnt(0)
	s_waitcnt lgkmcnt(0)
	v_mfma_f32_16x16x32_bf16 v[76:79], v[48:51], v[162:165], v[76:79]
	v_mfma_f32_16x16x32_bf16 v[72:75], v[64:67], v[162:165], v[72:75]
	v_mfma_f32_16x16x32_bf16 v[60:63], v[48:51], v[182:185], v[60:63]
	v_mfma_f32_16x16x32_bf16 v[56:59], v[64:67], v[182:185], v[56:59]
	v_mfma_f32_16x16x32_bf16 v[28:31], v[48:51], v[190:193], v[28:31]
	v_mfma_f32_16x16x32_bf16 v[24:27], v[64:67], v[190:193], v[24:27]
	v_mfma_f32_16x16x32_bf16 v[12:15], v[48:51], v[198:201], v[12:15]
	v_mfma_f32_16x16x32_bf16 v[8:11], v[64:67], v[198:201], v[8:11]
	v_mfma_f32_16x16x32_bf16 v[76:79], v[52:55], v[166:169], v[76:79]
	v_mfma_f32_16x16x32_bf16 v[72:75], v[68:71], v[166:169], v[72:75]
	v_mfma_f32_16x16x32_bf16 v[60:63], v[52:55], v[186:189], v[60:63]
	v_mfma_f32_16x16x32_bf16 v[56:59], v[68:71], v[186:189], v[56:59]
	v_mfma_f32_16x16x32_bf16 v[28:31], v[52:55], v[194:197], v[28:31]
	v_mfma_f32_16x16x32_bf16 v[24:27], v[68:71], v[194:197], v[24:27]
	v_mfma_f32_16x16x32_bf16 v[12:15], v[52:55], v[204:207], v[12:15]
	v_mfma_f32_16x16x32_bf16 v[8:11], v[68:71], v[204:207], v[8:11]
	s_barrier
	s_add_i32 s33, s62, s69
	v_lshl_add_u64 v[48:49], v[230:231], 0, s[42:43]
	s_mov_b32 m0, s33
	s_nop 0
	global_load_lds_dwordx4 v[48:49], off
	v_lshl_add_u64 v[48:49], v[232:233], 0, s[42:43]
	s_add_i32 m0, s33, 0x2000
	s_nop 0
	global_load_lds_dwordx4 v[48:49], off
	s_waitcnt vmcnt(6)
	s_barrier
	v_mfma_f32_16x16x32_bf16 v[32:35], v[208:211], v[162:165], v[32:35]
	v_mfma_f32_16x16x32_bf16 v[68:71], v[212:215], v[166:169], v[32:35]
	v_mfma_f32_16x16x32_bf16 v[32:35], v[216:219], v[162:165], v[40:43]
	v_mfma_f32_16x16x32_bf16 v[64:67], v[220:223], v[166:169], v[32:35]
	v_mfma_f32_16x16x32_bf16 v[32:35], v[208:211], v[182:185], v[44:47]
	v_mfma_f32_16x16x32_bf16 v[44:47], v[212:215], v[186:189], v[32:35]
	v_mfma_f32_16x16x32_bf16 v[32:35], v[216:219], v[182:185], v[36:39]
	v_mfma_f32_16x16x32_bf16 v[20:23], v[208:211], v[190:193], v[20:23]
	v_mfma_f32_16x16x32_bf16 v[16:19], v[216:219], v[190:193], v[16:19]
	v_mfma_f32_16x16x32_bf16 v[4:7], v[208:211], v[198:201], v[4:7]
	v_mfma_f32_16x16x32_bf16 v[0:3], v[216:219], v[198:201], v[0:3]
	v_mfma_f32_16x16x32_bf16 v[36:39], v[220:223], v[186:189], v[32:35]
	v_mfma_f32_16x16x32_bf16 v[20:23], v[212:215], v[194:197], v[20:23]
	v_mfma_f32_16x16x32_bf16 v[16:19], v[220:223], v[194:197], v[16:19]
	v_mfma_f32_16x16x32_bf16 v[4:7], v[212:215], v[204:207], v[4:7]
	v_mfma_f32_16x16x32_bf16 v[0:3], v[220:223], v[204:207], v[0:3]
	s_add_i32 s86, s86, 2
	s_add_u32 s60, s60, 0x100
	s_addc_u32 s61, s61, 0
	s_add_u32 s84, s84, 0x100
	s_addc_u32 s85, s85, 0
	s_cmp_gt_u32 s86, 29
	s_barrier
	s_cbranch_scc0 .LBB0_882
	s_lshl_b32 s33, s58, 8
	s_add_i32 s33, s33, s77
	v_lshl_or_b32 v32, s56, 8, v176
	v_or_b32_e32 v40, s33, v174
	v_or_b32_e32 v34, v32, v175
	v_ashrrev_i32_e32 v41, 31, v40
	v_ashrrev_i32_e32 v35, 31, v34
	v_lshlrev_b64 v[168:169], 12, v[40:41]
	v_lshl_add_u64 v[42:43], s[16:17], 0, v[168:169]
	v_lshlrev_b64 v[162:163], 1, v[34:35]
	v_lshl_add_u64 v[34:35], v[42:43], 0, v[162:163]
	global_load_dwordx4 v[182:185], v[34:35], off
	v_or_b32_e32 v34, 8, v40
	v_ashrrev_i32_e32 v35, 31, v34
	v_or_b32_e32 v164, s33, v172
	v_lshlrev_b64 v[170:171], 12, v[34:35]
	v_ashrrev_i32_e32 v165, 31, v164
	v_lshl_add_u64 v[34:35], s[16:17], 0, v[170:171]
	v_lshl_add_u64 v[166:167], v[164:165], 2, s[40:41]
	v_lshl_add_u64 v[34:35], v[34:35], 0, v[162:163]
	global_load_dword v181, v[166:167], off
	v_lshl_add_u64 v[40:41], s[38:39], 0, v[168:169]
	global_load_dwordx4 v[190:193], v[34:35], off
	v_lshl_add_u64 v[34:35], s[38:39], 0, v[170:171]
	v_lshl_add_u64 v[40:41], v[40:41], 0, v[162:163]
	v_lshl_add_u64 v[34:35], v[34:35], 0, v[162:163]
	global_load_dwordx4 v[186:189], v[40:41], off
	global_load_dwordx4 v[194:197], v[34:35], off
	v_ashrrev_i32_e32 v33, 31, v32
	v_lshl_add_u64 v[40:41], v[32:33], 2, s[10:11]
	global_load_dwordx4 v[52:55], v[40:41], off
	global_load_dwordx4 v[48:51], v[40:41], off offset:16
	global_load_dwordx4 v[32:35], v[40:41], off offset:48
	s_nop 0
	global_load_dwordx4 v[40:43], v[40:41], off offset:32
	v_or_b32_e32 v216, 16, v164
	v_ashrrev_i32_e32 v217, 31, v216
	v_lshl_add_u64 v[218:219], v[216:217], 2, s[40:41]
	global_load_dword v226, v[218:219], off
	v_sub_u32_e32 v218, v216, v172
	v_add_u32_e32 v218, v218, v174
	v_ashrrev_i32_e32 v219, 31, v218
	v_lshlrev_b64 v[218:219], 12, v[218:219]
	v_lshl_add_u64 v[220:221], s[16:17], 0, v[218:219]
	v_lshl_add_u64 v[220:221], v[220:221], 0, v[162:163]
	global_load_dwordx4 v[228:231], v[220:221], off
	v_lshl_add_u64 v[220:221], s[38:39], 0, v[218:219]
	v_lshl_add_u64 v[220:221], v[220:221], 0, v[162:163]
	global_load_dwordx4 v[232:235], v[220:221], off
	v_lshl_add_u64 v[220:221], v[218:219], 0, s[44:45]
	v_lshl_add_u64 v[224:225], s[38:39], 0, v[220:221]
	v_lshl_add_u64 v[222:223], s[16:17], 0, v[220:221]
	v_lshl_add_u64 v[224:225], v[224:225], 0, v[162:163]
	v_lshl_add_u64 v[222:223], v[222:223], 0, v[162:163]
	global_load_dwordx4 v[236:239], v[224:225], off
	global_load_dwordx4 v[240:243], v[222:223], off
	v_mul_f32_e32 v140, 0xbfb8aa3b, v140
	v_exp_f32_e32 v140, v140
	v_mul_f32_e32 v141, 0xbfb8aa3b, v141
	v_exp_f32_e32 v141, v141
	v_mov_b32_e32 v212, 0
	v_mov_b32_e32 v204, 0
	v_mov_b32_e32 v208, 0
	v_add_f32_e32 v140, 1.0, v140
	v_mov_b32_e32 v198, 0
	v_rcp_f32_e32 v140, v140
	v_add_f32_e32 v141, 1.0, v141
	v_rcp_f32_e32 v141, v141
	v_mov_b32_e32 v213, 0
	v_mul_f32_e32 v136, 0xbfb8aa3b, v136
	v_mov_b32_e32 v205, 0
	v_mov_b32_e32 v209, 0
	v_exp_f32_e32 v136, v136
	v_mov_b32_e32 v199, 0
	v_mul_f32_e32 v137, 0xbfb8aa3b, v137
	v_exp_f32_e32 v137, v137
	v_mov_b32_e32 v214, 0
	v_mov_b32_e32 v206, 0
	v_mov_b32_e32 v210, 0
	v_add_f32_e32 v136, 1.0, v136
	v_mov_b32_e32 v200, 0
	v_rcp_f32_e32 v136, v136
	v_add_f32_e32 v137, 1.0, v137
	v_mul_f32_e32 v132, 0xbfb8aa3b, v132
	v_rcp_f32_e32 v137, v137
	v_exp_f32_e32 v132, v132
	v_mul_f32_e32 v133, 0xbfb8aa3b, v133
	v_exp_f32_e32 v133, v133
	v_mov_b32_e32 v215, 0
	v_add_f32_e32 v132, 1.0, v132
	v_rcp_f32_e32 v132, v132
	v_add_f32_e32 v133, 1.0, v133
	v_rcp_f32_e32 v133, v133
	v_mov_b32_e32 v207, 0
	v_mov_b32_e32 v211, 0
	v_mov_b32_e32 v201, 0
	v_mul_f32_e32 v128, 0xbfb8aa3b, v128
	v_exp_f32_e32 v128, v128
	v_mul_f32_e32 v129, 0xbfb8aa3b, v129
	v_exp_f32_e32 v129, v129
	v_add_f32_e32 v128, 1.0, v128
	v_rcp_f32_e32 v128, v128
	v_add_f32_e32 v129, 1.0, v129
	v_rcp_f32_e32 v129, v129
	s_waitcnt vmcnt(5)
; __device__ __forceinline__ float bflo(unsigned w) { return __uint_as_float(w << 16); }
; __device__ __forceinline__ float bfhi(unsigned w) { return __uint_as_float(w & 0xffff0000u); }
;     __device__ __forceinline__ void operator()(const f32x4 (&acc)[2][2][4][2], const Unit& u, int wr, int wc, int fr, int fq) const {
;     ...
;             for (int m = 0; m < 4; ++m) { const int row = row0 + ai * HALF + m * 16; const size_t off = (size_t)row * D + col0; const float ri = __builtin_amdgcn_rsqf(sse[row] * (1.f / D) + EPS); float sq = 0.f; u32x4 w[2];
;                 u32x4 rr[2], ee[2]; load_pair_lines(R, D, row, fr, col0, rr[0], rr[1]); load_pair_lines(E, D, row, fr, col0, ee[0], ee[1]);
; #pragma unroll
;                 for (int bj = 0; bj < 2; ++bj) { const u32x4 rw = rr[bj], ew = ee[bj];
;                     const float r[8] = {bflo(rw.x), bfhi(rw.x), bflo(rw.y), bfhi(rw.y), bflo(rw.z), bfhi(rw.z), bflo(rw.w), bfhi(rw.w)};
;                     const float e[8] = {bflo(ew.x), bfhi(ew.x), bflo(ew.y), bfhi(ew.y), bflo(ew.z), bfhi(ew.z), bflo(ew.w), bfhi(ew.w)};
;                     float o[8];
; #pragma unroll
;                     for (int j = 0; j < 8; ++j) { const float a = acc[ai][bj][m][j >> 2][j & 3]; const float gg = gv[bj][j >> 2][j & 3];
;                         o[j] = r[j] + e[j] * ri * gg * __builtin_amdgcn_rcpf(1.f + __builtin_amdgcn_exp2f(-a * LOG2E)); }
	v_mov_b32_dpp v198, v182 row_ror:8 row_mask:0xf bank_mask:0xf
	v_mov_b32_dpp v199, v183 row_ror:8 row_mask:0xf bank_mask:0xf
	v_mov_b32_dpp v200, v184 row_ror:8 row_mask:0xf bank_mask:0xf
	v_mov_b32_dpp v201, v185 row_ror:8 row_mask:0xf bank_mask:0xf
	v_fmamk_f32 v181, v181, 0x3a000000, v180
	v_rsq_f32_e32 v181, v181
	v_mov_b32_dpp v204, v190 row_ror:8 row_mask:0xf bank_mask:0xf
	v_cndmask_b32_e64 v182, v204, v182, s[6:7]
	v_cndmask_b32_e64 v190, v190, v198, s[6:7]
	v_lshlrev_b32_e32 v198, 16, v182
	v_mov_b32_dpp v208, v186 row_ror:8 row_mask:0xf bank_mask:0xf
	v_mov_b32_dpp v212, v194 row_ror:8 row_mask:0xf bank_mask:0xf
	v_cndmask_b32_e64 v186, v212, v186, s[6:7]
	v_lshlrev_b32_e32 v204, 16, v186
	v_mul_f32_e32 v204, v181, v204
	v_and_b32_e32 v186, 0xffff0000, v186
	v_mul_f32_e32 v204, v52, v204
	v_fmac_f32_e32 v198, v140, v204
	v_mul_f32_e32 v140, v181, v186
	v_and_b32_e32 v182, 0xffff0000, v182
	v_mul_f32_e32 v140, v53, v140
	v_fmac_f32_e32 v182, v141, v140
	v_mul_f32_e32 v140, 0xbfb8aa3b, v142
	v_exp_f32_e32 v140, v140
	v_mul_f32_e32 v142, 0xbfb8aa3b, v143
	v_exp_f32_e32 v142, v142
	v_mov_b32_dpp v213, v195 row_ror:8 row_mask:0xf bank_mask:0xf
	v_add_f32_e32 v140, 1.0, v140
	v_mov_b32_dpp v209, v187 row_ror:8 row_mask:0xf bank_mask:0xf
	v_mov_b32_dpp v205, v191 row_ror:8 row_mask:0xf bank_mask:0xf
	v_cndmask_b32_e64 v187, v213, v187, s[6:7]
	v_rcp_f32_e32 v140, v140
	v_cndmask_b32_e64 v183, v205, v183, s[6:7]
	v_lshlrev_b32_e32 v205, 16, v187
	v_add_f32_e32 v142, 1.0, v142
	v_mul_f32_e32 v141, v181, v205
	v_rcp_f32_e32 v142, v142
	v_cndmask_b32_e64 v191, v191, v199, s[6:7]
	v_mov_b32_dpp v214, v196 row_ror:8 row_mask:0xf bank_mask:0xf
	v_lshlrev_b32_e32 v199, 16, v183
	v_and_b32_e32 v187, 0xffff0000, v187
	v_mul_f32_e32 v141, v54, v141
	v_mov_b32_dpp v210, v188 row_ror:8 row_mask:0xf bank_mask:0xf
	v_mov_b32_dpp v206, v192 row_ror:8 row_mask:0xf bank_mask:0xf
	v_cndmask_b32_e64 v188, v214, v188, s[6:7]
	v_fmac_f32_e32 v199, v140, v141
	v_mul_f32_e32 v140, v181, v187
	v_cndmask_b32_e64 v184, v206, v184, s[6:7]
	v_and_b32_e32 v183, 0xffff0000, v183
	v_lshlrev_b32_e32 v206, 16, v188
	v_mul_f32_e32 v140, v55, v140
	v_fmac_f32_e32 v183, v142, v140
	v_mul_f32_e32 v140, v181, v206
	v_cndmask_b32_e64 v192, v192, v200, s[6:7]
	v_lshlrev_b32_e32 v200, 16, v184
	v_and_b32_e32 v188, 0xffff0000, v188
	v_mul_f32_e32 v140, v48, v140
	v_fmac_f32_e32 v200, v136, v140
	v_mul_f32_e32 v136, v181, v188
	v_and_b32_e32 v184, 0xffff0000, v184
	v_mul_f32_e32 v136, v49, v136
	v_fmac_f32_e32 v184, v137, v136
	v_mul_f32_e32 v136, 0xbfb8aa3b, v138
	v_cndmask_b32_e64 v194, v194, v208, s[6:7]
	v_exp_f32_e32 v136, v136
	v_mul_f32_e32 v138, 0xbfb8aa3b, v139
	v_lshlrev_b32_e32 v187, 16, v194
	v_exp_f32_e32 v138, v138
	v_mul_f32_e32 v187, v181, v187
	v_lshlrev_b32_e32 v141, 16, v190
	v_and_b32_e32 v188, 0xffff0000, v194
	v_mul_f32_e32 v187, v40, v187
	v_mov_b32_dpp v215, v197 row_ror:8 row_mask:0xf bank_mask:0xf
	v_add_f32_e32 v136, 1.0, v136
	v_fmac_f32_e32 v141, v132, v187
	v_mul_f32_e32 v132, v181, v188
	v_mov_b32_dpp v211, v189 row_ror:8 row_mask:0xf bank_mask:0xf
	v_mov_b32_dpp v207, v193 row_ror:8 row_mask:0xf bank_mask:0xf
	v_cndmask_b32_e64 v189, v215, v189, s[6:7]
	v_rcp_f32_e32 v136, v136
	v_and_b32_e32 v142, 0xffff0000, v190
	v_mul_f32_e32 v132, v41, v132
	v_cndmask_b32_e64 v185, v207, v185, s[6:7]
	v_lshlrev_b32_e32 v207, 16, v189
	v_add_f32_e32 v138, 1.0, v138
	v_fmac_f32_e32 v142, v133, v132
	v_mul_f32_e32 v132, 0xbfb8aa3b, v134
	v_mul_f32_e32 v137, v181, v207
	v_rcp_f32_e32 v138, v138
	v_exp_f32_e32 v132, v132
	v_cndmask_b32_e64 v193, v193, v201, s[6:7]
	v_lshlrev_b32_e32 v201, 16, v185
	v_and_b32_e32 v189, 0xffff0000, v189
	v_mul_f32_e32 v137, v50, v137
	v_mul_f32_e32 v134, 0xbfb8aa3b, v135
	v_fmac_f32_e32 v201, v136, v137
	v_mul_f32_e32 v136, v181, v189
	v_exp_f32_e32 v134, v134
	v_and_b32_e32 v185, 0xffff0000, v185
	v_mul_f32_e32 v136, v51, v136
	v_fmac_f32_e32 v185, v138, v136
	v_mul_f32_e32 v136, v182, v182
	v_mul_f32_e32 v137, v183, v183
	v_add_f32_e32 v132, 1.0, v132
	v_cndmask_b32_e64 v195, v195, v209, s[6:7]
	v_fmac_f32_e32 v136, v198, v198
	v_fmac_f32_e32 v137, v199, v199
	v_rcp_f32_e32 v132, v132
	v_add_f32_e32 v136, v136, v137
	v_mul_f32_e32 v137, v184, v184
; __device__ __forceinline__ unsigned cvt_pk_bf16(float lo, float hi) { unsigned r; asm volatile("v_cvt_pk_bf16_f32 %0, %1, %2" : "=v"(r) : "v"(lo), "v"(hi)); return r; }
;     __device__ __forceinline__ void operator()(const f32x4 (&acc)[2][2][4][2], const Unit& u, int wr, int wc, int fr, int fq) const {
;     ...
;                         o[j] = r[j] + e[j] * ri * gg * __builtin_amdgcn_rcpf(1.f + __builtin_amdgcn_exp2f(-a * LOG2E)); }
;                     if (OUT) { *(f32x4*)(OUT + off + 8 * bj) = (f32x4){o[0], o[1], o[2], o[3]}; *(f32x4*)(OUT + off + 8 * bj + 4) = (f32x4){o[4], o[5], o[6], o[7]}; }
;                     else { sq += (o[0] * o[0] + o[1] * o[1]) + (o[2] * o[2] + o[3] * o[3]) + (o[4] * o[4] + o[5] * o[5]) + (o[6] * o[6] + o[7] * o[7]);
;                         w[bj].x = cvt_pk_bf16(o[0], o[1]); w[bj].y = cvt_pk_bf16(o[2], o[3]); w[bj].z = cvt_pk_bf16(o[4], o[5]); w[bj].w = cvt_pk_bf16(o[6], o[7]); } }
;                 if (!OUT) { store_pair_lines(O, D, row, fr, col0, w[0], w[1]);
;                     sq += __shfl_xor(sq, 16); sq += __shfl_xor(sq, 32); if (fq == 0) unsafeAtomicAdd(ssout + row, sq); } }
	v_lshlrev_b32_e32 v189, 16, v195
	v_add_f32_e32 v134, 1.0, v134
	v_fmac_f32_e32 v137, v200, v200
	v_mul_f32_e32 v133, v181, v189
	v_rcp_f32_e32 v134, v134
	v_add_f32_e32 v136, v137, v136
	v_mul_f32_e32 v137, v185, v185
	v_lshlrev_b32_e32 v143, 16, v191
	v_and_b32_e32 v190, 0xffff0000, v195
	v_mul_f32_e32 v133, v42, v133
	v_cndmask_b32_e64 v196, v196, v210, s[6:7]
	v_fmac_f32_e32 v137, v201, v201
	v_fmac_f32_e32 v143, v132, v133
	v_mul_f32_e32 v132, v181, v190
	v_add_f32_e32 v136, v137, v136
	v_cvt_pk_bf16_f32 v137, v198, v182
	v_and_b32_e32 v182, 0xffff0000, v191
	v_lshlrev_b32_e32 v191, 16, v196
	v_mul_f32_e32 v132, v43, v132
	v_fmac_f32_e32 v182, v134, v132
	v_mul_f32_e32 v132, v181, v191
	v_cvt_pk_bf16_f32 v138, v199, v183
	v_cvt_pk_bf16_f32 v139, v200, v184
	v_lshlrev_b32_e32 v183, 16, v192
	v_and_b32_e32 v184, 0xffff0000, v192
	v_and_b32_e32 v192, 0xffff0000, v196
	v_mul_f32_e32 v132, v32, v132
	v_fmac_f32_e32 v183, v128, v132
	v_mul_f32_e32 v128, v181, v192
	v_mul_f32_e32 v128, v33, v128
	v_fmac_f32_e32 v184, v129, v128
	v_mul_f32_e32 v128, 0xbfb8aa3b, v130
	v_exp_f32_e32 v128, v128
	v_mul_f32_e32 v130, 0xbfb8aa3b, v131
	v_exp_f32_e32 v130, v130
	v_cndmask_b32_e64 v197, v197, v211, s[6:7]
	v_add_f32_e32 v128, 1.0, v128
	v_rcp_f32_e32 v128, v128
	v_cvt_pk_bf16_f32 v140, v201, v185
	v_lshlrev_b32_e32 v185, 16, v193
	v_and_b32_e32 v186, 0xffff0000, v193
	v_lshlrev_b32_e32 v193, 16, v197
	v_add_f32_e32 v130, 1.0, v130
	v_mul_f32_e32 v129, v181, v193
	v_rcp_f32_e32 v130, v130
	v_and_b32_e32 v194, 0xffff0000, v197
	v_mul_f32_e32 v129, v34, v129
	v_fmac_f32_e32 v185, v128, v129
	v_mul_f32_e32 v128, v181, v194
	v_mul_f32_e32 v128, v35, v128
	v_fmac_f32_e32 v186, v130, v128
	v_mul_f32_e32 v128, v142, v142
	v_mul_f32_e32 v129, v182, v182
	v_fmac_f32_e32 v128, v141, v141
	v_fmac_f32_e32 v129, v143, v143
	v_add_f32_e32 v128, v128, v129
	v_mul_f32_e32 v129, v184, v184
	v_fmac_f32_e32 v129, v183, v183
	v_add_f32_e32 v128, v129, v128
	v_mul_f32_e32 v129, v186, v186
	v_fmac_f32_e32 v129, v185, v185
	v_add_f32_e32 v128, v129, v128
	v_add_f32_e32 v135, v128, v136
	v_cvt_pk_bf16_f32 v128, v141, v142
	v_cvt_pk_bf16_f32 v129, v143, v182
	v_mov_b32_e32 v143, 0
	v_mov_b32_e32 v130, 0
	v_mov_b32_e32 v134, 0
	v_mov_b32_dpp v143, v138 row_ror:8 row_mask:0xf bank_mask:0xf
	v_mov_b32_dpp v130, v128 row_ror:8 row_mask:0xf bank_mask:0xf
	v_mov_b32_e32 v131, 0
	v_mov_b32_dpp v134, v137 row_ror:8 row_mask:0xf bank_mask:0xf
	v_cndmask_b32_e64 v130, v130, v137, s[6:7]
	v_mov_b32_dpp v131, v129 row_ror:8 row_mask:0xf bank_mask:0xf
	v_cndmask_b32_e64 v137, v129, v143, s[6:7]
	v_and_b32_e32 v129, 64, v203
	v_cndmask_b32_e64 v136, v128, v134, s[6:7]
	v_xor_b32_e32 v128, 16, v203
	v_add_u32_e32 v143, 64, v129
	v_cmp_lt_i32_e32 vcc, v128, v143
	v_cvt_pk_bf16_f32 v141, v183, v184
	v_mov_b32_e32 v181, 0
	v_mov_b32_e32 v133, 0
	v_cndmask_b32_e32 v128, v203, v128, vcc
	v_lshlrev_b32_e32 v134, 2, v128
	ds_bpermute_b32 v183, v134, v135
	v_cvt_pk_bf16_f32 v142, v185, v186
	v_mov_b32_dpp v181, v139 row_ror:8 row_mask:0xf bank_mask:0xf
	v_mov_b32_e32 v182, 0
	v_mov_b32_e32 v132, 0
	v_mov_b32_dpp v133, v142 row_ror:8 row_mask:0xf bank_mask:0xf
	v_lshl_add_u64 v[128:129], s[36:37], 0, v[168:169]
	v_mov_b32_dpp v182, v140 row_ror:8 row_mask:0xf bank_mask:0xf
	v_mov_b32_dpp v132, v141 row_ror:8 row_mask:0xf bank_mask:0xf
	v_cndmask_b32_e64 v131, v131, v138, s[6:7]
	v_cndmask_b32_e64 v133, v133, v140, s[6:7]
	v_cndmask_b32_e64 v138, v141, v181, s[6:7]
	v_lshl_add_u64 v[140:141], v[128:129], 0, v[162:163]
	v_xor_b32_e32 v129, 32, v203
	v_cmp_lt_i32_e32 vcc, v129, v143
	s_waitcnt lgkmcnt(0)
	v_add_f32_e32 v128, v135, v183
	v_cndmask_b32_e64 v132, v132, v139, s[6:7]
	v_cndmask_b32_e32 v129, v203, v129, vcc
	v_lshlrev_b32_e32 v135, 2, v129
	ds_bpermute_b32 v129, v135, v128
	global_store_dwordx4 v[140:141], v[130:133], off
	v_cndmask_b32_e64 v139, v142, v182, s[6:7]
	s_nop 0
	v_lshl_add_u64 v[130:131], s[36:37], 0, v[170:171]
	v_lshl_add_u64 v[130:131], v[130:131], 0, v[162:163]
	global_store_dwordx4 v[130:131], v[136:139], off
	s_and_saveexec_b64 s[56:57], s[8:9]
	s_cbranch_execz .LBB0_885
	v_lshl_add_u64 v[130:131], v[164:165], 2, s[18:19]
	s_waitcnt lgkmcnt(0)
	v_add_f32_e32 v128, v128, v129
	global_atomic_add_f32 v[130:131], v128, off

; #define PG8_STAGE(bufoff, gbase, voff) do { _Pragma("unroll") for (int _i = 0; _i < 2; ++_i) \
;         __builtin_amdgcn_global_load_lds((const unsigned*)((const char*)(gbase) + (voff)[_i]), (LAS unsigned*)(lds + (bufoff) + ldsw + _i * 8192), 16, 0, 0); } while (0)
; #define PG8_LDA(dst, b, h) do { _Pragma("unroll") for (int m = 0; m < 4; ++m) _Pragma("unroll") for (int k = 0; k < 2; ++k) dst[m][k] = *(const LAS bf16x8*)(lds + PG8_SA(b, h) + aoff + m * 2048 + k * 1024); } while (0)
; #define PG8_LDB(dst, b, h) do { _Pragma("unroll") for (int n = 0; n < 2; ++n) _Pragma("unroll") for (int k = 0; k < 2; ++k) dst[n][k] = *(const LAS bf16x8*)(lds + PG8_SB(b, h) + boff + n * 2048 + k * 1024); } while (0)
; #define PG8_MMA(ai, bj, At, Bt) do { __builtin_amdgcn_s_setprio(1); _Pragma("unroll") for (int m = 0; m < 4; ++m) _Pragma("unroll") for (int n = 0; n < 2; ++n) _Pragma("unroll") for (int k = 0; k < 2; ++k) \
;         acc[ai][bj][m][n] = __builtin_amdgcn_mfma_f32_16x16x32_bf16(Bt[n][k], At[m][k], acc[ai][bj][m][n], 0, 0, 0); __builtin_amdgcn_s_setprio(0); } while (0)
; #define PG8_WAIT_L(n) asm volatile("s_waitcnt lgkmcnt(" #n ")" ::: "memory")
; #define PG8_BAR __builtin_amdgcn_s_barrier()
; #define PG8_SCHED __builtin_amdgcn_sched_barrier(0)
; template <class Epi>
; __device__ __forceinline__ void gemm_phase(LAS unsigned char* lds, const Gemm g, const StaticOrder& S, const Epi& E) {
;     ...
;             const bool last = (t == nt - 2);
;             const char* a1 = cA + (size_t)(t + 1) * kstep;
;             const char* a2 = last ? nA : cA + (size_t)(t + 2) * kstep; const char* b2 = last ? nB : cB + (size_t)(t + 2) * kstep;
;             const char* a3 = a2 + kstep; const char* b3 = b2 + kstep;
;             PG8_LDB(B0, 0, 0); PG8_SCHED; PG8_LDA(At, 0, 0); PG8_STAGE(PG8_SA(1, 1), a1 + hstep, voffA);
;             PG8_WAIT_L(8); PG8_BAR; PG8_WAIT_L(0); PG8_MMA(0, 0, At, B0); PG8_BAR; PG8_SCHED;
;             PG8_LDB(B1, 0, 1); PG8_STAGE(PG8_SB(0, 0), b2, voffB0);
;             PG8_BAR; PG8_WAIT_L(0); PG8_MMA(0, 1, At, B1); PG8_BAR;
;             PG8_LDA(At, 0, 1); PG8_STAGE(PG8_SA(0, 0), a2, voffA);
;             PG8_BAR; PG8_WAIT_L(0); PG8_MMA(1, 0, At, B0); PG8_BAR; PG8_SCHED;
;             PG8_STAGE(PG8_SB(0, 1), b2, voffB1);
.LBB0_962:
	ds_read_b128 v[146:149], v158
	ds_read_b128 v[150:153], v158 offset:1024
	ds_read_b128 v[162:165], v158 offset:2048
	ds_read_b128 v[166:169], v158 offset:3072
	s_add_u32 s33, s46, 0xfff80080
	s_addc_u32 s48, s47, -1
	s_cmp_eq_u32 s77, 28
	s_cselect_b32 s49, s37, s48
	s_cselect_b32 s48, s72, s33
	s_cselect_b32 s51, s19, s75
	s_cselect_b32 s50, s73, s74
	v_lshl_add_u64 v[204:205], s[46:47], 0, v[140:141]
	s_add_i32 m0, s45, 0xc000
	ds_read_b128 v[170:173], v159
	ds_read_b128 v[174:177], v159 offset:1024
	ds_read_b128 v[178:181], v159 offset:2048
	ds_read_b128 v[182:185], v159 offset:3072
	ds_read_b128 v[186:189], v159 offset:4096
	ds_read_b128 v[190:193], v159 offset:5120
	ds_read_b128 v[194:197], v159 offset:6144
	ds_read_b128 v[198:201], v159 offset:7168
	global_load_lds_dwordx4 v[204:205], off
	v_lshl_add_u64 v[204:205], s[46:47], 0, v[142:143]
	s_add_i32 m0, s45, 0xe000
	s_nop 0
	global_load_lds_dwordx4 v[204:205], off
	s_waitcnt lgkmcnt(8)
	s_barrier
	s_waitcnt lgkmcnt(0)
	s_waitcnt lgkmcnt(0)
	v_mfma_f32_16x16x32_bf16 v[124:127], v[146:149], v[170:173], v[124:127]
	v_mfma_f32_16x16x32_bf16 v[120:123], v[162:165], v[170:173], v[120:123]
	v_mfma_f32_16x16x32_bf16 v[108:111], v[146:149], v[178:181], v[108:111]
	v_mfma_f32_16x16x32_bf16 v[104:107], v[162:165], v[178:181], v[104:107]
	v_mfma_f32_16x16x32_bf16 v[92:95], v[146:149], v[186:189], v[92:95]
	v_mfma_f32_16x16x32_bf16 v[88:91], v[162:165], v[186:189], v[88:91]
	v_mfma_f32_16x16x32_bf16 v[76:79], v[146:149], v[194:197], v[76:79]
	v_mfma_f32_16x16x32_bf16 v[72:75], v[162:165], v[194:197], v[72:75]
	v_mfma_f32_16x16x32_bf16 v[124:127], v[150:153], v[174:177], v[124:127]
	v_mfma_f32_16x16x32_bf16 v[120:123], v[166:169], v[174:177], v[120:123]
	v_mfma_f32_16x16x32_bf16 v[108:111], v[150:153], v[182:185], v[108:111]
	v_mfma_f32_16x16x32_bf16 v[104:107], v[166:169], v[182:185], v[104:107]
	v_mfma_f32_16x16x32_bf16 v[92:95], v[150:153], v[190:193], v[92:95]
	v_mfma_f32_16x16x32_bf16 v[88:91], v[166:169], v[190:193], v[88:91]
	v_mfma_f32_16x16x32_bf16 v[76:79], v[150:153], v[198:201], v[76:79]
	v_mfma_f32_16x16x32_bf16 v[72:75], v[166:169], v[198:201], v[72:75]
	s_barrier
	s_add_i32 s33, s68, s57
	v_lshl_add_u64 v[220:221], s[50:51], 0, v[134:135]
	s_mov_b32 m0, s33
	ds_read_b128 v[204:207], v160
	ds_read_b128 v[208:211], v160 offset:1024
	ds_read_b128 v[212:215], v160 offset:2048
	ds_read_b128 v[216:219], v160 offset:3072
	global_load_lds_dwordx4 v[220:221], off
	v_lshl_add_u64 v[222:223], s[50:51], 0, v[128:129]
	s_add_i32 m0, s33, 0x2000
	s_nop 0
	global_load_lds_dwordx4 v[222:223], off
	s_barrier
	s_waitcnt lgkmcnt(0)
	s_waitcnt lgkmcnt(0)
	v_mfma_f32_16x16x32_bf16 v[116:119], v[204:207], v[170:173], v[116:119]
	v_mfma_f32_16x16x32_bf16 v[112:115], v[212:215], v[170:173], v[112:115]
	v_mfma_f32_16x16x32_bf16 v[100:103], v[204:207], v[178:181], v[100:103]
	v_mfma_f32_16x16x32_bf16 v[96:99], v[212:215], v[178:181], v[96:99]
	v_mfma_f32_16x16x32_bf16 v[84:87], v[204:207], v[186:189], v[84:87]
	v_mfma_f32_16x16x32_bf16 v[80:83], v[212:215], v[186:189], v[80:83]
	v_mfma_f32_16x16x32_bf16 v[68:71], v[204:207], v[194:197], v[68:71]
	v_mfma_f32_16x16x32_bf16 v[64:67], v[212:215], v[194:197], v[64:67]
	v_mfma_f32_16x16x32_bf16 v[116:119], v[208:211], v[174:177], v[116:119]
	v_mfma_f32_16x16x32_bf16 v[112:115], v[216:219], v[174:177], v[112:115]
	v_mfma_f32_16x16x32_bf16 v[100:103], v[208:211], v[182:185], v[100:103]
	v_mfma_f32_16x16x32_bf16 v[96:99], v[216:219], v[182:185], v[96:99]
	v_mfma_f32_16x16x32_bf16 v[84:87], v[208:211], v[190:193], v[84:87]
	v_mfma_f32_16x16x32_bf16 v[80:83], v[216:219], v[190:193], v[80:83]
	v_mfma_f32_16x16x32_bf16 v[68:71], v[208:211], v[198:201], v[68:71]
	v_mfma_f32_16x16x32_bf16 v[64:67], v[216:219], v[198:201], v[64:67]
	s_mov_b32 m0, s45
	v_lshl_add_u64 v[224:225], s[48:49], 0, v[138:139]
	s_barrier
	ds_read_b128 v[170:173], v159 offset:16384
	ds_read_b128 v[174:177], v159 offset:17408
	ds_read_b128 v[178:181], v159 offset:18432
	ds_read_b128 v[182:185], v159 offset:19456
	ds_read_b128 v[186:189], v159 offset:20480
	ds_read_b128 v[190:193], v159 offset:21504
	ds_read_b128 v[194:197], v159 offset:22528
	ds_read_b128 v[198:201], v159 offset:23552
	global_load_lds_dwordx4 v[224:225], off
	v_lshl_add_u64 v[226:227], s[48:49], 0, v[132:133]
	s_mov_b32 m0, s59
	s_nop 0
	global_load_lds_dwordx4 v[226:227], off
	s_barrier
	s_waitcnt lgkmcnt(0)
	s_waitcnt lgkmcnt(0)
	v_mfma_f32_16x16x32_bf16 v[60:63], v[146:149], v[170:173], v[60:63]
	v_mfma_f32_16x16x32_bf16 v[56:59], v[162:165], v[170:173], v[56:59]
	v_mfma_f32_16x16x32_bf16 v[44:47], v[146:149], v[178:181], v[44:47]
	v_mfma_f32_16x16x32_bf16 v[40:43], v[162:165], v[178:181], v[40:43]
	v_mfma_f32_16x16x32_bf16 v[28:31], v[146:149], v[186:189], v[28:31]
	v_mfma_f32_16x16x32_bf16 v[24:27], v[162:165], v[186:189], v[24:27]
	v_mfma_f32_16x16x32_bf16 v[12:15], v[146:149], v[194:197], v[12:15]
	v_mfma_f32_16x16x32_bf16 v[8:11], v[162:165], v[194:197], v[8:11]
	v_mfma_f32_16x16x32_bf16 v[60:63], v[150:153], v[174:177], v[60:63]
	v_mfma_f32_16x16x32_bf16 v[56:59], v[166:169], v[174:177], v[56:59]
	v_mfma_f32_16x16x32_bf16 v[44:47], v[150:153], v[182:185], v[44:47]
	v_mfma_f32_16x16x32_bf16 v[40:43], v[166:169], v[182:185], v[40:43]
	v_mfma_f32_16x16x32_bf16 v[28:31], v[150:153], v[190:193], v[28:31]
	v_mfma_f32_16x16x32_bf16 v[24:27], v[166:169], v[190:193], v[24:27]
	v_mfma_f32_16x16x32_bf16 v[12:15], v[150:153], v[198:201], v[12:15]
	v_mfma_f32_16x16x32_bf16 v[8:11], v[166:169], v[198:201], v[8:11]
	s_barrier
; #define PG8_STAGE(bufoff, gbase, voff) do { _Pragma("unroll") for (int _i = 0; _i < 2; ++_i) \
;         __builtin_amdgcn_global_load_lds((const unsigned*)((const char*)(gbase) + (voff)[_i]), (LAS unsigned*)(lds + (bufoff) + ldsw + _i * 8192), 16, 0, 0); } while (0)
; #define PG8_LDA(dst, b, h) do { _Pragma("unroll") for (int m = 0; m < 4; ++m) _Pragma("unroll") for (int k = 0; k < 2; ++k) dst[m][k] = *(const LAS bf16x8*)(lds + PG8_SA(b, h) + aoff + m * 2048 + k * 1024); } while (0)
; #define PG8_LDB(dst, b, h) do { _Pragma("unroll") for (int n = 0; n < 2; ++n) _Pragma("unroll") for (int k = 0; k < 2; ++k) dst[n][k] = *(const LAS bf16x8*)(lds + PG8_SB(b, h) + boff + n * 2048 + k * 1024); } while (0)
; #define PG8_MMA(ai, bj, At, Bt) do { __builtin_amdgcn_s_setprio(1); _Pragma("unroll") for (int m = 0; m < 4; ++m) _Pragma("unroll") for (int n = 0; n < 2; ++n) _Pragma("unroll") for (int k = 0; k < 2; ++k) \
;         acc[ai][bj][m][n] = __builtin_amdgcn_mfma_f32_16x16x32_bf16(Bt[n][k], At[m][k], acc[ai][bj][m][n], 0, 0, 0); __builtin_amdgcn_s_setprio(0); } while (0)
; #define PG8_WAIT_V(n) asm volatile("s_waitcnt vmcnt(" #n ")" ::: "memory")
; #define PG8_WAIT_L(n) asm volatile("s_waitcnt lgkmcnt(" #n ")" ::: "memory")
; #define PG8_BAR __builtin_amdgcn_s_barrier()
; #define PG8_SCHED __builtin_amdgcn_sched_barrier(0)
; template <class Epi>
; __device__ __forceinline__ void gemm_phase(LAS unsigned char* lds, const Gemm g, const StaticOrder& S, const Epi& E) {
;     ...
;             PG8_STAGE(PG8_SB(0, 1), b2, voffB1);
;             PG8_WAIT_V(6); PG8_BAR; PG8_MMA(1, 1, At, B1); PG8_BAR;
;             PG8_LDB(B0, 1, 0); PG8_SCHED; PG8_LDA(At, 1, 0); PG8_STAGE(PG8_SA(0, 1), a2 + hstep, voffA);
;             PG8_WAIT_L(8); PG8_BAR; PG8_WAIT_L(0); PG8_MMA(0, 0, At, B0); PG8_BAR; PG8_SCHED;
;             PG8_LDB(B1, 1, 1); PG8_STAGE(PG8_SB(1, 0), b3, voffB0);
;             PG8_BAR; PG8_WAIT_L(0); PG8_MMA(0, 1, At, B1); PG8_BAR;
;             PG8_LDA(At, 1, 1); PG8_STAGE(PG8_SA(1, 0), a3, voffA);
;             PG8_BAR; PG8_WAIT_L(0); PG8_MMA(1, 0, At, B0); PG8_BAR; PG8_SCHED;
;             PG8_STAGE(PG8_SB(1, 1), b3, voffB1);
	s_add_i32 s33, s69, s57
	v_lshl_add_u64 v[228:229], s[50:51], 0, v[136:137]
	s_mov_b32 m0, s33
	v_lshl_add_u64 v[230:231], s[50:51], 0, v[130:131]
	global_load_lds_dwordx4 v[228:229], off
	s_add_i32 m0, s33, 0x2000
	s_nop 0
	global_load_lds_dwordx4 v[230:231], off
	s_waitcnt vmcnt(6)
	s_barrier
	v_mfma_f32_16x16x32_bf16 v[52:55], v[204:207], v[170:173], v[52:55]
	v_mfma_f32_16x16x32_bf16 v[48:51], v[212:215], v[170:173], v[48:51]
	v_mfma_f32_16x16x32_bf16 v[36:39], v[204:207], v[178:181], v[36:39]
	v_mfma_f32_16x16x32_bf16 v[32:35], v[212:215], v[178:181], v[32:35]
	v_mfma_f32_16x16x32_bf16 v[20:23], v[204:207], v[186:189], v[20:23]
	v_mfma_f32_16x16x32_bf16 v[16:19], v[212:215], v[186:189], v[16:19]
	v_mfma_f32_16x16x32_bf16 v[4:7], v[204:207], v[194:197], v[4:7]
	v_mfma_f32_16x16x32_bf16 v[0:3], v[212:215], v[194:197], v[0:3]
	v_mfma_f32_16x16x32_bf16 v[52:55], v[208:211], v[174:177], v[52:55]
	v_mfma_f32_16x16x32_bf16 v[48:51], v[216:219], v[174:177], v[48:51]
	v_mfma_f32_16x16x32_bf16 v[36:39], v[208:211], v[182:185], v[36:39]
	v_mfma_f32_16x16x32_bf16 v[32:35], v[216:219], v[182:185], v[32:35]
	v_mfma_f32_16x16x32_bf16 v[20:23], v[208:211], v[190:193], v[20:23]
	v_mfma_f32_16x16x32_bf16 v[16:19], v[216:219], v[190:193], v[16:19]
	v_mfma_f32_16x16x32_bf16 v[4:7], v[208:211], v[198:201], v[4:7]
	v_mfma_f32_16x16x32_bf16 v[0:3], v[216:219], v[198:201], v[0:3]
	s_add_i32 s33, 0, 0x18000
	v_add_u32_e32 v166, s33, v155
	s_barrier
	ds_read_b128 v[146:149], v166
	ds_read_b128 v[150:153], v166 offset:1024
	ds_read_b128 v[162:165], v166 offset:2048
	ds_read_b128 v[166:169], v166 offset:3072
	s_add_u32 s48, s48, 0x80000
	s_addc_u32 s49, s49, 0
	s_mov_b32 m0, s60
	v_lshl_add_u64 v[204:205], s[48:49], 0, v[138:139]
	ds_read_b128 v[170:173], v159 offset:32768
	ds_read_b128 v[174:177], v159 offset:33792
	ds_read_b128 v[178:181], v159 offset:34816
	ds_read_b128 v[182:185], v159 offset:35840
	ds_read_b128 v[186:189], v159 offset:36864
	ds_read_b128 v[190:193], v159 offset:37888
	ds_read_b128 v[194:197], v159 offset:38912
	ds_read_b128 v[198:201], v159 offset:39936
	global_load_lds_dwordx4 v[204:205], off
	v_lshl_add_u64 v[204:205], s[48:49], 0, v[132:133]
	s_mov_b32 m0, s61
	s_nop 0
	global_load_lds_dwordx4 v[204:205], off
	s_waitcnt lgkmcnt(8)
	s_barrier
	s_waitcnt lgkmcnt(0)
	s_waitcnt lgkmcnt(0)
	v_mfma_f32_16x16x32_bf16 v[124:127], v[146:149], v[170:173], v[124:127]
	v_mfma_f32_16x16x32_bf16 v[120:123], v[162:165], v[170:173], v[120:123]
	v_mfma_f32_16x16x32_bf16 v[108:111], v[146:149], v[178:181], v[108:111]
	v_mfma_f32_16x16x32_bf16 v[104:107], v[162:165], v[178:181], v[104:107]
	v_mfma_f32_16x16x32_bf16 v[92:95], v[146:149], v[186:189], v[92:95]
	v_mfma_f32_16x16x32_bf16 v[88:91], v[162:165], v[186:189], v[88:91]
	v_mfma_f32_16x16x32_bf16 v[76:79], v[146:149], v[194:197], v[76:79]
	v_mfma_f32_16x16x32_bf16 v[72:75], v[162:165], v[194:197], v[72:75]
	v_mfma_f32_16x16x32_bf16 v[124:127], v[150:153], v[174:177], v[124:127]
	v_mfma_f32_16x16x32_bf16 v[120:123], v[166:169], v[174:177], v[120:123]
	v_mfma_f32_16x16x32_bf16 v[108:111], v[150:153], v[182:185], v[108:111]
	v_mfma_f32_16x16x32_bf16 v[104:107], v[166:169], v[182:185], v[104:107]
	v_mfma_f32_16x16x32_bf16 v[92:95], v[150:153], v[190:193], v[92:95]
	v_mfma_f32_16x16x32_bf16 v[88:91], v[166:169], v[190:193], v[88:91]
	v_mfma_f32_16x16x32_bf16 v[76:79], v[150:153], v[198:201], v[76:79]
	v_mfma_f32_16x16x32_bf16 v[72:75], v[166:169], v[198:201], v[72:75]
	s_barrier
	s_add_i32 s48, 0, 0x1c000
	s_add_i32 s33, s33, s57
	v_add_u32_e32 v216, s48, v155
	v_lshl_add_u64 v[220:221], v[220:221], 0, s[16:17]
	s_mov_b32 m0, s33
	ds_read_b128 v[204:207], v216
	ds_read_b128 v[208:211], v216 offset:1024
	ds_read_b128 v[212:215], v216 offset:2048
	ds_read_b128 v[216:219], v216 offset:3072
	global_load_lds_dwordx4 v[220:221], off
	v_lshl_add_u64 v[220:221], v[222:223], 0, s[16:17]
	s_add_i32 m0, s33, 0x2000
	s_nop 0
	global_load_lds_dwordx4 v[220:221], off
	s_barrier
	s_waitcnt lgkmcnt(0)
	s_waitcnt lgkmcnt(0)
	v_mfma_f32_16x16x32_bf16 v[116:119], v[204:207], v[170:173], v[116:119]
	v_mfma_f32_16x16x32_bf16 v[112:115], v[212:215], v[170:173], v[112:115]
	v_mfma_f32_16x16x32_bf16 v[100:103], v[204:207], v[178:181], v[100:103]
	v_mfma_f32_16x16x32_bf16 v[96:99], v[212:215], v[178:181], v[96:99]
	v_mfma_f32_16x16x32_bf16 v[84:87], v[204:207], v[186:189], v[84:87]
	v_mfma_f32_16x16x32_bf16 v[80:83], v[212:215], v[186:189], v[80:83]
	v_mfma_f32_16x16x32_bf16 v[68:71], v[204:207], v[194:197], v[68:71]
	v_mfma_f32_16x16x32_bf16 v[64:67], v[212:215], v[194:197], v[64:67]
	v_mfma_f32_16x16x32_bf16 v[116:119], v[208:211], v[174:177], v[116:119]
	v_mfma_f32_16x16x32_bf16 v[112:115], v[216:219], v[174:177], v[112:115]
	v_mfma_f32_16x16x32_bf16 v[100:103], v[208:211], v[182:185], v[100:103]
	v_mfma_f32_16x16x32_bf16 v[96:99], v[216:219], v[182:185], v[96:99]
	v_mfma_f32_16x16x32_bf16 v[84:87], v[208:211], v[190:193], v[84:87]
	v_mfma_f32_16x16x32_bf16 v[80:83], v[216:219], v[190:193], v[80:83]
	v_mfma_f32_16x16x32_bf16 v[68:71], v[208:211], v[198:201], v[68:71]
	v_mfma_f32_16x16x32_bf16 v[64:67], v[216:219], v[198:201], v[64:67]
	s_mov_b32 m0, s63
	v_lshl_add_u64 v[220:221], v[224:225], 0, s[16:17]
	s_barrier
	ds_read_b128 v[170:173], v159 offset:49152
	ds_read_b128 v[174:177], v159 offset:50176
	ds_read_b128 v[178:181], v159 offset:51200
	ds_read_b128 v[182:185], v159 offset:52224
	ds_read_b128 v[186:189], v159 offset:53248
	ds_read_b128 v[190:193], v159 offset:54272
	ds_read_b128 v[194:197], v159 offset:55296
	ds_read_b128 v[198:201], v159 offset:56320
	global_load_lds_dwordx4 v[220:221], off
	v_lshl_add_u64 v[220:221], v[226:227], 0, s[16:17]
	s_mov_b32 m0, s64
	s_nop 0
	global_load_lds_dwordx4 v[220:221], off
	s_barrier
; __device__ __forceinline__ unsigned cvt_pk_bf16(float lo, float hi) { unsigned r; asm volatile("v_cvt_pk_bf16_f32 %0, %1, %2" : "=v"(r) : "v"(lo), "v"(hi)); return r; }
; #define PG8_STAGE(bufoff, gbase, voff) do { _Pragma("unroll") for (int _i = 0; _i < 2; ++_i) \
;         __builtin_amdgcn_global_load_lds((const unsigned*)((const char*)(gbase) + (voff)[_i]), (LAS unsigned*)(lds + (bufoff) + ldsw + _i * 8192), 16, 0, 0); } while (0)
; #define PG8_WAIT_V(n) asm volatile("s_waitcnt vmcnt(" #n ")" ::: "memory")
; #define PG8_WAIT_L(n) asm volatile("s_waitcnt lgkmcnt(" #n ")" ::: "memory")
; #define PG8_BAR __builtin_amdgcn_s_barrier()
; #define PG8_SCHED __builtin_amdgcn_sched_barrier(0)
;     __device__ __forceinline__ void operator()(const f32x4 (&acc)[2][2][4][2], const Unit& u, int wr, int wc, int fr, int fq) const {
;         const int row0 = u.pm * BM + wr * 64 + fr; const int col0 = u.pn * BM + wc * 64 + 16 * fq;
; #pragma unroll
;         for (int ai = 0; ai < 2; ++ai)
; #pragma unroll
;             for (int m = 0; m < 4; ++m) { const int row = row0 + ai * HALF + m * 16;
;                 const float rs = ssin ? __builtin_amdgcn_rsqf(ssin[row] * (1.f / D) + EPS) : 1.0f; float sq = 0.f; u32x4 w[2];
; #pragma unroll
;                 for (int bj = 0; bj < 2; ++bj) { f32x4 v0 = acc[ai][bj][m][0] * rs, v1 = acc[ai][bj][m][1] * rs;
;                     if (ACT == 1) {
; #pragma unroll
;                         for (int j = 0; j < 4; ++j) { const float a = fmaxf(v0[j], 0.f), b = fmaxf(v1[j], 0.f); v0[j] = a * a; v1[j] = b * b; } }
;                     sq += (v0[0] * v0[0] + v0[1] * v0[1]) + (v0[2] * v0[2] + v0[3] * v0[3]) + (v1[0] * v1[0] + v1[1] * v1[1]) + (v1[2] * v1[2] + v1[3] * v1[3]);
;                     w[bj].x = cvt_pk_bf16(v0[0], v0[1]); w[bj].y = cvt_pk_bf16(v0[2], v0[3]); w[bj].z = cvt_pk_bf16(v1[0], v1[1]); w[bj].w = cvt_pk_bf16(v1[2], v1[3]); }
;                 store_pair_lines(O, ldc, row, fr, col0, w[0], w[1]);
; template <class Epi>
; __device__ __forceinline__ void gemm_phase(LAS unsigned char* lds, const Gemm g, const StaticOrder& S, const Epi& E) {
;     ...
;             PG8_BAR; PG8_WAIT_L(0); PG8_MMA(1, 0, At, B0); PG8_BAR; PG8_SCHED;
;             PG8_STAGE(PG8_SB(1, 1), b3, voffB1);
;             PG8_WAIT_V(6); PG8_BAR; PG8_MMA(1, 1, At, B1); PG8_BAR;
;         }
;         E(acc, cur, wr, wc, fr, fq);
	s_waitcnt lgkmcnt(0)
	s_waitcnt lgkmcnt(0)
	v_mfma_f32_16x16x32_bf16 v[60:63], v[146:149], v[170:173], v[60:63]
	v_mfma_f32_16x16x32_bf16 v[56:59], v[162:165], v[170:173], v[56:59]
	v_mfma_f32_16x16x32_bf16 v[44:47], v[146:149], v[178:181], v[44:47]
	v_mfma_f32_16x16x32_bf16 v[40:43], v[162:165], v[178:181], v[40:43]
	v_mfma_f32_16x16x32_bf16 v[28:31], v[146:149], v[186:189], v[28:31]
	v_mfma_f32_16x16x32_bf16 v[24:27], v[162:165], v[186:189], v[24:27]
	v_mfma_f32_16x16x32_bf16 v[12:15], v[146:149], v[194:197], v[12:15]
	v_mfma_f32_16x16x32_bf16 v[8:11], v[162:165], v[194:197], v[8:11]
	v_mfma_f32_16x16x32_bf16 v[60:63], v[150:153], v[174:177], v[60:63]
	v_mfma_f32_16x16x32_bf16 v[56:59], v[166:169], v[174:177], v[56:59]
	v_mfma_f32_16x16x32_bf16 v[44:47], v[150:153], v[182:185], v[44:47]
	v_mfma_f32_16x16x32_bf16 v[40:43], v[166:169], v[182:185], v[40:43]
	v_mfma_f32_16x16x32_bf16 v[28:31], v[150:153], v[190:193], v[28:31]
	v_mfma_f32_16x16x32_bf16 v[24:27], v[166:169], v[190:193], v[24:27]
	v_mfma_f32_16x16x32_bf16 v[12:15], v[150:153], v[198:201], v[12:15]
	v_mfma_f32_16x16x32_bf16 v[8:11], v[166:169], v[198:201], v[8:11]
	s_barrier
	s_add_i32 s33, s48, s57
	v_lshl_add_u64 v[146:147], v[228:229], 0, s[16:17]
	s_mov_b32 m0, s33
	s_nop 0
	global_load_lds_dwordx4 v[146:147], off
	v_lshl_add_u64 v[146:147], v[230:231], 0, s[16:17]
	s_add_i32 m0, s33, 0x2000
	s_nop 0
	global_load_lds_dwordx4 v[146:147], off
	s_waitcnt vmcnt(6)
	s_barrier
	v_mfma_f32_16x16x32_bf16 v[52:55], v[204:207], v[170:173], v[52:55]
	v_mfma_f32_16x16x32_bf16 v[48:51], v[212:215], v[170:173], v[48:51]
	v_mfma_f32_16x16x32_bf16 v[36:39], v[204:207], v[178:181], v[36:39]
	v_mfma_f32_16x16x32_bf16 v[32:35], v[212:215], v[178:181], v[32:35]
	v_mfma_f32_16x16x32_bf16 v[20:23], v[204:207], v[186:189], v[20:23]
	v_mfma_f32_16x16x32_bf16 v[16:19], v[212:215], v[186:189], v[16:19]
	v_mfma_f32_16x16x32_bf16 v[4:7], v[204:207], v[194:197], v[4:7]
	v_mfma_f32_16x16x32_bf16 v[0:3], v[212:215], v[194:197], v[0:3]
	v_mfma_f32_16x16x32_bf16 v[52:55], v[208:211], v[174:177], v[52:55]
	v_mfma_f32_16x16x32_bf16 v[48:51], v[216:219], v[174:177], v[48:51]
	v_mfma_f32_16x16x32_bf16 v[36:39], v[208:211], v[182:185], v[36:39]
	v_mfma_f32_16x16x32_bf16 v[32:35], v[216:219], v[182:185], v[32:35]
	v_mfma_f32_16x16x32_bf16 v[20:23], v[208:211], v[190:193], v[20:23]
	v_mfma_f32_16x16x32_bf16 v[16:19], v[216:219], v[190:193], v[16:19]
	v_mfma_f32_16x16x32_bf16 v[4:7], v[208:211], v[198:201], v[4:7]
	v_mfma_f32_16x16x32_bf16 v[0:3], v[216:219], v[198:201], v[0:3]
	s_add_i32 s77, s77, 2
	s_add_u32 s46, s46, 0x100
	s_addc_u32 s47, s47, 0
	s_add_u32 s74, s74, 0x100
	s_addc_u32 s75, s75, 0
	s_cmp_gt_u32 s77, 29
	s_barrier
	s_cbranch_scc0 .LBB0_962
	s_lshl_b32 s19, s44, 8
	s_add_i32 s19, s19, s65
	v_or_b32_e32 v152, s19, v154
	v_ashrrev_i32_e32 v153, 31, v152
	v_lshl_add_u64 v[150:151], v[152:153], 2, s[10:11]
	global_load_dword v153, v[150:151], off
	v_or_b32_e32 v180, 16, v152
	v_ashrrev_i32_e32 v181, 31, v180
	v_lshl_add_u64 v[182:183], v[180:181], 2, s[10:11]
	global_load_dword v179, v[182:183], off
	v_or_b32_e32 v180, 32, v152
	v_ashrrev_i32_e32 v181, 31, v180
	v_lshl_add_u64 v[182:183], v[180:181], 2, s[10:11]
	global_load_dword v184, v[182:183], off
	v_or_b32_e32 v180, 48, v152
	v_ashrrev_i32_e32 v181, 31, v180
	v_lshl_add_u64 v[182:183], v[180:181], 2, s[10:11]
	global_load_dword v185, v[182:183], off
	global_load_dword v186, v[150:151], off offset:512
	global_load_dword v187, v[150:151], off offset:576
	global_load_dword v188, v[150:151], off offset:640
	global_load_dword v189, v[150:151], off offset:704
	v_lshl_or_b32 v148, s71, 8, v157
	v_mov_b32_e32 v169, 0
	v_mov_b32_e32 v175, 0
	v_mov_b32_e32 v176, 0
	v_mov_b32_e32 v177, 0
	v_mov_b32_e32 v178, 0
	v_mov_b64_e32 v[146:147], s[8:9]
	v_ashrrev_i32_e32 v149, 31, v148
	v_or_b32_e32 v164, s19, v156
	v_mov_b32_e32 v172, 0
	v_mov_b32_e32 v173, 0
	v_mov_b32_e32 v174, 0
	v_lshlrev_b64 v[148:149], 1, v[148:149]
	v_mad_i64_i32 v[162:163], s[46:47], v164, s70, v[146:147]
	v_or_b32_e32 v165, 8, v164
	v_or_b32_e32 v164, 16, v152
	v_lshl_add_u64 v[162:163], v[162:163], 0, v[148:149]
	v_mad_i64_i32 v[166:167], s[46:47], v165, s70, v[146:147]
	v_ashrrev_i32_e32 v165, 31, v164
	v_lshl_add_u64 v[166:167], v[166:167], 0, v[148:149]
	v_lshl_add_u64 v[170:171], v[164:165], 2, s[10:11]
	s_and_b64 vcc, exec, s[40:41]
	s_mov_b32 s71, s18
	s_mov_b32 s44, s36
	s_mov_b64 s[48:49], s[42:43]
	s_waitcnt vmcnt(7)
	v_fmamk_f32 v153, v153, 0x3a000000, v161
	v_rsq_f32_e32 v168, v153
	v_mov_b32_e32 v153, 0
	v_pk_mul_f32 v[124:125], v[124:125], v[168:169] op_sel_hi:[1,0]
	v_pk_mul_f32 v[120:121], v[120:121], v[168:169] op_sel_hi:[1,0]
	v_pk_mul_f32 v[118:119], v[118:119], v[168:169] op_sel_hi:[1,0]
	v_pk_mul_f32 v[116:117], v[116:117], v[168:169] op_sel_hi:[1,0]
	v_pk_mul_f32 v[126:127], v[126:127], v[168:169] op_sel_hi:[1,0]
	v_pk_mul_f32 v[122:123], v[122:123], v[168:169] op_sel_hi:[1,0]
	v_pk_mul_f32 v[114:115], v[114:115], v[168:169] op_sel_hi:[1,0]
	v_pk_mul_f32 v[112:113], v[112:113], v[168:169] op_sel_hi:[1,0]
	v_cvt_pk_bf16_f32 v124, v124, v125
	v_cvt_pk_bf16_f32 v125, v126, v127
	v_cvt_pk_bf16_f32 v120, v120, v121
	v_cvt_pk_bf16_f32 v121, v122, v123
	v_cvt_pk_bf16_f32 v116, v116, v117
	v_cvt_pk_bf16_f32 v117, v118, v119
	s_nop 0
	v_cvt_pk_bf16_f32 v118, v112, v113
	v_cvt_pk_bf16_f32 v119, v114, v115
	s_nop 0
	v_mov_b32_dpp v169, v124 row_ror:8 row_mask:0xf bank_mask:0xf
	v_mov_b32_dpp v172, v125 row_ror:8 row_mask:0xf bank_mask:0xf
	v_mov_b32_dpp v175, v116 row_ror:8 row_mask:0xf bank_mask:0xf
	v_mov_b32_dpp v176, v117 row_ror:8 row_mask:0xf bank_mask:0xf
	v_mov_b32_dpp v177, v118 row_ror:8 row_mask:0xf bank_mask:0xf
	v_mov_b32_dpp v178, v119 row_ror:8 row_mask:0xf bank_mask:0xf
	v_mov_b32_dpp v173, v120 row_ror:8 row_mask:0xf bank_mask:0xf
	v_mov_b32_dpp v174, v121 row_ror:8 row_mask:0xf bank_mask:0xf
	v_cndmask_b32_e64 v112, v175, v124, s[6:7]
	v_cndmask_b32_e64 v113, v176, v125, s[6:7]
	v_cndmask_b32_e64 v114, v177, v120, s[6:7]
	v_cndmask_b32_e64 v115, v178, v121, s[6:7]
	v_cndmask_b32_e64 v116, v116, v169, s[6:7]
	v_cndmask_b32_e64 v117, v117, v172, s[6:7]
	v_cndmask_b32_e64 v118, v118, v173, s[6:7]
	v_cndmask_b32_e64 v119, v119, v174, s[6:7]
	global_store_dwordx4 v[162:163], v[112:115], off
	global_store_dwordx4 v[166:167], v[116:119], off
	s_waitcnt vmcnt(8)
; __device__ __forceinline__ unsigned cvt_pk_bf16(float lo, float hi) { unsigned r; asm volatile("v_cvt_pk_bf16_f32 %0, %1, %2" : "=v"(r) : "v"(lo), "v"(hi)); return r; }
;     __device__ __forceinline__ void operator()(const f32x4 (&acc)[2][2][4][2], const Unit& u, int wr, int wc, int fr, int fq) const {
;     ...
;             for (int m = 0; m < 4; ++m) { const int row = row0 + ai * HALF + m * 16;
;                 const float rs = ssin ? __builtin_amdgcn_rsqf(ssin[row] * (1.f / D) + EPS) : 1.0f; float sq = 0.f; u32x4 w[2];
; #pragma unroll
;                 for (int bj = 0; bj < 2; ++bj) { f32x4 v0 = acc[ai][bj][m][0] * rs, v1 = acc[ai][bj][m][1] * rs;
;                     if (ACT == 1) {
; #pragma unroll
;                         for (int j = 0; j < 4; ++j) { const float a = fmaxf(v0[j], 0.f), b = fmaxf(v1[j], 0.f); v0[j] = a * a; v1[j] = b * b; } }
;                     sq += (v0[0] * v0[0] + v0[1] * v0[1]) + (v0[2] * v0[2] + v0[3] * v0[3]) + (v1[0] * v1[0] + v1[1] * v1[1]) + (v1[2] * v1[2] + v1[3] * v1[3]);
;                     w[bj].x = cvt_pk_bf16(v0[0], v0[1]); w[bj].y = cvt_pk_bf16(v0[2], v0[3]); w[bj].z = cvt_pk_bf16(v1[0], v1[1]); w[bj].w = cvt_pk_bf16(v1[2], v1[3]); }
;                 store_pair_lines(O, ldc, row, fr, col0, w[0], w[1]);
	s_nop 0
	v_mov_b32_e32 v118, v179
	s_nop 1
	v_or_b32_e32 v112, 32, v152
	v_mov_b32_e32 v119, 0
	v_sub_u32_e32 v114, v164, v154
	v_mov_b32_e32 v125, 0
	v_mov_b32_e32 v126, 0
	v_mov_b32_e32 v127, 0
	v_ashrrev_i32_e32 v113, 31, v112
	v_add_u32_e32 v120, v114, v156
	v_mov_b32_e32 v122, 0
	v_mov_b32_e32 v123, 0
	v_mov_b32_e32 v124, 0
	v_lshl_add_u64 v[114:115], v[112:113], 2, s[10:11]
	v_mad_i64_i32 v[116:117], s[46:47], v120, s70, v[146:147]
	v_add_u32_e32 v113, 8, v120
	v_lshl_add_u64 v[116:117], v[116:117], 0, v[148:149]
	v_mad_i64_i32 v[120:121], s[46:47], v113, s70, v[146:147]
	v_lshl_add_u64 v[120:121], v[120:121], 0, v[148:149]
	v_mov_b32_e32 v113, 0
	v_fmamk_f32 v118, v118, 0x3a000000, v161
	v_rsq_f32_e32 v118, v118
	s_nop 0
	v_pk_mul_f32 v[108:109], v[108:109], v[118:119] op_sel_hi:[1,0]
	v_pk_mul_f32 v[104:105], v[104:105], v[118:119] op_sel_hi:[1,0]
	v_pk_mul_f32 v[102:103], v[102:103], v[118:119] op_sel_hi:[1,0]
	v_pk_mul_f32 v[100:101], v[100:101], v[118:119] op_sel_hi:[1,0]
	v_pk_mul_f32 v[110:111], v[110:111], v[118:119] op_sel_hi:[1,0]
	v_pk_mul_f32 v[106:107], v[106:107], v[118:119] op_sel_hi:[1,0]
	v_pk_mul_f32 v[98:99], v[98:99], v[118:119] op_sel_hi:[1,0]
	v_pk_mul_f32 v[96:97], v[96:97], v[118:119] op_sel_hi:[1,0]
	v_cvt_pk_bf16_f32 v108, v108, v109
	v_cvt_pk_bf16_f32 v109, v110, v111
	v_cvt_pk_bf16_f32 v104, v104, v105
	v_cvt_pk_bf16_f32 v105, v106, v107
	v_cvt_pk_bf16_f32 v100, v100, v101
	v_cvt_pk_bf16_f32 v101, v102, v103
	s_nop 0
	v_cvt_pk_bf16_f32 v102, v96, v97
	v_cvt_pk_bf16_f32 v103, v98, v99
	s_nop 0
	v_mov_b32_dpp v119, v108 row_ror:8 row_mask:0xf bank_mask:0xf
	v_mov_b32_dpp v122, v109 row_ror:8 row_mask:0xf bank_mask:0xf
	v_mov_b32_dpp v125, v100 row_ror:8 row_mask:0xf bank_mask:0xf
	v_mov_b32_dpp v126, v101 row_ror:8 row_mask:0xf bank_mask:0xf
	v_mov_b32_dpp v127, v102 row_ror:8 row_mask:0xf bank_mask:0xf
	v_mov_b32_dpp v153, v103 row_ror:8 row_mask:0xf bank_mask:0xf
	v_mov_b32_dpp v123, v104 row_ror:8 row_mask:0xf bank_mask:0xf
	v_mov_b32_dpp v124, v105 row_ror:8 row_mask:0xf bank_mask:0xf
	v_cndmask_b32_e64 v96, v125, v108, s[6:7]
	v_cndmask_b32_e64 v97, v126, v109, s[6:7]
	v_cndmask_b32_e64 v98, v127, v104, s[6:7]
	v_cndmask_b32_e64 v99, v153, v105, s[6:7]
	v_cndmask_b32_e64 v100, v100, v119, s[6:7]
	v_cndmask_b32_e64 v101, v101, v122, s[6:7]
	v_cndmask_b32_e64 v102, v102, v123, s[6:7]
	v_cndmask_b32_e64 v103, v103, v124, s[6:7]
	global_store_dwordx4 v[116:117], v[96:99], off
	global_store_dwordx4 v[120:121], v[100:103], off
	s_waitcnt vmcnt(9)
	s_nop 0
	v_mov_b32_e32 v102, v184
	s_nop 1
	v_or_b32_e32 v96, 48, v152
	v_mov_b32_e32 v103, 0
	v_sub_u32_e32 v98, v112, v154
	v_mov_b32_e32 v109, 0
	v_mov_b32_e32 v110, 0
	v_mov_b32_e32 v111, 0
	v_ashrrev_i32_e32 v97, 31, v96
	v_add_u32_e32 v104, v98, v156
	v_mov_b32_e32 v106, 0
	v_mov_b32_e32 v107, 0
	v_mov_b32_e32 v108, 0
	v_lshl_add_u64 v[98:99], v[96:97], 2, s[10:11]
	v_mad_i64_i32 v[100:101], s[46:47], v104, s70, v[146:147]
	v_add_u32_e32 v97, 8, v104
	v_lshl_add_u64 v[100:101], v[100:101], 0, v[148:149]
	v_mad_i64_i32 v[104:105], s[46:47], v97, s70, v[146:147]
	v_lshl_add_u64 v[104:105], v[104:105], 0, v[148:149]
	v_fmamk_f32 v102, v102, 0x3a000000, v161
	v_rsq_f32_e32 v102, v102
	s_nop 0
	v_pk_mul_f32 v[92:93], v[92:93], v[102:103] op_sel_hi:[1,0]
	v_pk_mul_f32 v[88:89], v[88:89], v[102:103] op_sel_hi:[1,0]
	v_pk_mul_f32 v[86:87], v[86:87], v[102:103] op_sel_hi:[1,0]
	v_pk_mul_f32 v[84:85], v[84:85], v[102:103] op_sel_hi:[1,0]
	v_pk_mul_f32 v[94:95], v[94:95], v[102:103] op_sel_hi:[1,0]
	v_pk_mul_f32 v[90:91], v[90:91], v[102:103] op_sel_hi:[1,0]
	v_pk_mul_f32 v[82:83], v[82:83], v[102:103] op_sel_hi:[1,0]
	v_pk_mul_f32 v[80:81], v[80:81], v[102:103] op_sel_hi:[1,0]
	v_cvt_pk_bf16_f32 v92, v92, v93
	v_cvt_pk_bf16_f32 v93, v94, v95
	v_cvt_pk_bf16_f32 v88, v88, v89
	v_cvt_pk_bf16_f32 v89, v90, v91
	v_cvt_pk_bf16_f32 v84, v84, v85
	v_cvt_pk_bf16_f32 v85, v86, v87
	s_nop 0
	v_cvt_pk_bf16_f32 v86, v80, v81
	v_cvt_pk_bf16_f32 v87, v82, v83
	s_nop 0
	v_mov_b32_dpp v103, v92 row_ror:8 row_mask:0xf bank_mask:0xf
	v_mov_b32_dpp v106, v93 row_ror:8 row_mask:0xf bank_mask:0xf
	v_mov_b32_dpp v109, v84 row_ror:8 row_mask:0xf bank_mask:0xf
	v_mov_b32_dpp v110, v85 row_ror:8 row_mask:0xf bank_mask:0xf
	v_mov_b32_dpp v111, v86 row_ror:8 row_mask:0xf bank_mask:0xf
	v_mov_b32_dpp v113, v87 row_ror:8 row_mask:0xf bank_mask:0xf
	v_mov_b32_dpp v107, v88 row_ror:8 row_mask:0xf bank_mask:0xf
	v_mov_b32_dpp v108, v89 row_ror:8 row_mask:0xf bank_mask:0xf
	v_cndmask_b32_e64 v80, v109, v92, s[6:7]
	v_cndmask_b32_e64 v81, v110, v93, s[6:7]
	v_cndmask_b32_e64 v82, v111, v88, s[6:7]
	v_cndmask_b32_e64 v83, v113, v89, s[6:7]
	v_cndmask_b32_e64 v84, v84, v103, s[6:7]
	v_cndmask_b32_e64 v85, v85, v106, s[6:7]
	v_cndmask_b32_e64 v86, v86, v107, s[6:7]
	v_cndmask_b32_e64 v87, v87, v108, s[6:7]
	global_store_dwordx4 v[100:101], v[80:83], off
	global_store_dwordx4 v[104:105], v[84:87], off
	s_waitcnt vmcnt(10)
; __device__ __forceinline__ unsigned cvt_pk_bf16(float lo, float hi) { unsigned r; asm volatile("v_cvt_pk_bf16_f32 %0, %1, %2" : "=v"(r) : "v"(lo), "v"(hi)); return r; }
;     __device__ __forceinline__ void operator()(const f32x4 (&acc)[2][2][4][2], const Unit& u, int wr, int wc, int fr, int fq) const {
;     ...
;             for (int m = 0; m < 4; ++m) { const int row = row0 + ai * HALF + m * 16;
;                 const float rs = ssin ? __builtin_amdgcn_rsqf(ssin[row] * (1.f / D) + EPS) : 1.0f; float sq = 0.f; u32x4 w[2];
; #pragma unroll
;                 for (int bj = 0; bj < 2; ++bj) { f32x4 v0 = acc[ai][bj][m][0] * rs, v1 = acc[ai][bj][m][1] * rs;
;                     if (ACT == 1) {
; #pragma unroll
;                         for (int j = 0; j < 4; ++j) { const float a = fmaxf(v0[j], 0.f), b = fmaxf(v1[j], 0.f); v0[j] = a * a; v1[j] = b * b; } }
;                     sq += (v0[0] * v0[0] + v0[1] * v0[1]) + (v0[2] * v0[2] + v0[3] * v0[3]) + (v1[0] * v1[0] + v1[1] * v1[1]) + (v1[2] * v1[2] + v1[3] * v1[3]);
;                     w[bj].x = cvt_pk_bf16(v0[0], v0[1]); w[bj].y = cvt_pk_bf16(v0[2], v0[3]); w[bj].z = cvt_pk_bf16(v1[0], v1[1]); w[bj].w = cvt_pk_bf16(v1[2], v1[3]); }
;                 store_pair_lines(O, ldc, row, fr, col0, w[0], w[1]);
	s_nop 0
	v_mov_b32_e32 v82, v185
	s_nop 1
	v_mov_b32_e32 v83, 0
	v_sub_u32_e32 v80, v96, v154
	v_mov_b32_e32 v89, 0
	v_mov_b32_e32 v90, 0
	v_mov_b32_e32 v91, 0
	v_mov_b32_e32 v92, 0
	v_add_u32_e32 v84, v80, v156
	v_mov_b32_e32 v86, 0
	v_mov_b32_e32 v87, 0
	v_mov_b32_e32 v88, 0
	v_mad_i64_i32 v[80:81], s[46:47], v84, s70, v[146:147]
	v_add_u32_e32 v84, 8, v84
	v_lshl_add_u64 v[80:81], v[80:81], 0, v[148:149]
	v_mad_i64_i32 v[84:85], s[46:47], v84, s70, v[146:147]
	v_lshl_add_u64 v[84:85], v[84:85], 0, v[148:149]
	v_fmamk_f32 v82, v82, 0x3a000000, v161
	v_rsq_f32_e32 v82, v82
	s_nop 0
	v_pk_mul_f32 v[76:77], v[76:77], v[82:83] op_sel_hi:[1,0]
	v_pk_mul_f32 v[72:73], v[72:73], v[82:83] op_sel_hi:[1,0]
	v_pk_mul_f32 v[70:71], v[70:71], v[82:83] op_sel_hi:[1,0]
	v_pk_mul_f32 v[68:69], v[68:69], v[82:83] op_sel_hi:[1,0]
	v_pk_mul_f32 v[78:79], v[78:79], v[82:83] op_sel_hi:[1,0]
	v_pk_mul_f32 v[74:75], v[74:75], v[82:83] op_sel_hi:[1,0]
	v_pk_mul_f32 v[66:67], v[66:67], v[82:83] op_sel_hi:[1,0]
	v_pk_mul_f32 v[64:65], v[64:65], v[82:83] op_sel_hi:[1,0]
	v_cvt_pk_bf16_f32 v76, v76, v77
	v_cvt_pk_bf16_f32 v77, v78, v79
	v_cvt_pk_bf16_f32 v72, v72, v73
	v_cvt_pk_bf16_f32 v73, v74, v75
	v_cvt_pk_bf16_f32 v68, v68, v69
	v_cvt_pk_bf16_f32 v69, v70, v71
	s_nop 0
	v_cvt_pk_bf16_f32 v70, v64, v65
	v_cvt_pk_bf16_f32 v71, v66, v67
	s_nop 0
	v_mov_b32_dpp v83, v76 row_ror:8 row_mask:0xf bank_mask:0xf
	v_mov_b32_dpp v86, v77 row_ror:8 row_mask:0xf bank_mask:0xf
	v_mov_b32_dpp v89, v68 row_ror:8 row_mask:0xf bank_mask:0xf
	v_mov_b32_dpp v90, v69 row_ror:8 row_mask:0xf bank_mask:0xf
	v_mov_b32_dpp v91, v70 row_ror:8 row_mask:0xf bank_mask:0xf
	v_mov_b32_dpp v92, v71 row_ror:8 row_mask:0xf bank_mask:0xf
	v_mov_b32_dpp v87, v72 row_ror:8 row_mask:0xf bank_mask:0xf
	v_mov_b32_dpp v88, v73 row_ror:8 row_mask:0xf bank_mask:0xf
	v_cndmask_b32_e64 v64, v89, v76, s[6:7]
	v_cndmask_b32_e64 v65, v90, v77, s[6:7]
	v_cndmask_b32_e64 v66, v91, v72, s[6:7]
	v_cndmask_b32_e64 v67, v92, v73, s[6:7]
	v_cndmask_b32_e64 v68, v68, v83, s[6:7]
	v_cndmask_b32_e64 v69, v69, v86, s[6:7]
	v_cndmask_b32_e64 v70, v70, v87, s[6:7]
	v_cndmask_b32_e64 v71, v71, v88, s[6:7]
	global_store_dwordx4 v[80:81], v[64:67], off
	global_store_dwordx4 v[84:85], v[68:71], off
	s_waitcnt vmcnt(11)
	s_nop 0
	v_mov_b32_e32 v66, v186
	s_nop 1
	v_sub_u32_e32 v64, v152, v154
	v_mov_b32_e32 v67, 0
	v_add_u32_e32 v77, v64, v156
	v_mov_b32_e32 v73, 0
	v_mov_b32_e32 v74, 0
	v_mov_b32_e32 v75, 0
	v_mov_b32_e32 v76, 0
	v_add_u32_e32 v64, 0x80, v77
	v_mov_b32_e32 v70, 0
	v_mov_b32_e32 v71, 0
	v_mov_b32_e32 v72, 0
	v_add_u32_e32 v68, 0x88, v77
	v_mad_i64_i32 v[64:65], s[46:47], v64, s70, v[146:147]
	v_mad_i64_i32 v[68:69], s[46:47], v68, s70, v[146:147]
	v_lshl_add_u64 v[64:65], v[64:65], 0, v[148:149]
	v_lshl_add_u64 v[68:69], v[68:69], 0, v[148:149]
	v_fmamk_f32 v66, v66, 0x3a000000, v161
	v_rsq_f32_e32 v66, v66
	s_nop 0
	v_pk_mul_f32 v[60:61], v[60:61], v[66:67] op_sel_hi:[1,0]
	v_pk_mul_f32 v[56:57], v[56:57], v[66:67] op_sel_hi:[1,0]
	v_pk_mul_f32 v[54:55], v[54:55], v[66:67] op_sel_hi:[1,0]
	v_pk_mul_f32 v[52:53], v[52:53], v[66:67] op_sel_hi:[1,0]
	v_pk_mul_f32 v[62:63], v[62:63], v[66:67] op_sel_hi:[1,0]
	v_pk_mul_f32 v[58:59], v[58:59], v[66:67] op_sel_hi:[1,0]
	v_pk_mul_f32 v[50:51], v[50:51], v[66:67] op_sel_hi:[1,0]
	v_pk_mul_f32 v[48:49], v[48:49], v[66:67] op_sel_hi:[1,0]
	v_cvt_pk_bf16_f32 v60, v60, v61
	v_cvt_pk_bf16_f32 v61, v62, v63
	v_cvt_pk_bf16_f32 v56, v56, v57
	v_cvt_pk_bf16_f32 v57, v58, v59
	v_cvt_pk_bf16_f32 v52, v52, v53
	v_cvt_pk_bf16_f32 v53, v54, v55
	s_nop 0
	v_cvt_pk_bf16_f32 v54, v48, v49
	v_cvt_pk_bf16_f32 v55, v50, v51
	s_nop 0
	v_mov_b32_dpp v67, v60 row_ror:8 row_mask:0xf bank_mask:0xf
	v_mov_b32_dpp v70, v61 row_ror:8 row_mask:0xf bank_mask:0xf
	v_mov_b32_dpp v73, v52 row_ror:8 row_mask:0xf bank_mask:0xf
	v_mov_b32_dpp v74, v53 row_ror:8 row_mask:0xf bank_mask:0xf
	v_mov_b32_dpp v75, v54 row_ror:8 row_mask:0xf bank_mask:0xf
	v_mov_b32_dpp v76, v55 row_ror:8 row_mask:0xf bank_mask:0xf
	v_mov_b32_dpp v71, v56 row_ror:8 row_mask:0xf bank_mask:0xf
	v_mov_b32_dpp v72, v57 row_ror:8 row_mask:0xf bank_mask:0xf
	v_cndmask_b32_e64 v48, v73, v60, s[6:7]
	v_cndmask_b32_e64 v49, v74, v61, s[6:7]
	v_cndmask_b32_e64 v50, v75, v56, s[6:7]
	v_cndmask_b32_e64 v51, v76, v57, s[6:7]
	v_cndmask_b32_e64 v52, v52, v67, s[6:7]
	v_cndmask_b32_e64 v53, v53, v70, s[6:7]
	v_cndmask_b32_e64 v54, v54, v71, s[6:7]
	v_cndmask_b32_e64 v55, v55, v72, s[6:7]
	global_store_dwordx4 v[64:65], v[48:51], off
	global_store_dwordx4 v[68:69], v[52:55], off
	s_waitcnt vmcnt(12)
; __device__ __forceinline__ unsigned cvt_pk_bf16(float lo, float hi) { unsigned r; asm volatile("v_cvt_pk_bf16_f32 %0, %1, %2" : "=v"(r) : "v"(lo), "v"(hi)); return r; }
; #define PG8_WAIT_V(n) asm volatile("s_waitcnt vmcnt(" #n ")" ::: "memory")
; #define PG8_BAR __builtin_amdgcn_s_barrier()
;     __device__ __forceinline__ void operator()(const f32x4 (&acc)[2][2][4][2], const Unit& u, int wr, int wc, int fr, int fq) const {
;     ...
;             for (int m = 0; m < 4; ++m) { const int row = row0 + ai * HALF + m * 16;
;                 const float rs = ssin ? __builtin_amdgcn_rsqf(ssin[row] * (1.f / D) + EPS) : 1.0f; float sq = 0.f; u32x4 w[2];
; #pragma unroll
;                 for (int bj = 0; bj < 2; ++bj) { f32x4 v0 = acc[ai][bj][m][0] * rs, v1 = acc[ai][bj][m][1] * rs;
;                     if (ACT == 1) {
; #pragma unroll
;                         for (int j = 0; j < 4; ++j) { const float a = fmaxf(v0[j], 0.f), b = fmaxf(v1[j], 0.f); v0[j] = a * a; v1[j] = b * b; } }
;                     sq += (v0[0] * v0[0] + v0[1] * v0[1]) + (v0[2] * v0[2] + v0[3] * v0[3]) + (v1[0] * v1[0] + v1[1] * v1[1]) + (v1[2] * v1[2] + v1[3] * v1[3]);
;                     w[bj].x = cvt_pk_bf16(v0[0], v0[1]); w[bj].y = cvt_pk_bf16(v0[2], v0[3]); w[bj].z = cvt_pk_bf16(v1[0], v1[1]); w[bj].w = cvt_pk_bf16(v1[2], v1[3]); }
;                 store_pair_lines(O, ldc, row, fr, col0, w[0], w[1]);
; template <class Epi>
; __device__ __forceinline__ void gemm_phase(LAS unsigned char* lds, const Gemm g, const StaticOrder& S, const Epi& E) {
;     ...
;         E(acc, cur, wr, wc, fr, fq);
;         if (!has_next) break;
; #pragma unroll
;         for (int a = 0; a < 2; ++a)
; #pragma unroll
;             for (int b = 0; b < 2; ++b)
; #pragma unroll
;                 for (int m = 0; m < 4; ++m)
; #pragma unroll
;                     for (int n = 0; n < 2; ++n) acc[a][b][m][n] = (f32x4){0.f, 0.f, 0.f, 0.f};
;         cur = nxt; cA = nA; cB = nB; ++ui;
;     }
;     PG8_WAIT_V(0);
;     if (wr == 0) PG8_BAR;
;     PG8_BAR;
	s_nop 0
	v_mov_b32_e32 v50, v187
	s_nop 1
	v_mov_b32_e32 v51, 0
	v_mov_b32_e32 v57, 0
	v_mov_b32_e32 v58, 0
	v_mov_b32_e32 v59, 0
	v_mov_b32_e32 v60, 0
	v_add_u32_e32 v48, 0x90, v77
	v_mov_b32_e32 v54, 0
	v_mov_b32_e32 v55, 0
	v_mov_b32_e32 v56, 0
	v_add_u32_e32 v52, 0x98, v77
	v_mad_i64_i32 v[48:49], s[46:47], v48, s70, v[146:147]
	v_mad_i64_i32 v[52:53], s[46:47], v52, s70, v[146:147]
	v_lshl_add_u64 v[48:49], v[48:49], 0, v[148:149]
	v_lshl_add_u64 v[52:53], v[52:53], 0, v[148:149]
	v_fmamk_f32 v50, v50, 0x3a000000, v161
	v_rsq_f32_e32 v50, v50
	s_nop 0
	v_pk_mul_f32 v[44:45], v[44:45], v[50:51] op_sel_hi:[1,0]
	v_pk_mul_f32 v[40:41], v[40:41], v[50:51] op_sel_hi:[1,0]
	v_pk_mul_f32 v[38:39], v[38:39], v[50:51] op_sel_hi:[1,0]
	v_pk_mul_f32 v[36:37], v[36:37], v[50:51] op_sel_hi:[1,0]
	v_pk_mul_f32 v[46:47], v[46:47], v[50:51] op_sel_hi:[1,0]
	v_pk_mul_f32 v[42:43], v[42:43], v[50:51] op_sel_hi:[1,0]
	v_pk_mul_f32 v[34:35], v[34:35], v[50:51] op_sel_hi:[1,0]
	v_pk_mul_f32 v[32:33], v[32:33], v[50:51] op_sel_hi:[1,0]
	v_cvt_pk_bf16_f32 v44, v44, v45
	v_cvt_pk_bf16_f32 v45, v46, v47
	v_cvt_pk_bf16_f32 v40, v40, v41
	v_cvt_pk_bf16_f32 v41, v42, v43
	v_cvt_pk_bf16_f32 v36, v36, v37
	v_cvt_pk_bf16_f32 v37, v38, v39
	s_nop 0
	v_cvt_pk_bf16_f32 v38, v32, v33
	v_cvt_pk_bf16_f32 v39, v34, v35
	s_nop 0
	v_mov_b32_dpp v51, v44 row_ror:8 row_mask:0xf bank_mask:0xf
	v_mov_b32_dpp v54, v45 row_ror:8 row_mask:0xf bank_mask:0xf
	v_mov_b32_dpp v57, v36 row_ror:8 row_mask:0xf bank_mask:0xf
	v_mov_b32_dpp v58, v37 row_ror:8 row_mask:0xf bank_mask:0xf
	v_mov_b32_dpp v59, v38 row_ror:8 row_mask:0xf bank_mask:0xf
	v_mov_b32_dpp v60, v39 row_ror:8 row_mask:0xf bank_mask:0xf
	v_mov_b32_dpp v55, v40 row_ror:8 row_mask:0xf bank_mask:0xf
	v_mov_b32_dpp v56, v41 row_ror:8 row_mask:0xf bank_mask:0xf
	v_cndmask_b32_e64 v32, v57, v44, s[6:7]
	v_cndmask_b32_e64 v33, v58, v45, s[6:7]
	v_cndmask_b32_e64 v34, v59, v40, s[6:7]
	v_cndmask_b32_e64 v35, v60, v41, s[6:7]
	v_cndmask_b32_e64 v36, v36, v51, s[6:7]
	v_cndmask_b32_e64 v37, v37, v54, s[6:7]
	v_cndmask_b32_e64 v38, v38, v55, s[6:7]
	v_cndmask_b32_e64 v39, v39, v56, s[6:7]
	global_store_dwordx4 v[48:49], v[32:35], off
	global_store_dwordx4 v[52:53], v[36:39], off
	s_waitcnt vmcnt(13)
	s_nop 0
	v_mov_b32_e32 v34, v188
	s_nop 1
	v_mov_b32_e32 v35, 0
	v_mov_b32_e32 v41, 0
	v_mov_b32_e32 v42, 0
	v_mov_b32_e32 v43, 0
	v_mov_b32_e32 v44, 0
	v_add_u32_e32 v32, 0xa0, v77
	v_mov_b32_e32 v38, 0
	v_mov_b32_e32 v39, 0
	v_mov_b32_e32 v40, 0
	v_add_u32_e32 v36, 0xa8, v77
	v_mad_i64_i32 v[32:33], s[46:47], v32, s70, v[146:147]
	v_mad_i64_i32 v[36:37], s[46:47], v36, s70, v[146:147]
	v_lshl_add_u64 v[32:33], v[32:33], 0, v[148:149]
	v_lshl_add_u64 v[36:37], v[36:37], 0, v[148:149]
	s_mov_b64 s[46:47], s[38:39]
	v_fmamk_f32 v34, v34, 0x3a000000, v161
	v_rsq_f32_e32 v34, v34
	s_nop 0
	v_pk_mul_f32 v[28:29], v[28:29], v[34:35] op_sel_hi:[1,0]
	v_pk_mul_f32 v[24:25], v[24:25], v[34:35] op_sel_hi:[1,0]
	v_pk_mul_f32 v[22:23], v[22:23], v[34:35] op_sel_hi:[1,0]
	v_pk_mul_f32 v[20:21], v[20:21], v[34:35] op_sel_hi:[1,0]
	v_pk_mul_f32 v[30:31], v[30:31], v[34:35] op_sel_hi:[1,0]
	v_pk_mul_f32 v[26:27], v[26:27], v[34:35] op_sel_hi:[1,0]
	v_pk_mul_f32 v[18:19], v[18:19], v[34:35] op_sel_hi:[1,0]
	v_pk_mul_f32 v[16:17], v[16:17], v[34:35] op_sel_hi:[1,0]
	v_cvt_pk_bf16_f32 v28, v28, v29
	v_cvt_pk_bf16_f32 v29, v30, v31
	v_cvt_pk_bf16_f32 v24, v24, v25
	v_cvt_pk_bf16_f32 v25, v26, v27
	v_cvt_pk_bf16_f32 v20, v20, v21
	v_cvt_pk_bf16_f32 v21, v22, v23
	s_nop 0
	v_cvt_pk_bf16_f32 v22, v16, v17
	v_cvt_pk_bf16_f32 v23, v18, v19
	s_nop 0
	v_mov_b32_dpp v35, v28 row_ror:8 row_mask:0xf bank_mask:0xf
	v_mov_b32_dpp v38, v29 row_ror:8 row_mask:0xf bank_mask:0xf
	v_mov_b32_dpp v41, v20 row_ror:8 row_mask:0xf bank_mask:0xf
	v_mov_b32_dpp v42, v21 row_ror:8 row_mask:0xf bank_mask:0xf
	v_mov_b32_dpp v43, v22 row_ror:8 row_mask:0xf bank_mask:0xf
	v_mov_b32_dpp v44, v23 row_ror:8 row_mask:0xf bank_mask:0xf
	v_mov_b32_dpp v39, v24 row_ror:8 row_mask:0xf bank_mask:0xf
	v_mov_b32_dpp v40, v25 row_ror:8 row_mask:0xf bank_mask:0xf
	v_cndmask_b32_e64 v16, v41, v28, s[6:7]
	v_cndmask_b32_e64 v17, v42, v29, s[6:7]
	v_cndmask_b32_e64 v18, v43, v24, s[6:7]
	v_cndmask_b32_e64 v19, v44, v25, s[6:7]
	v_cndmask_b32_e64 v20, v20, v35, s[6:7]
	v_cndmask_b32_e64 v21, v21, v38, s[6:7]
	v_cndmask_b32_e64 v22, v22, v39, s[6:7]
	v_cndmask_b32_e64 v23, v23, v40, s[6:7]
	global_store_dwordx4 v[32:33], v[16:19], off
	global_store_dwordx4 v[36:37], v[20:23], off
	s_waitcnt vmcnt(14)
	s_nop 0
	v_mov_b32_e32 v18, v189
	s_nop 1
	v_mov_b32_e32 v19, 0
	v_mov_b32_e32 v25, 0
	v_mov_b32_e32 v26, 0
	v_mov_b32_e32 v27, 0
	v_mov_b32_e32 v28, 0
	v_add_u32_e32 v16, 0xb0, v77
	v_mov_b32_e32 v22, 0
	v_mov_b32_e32 v23, 0
	v_mov_b32_e32 v24, 0
	v_add_u32_e32 v20, 0xb8, v77
	v_mad_i64_i32 v[16:17], s[38:39], v16, s70, v[146:147]
	v_mad_i64_i32 v[20:21], s[38:39], v20, s70, v[146:147]
	v_lshl_add_u64 v[16:17], v[16:17], 0, v[148:149]
	v_lshl_add_u64 v[20:21], v[20:21], 0, v[148:149]
	v_fmamk_f32 v18, v18, 0x3a000000, v161
	v_rsq_f32_e32 v18, v18
	s_nop 0
	v_pk_mul_f32 v[12:13], v[12:13], v[18:19] op_sel_hi:[1,0]
	v_pk_mul_f32 v[8:9], v[8:9], v[18:19] op_sel_hi:[1,0]
	v_pk_mul_f32 v[6:7], v[6:7], v[18:19] op_sel_hi:[1,0]
	v_pk_mul_f32 v[4:5], v[4:5], v[18:19] op_sel_hi:[1,0]
	v_pk_mul_f32 v[14:15], v[14:15], v[18:19] op_sel_hi:[1,0]
	v_pk_mul_f32 v[10:11], v[10:11], v[18:19] op_sel_hi:[1,0]
	v_pk_mul_f32 v[2:3], v[2:3], v[18:19] op_sel_hi:[1,0]
	v_pk_mul_f32 v[0:1], v[0:1], v[18:19] op_sel_hi:[1,0]
	v_cvt_pk_bf16_f32 v12, v12, v13
	v_cvt_pk_bf16_f32 v13, v14, v15
	v_cvt_pk_bf16_f32 v8, v8, v9
	v_cvt_pk_bf16_f32 v9, v10, v11
	v_cvt_pk_bf16_f32 v4, v4, v5
	v_cvt_pk_bf16_f32 v5, v6, v7
	s_nop 0
	v_cvt_pk_bf16_f32 v6, v0, v1
	v_cvt_pk_bf16_f32 v7, v2, v3
	s_nop 0
	v_mov_b32_dpp v19, v12 row_ror:8 row_mask:0xf bank_mask:0xf
	v_mov_b32_dpp v22, v13 row_ror:8 row_mask:0xf bank_mask:0xf
	v_mov_b32_dpp v25, v4 row_ror:8 row_mask:0xf bank_mask:0xf
	v_mov_b32_dpp v26, v5 row_ror:8 row_mask:0xf bank_mask:0xf
	v_mov_b32_dpp v27, v6 row_ror:8 row_mask:0xf bank_mask:0xf
	v_mov_b32_dpp v28, v7 row_ror:8 row_mask:0xf bank_mask:0xf
	v_mov_b32_dpp v23, v8 row_ror:8 row_mask:0xf bank_mask:0xf
	v_mov_b32_dpp v24, v9 row_ror:8 row_mask:0xf bank_mask:0xf
	v_cndmask_b32_e64 v0, v25, v12, s[6:7]
	v_cndmask_b32_e64 v1, v26, v13, s[6:7]
	v_cndmask_b32_e64 v2, v27, v8, s[6:7]
	v_cndmask_b32_e64 v3, v28, v9, s[6:7]
	v_cndmask_b32_e64 v4, v4, v19, s[6:7]
	v_cndmask_b32_e64 v5, v5, v22, s[6:7]
	v_cndmask_b32_e64 v6, v6, v23, s[6:7]
	v_cndmask_b32_e64 v7, v7, v24, s[6:7]
	global_store_dwordx4 v[16:17], v[0:3], off
	global_store_dwordx4 v[20:21], v[4:7], off
	s_cbranch_vccz .LBB0_958
	s_waitcnt vmcnt(0)
	s_cmpk_gt_u32 s52, 0xff
	s_cbranch_scc1 .LBB0_966
	s_barrier

; #define PG8_STAGE(bufoff, gbase, voff) do { _Pragma("unroll") for (int _i = 0; _i < 2; ++_i) \
;         __builtin_amdgcn_global_load_lds((const unsigned*)((const char*)(gbase) + (voff)[_i]), (LAS unsigned*)(lds + (bufoff) + ldsw + _i * 8192), 16, 0, 0); } while (0)
; #define PG8_LDA(dst, b, h) do { _Pragma("unroll") for (int m = 0; m < 4; ++m) _Pragma("unroll") for (int k = 0; k < 2; ++k) dst[m][k] = *(const LAS bf16x8*)(lds + PG8_SA(b, h) + aoff + m * 2048 + k * 1024); } while (0)
; #define PG8_LDB(dst, b, h) do { _Pragma("unroll") for (int n = 0; n < 2; ++n) _Pragma("unroll") for (int k = 0; k < 2; ++k) dst[n][k] = *(const LAS bf16x8*)(lds + PG8_SB(b, h) + boff + n * 2048 + k * 1024); } while (0)
; #define PG8_MMA(ai, bj, At, Bt) do { __builtin_amdgcn_s_setprio(1); _Pragma("unroll") for (int m = 0; m < 4; ++m) _Pragma("unroll") for (int n = 0; n < 2; ++n) _Pragma("unroll") for (int k = 0; k < 2; ++k) \
;         acc[ai][bj][m][n] = __builtin_amdgcn_mfma_f32_16x16x32_bf16(Bt[n][k], At[m][k], acc[ai][bj][m][n], 0, 0, 0); __builtin_amdgcn_s_setprio(0); } while (0)
; #define PG8_WAIT_L(n) asm volatile("s_waitcnt lgkmcnt(" #n ")" ::: "memory")
; #define PG8_BAR __builtin_amdgcn_s_barrier()
; #define PG8_SCHED __builtin_amdgcn_sched_barrier(0)
; template <class Epi>
; __device__ __forceinline__ void gemm_phase(LAS unsigned char* lds, const Gemm g, const StaticOrder& S, const Epi& E) {
;     ...
;             const bool last = (t == nt - 2);
;             const char* a1 = cA + (size_t)(t + 1) * kstep;
;             const char* a2 = last ? nA : cA + (size_t)(t + 2) * kstep; const char* b2 = last ? nB : cB + (size_t)(t + 2) * kstep;
;             const char* a3 = a2 + kstep; const char* b3 = b2 + kstep;
;             PG8_LDB(B0, 0, 0); PG8_SCHED; PG8_LDA(At, 0, 0); PG8_STAGE(PG8_SA(1, 1), a1 + hstep, voffA);
;             PG8_WAIT_L(8); PG8_BAR; PG8_WAIT_L(0); PG8_MMA(0, 0, At, B0); PG8_BAR; PG8_SCHED;
;             PG8_LDB(B1, 0, 1); PG8_STAGE(PG8_SB(0, 0), b2, voffB0);
;             PG8_BAR; PG8_WAIT_L(0); PG8_MMA(0, 1, At, B1); PG8_BAR;
;             PG8_LDA(At, 0, 1); PG8_STAGE(PG8_SA(0, 0), a2, voffA);
;             PG8_BAR; PG8_WAIT_L(0); PG8_MMA(1, 0, At, B0); PG8_BAR; PG8_SCHED;
;             PG8_STAGE(PG8_SB(0, 1), b2, voffB1);
.LBB0_1245:
	ds_read_b128 v[146:149], v154
	ds_read_b128 v[158:161], v154 offset:1024
	ds_read_b128 v[162:165], v154 offset:2048
	ds_read_b128 v[166:169], v154 offset:3072
	s_add_u32 s33, s46, 0xfff80080
	s_addc_u32 s48, s47, -1
	s_cmp_eq_u32 s73, 28
	s_cselect_b32 s49, s35, s48
	s_cselect_b32 s48, s43, s33
	s_cselect_b32 s51, s31, s72
	s_cselect_b32 s50, s70, s71
	v_lshl_add_u64 v[204:205], s[46:47], 0, v[140:141]
	s_add_i32 m0, s45, 0xc000
	ds_read_b128 v[170:173], v155
	ds_read_b128 v[174:177], v155 offset:1024
	ds_read_b128 v[178:181], v155 offset:2048
	ds_read_b128 v[182:185], v155 offset:3072
	ds_read_b128 v[186:189], v155 offset:4096
	ds_read_b128 v[190:193], v155 offset:5120
	ds_read_b128 v[194:197], v155 offset:6144
	ds_read_b128 v[198:201], v155 offset:7168
	global_load_lds_dwordx4 v[204:205], off
	v_lshl_add_u64 v[204:205], s[46:47], 0, v[142:143]
	s_add_i32 m0, s45, 0xe000
	s_nop 0
	global_load_lds_dwordx4 v[204:205], off
	s_waitcnt lgkmcnt(8)
	s_barrier
	s_waitcnt lgkmcnt(0)
	s_waitcnt lgkmcnt(0)
	v_mfma_f32_16x16x32_bf16 v[124:127], v[146:149], v[170:173], v[124:127]
	v_mfma_f32_16x16x32_bf16 v[120:123], v[162:165], v[170:173], v[120:123]
	v_mfma_f32_16x16x32_bf16 v[108:111], v[146:149], v[178:181], v[108:111]
	v_mfma_f32_16x16x32_bf16 v[104:107], v[162:165], v[178:181], v[104:107]
	v_mfma_f32_16x16x32_bf16 v[92:95], v[146:149], v[186:189], v[92:95]
	v_mfma_f32_16x16x32_bf16 v[88:91], v[162:165], v[186:189], v[88:91]
	v_mfma_f32_16x16x32_bf16 v[76:79], v[146:149], v[194:197], v[76:79]
	v_mfma_f32_16x16x32_bf16 v[72:75], v[162:165], v[194:197], v[72:75]
	v_mfma_f32_16x16x32_bf16 v[124:127], v[158:161], v[174:177], v[124:127]
	v_mfma_f32_16x16x32_bf16 v[120:123], v[166:169], v[174:177], v[120:123]
	v_mfma_f32_16x16x32_bf16 v[108:111], v[158:161], v[182:185], v[108:111]
	v_mfma_f32_16x16x32_bf16 v[104:107], v[166:169], v[182:185], v[104:107]
	v_mfma_f32_16x16x32_bf16 v[92:95], v[158:161], v[190:193], v[92:95]
	v_mfma_f32_16x16x32_bf16 v[88:91], v[166:169], v[190:193], v[88:91]
	v_mfma_f32_16x16x32_bf16 v[76:79], v[158:161], v[198:201], v[76:79]
	v_mfma_f32_16x16x32_bf16 v[72:75], v[166:169], v[198:201], v[72:75]
	s_barrier
	s_add_i32 s33, s68, s57
	v_lshl_add_u64 v[220:221], s[50:51], 0, v[130:131]
	s_mov_b32 m0, s33
	ds_read_b128 v[204:207], v156
	ds_read_b128 v[208:211], v156 offset:1024
	ds_read_b128 v[212:215], v156 offset:2048
	ds_read_b128 v[216:219], v156 offset:3072
	global_load_lds_dwordx4 v[220:221], off
	v_lshl_add_u64 v[222:223], s[50:51], 0, v[136:137]
	s_add_i32 m0, s33, 0x2000
	s_nop 0
	global_load_lds_dwordx4 v[222:223], off
	s_barrier
	s_waitcnt lgkmcnt(0)
	s_waitcnt lgkmcnt(0)
	v_mfma_f32_16x16x32_bf16 v[116:119], v[204:207], v[170:173], v[116:119]
	v_mfma_f32_16x16x32_bf16 v[112:115], v[212:215], v[170:173], v[112:115]
	v_mfma_f32_16x16x32_bf16 v[100:103], v[204:207], v[178:181], v[100:103]
	v_mfma_f32_16x16x32_bf16 v[96:99], v[212:215], v[178:181], v[96:99]
	v_mfma_f32_16x16x32_bf16 v[84:87], v[204:207], v[186:189], v[84:87]
	v_mfma_f32_16x16x32_bf16 v[80:83], v[212:215], v[186:189], v[80:83]
	v_mfma_f32_16x16x32_bf16 v[68:71], v[204:207], v[194:197], v[68:71]
	v_mfma_f32_16x16x32_bf16 v[64:67], v[212:215], v[194:197], v[64:67]
	v_mfma_f32_16x16x32_bf16 v[116:119], v[208:211], v[174:177], v[116:119]
	v_mfma_f32_16x16x32_bf16 v[112:115], v[216:219], v[174:177], v[112:115]
	v_mfma_f32_16x16x32_bf16 v[100:103], v[208:211], v[182:185], v[100:103]
	v_mfma_f32_16x16x32_bf16 v[96:99], v[216:219], v[182:185], v[96:99]
	v_mfma_f32_16x16x32_bf16 v[84:87], v[208:211], v[190:193], v[84:87]
	v_mfma_f32_16x16x32_bf16 v[80:83], v[216:219], v[190:193], v[80:83]
	v_mfma_f32_16x16x32_bf16 v[68:71], v[208:211], v[198:201], v[68:71]
	v_mfma_f32_16x16x32_bf16 v[64:67], v[216:219], v[198:201], v[64:67]
	s_mov_b32 m0, s45
	v_lshl_add_u64 v[224:225], s[48:49], 0, v[128:129]
	s_barrier
	ds_read_b128 v[170:173], v155 offset:16384
	ds_read_b128 v[174:177], v155 offset:17408
	ds_read_b128 v[178:181], v155 offset:18432
	ds_read_b128 v[182:185], v155 offset:19456
	ds_read_b128 v[186:189], v155 offset:20480
	ds_read_b128 v[190:193], v155 offset:21504
	ds_read_b128 v[194:197], v155 offset:22528
	ds_read_b128 v[198:201], v155 offset:23552
	global_load_lds_dwordx4 v[224:225], off
	v_lshl_add_u64 v[226:227], s[48:49], 0, v[134:135]
	s_mov_b32 m0, s58
	s_nop 0
	global_load_lds_dwordx4 v[226:227], off
	s_barrier
	s_waitcnt lgkmcnt(0)
	s_waitcnt lgkmcnt(0)
	v_mfma_f32_16x16x32_bf16 v[60:63], v[146:149], v[170:173], v[60:63]
	v_mfma_f32_16x16x32_bf16 v[56:59], v[162:165], v[170:173], v[56:59]
	v_mfma_f32_16x16x32_bf16 v[44:47], v[146:149], v[178:181], v[44:47]
	v_mfma_f32_16x16x32_bf16 v[40:43], v[162:165], v[178:181], v[40:43]
	v_mfma_f32_16x16x32_bf16 v[28:31], v[146:149], v[186:189], v[28:31]
	v_mfma_f32_16x16x32_bf16 v[24:27], v[162:165], v[186:189], v[24:27]
	v_mfma_f32_16x16x32_bf16 v[12:15], v[146:149], v[194:197], v[12:15]
	v_mfma_f32_16x16x32_bf16 v[8:11], v[162:165], v[194:197], v[8:11]
	v_mfma_f32_16x16x32_bf16 v[60:63], v[158:161], v[174:177], v[60:63]
	v_mfma_f32_16x16x32_bf16 v[56:59], v[166:169], v[174:177], v[56:59]
	v_mfma_f32_16x16x32_bf16 v[44:47], v[158:161], v[182:185], v[44:47]
	v_mfma_f32_16x16x32_bf16 v[40:43], v[166:169], v[182:185], v[40:43]
	v_mfma_f32_16x16x32_bf16 v[28:31], v[158:161], v[190:193], v[28:31]
	v_mfma_f32_16x16x32_bf16 v[24:27], v[166:169], v[190:193], v[24:27]
	v_mfma_f32_16x16x32_bf16 v[12:15], v[158:161], v[198:201], v[12:15]
	v_mfma_f32_16x16x32_bf16 v[8:11], v[166:169], v[198:201], v[8:11]
	s_barrier
; #define PG8_STAGE(bufoff, gbase, voff) do { _Pragma("unroll") for (int _i = 0; _i < 2; ++_i) \
;         __builtin_amdgcn_global_load_lds((const unsigned*)((const char*)(gbase) + (voff)[_i]), (LAS unsigned*)(lds + (bufoff) + ldsw + _i * 8192), 16, 0, 0); } while (0)
; #define PG8_LDA(dst, b, h) do { _Pragma("unroll") for (int m = 0; m < 4; ++m) _Pragma("unroll") for (int k = 0; k < 2; ++k) dst[m][k] = *(const LAS bf16x8*)(lds + PG8_SA(b, h) + aoff + m * 2048 + k * 1024); } while (0)
; #define PG8_LDB(dst, b, h) do { _Pragma("unroll") for (int n = 0; n < 2; ++n) _Pragma("unroll") for (int k = 0; k < 2; ++k) dst[n][k] = *(const LAS bf16x8*)(lds + PG8_SB(b, h) + boff + n * 2048 + k * 1024); } while (0)
; #define PG8_MMA(ai, bj, At, Bt) do { __builtin_amdgcn_s_setprio(1); _Pragma("unroll") for (int m = 0; m < 4; ++m) _Pragma("unroll") for (int n = 0; n < 2; ++n) _Pragma("unroll") for (int k = 0; k < 2; ++k) \
;         acc[ai][bj][m][n] = __builtin_amdgcn_mfma_f32_16x16x32_bf16(Bt[n][k], At[m][k], acc[ai][bj][m][n], 0, 0, 0); __builtin_amdgcn_s_setprio(0); } while (0)
; #define PG8_WAIT_V(n) asm volatile("s_waitcnt vmcnt(" #n ")" ::: "memory")
; #define PG8_WAIT_L(n) asm volatile("s_waitcnt lgkmcnt(" #n ")" ::: "memory")
; #define PG8_BAR __builtin_amdgcn_s_barrier()
; #define PG8_SCHED __builtin_amdgcn_sched_barrier(0)
; template <class Epi>
; __device__ __forceinline__ void gemm_phase(LAS unsigned char* lds, const Gemm g, const StaticOrder& S, const Epi& E) {
;     ...
;             PG8_STAGE(PG8_SB(0, 1), b2, voffB1);
;             PG8_WAIT_V(6); PG8_BAR; PG8_MMA(1, 1, At, B1); PG8_BAR;
;             PG8_LDB(B0, 1, 0); PG8_SCHED; PG8_LDA(At, 1, 0); PG8_STAGE(PG8_SA(0, 1), a2 + hstep, voffA);
;             PG8_WAIT_L(8); PG8_BAR; PG8_WAIT_L(0); PG8_MMA(0, 0, At, B0); PG8_BAR; PG8_SCHED;
;             PG8_LDB(B1, 1, 1); PG8_STAGE(PG8_SB(1, 0), b3, voffB0);
;             PG8_BAR; PG8_WAIT_L(0); PG8_MMA(0, 1, At, B1); PG8_BAR;
;             PG8_LDA(At, 1, 1); PG8_STAGE(PG8_SA(1, 0), a3, voffA);
;             PG8_BAR; PG8_WAIT_L(0); PG8_MMA(1, 0, At, B0); PG8_BAR; PG8_SCHED;
;             PG8_STAGE(PG8_SB(1, 1), b3, voffB1);
	s_add_i32 s33, s69, s57
	v_lshl_add_u64 v[228:229], s[50:51], 0, v[132:133]
	s_mov_b32 m0, s33
	v_lshl_add_u64 v[230:231], s[50:51], 0, v[138:139]
	global_load_lds_dwordx4 v[228:229], off
	s_add_i32 m0, s33, 0x2000
	s_nop 0
	global_load_lds_dwordx4 v[230:231], off
	s_waitcnt vmcnt(6)
	s_barrier
	v_mfma_f32_16x16x32_bf16 v[52:55], v[204:207], v[170:173], v[52:55]
	v_mfma_f32_16x16x32_bf16 v[48:51], v[212:215], v[170:173], v[48:51]
	v_mfma_f32_16x16x32_bf16 v[36:39], v[204:207], v[178:181], v[36:39]
	v_mfma_f32_16x16x32_bf16 v[32:35], v[212:215], v[178:181], v[32:35]
	v_mfma_f32_16x16x32_bf16 v[20:23], v[204:207], v[186:189], v[20:23]
	v_mfma_f32_16x16x32_bf16 v[16:19], v[212:215], v[186:189], v[16:19]
	v_mfma_f32_16x16x32_bf16 v[4:7], v[204:207], v[194:197], v[4:7]
	v_mfma_f32_16x16x32_bf16 v[0:3], v[212:215], v[194:197], v[0:3]
	v_mfma_f32_16x16x32_bf16 v[52:55], v[208:211], v[174:177], v[52:55]
	v_mfma_f32_16x16x32_bf16 v[48:51], v[216:219], v[174:177], v[48:51]
	v_mfma_f32_16x16x32_bf16 v[36:39], v[208:211], v[182:185], v[36:39]
	v_mfma_f32_16x16x32_bf16 v[32:35], v[216:219], v[182:185], v[32:35]
	v_mfma_f32_16x16x32_bf16 v[20:23], v[208:211], v[190:193], v[20:23]
	v_mfma_f32_16x16x32_bf16 v[16:19], v[216:219], v[190:193], v[16:19]
	v_mfma_f32_16x16x32_bf16 v[4:7], v[208:211], v[198:201], v[4:7]
	v_mfma_f32_16x16x32_bf16 v[0:3], v[216:219], v[198:201], v[0:3]
	s_add_i32 s33, 0, 0x18000
	v_add_u32_e32 v157, s33, v151
	s_barrier
	ds_read_b128 v[146:149], v157
	ds_read_b128 v[158:161], v157 offset:1024
	ds_read_b128 v[162:165], v157 offset:2048
	ds_read_b128 v[166:169], v157 offset:3072
	s_add_u32 s48, s48, 0x80000
	s_addc_u32 s49, s49, 0
	s_mov_b32 m0, s59
	v_lshl_add_u64 v[204:205], s[48:49], 0, v[128:129]
	ds_read_b128 v[170:173], v155 offset:32768
	ds_read_b128 v[174:177], v155 offset:33792
	ds_read_b128 v[178:181], v155 offset:34816
	ds_read_b128 v[182:185], v155 offset:35840
	ds_read_b128 v[186:189], v155 offset:36864
	ds_read_b128 v[190:193], v155 offset:37888
	ds_read_b128 v[194:197], v155 offset:38912
	ds_read_b128 v[198:201], v155 offset:39936
	global_load_lds_dwordx4 v[204:205], off
	v_lshl_add_u64 v[204:205], s[48:49], 0, v[134:135]
	s_mov_b32 m0, s60
	s_nop 0
	global_load_lds_dwordx4 v[204:205], off
	s_waitcnt lgkmcnt(8)
	s_barrier
	s_waitcnt lgkmcnt(0)
	s_waitcnt lgkmcnt(0)
	v_mfma_f32_16x16x32_bf16 v[124:127], v[146:149], v[170:173], v[124:127]
	v_mfma_f32_16x16x32_bf16 v[120:123], v[162:165], v[170:173], v[120:123]
	v_mfma_f32_16x16x32_bf16 v[108:111], v[146:149], v[178:181], v[108:111]
	v_mfma_f32_16x16x32_bf16 v[104:107], v[162:165], v[178:181], v[104:107]
	v_mfma_f32_16x16x32_bf16 v[92:95], v[146:149], v[186:189], v[92:95]
	v_mfma_f32_16x16x32_bf16 v[88:91], v[162:165], v[186:189], v[88:91]
	v_mfma_f32_16x16x32_bf16 v[76:79], v[146:149], v[194:197], v[76:79]
	v_mfma_f32_16x16x32_bf16 v[72:75], v[162:165], v[194:197], v[72:75]
	v_mfma_f32_16x16x32_bf16 v[124:127], v[158:161], v[174:177], v[124:127]
	v_mfma_f32_16x16x32_bf16 v[120:123], v[166:169], v[174:177], v[120:123]
	v_mfma_f32_16x16x32_bf16 v[108:111], v[158:161], v[182:185], v[108:111]
	v_mfma_f32_16x16x32_bf16 v[104:107], v[166:169], v[182:185], v[104:107]
	v_mfma_f32_16x16x32_bf16 v[92:95], v[158:161], v[190:193], v[92:95]
	v_mfma_f32_16x16x32_bf16 v[88:91], v[166:169], v[190:193], v[88:91]
	v_mfma_f32_16x16x32_bf16 v[76:79], v[158:161], v[198:201], v[76:79]
	v_mfma_f32_16x16x32_bf16 v[72:75], v[166:169], v[198:201], v[72:75]
	s_barrier
	s_add_i32 s48, 0, 0x1c000
	s_add_i32 s33, s33, s57
	v_add_u32_e32 v157, s48, v151
	v_lshl_add_u64 v[220:221], v[220:221], 0, s[26:27]
	s_mov_b32 m0, s33
	ds_read_b128 v[204:207], v157
	ds_read_b128 v[208:211], v157 offset:1024
	ds_read_b128 v[212:215], v157 offset:2048
	ds_read_b128 v[216:219], v157 offset:3072
	global_load_lds_dwordx4 v[220:221], off
	v_lshl_add_u64 v[220:221], v[222:223], 0, s[26:27]
	s_add_i32 m0, s33, 0x2000
	s_nop 0
	global_load_lds_dwordx4 v[220:221], off
	s_barrier
	s_waitcnt lgkmcnt(0)
	s_waitcnt lgkmcnt(0)
	v_mfma_f32_16x16x32_bf16 v[116:119], v[204:207], v[170:173], v[116:119]
	v_mfma_f32_16x16x32_bf16 v[112:115], v[212:215], v[170:173], v[112:115]
	v_mfma_f32_16x16x32_bf16 v[100:103], v[204:207], v[178:181], v[100:103]
	v_mfma_f32_16x16x32_bf16 v[96:99], v[212:215], v[178:181], v[96:99]
	v_mfma_f32_16x16x32_bf16 v[84:87], v[204:207], v[186:189], v[84:87]
	v_mfma_f32_16x16x32_bf16 v[80:83], v[212:215], v[186:189], v[80:83]
	v_mfma_f32_16x16x32_bf16 v[68:71], v[204:207], v[194:197], v[68:71]
	v_mfma_f32_16x16x32_bf16 v[64:67], v[212:215], v[194:197], v[64:67]
	v_mfma_f32_16x16x32_bf16 v[116:119], v[208:211], v[174:177], v[116:119]
	v_mfma_f32_16x16x32_bf16 v[112:115], v[216:219], v[174:177], v[112:115]
	v_mfma_f32_16x16x32_bf16 v[100:103], v[208:211], v[182:185], v[100:103]
	v_mfma_f32_16x16x32_bf16 v[96:99], v[216:219], v[182:185], v[96:99]
	v_mfma_f32_16x16x32_bf16 v[84:87], v[208:211], v[190:193], v[84:87]
	v_mfma_f32_16x16x32_bf16 v[80:83], v[216:219], v[190:193], v[80:83]
	v_mfma_f32_16x16x32_bf16 v[68:71], v[208:211], v[198:201], v[68:71]
	v_mfma_f32_16x16x32_bf16 v[64:67], v[216:219], v[198:201], v[64:67]
	s_mov_b32 m0, s62
	v_lshl_add_u64 v[220:221], v[224:225], 0, s[26:27]
	s_barrier
	ds_read_b128 v[170:173], v155 offset:49152
	ds_read_b128 v[174:177], v155 offset:50176
	ds_read_b128 v[178:181], v155 offset:51200
	ds_read_b128 v[182:185], v155 offset:52224
	ds_read_b128 v[186:189], v155 offset:53248
	ds_read_b128 v[190:193], v155 offset:54272
	ds_read_b128 v[194:197], v155 offset:55296
	ds_read_b128 v[198:201], v155 offset:56320
	global_load_lds_dwordx4 v[220:221], off
	v_lshl_add_u64 v[220:221], v[226:227], 0, s[26:27]
	s_mov_b32 m0, s63
	s_nop 0
	global_load_lds_dwordx4 v[220:221], off
	s_barrier
; __device__ __forceinline__ unsigned cvt_pk_bf16(float lo, float hi) { unsigned r; asm volatile("v_cvt_pk_bf16_f32 %0, %1, %2" : "=v"(r) : "v"(lo), "v"(hi)); return r; }
; __device__ __forceinline__ float bflo(unsigned w) { return __uint_as_float(w << 16); }
; __device__ __forceinline__ float bfhi(unsigned w) { return __uint_as_float(w & 0xffff0000u); }
; #define PG8_STAGE(bufoff, gbase, voff) do { _Pragma("unroll") for (int _i = 0; _i < 2; ++_i) \
;         __builtin_amdgcn_global_load_lds((const unsigned*)((const char*)(gbase) + (voff)[_i]), (LAS unsigned*)(lds + (bufoff) + ldsw + _i * 8192), 16, 0, 0); } while (0)
;     __device__ __forceinline__ void operator()(const f32x4 (&acc)[2][2][4][2], const Unit& u, int wr, int wc, int fr, int fq) const {
;     ...
;             for (int m = 0; m < 4; ++m) { const int row = row0 + ai * HALF + m * 16; const size_t off = (size_t)row * D + col0; float sq = 0.f; u32x4 w[2];
;                 const float sc = rsin ? __builtin_amdgcn_rcpf(rsin[row] * (1.f / D) + EPS) : 1.0f;
;                 u32x4 rr[2]; if (R) load_pair_lines(R, D, row, fr, col0, rr[0], rr[1]);
; #pragma unroll
;                 for (int bj = 0; bj < 2; ++bj) { f32x4 r0, r1;
;                     if (R) { const u32x4 rw = rr[bj]; r0 = (f32x4){bflo(rw.x), bfhi(rw.x), bflo(rw.y), bfhi(rw.y)}; r1 = (f32x4){bflo(rw.z), bfhi(rw.z), bflo(rw.w), bfhi(rw.w)}; }
;                     else { const float* rp = (row < 8192 ? src_p + off : src_s + (off - (size_t)8192 * D)) + 8 * bj; r0 = *(const f32x4*)rp; r1 = *(const f32x4*)(rp + 4); }
;                     const f32x4 o0 = r0 + acc[ai][bj][m][0] * sc, o1 = r1 + acc[ai][bj][m][1] * sc;
;                     sq += (o0[0] * o0[0] + o0[1] * o0[1]) + (o0[2] * o0[2] + o0[3] * o0[3]) + (o1[0] * o1[0] + o1[1] * o1[1]) + (o1[2] * o1[2] + o1[3] * o1[3]);
;                     w[bj].x = cvt_pk_bf16(o0[0], o0[1]); w[bj].y = cvt_pk_bf16(o0[2], o0[3]); w[bj].z = cvt_pk_bf16(o1[0], o1[1]); w[bj].w = cvt_pk_bf16(o1[2], o1[3]); }
; template <class Epi>
; __device__ __forceinline__ void gemm_phase(LAS unsigned char* lds, const Gemm g, const StaticOrder& S, const Epi& E) {
;     ...
;             PG8_BAR; PG8_WAIT_L(0); PG8_MMA(1, 0, At, B0); PG8_BAR; PG8_SCHED;
;             PG8_STAGE(PG8_SB(1, 1), b3, voffB1);
;             PG8_WAIT_V(6); PG8_BAR; PG8_MMA(1, 1, At, B1); PG8_BAR;
;         }
;         E(acc, cur, wr, wc, fr, fq);
	s_waitcnt lgkmcnt(0)
	s_waitcnt lgkmcnt(0)
	v_mfma_f32_16x16x32_bf16 v[60:63], v[146:149], v[170:173], v[60:63]
	v_mfma_f32_16x16x32_bf16 v[56:59], v[162:165], v[170:173], v[56:59]
	v_mfma_f32_16x16x32_bf16 v[44:47], v[146:149], v[178:181], v[44:47]
	v_mfma_f32_16x16x32_bf16 v[40:43], v[162:165], v[178:181], v[40:43]
	v_mfma_f32_16x16x32_bf16 v[28:31], v[146:149], v[186:189], v[28:31]
	v_mfma_f32_16x16x32_bf16 v[24:27], v[162:165], v[186:189], v[24:27]
	v_mfma_f32_16x16x32_bf16 v[12:15], v[146:149], v[194:197], v[12:15]
	v_mfma_f32_16x16x32_bf16 v[8:11], v[162:165], v[194:197], v[8:11]
	v_mfma_f32_16x16x32_bf16 v[60:63], v[158:161], v[174:177], v[60:63]
	v_mfma_f32_16x16x32_bf16 v[56:59], v[166:169], v[174:177], v[56:59]
	v_mfma_f32_16x16x32_bf16 v[44:47], v[158:161], v[182:185], v[44:47]
	v_mfma_f32_16x16x32_bf16 v[40:43], v[166:169], v[182:185], v[40:43]
	v_mfma_f32_16x16x32_bf16 v[28:31], v[158:161], v[190:193], v[28:31]
	v_mfma_f32_16x16x32_bf16 v[24:27], v[166:169], v[190:193], v[24:27]
	v_mfma_f32_16x16x32_bf16 v[12:15], v[158:161], v[198:201], v[12:15]
	v_mfma_f32_16x16x32_bf16 v[8:11], v[166:169], v[198:201], v[8:11]
	s_barrier
	s_add_i32 s33, s48, s57
	v_lshl_add_u64 v[146:147], v[228:229], 0, s[26:27]
	s_mov_b32 m0, s33
	s_nop 0
	global_load_lds_dwordx4 v[146:147], off
	v_lshl_add_u64 v[146:147], v[230:231], 0, s[26:27]
	s_add_i32 m0, s33, 0x2000
	s_nop 0
	global_load_lds_dwordx4 v[146:147], off
	s_waitcnt vmcnt(6)
	s_barrier
	v_mfma_f32_16x16x32_bf16 v[52:55], v[204:207], v[170:173], v[52:55]
	v_mfma_f32_16x16x32_bf16 v[48:51], v[212:215], v[170:173], v[48:51]
	v_mfma_f32_16x16x32_bf16 v[36:39], v[204:207], v[178:181], v[36:39]
	v_mfma_f32_16x16x32_bf16 v[32:35], v[212:215], v[178:181], v[32:35]
	v_mfma_f32_16x16x32_bf16 v[20:23], v[204:207], v[186:189], v[20:23]
	v_mfma_f32_16x16x32_bf16 v[16:19], v[212:215], v[186:189], v[16:19]
	v_mfma_f32_16x16x32_bf16 v[4:7], v[204:207], v[194:197], v[4:7]
	v_mfma_f32_16x16x32_bf16 v[0:3], v[212:215], v[194:197], v[0:3]
	v_mfma_f32_16x16x32_bf16 v[52:55], v[208:211], v[174:177], v[52:55]
	v_mfma_f32_16x16x32_bf16 v[48:51], v[216:219], v[174:177], v[48:51]
	v_mfma_f32_16x16x32_bf16 v[36:39], v[208:211], v[182:185], v[36:39]
	v_mfma_f32_16x16x32_bf16 v[32:35], v[216:219], v[182:185], v[32:35]
	v_mfma_f32_16x16x32_bf16 v[20:23], v[208:211], v[190:193], v[20:23]
	v_mfma_f32_16x16x32_bf16 v[16:19], v[216:219], v[190:193], v[16:19]
	v_mfma_f32_16x16x32_bf16 v[4:7], v[208:211], v[198:201], v[4:7]
	v_mfma_f32_16x16x32_bf16 v[0:3], v[216:219], v[198:201], v[0:3]
	s_add_i32 s73, s73, 2
	s_add_u32 s46, s46, 0x100
	s_addc_u32 s47, s47, 0
	s_add_u32 s71, s71, 0x100
	s_addc_u32 s72, s72, 0
	s_cmp_gt_u32 s73, 29
	s_barrier
	s_cbranch_scc0 .LBB0_1245
	s_lshl_b32 s31, s44, 8
	s_add_i32 s31, s31, s64
	v_or_b32_e32 v148, s31, v152
	v_ashrrev_i32_e32 v149, 31, v148
	v_lshlrev_b64 v[166:167], 12, v[148:149]
	v_or_b32_e32 v148, 8, v148
	v_lshl_or_b32 v146, s42, 8, v153
	v_ashrrev_i32_e32 v149, 31, v148
	v_ashrrev_i32_e32 v147, 31, v146
	v_lshlrev_b64 v[168:169], 12, v[148:149]
	v_lshl_add_u64 v[158:159], s[10:11], 0, v[166:167]
	v_lshlrev_b64 v[146:147], 1, v[146:147]
	v_lshl_add_u64 v[148:149], s[10:11], 0, v[168:169]
	v_lshl_add_u64 v[158:159], v[158:159], 0, v[146:147]
	v_lshl_add_u64 v[148:149], v[148:149], 0, v[146:147]
	global_load_dwordx4 v[158:161], v[158:159], off
	v_mov_b32_e32 v157, 0
	global_load_dwordx4 v[162:165], v[148:149], off
	v_or_b32_e32 v194, s31, v150
	v_or_b32_e32 v184, 16, v194
	v_sub_u32_e32 v185, v184, v150
	v_add_u32_e32 v186, v185, v152
	v_ashrrev_i32_e32 v187, 31, v186
	v_lshlrev_b64 v[190:191], 12, v[186:187]
	v_lshl_add_u64 v[192:193], v[190:191], 0, s[28:29]
	v_lshl_add_u64 v[186:187], s[10:11], 0, v[190:191]
	v_lshl_add_u64 v[188:189], s[10:11], 0, v[192:193]
	v_lshl_add_u64 v[186:187], v[186:187], 0, v[146:147]
	v_lshl_add_u64 v[188:189], v[188:189], 0, v[146:147]
	global_load_dwordx4 v[196:199], v[186:187], off
	global_load_dwordx4 v[204:207], v[188:189], off
	v_or_b32_e32 v194, s31, v150
	v_or_b32_e32 v184, 32, v194
	v_sub_u32_e32 v185, v184, v150
	v_add_u32_e32 v186, v185, v152
	v_ashrrev_i32_e32 v187, 31, v186
	v_lshlrev_b64 v[190:191], 12, v[186:187]
	v_lshl_add_u64 v[192:193], v[190:191], 0, s[28:29]
	v_lshl_add_u64 v[186:187], s[10:11], 0, v[190:191]
	v_lshl_add_u64 v[188:189], s[10:11], 0, v[192:193]
	v_lshl_add_u64 v[186:187], v[186:187], 0, v[146:147]
	v_lshl_add_u64 v[188:189], v[188:189], 0, v[146:147]
	global_load_dwordx4 v[208:211], v[186:187], off
	global_load_dwordx4 v[212:215], v[188:189], off
	v_or_b32_e32 v194, s31, v150
	v_or_b32_e32 v184, 48, v194
	v_sub_u32_e32 v185, v184, v150
	v_add_u32_e32 v186, v185, v152
	v_ashrrev_i32_e32 v187, 31, v186
	v_lshlrev_b64 v[190:191], 12, v[186:187]
	v_lshl_add_u64 v[192:193], v[190:191], 0, s[28:29]
	v_lshl_add_u64 v[186:187], s[10:11], 0, v[190:191]
	v_lshl_add_u64 v[188:189], s[10:11], 0, v[192:193]
	v_lshl_add_u64 v[186:187], v[186:187], 0, v[146:147]
	v_lshl_add_u64 v[188:189], v[188:189], 0, v[146:147]
	global_load_dwordx4 v[216:219], v[186:187], off
	global_load_dwordx4 v[220:223], v[188:189], off
	v_or_b32_e32 v194, s31, v150
	v_add_u32_e32 v184, 0x80, v194
	v_sub_u32_e32 v185, v184, v150
	v_add_u32_e32 v186, v185, v152
	v_ashrrev_i32_e32 v187, 31, v186
	v_lshlrev_b64 v[190:191], 12, v[186:187]
	v_lshl_add_u64 v[192:193], v[190:191], 0, s[28:29]
	v_lshl_add_u64 v[186:187], s[10:11], 0, v[190:191]
	v_lshl_add_u64 v[188:189], s[10:11], 0, v[192:193]
	v_lshl_add_u64 v[186:187], v[186:187], 0, v[146:147]
	v_lshl_add_u64 v[188:189], v[188:189], 0, v[146:147]
	global_load_dwordx4 v[224:227], v[186:187], off
; __device__ __forceinline__ unsigned cvt_pk_bf16(float lo, float hi) { unsigned r; asm volatile("v_cvt_pk_bf16_f32 %0, %1, %2" : "=v"(r) : "v"(lo), "v"(hi)); return r; }
; __device__ __forceinline__ float bflo(unsigned w) { return __uint_as_float(w << 16); }
; __device__ __forceinline__ float bfhi(unsigned w) { return __uint_as_float(w & 0xffff0000u); }
;     __device__ __forceinline__ void operator()(const f32x4 (&acc)[2][2][4][2], const Unit& u, int wr, int wc, int fr, int fq) const {
;     ...
;             for (int m = 0; m < 4; ++m) { const int row = row0 + ai * HALF + m * 16; const size_t off = (size_t)row * D + col0; float sq = 0.f; u32x4 w[2];
;                 const float sc = rsin ? __builtin_amdgcn_rcpf(rsin[row] * (1.f / D) + EPS) : 1.0f;
;                 u32x4 rr[2]; if (R) load_pair_lines(R, D, row, fr, col0, rr[0], rr[1]);
; #pragma unroll
;                 for (int bj = 0; bj < 2; ++bj) { f32x4 r0, r1;
;                     if (R) { const u32x4 rw = rr[bj]; r0 = (f32x4){bflo(rw.x), bfhi(rw.x), bflo(rw.y), bfhi(rw.y)}; r1 = (f32x4){bflo(rw.z), bfhi(rw.z), bflo(rw.w), bfhi(rw.w)}; }
;                     else { const float* rp = (row < 8192 ? src_p + off : src_s + (off - (size_t)8192 * D)) + 8 * bj; r0 = *(const f32x4*)rp; r1 = *(const f32x4*)(rp + 4); }
;                     const f32x4 o0 = r0 + acc[ai][bj][m][0] * sc, o1 = r1 + acc[ai][bj][m][1] * sc;
;                     sq += (o0[0] * o0[0] + o0[1] * o0[1]) + (o0[2] * o0[2] + o0[3] * o0[3]) + (o1[0] * o1[0] + o1[1] * o1[1]) + (o1[2] * o1[2] + o1[3] * o1[3]);
;                     w[bj].x = cvt_pk_bf16(o0[0], o0[1]); w[bj].y = cvt_pk_bf16(o0[2], o0[3]); w[bj].z = cvt_pk_bf16(o1[0], o1[1]); w[bj].w = cvt_pk_bf16(o1[2], o1[3]); }
;                 store_pair_lines(O, D, row, fr, col0, w[0], w[1]);
;                 if (ssout) { sq += __shfl_xor(sq, 16); sq += __shfl_xor(sq, 32); if (fq == 0) unsafeAtomicAdd(ssout + row, sq); } }
	global_load_dwordx4 v[228:231], v[188:189], off
	v_or_b32_e32 v194, s31, v150
	v_add_u32_e32 v184, 0x90, v194
	v_sub_u32_e32 v185, v184, v150
	v_add_u32_e32 v186, v185, v152
	v_ashrrev_i32_e32 v187, 31, v186
	v_lshlrev_b64 v[190:191], 12, v[186:187]
	v_lshl_add_u64 v[192:193], v[190:191], 0, s[28:29]
	v_lshl_add_u64 v[186:187], s[10:11], 0, v[190:191]
	v_lshl_add_u64 v[188:189], s[10:11], 0, v[192:193]
	v_lshl_add_u64 v[186:187], v[186:187], 0, v[146:147]
	v_lshl_add_u64 v[188:189], v[188:189], 0, v[146:147]
	global_load_dwordx4 v[232:235], v[186:187], off
	global_load_dwordx4 v[236:239], v[188:189], off
	v_or_b32_e32 v194, s31, v150
	v_add_u32_e32 v184, 0xa0, v194
	v_sub_u32_e32 v185, v184, v150
	v_add_u32_e32 v186, v185, v152
	v_ashrrev_i32_e32 v187, 31, v186
	v_lshlrev_b64 v[190:191], 12, v[186:187]
	v_lshl_add_u64 v[192:193], v[190:191], 0, s[28:29]
	v_lshl_add_u64 v[186:187], s[10:11], 0, v[190:191]
	v_lshl_add_u64 v[188:189], s[10:11], 0, v[192:193]
	v_lshl_add_u64 v[186:187], v[186:187], 0, v[146:147]
	v_lshl_add_u64 v[188:189], v[188:189], 0, v[146:147]
	global_load_dwordx4 v[240:243], v[186:187], off
	global_load_dwordx4 v[244:247], v[188:189], off
	v_mov_b32_e32 v149, 0
	v_mov_b32_e32 v171, 0
	v_mov_b32_e32 v172, 0
	v_mov_b32_e32 v173, 0
	v_mov_b32_e32 v170, 0
	v_mov_b32_e32 v174, 0
	v_mov_b32_e32 v175, 0
	v_mov_b32_e32 v182, 0
	v_mov_b32_e32 v178, 0
	v_mov_b32_e32 v181, 0
	v_mov_b32_e32 v183, 0
	v_mov_b32_e32 v179, 0
	v_mov_b32_e32 v180, 0
	v_or_b32_e32 v148, s31, v150
	s_waitcnt vmcnt(12)
	v_mov_b32_dpp v149, v158 row_ror:8 row_mask:0xf bank_mask:0xf
	v_mov_b32_dpp v157, v159 row_ror:8 row_mask:0xf bank_mask:0xf
	v_mov_b32_dpp v171, v161 row_ror:8 row_mask:0xf bank_mask:0xf
	v_mov_b32_dpp v172, v162 row_ror:8 row_mask:0xf bank_mask:0xf
	v_mov_b32_dpp v173, v163 row_ror:8 row_mask:0xf bank_mask:0xf
	v_mov_b32_dpp v170, v160 row_ror:8 row_mask:0xf bank_mask:0xf
	v_mov_b32_dpp v174, v164 row_ror:8 row_mask:0xf bank_mask:0xf
	v_mov_b32_dpp v175, v165 row_ror:8 row_mask:0xf bank_mask:0xf
	v_cndmask_b32_e64 v165, v165, v171, s[6:7]
	v_cndmask_b32_e64 v157, v163, v157, s[6:7]
	v_cndmask_b32_e64 v149, v162, v149, s[6:7]
	v_cndmask_b32_e64 v173, v173, v159, s[6:7]
	v_cndmask_b32_e64 v171, v172, v158, s[6:7]
	v_cndmask_b32_e64 v164, v164, v170, s[6:7]
	v_cndmask_b32_e64 v177, v175, v161, s[6:7]
	v_cndmask_b32_e64 v175, v174, v160, s[6:7]
	v_lshlrev_b32_e32 v158, 16, v149
	v_and_b32_e32 v159, 0xffff0000, v149
	v_lshlrev_b32_e32 v160, 16, v157
	v_and_b32_e32 v161, 0xffff0000, v157
	v_lshlrev_b32_e32 v170, 16, v171
	v_and_b32_e32 v171, 0xffff0000, v171
	v_lshlrev_b32_e32 v172, 16, v173
	v_and_b32_e32 v173, 0xffff0000, v173
	v_lshlrev_b32_e32 v174, 16, v175
	v_and_b32_e32 v175, 0xffff0000, v175
	v_pk_add_f32 v[160:161], v[118:119], v[160:161]
	v_pk_add_f32 v[158:159], v[116:117], v[158:159]
	v_pk_add_f32 v[116:117], v[126:127], v[172:173]
	v_pk_add_f32 v[118:119], v[124:125], v[170:171]
	v_lshlrev_b32_e32 v176, 16, v177
	v_and_b32_e32 v177, 0xffff0000, v177
	v_pk_add_f32 v[120:121], v[120:121], v[174:175]
	v_mul_f32_e32 v124, v119, v119
	v_mul_f32_e32 v125, v117, v117
	v_lshlrev_b32_e32 v162, 16, v164
	v_and_b32_e32 v163, 0xffff0000, v164
	v_lshlrev_b32_e32 v164, 16, v165
	v_and_b32_e32 v165, 0xffff0000, v165
	v_pk_add_f32 v[122:123], v[122:123], v[176:177]
	v_mul_f32_e32 v126, v121, v121
	v_fmac_f32_e32 v124, v118, v118
	v_fmac_f32_e32 v125, v116, v116
	v_pk_add_f32 v[114:115], v[114:115], v[164:165]
	v_mul_f32_e32 v127, v123, v123
	v_cvt_pk_bf16_f32 v119, v118, v119
	v_cvt_pk_bf16_f32 v117, v116, v117
	v_cvt_pk_bf16_f32 v121, v120, v121
	v_fmac_f32_e32 v126, v120, v120
	v_add_f32_e32 v116, v124, v125
	v_mov_b32_e32 v120, 0
	v_pk_add_f32 v[112:113], v[112:113], v[162:163]
	v_cvt_pk_bf16_f32 v123, v122, v123
	v_cvt_pk_bf16_f32 v149, v158, v159
	v_cvt_pk_bf16_f32 v157, v160, v161
	v_fmac_f32_e32 v127, v122, v122
	v_cvt_pk_bf16_f32 v162, v112, v113
	v_cvt_pk_bf16_f32 v163, v114, v115
	v_add_f32_e32 v116, v126, v116
	v_mov_b32_dpp v182, v149 row_ror:8 row_mask:0xf bank_mask:0xf
	v_mov_b32_dpp v120, v163 row_ror:8 row_mask:0xf bank_mask:0xf
	v_mul_f32_e32 v115, v115, v115
	v_mov_b32_dpp v178, v119 row_ror:8 row_mask:0xf bank_mask:0xf
	v_mov_b32_dpp v181, v123 row_ror:8 row_mask:0xf bank_mask:0xf
	v_add_f32_e32 v122, v127, v116
	v_cndmask_b32_e64 v116, v182, v119, s[6:7]
	v_cndmask_b32_e64 v119, v120, v123, s[6:7]
	v_fmac_f32_e32 v115, v114, v114
	v_mul_f32_e32 v114, v159, v159
	v_mul_f32_e32 v123, v161, v161
	v_fmac_f32_e32 v114, v158, v158
	v_fmac_f32_e32 v123, v160, v160
	v_mul_f32_e32 v113, v113, v113
	v_add_f32_e32 v114, v114, v123
	v_fmac_f32_e32 v113, v112, v112
	v_add_f32_e32 v112, v113, v114
	v_add_f32_e32 v112, v115, v112
	v_and_b32_e32 v113, 64, v203
	v_add_f32_e32 v115, v112, v122
	v_xor_b32_e32 v112, 16, v203
	v_add_u32_e32 v126, 64, v113
	v_cmp_lt_i32_e32 vcc, v112, v126
	v_mov_b32_e32 v118, 0
	v_mov_b32_dpp v183, v157 row_ror:8 row_mask:0xf bank_mask:0xf
	v_cndmask_b32_e32 v112, v203, v112, vcc
	v_lshlrev_b32_e32 v114, 2, v112
	ds_bpermute_b32 v127, v114, v115
	v_lshl_add_u64 v[112:113], s[16:17], 0, v[166:167]
	v_lshl_add_u64 v[124:125], v[112:113], 0, v[146:147]
	v_xor_b32_e32 v113, 32, v203
	v_cmp_lt_i32_e32 vcc, v113, v126
	s_waitcnt lgkmcnt(0)
	v_add_f32_e32 v112, v115, v127
	v_mov_b32_dpp v118, v162 row_ror:8 row_mask:0xf bank_mask:0xf
	v_cndmask_b32_e32 v113, v203, v113, vcc
	v_lshlrev_b32_e32 v115, 2, v113
	ds_bpermute_b32 v113, v115, v112
	v_mov_b32_dpp v179, v117 row_ror:8 row_mask:0xf bank_mask:0xf
	v_cndmask_b32_e64 v117, v183, v117, s[6:7]
	v_cndmask_b32_e64 v118, v118, v121, s[6:7]
	v_mov_b32_dpp v180, v121 row_ror:8 row_mask:0xf bank_mask:0xf
	global_store_dwordx4 v[124:125], v[116:119], off
	v_cndmask_b32_e64 v120, v149, v178, s[6:7]
	v_cndmask_b32_e64 v121, v157, v179, s[6:7]
	v_lshl_add_u64 v[116:117], s[16:17], 0, v[168:169]
	v_cndmask_b32_e64 v122, v162, v180, s[6:7]
	v_cndmask_b32_e64 v123, v163, v181, s[6:7]
	v_lshl_add_u64 v[116:117], v[116:117], 0, v[146:147]
	global_store_dwordx4 v[116:117], v[120:123], off
	s_and_saveexec_b64 s[42:43], s[8:9]
	s_cbranch_execz .LBB0_1248
	v_ashrrev_i32_e32 v149, 31, v148
	s_waitcnt lgkmcnt(0)
	v_add_f32_e32 v116, v112, v113
	v_lshl_add_u64 v[112:113], v[148:149], 2, s[18:19]
	global_atomic_add_f32 v[112:113], v116, off

; #define PG8_STAGE(bufoff, gbase, voff) do { _Pragma("unroll") for (int _i = 0; _i < 2; ++_i) \
;         __builtin_amdgcn_global_load_lds((const unsigned*)((const char*)(gbase) + (voff)[_i]), (LAS unsigned*)(lds + (bufoff) + ldsw + _i * 8192), 16, 0, 0); } while (0)
; #define PG8_LDA(dst, b, h) do { _Pragma("unroll") for (int m = 0; m < 4; ++m) _Pragma("unroll") for (int k = 0; k < 2; ++k) dst[m][k] = *(const LAS bf16x8*)(lds + PG8_SA(b, h) + aoff + m * 2048 + k * 1024); } while (0)
; #define PG8_LDB(dst, b, h) do { _Pragma("unroll") for (int n = 0; n < 2; ++n) _Pragma("unroll") for (int k = 0; k < 2; ++k) dst[n][k] = *(const LAS bf16x8*)(lds + PG8_SB(b, h) + boff + n * 2048 + k * 1024); } while (0)
; #define PG8_MMA(ai, bj, At, Bt) do { __builtin_amdgcn_s_setprio(1); _Pragma("unroll") for (int m = 0; m < 4; ++m) _Pragma("unroll") for (int n = 0; n < 2; ++n) _Pragma("unroll") for (int k = 0; k < 2; ++k) \
;         acc[ai][bj][m][n] = __builtin_amdgcn_mfma_f32_16x16x32_bf16(Bt[n][k], At[m][k], acc[ai][bj][m][n], 0, 0, 0); __builtin_amdgcn_s_setprio(0); } while (0)
; #define PG8_WAIT_L(n) asm volatile("s_waitcnt lgkmcnt(" #n ")" ::: "memory")
; #define PG8_BAR __builtin_amdgcn_s_barrier()
; #define PG8_SCHED __builtin_amdgcn_sched_barrier(0)
; template <class Epi>
; __device__ __forceinline__ void gemm_phase(LAS unsigned char* lds, const Gemm g, const StaticOrder& S, const Epi& E) {
;     ...
;         for (int t = 0; t < nt; t += 2) {
;             const bool last = (t == nt - 2);
;             const char* a1 = cA + (size_t)(t + 1) * kstep;
;             const char* a2 = last ? nA : cA + (size_t)(t + 2) * kstep; const char* b2 = last ? nB : cB + (size_t)(t + 2) * kstep;
;             const char* a3 = a2 + kstep; const char* b3 = b2 + kstep;
;             PG8_LDB(B0, 0, 0); PG8_SCHED; PG8_LDA(At, 0, 0); PG8_STAGE(PG8_SA(1, 1), a1 + hstep, voffA);
;             PG8_WAIT_L(8); PG8_BAR; PG8_WAIT_L(0); PG8_MMA(0, 0, At, B0); PG8_BAR; PG8_SCHED;
;             PG8_LDB(B1, 0, 1); PG8_STAGE(PG8_SB(0, 0), b2, voffB0);
;             PG8_BAR; PG8_WAIT_L(0); PG8_MMA(0, 1, At, B1); PG8_BAR;
;             PG8_LDA(At, 0, 1); PG8_STAGE(PG8_SA(0, 0), a2, voffA);
;             PG8_BAR; PG8_WAIT_L(0); PG8_MMA(1, 0, At, B0); PG8_BAR; PG8_SCHED;
;             PG8_STAGE(PG8_SB(0, 1), b2, voffB1);
.LBB0_1277:
	s_add_u32 s33, s44, s52
	s_addc_u32 s53, s45, 0
	s_add_u32 s50, s33, 0x100
	s_addc_u32 s51, s53, 0
	v_cndmask_b32_e64 v153, 0, 1, s[48:49]
	s_and_b64 s[48:49], s[46:47], exec
	s_cselect_b32 s51, s29, s51
	s_cselect_b32 s50, s39, s50
	s_add_u32 s48, s42, s52
	s_addc_u32 s49, s43, 0
	s_add_u32 s48, s48, 0x100
	s_addc_u32 s49, s49, 0
	s_and_b64 s[46:47], s[46:47], exec
	ds_read_b128 v[142:145], v150
	ds_read_b128 v[154:157], v150 offset:1024
	ds_read_b128 v[158:161], v150 offset:2048
	ds_read_b128 v[162:165], v150 offset:3072
	s_cselect_b32 s48, s73, s48
	s_cselect_b32 s49, s27, s49
	s_add_u32 s52, s33, 0x10080
	s_addc_u32 s53, s53, 0
	s_add_i32 s82, s71, s59
	s_add_i32 s78, s72, s59
	s_add_i32 m0, s41, 0xc000
	s_add_i32 s33, s41, 0xe000
	s_add_i32 s81, s82, 0x2000
	s_add_i32 s77, s78, 0x2000
	s_add_i32 s76, 0, 0x18000
	s_add_u32 s46, s50, 0x10000
	s_addc_u32 s47, s51, 0
	s_add_i32 s74, 0, 0x1c000
	s_add_i32 s75, s76, s59
	s_add_i32 s80, s74, s59
	s_add_i32 s83, s75, 0x2000
	s_add_i32 s79, s80, 0x2000
	v_cmp_ne_u32_e32 vcc, 1, v153
	v_lshl_add_u64 v[198:199], s[52:53], 0, v[128:129]
	ds_read_b128 v[166:169], v151
	ds_read_b128 v[170:173], v151 offset:1024
	ds_read_b128 v[174:177], v151 offset:2048
	ds_read_b128 v[178:181], v151 offset:3072
	ds_read_b128 v[182:185], v151 offset:4096
	ds_read_b128 v[186:189], v151 offset:5120
	ds_read_b128 v[190:193], v151 offset:6144
	ds_read_b128 v[194:197], v151 offset:7168
	global_load_lds_dwordx4 v[198:199], off
	v_lshl_add_u64 v[198:199], s[52:53], 0, v[134:135]
	s_mov_b32 m0, s33
	s_nop 0
	global_load_lds_dwordx4 v[198:199], off
	s_waitcnt lgkmcnt(8)
	s_barrier
	s_waitcnt lgkmcnt(0)
	s_waitcnt lgkmcnt(0)
	v_mfma_f32_16x16x32_bf16 v[124:127], v[142:145], v[166:169], v[124:127]
	v_mfma_f32_16x16x32_bf16 v[120:123], v[158:161], v[166:169], v[120:123]
	v_mfma_f32_16x16x32_bf16 v[108:111], v[142:145], v[174:177], v[108:111]
	v_mfma_f32_16x16x32_bf16 v[104:107], v[158:161], v[174:177], v[104:107]
	v_mfma_f32_16x16x32_bf16 v[92:95], v[142:145], v[182:185], v[92:95]
	v_mfma_f32_16x16x32_bf16 v[88:91], v[158:161], v[182:185], v[88:91]
	v_mfma_f32_16x16x32_bf16 v[76:79], v[142:145], v[190:193], v[76:79]
	v_mfma_f32_16x16x32_bf16 v[72:75], v[158:161], v[190:193], v[72:75]
	v_mfma_f32_16x16x32_bf16 v[124:127], v[154:157], v[170:173], v[124:127]
	v_mfma_f32_16x16x32_bf16 v[120:123], v[162:165], v[170:173], v[120:123]
	v_mfma_f32_16x16x32_bf16 v[108:111], v[154:157], v[178:181], v[108:111]
	v_mfma_f32_16x16x32_bf16 v[104:107], v[162:165], v[178:181], v[104:107]
	v_mfma_f32_16x16x32_bf16 v[92:95], v[154:157], v[186:189], v[92:95]
	v_mfma_f32_16x16x32_bf16 v[88:91], v[162:165], v[186:189], v[88:91]
	v_mfma_f32_16x16x32_bf16 v[76:79], v[154:157], v[194:197], v[76:79]
	v_mfma_f32_16x16x32_bf16 v[72:75], v[162:165], v[194:197], v[72:75]
	s_barrier
	s_mov_b32 m0, s82
	v_lshl_add_u64 v[216:217], s[48:49], 0, v[130:131]
	ds_read_b128 v[198:201], v152
	ds_read_b128 v[204:207], v152 offset:1024
	ds_read_b128 v[208:211], v152 offset:2048
	ds_read_b128 v[212:215], v152 offset:3072
	global_load_lds_dwordx4 v[216:217], off
	v_lshl_add_u64 v[218:219], s[48:49], 0, v[136:137]
	s_mov_b32 m0, s81
	s_nop 0
	global_load_lds_dwordx4 v[218:219], off
	s_barrier
	s_waitcnt lgkmcnt(0)
	s_waitcnt lgkmcnt(0)
	v_mfma_f32_16x16x32_bf16 v[116:119], v[198:201], v[166:169], v[116:119]
	v_mfma_f32_16x16x32_bf16 v[112:115], v[208:211], v[166:169], v[112:115]
	v_mfma_f32_16x16x32_bf16 v[100:103], v[198:201], v[174:177], v[100:103]
	v_mfma_f32_16x16x32_bf16 v[96:99], v[208:211], v[174:177], v[96:99]
	v_mfma_f32_16x16x32_bf16 v[84:87], v[198:201], v[182:185], v[84:87]
	v_mfma_f32_16x16x32_bf16 v[80:83], v[208:211], v[182:185], v[80:83]
	v_mfma_f32_16x16x32_bf16 v[68:71], v[198:201], v[190:193], v[68:71]
	v_mfma_f32_16x16x32_bf16 v[64:67], v[208:211], v[190:193], v[64:67]
	v_mfma_f32_16x16x32_bf16 v[116:119], v[204:207], v[170:173], v[116:119]
	v_mfma_f32_16x16x32_bf16 v[112:115], v[212:215], v[170:173], v[112:115]
	v_mfma_f32_16x16x32_bf16 v[100:103], v[204:207], v[178:181], v[100:103]
	v_mfma_f32_16x16x32_bf16 v[96:99], v[212:215], v[178:181], v[96:99]
	v_mfma_f32_16x16x32_bf16 v[84:87], v[204:207], v[186:189], v[84:87]
	v_mfma_f32_16x16x32_bf16 v[80:83], v[212:215], v[186:189], v[80:83]
	v_mfma_f32_16x16x32_bf16 v[68:71], v[204:207], v[194:197], v[68:71]
	v_mfma_f32_16x16x32_bf16 v[64:67], v[212:215], v[194:197], v[64:67]
	s_mov_b32 m0, s41
	v_lshl_add_u64 v[220:221], s[50:51], 0, v[128:129]
	s_barrier
	ds_read_b128 v[166:169], v151 offset:16384
	ds_read_b128 v[170:173], v151 offset:17408
	ds_read_b128 v[174:177], v151 offset:18432
	ds_read_b128 v[178:181], v151 offset:19456
	ds_read_b128 v[182:185], v151 offset:20480
	ds_read_b128 v[186:189], v151 offset:21504
	ds_read_b128 v[190:193], v151 offset:22528
	ds_read_b128 v[194:197], v151 offset:23552
	global_load_lds_dwordx4 v[220:221], off
	v_lshl_add_u64 v[222:223], s[50:51], 0, v[134:135]
	s_mov_b32 m0, s60
	s_nop 0
	global_load_lds_dwordx4 v[222:223], off
	s_barrier
	s_waitcnt lgkmcnt(0)
	s_waitcnt lgkmcnt(0)
	v_mfma_f32_16x16x32_bf16 v[60:63], v[142:145], v[166:169], v[60:63]
	v_mfma_f32_16x16x32_bf16 v[56:59], v[158:161], v[166:169], v[56:59]
	v_mfma_f32_16x16x32_bf16 v[44:47], v[142:145], v[174:177], v[44:47]
	v_mfma_f32_16x16x32_bf16 v[40:43], v[158:161], v[174:177], v[40:43]
	v_mfma_f32_16x16x32_bf16 v[28:31], v[142:145], v[182:185], v[28:31]
	v_mfma_f32_16x16x32_bf16 v[24:27], v[158:161], v[182:185], v[24:27]
	v_mfma_f32_16x16x32_bf16 v[12:15], v[142:145], v[190:193], v[12:15]
	v_mfma_f32_16x16x32_bf16 v[8:11], v[158:161], v[190:193], v[8:11]
	v_mfma_f32_16x16x32_bf16 v[60:63], v[154:157], v[170:173], v[60:63]
	v_mfma_f32_16x16x32_bf16 v[56:59], v[162:165], v[170:173], v[56:59]
	v_mfma_f32_16x16x32_bf16 v[44:47], v[154:157], v[178:181], v[44:47]
	v_mfma_f32_16x16x32_bf16 v[40:43], v[162:165], v[178:181], v[40:43]
	v_mfma_f32_16x16x32_bf16 v[28:31], v[154:157], v[186:189], v[28:31]
	v_mfma_f32_16x16x32_bf16 v[24:27], v[162:165], v[186:189], v[24:27]
	v_mfma_f32_16x16x32_bf16 v[12:15], v[154:157], v[194:197], v[12:15]
	v_mfma_f32_16x16x32_bf16 v[8:11], v[162:165], v[194:197], v[8:11]
	s_barrier
; #define PG8_STAGE(bufoff, gbase, voff) do { _Pragma("unroll") for (int _i = 0; _i < 2; ++_i) \
;         __builtin_amdgcn_global_load_lds((const unsigned*)((const char*)(gbase) + (voff)[_i]), (LAS unsigned*)(lds + (bufoff) + ldsw + _i * 8192), 16, 0, 0); } while (0)
; #define PG8_LDA(dst, b, h) do { _Pragma("unroll") for (int m = 0; m < 4; ++m) _Pragma("unroll") for (int k = 0; k < 2; ++k) dst[m][k] = *(const LAS bf16x8*)(lds + PG8_SA(b, h) + aoff + m * 2048 + k * 1024); } while (0)
; #define PG8_LDB(dst, b, h) do { _Pragma("unroll") for (int n = 0; n < 2; ++n) _Pragma("unroll") for (int k = 0; k < 2; ++k) dst[n][k] = *(const LAS bf16x8*)(lds + PG8_SB(b, h) + boff + n * 2048 + k * 1024); } while (0)
; #define PG8_MMA(ai, bj, At, Bt) do { __builtin_amdgcn_s_setprio(1); _Pragma("unroll") for (int m = 0; m < 4; ++m) _Pragma("unroll") for (int n = 0; n < 2; ++n) _Pragma("unroll") for (int k = 0; k < 2; ++k) \
;         acc[ai][bj][m][n] = __builtin_amdgcn_mfma_f32_16x16x32_bf16(Bt[n][k], At[m][k], acc[ai][bj][m][n], 0, 0, 0); __builtin_amdgcn_s_setprio(0); } while (0)
; #define PG8_WAIT_V(n) asm volatile("s_waitcnt vmcnt(" #n ")" ::: "memory")
; #define PG8_WAIT_L(n) asm volatile("s_waitcnt lgkmcnt(" #n ")" ::: "memory")
; #define PG8_BAR __builtin_amdgcn_s_barrier()
; #define PG8_SCHED __builtin_amdgcn_sched_barrier(0)
; template <class Epi>
; __device__ __forceinline__ void gemm_phase(LAS unsigned char* lds, const Gemm g, const StaticOrder& S, const Epi& E) {
;     ...
;             PG8_STAGE(PG8_SB(0, 1), b2, voffB1);
;             PG8_WAIT_V(6); PG8_BAR; PG8_MMA(1, 1, At, B1); PG8_BAR;
;             PG8_LDB(B0, 1, 0); PG8_SCHED; PG8_LDA(At, 1, 0); PG8_STAGE(PG8_SA(0, 1), a2 + hstep, voffA);
;             PG8_WAIT_L(8); PG8_BAR; PG8_WAIT_L(0); PG8_MMA(0, 0, At, B0); PG8_BAR; PG8_SCHED;
;             PG8_LDB(B1, 1, 1); PG8_STAGE(PG8_SB(1, 0), b3, voffB0);
;             PG8_BAR; PG8_WAIT_L(0); PG8_MMA(0, 1, At, B1); PG8_BAR;
;             PG8_LDA(At, 1, 1); PG8_STAGE(PG8_SA(1, 0), a3, voffA);
;             PG8_BAR; PG8_WAIT_L(0); PG8_MMA(1, 0, At, B0); PG8_BAR; PG8_SCHED;
;             PG8_STAGE(PG8_SB(1, 1), b3, voffB1);
	s_mov_b32 m0, s78
	v_lshl_add_u64 v[224:225], s[48:49], 0, v[132:133]
	global_load_lds_dwordx4 v[224:225], off
	v_lshl_add_u64 v[226:227], s[48:49], 0, v[138:139]
	s_mov_b32 m0, s77
	s_nop 0
	global_load_lds_dwordx4 v[226:227], off
	s_waitcnt vmcnt(6)
	s_barrier
	v_mfma_f32_16x16x32_bf16 v[52:55], v[198:201], v[166:169], v[52:55]
	v_mfma_f32_16x16x32_bf16 v[48:51], v[208:211], v[166:169], v[48:51]
	v_mfma_f32_16x16x32_bf16 v[36:39], v[198:201], v[174:177], v[36:39]
	v_mfma_f32_16x16x32_bf16 v[32:35], v[208:211], v[174:177], v[32:35]
	v_mfma_f32_16x16x32_bf16 v[20:23], v[198:201], v[182:185], v[20:23]
	v_mfma_f32_16x16x32_bf16 v[16:19], v[208:211], v[182:185], v[16:19]
	v_mfma_f32_16x16x32_bf16 v[4:7], v[198:201], v[190:193], v[4:7]
	v_mfma_f32_16x16x32_bf16 v[0:3], v[208:211], v[190:193], v[0:3]
	v_mfma_f32_16x16x32_bf16 v[52:55], v[204:207], v[170:173], v[52:55]
	v_mfma_f32_16x16x32_bf16 v[48:51], v[212:215], v[170:173], v[48:51]
	v_mfma_f32_16x16x32_bf16 v[36:39], v[204:207], v[178:181], v[36:39]
	v_mfma_f32_16x16x32_bf16 v[32:35], v[212:215], v[178:181], v[32:35]
	v_mfma_f32_16x16x32_bf16 v[20:23], v[204:207], v[186:189], v[20:23]
	v_mfma_f32_16x16x32_bf16 v[16:19], v[212:215], v[186:189], v[16:19]
	v_mfma_f32_16x16x32_bf16 v[4:7], v[204:207], v[194:197], v[4:7]
	v_mfma_f32_16x16x32_bf16 v[0:3], v[212:215], v[194:197], v[0:3]
	v_add_u32_e32 v153, s76, v147
	s_barrier
	ds_read_b128 v[142:145], v153
	ds_read_b128 v[154:157], v153 offset:1024
	ds_read_b128 v[158:161], v153 offset:2048
	ds_read_b128 v[162:165], v153 offset:3072
	s_mov_b32 m0, s61
	v_lshl_add_u64 v[198:199], s[46:47], 0, v[128:129]
	ds_read_b128 v[166:169], v151 offset:32768
	ds_read_b128 v[170:173], v151 offset:33792
	ds_read_b128 v[174:177], v151 offset:34816
	ds_read_b128 v[178:181], v151 offset:35840
	ds_read_b128 v[182:185], v151 offset:36864
	ds_read_b128 v[186:189], v151 offset:37888
	ds_read_b128 v[190:193], v151 offset:38912
	ds_read_b128 v[194:197], v151 offset:39936
	global_load_lds_dwordx4 v[198:199], off
	v_lshl_add_u64 v[198:199], s[46:47], 0, v[134:135]
	s_mov_b32 m0, s62
	s_nop 0
	global_load_lds_dwordx4 v[198:199], off
	s_waitcnt lgkmcnt(8)
	s_barrier
	s_waitcnt lgkmcnt(0)
	s_waitcnt lgkmcnt(0)
	v_mfma_f32_16x16x32_bf16 v[124:127], v[142:145], v[166:169], v[124:127]
	v_mfma_f32_16x16x32_bf16 v[120:123], v[158:161], v[166:169], v[120:123]
	v_mfma_f32_16x16x32_bf16 v[108:111], v[142:145], v[174:177], v[108:111]
	v_mfma_f32_16x16x32_bf16 v[104:107], v[158:161], v[174:177], v[104:107]
	v_mfma_f32_16x16x32_bf16 v[92:95], v[142:145], v[182:185], v[92:95]
	v_mfma_f32_16x16x32_bf16 v[88:91], v[158:161], v[182:185], v[88:91]
	v_mfma_f32_16x16x32_bf16 v[76:79], v[142:145], v[190:193], v[76:79]
	v_mfma_f32_16x16x32_bf16 v[72:75], v[158:161], v[190:193], v[72:75]
	v_mfma_f32_16x16x32_bf16 v[124:127], v[154:157], v[170:173], v[124:127]
	v_mfma_f32_16x16x32_bf16 v[120:123], v[162:165], v[170:173], v[120:123]
	v_mfma_f32_16x16x32_bf16 v[108:111], v[154:157], v[178:181], v[108:111]
	v_mfma_f32_16x16x32_bf16 v[104:107], v[162:165], v[178:181], v[104:107]
	v_mfma_f32_16x16x32_bf16 v[92:95], v[154:157], v[186:189], v[92:95]
	v_mfma_f32_16x16x32_bf16 v[88:91], v[162:165], v[186:189], v[88:91]
	v_mfma_f32_16x16x32_bf16 v[76:79], v[154:157], v[194:197], v[76:79]
	v_mfma_f32_16x16x32_bf16 v[72:75], v[162:165], v[194:197], v[72:75]
	s_barrier
	s_mov_b32 m0, s75
	v_add_u32_e32 v153, s74, v147
	v_lshl_add_u64 v[216:217], v[216:217], 0, s[18:19]
	ds_read_b128 v[198:201], v153
	ds_read_b128 v[204:207], v153 offset:1024
	ds_read_b128 v[208:211], v153 offset:2048
	ds_read_b128 v[212:215], v153 offset:3072
	global_load_lds_dwordx4 v[216:217], off
	v_lshl_add_u64 v[216:217], v[218:219], 0, s[18:19]
	s_mov_b32 m0, s83
	s_nop 0
	global_load_lds_dwordx4 v[216:217], off
	s_barrier
	s_waitcnt lgkmcnt(0)
	s_waitcnt lgkmcnt(0)
	v_mfma_f32_16x16x32_bf16 v[116:119], v[198:201], v[166:169], v[116:119]
	v_mfma_f32_16x16x32_bf16 v[112:115], v[208:211], v[166:169], v[112:115]
	v_mfma_f32_16x16x32_bf16 v[100:103], v[198:201], v[174:177], v[100:103]
	v_mfma_f32_16x16x32_bf16 v[96:99], v[208:211], v[174:177], v[96:99]
	v_mfma_f32_16x16x32_bf16 v[84:87], v[198:201], v[182:185], v[84:87]
	v_mfma_f32_16x16x32_bf16 v[80:83], v[208:211], v[182:185], v[80:83]
	v_mfma_f32_16x16x32_bf16 v[68:71], v[198:201], v[190:193], v[68:71]
	v_mfma_f32_16x16x32_bf16 v[64:67], v[208:211], v[190:193], v[64:67]
	v_mfma_f32_16x16x32_bf16 v[116:119], v[204:207], v[170:173], v[116:119]
	v_mfma_f32_16x16x32_bf16 v[112:115], v[212:215], v[170:173], v[112:115]
	v_mfma_f32_16x16x32_bf16 v[100:103], v[204:207], v[178:181], v[100:103]
	v_mfma_f32_16x16x32_bf16 v[96:99], v[212:215], v[178:181], v[96:99]
	v_mfma_f32_16x16x32_bf16 v[84:87], v[204:207], v[186:189], v[84:87]
	v_mfma_f32_16x16x32_bf16 v[80:83], v[212:215], v[186:189], v[80:83]
	v_mfma_f32_16x16x32_bf16 v[68:71], v[204:207], v[194:197], v[68:71]
	v_mfma_f32_16x16x32_bf16 v[64:67], v[212:215], v[194:197], v[64:67]
	s_mov_b32 m0, s64
	v_lshl_add_u64 v[216:217], v[220:221], 0, s[18:19]
	s_barrier
	ds_read_b128 v[166:169], v151 offset:49152
	ds_read_b128 v[170:173], v151 offset:50176
	ds_read_b128 v[174:177], v151 offset:51200
	ds_read_b128 v[178:181], v151 offset:52224
	ds_read_b128 v[182:185], v151 offset:53248
	ds_read_b128 v[186:189], v151 offset:54272
	ds_read_b128 v[190:193], v151 offset:55296
	ds_read_b128 v[194:197], v151 offset:56320
	global_load_lds_dwordx4 v[216:217], off
	v_lshl_add_u64 v[216:217], v[222:223], 0, s[18:19]
	s_mov_b32 m0, s65
	s_nop 0
	global_load_lds_dwordx4 v[216:217], off
	s_barrier
; __device__ __forceinline__ unsigned cvt_pk_bf16(float lo, float hi) { unsigned r; asm volatile("v_cvt_pk_bf16_f32 %0, %1, %2" : "=v"(r) : "v"(lo), "v"(hi)); return r; }
; #define PG8_STAGE(bufoff, gbase, voff) do { _Pragma("unroll") for (int _i = 0; _i < 2; ++_i) \
;         __builtin_amdgcn_global_load_lds((const unsigned*)((const char*)(gbase) + (voff)[_i]), (LAS unsigned*)(lds + (bufoff) + ldsw + _i * 8192), 16, 0, 0); } while (0)
; #define PG8_MMA(ai, bj, At, Bt) do { __builtin_amdgcn_s_setprio(1); _Pragma("unroll") for (int m = 0; m < 4; ++m) _Pragma("unroll") for (int n = 0; n < 2; ++n) _Pragma("unroll") for (int k = 0; k < 2; ++k) \
;         acc[ai][bj][m][n] = __builtin_amdgcn_mfma_f32_16x16x32_bf16(Bt[n][k], At[m][k], acc[ai][bj][m][n], 0, 0, 0); __builtin_amdgcn_s_setprio(0); } while (0)
;     __device__ __forceinline__ void operator()(const f32x4 (&acc)[2][2][4][2], const Unit& u, int wr, int wc, int fr, int fq) const {
;     ...
;             for (int m = 0; m < 4; ++m) { const int row = row0 + ai * HALF + m * 16;
;                 const float rs = ssin ? __builtin_amdgcn_rsqf(ssin[row] * (1.f / D) + EPS) : 1.0f; float sq = 0.f; u32x4 w[2];
; #pragma unroll
;                 for (int bj = 0; bj < 2; ++bj) { f32x4 v0 = acc[ai][bj][m][0] * rs, v1 = acc[ai][bj][m][1] * rs;
;                     if (ACT == 1) {
; #pragma unroll
;                         for (int j = 0; j < 4; ++j) { const float a = fmaxf(v0[j], 0.f), b = fmaxf(v1[j], 0.f); v0[j] = a * a; v1[j] = b * b; } }
;                     sq += (v0[0] * v0[0] + v0[1] * v0[1]) + (v0[2] * v0[2] + v0[3] * v0[3]) + (v1[0] * v1[0] + v1[1] * v1[1]) + (v1[2] * v1[2] + v1[3] * v1[3]);
;                     w[bj].x = cvt_pk_bf16(v0[0], v0[1]); w[bj].y = cvt_pk_bf16(v0[2], v0[3]); w[bj].z = cvt_pk_bf16(v1[0], v1[1]); w[bj].w = cvt_pk_bf16(v1[2], v1[3]); }
;                 store_pair_lines(O, ldc, row, fr, col0, w[0], w[1]);
;                 if (ssout) { sq += __shfl_xor(sq, 16); sq += __shfl_xor(sq, 32); if (fq == 0) unsafeAtomicAdd(ssout + row, sq); } }
; template <class Epi>
; __device__ __forceinline__ void gemm_phase(LAS unsigned char* lds, const Gemm g, const StaticOrder& S, const Epi& E) {
;     ...
;             PG8_BAR; PG8_WAIT_L(0); PG8_MMA(1, 0, At, B0); PG8_BAR; PG8_SCHED;
;             PG8_STAGE(PG8_SB(1, 1), b3, voffB1);
;             PG8_WAIT_V(6); PG8_BAR; PG8_MMA(1, 1, At, B1); PG8_BAR;
;         }
	s_waitcnt lgkmcnt(0)
	s_waitcnt lgkmcnt(0)
	v_mfma_f32_16x16x32_bf16 v[60:63], v[142:145], v[166:169], v[60:63]
	v_mfma_f32_16x16x32_bf16 v[56:59], v[158:161], v[166:169], v[56:59]
	v_mfma_f32_16x16x32_bf16 v[44:47], v[142:145], v[174:177], v[44:47]
	v_mfma_f32_16x16x32_bf16 v[40:43], v[158:161], v[174:177], v[40:43]
	v_mfma_f32_16x16x32_bf16 v[28:31], v[142:145], v[182:185], v[28:31]
	v_mfma_f32_16x16x32_bf16 v[24:27], v[158:161], v[182:185], v[24:27]
	v_mfma_f32_16x16x32_bf16 v[12:15], v[142:145], v[190:193], v[12:15]
	v_mfma_f32_16x16x32_bf16 v[8:11], v[158:161], v[190:193], v[8:11]
	v_mfma_f32_16x16x32_bf16 v[60:63], v[154:157], v[170:173], v[60:63]
	v_mfma_f32_16x16x32_bf16 v[56:59], v[162:165], v[170:173], v[56:59]
	v_mfma_f32_16x16x32_bf16 v[44:47], v[154:157], v[178:181], v[44:47]
	v_mfma_f32_16x16x32_bf16 v[40:43], v[162:165], v[178:181], v[40:43]
	v_mfma_f32_16x16x32_bf16 v[28:31], v[154:157], v[186:189], v[28:31]
	v_mfma_f32_16x16x32_bf16 v[24:27], v[162:165], v[186:189], v[24:27]
	v_mfma_f32_16x16x32_bf16 v[12:15], v[154:157], v[194:197], v[12:15]
	v_mfma_f32_16x16x32_bf16 v[8:11], v[162:165], v[194:197], v[8:11]
	s_barrier
	s_mov_b32 m0, s80
	v_lshl_add_u64 v[142:143], v[224:225], 0, s[18:19]
	global_load_lds_dwordx4 v[142:143], off
	v_lshl_add_u64 v[142:143], v[226:227], 0, s[18:19]
	s_mov_b32 m0, s79
	s_nop 0
	global_load_lds_dwordx4 v[142:143], off
	s_waitcnt vmcnt(6)
	s_barrier
	v_mfma_f32_16x16x32_bf16 v[52:55], v[198:201], v[166:169], v[52:55]
	v_mfma_f32_16x16x32_bf16 v[48:51], v[208:211], v[166:169], v[48:51]
	v_mfma_f32_16x16x32_bf16 v[36:39], v[198:201], v[174:177], v[36:39]
	v_mfma_f32_16x16x32_bf16 v[32:35], v[208:211], v[174:177], v[32:35]
	v_mfma_f32_16x16x32_bf16 v[20:23], v[198:201], v[182:185], v[20:23]
	v_mfma_f32_16x16x32_bf16 v[16:19], v[208:211], v[182:185], v[16:19]
	v_mfma_f32_16x16x32_bf16 v[4:7], v[198:201], v[190:193], v[4:7]
	v_mfma_f32_16x16x32_bf16 v[0:3], v[208:211], v[190:193], v[0:3]
	v_mfma_f32_16x16x32_bf16 v[52:55], v[204:207], v[170:173], v[52:55]
	v_mfma_f32_16x16x32_bf16 v[48:51], v[212:215], v[170:173], v[48:51]
	v_mfma_f32_16x16x32_bf16 v[36:39], v[204:207], v[178:181], v[36:39]
	v_mfma_f32_16x16x32_bf16 v[32:35], v[212:215], v[178:181], v[32:35]
	v_mfma_f32_16x16x32_bf16 v[20:23], v[204:207], v[186:189], v[20:23]
	v_mfma_f32_16x16x32_bf16 v[16:19], v[212:215], v[186:189], v[16:19]
	v_mfma_f32_16x16x32_bf16 v[4:7], v[204:207], v[194:197], v[4:7]
	v_mfma_f32_16x16x32_bf16 v[0:3], v[212:215], v[194:197], v[0:3]
	s_movk_i32 s52, 0x100
	s_mov_b64 s[48:49], 0
	s_mov_b64 s[46:47], -1
	s_barrier
	s_cbranch_vccz .LBB0_1277
	v_cvt_pk_bf16_f32 v145, v124, v125
	v_cvt_pk_bf16_f32 v153, v126, v127
	v_cvt_pk_bf16_f32 v156, v120, v121
	v_cvt_pk_bf16_f32 v157, v122, v123
	v_cvt_pk_bf16_f32 v158, v116, v117
	v_cvt_pk_bf16_f32 v159, v118, v119
	v_cvt_pk_bf16_f32 v160, v112, v113
	v_cvt_pk_bf16_f32 v161, v114, v115
	v_mul_f32_e32 v123, v123, v123
	v_mul_f32_e32 v115, v115, v115
	v_fmac_f32_e32 v123, v122, v122
	v_mul_f32_e32 v122, v125, v125
	v_fmac_f32_e32 v115, v114, v114
	v_mul_f32_e32 v114, v117, v117
	v_fmac_f32_e32 v122, v124, v124
	v_mul_f32_e32 v124, v127, v127
	v_fmac_f32_e32 v114, v116, v116
	v_mul_f32_e32 v116, v119, v119
	v_fmac_f32_e32 v124, v126, v126
	v_mul_f32_e32 v121, v121, v121
	v_fmac_f32_e32 v116, v118, v118
	v_mul_f32_e32 v113, v113, v113
	v_add_f32_e32 v122, v122, v124
	v_fmac_f32_e32 v121, v120, v120
	v_add_f32_e32 v114, v114, v116
	v_fmac_f32_e32 v113, v112, v112
	v_add_f32_e32 v120, v122, v121
	v_add_f32_e32 v112, v114, v113
	s_lshl_b32 s27, s40, 8
	v_mov_b32_e32 v162, 0
	v_add_f32_e32 v120, v123, v120
	v_add_f32_e32 v112, v115, v112
	v_and_b32_e32 v113, 64, v203
	s_add_i32 s27, s27, s66
	v_mov_b32_dpp v162, v145 row_ror:8 row_mask:0xf bank_mask:0xf
	v_mov_b32_e32 v163, 0
	v_mov_b32_e32 v154, 0
	v_add_f32_e32 v115, v120, v112
	v_xor_b32_e32 v112, 16, v203
	v_add_u32_e32 v118, 64, v113
	v_mov_b32_dpp v163, v153 row_ror:8 row_mask:0xf bank_mask:0xf
	v_mov_b32_e32 v164, 0
	v_mov_b32_e32 v165, 0
	v_mov_b32_dpp v154, v158 row_ror:8 row_mask:0xf bank_mask:0xf
	v_mov_b32_e32 v155, 0
	v_cndmask_b32_e64 v158, v158, v162, s[6:7]
	v_or_b32_e32 v162, s27, v148
	v_cmp_lt_i32_e32 vcc, v112, v118
	v_lshl_or_b32 v142, s38, 8, v149
	v_mov_b32_dpp v164, v156 row_ror:8 row_mask:0xf bank_mask:0xf
	v_mov_b32_dpp v165, v157 row_ror:8 row_mask:0xf bank_mask:0xf
	v_mov_b32_dpp v155, v159 row_ror:8 row_mask:0xf bank_mask:0xf
	v_mov_b32_e32 v166, 0
	v_mov_b32_e32 v167, 0
	v_cndmask_b32_e64 v159, v159, v163, s[6:7]
	v_ashrrev_i32_e32 v163, 31, v162
	v_cndmask_b32_e32 v112, v203, v112, vcc
	v_ashrrev_i32_e32 v143, 31, v142
	v_mov_b32_dpp v166, v160 row_ror:8 row_mask:0xf bank_mask:0xf
	v_mov_b32_dpp v167, v161 row_ror:8 row_mask:0xf bank_mask:0xf
	v_cndmask_b32_e64 v160, v160, v164, s[6:7]
	v_cndmask_b32_e64 v161, v161, v165, s[6:7]
	v_lshlrev_b64 v[164:165], 12, v[162:163]
	v_lshlrev_b32_e32 v114, 2, v112
	v_cndmask_b32_e64 v156, v166, v156, s[6:7]
	v_cndmask_b32_e64 v157, v167, v157, s[6:7]
	v_lshl_add_u64 v[164:165], s[10:11], 0, v[164:165]
	v_lshlrev_b64 v[166:167], 1, v[142:143]
	ds_bpermute_b32 v119, v114, v115
	v_cndmask_b32_e64 v154, v154, v145, s[6:7]
	v_cndmask_b32_e64 v155, v155, v153, s[6:7]
	v_lshl_add_u64 v[112:113], v[164:165], 0, v[166:167]
	global_store_dwordx4 v[112:113], v[154:157], off
	v_xor_b32_e32 v113, 32, v203
	v_cmp_lt_i32_e32 vcc, v113, v118
	s_waitcnt lgkmcnt(0)
	v_add_f32_e32 v112, v115, v119
	v_or_b32_e32 v116, 8, v162
	v_cndmask_b32_e32 v113, v203, v113, vcc
	v_lshlrev_b32_e32 v115, 2, v113
	ds_bpermute_b32 v113, v115, v112
	v_ashrrev_i32_e32 v117, 31, v116
	v_lshlrev_b64 v[116:117], 12, v[116:117]
	v_lshl_add_u64 v[116:117], s[10:11], 0, v[116:117]
	v_or_b32_e32 v144, s27, v146
	v_lshl_add_u64 v[116:117], v[116:117], 0, v[166:167]
	global_store_dwordx4 v[116:117], v[158:161], off
	s_and_saveexec_b64 s[38:39], s[8:9]
	s_cbranch_execz .LBB0_1280
	v_ashrrev_i32_e32 v145, 31, v144
	s_waitcnt lgkmcnt(0)
	v_add_f32_e32 v116, v112, v113
	v_lshl_add_u64 v[112:113], v[144:145], 2, s[16:17]
	global_atomic_add_f32 v[112:113], v116, off

; #define PG8_STAGE(bufoff, gbase, voff) do { _Pragma("unroll") for (int _i = 0; _i < 2; ++_i) \
;         __builtin_amdgcn_global_load_lds((const unsigned*)((const char*)(gbase) + (voff)[_i]), (LAS unsigned*)(lds + (bufoff) + ldsw + _i * 8192), 16, 0, 0); } while (0)
; #define PG8_LDA(dst, b, h) do { _Pragma("unroll") for (int m = 0; m < 4; ++m) _Pragma("unroll") for (int k = 0; k < 2; ++k) dst[m][k] = *(const LAS bf16x8*)(lds + PG8_SA(b, h) + aoff + m * 2048 + k * 1024); } while (0)
; #define PG8_LDB(dst, b, h) do { _Pragma("unroll") for (int n = 0; n < 2; ++n) _Pragma("unroll") for (int k = 0; k < 2; ++k) dst[n][k] = *(const LAS bf16x8*)(lds + PG8_SB(b, h) + boff + n * 2048 + k * 1024); } while (0)
; #define PG8_MMA(ai, bj, At, Bt) do { __builtin_amdgcn_s_setprio(1); _Pragma("unroll") for (int m = 0; m < 4; ++m) _Pragma("unroll") for (int n = 0; n < 2; ++n) _Pragma("unroll") for (int k = 0; k < 2; ++k) \
;         acc[ai][bj][m][n] = __builtin_amdgcn_mfma_f32_16x16x32_bf16(Bt[n][k], At[m][k], acc[ai][bj][m][n], 0, 0, 0); __builtin_amdgcn_s_setprio(0); } while (0)
; #define PG8_WAIT_L(n) asm volatile("s_waitcnt lgkmcnt(" #n ")" ::: "memory")
; #define PG8_BAR __builtin_amdgcn_s_barrier()
; #define PG8_SCHED __builtin_amdgcn_sched_barrier(0)
; template <class Epi>
; __device__ __forceinline__ void gemm_phase(LAS unsigned char* lds, const Gemm g, const StaticOrder& S, const Epi& E) {
;     ...
;             const bool last = (t == nt - 2);
;             const char* a1 = cA + (size_t)(t + 1) * kstep;
;             const char* a2 = last ? nA : cA + (size_t)(t + 2) * kstep; const char* b2 = last ? nB : cB + (size_t)(t + 2) * kstep;
;             const char* a3 = a2 + kstep; const char* b3 = b2 + kstep;
;             PG8_LDB(B0, 0, 0); PG8_SCHED; PG8_LDA(At, 0, 0); PG8_STAGE(PG8_SA(1, 1), a1 + hstep, voffA);
;             PG8_WAIT_L(8); PG8_BAR; PG8_WAIT_L(0); PG8_MMA(0, 0, At, B0); PG8_BAR; PG8_SCHED;
;             PG8_LDB(B1, 0, 1); PG8_STAGE(PG8_SB(0, 0), b2, voffB0);
;             PG8_BAR; PG8_WAIT_L(0); PG8_MMA(0, 1, At, B1); PG8_BAR;
;             PG8_LDA(At, 0, 1); PG8_STAGE(PG8_SA(0, 0), a2, voffA);
;             PG8_BAR; PG8_WAIT_L(0); PG8_MMA(1, 0, At, B0); PG8_BAR; PG8_SCHED;
;             PG8_STAGE(PG8_SB(0, 1), b2, voffB1);
.LBB0_1365:
	ds_read_b128 v[160:163], v157
	ds_read_b128 v[164:167], v157 offset:1024
	ds_read_b128 v[168:171], v157 offset:2048
	ds_read_b128 v[172:175], v157 offset:3072
	s_add_u32 s33, s38, 0xfff80080
	s_addc_u32 s40, s39, -1
	s_cmp_eq_u32 s64, 28
	s_cselect_b32 s41, s27, s40
	s_cselect_b32 s40, s60, s33
	s_cselect_b32 s43, s19, s63
	s_cselect_b32 s42, s61, s62
	v_lshl_add_u64 v[200:201], s[38:39], 0, v[140:141]
	s_add_i32 m0, s37, 0xc000
	ds_read_b128 v[176:179], v158
	ds_read_b128 v[180:183], v158 offset:1024
	ds_read_b128 v[184:187], v158 offset:2048
	ds_read_b128 v[188:191], v158 offset:3072
	ds_read_b128 v[192:195], v158 offset:4096
	ds_read_b128 v[196:199], v158 offset:5120
	ds_read_b128 v[204:207], v158 offset:6144
	ds_read_b128 v[208:211], v158 offset:7168
	global_load_lds_dwordx4 v[200:201], off
	v_lshl_add_u64 v[200:201], s[38:39], 0, v[142:143]
	s_add_i32 m0, s37, 0xe000
	s_nop 0
	global_load_lds_dwordx4 v[200:201], off
	s_waitcnt lgkmcnt(8)
	s_barrier
	s_waitcnt lgkmcnt(0)
	s_waitcnt lgkmcnt(0)
	v_mfma_f32_16x16x32_bf16 v[124:127], v[160:163], v[176:179], v[124:127]
	v_mfma_f32_16x16x32_bf16 v[120:123], v[168:171], v[176:179], v[120:123]
	v_mfma_f32_16x16x32_bf16 v[108:111], v[160:163], v[184:187], v[108:111]
	v_mfma_f32_16x16x32_bf16 v[104:107], v[168:171], v[184:187], v[104:107]
	v_mfma_f32_16x16x32_bf16 v[92:95], v[160:163], v[192:195], v[92:95]
	v_mfma_f32_16x16x32_bf16 v[88:91], v[168:171], v[192:195], v[88:91]
	v_mfma_f32_16x16x32_bf16 v[76:79], v[160:163], v[204:207], v[76:79]
	v_mfma_f32_16x16x32_bf16 v[72:75], v[168:171], v[204:207], v[72:75]
	v_mfma_f32_16x16x32_bf16 v[124:127], v[164:167], v[180:183], v[124:127]
	v_mfma_f32_16x16x32_bf16 v[120:123], v[172:175], v[180:183], v[120:123]
	v_mfma_f32_16x16x32_bf16 v[108:111], v[164:167], v[188:191], v[108:111]
	v_mfma_f32_16x16x32_bf16 v[104:107], v[172:175], v[188:191], v[104:107]
	v_mfma_f32_16x16x32_bf16 v[92:95], v[164:167], v[196:199], v[92:95]
	v_mfma_f32_16x16x32_bf16 v[88:91], v[172:175], v[196:199], v[88:91]
	v_mfma_f32_16x16x32_bf16 v[76:79], v[164:167], v[208:211], v[76:79]
	v_mfma_f32_16x16x32_bf16 v[72:75], v[172:175], v[208:211], v[72:75]
	s_barrier
	s_add_i32 s33, s56, s46
	v_lshl_add_u64 v[200:201], s[42:43], 0, v[130:131]
	s_mov_b32 m0, s33
	ds_read_b128 v[212:215], v159
	ds_read_b128 v[216:219], v159 offset:1024
	ds_read_b128 v[220:223], v159 offset:2048
	ds_read_b128 v[224:227], v159 offset:3072
	global_load_lds_dwordx4 v[200:201], off
	v_lshl_add_u64 v[228:229], s[42:43], 0, v[136:137]
	s_add_i32 m0, s33, 0x2000
	s_nop 0
	global_load_lds_dwordx4 v[228:229], off
	s_barrier
	s_waitcnt lgkmcnt(0)
	s_waitcnt lgkmcnt(0)
	v_mfma_f32_16x16x32_bf16 v[116:119], v[212:215], v[176:179], v[116:119]
	v_mfma_f32_16x16x32_bf16 v[112:115], v[220:223], v[176:179], v[112:115]
	v_mfma_f32_16x16x32_bf16 v[100:103], v[212:215], v[184:187], v[100:103]
	v_mfma_f32_16x16x32_bf16 v[96:99], v[220:223], v[184:187], v[96:99]
	v_mfma_f32_16x16x32_bf16 v[84:87], v[212:215], v[192:195], v[84:87]
	v_mfma_f32_16x16x32_bf16 v[80:83], v[220:223], v[192:195], v[80:83]
	v_mfma_f32_16x16x32_bf16 v[68:71], v[212:215], v[204:207], v[68:71]
	v_mfma_f32_16x16x32_bf16 v[64:67], v[220:223], v[204:207], v[64:67]
	v_mfma_f32_16x16x32_bf16 v[116:119], v[216:219], v[180:183], v[116:119]
	v_mfma_f32_16x16x32_bf16 v[112:115], v[224:227], v[180:183], v[112:115]
	v_mfma_f32_16x16x32_bf16 v[100:103], v[216:219], v[188:191], v[100:103]
	v_mfma_f32_16x16x32_bf16 v[96:99], v[224:227], v[188:191], v[96:99]
	v_mfma_f32_16x16x32_bf16 v[84:87], v[216:219], v[196:199], v[84:87]
	v_mfma_f32_16x16x32_bf16 v[80:83], v[224:227], v[196:199], v[80:83]
	v_mfma_f32_16x16x32_bf16 v[68:71], v[216:219], v[208:211], v[68:71]
	v_mfma_f32_16x16x32_bf16 v[64:67], v[224:227], v[208:211], v[64:67]
	s_mov_b32 m0, s37
	v_lshl_add_u64 v[230:231], s[40:41], 0, v[128:129]
	s_barrier
	ds_read_b128 v[176:179], v158 offset:16384
	ds_read_b128 v[180:183], v158 offset:17408
	ds_read_b128 v[184:187], v158 offset:18432
	ds_read_b128 v[188:191], v158 offset:19456
	ds_read_b128 v[192:195], v158 offset:20480
	ds_read_b128 v[196:199], v158 offset:21504
	ds_read_b128 v[204:207], v158 offset:22528
	ds_read_b128 v[208:211], v158 offset:23552
	global_load_lds_dwordx4 v[230:231], off
	v_lshl_add_u64 v[232:233], s[40:41], 0, v[134:135]
	s_mov_b32 m0, s47
	s_nop 0
	global_load_lds_dwordx4 v[232:233], off
	s_barrier
	s_waitcnt lgkmcnt(0)
	s_waitcnt lgkmcnt(0)
	v_mfma_f32_16x16x32_bf16 v[60:63], v[160:163], v[176:179], v[60:63]
	v_mfma_f32_16x16x32_bf16 v[56:59], v[168:171], v[176:179], v[56:59]
	v_mfma_f32_16x16x32_bf16 v[44:47], v[160:163], v[184:187], v[44:47]
	v_mfma_f32_16x16x32_bf16 v[40:43], v[168:171], v[184:187], v[40:43]
	v_mfma_f32_16x16x32_bf16 v[28:31], v[160:163], v[192:195], v[28:31]
	v_mfma_f32_16x16x32_bf16 v[24:27], v[168:171], v[192:195], v[24:27]
	v_mfma_f32_16x16x32_bf16 v[12:15], v[160:163], v[204:207], v[12:15]
	v_mfma_f32_16x16x32_bf16 v[8:11], v[168:171], v[204:207], v[8:11]
	v_mfma_f32_16x16x32_bf16 v[60:63], v[164:167], v[180:183], v[60:63]
	v_mfma_f32_16x16x32_bf16 v[56:59], v[172:175], v[180:183], v[56:59]
	v_mfma_f32_16x16x32_bf16 v[44:47], v[164:167], v[188:191], v[44:47]
	v_mfma_f32_16x16x32_bf16 v[40:43], v[172:175], v[188:191], v[40:43]
	v_mfma_f32_16x16x32_bf16 v[28:31], v[164:167], v[196:199], v[28:31]
	v_mfma_f32_16x16x32_bf16 v[24:27], v[172:175], v[196:199], v[24:27]
	v_mfma_f32_16x16x32_bf16 v[12:15], v[164:167], v[208:211], v[12:15]
	v_mfma_f32_16x16x32_bf16 v[8:11], v[172:175], v[208:211], v[8:11]
	s_barrier
; #define PG8_STAGE(bufoff, gbase, voff) do { _Pragma("unroll") for (int _i = 0; _i < 2; ++_i) \
;         __builtin_amdgcn_global_load_lds((const unsigned*)((const char*)(gbase) + (voff)[_i]), (LAS unsigned*)(lds + (bufoff) + ldsw + _i * 8192), 16, 0, 0); } while (0)
; #define PG8_LDA(dst, b, h) do { _Pragma("unroll") for (int m = 0; m < 4; ++m) _Pragma("unroll") for (int k = 0; k < 2; ++k) dst[m][k] = *(const LAS bf16x8*)(lds + PG8_SA(b, h) + aoff + m * 2048 + k * 1024); } while (0)
; #define PG8_LDB(dst, b, h) do { _Pragma("unroll") for (int n = 0; n < 2; ++n) _Pragma("unroll") for (int k = 0; k < 2; ++k) dst[n][k] = *(const LAS bf16x8*)(lds + PG8_SB(b, h) + boff + n * 2048 + k * 1024); } while (0)
; #define PG8_MMA(ai, bj, At, Bt) do { __builtin_amdgcn_s_setprio(1); _Pragma("unroll") for (int m = 0; m < 4; ++m) _Pragma("unroll") for (int n = 0; n < 2; ++n) _Pragma("unroll") for (int k = 0; k < 2; ++k) \
;         acc[ai][bj][m][n] = __builtin_amdgcn_mfma_f32_16x16x32_bf16(Bt[n][k], At[m][k], acc[ai][bj][m][n], 0, 0, 0); __builtin_amdgcn_s_setprio(0); } while (0)
; #define PG8_WAIT_V(n) asm volatile("s_waitcnt vmcnt(" #n ")" ::: "memory")
; #define PG8_WAIT_L(n) asm volatile("s_waitcnt lgkmcnt(" #n ")" ::: "memory")
; #define PG8_BAR __builtin_amdgcn_s_barrier()
; #define PG8_SCHED __builtin_amdgcn_sched_barrier(0)
; template <class Epi>
; __device__ __forceinline__ void gemm_phase(LAS unsigned char* lds, const Gemm g, const StaticOrder& S, const Epi& E) {
;     ...
;             PG8_STAGE(PG8_SB(0, 1), b2, voffB1);
;             PG8_WAIT_V(6); PG8_BAR; PG8_MMA(1, 1, At, B1); PG8_BAR;
;             PG8_LDB(B0, 1, 0); PG8_SCHED; PG8_LDA(At, 1, 0); PG8_STAGE(PG8_SA(0, 1), a2 + hstep, voffA);
;             PG8_WAIT_L(8); PG8_BAR; PG8_WAIT_L(0); PG8_MMA(0, 0, At, B0); PG8_BAR; PG8_SCHED;
;             PG8_LDB(B1, 1, 1); PG8_STAGE(PG8_SB(1, 0), b3, voffB0);
;             PG8_BAR; PG8_WAIT_L(0); PG8_MMA(0, 1, At, B1); PG8_BAR;
;             PG8_LDA(At, 1, 1); PG8_STAGE(PG8_SA(1, 0), a3, voffA);
;             PG8_BAR; PG8_WAIT_L(0); PG8_MMA(1, 0, At, B0); PG8_BAR; PG8_SCHED;
;             PG8_STAGE(PG8_SB(1, 1), b3, voffB1);
	s_add_i32 s33, s57, s46
	v_lshl_add_u64 v[234:235], s[42:43], 0, v[132:133]
	s_mov_b32 m0, s33
	v_lshl_add_u64 v[236:237], s[42:43], 0, v[138:139]
	global_load_lds_dwordx4 v[234:235], off
	s_add_i32 m0, s33, 0x2000
	s_nop 0
	global_load_lds_dwordx4 v[236:237], off
	s_waitcnt vmcnt(6)
	s_barrier
	v_mfma_f32_16x16x32_bf16 v[52:55], v[212:215], v[176:179], v[52:55]
	v_mfma_f32_16x16x32_bf16 v[48:51], v[220:223], v[176:179], v[48:51]
	v_mfma_f32_16x16x32_bf16 v[36:39], v[212:215], v[184:187], v[36:39]
	v_mfma_f32_16x16x32_bf16 v[32:35], v[220:223], v[184:187], v[32:35]
	v_mfma_f32_16x16x32_bf16 v[20:23], v[212:215], v[192:195], v[20:23]
	v_mfma_f32_16x16x32_bf16 v[16:19], v[220:223], v[192:195], v[16:19]
	v_mfma_f32_16x16x32_bf16 v[4:7], v[212:215], v[204:207], v[4:7]
	v_mfma_f32_16x16x32_bf16 v[0:3], v[220:223], v[204:207], v[0:3]
	v_mfma_f32_16x16x32_bf16 v[52:55], v[216:219], v[180:183], v[52:55]
	v_mfma_f32_16x16x32_bf16 v[48:51], v[224:227], v[180:183], v[48:51]
	v_mfma_f32_16x16x32_bf16 v[36:39], v[216:219], v[188:191], v[36:39]
	v_mfma_f32_16x16x32_bf16 v[32:35], v[224:227], v[188:191], v[32:35]
	v_mfma_f32_16x16x32_bf16 v[20:23], v[216:219], v[196:199], v[20:23]
	v_mfma_f32_16x16x32_bf16 v[16:19], v[224:227], v[196:199], v[16:19]
	v_mfma_f32_16x16x32_bf16 v[4:7], v[216:219], v[208:211], v[4:7]
	v_mfma_f32_16x16x32_bf16 v[0:3], v[224:227], v[208:211], v[0:3]
	s_add_i32 s33, 0, 0x18000
	v_add_u32_e32 v172, s33, v147
	s_barrier
	ds_read_b128 v[160:163], v172
	ds_read_b128 v[164:167], v172 offset:1024
	ds_read_b128 v[168:171], v172 offset:2048
	ds_read_b128 v[172:175], v172 offset:3072
	s_add_u32 s40, s40, 0x80000
	s_addc_u32 s41, s41, 0
	s_mov_b32 m0, s48
	v_lshl_add_u64 v[212:213], s[40:41], 0, v[128:129]
	ds_read_b128 v[176:179], v158 offset:32768
	ds_read_b128 v[180:183], v158 offset:33792
	ds_read_b128 v[184:187], v158 offset:34816
	ds_read_b128 v[188:191], v158 offset:35840
	ds_read_b128 v[192:195], v158 offset:36864
	ds_read_b128 v[196:199], v158 offset:37888
	ds_read_b128 v[204:207], v158 offset:38912
	ds_read_b128 v[208:211], v158 offset:39936
	global_load_lds_dwordx4 v[212:213], off
	v_lshl_add_u64 v[212:213], s[40:41], 0, v[134:135]
	s_mov_b32 m0, s49
	s_nop 0
	global_load_lds_dwordx4 v[212:213], off
	s_waitcnt lgkmcnt(8)
	s_barrier
	s_waitcnt lgkmcnt(0)
	s_waitcnt lgkmcnt(0)
	v_mfma_f32_16x16x32_bf16 v[124:127], v[160:163], v[176:179], v[124:127]
	v_mfma_f32_16x16x32_bf16 v[120:123], v[168:171], v[176:179], v[120:123]
	v_mfma_f32_16x16x32_bf16 v[108:111], v[160:163], v[184:187], v[108:111]
	v_mfma_f32_16x16x32_bf16 v[104:107], v[168:171], v[184:187], v[104:107]
	v_mfma_f32_16x16x32_bf16 v[92:95], v[160:163], v[192:195], v[92:95]
	v_mfma_f32_16x16x32_bf16 v[88:91], v[168:171], v[192:195], v[88:91]
	v_mfma_f32_16x16x32_bf16 v[76:79], v[160:163], v[204:207], v[76:79]
	v_mfma_f32_16x16x32_bf16 v[72:75], v[168:171], v[204:207], v[72:75]
	v_mfma_f32_16x16x32_bf16 v[124:127], v[164:167], v[180:183], v[124:127]
	v_mfma_f32_16x16x32_bf16 v[120:123], v[172:175], v[180:183], v[120:123]
	v_mfma_f32_16x16x32_bf16 v[108:111], v[164:167], v[188:191], v[108:111]
	v_mfma_f32_16x16x32_bf16 v[104:107], v[172:175], v[188:191], v[104:107]
	v_mfma_f32_16x16x32_bf16 v[92:95], v[164:167], v[196:199], v[92:95]
	v_mfma_f32_16x16x32_bf16 v[88:91], v[172:175], v[196:199], v[88:91]
	v_mfma_f32_16x16x32_bf16 v[76:79], v[164:167], v[208:211], v[76:79]
	v_mfma_f32_16x16x32_bf16 v[72:75], v[172:175], v[208:211], v[72:75]
	s_barrier
	s_add_i32 s40, 0, 0x1c000
	s_add_i32 s33, s33, s46
	v_add_u32_e32 v203, s40, v147
	v_lshl_add_u64 v[200:201], v[200:201], 0, s[16:17]
	s_mov_b32 m0, s33
	ds_read_b128 v[212:215], v203
	ds_read_b128 v[216:219], v203 offset:1024
	ds_read_b128 v[220:223], v203 offset:2048
	ds_read_b128 v[224:227], v203 offset:3072
	global_load_lds_dwordx4 v[200:201], off
	v_lshl_add_u64 v[200:201], v[228:229], 0, s[16:17]
	s_add_i32 m0, s33, 0x2000
	s_nop 0
	global_load_lds_dwordx4 v[200:201], off
	s_barrier
	s_waitcnt lgkmcnt(0)
	s_waitcnt lgkmcnt(0)
	v_mfma_f32_16x16x32_bf16 v[116:119], v[212:215], v[176:179], v[116:119]
	v_mfma_f32_16x16x32_bf16 v[112:115], v[220:223], v[176:179], v[112:115]
	v_mfma_f32_16x16x32_bf16 v[100:103], v[212:215], v[184:187], v[100:103]
	v_mfma_f32_16x16x32_bf16 v[96:99], v[220:223], v[184:187], v[96:99]
	v_mfma_f32_16x16x32_bf16 v[84:87], v[212:215], v[192:195], v[84:87]
	v_mfma_f32_16x16x32_bf16 v[80:83], v[220:223], v[192:195], v[80:83]
	v_mfma_f32_16x16x32_bf16 v[68:71], v[212:215], v[204:207], v[68:71]
	v_mfma_f32_16x16x32_bf16 v[64:67], v[220:223], v[204:207], v[64:67]
	v_mfma_f32_16x16x32_bf16 v[116:119], v[216:219], v[180:183], v[116:119]
	v_mfma_f32_16x16x32_bf16 v[112:115], v[224:227], v[180:183], v[112:115]
	v_mfma_f32_16x16x32_bf16 v[100:103], v[216:219], v[188:191], v[100:103]
	v_mfma_f32_16x16x32_bf16 v[96:99], v[224:227], v[188:191], v[96:99]
	v_mfma_f32_16x16x32_bf16 v[84:87], v[216:219], v[196:199], v[84:87]
	v_mfma_f32_16x16x32_bf16 v[80:83], v[224:227], v[196:199], v[80:83]
	v_mfma_f32_16x16x32_bf16 v[68:71], v[216:219], v[208:211], v[68:71]
	v_mfma_f32_16x16x32_bf16 v[64:67], v[224:227], v[208:211], v[64:67]
	s_mov_b32 m0, s51
	v_lshl_add_u64 v[200:201], v[230:231], 0, s[16:17]
	s_barrier
	ds_read_b128 v[176:179], v158 offset:49152
	ds_read_b128 v[180:183], v158 offset:50176
	ds_read_b128 v[184:187], v158 offset:51200
	ds_read_b128 v[188:191], v158 offset:52224
	ds_read_b128 v[192:195], v158 offset:53248
	ds_read_b128 v[196:199], v158 offset:54272
	ds_read_b128 v[204:207], v158 offset:55296
	ds_read_b128 v[208:211], v158 offset:56320
	global_load_lds_dwordx4 v[200:201], off
	v_lshl_add_u64 v[200:201], v[232:233], 0, s[16:17]
	s_mov_b32 m0, s52
	s_nop 0
	global_load_lds_dwordx4 v[200:201], off
	s_barrier
; __device__ __forceinline__ unsigned cvt_pk_bf16(float lo, float hi) { unsigned r; asm volatile("v_cvt_pk_bf16_f32 %0, %1, %2" : "=v"(r) : "v"(lo), "v"(hi)); return r; }
; #define PG8_STAGE(bufoff, gbase, voff) do { _Pragma("unroll") for (int _i = 0; _i < 2; ++_i) \
;         __builtin_amdgcn_global_load_lds((const unsigned*)((const char*)(gbase) + (voff)[_i]), (LAS unsigned*)(lds + (bufoff) + ldsw + _i * 8192), 16, 0, 0); } while (0)
; #define PG8_MMA(ai, bj, At, Bt) do { __builtin_amdgcn_s_setprio(1); _Pragma("unroll") for (int m = 0; m < 4; ++m) _Pragma("unroll") for (int n = 0; n < 2; ++n) _Pragma("unroll") for (int k = 0; k < 2; ++k) \
;         acc[ai][bj][m][n] = __builtin_amdgcn_mfma_f32_16x16x32_bf16(Bt[n][k], At[m][k], acc[ai][bj][m][n], 0, 0, 0); __builtin_amdgcn_s_setprio(0); } while (0)
; #define PG8_WAIT_V(n) asm volatile("s_waitcnt vmcnt(" #n ")" ::: "memory")
;     __device__ __forceinline__ void operator()(const f32x4 (&acc)[2][2][4][2], const Unit& u, int wr, int wc, int fr, int fq) const {
;     ...
;             for (int m = 0; m < 4; ++m) { const int row = row0 + ai * HALF + m * 16;
;                 const float rs = ssin ? __builtin_amdgcn_rsqf(ssin[row] * (1.f / D) + EPS) : 1.0f; float sq = 0.f; u32x4 w[2];
; #pragma unroll
;                 for (int bj = 0; bj < 2; ++bj) { f32x4 v0 = acc[ai][bj][m][0] * rs, v1 = acc[ai][bj][m][1] * rs;
;                     if (ACT == 1) {
; #pragma unroll
;                         for (int j = 0; j < 4; ++j) { const float a = fmaxf(v0[j], 0.f), b = fmaxf(v1[j], 0.f); v0[j] = a * a; v1[j] = b * b; } }
;                     sq += (v0[0] * v0[0] + v0[1] * v0[1]) + (v0[2] * v0[2] + v0[3] * v0[3]) + (v1[0] * v1[0] + v1[1] * v1[1]) + (v1[2] * v1[2] + v1[3] * v1[3]);
;                     w[bj].x = cvt_pk_bf16(v0[0], v0[1]); w[bj].y = cvt_pk_bf16(v0[2], v0[3]); w[bj].z = cvt_pk_bf16(v1[0], v1[1]); w[bj].w = cvt_pk_bf16(v1[2], v1[3]); }
;                 store_pair_lines(O, ldc, row, fr, col0, w[0], w[1]);
; template <class Epi>
; __device__ __forceinline__ void gemm_phase(LAS unsigned char* lds, const Gemm g, const StaticOrder& S, const Epi& E) {
;     ...
;             PG8_BAR; PG8_WAIT_L(0); PG8_MMA(1, 0, At, B0); PG8_BAR; PG8_SCHED;
;             PG8_STAGE(PG8_SB(1, 1), b3, voffB1);
;             PG8_WAIT_V(6); PG8_BAR; PG8_MMA(1, 1, At, B1); PG8_BAR;
;         }
;         E(acc, cur, wr, wc, fr, fq);
	s_waitcnt lgkmcnt(0)
	s_waitcnt lgkmcnt(0)
	v_mfma_f32_16x16x32_bf16 v[60:63], v[160:163], v[176:179], v[60:63]
	v_mfma_f32_16x16x32_bf16 v[56:59], v[168:171], v[176:179], v[56:59]
	v_mfma_f32_16x16x32_bf16 v[44:47], v[160:163], v[184:187], v[44:47]
	v_mfma_f32_16x16x32_bf16 v[40:43], v[168:171], v[184:187], v[40:43]
	v_mfma_f32_16x16x32_bf16 v[28:31], v[160:163], v[192:195], v[28:31]
	v_mfma_f32_16x16x32_bf16 v[24:27], v[168:171], v[192:195], v[24:27]
	v_mfma_f32_16x16x32_bf16 v[12:15], v[160:163], v[204:207], v[12:15]
	v_mfma_f32_16x16x32_bf16 v[8:11], v[168:171], v[204:207], v[8:11]
	v_mfma_f32_16x16x32_bf16 v[60:63], v[164:167], v[180:183], v[60:63]
	v_mfma_f32_16x16x32_bf16 v[56:59], v[172:175], v[180:183], v[56:59]
	v_mfma_f32_16x16x32_bf16 v[44:47], v[164:167], v[188:191], v[44:47]
	v_mfma_f32_16x16x32_bf16 v[40:43], v[172:175], v[188:191], v[40:43]
	v_mfma_f32_16x16x32_bf16 v[28:31], v[164:167], v[196:199], v[28:31]
	v_mfma_f32_16x16x32_bf16 v[24:27], v[172:175], v[196:199], v[24:27]
	v_mfma_f32_16x16x32_bf16 v[12:15], v[164:167], v[208:211], v[12:15]
	v_mfma_f32_16x16x32_bf16 v[8:11], v[172:175], v[208:211], v[8:11]
	s_barrier
	s_add_i32 s33, s40, s46
	v_lshl_add_u64 v[160:161], v[234:235], 0, s[16:17]
	s_mov_b32 m0, s33
	s_nop 0
	global_load_lds_dwordx4 v[160:161], off
	v_lshl_add_u64 v[160:161], v[236:237], 0, s[16:17]
	s_add_i32 m0, s33, 0x2000
	s_nop 0
	global_load_lds_dwordx4 v[160:161], off
	s_waitcnt vmcnt(6)
	s_barrier
	v_mfma_f32_16x16x32_bf16 v[52:55], v[212:215], v[176:179], v[52:55]
	v_mfma_f32_16x16x32_bf16 v[48:51], v[220:223], v[176:179], v[48:51]
	v_mfma_f32_16x16x32_bf16 v[36:39], v[212:215], v[184:187], v[36:39]
	v_mfma_f32_16x16x32_bf16 v[32:35], v[220:223], v[184:187], v[32:35]
	v_mfma_f32_16x16x32_bf16 v[20:23], v[212:215], v[192:195], v[20:23]
	v_mfma_f32_16x16x32_bf16 v[16:19], v[220:223], v[192:195], v[16:19]
	v_mfma_f32_16x16x32_bf16 v[4:7], v[212:215], v[204:207], v[4:7]
	v_mfma_f32_16x16x32_bf16 v[0:3], v[220:223], v[204:207], v[0:3]
	v_mfma_f32_16x16x32_bf16 v[52:55], v[216:219], v[180:183], v[52:55]
	v_mfma_f32_16x16x32_bf16 v[48:51], v[224:227], v[180:183], v[48:51]
	v_mfma_f32_16x16x32_bf16 v[36:39], v[216:219], v[188:191], v[36:39]
	v_mfma_f32_16x16x32_bf16 v[32:35], v[224:227], v[188:191], v[32:35]
	v_mfma_f32_16x16x32_bf16 v[20:23], v[216:219], v[196:199], v[20:23]
	v_mfma_f32_16x16x32_bf16 v[16:19], v[224:227], v[196:199], v[16:19]
	v_mfma_f32_16x16x32_bf16 v[4:7], v[216:219], v[208:211], v[4:7]
	v_mfma_f32_16x16x32_bf16 v[0:3], v[224:227], v[208:211], v[0:3]
	s_add_i32 s64, s64, 2
	s_add_u32 s38, s38, 0x100
	s_addc_u32 s39, s39, 0
	s_add_u32 s62, s62, 0x100
	s_addc_u32 s63, s63, 0
	s_cmp_gt_u32 s64, 29
	s_barrier
	s_cbranch_scc0 .LBB0_1365
	v_max_f32_e32 v124, v124, v124
	v_max_f32_e32 v120, v120, v120
	v_max_f32_e32 v125, v125, v125
	v_max_f32_e32 v121, v121, v121
	v_max_f32_e32 v122, v122, v122
	v_max_f32_e32 v118, v118, v118
	v_max_f32_e32 v119, v119, v119
	v_max_f32_e32 v124, 0, v124
	v_max_f32_e32 v120, 0, v120
	v_max_f32_e32 v125, 0, v125
	v_max_f32_e32 v121, 0, v121
	v_max_f32_e32 v126, v126, v126
	v_max_f32_e32 v122, 0, v122
	v_max_f32_e32 v127, v127, v127
	v_max_f32_e32 v123, v123, v123
	v_max_f32_e32 v116, v116, v116
	v_max_f32_e32 v112, v112, v112
	v_max_f32_e32 v117, v117, v117
	v_max_f32_e32 v113, v113, v113
	v_max_f32_e32 v118, 0, v118
	v_max_f32_e32 v114, v114, v114
	v_max_f32_e32 v119, 0, v119
	v_mul_f32_e32 v124, v124, v124
	v_mul_f32_e32 v120, v120, v120
	v_mul_f32_e32 v125, v125, v125
	v_mul_f32_e32 v121, v121, v121
	v_max_f32_e32 v126, 0, v126
	v_mul_f32_e32 v122, v122, v122
	v_max_f32_e32 v127, 0, v127
	v_max_f32_e32 v123, 0, v123
	v_max_f32_e32 v116, 0, v116
	v_max_f32_e32 v112, 0, v112
	v_max_f32_e32 v117, 0, v117
	v_max_f32_e32 v113, 0, v113
	v_max_f32_e32 v114, 0, v114
	v_mul_f32_e32 v118, v118, v118
	v_max_f32_e32 v115, v115, v115
	v_mul_f32_e32 v119, v119, v119
	s_lshl_b32 s19, s36, 8
	v_mul_f32_e32 v126, v126, v126
	v_mul_f32_e32 v127, v127, v127
	v_mul_f32_e32 v123, v123, v123
	v_cvt_pk_bf16_f32 v124, v124, v125
	v_cvt_pk_bf16_f32 v125, v126, v127
	v_cvt_pk_bf16_f32 v120, v120, v121
	v_cvt_pk_bf16_f32 v121, v122, v123
	v_mul_f32_e32 v116, v116, v116
	v_mul_f32_e32 v112, v112, v112
	v_mul_f32_e32 v117, v117, v117
	v_mul_f32_e32 v113, v113, v113
	v_mul_f32_e32 v114, v114, v114
	v_max_f32_e32 v115, 0, v115
	v_cvt_pk_bf16_f32 v122, v116, v117
	v_cvt_pk_bf16_f32 v119, v118, v119
	v_mov_b32_e32 v118, 0
	s_add_i32 s19, s19, s53
	v_mul_f32_e32 v115, v115, v115
	v_cvt_pk_bf16_f32 v112, v112, v113
	v_cvt_pk_bf16_f32 v113, v114, v115
	v_mov_b32_dpp v118, v124 row_ror:8 row_mask:0xf bank_mask:0xf
	v_mov_b32_e32 v123, 0
	v_mov_b32_e32 v114, 0
	v_mov_b32_e32 v126, 0
	v_mov_b32_dpp v123, v125 row_ror:8 row_mask:0xf bank_mask:0xf
	v_mov_b32_e32 v127, 0
	v_mov_b32_dpp v114, v122 row_ror:8 row_mask:0xf bank_mask:0xf
	v_mov_b32_e32 v115, 0
	v_mov_b32_e32 v116, 0
	v_mov_b32_e32 v117, 0
	v_cndmask_b32_e64 v118, v122, v118, s[6:7]
	v_or_b32_e32 v122, s19, v148
	v_lshl_or_b32 v162, s59, 8, v156
	v_mov_b32_dpp v126, v120 row_ror:8 row_mask:0xf bank_mask:0xf
	v_mov_b32_dpp v127, v121 row_ror:8 row_mask:0xf bank_mask:0xf
	v_mov_b32_dpp v115, v119 row_ror:8 row_mask:0xf bank_mask:0xf
	v_mov_b32_dpp v116, v112 row_ror:8 row_mask:0xf bank_mask:0xf
	v_mov_b32_dpp v117, v113 row_ror:8 row_mask:0xf bank_mask:0xf
	v_cndmask_b32_e64 v119, v119, v123, s[6:7]
	v_ashrrev_i32_e32 v123, 31, v122
	v_ashrrev_i32_e32 v163, 31, v162
	v_cndmask_b32_e64 v116, v116, v120, s[6:7]
	v_cndmask_b32_e64 v117, v117, v121, s[6:7]
	v_cndmask_b32_e64 v120, v112, v126, s[6:7]
	v_cndmask_b32_e64 v121, v113, v127, s[6:7]
; __device__ __forceinline__ unsigned cvt_pk_bf16(float lo, float hi) { unsigned r; asm volatile("v_cvt_pk_bf16_f32 %0, %1, %2" : "=v"(r) : "v"(lo), "v"(hi)); return r; }
;     __device__ __forceinline__ void operator()(const f32x4 (&acc)[2][2][4][2], const Unit& u, int wr, int wc, int fr, int fq) const {
;     ...
;             for (int m = 0; m < 4; ++m) { const int row = row0 + ai * HALF + m * 16;
;                 const float rs = ssin ? __builtin_amdgcn_rsqf(ssin[row] * (1.f / D) + EPS) : 1.0f; float sq = 0.f; u32x4 w[2];
; #pragma unroll
;                 for (int bj = 0; bj < 2; ++bj) { f32x4 v0 = acc[ai][bj][m][0] * rs, v1 = acc[ai][bj][m][1] * rs;
;                     if (ACT == 1) {
; #pragma unroll
;                         for (int j = 0; j < 4; ++j) { const float a = fmaxf(v0[j], 0.f), b = fmaxf(v1[j], 0.f); v0[j] = a * a; v1[j] = b * b; } }
;                     sq += (v0[0] * v0[0] + v0[1] * v0[1]) + (v0[2] * v0[2] + v0[3] * v0[3]) + (v1[0] * v1[0] + v1[1] * v1[1]) + (v1[2] * v1[2] + v1[3] * v1[3]);
;                     w[bj].x = cvt_pk_bf16(v0[0], v0[1]); w[bj].y = cvt_pk_bf16(v0[2], v0[3]); w[bj].z = cvt_pk_bf16(v1[0], v1[1]); w[bj].w = cvt_pk_bf16(v1[2], v1[3]); }
;                 store_pair_lines(O, ldc, row, fr, col0, w[0], w[1]);
	v_lshlrev_b64 v[112:113], 14, v[122:123]
	v_cndmask_b32_e64 v114, v114, v124, s[6:7]
	v_cndmask_b32_e64 v115, v115, v125, s[6:7]
	v_lshl_add_u64 v[124:125], s[12:13], 0, v[112:113]
	v_lshlrev_b64 v[112:113], 1, v[162:163]
	v_lshl_add_u64 v[124:125], v[124:125], 0, v[112:113]
	global_store_dwordx4 v[124:125], v[114:117], off
	v_max_f32_e32 v108, v108, v108
	v_max_f32_e32 v104, v104, v104
	v_or_b32_e32 v114, 8, v122
	v_ashrrev_i32_e32 v115, 31, v114
	v_lshlrev_b64 v[114:115], 14, v[114:115]
	v_max_f32_e32 v109, v109, v109
	v_max_f32_e32 v105, v105, v105
	v_max_f32_e32 v100, v100, v100
	v_max_f32_e32 v101, v101, v101
	v_max_f32_e32 v102, v102, v102
	v_max_f32_e32 v98, v98, v98
	v_max_f32_e32 v103, v103, v103
	v_lshl_add_u64 v[114:115], s[12:13], 0, v[114:115]
	v_max_f32_e32 v108, 0, v108
	v_max_f32_e32 v104, 0, v104
	v_max_f32_e32 v109, 0, v109
	v_max_f32_e32 v105, 0, v105
	v_max_f32_e32 v110, v110, v110
	v_max_f32_e32 v106, v106, v106
	v_max_f32_e32 v111, v111, v111
	v_max_f32_e32 v107, v107, v107
	v_max_f32_e32 v100, 0, v100
	v_max_f32_e32 v96, v96, v96
	v_max_f32_e32 v101, 0, v101
	v_max_f32_e32 v97, v97, v97
	v_max_f32_e32 v102, 0, v102
	v_max_f32_e32 v98, 0, v98
	v_max_f32_e32 v103, 0, v103
	v_max_f32_e32 v99, v99, v99
	v_lshl_add_u64 v[114:115], v[114:115], 0, v[112:113]
	v_mul_f32_e32 v108, v108, v108
	v_mul_f32_e32 v104, v104, v104
	v_mul_f32_e32 v109, v109, v109
	v_mul_f32_e32 v105, v105, v105
	v_max_f32_e32 v110, 0, v110
	v_max_f32_e32 v106, 0, v106
	v_max_f32_e32 v111, 0, v111
	v_max_f32_e32 v107, 0, v107
	v_max_f32_e32 v96, 0, v96
	v_mul_f32_e32 v100, v100, v100
	v_max_f32_e32 v97, 0, v97
	v_mul_f32_e32 v101, v101, v101
	v_mul_f32_e32 v102, v102, v102
	v_mul_f32_e32 v98, v98, v98
	v_max_f32_e32 v99, 0, v99
	v_mul_f32_e32 v103, v103, v103
	global_store_dwordx4 v[114:115], v[118:121], off
	v_mul_f32_e32 v110, v110, v110
	v_mul_f32_e32 v106, v106, v106
	v_mul_f32_e32 v111, v111, v111
	v_mul_f32_e32 v107, v107, v107
	v_cvt_pk_bf16_f32 v108, v108, v109
	v_cvt_pk_bf16_f32 v109, v110, v111
	v_cvt_pk_bf16_f32 v104, v104, v105
	v_cvt_pk_bf16_f32 v105, v106, v107
	v_mul_f32_e32 v96, v96, v96
	v_mul_f32_e32 v97, v97, v97
	v_mul_f32_e32 v99, v99, v99
	v_cvt_pk_bf16_f32 v100, v100, v101
	v_cvt_pk_bf16_f32 v101, v102, v103
	v_cvt_pk_bf16_f32 v102, v96, v97
	v_cvt_pk_bf16_f32 v103, v98, v99
	v_mov_b32_e32 v98, 0
	v_or_b32_e32 v160, s19, v146
	v_mov_b32_e32 v110, 0
	v_mov_b32_dpp v98, v102 row_ror:8 row_mask:0xf bank_mask:0xf
	v_mov_b32_e32 v99, 0
	v_mov_b32_dpp v110, v104 row_ror:8 row_mask:0xf bank_mask:0xf
	v_mov_b32_e32 v111, 0
	v_mov_b32_dpp v99, v103 row_ror:8 row_mask:0xf bank_mask:0xf
	v_cndmask_b32_e64 v98, v98, v104, s[6:7]
	v_add_u32_e32 v104, v149, v160
	v_mov_b32_dpp v111, v105 row_ror:8 row_mask:0xf bank_mask:0xf
	v_cndmask_b32_e64 v99, v99, v105, s[6:7]
	v_ashrrev_i32_e32 v105, 31, v104
	v_mov_b32_e32 v96, 0
	v_mov_b32_e32 v97, 0
	v_lshlrev_b64 v[104:105], 14, v[104:105]
	v_mov_b32_dpp v96, v100 row_ror:8 row_mask:0xf bank_mask:0xf
	v_mov_b32_dpp v97, v101 row_ror:8 row_mask:0xf bank_mask:0xf
	v_lshl_add_u64 v[104:105], s[12:13], 0, v[104:105]
	v_mov_b32_e32 v106, 0
	v_mov_b32_e32 v107, 0
	v_cndmask_b32_e64 v96, v96, v108, s[6:7]
	v_cndmask_b32_e64 v97, v97, v109, s[6:7]
	v_lshl_add_u64 v[104:105], v[104:105], 0, v[112:113]
	v_max_f32_e32 v92, v92, v92
	v_max_f32_e32 v88, v88, v88
	v_max_f32_e32 v93, v93, v93
	v_max_f32_e32 v89, v89, v89
	v_max_f32_e32 v84, v84, v84
	v_max_f32_e32 v85, v85, v85
	v_max_f32_e32 v86, v86, v86
	v_max_f32_e32 v82, v82, v82
	v_max_f32_e32 v87, v87, v87
	v_mov_b32_dpp v106, v108 row_ror:8 row_mask:0xf bank_mask:0xf
	v_mov_b32_dpp v107, v109 row_ror:8 row_mask:0xf bank_mask:0xf
	global_store_dwordx4 v[104:105], v[96:99], off
	v_max_f32_e32 v92, 0, v92
	v_max_f32_e32 v88, 0, v88
	v_add_co_u32_e32 v96, vcc, s58, v104
	v_max_f32_e32 v93, 0, v93
	v_max_f32_e32 v89, 0, v89
	v_max_f32_e32 v94, v94, v94
	v_max_f32_e32 v90, v90, v90
	v_max_f32_e32 v95, v95, v95
	v_max_f32_e32 v91, v91, v91
	v_max_f32_e32 v84, 0, v84
	v_max_f32_e32 v80, v80, v80
	v_max_f32_e32 v85, 0, v85
	v_max_f32_e32 v81, v81, v81
	v_max_f32_e32 v86, 0, v86
	v_max_f32_e32 v82, 0, v82
	v_max_f32_e32 v87, 0, v87
	v_max_f32_e32 v83, v83, v83
	v_cndmask_b32_e64 v100, v100, v106, s[6:7]
	v_cndmask_b32_e64 v101, v101, v107, s[6:7]
	v_cndmask_b32_e64 v102, v102, v110, s[6:7]
	v_cndmask_b32_e64 v103, v103, v111, s[6:7]
	v_addc_co_u32_e32 v97, vcc, 0, v105, vcc
	v_mul_f32_e32 v92, v92, v92
	v_mul_f32_e32 v88, v88, v88
	v_mul_f32_e32 v93, v93, v93
	v_mul_f32_e32 v89, v89, v89
	v_max_f32_e32 v94, 0, v94
	v_max_f32_e32 v90, 0, v90
	v_max_f32_e32 v95, 0, v95
	v_max_f32_e32 v91, 0, v91
	v_max_f32_e32 v80, 0, v80
	v_mul_f32_e32 v84, v84, v84
	v_max_f32_e32 v81, 0, v81
	v_mul_f32_e32 v85, v85, v85
	v_mul_f32_e32 v86, v86, v86
	v_mul_f32_e32 v82, v82, v82
	v_max_f32_e32 v83, 0, v83
	v_mul_f32_e32 v87, v87, v87
	global_store_dwordx4 v[96:97], v[100:103], off
	v_mul_f32_e32 v94, v94, v94
	v_mul_f32_e32 v90, v90, v90
	v_mul_f32_e32 v95, v95, v95
	v_mul_f32_e32 v91, v91, v91
	v_cvt_pk_bf16_f32 v92, v92, v93
	v_cvt_pk_bf16_f32 v93, v94, v95
	v_cvt_pk_bf16_f32 v88, v88, v89
	v_cvt_pk_bf16_f32 v89, v90, v91
	v_mul_f32_e32 v80, v80, v80
	v_mul_f32_e32 v81, v81, v81
	v_mul_f32_e32 v83, v83, v83
	v_cvt_pk_bf16_f32 v84, v84, v85
	v_cvt_pk_bf16_f32 v85, v86, v87
	v_cvt_pk_bf16_f32 v86, v80, v81
	v_cvt_pk_bf16_f32 v87, v82, v83
	v_mov_b32_e32 v82, 0
	v_mov_b32_e32 v94, 0
	v_mov_b32_e32 v83, 0
	v_mov_b32_dpp v82, v86 row_ror:8 row_mask:0xf bank_mask:0xf
	v_mov_b32_dpp v94, v88 row_ror:8 row_mask:0xf bank_mask:0xf
	v_mov_b32_e32 v95, 0
	v_mov_b32_dpp v83, v87 row_ror:8 row_mask:0xf bank_mask:0xf
; __device__ __forceinline__ unsigned cvt_pk_bf16(float lo, float hi) { unsigned r; asm volatile("v_cvt_pk_bf16_f32 %0, %1, %2" : "=v"(r) : "v"(lo), "v"(hi)); return r; }
;     __device__ __forceinline__ void operator()(const f32x4 (&acc)[2][2][4][2], const Unit& u, int wr, int wc, int fr, int fq) const {
;     ...
;             for (int m = 0; m < 4; ++m) { const int row = row0 + ai * HALF + m * 16;
;                 const float rs = ssin ? __builtin_amdgcn_rsqf(ssin[row] * (1.f / D) + EPS) : 1.0f; float sq = 0.f; u32x4 w[2];
; #pragma unroll
;                 for (int bj = 0; bj < 2; ++bj) { f32x4 v0 = acc[ai][bj][m][0] * rs, v1 = acc[ai][bj][m][1] * rs;
;                     if (ACT == 1) {
; #pragma unroll
;                         for (int j = 0; j < 4; ++j) { const float a = fmaxf(v0[j], 0.f), b = fmaxf(v1[j], 0.f); v0[j] = a * a; v1[j] = b * b; } }
;                     sq += (v0[0] * v0[0] + v0[1] * v0[1]) + (v0[2] * v0[2] + v0[3] * v0[3]) + (v1[0] * v1[0] + v1[1] * v1[1]) + (v1[2] * v1[2] + v1[3] * v1[3]);
;                     w[bj].x = cvt_pk_bf16(v0[0], v0[1]); w[bj].y = cvt_pk_bf16(v0[2], v0[3]); w[bj].z = cvt_pk_bf16(v1[0], v1[1]); w[bj].w = cvt_pk_bf16(v1[2], v1[3]); }
;                 store_pair_lines(O, ldc, row, fr, col0, w[0], w[1]);
	v_cndmask_b32_e64 v82, v82, v88, s[6:7]
	v_add_u32_e32 v88, v150, v160
	v_mov_b32_dpp v95, v89 row_ror:8 row_mask:0xf bank_mask:0xf
	v_cndmask_b32_e64 v83, v83, v89, s[6:7]
	v_ashrrev_i32_e32 v89, 31, v88
	v_mov_b32_e32 v80, 0
	v_mov_b32_e32 v81, 0
	v_lshlrev_b64 v[88:89], 14, v[88:89]
	v_mov_b32_dpp v80, v84 row_ror:8 row_mask:0xf bank_mask:0xf
	v_mov_b32_dpp v81, v85 row_ror:8 row_mask:0xf bank_mask:0xf
	v_lshl_add_u64 v[88:89], s[12:13], 0, v[88:89]
	v_mov_b32_e32 v90, 0
	v_mov_b32_e32 v91, 0
	v_cndmask_b32_e64 v80, v80, v92, s[6:7]
	v_cndmask_b32_e64 v81, v81, v93, s[6:7]
	v_lshl_add_u64 v[88:89], v[88:89], 0, v[112:113]
	v_max_f32_e32 v76, v76, v76
	v_max_f32_e32 v72, v72, v72
	v_max_f32_e32 v77, v77, v77
	v_max_f32_e32 v73, v73, v73
	v_max_f32_e32 v68, v68, v68
	v_max_f32_e32 v69, v69, v69
	v_max_f32_e32 v70, v70, v70
	v_max_f32_e32 v66, v66, v66
	v_max_f32_e32 v71, v71, v71
	v_mov_b32_dpp v90, v92 row_ror:8 row_mask:0xf bank_mask:0xf
	v_mov_b32_dpp v91, v93 row_ror:8 row_mask:0xf bank_mask:0xf
	global_store_dwordx4 v[88:89], v[80:83], off
	v_max_f32_e32 v76, 0, v76
	v_max_f32_e32 v72, 0, v72
	v_add_co_u32_e32 v80, vcc, s58, v88
	v_max_f32_e32 v77, 0, v77
	v_max_f32_e32 v73, 0, v73
	v_max_f32_e32 v78, v78, v78
	v_max_f32_e32 v74, v74, v74
	v_max_f32_e32 v79, v79, v79
	v_max_f32_e32 v75, v75, v75
	v_max_f32_e32 v68, 0, v68
	v_max_f32_e32 v64, v64, v64
	v_max_f32_e32 v69, 0, v69
	v_max_f32_e32 v65, v65, v65
	v_max_f32_e32 v70, 0, v70
	v_max_f32_e32 v66, 0, v66
	v_max_f32_e32 v71, 0, v71
	v_max_f32_e32 v67, v67, v67
	v_cndmask_b32_e64 v84, v84, v90, s[6:7]
	v_cndmask_b32_e64 v85, v85, v91, s[6:7]
	v_cndmask_b32_e64 v86, v86, v94, s[6:7]
	v_cndmask_b32_e64 v87, v87, v95, s[6:7]
	v_addc_co_u32_e32 v81, vcc, 0, v89, vcc
	v_mul_f32_e32 v76, v76, v76
	v_mul_f32_e32 v72, v72, v72
	v_mul_f32_e32 v77, v77, v77
	v_mul_f32_e32 v73, v73, v73
	v_max_f32_e32 v78, 0, v78
	v_max_f32_e32 v74, 0, v74
	v_max_f32_e32 v79, 0, v79
	v_max_f32_e32 v75, 0, v75
	v_max_f32_e32 v64, 0, v64
	v_mul_f32_e32 v68, v68, v68
	v_max_f32_e32 v65, 0, v65
	v_mul_f32_e32 v69, v69, v69
	v_mul_f32_e32 v70, v70, v70
	v_mul_f32_e32 v66, v66, v66
	v_max_f32_e32 v67, 0, v67
	v_mul_f32_e32 v71, v71, v71
	global_store_dwordx4 v[80:81], v[84:87], off
	v_mul_f32_e32 v78, v78, v78
	v_mul_f32_e32 v74, v74, v74
	v_mul_f32_e32 v79, v79, v79
	v_mul_f32_e32 v75, v75, v75
	v_cvt_pk_bf16_f32 v76, v76, v77
	v_cvt_pk_bf16_f32 v77, v78, v79
	v_cvt_pk_bf16_f32 v72, v72, v73
	v_cvt_pk_bf16_f32 v73, v74, v75
	v_mul_f32_e32 v64, v64, v64
	v_mul_f32_e32 v65, v65, v65
	v_mul_f32_e32 v67, v67, v67
	v_cvt_pk_bf16_f32 v68, v68, v69
	v_cvt_pk_bf16_f32 v69, v70, v71
	v_cvt_pk_bf16_f32 v70, v64, v65
	v_cvt_pk_bf16_f32 v71, v66, v67
	v_mov_b32_e32 v66, 0
	v_mov_b32_e32 v78, 0
	v_mov_b32_e32 v67, 0
	v_mov_b32_dpp v66, v70 row_ror:8 row_mask:0xf bank_mask:0xf
	v_mov_b32_dpp v78, v72 row_ror:8 row_mask:0xf bank_mask:0xf
	v_mov_b32_e32 v79, 0
	v_mov_b32_dpp v67, v71 row_ror:8 row_mask:0xf bank_mask:0xf
	v_cndmask_b32_e64 v66, v66, v72, s[6:7]
	v_add_u32_e32 v72, v151, v160
	v_mov_b32_dpp v79, v73 row_ror:8 row_mask:0xf bank_mask:0xf
	v_cndmask_b32_e64 v67, v67, v73, s[6:7]
	v_ashrrev_i32_e32 v73, 31, v72
	v_mov_b32_e32 v64, 0
	v_mov_b32_e32 v65, 0
	v_lshlrev_b64 v[72:73], 14, v[72:73]
	v_mov_b32_dpp v64, v68 row_ror:8 row_mask:0xf bank_mask:0xf
	v_mov_b32_dpp v65, v69 row_ror:8 row_mask:0xf bank_mask:0xf
	v_lshl_add_u64 v[72:73], s[12:13], 0, v[72:73]
	v_mov_b32_e32 v74, 0
	v_mov_b32_e32 v75, 0
	v_cndmask_b32_e64 v64, v64, v76, s[6:7]
	v_cndmask_b32_e64 v65, v65, v77, s[6:7]
	v_lshl_add_u64 v[72:73], v[72:73], 0, v[112:113]
	v_max_f32_e32 v60, v60, v60
	v_max_f32_e32 v56, v56, v56
	v_max_f32_e32 v61, v61, v61
	v_max_f32_e32 v57, v57, v57
	v_max_f32_e32 v52, v52, v52
	v_max_f32_e32 v53, v53, v53
	v_max_f32_e32 v54, v54, v54
	v_max_f32_e32 v50, v50, v50
	v_max_f32_e32 v55, v55, v55
	v_mov_b32_dpp v74, v76 row_ror:8 row_mask:0xf bank_mask:0xf
	v_mov_b32_dpp v75, v77 row_ror:8 row_mask:0xf bank_mask:0xf
	global_store_dwordx4 v[72:73], v[64:67], off
	v_max_f32_e32 v60, 0, v60
	v_max_f32_e32 v56, 0, v56
	v_add_co_u32_e32 v64, vcc, s58, v72
	v_max_f32_e32 v61, 0, v61
	v_max_f32_e32 v57, 0, v57
	v_max_f32_e32 v62, v62, v62
	v_max_f32_e32 v58, v58, v58
	v_max_f32_e32 v63, v63, v63
	v_max_f32_e32 v59, v59, v59
	v_max_f32_e32 v52, 0, v52
	v_max_f32_e32 v48, v48, v48
	v_max_f32_e32 v53, 0, v53
	v_max_f32_e32 v49, v49, v49
	v_max_f32_e32 v54, 0, v54
	v_max_f32_e32 v50, 0, v50
	v_max_f32_e32 v55, 0, v55
	v_max_f32_e32 v51, v51, v51
	v_cndmask_b32_e64 v68, v68, v74, s[6:7]
	v_cndmask_b32_e64 v69, v69, v75, s[6:7]
	v_cndmask_b32_e64 v70, v70, v78, s[6:7]
	v_cndmask_b32_e64 v71, v71, v79, s[6:7]
	v_addc_co_u32_e32 v65, vcc, 0, v73, vcc
	v_mul_f32_e32 v60, v60, v60
	v_mul_f32_e32 v56, v56, v56
	v_mul_f32_e32 v61, v61, v61
	v_mul_f32_e32 v57, v57, v57
	v_max_f32_e32 v62, 0, v62
	v_max_f32_e32 v58, 0, v58
	v_max_f32_e32 v63, 0, v63
	v_max_f32_e32 v59, 0, v59
	v_max_f32_e32 v48, 0, v48
	v_mul_f32_e32 v52, v52, v52
	v_max_f32_e32 v49, 0, v49
	v_mul_f32_e32 v53, v53, v53
	v_mul_f32_e32 v54, v54, v54
	v_mul_f32_e32 v50, v50, v50
	v_max_f32_e32 v51, 0, v51
	v_mul_f32_e32 v55, v55, v55
	global_store_dwordx4 v[64:65], v[68:71], off
	v_mul_f32_e32 v62, v62, v62
	v_mul_f32_e32 v58, v58, v58
	v_mul_f32_e32 v63, v63, v63
	v_mul_f32_e32 v59, v59, v59
	v_cvt_pk_bf16_f32 v60, v60, v61
	v_cvt_pk_bf16_f32 v61, v62, v63
	v_cvt_pk_bf16_f32 v56, v56, v57
	v_cvt_pk_bf16_f32 v57, v58, v59
	v_mul_f32_e32 v48, v48, v48
	v_mul_f32_e32 v49, v49, v49
	v_mul_f32_e32 v51, v51, v51
	v_cvt_pk_bf16_f32 v52, v52, v53
	v_cvt_pk_bf16_f32 v53, v54, v55
; __device__ __forceinline__ unsigned cvt_pk_bf16(float lo, float hi) { unsigned r; asm volatile("v_cvt_pk_bf16_f32 %0, %1, %2" : "=v"(r) : "v"(lo), "v"(hi)); return r; }
;     __device__ __forceinline__ void operator()(const f32x4 (&acc)[2][2][4][2], const Unit& u, int wr, int wc, int fr, int fq) const {
;     ...
;             for (int m = 0; m < 4; ++m) { const int row = row0 + ai * HALF + m * 16;
;                 const float rs = ssin ? __builtin_amdgcn_rsqf(ssin[row] * (1.f / D) + EPS) : 1.0f; float sq = 0.f; u32x4 w[2];
; #pragma unroll
;                 for (int bj = 0; bj < 2; ++bj) { f32x4 v0 = acc[ai][bj][m][0] * rs, v1 = acc[ai][bj][m][1] * rs;
;                     if (ACT == 1) {
; #pragma unroll
;                         for (int j = 0; j < 4; ++j) { const float a = fmaxf(v0[j], 0.f), b = fmaxf(v1[j], 0.f); v0[j] = a * a; v1[j] = b * b; } }
;                     sq += (v0[0] * v0[0] + v0[1] * v0[1]) + (v0[2] * v0[2] + v0[3] * v0[3]) + (v1[0] * v1[0] + v1[1] * v1[1]) + (v1[2] * v1[2] + v1[3] * v1[3]);
;                     w[bj].x = cvt_pk_bf16(v0[0], v0[1]); w[bj].y = cvt_pk_bf16(v0[2], v0[3]); w[bj].z = cvt_pk_bf16(v1[0], v1[1]); w[bj].w = cvt_pk_bf16(v1[2], v1[3]); }
;                 store_pair_lines(O, ldc, row, fr, col0, w[0], w[1]);
	v_cvt_pk_bf16_f32 v54, v48, v49
	v_cvt_pk_bf16_f32 v55, v50, v51
	v_mov_b32_e32 v50, 0
	v_mov_b32_e32 v62, 0
	v_mov_b32_e32 v51, 0
	v_mov_b32_dpp v50, v54 row_ror:8 row_mask:0xf bank_mask:0xf
	v_mov_b32_dpp v62, v56 row_ror:8 row_mask:0xf bank_mask:0xf
	v_mov_b32_e32 v63, 0
	v_mov_b32_dpp v51, v55 row_ror:8 row_mask:0xf bank_mask:0xf
	v_cndmask_b32_e64 v50, v50, v56, s[6:7]
	v_add_u32_e32 v56, v152, v160
	v_mov_b32_dpp v63, v57 row_ror:8 row_mask:0xf bank_mask:0xf
	v_cndmask_b32_e64 v51, v51, v57, s[6:7]
	v_ashrrev_i32_e32 v57, 31, v56
	v_mov_b32_e32 v48, 0
	v_mov_b32_e32 v49, 0
	v_lshlrev_b64 v[56:57], 14, v[56:57]
	v_mov_b32_dpp v48, v52 row_ror:8 row_mask:0xf bank_mask:0xf
	v_mov_b32_dpp v49, v53 row_ror:8 row_mask:0xf bank_mask:0xf
	v_lshl_add_u64 v[56:57], s[12:13], 0, v[56:57]
	v_mov_b32_e32 v58, 0
	v_mov_b32_e32 v59, 0
	v_cndmask_b32_e64 v48, v48, v60, s[6:7]
	v_cndmask_b32_e64 v49, v49, v61, s[6:7]
	v_lshl_add_u64 v[56:57], v[56:57], 0, v[112:113]
	v_max_f32_e32 v44, v44, v44
	v_max_f32_e32 v40, v40, v40
	v_max_f32_e32 v45, v45, v45
	v_max_f32_e32 v41, v41, v41
	v_max_f32_e32 v36, v36, v36
	v_max_f32_e32 v37, v37, v37
	v_max_f32_e32 v38, v38, v38
	v_max_f32_e32 v34, v34, v34
	v_max_f32_e32 v39, v39, v39
	v_mov_b32_dpp v58, v60 row_ror:8 row_mask:0xf bank_mask:0xf
	v_mov_b32_dpp v59, v61 row_ror:8 row_mask:0xf bank_mask:0xf
	global_store_dwordx4 v[56:57], v[48:51], off
	v_max_f32_e32 v44, 0, v44
	v_max_f32_e32 v40, 0, v40
	v_add_co_u32_e32 v48, vcc, s58, v56
	v_max_f32_e32 v45, 0, v45
	v_max_f32_e32 v41, 0, v41
	v_max_f32_e32 v46, v46, v46
	v_max_f32_e32 v42, v42, v42
	v_max_f32_e32 v47, v47, v47
	v_max_f32_e32 v43, v43, v43
	v_max_f32_e32 v36, 0, v36
	v_max_f32_e32 v32, v32, v32
	v_max_f32_e32 v37, 0, v37
	v_max_f32_e32 v33, v33, v33
	v_max_f32_e32 v38, 0, v38
	v_max_f32_e32 v34, 0, v34
	v_max_f32_e32 v39, 0, v39
	v_max_f32_e32 v35, v35, v35
	v_cndmask_b32_e64 v52, v52, v58, s[6:7]
	v_cndmask_b32_e64 v53, v53, v59, s[6:7]
	v_cndmask_b32_e64 v54, v54, v62, s[6:7]
	v_cndmask_b32_e64 v55, v55, v63, s[6:7]
	v_addc_co_u32_e32 v49, vcc, 0, v57, vcc
	v_mul_f32_e32 v44, v44, v44
	v_mul_f32_e32 v40, v40, v40
	v_mul_f32_e32 v45, v45, v45
	v_mul_f32_e32 v41, v41, v41
	v_max_f32_e32 v46, 0, v46
	v_max_f32_e32 v42, 0, v42
	v_max_f32_e32 v47, 0, v47
	v_max_f32_e32 v43, 0, v43
	v_max_f32_e32 v32, 0, v32
	v_mul_f32_e32 v36, v36, v36
	v_max_f32_e32 v33, 0, v33
	v_mul_f32_e32 v37, v37, v37
	v_mul_f32_e32 v38, v38, v38
	v_mul_f32_e32 v34, v34, v34
	v_max_f32_e32 v35, 0, v35
	v_mul_f32_e32 v39, v39, v39
	global_store_dwordx4 v[48:49], v[52:55], off
	v_mul_f32_e32 v46, v46, v46
	v_mul_f32_e32 v42, v42, v42
	v_mul_f32_e32 v47, v47, v47
	v_mul_f32_e32 v43, v43, v43
	v_cvt_pk_bf16_f32 v44, v44, v45
	v_cvt_pk_bf16_f32 v45, v46, v47
	v_cvt_pk_bf16_f32 v40, v40, v41
	v_cvt_pk_bf16_f32 v41, v42, v43
	v_mul_f32_e32 v32, v32, v32
	v_mul_f32_e32 v33, v33, v33
	v_mul_f32_e32 v35, v35, v35
	v_cvt_pk_bf16_f32 v36, v36, v37
	v_cvt_pk_bf16_f32 v37, v38, v39
	v_cvt_pk_bf16_f32 v38, v32, v33
	v_cvt_pk_bf16_f32 v39, v34, v35
	v_mov_b32_e32 v34, 0
	v_mov_b32_e32 v46, 0
	v_mov_b32_e32 v35, 0
	v_mov_b32_dpp v34, v38 row_ror:8 row_mask:0xf bank_mask:0xf
	v_mov_b32_dpp v46, v40 row_ror:8 row_mask:0xf bank_mask:0xf
	v_mov_b32_e32 v47, 0
	v_mov_b32_dpp v35, v39 row_ror:8 row_mask:0xf bank_mask:0xf
	v_cndmask_b32_e64 v34, v34, v40, s[6:7]
	v_add_u32_e32 v40, v153, v160
	v_mov_b32_dpp v47, v41 row_ror:8 row_mask:0xf bank_mask:0xf
	v_cndmask_b32_e64 v35, v35, v41, s[6:7]
	v_ashrrev_i32_e32 v41, 31, v40
	v_mov_b32_e32 v32, 0
	v_mov_b32_e32 v33, 0
	v_lshlrev_b64 v[40:41], 14, v[40:41]
	v_mov_b32_dpp v32, v36 row_ror:8 row_mask:0xf bank_mask:0xf
	v_mov_b32_dpp v33, v37 row_ror:8 row_mask:0xf bank_mask:0xf
	v_lshl_add_u64 v[40:41], s[12:13], 0, v[40:41]
	v_mov_b32_e32 v42, 0
	v_mov_b32_e32 v43, 0
	v_cndmask_b32_e64 v32, v32, v44, s[6:7]
	v_cndmask_b32_e64 v33, v33, v45, s[6:7]
	v_lshl_add_u64 v[40:41], v[40:41], 0, v[112:113]
	v_max_f32_e32 v28, v28, v28
	v_max_f32_e32 v24, v24, v24
	v_max_f32_e32 v29, v29, v29
	v_max_f32_e32 v25, v25, v25
	v_max_f32_e32 v20, v20, v20
	v_max_f32_e32 v21, v21, v21
	v_max_f32_e32 v22, v22, v22
	v_max_f32_e32 v18, v18, v18
	v_max_f32_e32 v23, v23, v23
	v_mov_b32_dpp v42, v44 row_ror:8 row_mask:0xf bank_mask:0xf
	v_mov_b32_dpp v43, v45 row_ror:8 row_mask:0xf bank_mask:0xf
	global_store_dwordx4 v[40:41], v[32:35], off
	v_max_f32_e32 v28, 0, v28
	v_max_f32_e32 v24, 0, v24
	v_add_co_u32_e32 v32, vcc, s58, v40
	v_max_f32_e32 v29, 0, v29
	v_max_f32_e32 v25, 0, v25
	v_max_f32_e32 v30, v30, v30
	v_max_f32_e32 v26, v26, v26
	v_max_f32_e32 v31, v31, v31
	v_max_f32_e32 v27, v27, v27
	v_max_f32_e32 v20, 0, v20
	v_max_f32_e32 v16, v16, v16
	v_max_f32_e32 v21, 0, v21
	v_max_f32_e32 v17, v17, v17
	v_max_f32_e32 v22, 0, v22
	v_max_f32_e32 v18, 0, v18
	v_max_f32_e32 v23, 0, v23
	v_max_f32_e32 v19, v19, v19
	v_cndmask_b32_e64 v36, v36, v42, s[6:7]
	v_cndmask_b32_e64 v37, v37, v43, s[6:7]
	v_cndmask_b32_e64 v38, v38, v46, s[6:7]
	v_cndmask_b32_e64 v39, v39, v47, s[6:7]
	v_addc_co_u32_e32 v33, vcc, 0, v41, vcc
	v_mul_f32_e32 v28, v28, v28
	v_mul_f32_e32 v24, v24, v24
	v_mul_f32_e32 v29, v29, v29
	v_mul_f32_e32 v25, v25, v25
	v_max_f32_e32 v30, 0, v30
	v_max_f32_e32 v26, 0, v26
; __device__ __forceinline__ unsigned cvt_pk_bf16(float lo, float hi) { unsigned r; asm volatile("v_cvt_pk_bf16_f32 %0, %1, %2" : "=v"(r) : "v"(lo), "v"(hi)); return r; }
; #define PG8_WAIT_V(n) asm volatile("s_waitcnt vmcnt(" #n ")" ::: "memory")
; #define PG8_BAR __builtin_amdgcn_s_barrier()
;     __device__ __forceinline__ void operator()(const f32x4 (&acc)[2][2][4][2], const Unit& u, int wr, int wc, int fr, int fq) const {
;     ...
;             for (int m = 0; m < 4; ++m) { const int row = row0 + ai * HALF + m * 16;
;                 const float rs = ssin ? __builtin_amdgcn_rsqf(ssin[row] * (1.f / D) + EPS) : 1.0f; float sq = 0.f; u32x4 w[2];
; #pragma unroll
;                 for (int bj = 0; bj < 2; ++bj) { f32x4 v0 = acc[ai][bj][m][0] * rs, v1 = acc[ai][bj][m][1] * rs;
;                     if (ACT == 1) {
; #pragma unroll
;                         for (int j = 0; j < 4; ++j) { const float a = fmaxf(v0[j], 0.f), b = fmaxf(v1[j], 0.f); v0[j] = a * a; v1[j] = b * b; } }
;                     sq += (v0[0] * v0[0] + v0[1] * v0[1]) + (v0[2] * v0[2] + v0[3] * v0[3]) + (v1[0] * v1[0] + v1[1] * v1[1]) + (v1[2] * v1[2] + v1[3] * v1[3]);
;                     w[bj].x = cvt_pk_bf16(v0[0], v0[1]); w[bj].y = cvt_pk_bf16(v0[2], v0[3]); w[bj].z = cvt_pk_bf16(v1[0], v1[1]); w[bj].w = cvt_pk_bf16(v1[2], v1[3]); }
;                 store_pair_lines(O, ldc, row, fr, col0, w[0], w[1]);
; template <class Epi>
; __device__ __forceinline__ void gemm_phase(LAS unsigned char* lds, const Gemm g, const StaticOrder& S, const Epi& E) {
;     ...
;         E(acc, cur, wr, wc, fr, fq);
;         if (!has_next) break;
; #pragma unroll
;         for (int a = 0; a < 2; ++a)
; #pragma unroll
;             for (int b = 0; b < 2; ++b)
; #pragma unroll
;                 for (int m = 0; m < 4; ++m)
; #pragma unroll
;                     for (int n = 0; n < 2; ++n) acc[a][b][m][n] = (f32x4){0.f, 0.f, 0.f, 0.f};
;         cur = nxt; cA = nA; cB = nB; ++ui;
;     }
;     PG8_WAIT_V(0);
;     if (wr == 0) PG8_BAR;
;     PG8_BAR;
	v_max_f32_e32 v31, 0, v31
	v_max_f32_e32 v27, 0, v27
	v_max_f32_e32 v16, 0, v16
	v_mul_f32_e32 v20, v20, v20
	v_max_f32_e32 v17, 0, v17
	v_mul_f32_e32 v21, v21, v21
	v_mul_f32_e32 v22, v22, v22
	v_mul_f32_e32 v18, v18, v18
	v_max_f32_e32 v19, 0, v19
	v_mul_f32_e32 v23, v23, v23
	global_store_dwordx4 v[32:33], v[36:39], off
	v_mul_f32_e32 v30, v30, v30
	v_mul_f32_e32 v26, v26, v26
	v_mul_f32_e32 v31, v31, v31
	v_mul_f32_e32 v27, v27, v27
	v_cvt_pk_bf16_f32 v28, v28, v29
	v_cvt_pk_bf16_f32 v29, v30, v31
	v_cvt_pk_bf16_f32 v24, v24, v25
	v_cvt_pk_bf16_f32 v25, v26, v27
	v_mul_f32_e32 v16, v16, v16
	v_mul_f32_e32 v17, v17, v17
	v_mul_f32_e32 v19, v19, v19
	v_cvt_pk_bf16_f32 v20, v20, v21
	v_cvt_pk_bf16_f32 v21, v22, v23
	v_cvt_pk_bf16_f32 v22, v16, v17
	v_cvt_pk_bf16_f32 v23, v18, v19
	v_mov_b32_e32 v18, 0
	v_mov_b32_e32 v30, 0
	v_mov_b32_e32 v19, 0
	v_mov_b32_dpp v18, v22 row_ror:8 row_mask:0xf bank_mask:0xf
	v_mov_b32_dpp v30, v24 row_ror:8 row_mask:0xf bank_mask:0xf
	v_mov_b32_e32 v31, 0
	v_mov_b32_dpp v19, v23 row_ror:8 row_mask:0xf bank_mask:0xf
	v_cndmask_b32_e64 v18, v18, v24, s[6:7]
	v_add_u32_e32 v24, v154, v160
	v_mov_b32_dpp v31, v25 row_ror:8 row_mask:0xf bank_mask:0xf
	v_cndmask_b32_e64 v19, v19, v25, s[6:7]
	v_ashrrev_i32_e32 v25, 31, v24
	v_mov_b32_e32 v16, 0
	v_mov_b32_e32 v17, 0
	v_lshlrev_b64 v[24:25], 14, v[24:25]
	v_mov_b32_dpp v16, v20 row_ror:8 row_mask:0xf bank_mask:0xf
	v_mov_b32_dpp v17, v21 row_ror:8 row_mask:0xf bank_mask:0xf
	v_lshl_add_u64 v[24:25], s[12:13], 0, v[24:25]
	v_mov_b32_e32 v26, 0
	v_mov_b32_e32 v27, 0
	v_cndmask_b32_e64 v16, v16, v28, s[6:7]
	v_cndmask_b32_e64 v17, v17, v29, s[6:7]
	v_lshl_add_u64 v[24:25], v[24:25], 0, v[112:113]
	v_max_f32_e32 v12, v12, v12
	v_max_f32_e32 v8, v8, v8
	v_max_f32_e32 v13, v13, v13
	v_max_f32_e32 v9, v9, v9
	v_max_f32_e32 v4, v4, v4
	v_max_f32_e32 v5, v5, v5
	v_max_f32_e32 v6, v6, v6
	v_max_f32_e32 v2, v2, v2
	v_max_f32_e32 v7, v7, v7
	v_mov_b32_dpp v26, v28 row_ror:8 row_mask:0xf bank_mask:0xf
	v_mov_b32_dpp v27, v29 row_ror:8 row_mask:0xf bank_mask:0xf
	global_store_dwordx4 v[24:25], v[16:19], off
	v_max_f32_e32 v12, 0, v12
	v_max_f32_e32 v8, 0, v8
	v_add_co_u32_e32 v16, vcc, s58, v24
	v_max_f32_e32 v13, 0, v13
	v_max_f32_e32 v9, 0, v9
	v_max_f32_e32 v14, v14, v14
	v_max_f32_e32 v10, v10, v10
	v_max_f32_e32 v15, v15, v15
	v_max_f32_e32 v11, v11, v11
	v_max_f32_e32 v4, 0, v4
	v_max_f32_e32 v0, v0, v0
	v_max_f32_e32 v5, 0, v5
	v_max_f32_e32 v1, v1, v1
	v_max_f32_e32 v6, 0, v6
	v_max_f32_e32 v2, 0, v2
	v_max_f32_e32 v7, 0, v7
	v_max_f32_e32 v3, v3, v3
	v_cndmask_b32_e64 v20, v20, v26, s[6:7]
	v_cndmask_b32_e64 v21, v21, v27, s[6:7]
	v_cndmask_b32_e64 v22, v22, v30, s[6:7]
	v_cndmask_b32_e64 v23, v23, v31, s[6:7]
	v_addc_co_u32_e32 v17, vcc, 0, v25, vcc
	v_mul_f32_e32 v12, v12, v12
	v_mul_f32_e32 v8, v8, v8
	v_mul_f32_e32 v13, v13, v13
	v_mul_f32_e32 v9, v9, v9
	v_max_f32_e32 v14, 0, v14
	v_max_f32_e32 v10, 0, v10
	v_max_f32_e32 v15, 0, v15
	v_max_f32_e32 v11, 0, v11
	v_max_f32_e32 v0, 0, v0
	v_mul_f32_e32 v4, v4, v4
	v_max_f32_e32 v1, 0, v1
	v_mul_f32_e32 v5, v5, v5
	v_mul_f32_e32 v6, v6, v6
	v_mul_f32_e32 v2, v2, v2
	v_max_f32_e32 v3, 0, v3
	v_mul_f32_e32 v7, v7, v7
	global_store_dwordx4 v[16:17], v[20:23], off
	v_mul_f32_e32 v14, v14, v14
	v_mul_f32_e32 v10, v10, v10
	v_mul_f32_e32 v15, v15, v15
	v_mul_f32_e32 v11, v11, v11
	v_cvt_pk_bf16_f32 v12, v12, v13
	v_cvt_pk_bf16_f32 v13, v14, v15
	v_cvt_pk_bf16_f32 v8, v8, v9
	v_cvt_pk_bf16_f32 v9, v10, v11
	v_mul_f32_e32 v0, v0, v0
	v_mul_f32_e32 v1, v1, v1
	v_mul_f32_e32 v3, v3, v3
	v_cvt_pk_bf16_f32 v4, v4, v5
	v_cvt_pk_bf16_f32 v5, v6, v7
	v_cvt_pk_bf16_f32 v6, v0, v1
	v_cvt_pk_bf16_f32 v7, v2, v3
	v_mov_b32_e32 v2, 0
	v_mov_b32_e32 v14, 0
	v_mov_b32_e32 v3, 0
	v_mov_b32_dpp v2, v6 row_ror:8 row_mask:0xf bank_mask:0xf
	v_mov_b32_dpp v14, v8 row_ror:8 row_mask:0xf bank_mask:0xf
	v_mov_b32_e32 v15, 0
	v_mov_b32_dpp v3, v7 row_ror:8 row_mask:0xf bank_mask:0xf
	v_cndmask_b32_e64 v2, v2, v8, s[6:7]
	v_add_u32_e32 v8, v155, v160
	v_mov_b32_dpp v15, v9 row_ror:8 row_mask:0xf bank_mask:0xf
	v_cndmask_b32_e64 v3, v3, v9, s[6:7]
	v_ashrrev_i32_e32 v9, 31, v8
	v_mov_b32_e32 v0, 0
	v_mov_b32_e32 v1, 0
	v_lshlrev_b64 v[8:9], 14, v[8:9]
	v_mov_b32_dpp v0, v4 row_ror:8 row_mask:0xf bank_mask:0xf
	v_mov_b32_dpp v1, v5 row_ror:8 row_mask:0xf bank_mask:0xf
	v_lshl_add_u64 v[8:9], s[12:13], 0, v[8:9]
	v_cndmask_b32_e64 v0, v0, v12, s[6:7]
	v_cndmask_b32_e64 v1, v1, v13, s[6:7]
	v_lshl_add_u64 v[8:9], v[8:9], 0, v[112:113]
	v_mov_b32_e32 v10, 0
	v_mov_b32_e32 v11, 0
	global_store_dwordx4 v[8:9], v[0:3], off
	v_mov_b32_dpp v10, v12 row_ror:8 row_mask:0xf bank_mask:0xf
	v_mov_b32_dpp v11, v13 row_ror:8 row_mask:0xf bank_mask:0xf
	v_add_co_u32_e32 v0, vcc, 0x20000, v8
	v_cndmask_b32_e64 v4, v4, v10, s[6:7]
	s_nop 0
	v_addc_co_u32_e32 v1, vcc, 0, v9, vcc
	v_cndmask_b32_e64 v5, v5, v11, s[6:7]
	v_cndmask_b32_e64 v6, v6, v14, s[6:7]
	v_cndmask_b32_e64 v7, v7, v15, s[6:7]
	s_and_b64 vcc, exec, s[30:31]
	s_mov_b32 s59, s18
	s_mov_b32 s36, s26
	s_mov_b64 s[40:41], s[34:35]
	s_mov_b64 s[38:39], s[28:29]
	global_store_dwordx4 v[0:1], v[4:7], off
	s_cbranch_vccz .LBB0_1357
	s_waitcnt vmcnt(0)
	s_cmpk_gt_u32 s44, 0xff
	s_cbranch_scc1 .LBB0_1369
	s_barrier

; #define PG8_STAGE(bufoff, gbase, voff) do { _Pragma("unroll") for (int _i = 0; _i < 2; ++_i) \
;         __builtin_amdgcn_global_load_lds((const unsigned*)((const char*)(gbase) + (voff)[_i]), (LAS unsigned*)(lds + (bufoff) + ldsw + _i * 8192), 16, 0, 0); } while (0)
; #define PG8_LDA(dst, b, h) do { _Pragma("unroll") for (int m = 0; m < 4; ++m) _Pragma("unroll") for (int k = 0; k < 2; ++k) dst[m][k] = *(const LAS bf16x8*)(lds + PG8_SA(b, h) + aoff + m * 2048 + k * 1024); } while (0)
; #define PG8_LDB(dst, b, h) do { _Pragma("unroll") for (int n = 0; n < 2; ++n) _Pragma("unroll") for (int k = 0; k < 2; ++k) dst[n][k] = *(const LAS bf16x8*)(lds + PG8_SB(b, h) + boff + n * 2048 + k * 1024); } while (0)
; #define PG8_MMA(ai, bj, At, Bt) do { __builtin_amdgcn_s_setprio(1); _Pragma("unroll") for (int m = 0; m < 4; ++m) _Pragma("unroll") for (int n = 0; n < 2; ++n) _Pragma("unroll") for (int k = 0; k < 2; ++k) \
;         acc[ai][bj][m][n] = __builtin_amdgcn_mfma_f32_16x16x32_bf16(Bt[n][k], At[m][k], acc[ai][bj][m][n], 0, 0, 0); __builtin_amdgcn_s_setprio(0); } while (0)
; #define PG8_WAIT_V(n) asm volatile("s_waitcnt vmcnt(" #n ")" ::: "memory")
; #define PG8_WAIT_L(n) asm volatile("s_waitcnt lgkmcnt(" #n ")" ::: "memory")
; #define PG8_BAR __builtin_amdgcn_s_barrier()
; template <class Epi>
; __device__ __forceinline__ void gemm_phase(LAS unsigned char* lds, const Gemm g, const StaticOrder& S, const Epi& E) {
;     ...
;         for (int t = 0; t < nt; t += 2) {
;             const bool last = (t == nt - 2);
;             const char* a1 = cA + (size_t)(t + 1) * kstep;
;             const char* a2 = last ? nA : cA + (size_t)(t + 2) * kstep; const char* b2 = last ? nB : cB + (size_t)(t + 2) * kstep;
;             const char* a3 = a2 + kstep; const char* b3 = b2 + kstep;
;             PG8_LDB(B0, 0, 0); PG8_SCHED; PG8_LDA(At, 0, 0); PG8_STAGE(PG8_SA(1, 1), a1 + hstep, voffA);
;             PG8_WAIT_L(8); PG8_BAR; PG8_WAIT_L(0); PG8_MMA(0, 0, At, B0); PG8_BAR; PG8_SCHED;
;             PG8_LDB(B1, 0, 1); PG8_STAGE(PG8_SB(0, 0), b2, voffB0);
;             PG8_BAR; PG8_WAIT_L(0); PG8_MMA(0, 1, At, B1); PG8_BAR;
;             PG8_LDA(At, 0, 1); PG8_STAGE(PG8_SA(0, 0), a2, voffA);
;             PG8_BAR; PG8_WAIT_L(0); PG8_MMA(1, 0, At, B0); PG8_BAR; PG8_SCHED;
;             PG8_STAGE(PG8_SB(0, 1), b2, voffB1);
;             PG8_WAIT_V(6); PG8_BAR; PG8_MMA(1, 1, At, B1); PG8_BAR;
.LBB0_1443:
	ds_read_b128 v[128:131], v179
	ds_read_b128 v[132:135], v179 offset:1024
	ds_read_b128 v[154:157], v179 offset:2048
	ds_read_b128 v[158:161], v179 offset:3072
	s_add_u32 s33, s42, 0xffe00080
	s_addc_u32 s44, s43, -1
	s_cmpk_eq_i32 s74, 0x7c
	s_cselect_b32 s45, s9, s44
	s_cselect_b32 s44, s11, s33
	s_cselect_b32 s47, s31, s73
	s_cselect_b32 s46, s35, s72
	v_lshl_add_u64 v[200:201], s[42:43], 0, v[148:149]
	s_add_i32 m0, s54, 0xc000
	ds_read_b128 v[162:165], v180
	ds_read_b128 v[166:169], v180 offset:1024
	ds_read_b128 v[170:173], v180 offset:2048
	ds_read_b128 v[184:187], v180 offset:3072
	ds_read_b128 v[188:191], v180 offset:4096
	ds_read_b128 v[192:195], v180 offset:5120
	ds_read_b128 v[196:199], v180 offset:6144
	ds_read_b128 v[204:207], v180 offset:7168
	global_load_lds_dwordx4 v[200:201], off
	v_lshl_add_u64 v[200:201], s[42:43], 0, v[150:151]
	s_add_i32 m0, s54, 0xe000
	s_nop 0
	global_load_lds_dwordx4 v[200:201], off
	s_waitcnt lgkmcnt(8)
	s_barrier
	s_waitcnt lgkmcnt(0)
	s_waitcnt lgkmcnt(0)
	v_mfma_f32_16x16x32_bf16 v[124:127], v[128:131], v[162:165], v[124:127]
	v_mfma_f32_16x16x32_bf16 v[120:123], v[154:157], v[162:165], v[120:123]
	v_mfma_f32_16x16x32_bf16 v[108:111], v[128:131], v[170:173], v[108:111]
	v_mfma_f32_16x16x32_bf16 v[104:107], v[154:157], v[170:173], v[104:107]
	v_mfma_f32_16x16x32_bf16 v[92:95], v[128:131], v[188:191], v[92:95]
	v_mfma_f32_16x16x32_bf16 v[88:91], v[154:157], v[188:191], v[88:91]
	v_mfma_f32_16x16x32_bf16 v[76:79], v[128:131], v[196:199], v[76:79]
	v_mfma_f32_16x16x32_bf16 v[72:75], v[154:157], v[196:199], v[72:75]
	v_mfma_f32_16x16x32_bf16 v[124:127], v[132:135], v[166:169], v[124:127]
	v_mfma_f32_16x16x32_bf16 v[120:123], v[158:161], v[166:169], v[120:123]
	v_mfma_f32_16x16x32_bf16 v[108:111], v[132:135], v[184:187], v[108:111]
	v_mfma_f32_16x16x32_bf16 v[104:107], v[158:161], v[184:187], v[104:107]
	v_mfma_f32_16x16x32_bf16 v[92:95], v[132:135], v[192:195], v[92:95]
	v_mfma_f32_16x16x32_bf16 v[88:91], v[158:161], v[192:195], v[88:91]
	v_mfma_f32_16x16x32_bf16 v[76:79], v[132:135], v[204:207], v[76:79]
	v_mfma_f32_16x16x32_bf16 v[72:75], v[158:161], v[204:207], v[72:75]
	s_barrier
	s_add_i32 s33, s66, s53
	v_lshl_add_u64 v[200:201], s[46:47], 0, v[138:139]
	s_mov_b32 m0, s33
	ds_read_b128 v[208:211], v181
	ds_read_b128 v[212:215], v181 offset:1024
	ds_read_b128 v[216:219], v181 offset:2048
	ds_read_b128 v[220:223], v181 offset:3072
	global_load_lds_dwordx4 v[200:201], off
	v_lshl_add_u64 v[224:225], s[46:47], 0, v[144:145]
	s_add_i32 m0, s33, 0x2000
	s_nop 0
	global_load_lds_dwordx4 v[224:225], off
	s_barrier
	s_waitcnt lgkmcnt(0)
	s_waitcnt lgkmcnt(0)
	v_mfma_f32_16x16x32_bf16 v[116:119], v[208:211], v[162:165], v[116:119]
	v_mfma_f32_16x16x32_bf16 v[112:115], v[216:219], v[162:165], v[112:115]
	v_mfma_f32_16x16x32_bf16 v[100:103], v[208:211], v[170:173], v[100:103]
	v_mfma_f32_16x16x32_bf16 v[96:99], v[216:219], v[170:173], v[96:99]
	v_mfma_f32_16x16x32_bf16 v[84:87], v[208:211], v[188:191], v[84:87]
	v_mfma_f32_16x16x32_bf16 v[80:83], v[216:219], v[188:191], v[80:83]
	v_mfma_f32_16x16x32_bf16 v[68:71], v[208:211], v[196:199], v[68:71]
	v_mfma_f32_16x16x32_bf16 v[64:67], v[216:219], v[196:199], v[64:67]
	v_mfma_f32_16x16x32_bf16 v[116:119], v[212:215], v[166:169], v[116:119]
	v_mfma_f32_16x16x32_bf16 v[112:115], v[220:223], v[166:169], v[112:115]
	v_mfma_f32_16x16x32_bf16 v[100:103], v[212:215], v[184:187], v[100:103]
	v_mfma_f32_16x16x32_bf16 v[96:99], v[220:223], v[184:187], v[96:99]
	v_mfma_f32_16x16x32_bf16 v[84:87], v[212:215], v[192:195], v[84:87]
	v_mfma_f32_16x16x32_bf16 v[80:83], v[220:223], v[192:195], v[80:83]
	v_mfma_f32_16x16x32_bf16 v[68:71], v[212:215], v[204:207], v[68:71]
	v_mfma_f32_16x16x32_bf16 v[64:67], v[220:223], v[204:207], v[64:67]
	s_mov_b32 m0, s54
	v_lshl_add_u64 v[226:227], s[44:45], 0, v[136:137]
	s_barrier
	ds_read_b128 v[162:165], v180 offset:16384
	ds_read_b128 v[166:169], v180 offset:17408
	ds_read_b128 v[170:173], v180 offset:18432
	ds_read_b128 v[184:187], v180 offset:19456
	ds_read_b128 v[188:191], v180 offset:20480
	ds_read_b128 v[192:195], v180 offset:21504
	ds_read_b128 v[196:199], v180 offset:22528
	ds_read_b128 v[204:207], v180 offset:23552
	global_load_lds_dwordx4 v[226:227], off
	v_lshl_add_u64 v[228:229], s[44:45], 0, v[142:143]
	s_mov_b32 m0, s55
	s_nop 0
	global_load_lds_dwordx4 v[228:229], off
	s_barrier
	s_waitcnt lgkmcnt(0)
	s_waitcnt lgkmcnt(0)
	v_mfma_f32_16x16x32_bf16 v[60:63], v[128:131], v[162:165], v[60:63]
	v_mfma_f32_16x16x32_bf16 v[56:59], v[154:157], v[162:165], v[56:59]
	v_mfma_f32_16x16x32_bf16 v[44:47], v[128:131], v[170:173], v[44:47]
	v_mfma_f32_16x16x32_bf16 v[40:43], v[154:157], v[170:173], v[40:43]
	v_mfma_f32_16x16x32_bf16 v[28:31], v[128:131], v[188:191], v[28:31]
	v_mfma_f32_16x16x32_bf16 v[24:27], v[154:157], v[188:191], v[24:27]
	v_mfma_f32_16x16x32_bf16 v[12:15], v[128:131], v[196:199], v[12:15]
	v_mfma_f32_16x16x32_bf16 v[8:11], v[154:157], v[196:199], v[8:11]
	v_mfma_f32_16x16x32_bf16 v[60:63], v[132:135], v[166:169], v[60:63]
	v_mfma_f32_16x16x32_bf16 v[56:59], v[158:161], v[166:169], v[56:59]
	v_mfma_f32_16x16x32_bf16 v[44:47], v[132:135], v[184:187], v[44:47]
	v_mfma_f32_16x16x32_bf16 v[40:43], v[158:161], v[184:187], v[40:43]
	v_mfma_f32_16x16x32_bf16 v[28:31], v[132:135], v[192:195], v[28:31]
	v_mfma_f32_16x16x32_bf16 v[24:27], v[158:161], v[192:195], v[24:27]
	v_mfma_f32_16x16x32_bf16 v[12:15], v[132:135], v[204:207], v[12:15]
	v_mfma_f32_16x16x32_bf16 v[8:11], v[158:161], v[204:207], v[8:11]
	s_barrier
; #define PG8_STAGE(bufoff, gbase, voff) do { _Pragma("unroll") for (int _i = 0; _i < 2; ++_i) \
;         __builtin_amdgcn_global_load_lds((const unsigned*)((const char*)(gbase) + (voff)[_i]), (LAS unsigned*)(lds + (bufoff) + ldsw + _i * 8192), 16, 0, 0); } while (0)
; #define PG8_LDA(dst, b, h) do { _Pragma("unroll") for (int m = 0; m < 4; ++m) _Pragma("unroll") for (int k = 0; k < 2; ++k) dst[m][k] = *(const LAS bf16x8*)(lds + PG8_SA(b, h) + aoff + m * 2048 + k * 1024); } while (0)
; #define PG8_LDB(dst, b, h) do { _Pragma("unroll") for (int n = 0; n < 2; ++n) _Pragma("unroll") for (int k = 0; k < 2; ++k) dst[n][k] = *(const LAS bf16x8*)(lds + PG8_SB(b, h) + boff + n * 2048 + k * 1024); } while (0)
; #define PG8_MMA(ai, bj, At, Bt) do { __builtin_amdgcn_s_setprio(1); _Pragma("unroll") for (int m = 0; m < 4; ++m) _Pragma("unroll") for (int n = 0; n < 2; ++n) _Pragma("unroll") for (int k = 0; k < 2; ++k) \
;         acc[ai][bj][m][n] = __builtin_amdgcn_mfma_f32_16x16x32_bf16(Bt[n][k], At[m][k], acc[ai][bj][m][n], 0, 0, 0); __builtin_amdgcn_s_setprio(0); } while (0)
; #define PG8_WAIT_V(n) asm volatile("s_waitcnt vmcnt(" #n ")" ::: "memory")
; #define PG8_WAIT_L(n) asm volatile("s_waitcnt lgkmcnt(" #n ")" ::: "memory")
; #define PG8_BAR __builtin_amdgcn_s_barrier()
; #define PG8_SCHED __builtin_amdgcn_sched_barrier(0)
; template <class Epi>
; __device__ __forceinline__ void gemm_phase(LAS unsigned char* lds, const Gemm g, const StaticOrder& S, const Epi& E) {
;     ...
;             PG8_STAGE(PG8_SB(0, 1), b2, voffB1);
;             PG8_WAIT_V(6); PG8_BAR; PG8_MMA(1, 1, At, B1); PG8_BAR;
;             PG8_LDB(B0, 1, 0); PG8_SCHED; PG8_LDA(At, 1, 0); PG8_STAGE(PG8_SA(0, 1), a2 + hstep, voffA);
;             PG8_WAIT_L(8); PG8_BAR; PG8_WAIT_L(0); PG8_MMA(0, 0, At, B0); PG8_BAR; PG8_SCHED;
;             PG8_LDB(B1, 1, 1); PG8_STAGE(PG8_SB(1, 0), b3, voffB0);
;             PG8_BAR; PG8_WAIT_L(0); PG8_MMA(0, 1, At, B1); PG8_BAR;
;             PG8_LDA(At, 1, 1); PG8_STAGE(PG8_SA(1, 0), a3, voffA);
;             PG8_BAR; PG8_WAIT_L(0); PG8_MMA(1, 0, At, B0); PG8_BAR; PG8_SCHED;
	s_add_i32 s33, s67, s53
	v_lshl_add_u64 v[230:231], s[46:47], 0, v[140:141]
	s_mov_b32 m0, s33
	v_lshl_add_u64 v[232:233], s[46:47], 0, v[146:147]
	global_load_lds_dwordx4 v[230:231], off
	s_add_i32 m0, s33, 0x2000
	s_nop 0
	global_load_lds_dwordx4 v[232:233], off
	s_waitcnt vmcnt(6)
	s_barrier
	v_mfma_f32_16x16x32_bf16 v[52:55], v[208:211], v[162:165], v[52:55]
	v_mfma_f32_16x16x32_bf16 v[48:51], v[216:219], v[162:165], v[48:51]
	v_mfma_f32_16x16x32_bf16 v[36:39], v[208:211], v[170:173], v[36:39]
	v_mfma_f32_16x16x32_bf16 v[32:35], v[216:219], v[170:173], v[32:35]
	v_mfma_f32_16x16x32_bf16 v[20:23], v[208:211], v[188:191], v[20:23]
	v_mfma_f32_16x16x32_bf16 v[16:19], v[216:219], v[188:191], v[16:19]
	v_mfma_f32_16x16x32_bf16 v[4:7], v[208:211], v[196:199], v[4:7]
	v_mfma_f32_16x16x32_bf16 v[0:3], v[216:219], v[196:199], v[0:3]
	v_mfma_f32_16x16x32_bf16 v[52:55], v[212:215], v[166:169], v[52:55]
	v_mfma_f32_16x16x32_bf16 v[48:51], v[220:223], v[166:169], v[48:51]
	v_mfma_f32_16x16x32_bf16 v[36:39], v[212:215], v[184:187], v[36:39]
	v_mfma_f32_16x16x32_bf16 v[32:35], v[220:223], v[184:187], v[32:35]
	v_mfma_f32_16x16x32_bf16 v[20:23], v[212:215], v[192:195], v[20:23]
	v_mfma_f32_16x16x32_bf16 v[16:19], v[220:223], v[192:195], v[16:19]
	v_mfma_f32_16x16x32_bf16 v[4:7], v[212:215], v[204:207], v[4:7]
	v_mfma_f32_16x16x32_bf16 v[0:3], v[220:223], v[204:207], v[0:3]
	s_add_i32 s33, 0, 0x18000
	v_add_u32_e32 v158, s33, v175
	s_barrier
	ds_read_b128 v[128:131], v158
	ds_read_b128 v[132:135], v158 offset:1024
	ds_read_b128 v[154:157], v158 offset:2048
	ds_read_b128 v[158:161], v158 offset:3072
	s_add_u32 s44, s44, 0x200000
	s_addc_u32 s45, s45, 0
	s_mov_b32 m0, s56
	v_lshl_add_u64 v[208:209], s[44:45], 0, v[136:137]
	ds_read_b128 v[162:165], v180 offset:32768
	ds_read_b128 v[166:169], v180 offset:33792
	ds_read_b128 v[170:173], v180 offset:34816
	ds_read_b128 v[184:187], v180 offset:35840
	ds_read_b128 v[188:191], v180 offset:36864
	ds_read_b128 v[192:195], v180 offset:37888
	ds_read_b128 v[196:199], v180 offset:38912
	ds_read_b128 v[204:207], v180 offset:39936
	global_load_lds_dwordx4 v[208:209], off
	v_lshl_add_u64 v[208:209], s[44:45], 0, v[142:143]
	s_mov_b32 m0, s57
	s_nop 0
	global_load_lds_dwordx4 v[208:209], off
	s_waitcnt lgkmcnt(8)
	s_barrier
	s_waitcnt lgkmcnt(0)
	s_waitcnt lgkmcnt(0)
	v_mfma_f32_16x16x32_bf16 v[124:127], v[128:131], v[162:165], v[124:127]
	v_mfma_f32_16x16x32_bf16 v[120:123], v[154:157], v[162:165], v[120:123]
	v_mfma_f32_16x16x32_bf16 v[108:111], v[128:131], v[170:173], v[108:111]
	v_mfma_f32_16x16x32_bf16 v[104:107], v[154:157], v[170:173], v[104:107]
	v_mfma_f32_16x16x32_bf16 v[92:95], v[128:131], v[188:191], v[92:95]
	v_mfma_f32_16x16x32_bf16 v[88:91], v[154:157], v[188:191], v[88:91]
	v_mfma_f32_16x16x32_bf16 v[76:79], v[128:131], v[196:199], v[76:79]
	v_mfma_f32_16x16x32_bf16 v[72:75], v[154:157], v[196:199], v[72:75]
	v_mfma_f32_16x16x32_bf16 v[124:127], v[132:135], v[166:169], v[124:127]
	v_mfma_f32_16x16x32_bf16 v[120:123], v[158:161], v[166:169], v[120:123]
	v_mfma_f32_16x16x32_bf16 v[108:111], v[132:135], v[184:187], v[108:111]
	v_mfma_f32_16x16x32_bf16 v[104:107], v[158:161], v[184:187], v[104:107]
	v_mfma_f32_16x16x32_bf16 v[92:95], v[132:135], v[192:195], v[92:95]
	v_mfma_f32_16x16x32_bf16 v[88:91], v[158:161], v[192:195], v[88:91]
	v_mfma_f32_16x16x32_bf16 v[76:79], v[132:135], v[204:207], v[76:79]
	v_mfma_f32_16x16x32_bf16 v[72:75], v[158:161], v[204:207], v[72:75]
	s_barrier
	s_add_i32 s44, 0, 0x1c000
	s_add_i32 s33, s33, s53
	v_add_u32_e32 v203, s44, v175
	v_lshl_add_u64 v[200:201], v[200:201], 0, s[26:27]
	s_mov_b32 m0, s33
	ds_read_b128 v[208:211], v203
	ds_read_b128 v[212:215], v203 offset:1024
	ds_read_b128 v[216:219], v203 offset:2048
	ds_read_b128 v[220:223], v203 offset:3072
	global_load_lds_dwordx4 v[200:201], off
	v_lshl_add_u64 v[200:201], v[224:225], 0, s[26:27]
	s_add_i32 m0, s33, 0x2000
	s_nop 0
	global_load_lds_dwordx4 v[200:201], off
	s_barrier
	s_waitcnt lgkmcnt(0)
	s_waitcnt lgkmcnt(0)
	v_mfma_f32_16x16x32_bf16 v[116:119], v[208:211], v[162:165], v[116:119]
	v_mfma_f32_16x16x32_bf16 v[112:115], v[216:219], v[162:165], v[112:115]
	v_mfma_f32_16x16x32_bf16 v[100:103], v[208:211], v[170:173], v[100:103]
	v_mfma_f32_16x16x32_bf16 v[96:99], v[216:219], v[170:173], v[96:99]
	v_mfma_f32_16x16x32_bf16 v[84:87], v[208:211], v[188:191], v[84:87]
	v_mfma_f32_16x16x32_bf16 v[80:83], v[216:219], v[188:191], v[80:83]
	v_mfma_f32_16x16x32_bf16 v[68:71], v[208:211], v[196:199], v[68:71]
	v_mfma_f32_16x16x32_bf16 v[64:67], v[216:219], v[196:199], v[64:67]
	v_mfma_f32_16x16x32_bf16 v[116:119], v[212:215], v[166:169], v[116:119]
	v_mfma_f32_16x16x32_bf16 v[112:115], v[220:223], v[166:169], v[112:115]
	v_mfma_f32_16x16x32_bf16 v[100:103], v[212:215], v[184:187], v[100:103]
	v_mfma_f32_16x16x32_bf16 v[96:99], v[220:223], v[184:187], v[96:99]
	v_mfma_f32_16x16x32_bf16 v[84:87], v[212:215], v[192:195], v[84:87]
	v_mfma_f32_16x16x32_bf16 v[80:83], v[220:223], v[192:195], v[80:83]
	v_mfma_f32_16x16x32_bf16 v[68:71], v[212:215], v[204:207], v[68:71]
	v_mfma_f32_16x16x32_bf16 v[64:67], v[220:223], v[204:207], v[64:67]
	s_mov_b32 m0, s60
	v_lshl_add_u64 v[200:201], v[226:227], 0, s[26:27]
	s_barrier
; __device__ __forceinline__ float bflo(unsigned w) { return __uint_as_float(w << 16); }
; __device__ __forceinline__ float bfhi(unsigned w) { return __uint_as_float(w & 0xffff0000u); }
; #define PG8_STAGE(bufoff, gbase, voff) do { _Pragma("unroll") for (int _i = 0; _i < 2; ++_i) \
;         __builtin_amdgcn_global_load_lds((const unsigned*)((const char*)(gbase) + (voff)[_i]), (LAS unsigned*)(lds + (bufoff) + ldsw + _i * 8192), 16, 0, 0); } while (0)
; #define PG8_LDA(dst, b, h) do { _Pragma("unroll") for (int m = 0; m < 4; ++m) _Pragma("unroll") for (int k = 0; k < 2; ++k) dst[m][k] = *(const LAS bf16x8*)(lds + PG8_SA(b, h) + aoff + m * 2048 + k * 1024); } while (0)
; #define PG8_WAIT_V(n) asm volatile("s_waitcnt vmcnt(" #n ")" ::: "memory")
; #define PG8_WAIT_L(n) asm volatile("s_waitcnt lgkmcnt(" #n ")" ::: "memory")
; #define PG8_BAR __builtin_amdgcn_s_barrier()
;     __device__ __forceinline__ void operator()(const f32x4 (&acc)[2][2][4][2], const Unit& u, int wr, int wc, int fr, int fq) const {
;         const int row0 = u.pm * BM + wr * 64 + fr, col0 = u.pn * BM + wc * 64 + 16 * fq;
; #pragma unroll
;         for (int ai = 0; ai < 2; ++ai)
; #pragma unroll
;             for (int m = 0; m < 4; ++m) { const int row = row0 + ai * HALF + m * 16; const size_t off = (size_t)row * D + col0; float sq = 0.f; u32x4 w[2];
;                 const float sc = rsin ? __builtin_amdgcn_rcpf(rsin[row] * (1.f / D) + EPS) : 1.0f;
;                 u32x4 rr[2]; if (R) load_pair_lines(R, D, row, fr, col0, rr[0], rr[1]);
; #pragma unroll
;                 for (int bj = 0; bj < 2; ++bj) { f32x4 r0, r1;
;                     if (R) { const u32x4 rw = rr[bj]; r0 = (f32x4){bflo(rw.x), bfhi(rw.x), bflo(rw.y), bfhi(rw.y)}; r1 = (f32x4){bflo(rw.z), bfhi(rw.z), bflo(rw.w), bfhi(rw.w)}; }
;                     else { const float* rp = (row < 8192 ? src_p + off : src_s + (off - (size_t)8192 * D)) + 8 * bj; r0 = *(const f32x4*)rp; r1 = *(const f32x4*)(rp + 4); }
; template <class Epi>
; __device__ __forceinline__ void gemm_phase(LAS unsigned char* lds, const Gemm g, const StaticOrder& S, const Epi& E) {
;     ...
;             PG8_LDA(At, 1, 1); PG8_STAGE(PG8_SA(1, 0), a3, voffA);
;             PG8_BAR; PG8_WAIT_L(0); PG8_MMA(1, 0, At, B0); PG8_BAR; PG8_SCHED;
;             PG8_STAGE(PG8_SB(1, 1), b3, voffB1);
;             PG8_WAIT_V(6); PG8_BAR; PG8_MMA(1, 1, At, B1); PG8_BAR;
;         }
	ds_read_b128 v[162:165], v180 offset:49152
	ds_read_b128 v[166:169], v180 offset:50176
	ds_read_b128 v[170:173], v180 offset:51200
	ds_read_b128 v[184:187], v180 offset:52224
	ds_read_b128 v[188:191], v180 offset:53248
	ds_read_b128 v[192:195], v180 offset:54272
	ds_read_b128 v[196:199], v180 offset:55296
	ds_read_b128 v[204:207], v180 offset:56320
	global_load_lds_dwordx4 v[200:201], off
	v_lshl_add_u64 v[200:201], v[228:229], 0, s[26:27]
	s_mov_b32 m0, s61
	s_nop 0
	global_load_lds_dwordx4 v[200:201], off
	s_barrier
	s_waitcnt lgkmcnt(0)
	s_waitcnt lgkmcnt(0)
	v_mfma_f32_16x16x32_bf16 v[60:63], v[128:131], v[162:165], v[60:63]
	v_mfma_f32_16x16x32_bf16 v[56:59], v[154:157], v[162:165], v[56:59]
	v_mfma_f32_16x16x32_bf16 v[44:47], v[128:131], v[170:173], v[44:47]
	v_mfma_f32_16x16x32_bf16 v[40:43], v[154:157], v[170:173], v[40:43]
	v_mfma_f32_16x16x32_bf16 v[28:31], v[128:131], v[188:191], v[28:31]
	v_mfma_f32_16x16x32_bf16 v[24:27], v[154:157], v[188:191], v[24:27]
	v_mfma_f32_16x16x32_bf16 v[12:15], v[128:131], v[196:199], v[12:15]
	v_mfma_f32_16x16x32_bf16 v[8:11], v[154:157], v[196:199], v[8:11]
	v_mfma_f32_16x16x32_bf16 v[60:63], v[132:135], v[166:169], v[60:63]
	v_mfma_f32_16x16x32_bf16 v[56:59], v[158:161], v[166:169], v[56:59]
	v_mfma_f32_16x16x32_bf16 v[44:47], v[132:135], v[184:187], v[44:47]
	v_mfma_f32_16x16x32_bf16 v[40:43], v[158:161], v[184:187], v[40:43]
	v_mfma_f32_16x16x32_bf16 v[28:31], v[132:135], v[192:195], v[28:31]
	v_mfma_f32_16x16x32_bf16 v[24:27], v[158:161], v[192:195], v[24:27]
	v_mfma_f32_16x16x32_bf16 v[12:15], v[132:135], v[204:207], v[12:15]
	v_mfma_f32_16x16x32_bf16 v[8:11], v[158:161], v[204:207], v[8:11]
	s_barrier
	s_add_i32 s33, s44, s53
	v_lshl_add_u64 v[128:129], v[230:231], 0, s[26:27]
	s_mov_b32 m0, s33
	s_nop 0
	global_load_lds_dwordx4 v[128:129], off
	v_lshl_add_u64 v[128:129], v[232:233], 0, s[26:27]
	s_add_i32 m0, s33, 0x2000
	s_nop 0
	global_load_lds_dwordx4 v[128:129], off
	s_waitcnt vmcnt(6)
	s_barrier
	v_mfma_f32_16x16x32_bf16 v[52:55], v[208:211], v[162:165], v[52:55]
	v_mfma_f32_16x16x32_bf16 v[48:51], v[216:219], v[162:165], v[48:51]
	v_mfma_f32_16x16x32_bf16 v[36:39], v[208:211], v[170:173], v[36:39]
	v_mfma_f32_16x16x32_bf16 v[32:35], v[216:219], v[170:173], v[32:35]
	v_mfma_f32_16x16x32_bf16 v[20:23], v[208:211], v[188:191], v[20:23]
	v_mfma_f32_16x16x32_bf16 v[16:19], v[216:219], v[188:191], v[16:19]
	v_mfma_f32_16x16x32_bf16 v[4:7], v[208:211], v[196:199], v[4:7]
	v_mfma_f32_16x16x32_bf16 v[0:3], v[216:219], v[196:199], v[0:3]
	v_mfma_f32_16x16x32_bf16 v[52:55], v[212:215], v[166:169], v[52:55]
	v_mfma_f32_16x16x32_bf16 v[48:51], v[220:223], v[166:169], v[48:51]
	v_mfma_f32_16x16x32_bf16 v[36:39], v[212:215], v[184:187], v[36:39]
	v_mfma_f32_16x16x32_bf16 v[32:35], v[220:223], v[184:187], v[32:35]
	v_mfma_f32_16x16x32_bf16 v[20:23], v[212:215], v[192:195], v[20:23]
	v_mfma_f32_16x16x32_bf16 v[16:19], v[220:223], v[192:195], v[16:19]
	v_mfma_f32_16x16x32_bf16 v[4:7], v[212:215], v[204:207], v[4:7]
	v_mfma_f32_16x16x32_bf16 v[0:3], v[220:223], v[204:207], v[0:3]
	s_add_i32 s74, s74, 2
	s_add_u32 s42, s42, 0x100
	s_addc_u32 s43, s43, 0
	s_add_u32 s72, s72, 0x100
	s_addc_u32 s73, s73, 0
	s_cmpk_gt_u32 s74, 0x7d
	s_barrier
	s_cbranch_scc0 .LBB0_1443
	s_lshl_b32 s9, s10, 8
	s_add_i32 s10, s9, s62
	v_or_b32_e32 v158, s10, v174
	v_ashrrev_i32_e32 v159, 31, v158
	v_lshl_add_u64 v[160:161], v[158:159], 2, s[18:19]
	global_load_dword v168, v[160:161], off
	v_lshl_or_b32 v156, s8, 8, v178
	v_or_b32_e32 v154, v156, v177
	v_ashrrev_i32_e32 v155, 31, v154
	v_cndmask_b32_e64 v128, 0, 1, s[28:29]
	v_or_b32_e32 v166, s10, v176
	v_cmp_ne_u32_e64 s[8:9], 1, v128
	s_andn2_b64 vcc, exec, s[28:29]
	v_lshlrev_b64 v[162:163], 1, v[154:155]
	v_ashrrev_i32_e32 v167, 31, v166
	v_or_b32_e32 v164, 8, v166
	s_cbranch_vccnz .LBB0_1447
	v_ashrrev_i32_e32 v165, 31, v164
	v_lshlrev_b64 v[128:129], 12, v[166:167]
	v_lshlrev_b64 v[132:133], 12, v[164:165]
	v_lshl_add_u64 v[128:129], s[16:17], 0, v[128:129]
	v_lshl_add_u64 v[132:133], s[16:17], 0, v[132:133]
	v_lshl_add_u64 v[128:129], v[128:129], 0, v[162:163]
	v_lshl_add_u64 v[132:133], v[132:133], 0, v[162:163]
	global_load_dwordx4 v[128:131], v[128:129], off
	v_mov_b32_e32 v157, 0
	global_load_dwordx4 v[132:135], v[132:133], off
	v_mov_b32_e32 v165, 0
	v_mov_b32_e32 v169, 0
	v_mov_b32_e32 v170, 0
	v_mov_b32_e32 v171, 0
	v_mov_b32_e32 v172, 0
	v_mov_b32_e32 v173, 0
	v_mov_b32_e32 v187, 0
	s_waitcnt vmcnt(0)
	v_mov_b32_dpp v157, v128 row_ror:8 row_mask:0xf bank_mask:0xf
	v_mov_b32_dpp v165, v129 row_ror:8 row_mask:0xf bank_mask:0xf
	v_mov_b32_dpp v169, v130 row_ror:8 row_mask:0xf bank_mask:0xf
	v_mov_b32_dpp v170, v131 row_ror:8 row_mask:0xf bank_mask:0xf
	v_mov_b32_dpp v171, v132 row_ror:8 row_mask:0xf bank_mask:0xf
	v_mov_b32_dpp v172, v133 row_ror:8 row_mask:0xf bank_mask:0xf
	v_mov_b32_dpp v173, v134 row_ror:8 row_mask:0xf bank_mask:0xf
	v_mov_b32_dpp v187, v135 row_ror:8 row_mask:0xf bank_mask:0xf
	v_cndmask_b32_e64 v184, v132, v157, s[6:7]
	v_cndmask_b32_e64 v185, v133, v165, s[6:7]
	v_cndmask_b32_e64 v186, v134, v169, s[6:7]
	v_cndmask_b32_e64 v188, v171, v128, s[6:7]
	v_cndmask_b32_e64 v189, v172, v129, s[6:7]
	v_cndmask_b32_e64 v190, v173, v130, s[6:7]
	v_cndmask_b32_e64 v191, v187, v131, s[6:7]
	v_cndmask_b32_e64 v187, v135, v170, s[6:7]
	s_and_b64 vcc, exec, s[8:9]
	v_cmp_gt_i32_e64 s[10:11], s58, v158
	s_cbranch_vccnz .LBB0_1448

; #define PG8_STAGE(bufoff, gbase, voff) do { _Pragma("unroll") for (int _i = 0; _i < 2; ++_i) \
;         __builtin_amdgcn_global_load_lds((const unsigned*)((const char*)(gbase) + (voff)[_i]), (LAS unsigned*)(lds + (bufoff) + ldsw + _i * 8192), 16, 0, 0); } while (0)
; #define PG8_LDA(dst, b, h) do { _Pragma("unroll") for (int m = 0; m < 4; ++m) _Pragma("unroll") for (int k = 0; k < 2; ++k) dst[m][k] = *(const LAS bf16x8*)(lds + PG8_SA(b, h) + aoff + m * 2048 + k * 1024); } while (0)
; #define PG8_LDB(dst, b, h) do { _Pragma("unroll") for (int n = 0; n < 2; ++n) _Pragma("unroll") for (int k = 0; k < 2; ++k) dst[n][k] = *(const LAS bf16x8*)(lds + PG8_SB(b, h) + boff + n * 2048 + k * 1024); } while (0)
; #define PG8_MMA(ai, bj, At, Bt) do { __builtin_amdgcn_s_setprio(1); _Pragma("unroll") for (int m = 0; m < 4; ++m) _Pragma("unroll") for (int n = 0; n < 2; ++n) _Pragma("unroll") for (int k = 0; k < 2; ++k) \
;         acc[ai][bj][m][n] = __builtin_amdgcn_mfma_f32_16x16x32_bf16(Bt[n][k], At[m][k], acc[ai][bj][m][n], 0, 0, 0); __builtin_amdgcn_s_setprio(0); } while (0)
; #define PG8_WAIT_V(n) asm volatile("s_waitcnt vmcnt(" #n ")" ::: "memory")
; #define PG8_WAIT_L(n) asm volatile("s_waitcnt lgkmcnt(" #n ")" ::: "memory")
; #define PG8_BAR __builtin_amdgcn_s_barrier()
; template <class Epi>
; __device__ __forceinline__ void gemm_phase(LAS unsigned char* lds, const Gemm g, const StaticOrder& S, const Epi& E) {
;     ...
;         for (int t = 0; t < nt; t += 2) {
;             const bool last = (t == nt - 2);
;             const char* a1 = cA + (size_t)(t + 1) * kstep;
;             const char* a2 = last ? nA : cA + (size_t)(t + 2) * kstep; const char* b2 = last ? nB : cB + (size_t)(t + 2) * kstep;
;             const char* a3 = a2 + kstep; const char* b3 = b2 + kstep;
;             PG8_LDB(B0, 0, 0); PG8_SCHED; PG8_LDA(At, 0, 0); PG8_STAGE(PG8_SA(1, 1), a1 + hstep, voffA);
;             PG8_WAIT_L(8); PG8_BAR; PG8_WAIT_L(0); PG8_MMA(0, 0, At, B0); PG8_BAR; PG8_SCHED;
;             PG8_LDB(B1, 0, 1); PG8_STAGE(PG8_SB(0, 0), b2, voffB0);
;             PG8_BAR; PG8_WAIT_L(0); PG8_MMA(0, 1, At, B1); PG8_BAR;
;             PG8_LDA(At, 0, 1); PG8_STAGE(PG8_SA(0, 0), a2, voffA);
;             PG8_BAR; PG8_WAIT_L(0); PG8_MMA(1, 0, At, B0); PG8_BAR; PG8_SCHED;
;             PG8_STAGE(PG8_SB(0, 1), b2, voffB1);
;             PG8_WAIT_V(6); PG8_BAR; PG8_MMA(1, 1, At, B1); PG8_BAR;
.LBB0_1603:
	ds_read_b128 v[40:43], v179
	ds_read_b128 v[44:47], v179 offset:1024
	ds_read_b128 v[56:59], v179 offset:2048
	ds_read_b128 v[60:63], v179 offset:3072
	s_add_u32 s36, s34, 0xfff80080
	s_addc_u32 s37, s35, -1
	s_cmp_eq_u32 s58, 28
	s_cselect_b32 s37, s23, s37
	s_cselect_b32 s36, s54, s36
	s_cselect_b32 s39, s19, s57
	s_cselect_b32 s38, s55, s56
	v_lshl_add_u64 v[172:173], s[34:35], 0, v[158:159]
	s_add_i32 m0, s31, 0xc000
	ds_read_b128 v[164:167], v180
	ds_read_b128 v[168:171], v180 offset:1024
	ds_read_b128 v[184:187], v180 offset:2048
	ds_read_b128 v[188:191], v180 offset:3072
	ds_read_b128 v[192:195], v180 offset:4096
	ds_read_b128 v[196:199], v180 offset:5120
	ds_read_b128 v[200:203], v180 offset:6144
	ds_read_b128 v[204:207], v180 offset:7168
	global_load_lds_dwordx4 v[172:173], off
	v_lshl_add_u64 v[172:173], s[34:35], 0, v[160:161]
	s_add_i32 m0, s31, 0xe000
	s_nop 0
	global_load_lds_dwordx4 v[172:173], off
	s_waitcnt lgkmcnt(8)
	s_barrier
	s_waitcnt lgkmcnt(0)
	s_waitcnt lgkmcnt(0)
	v_mfma_f32_16x16x32_bf16 v[140:143], v[40:43], v[164:167], v[140:143]
	v_mfma_f32_16x16x32_bf16 v[136:139], v[56:59], v[164:167], v[136:139]
	v_mfma_f32_16x16x32_bf16 v[124:127], v[40:43], v[184:187], v[124:127]
	v_mfma_f32_16x16x32_bf16 v[120:123], v[56:59], v[184:187], v[120:123]
	v_mfma_f32_16x16x32_bf16 v[108:111], v[40:43], v[192:195], v[108:111]
	v_mfma_f32_16x16x32_bf16 v[104:107], v[56:59], v[192:195], v[104:107]
	v_mfma_f32_16x16x32_bf16 v[92:95], v[40:43], v[200:203], v[92:95]
	v_mfma_f32_16x16x32_bf16 v[88:91], v[56:59], v[200:203], v[88:91]
	v_mfma_f32_16x16x32_bf16 v[140:143], v[44:47], v[168:171], v[140:143]
	v_mfma_f32_16x16x32_bf16 v[136:139], v[60:63], v[168:171], v[136:139]
	v_mfma_f32_16x16x32_bf16 v[124:127], v[44:47], v[188:191], v[124:127]
	v_mfma_f32_16x16x32_bf16 v[120:123], v[60:63], v[188:191], v[120:123]
	v_mfma_f32_16x16x32_bf16 v[108:111], v[44:47], v[196:199], v[108:111]
	v_mfma_f32_16x16x32_bf16 v[104:107], v[60:63], v[196:199], v[104:107]
	v_mfma_f32_16x16x32_bf16 v[92:95], v[44:47], v[204:207], v[92:95]
	v_mfma_f32_16x16x32_bf16 v[88:91], v[60:63], v[204:207], v[88:91]
	s_barrier
	s_add_i32 s59, s51, s41
	v_lshl_add_u64 v[172:173], s[38:39], 0, v[146:147]
	s_mov_b32 m0, s59
	ds_read_b128 v[208:211], v181
	ds_read_b128 v[212:215], v181 offset:1024
	ds_read_b128 v[216:219], v181 offset:2048
	ds_read_b128 v[220:223], v181 offset:3072
	global_load_lds_dwordx4 v[172:173], off
	v_lshl_add_u64 v[224:225], s[38:39], 0, v[152:153]
	s_add_i32 m0, s59, 0x2000
	s_nop 0
	global_load_lds_dwordx4 v[224:225], off
	s_barrier
	s_waitcnt lgkmcnt(0)
	s_waitcnt lgkmcnt(0)
	v_mfma_f32_16x16x32_bf16 v[132:135], v[208:211], v[164:167], v[132:135]
	v_mfma_f32_16x16x32_bf16 v[128:131], v[216:219], v[164:167], v[128:131]
	v_mfma_f32_16x16x32_bf16 v[116:119], v[208:211], v[184:187], v[116:119]
	v_mfma_f32_16x16x32_bf16 v[112:115], v[216:219], v[184:187], v[112:115]
	v_mfma_f32_16x16x32_bf16 v[100:103], v[208:211], v[192:195], v[100:103]
	v_mfma_f32_16x16x32_bf16 v[96:99], v[216:219], v[192:195], v[96:99]
	v_mfma_f32_16x16x32_bf16 v[84:87], v[208:211], v[200:203], v[84:87]
	v_mfma_f32_16x16x32_bf16 v[80:83], v[216:219], v[200:203], v[80:83]
	v_mfma_f32_16x16x32_bf16 v[132:135], v[212:215], v[168:171], v[132:135]
	v_mfma_f32_16x16x32_bf16 v[128:131], v[220:223], v[168:171], v[128:131]
	v_mfma_f32_16x16x32_bf16 v[116:119], v[212:215], v[188:191], v[116:119]
	v_mfma_f32_16x16x32_bf16 v[112:115], v[220:223], v[188:191], v[112:115]
	v_mfma_f32_16x16x32_bf16 v[100:103], v[212:215], v[196:199], v[100:103]
	v_mfma_f32_16x16x32_bf16 v[96:99], v[220:223], v[196:199], v[96:99]
	v_mfma_f32_16x16x32_bf16 v[84:87], v[212:215], v[204:207], v[84:87]
	v_mfma_f32_16x16x32_bf16 v[80:83], v[220:223], v[204:207], v[80:83]
	s_mov_b32 m0, s31
	v_lshl_add_u64 v[226:227], s[36:37], 0, v[144:145]
	s_barrier
	ds_read_b128 v[164:167], v180 offset:16384
	ds_read_b128 v[168:171], v180 offset:17408
	ds_read_b128 v[184:187], v180 offset:18432
	ds_read_b128 v[188:191], v180 offset:19456
	ds_read_b128 v[192:195], v180 offset:20480
	ds_read_b128 v[196:199], v180 offset:21504
	ds_read_b128 v[200:203], v180 offset:22528
	ds_read_b128 v[204:207], v180 offset:23552
	global_load_lds_dwordx4 v[226:227], off
	v_lshl_add_u64 v[228:229], s[36:37], 0, v[150:151]
	s_mov_b32 m0, s42
	s_nop 0
	global_load_lds_dwordx4 v[228:229], off
	s_barrier
	s_waitcnt lgkmcnt(0)
	s_waitcnt lgkmcnt(0)
	v_mfma_f32_16x16x32_bf16 v[76:79], v[40:43], v[164:167], v[76:79]
	v_mfma_f32_16x16x32_bf16 v[72:75], v[56:59], v[164:167], v[72:75]
	v_mfma_f32_16x16x32_bf16 v[52:55], v[40:43], v[184:187], v[52:55]
	v_mfma_f32_16x16x32_bf16 v[48:51], v[56:59], v[184:187], v[48:51]
	v_mfma_f32_16x16x32_bf16 v[28:31], v[40:43], v[192:195], v[28:31]
	v_mfma_f32_16x16x32_bf16 v[24:27], v[56:59], v[192:195], v[24:27]
	v_mfma_f32_16x16x32_bf16 v[12:15], v[40:43], v[200:203], v[12:15]
	v_mfma_f32_16x16x32_bf16 v[8:11], v[56:59], v[200:203], v[8:11]
	v_mfma_f32_16x16x32_bf16 v[76:79], v[44:47], v[168:171], v[76:79]
	v_mfma_f32_16x16x32_bf16 v[72:75], v[60:63], v[168:171], v[72:75]
	v_mfma_f32_16x16x32_bf16 v[52:55], v[44:47], v[188:191], v[52:55]
	v_mfma_f32_16x16x32_bf16 v[48:51], v[60:63], v[188:191], v[48:51]
	v_mfma_f32_16x16x32_bf16 v[28:31], v[44:47], v[196:199], v[28:31]
	v_mfma_f32_16x16x32_bf16 v[24:27], v[60:63], v[196:199], v[24:27]
	v_mfma_f32_16x16x32_bf16 v[12:15], v[44:47], v[204:207], v[12:15]
	v_mfma_f32_16x16x32_bf16 v[8:11], v[60:63], v[204:207], v[8:11]
	s_barrier
; #define PG8_STAGE(bufoff, gbase, voff) do { _Pragma("unroll") for (int _i = 0; _i < 2; ++_i) \
;         __builtin_amdgcn_global_load_lds((const unsigned*)((const char*)(gbase) + (voff)[_i]), (LAS unsigned*)(lds + (bufoff) + ldsw + _i * 8192), 16, 0, 0); } while (0)
; #define PG8_LDA(dst, b, h) do { _Pragma("unroll") for (int m = 0; m < 4; ++m) _Pragma("unroll") for (int k = 0; k < 2; ++k) dst[m][k] = *(const LAS bf16x8*)(lds + PG8_SA(b, h) + aoff + m * 2048 + k * 1024); } while (0)
; #define PG8_LDB(dst, b, h) do { _Pragma("unroll") for (int n = 0; n < 2; ++n) _Pragma("unroll") for (int k = 0; k < 2; ++k) dst[n][k] = *(const LAS bf16x8*)(lds + PG8_SB(b, h) + boff + n * 2048 + k * 1024); } while (0)
; #define PG8_MMA(ai, bj, At, Bt) do { __builtin_amdgcn_s_setprio(1); _Pragma("unroll") for (int m = 0; m < 4; ++m) _Pragma("unroll") for (int n = 0; n < 2; ++n) _Pragma("unroll") for (int k = 0; k < 2; ++k) \
;         acc[ai][bj][m][n] = __builtin_amdgcn_mfma_f32_16x16x32_bf16(Bt[n][k], At[m][k], acc[ai][bj][m][n], 0, 0, 0); __builtin_amdgcn_s_setprio(0); } while (0)
; #define PG8_WAIT_V(n) asm volatile("s_waitcnt vmcnt(" #n ")" ::: "memory")
; #define PG8_WAIT_L(n) asm volatile("s_waitcnt lgkmcnt(" #n ")" ::: "memory")
; #define PG8_BAR __builtin_amdgcn_s_barrier()
; #define PG8_SCHED __builtin_amdgcn_sched_barrier(0)
; template <class Epi>
; __device__ __forceinline__ void gemm_phase(LAS unsigned char* lds, const Gemm g, const StaticOrder& S, const Epi& E) {
;     ...
;             PG8_STAGE(PG8_SB(0, 1), b2, voffB1);
;             PG8_WAIT_V(6); PG8_BAR; PG8_MMA(1, 1, At, B1); PG8_BAR;
;             PG8_LDB(B0, 1, 0); PG8_SCHED; PG8_LDA(At, 1, 0); PG8_STAGE(PG8_SA(0, 1), a2 + hstep, voffA);
;             PG8_WAIT_L(8); PG8_BAR; PG8_WAIT_L(0); PG8_MMA(0, 0, At, B0); PG8_BAR; PG8_SCHED;
;             PG8_LDB(B1, 1, 1); PG8_STAGE(PG8_SB(1, 0), b3, voffB0);
;             PG8_BAR; PG8_WAIT_L(0); PG8_MMA(0, 1, At, B1); PG8_BAR;
;             PG8_LDA(At, 1, 1); PG8_STAGE(PG8_SA(1, 0), a3, voffA);
;             PG8_BAR; PG8_WAIT_L(0); PG8_MMA(1, 0, At, B0); PG8_BAR; PG8_SCHED;
	s_add_i32 s59, s52, s41
	v_lshl_add_u64 v[230:231], s[38:39], 0, v[148:149]
	s_mov_b32 m0, s59
	v_lshl_add_u64 v[232:233], s[38:39], 0, v[154:155]
	global_load_lds_dwordx4 v[230:231], off
	s_add_i32 m0, s59, 0x2000
	s_nop 0
	global_load_lds_dwordx4 v[232:233], off
	s_waitcnt vmcnt(6)
	s_barrier
	v_mfma_f32_16x16x32_bf16 v[36:39], v[208:211], v[184:187], v[36:39]
	v_mfma_f32_16x16x32_bf16 v[32:35], v[216:219], v[184:187], v[32:35]
	v_mfma_f32_16x16x32_bf16 v[20:23], v[208:211], v[192:195], v[20:23]
	v_mfma_f32_16x16x32_bf16 v[16:19], v[216:219], v[192:195], v[16:19]
	v_mfma_f32_16x16x32_bf16 v[4:7], v[208:211], v[200:203], v[4:7]
	v_mfma_f32_16x16x32_bf16 v[0:3], v[216:219], v[200:203], v[0:3]
	v_mfma_f32_16x16x32_bf16 v[40:43], v[208:211], v[164:167], v[68:71]
	v_mfma_f32_16x16x32_bf16 v[44:47], v[216:219], v[164:167], v[64:67]
	v_mfma_f32_16x16x32_bf16 v[36:39], v[212:215], v[188:191], v[36:39]
	v_mfma_f32_16x16x32_bf16 v[32:35], v[220:223], v[188:191], v[32:35]
	v_mfma_f32_16x16x32_bf16 v[20:23], v[212:215], v[196:199], v[20:23]
	v_mfma_f32_16x16x32_bf16 v[16:19], v[220:223], v[196:199], v[16:19]
	v_mfma_f32_16x16x32_bf16 v[4:7], v[212:215], v[204:207], v[4:7]
	v_mfma_f32_16x16x32_bf16 v[0:3], v[220:223], v[204:207], v[0:3]
	v_mfma_f32_16x16x32_bf16 v[40:43], v[212:215], v[168:171], v[40:43]
	v_mfma_f32_16x16x32_bf16 v[44:47], v[220:223], v[168:171], v[44:47]
	s_add_i32 s38, 0, 0x18000
	v_add_u32_e32 v68, s38, v175
	s_barrier
	ds_read_b128 v[56:59], v68
	ds_read_b128 v[60:63], v68 offset:1024
	ds_read_b128 v[64:67], v68 offset:2048
	ds_read_b128 v[68:71], v68 offset:3072
	s_add_u32 s36, s36, 0x80000
	s_addc_u32 s37, s37, 0
	s_mov_b32 m0, s43
	v_lshl_add_u64 v[208:209], s[36:37], 0, v[144:145]
	ds_read_b128 v[164:167], v180 offset:32768
	ds_read_b128 v[168:171], v180 offset:33792
	ds_read_b128 v[184:187], v180 offset:34816
	ds_read_b128 v[188:191], v180 offset:35840
	ds_read_b128 v[192:195], v180 offset:36864
	ds_read_b128 v[196:199], v180 offset:37888
	ds_read_b128 v[200:203], v180 offset:38912
	ds_read_b128 v[204:207], v180 offset:39936
	global_load_lds_dwordx4 v[208:209], off
	v_lshl_add_u64 v[208:209], s[36:37], 0, v[150:151]
	s_mov_b32 m0, s44
	s_nop 0
	global_load_lds_dwordx4 v[208:209], off
	s_waitcnt lgkmcnt(8)
	s_barrier
	s_waitcnt lgkmcnt(0)
	s_waitcnt lgkmcnt(0)
	v_mfma_f32_16x16x32_bf16 v[140:143], v[56:59], v[164:167], v[140:143]
	v_mfma_f32_16x16x32_bf16 v[136:139], v[64:67], v[164:167], v[136:139]
	v_mfma_f32_16x16x32_bf16 v[124:127], v[56:59], v[184:187], v[124:127]
	v_mfma_f32_16x16x32_bf16 v[120:123], v[64:67], v[184:187], v[120:123]
	v_mfma_f32_16x16x32_bf16 v[108:111], v[56:59], v[192:195], v[108:111]
	v_mfma_f32_16x16x32_bf16 v[104:107], v[64:67], v[192:195], v[104:107]
	v_mfma_f32_16x16x32_bf16 v[92:95], v[56:59], v[200:203], v[92:95]
	v_mfma_f32_16x16x32_bf16 v[88:91], v[64:67], v[200:203], v[88:91]
	v_mfma_f32_16x16x32_bf16 v[140:143], v[60:63], v[168:171], v[140:143]
	v_mfma_f32_16x16x32_bf16 v[136:139], v[68:71], v[168:171], v[136:139]
	v_mfma_f32_16x16x32_bf16 v[124:127], v[60:63], v[188:191], v[124:127]
	v_mfma_f32_16x16x32_bf16 v[120:123], v[68:71], v[188:191], v[120:123]
	v_mfma_f32_16x16x32_bf16 v[108:111], v[60:63], v[196:199], v[108:111]
	v_mfma_f32_16x16x32_bf16 v[104:107], v[68:71], v[196:199], v[104:107]
	v_mfma_f32_16x16x32_bf16 v[92:95], v[60:63], v[204:207], v[92:95]
	v_mfma_f32_16x16x32_bf16 v[88:91], v[68:71], v[204:207], v[88:91]
	s_barrier
	s_add_i32 s36, 0, 0x1c000
	s_add_i32 s37, s38, s41
	v_add_u32_e32 v183, s36, v175
	v_lshl_add_u64 v[172:173], v[172:173], 0, s[14:15]
	s_mov_b32 m0, s37
	ds_read_b128 v[208:211], v183
	ds_read_b128 v[212:215], v183 offset:1024
	ds_read_b128 v[216:219], v183 offset:2048
	ds_read_b128 v[220:223], v183 offset:3072
	global_load_lds_dwordx4 v[172:173], off
	v_lshl_add_u64 v[172:173], v[224:225], 0, s[14:15]
	s_add_i32 m0, s37, 0x2000
	s_nop 0
	global_load_lds_dwordx4 v[172:173], off
	s_barrier
	s_waitcnt lgkmcnt(0)
	s_waitcnt lgkmcnt(0)
	v_mfma_f32_16x16x32_bf16 v[132:135], v[208:211], v[164:167], v[132:135]
	v_mfma_f32_16x16x32_bf16 v[128:131], v[216:219], v[164:167], v[128:131]
	v_mfma_f32_16x16x32_bf16 v[116:119], v[208:211], v[184:187], v[116:119]
	v_mfma_f32_16x16x32_bf16 v[112:115], v[216:219], v[184:187], v[112:115]
	v_mfma_f32_16x16x32_bf16 v[100:103], v[208:211], v[192:195], v[100:103]
	v_mfma_f32_16x16x32_bf16 v[96:99], v[216:219], v[192:195], v[96:99]
	v_mfma_f32_16x16x32_bf16 v[84:87], v[208:211], v[200:203], v[84:87]
	v_mfma_f32_16x16x32_bf16 v[80:83], v[216:219], v[200:203], v[80:83]
	v_mfma_f32_16x16x32_bf16 v[132:135], v[212:215], v[168:171], v[132:135]
	v_mfma_f32_16x16x32_bf16 v[128:131], v[220:223], v[168:171], v[128:131]
	v_mfma_f32_16x16x32_bf16 v[116:119], v[212:215], v[188:191], v[116:119]
	v_mfma_f32_16x16x32_bf16 v[112:115], v[220:223], v[188:191], v[112:115]
	v_mfma_f32_16x16x32_bf16 v[100:103], v[212:215], v[196:199], v[100:103]
	v_mfma_f32_16x16x32_bf16 v[96:99], v[220:223], v[196:199], v[96:99]
	v_mfma_f32_16x16x32_bf16 v[84:87], v[212:215], v[204:207], v[84:87]
	v_mfma_f32_16x16x32_bf16 v[80:83], v[220:223], v[204:207], v[80:83]
	s_mov_b32 m0, s47
	v_lshl_add_u64 v[172:173], v[226:227], 0, s[14:15]
	s_barrier
	ds_read_b128 v[164:167], v180 offset:49152
	ds_read_b128 v[168:171], v180 offset:50176
	ds_read_b128 v[184:187], v180 offset:51200
	ds_read_b128 v[188:191], v180 offset:52224
	ds_read_b128 v[192:195], v180 offset:53248
	ds_read_b128 v[196:199], v180 offset:54272
	ds_read_b128 v[200:203], v180 offset:55296
	ds_read_b128 v[204:207], v180 offset:56320
	global_load_lds_dwordx4 v[172:173], off
	v_lshl_add_u64 v[172:173], v[228:229], 0, s[14:15]
	s_mov_b32 m0, s48
	s_nop 0
	global_load_lds_dwordx4 v[172:173], off
	s_barrier
; __device__ __forceinline__ float bflo(unsigned w) { return __uint_as_float(w << 16); }
; __device__ __forceinline__ float bfhi(unsigned w) { return __uint_as_float(w & 0xffff0000u); }
; #define PG8_STAGE(bufoff, gbase, voff) do { _Pragma("unroll") for (int _i = 0; _i < 2; ++_i) \
;         __builtin_amdgcn_global_load_lds((const unsigned*)((const char*)(gbase) + (voff)[_i]), (LAS unsigned*)(lds + (bufoff) + ldsw + _i * 8192), 16, 0, 0); } while (0)
;     __device__ __forceinline__ void operator()(const f32x4 (&acc)[2][2][4][2], const Unit& u, int wr, int wc, int fr, int fq) const {
;         const int row0 = u.pm * BM + wr * 64 + fr, col0 = u.pn * BM + wc * 64 + 8 * fq;
;         f32x4 gv[2][2];
; #pragma unroll
;         for (int bj = 0; bj < 2; ++bj) { gv[bj][0] = *(const f32x4*)(g + col0 + 32 * bj); gv[bj][1] = *(const f32x4*)(g + col0 + 32 * bj + 4); }
;         const bool lo = fr < 8;
; #pragma unroll
;         for (int ai = 0; ai < 2; ++ai)
; #pragma unroll
;             for (int m = 0; m < 4; ++m) { const int row = row0 + ai * HALF + m * 16; const float ri = __builtin_amdgcn_rsqf(sse[row] * (1.f / D) + EPS);
;                 u32x4 rr[2], ee[2]; load_pair_lines(R, D, row, fr, col0, rr[0], rr[1], 32); load_pair_lines(E, D, row, fr, col0, ee[0], ee[1], 32);
;                 float* orow = OUT + (size_t)(row - fr + (fr & 7)) * D + col0 + (lo ? 0 : 4);
; #pragma unroll
;                 for (int bj = 0; bj < 2; ++bj) { const u32x4 rw = rr[bj], ew = ee[bj];
;                     const float r[8] = {bflo(rw.x), bfhi(rw.x), bflo(rw.y), bfhi(rw.y), bflo(rw.z), bfhi(rw.z), bflo(rw.w), bfhi(rw.w)};
;                     const float e[8] = {bflo(ew.x), bfhi(ew.x), bflo(ew.y), bfhi(ew.y), bflo(ew.z), bfhi(ew.z), bflo(ew.w), bfhi(ew.w)};
;                     float o[8];
; #pragma unroll
;                     for (int j = 0; j < 8; ++j) { const float a = acc[ai][bj][m][j >> 2][j & 3]; const float gg = gv[bj][j >> 2][j & 3];
;                         o[j] = r[j] + e[j] * ri * gg * __builtin_amdgcn_rcpf(1.f + __builtin_amdgcn_exp2f(-a * LOG2E)); }
; template <class Epi>
; __device__ __forceinline__ void gemm_phase(LAS unsigned char* lds, const Gemm g, const StaticOrder& S, const Epi& E) {
;     ...
;             PG8_STAGE(PG8_SB(1, 1), b3, voffB1);
;             PG8_WAIT_V(6); PG8_BAR; PG8_MMA(1, 1, At, B1); PG8_BAR;
;         }
;         E(acc, cur, wr, wc, fr, fq);
	s_waitcnt lgkmcnt(0)
	s_waitcnt lgkmcnt(0)
	v_mfma_f32_16x16x32_bf16 v[76:79], v[56:59], v[164:167], v[76:79]
	v_mfma_f32_16x16x32_bf16 v[72:75], v[64:67], v[164:167], v[72:75]
	v_mfma_f32_16x16x32_bf16 v[52:55], v[56:59], v[184:187], v[52:55]
	v_mfma_f32_16x16x32_bf16 v[48:51], v[64:67], v[184:187], v[48:51]
	v_mfma_f32_16x16x32_bf16 v[28:31], v[56:59], v[192:195], v[28:31]
	v_mfma_f32_16x16x32_bf16 v[24:27], v[64:67], v[192:195], v[24:27]
	v_mfma_f32_16x16x32_bf16 v[12:15], v[56:59], v[200:203], v[12:15]
	v_mfma_f32_16x16x32_bf16 v[8:11], v[64:67], v[200:203], v[8:11]
	v_mfma_f32_16x16x32_bf16 v[76:79], v[60:63], v[168:171], v[76:79]
	v_mfma_f32_16x16x32_bf16 v[72:75], v[68:71], v[168:171], v[72:75]
	v_mfma_f32_16x16x32_bf16 v[52:55], v[60:63], v[188:191], v[52:55]
	v_mfma_f32_16x16x32_bf16 v[48:51], v[68:71], v[188:191], v[48:51]
	v_mfma_f32_16x16x32_bf16 v[28:31], v[60:63], v[196:199], v[28:31]
	v_mfma_f32_16x16x32_bf16 v[24:27], v[68:71], v[196:199], v[24:27]
	v_mfma_f32_16x16x32_bf16 v[12:15], v[60:63], v[204:207], v[12:15]
	v_mfma_f32_16x16x32_bf16 v[8:11], v[68:71], v[204:207], v[8:11]
	s_barrier
	s_add_i32 s36, s36, s41
	v_lshl_add_u64 v[56:57], v[230:231], 0, s[14:15]
	s_mov_b32 m0, s36
	s_nop 0
	global_load_lds_dwordx4 v[56:57], off
	v_lshl_add_u64 v[56:57], v[232:233], 0, s[14:15]
	s_add_i32 m0, s36, 0x2000
	s_nop 0
	global_load_lds_dwordx4 v[56:57], off
	s_waitcnt vmcnt(6)
	s_barrier
	v_mfma_f32_16x16x32_bf16 v[40:43], v[208:211], v[164:167], v[40:43]
	v_mfma_f32_16x16x32_bf16 v[68:71], v[212:215], v[168:171], v[40:43]
	v_mfma_f32_16x16x32_bf16 v[40:43], v[216:219], v[164:167], v[44:47]
	v_mfma_f32_16x16x32_bf16 v[36:39], v[208:211], v[184:187], v[36:39]
	v_mfma_f32_16x16x32_bf16 v[32:35], v[216:219], v[184:187], v[32:35]
	v_mfma_f32_16x16x32_bf16 v[20:23], v[208:211], v[192:195], v[20:23]
	v_mfma_f32_16x16x32_bf16 v[16:19], v[216:219], v[192:195], v[16:19]
	v_mfma_f32_16x16x32_bf16 v[4:7], v[208:211], v[200:203], v[4:7]
	v_mfma_f32_16x16x32_bf16 v[0:3], v[216:219], v[200:203], v[0:3]
	v_mfma_f32_16x16x32_bf16 v[64:67], v[220:223], v[168:171], v[40:43]
	v_mfma_f32_16x16x32_bf16 v[36:39], v[212:215], v[188:191], v[36:39]
	v_mfma_f32_16x16x32_bf16 v[32:35], v[220:223], v[188:191], v[32:35]
	v_mfma_f32_16x16x32_bf16 v[20:23], v[212:215], v[196:199], v[20:23]
	v_mfma_f32_16x16x32_bf16 v[16:19], v[220:223], v[196:199], v[16:19]
	v_mfma_f32_16x16x32_bf16 v[4:7], v[212:215], v[204:207], v[4:7]
	v_mfma_f32_16x16x32_bf16 v[0:3], v[220:223], v[204:207], v[0:3]
	s_add_i32 s58, s58, 2
	s_add_u32 s34, s34, 0x100
	s_addc_u32 s35, s35, 0
	s_add_u32 s56, s56, 0x100
	s_addc_u32 s57, s57, 0
	s_cmp_gt_u32 s58, 29
	s_barrier
	s_cbranch_scc0 .LBB0_1603
	s_lshl_b32 s19, s30, 8
	s_add_i32 s19, s19, s49
	v_lshl_or_b32 v40, s53, 8, v178
	v_or_b32_e32 v172, s19, v176
	v_or_b32_e32 v42, v40, v177
	v_ashrrev_i32_e32 v173, 31, v172
	v_or_b32_e32 v170, s19, v174
	v_ashrrev_i32_e32 v43, 31, v42
	v_lshlrev_b64 v[44:45], 12, v[172:173]
	v_ashrrev_i32_e32 v171, 31, v170
	v_lshl_add_u64 v[46:47], s[8:9], 0, v[44:45]
	v_lshlrev_b64 v[164:165], 1, v[42:43]
	v_lshl_add_u64 v[168:169], v[170:171], 2, s[6:7]
	v_lshl_add_u64 v[42:43], v[46:47], 0, v[164:165]
	global_load_dword v171, v[168:169], off
	global_load_dwordx4 v[184:187], v[42:43], off
	v_or_b32_e32 v42, 8, v172
	v_ashrrev_i32_e32 v43, 31, v42
	v_lshlrev_b64 v[42:43], 12, v[42:43]
	v_lshl_add_u64 v[46:47], s[8:9], 0, v[42:43]
	v_lshl_add_u64 v[44:45], s[10:11], 0, v[44:45]
	v_lshl_add_u64 v[42:43], s[10:11], 0, v[42:43]
	v_lshl_add_u64 v[46:47], v[46:47], 0, v[164:165]
	v_lshl_add_u64 v[44:45], v[44:45], 0, v[164:165]
	v_lshl_add_u64 v[42:43], v[42:43], 0, v[164:165]
	global_load_dwordx4 v[188:191], v[46:47], off
	global_load_dwordx4 v[192:195], v[44:45], off
	global_load_dwordx4 v[196:199], v[42:43], off
	v_ashrrev_i32_e32 v41, 31, v40
	v_lshlrev_b64 v[166:167], 2, v[40:41]
	v_lshl_add_u64 v[44:45], s[12:13], 0, v[166:167]
	global_load_dwordx4 v[56:59], v[44:45], off
	global_load_dwordx4 v[60:63], v[44:45], off offset:16
	v_mul_f32_e32 v40, 0xbfb8aa3b, v140
	v_exp_f32_e32 v215, v40
	global_load_dwordx4 v[40:43], v[44:45], off offset:128
	s_nop 0
	global_load_dwordx4 v[44:47], v[44:45], off offset:144
	v_or_b32_e32 v216, 16, v170
	v_ashrrev_i32_e32 v217, 31, v216
	v_lshl_add_u64 v[218:219], v[216:217], 2, s[6:7]
	v_sub_u32_e32 v216, v216, v174
	v_add_u32_e32 v222, v216, v176
	v_ashrrev_i32_e32 v223, 31, v222
	v_lshlrev_b64 v[216:217], 12, v[222:223]
	v_lshl_add_u64 v[224:225], v[216:217], 0, s[16:17]
	global_load_dword v228, v[218:219], off
	v_lshl_add_u64 v[218:219], s[8:9], 0, v[216:217]
	v_lshl_add_u64 v[220:221], s[8:9], 0, v[224:225]
	v_lshl_add_u64 v[216:217], s[10:11], 0, v[216:217]
	v_lshl_add_u64 v[218:219], v[218:219], 0, v[164:165]
	v_lshl_add_u64 v[220:221], v[220:221], 0, v[164:165]
	v_lshl_add_u64 v[216:217], v[216:217], 0, v[164:165]
	global_load_dwordx4 v[232:235], v[218:219], off
	global_load_dwordx4 v[236:239], v[220:221], off
	global_load_dwordx4 v[240:243], v[216:217], off
	v_lshl_add_u64 v[216:217], s[10:11], 0, v[224:225]
	v_lshl_add_u64 v[216:217], v[216:217], 0, v[164:165]
	global_load_dwordx4 v[244:247], v[216:217], off
	v_mul_f32_e32 v141, 0xbfb8aa3b, v141
	v_mul_f32_e32 v136, 0xbfb8aa3b, v136
	v_mul_f32_e32 v137, 0xbfb8aa3b, v137
	v_exp_f32_e32 v141, v141
	v_mul_f32_e32 v142, 0xbfb8aa3b, v142
	v_exp_f32_e32 v136, v136
	v_exp_f32_e32 v137, v137
	v_exp_f32_e32 v142, v142
	v_mul_f32_e32 v143, 0xbfb8aa3b, v143
	v_exp_f32_e32 v143, v143
	v_mov_b32_e32 v200, 0
	v_mov_b32_e32 v204, 0
	v_mov_b32_e32 v213, 0
	v_mov_b32_e32 v183, 0
	v_add_f32_e32 v141, 1.0, v141
	v_add_f32_e32 v136, 1.0, v136
	v_add_f32_e32 v137, 1.0, v137
	v_mov_b32_e32 v201, 0
	v_mov_b32_e32 v203, 0
	v_mov_b32_e32 v205, 0
	v_mov_b32_e32 v206, 0
	v_rcp_f32_e32 v136, v136
	v_rcp_f32_e32 v137, v137
	v_mov_b32_e32 v202, 0
	v_mul_f32_e32 v138, 0xbfb8aa3b, v138
	v_mul_f32_e32 v139, 0xbfb8aa3b, v139
	v_mov_b32_e32 v211, 0
	v_exp_f32_e32 v138, v138
	v_exp_f32_e32 v139, v139
	v_mov_b32_e32 v207, 0
	v_mov_b32_e32 v214, 0
	v_mov_b32_e32 v210, 0
	v_add_f32_e32 v138, 1.0, v138
	v_add_f32_e32 v139, 1.0, v139
	v_rcp_f32_e32 v138, v138
	v_rcp_f32_e32 v139, v139
	v_mov_b32_e32 v212, 0
	v_mov_b32_e32 v208, 0
	v_mul_f32_e32 v128, 0xbfb8aa3b, v128
	v_mul_f32_e32 v129, 0xbfb8aa3b, v129
	v_exp_f32_e32 v128, v128
	v_exp_f32_e32 v129, v129
	v_mul_f32_e32 v132, 0xbfb8aa3b, v132
	v_mul_f32_e32 v133, 0xbfb8aa3b, v133
	v_mov_b32_e32 v209, 0
	v_exp_f32_e32 v132, v132
	v_exp_f32_e32 v133, v133
	v_lshlrev_b64 v[172:173], 13, v[172:173]
	v_add_f32_e32 v128, 1.0, v128
	v_add_f32_e32 v129, 1.0, v129
	v_lshl_add_u64 v[172:173], s[4:5], 0, v[172:173]
	v_rcp_f32_e32 v128, v128
	v_mul_f32_e32 v130, 0xbfb8aa3b, v130
	v_mul_f32_e32 v131, 0xbfb8aa3b, v131
	v_rcp_f32_e32 v129, v129
	v_lshl_add_u64 v[172:173], v[172:173], 0, v[166:167]
	v_exp_f32_e32 v130, v130
	v_exp_f32_e32 v131, v131
	v_lshl_add_u64 v[172:173], v[172:173], 0, v[156:157]
	s_waitcnt vmcnt(5)
; __device__ __forceinline__ float bflo(unsigned w) { return __uint_as_float(w << 16); }
; __device__ __forceinline__ float bfhi(unsigned w) { return __uint_as_float(w & 0xffff0000u); }
; __device__ __forceinline__ unsigned dpp_ror8(unsigned x) { return (unsigned)__builtin_amdgcn_update_dpp(0, (int)x, 0x128, 0xf, 0xf, false); }
;     __device__ __forceinline__ void operator()(const f32x4 (&acc)[2][2][4][2], const Unit& u, int wr, int wc, int fr, int fq) const {
;     ...
;         for (int ai = 0; ai < 2; ++ai)
; #pragma unroll
;             for (int m = 0; m < 4; ++m) { const int row = row0 + ai * HALF + m * 16; const float ri = __builtin_amdgcn_rsqf(sse[row] * (1.f / D) + EPS);
;                 u32x4 rr[2], ee[2]; load_pair_lines(R, D, row, fr, col0, rr[0], rr[1], 32); load_pair_lines(E, D, row, fr, col0, ee[0], ee[1], 32);
;                 float* orow = OUT + (size_t)(row - fr + (fr & 7)) * D + col0 + (lo ? 0 : 4);
; #pragma unroll
;                 for (int bj = 0; bj < 2; ++bj) { const u32x4 rw = rr[bj], ew = ee[bj];
;                     const float r[8] = {bflo(rw.x), bfhi(rw.x), bflo(rw.y), bfhi(rw.y), bflo(rw.z), bfhi(rw.z), bflo(rw.w), bfhi(rw.w)};
;                     const float e[8] = {bflo(ew.x), bfhi(ew.x), bflo(ew.y), bfhi(ew.y), bflo(ew.z), bfhi(ew.z), bflo(ew.w), bfhi(ew.w)};
;                     float o[8];
; #pragma unroll
;                     for (int j = 0; j < 8; ++j) { const float a = acc[ai][bj][m][j >> 2][j & 3]; const float gg = gv[bj][j >> 2][j & 3];
;                         o[j] = r[j] + e[j] * ri * gg * __builtin_amdgcn_rcpf(1.f + __builtin_amdgcn_exp2f(-a * LOG2E)); }
;                     f32x4 o1, o2;
; #pragma unroll
;                     for (int j = 0; j < 4; ++j) { const unsigned a = __float_as_uint(o[j]), b = __float_as_uint(o[4 + j]); const unsigned sa = dpp_ror8(a), sb = dpp_ror8(b);
;                         o1[j] = __uint_as_float(lo ? a : sb); o2[j] = __uint_as_float(lo ? sa : b); }
;                     *(f32x4*)(orow + 32 * bj) = o1; *(f32x4*)(orow + (size_t)8 * D + 32 * bj) = o2; } }
	v_fmamk_f32 v140, v171, 0x3a000000, v182
	v_rsq_f32_e32 v140, v140
	v_mov_b32_dpp v200, v185 row_ror:8 row_mask:0xf bank_mask:0xf
	v_mov_b32_dpp v183, v184 row_ror:8 row_mask:0xf bank_mask:0xf
	v_mov_b32_dpp v201, v186 row_ror:8 row_mask:0xf bank_mask:0xf
	v_mov_b32_dpp v202, v187 row_ror:8 row_mask:0xf bank_mask:0xf
	v_add_f32_e32 v132, 1.0, v132
	v_add_f32_e32 v133, 1.0, v133
	v_rcp_f32_e32 v132, v132
	v_mul_f32_e32 v134, 0xbfb8aa3b, v134
	v_mul_f32_e32 v135, 0xbfb8aa3b, v135
	v_mov_b32_dpp v204, v189 row_ror:8 row_mask:0xf bank_mask:0xf
	v_cndmask_b32_e64 v171, v189, v200, s[0:1]
	v_mov_b32_dpp v213, v198 row_ror:8 row_mask:0xf bank_mask:0xf
	v_cndmask_b32_e64 v200, v204, v185, s[0:1]
	v_cndmask_b32_e64 v189, v213, v194, s[0:1]
	v_rcp_f32_e32 v185, v141
	v_add_f32_e32 v141, 1.0, v142
	v_mov_b32_dpp v203, v188 row_ror:8 row_mask:0xf bank_mask:0xf
	v_mov_b32_dpp v205, v190 row_ror:8 row_mask:0xf bank_mask:0xf
	v_mov_b32_dpp v206, v191 row_ror:8 row_mask:0xf bank_mask:0xf
	v_cndmask_b32_e64 v183, v188, v183, s[0:1]
	v_rcp_f32_e32 v142, v141
	v_add_f32_e32 v141, 1.0, v143
	v_lshlrev_b32_e32 v188, 16, v189
	v_and_b32_e32 v189, 0xffff0000, v189
	v_cndmask_b32_e64 v190, v190, v201, s[0:1]
	v_cndmask_b32_e64 v201, v206, v187, s[0:1]
	v_cndmask_b32_e64 v187, v205, v186, s[0:1]
	v_pk_mul_f32 v[188:189], v[140:141], v[188:189] op_sel_hi:[0,1]
	v_cndmask_b32_e64 v191, v191, v202, s[0:1]
	v_mov_b32_dpp v211, v196 row_ror:8 row_mask:0xf bank_mask:0xf
	v_cndmask_b32_e64 v202, v203, v184, s[0:1]
	v_add_f32_e32 v184, 1.0, v215
	v_lshlrev_b32_e32 v186, 16, v187
	v_and_b32_e32 v187, 0xffff0000, v187
	v_pk_mul_f32 v[188:189], v[60:61], v[188:189]
	v_mov_b32_dpp v207, v192 row_ror:8 row_mask:0xf bank_mask:0xf
	v_cndmask_b32_e64 v192, v211, v192, s[0:1]
	v_rcp_f32_e32 v184, v184
	v_rcp_f32_e32 v143, v141
	v_pk_fma_f32 v[188:189], v[136:137], v[188:189], v[186:187]
	v_mov_b32_e32 v141, v157
	v_lshlrev_b32_e32 v186, 16, v192
	v_and_b32_e32 v187, 0xffff0000, v192
	v_mov_b32_dpp v141, v188 row_ror:8 row_mask:0xf bank_mask:0xf
	v_mov_b32_dpp v214, v199 row_ror:8 row_mask:0xf bank_mask:0xf
	v_pk_mul_f32 v[186:187], v[140:141], v[186:187] op_sel_hi:[0,1]
	v_mov_b32_dpp v210, v195 row_ror:8 row_mask:0xf bank_mask:0xf
	v_cndmask_b32_e64 v195, v214, v195, s[0:1]
	v_lshlrev_b32_e32 v136, 16, v202
	v_and_b32_e32 v137, 0xffff0000, v202
	v_pk_mul_f32 v[186:187], v[56:57], v[186:187]
	v_mov_b32_dpp v212, v197 row_ror:8 row_mask:0xf bank_mask:0xf
	v_pk_fma_f32 v[136:137], v[184:185], v[186:187], v[136:137]
	v_lshlrev_b32_e32 v186, 16, v195
	v_and_b32_e32 v187, 0xffff0000, v195
	v_pk_mul_f32 v[186:187], v[140:141], v[186:187] op_sel_hi:[0,1]
	v_mov_b32_dpp v208, v193 row_ror:8 row_mask:0xf bank_mask:0xf
	v_cndmask_b32_e64 v193, v212, v193, s[0:1]
	v_lshlrev_b32_e32 v184, 16, v201
	v_and_b32_e32 v185, 0xffff0000, v201
	v_pk_mul_f32 v[186:187], v[62:63], v[186:187]
	v_mov_b32_dpp v209, v194 row_ror:8 row_mask:0xf bank_mask:0xf
	v_pk_fma_f32 v[184:185], v[138:139], v[186:187], v[184:185]
	v_lshlrev_b32_e32 v186, 16, v193
	v_and_b32_e32 v187, 0xffff0000, v193
	v_pk_mul_f32 v[186:187], v[140:141], v[186:187] op_sel_hi:[0,1]
	v_lshlrev_b32_e32 v138, 16, v200
	v_and_b32_e32 v139, 0xffff0000, v200
	v_pk_mul_f32 v[186:187], v[58:59], v[186:187]
	v_cndmask_b32_e64 v194, v197, v208, s[0:1]
	v_pk_fma_f32 v[138:139], v[142:143], v[186:187], v[138:139]
	v_mov_b32_e32 v142, v157
	v_mov_b32_e32 v143, v157
	v_cndmask_b32_e64 v197, v199, v210, s[0:1]
	v_cndmask_b32_e64 v198, v198, v209, s[0:1]
	v_mov_b32_e32 v199, v157
	v_mov_b32_e32 v195, v157
	v_mov_b32_e32 v201, v157
	v_mov_b32_dpp v142, v138 row_ror:8 row_mask:0xf bank_mask:0xf
	v_mov_b32_dpp v143, v139 row_ror:8 row_mask:0xf bank_mask:0xf
	v_mov_b32_dpp v199, v189 row_ror:8 row_mask:0xf bank_mask:0xf
	v_mov_b32_e32 v192, v157
	v_mov_b32_e32 v202, v157
	v_mov_b32_dpp v195, v184 row_ror:8 row_mask:0xf bank_mask:0xf
	v_mov_b32_dpp v201, v185 row_ror:8 row_mask:0xf bank_mask:0xf
	v_cndmask_b32_e64 v187, v185, v143, s[0:1]
	v_cndmask_b32_e64 v186, v184, v142, s[0:1]
	v_lshlrev_b32_e32 v142, 16, v198
	v_and_b32_e32 v143, 0xffff0000, v198
	v_mov_b32_dpp v192, v136 row_ror:8 row_mask:0xf bank_mask:0xf
	v_mov_b32_dpp v202, v137 row_ror:8 row_mask:0xf bank_mask:0xf
	v_cndmask_b32_e64 v139, v201, v139, s[0:1]
	v_cndmask_b32_e64 v138, v195, v138, s[0:1]
	v_cndmask_b32_e64 v137, v199, v137, s[0:1]
	v_cndmask_b32_e64 v136, v141, v136, s[0:1]
	v_pk_mul_f32 v[142:143], v[140:141], v[142:143] op_sel_hi:[0,1]
	v_cndmask_b32_e64 v196, v196, v207, s[0:1]
	global_store_dwordx4 v[172:173], v[136:139], off
	v_rcp_f32_e32 v133, v133
	v_pk_mul_f32 v[142:143], v[44:45], v[142:143]
	v_lshlrev_b32_e32 v138, 16, v190
	v_and_b32_e32 v139, 0xffff0000, v190
	v_exp_f32_e32 v134, v134
	v_exp_f32_e32 v135, v135
	v_pk_fma_f32 v[138:139], v[128:129], v[142:143], v[138:139]
	v_lshlrev_b32_e32 v142, 16, v196
	v_and_b32_e32 v143, 0xffff0000, v196
	v_add_f32_e32 v130, 1.0, v130
	v_add_f32_e32 v131, 1.0, v131
	v_pk_mul_f32 v[142:143], v[140:141], v[142:143] op_sel_hi:[0,1]
	v_rcp_f32_e32 v130, v130
	v_rcp_f32_e32 v131, v131
	v_lshlrev_b32_e32 v128, 16, v183
	v_and_b32_e32 v129, 0xffff0000, v183
	v_pk_mul_f32 v[142:143], v[40:41], v[142:143]
	v_add_f32_e32 v134, 1.0, v134
	v_pk_fma_f32 v[128:129], v[132:133], v[142:143], v[128:129]
	v_lshlrev_b32_e32 v142, 16, v197
	v_and_b32_e32 v143, 0xffff0000, v197
	v_add_f32_e32 v135, 1.0, v135
	v_pk_mul_f32 v[142:143], v[140:141], v[142:143] op_sel_hi:[0,1]
	v_rcp_f32_e32 v134, v134
	v_rcp_f32_e32 v135, v135
	v_lshlrev_b32_e32 v132, 16, v191
	v_and_b32_e32 v133, 0xffff0000, v191
	v_pk_mul_f32 v[142:143], v[46:47], v[142:143]
; __device__ __forceinline__ float bflo(unsigned w) { return __uint_as_float(w << 16); }
; __device__ __forceinline__ float bfhi(unsigned w) { return __uint_as_float(w & 0xffff0000u); }
; __device__ __forceinline__ unsigned dpp_ror8(unsigned x) { return (unsigned)__builtin_amdgcn_update_dpp(0, (int)x, 0x128, 0xf, 0xf, false); }
;     __device__ __forceinline__ void operator()(const f32x4 (&acc)[2][2][4][2], const Unit& u, int wr, int wc, int fr, int fq) const {
;     ...
;         for (int ai = 0; ai < 2; ++ai)
; #pragma unroll
;             for (int m = 0; m < 4; ++m) { const int row = row0 + ai * HALF + m * 16; const float ri = __builtin_amdgcn_rsqf(sse[row] * (1.f / D) + EPS);
;                 u32x4 rr[2], ee[2]; load_pair_lines(R, D, row, fr, col0, rr[0], rr[1], 32); load_pair_lines(E, D, row, fr, col0, ee[0], ee[1], 32);
;                 float* orow = OUT + (size_t)(row - fr + (fr & 7)) * D + col0 + (lo ? 0 : 4);
; #pragma unroll
;                 for (int bj = 0; bj < 2; ++bj) { const u32x4 rw = rr[bj], ew = ee[bj];
;                     const float r[8] = {bflo(rw.x), bfhi(rw.x), bflo(rw.y), bfhi(rw.y), bflo(rw.z), bfhi(rw.z), bflo(rw.w), bfhi(rw.w)};
;                     const float e[8] = {bflo(ew.x), bfhi(ew.x), bflo(ew.y), bfhi(ew.y), bflo(ew.z), bfhi(ew.z), bflo(ew.w), bfhi(ew.w)};
;                     float o[8];
; #pragma unroll
;                     for (int j = 0; j < 8; ++j) { const float a = acc[ai][bj][m][j >> 2][j & 3]; const float gg = gv[bj][j >> 2][j & 3];
;                         o[j] = r[j] + e[j] * ri * gg * __builtin_amdgcn_rcpf(1.f + __builtin_amdgcn_exp2f(-a * LOG2E)); }
;                     f32x4 o1, o2;
; #pragma unroll
;                     for (int j = 0; j < 4; ++j) { const unsigned a = __float_as_uint(o[j]), b = __float_as_uint(o[4 + j]); const unsigned sa = dpp_ror8(a), sb = dpp_ror8(b);
;                         o1[j] = __uint_as_float(lo ? a : sb); o2[j] = __uint_as_float(lo ? sa : b); }
;                     *(f32x4*)(orow + 32 * bj) = o1; *(f32x4*)(orow + (size_t)8 * D + 32 * bj) = o2; } }
	v_add_co_u32_e32 v136, vcc, s45, v172
	v_pk_fma_f32 v[132:133], v[130:131], v[142:143], v[132:133]
	v_lshlrev_b32_e32 v142, 16, v194
	v_and_b32_e32 v143, 0xffff0000, v194
	v_cndmask_b32_e64 v185, v189, v202, s[0:1]
	v_cndmask_b32_e64 v184, v188, v192, s[0:1]
	v_addc_co_u32_e32 v137, vcc, 0, v173, vcc
	v_pk_mul_f32 v[140:141], v[140:141], v[142:143] op_sel_hi:[0,1]
	global_store_dwordx4 v[136:137], v[184:187], off
	v_mov_b32_e32 v188, v157
	v_lshlrev_b32_e32 v130, 16, v171
	v_mov_b32_e32 v184, v157
	v_mov_b32_e32 v185, v157
	v_mov_b32_e32 v187, v157
	v_and_b32_e32 v131, 0xffff0000, v171
	v_pk_mul_f32 v[140:141], v[42:43], v[140:141]
	v_mov_b32_dpp v184, v138 row_ror:8 row_mask:0xf bank_mask:0xf
	v_mov_b32_dpp v185, v139 row_ror:8 row_mask:0xf bank_mask:0xf
	v_mov_b32_e32 v183, v157
	v_mov_b32_e32 v186, v157
	v_mov_b32_dpp v187, v132 row_ror:8 row_mask:0xf bank_mask:0xf
	v_mov_b32_dpp v188, v133 row_ror:8 row_mask:0xf bank_mask:0xf
	v_pk_fma_f32 v[130:131], v[134:135], v[140:141], v[130:131]
	v_mov_b32_e32 v134, v157
	v_mov_b32_e32 v135, v157
	v_mov_b32_dpp v183, v128 row_ror:8 row_mask:0xf bank_mask:0xf
	v_mov_b32_dpp v186, v129 row_ror:8 row_mask:0xf bank_mask:0xf
	v_mov_b32_dpp v134, v130 row_ror:8 row_mask:0xf bank_mask:0xf
	v_mov_b32_dpp v135, v131 row_ror:8 row_mask:0xf bank_mask:0xf
	v_cndmask_b32_e64 v131, v188, v131, s[0:1]
	v_cndmask_b32_e64 v130, v187, v130, s[0:1]
	v_cndmask_b32_e64 v129, v185, v129, s[0:1]
	v_cndmask_b32_e64 v128, v184, v128, s[0:1]
	v_cndmask_b32_e64 v135, v133, v135, s[0:1]
	v_cndmask_b32_e64 v134, v132, v134, s[0:1]
	v_cndmask_b32_e64 v133, v139, v186, s[0:1]
	v_cndmask_b32_e64 v132, v138, v183, s[0:1]
	global_store_dwordx4 v[172:173], v[128:131], off offset:128
	global_store_dwordx4 v[136:137], v[132:135], off offset:128
	v_mov_b32_e32 v183, v157
	v_or_b32_e32 v128, 16, v170
	v_ashrrev_i32_e32 v129, 31, v128
	v_lshl_add_u64 v[130:131], v[128:129], 2, s[6:7]
	v_sub_u32_e32 v128, v128, v174
	v_add_u32_e32 v142, v128, v176
	v_ashrrev_i32_e32 v143, 31, v142
	v_lshlrev_b64 v[128:129], 12, v[142:143]
	v_lshl_add_u64 v[172:173], v[128:129], 0, s[16:17]
	s_waitcnt vmcnt(4)
	s_nop 0
	v_mov_b32_e32 v171, v228
	v_lshl_add_u64 v[130:131], s[8:9], 0, v[128:129]
	v_lshl_add_u64 v[134:135], s[8:9], 0, v[172:173]
	v_lshl_add_u64 v[128:129], s[10:11], 0, v[128:129]
	v_lshl_add_u64 v[130:131], v[130:131], 0, v[164:165]
	v_lshl_add_u64 v[134:135], v[134:135], 0, v[164:165]
	v_lshl_add_u64 v[128:129], v[128:129], 0, v[164:165]
	v_mov_b64_e32 v[130:131], v[232:233]
	v_mov_b64_e32 v[132:133], v[234:235]
	v_mov_b32_e32 v189, v157
	v_mov_b64_e32 v[134:135], v[236:237]
	v_mov_b64_e32 v[136:137], v[238:239]
	v_mov_b32_e32 v190, v157
	v_mov_b64_e32 v[138:139], v[240:241]
	v_mov_b64_e32 v[140:141], v[242:243]
	v_lshl_add_u64 v[128:129], s[10:11], 0, v[172:173]
	v_lshl_add_u64 v[128:129], v[128:129], 0, v[164:165]
	v_mov_b64_e32 v[184:185], v[244:245]
	v_mov_b64_e32 v[186:187], v[246:247]
	s_nop 1
	v_or_b32_e32 v216, 32, v170
	v_ashrrev_i32_e32 v217, 31, v216
	v_lshl_add_u64 v[218:219], v[216:217], 2, s[6:7]
	v_sub_u32_e32 v216, v216, v174
	v_add_u32_e32 v224, v216, v176
	v_ashrrev_i32_e32 v225, 31, v224
	v_lshlrev_b64 v[216:217], 12, v[224:225]
	v_lshl_add_u64 v[222:223], v[216:217], 0, s[16:17]
	v_lshl_add_u64 v[220:221], s[8:9], 0, v[222:223]
	global_load_dword v228, v[218:219], off
	v_lshl_add_u64 v[218:219], s[8:9], 0, v[216:217]
	v_lshl_add_u64 v[220:221], v[220:221], 0, v[164:165]
	v_lshl_add_u64 v[216:217], s[10:11], 0, v[216:217]
	v_lshl_add_u64 v[218:219], v[218:219], 0, v[164:165]
	global_load_dwordx4 v[232:235], v[220:221], off
	v_lshl_add_u64 v[216:217], v[216:217], 0, v[164:165]
	global_load_dwordx4 v[236:239], v[218:219], off
	global_load_dwordx4 v[240:243], v[216:217], off
	v_lshl_add_u64 v[216:217], s[10:11], 0, v[222:223]
	v_lshl_add_u64 v[216:217], v[216:217], 0, v[164:165]
	global_load_dwordx4 v[244:247], v[216:217], off
	v_mov_b32_e32 v173, v157
	v_mov_b32_e32 v129, v157
	v_mov_b32_e32 v172, v157
	v_mov_b32_e32 v188, v157
	v_mul_f32_e32 v120, 0xbfb8aa3b, v120
	v_mul_f32_e32 v121, 0xbfb8aa3b, v121
	v_mul_f32_e32 v124, 0xbfb8aa3b, v124
	v_exp_f32_e32 v120, v120
	v_exp_f32_e32 v121, v121
	v_mul_f32_e32 v122, 0xbfb8aa3b, v122
	v_mul_f32_e32 v123, 0xbfb8aa3b, v123
	v_add_f32_e32 v120, 1.0, v120
	v_add_f32_e32 v121, 1.0, v121
	v_rcp_f32_e32 v120, v120
	v_rcp_f32_e32 v121, v121
	v_exp_f32_e32 v122, v122
	v_exp_f32_e32 v123, v123
	v_mul_f32_e32 v126, 0xbfb8aa3b, v126
	v_mul_f32_e32 v127, 0xbfb8aa3b, v127
	v_exp_f32_e32 v126, v126
	v_exp_f32_e32 v127, v127
	v_add_f32_e32 v122, 1.0, v122
	v_add_f32_e32 v123, 1.0, v123
	v_rcp_f32_e32 v122, v122
	v_rcp_f32_e32 v123, v123
	v_add_f32_e32 v126, 1.0, v126
	v_add_f32_e32 v127, 1.0, v127
	v_mul_f32_e32 v112, 0xbfb8aa3b, v112
	v_mul_f32_e32 v113, 0xbfb8aa3b, v113
	v_rcp_f32_e32 v126, v126
	v_rcp_f32_e32 v127, v127
	v_exp_f32_e32 v112, v112
	v_exp_f32_e32 v113, v113
	v_mul_f32_e32 v116, 0xbfb8aa3b, v116
	v_mul_f32_e32 v117, 0xbfb8aa3b, v117
	v_exp_f32_e32 v116, v116
	v_exp_f32_e32 v117, v117
	v_add_f32_e32 v112, 1.0, v112
	v_add_f32_e32 v113, 1.0, v113
	v_rcp_f32_e32 v112, v112
	v_rcp_f32_e32 v113, v113
	v_mul_f32_e32 v114, 0xbfb8aa3b, v114
	v_mul_f32_e32 v115, 0xbfb8aa3b, v115
	v_add_f32_e32 v116, 1.0, v116
	v_add_f32_e32 v117, 1.0, v117
	v_exp_f32_e32 v114, v114
	v_exp_f32_e32 v115, v115
	v_rcp_f32_e32 v116, v116
	v_rcp_f32_e32 v117, v117
	v_mul_f32_e32 v118, 0xbfb8aa3b, v118
	v_mul_f32_e32 v119, 0xbfb8aa3b, v119
	v_exp_f32_e32 v118, v118
	v_exp_f32_e32 v119, v119
	v_add_f32_e32 v114, 1.0, v114
	v_add_f32_e32 v115, 1.0, v115
	v_rcp_f32_e32 v114, v114
	v_rcp_f32_e32 v115, v115
; __device__ __forceinline__ float bflo(unsigned w) { return __uint_as_float(w << 16); }
; __device__ __forceinline__ float bfhi(unsigned w) { return __uint_as_float(w & 0xffff0000u); }
; __device__ __forceinline__ unsigned dpp_ror8(unsigned x) { return (unsigned)__builtin_amdgcn_update_dpp(0, (int)x, 0x128, 0xf, 0xf, false); }
;     __device__ __forceinline__ void operator()(const f32x4 (&acc)[2][2][4][2], const Unit& u, int wr, int wc, int fr, int fq) const {
;     ...
;         for (int ai = 0; ai < 2; ++ai)
; #pragma unroll
;             for (int m = 0; m < 4; ++m) { const int row = row0 + ai * HALF + m * 16; const float ri = __builtin_amdgcn_rsqf(sse[row] * (1.f / D) + EPS);
;                 u32x4 rr[2], ee[2]; load_pair_lines(R, D, row, fr, col0, rr[0], rr[1], 32); load_pair_lines(E, D, row, fr, col0, ee[0], ee[1], 32);
;                 float* orow = OUT + (size_t)(row - fr + (fr & 7)) * D + col0 + (lo ? 0 : 4);
; #pragma unroll
;                 for (int bj = 0; bj < 2; ++bj) { const u32x4 rw = rr[bj], ew = ee[bj];
;                     const float r[8] = {bflo(rw.x), bfhi(rw.x), bflo(rw.y), bfhi(rw.y), bflo(rw.z), bfhi(rw.z), bflo(rw.w), bfhi(rw.w)};
;                     const float e[8] = {bflo(ew.x), bfhi(ew.x), bflo(ew.y), bfhi(ew.y), bflo(ew.z), bfhi(ew.z), bflo(ew.w), bfhi(ew.w)};
;                     float o[8];
; #pragma unroll
;                     for (int j = 0; j < 8; ++j) { const float a = acc[ai][bj][m][j >> 2][j & 3]; const float gg = gv[bj][j >> 2][j & 3];
;                         o[j] = r[j] + e[j] * ri * gg * __builtin_amdgcn_rcpf(1.f + __builtin_amdgcn_exp2f(-a * LOG2E)); }
;                     f32x4 o1, o2;
; #pragma unroll
;                     for (int j = 0; j < 4; ++j) { const unsigned a = __float_as_uint(o[j]), b = __float_as_uint(o[4 + j]); const unsigned sa = dpp_ror8(a), sb = dpp_ror8(b);
;                         o1[j] = __uint_as_float(lo ? a : sb); o2[j] = __uint_as_float(lo ? sa : b); }
;                     *(f32x4*)(orow + 32 * bj) = o1; *(f32x4*)(orow + (size_t)8 * D + 32 * bj) = o2; } }
	v_add_f32_e32 v118, 1.0, v118
	v_add_f32_e32 v119, 1.0, v119
	v_rcp_f32_e32 v118, v118
	v_rcp_f32_e32 v119, v119
	v_mul_f32_e32 v104, 0xbfb8aa3b, v104
	v_mul_f32_e32 v105, 0xbfb8aa3b, v105
	v_mul_f32_e32 v108, 0xbfb8aa3b, v108
	v_exp_f32_e32 v104, v104
	v_fmamk_f32 v128, v171, 0x3a000000, v182
	v_mov_b32_e32 v171, v157
	v_rsq_f32_e32 v128, v128
	v_exp_f32_e32 v105, v105
	v_add_f32_e32 v104, 1.0, v104
	v_rcp_f32_e32 v104, v104
	v_mul_f32_e32 v106, 0xbfb8aa3b, v106
	v_mov_b32_dpp v171, v131 row_ror:8 row_mask:0xf bank_mask:0xf
	v_mov_b32_dpp v173, v133 row_ror:8 row_mask:0xf bank_mask:0xf
	v_mov_b32_dpp v183, v134 row_ror:8 row_mask:0xf bank_mask:0xf
	v_mov_b32_dpp v189, v136 row_ror:8 row_mask:0xf bank_mask:0xf
	v_mov_b32_dpp v190, v137 row_ror:8 row_mask:0xf bank_mask:0xf
	v_mov_b32_dpp v129, v130 row_ror:8 row_mask:0xf bank_mask:0xf
	v_mov_b32_dpp v172, v132 row_ror:8 row_mask:0xf bank_mask:0xf
	v_mov_b32_dpp v188, v135 row_ror:8 row_mask:0xf bank_mask:0xf
	v_cndmask_b32_e64 v190, v190, v133, s[0:1]
	v_cndmask_b32_e64 v183, v183, v130, s[0:1]
	v_cndmask_b32_e64 v133, v189, v132, s[0:1]
	v_cndmask_b32_e64 v171, v135, v171, s[0:1]
	v_cndmask_b32_e64 v137, v137, v173, s[0:1]
	v_mov_b32_e32 v130, v157
	v_mov_b32_e32 v132, v157
	v_mov_b32_e32 v135, v157
	v_mov_b32_e32 v173, v157
	v_cndmask_b32_e64 v129, v134, v129, s[0:1]
	v_cndmask_b32_e64 v136, v136, v172, s[0:1]
	v_mov_b32_dpp v130, v138 row_ror:8 row_mask:0xf bank_mask:0xf
	v_mov_b32_dpp v132, v140 row_ror:8 row_mask:0xf bank_mask:0xf
	v_mov_b32_e32 v134, v157
	v_mov_b32_dpp v135, v184 row_ror:8 row_mask:0xf bank_mask:0xf
	v_mov_b32_e32 v172, v157
	v_mov_b32_dpp v173, v186 row_ror:8 row_mask:0xf bank_mask:0xf
	v_cndmask_b32_e64 v188, v188, v131, s[0:1]
	v_mov_b32_e32 v131, v157
	v_mov_b32_dpp v134, v141 row_ror:8 row_mask:0xf bank_mask:0xf
	v_mov_b32_dpp v172, v185 row_ror:8 row_mask:0xf bank_mask:0xf
	v_cndmask_b32_e64 v138, v135, v138, s[0:1]
	v_cndmask_b32_e64 v135, v173, v140, s[0:1]
	v_cndmask_b32_e64 v173, v184, v130, s[0:1]
	v_cndmask_b32_e64 v184, v186, v132, s[0:1]
	v_exp_f32_e32 v132, v124
	v_mul_f32_e32 v124, 0xbfb8aa3b, v125
	v_mov_b32_dpp v131, v139 row_ror:8 row_mask:0xf bank_mask:0xf
	v_cndmask_b32_e64 v139, v172, v139, s[0:1]
	v_cndmask_b32_e64 v172, v187, v134, s[0:1]
	v_exp_f32_e32 v134, v124
	v_cndmask_b32_e64 v140, v185, v131, s[0:1]
	v_lshlrev_b64 v[130:131], 13, v[142:143]
	v_lshl_add_u64 v[130:131], s[4:5], 0, v[130:131]
	v_lshl_add_u64 v[130:131], v[130:131], 0, v[166:167]
	v_lshl_add_u64 v[124:125], v[130:131], 0, v[156:157]
	v_add_f32_e32 v131, 1.0, v134
	v_lshlrev_b32_e32 v134, 16, v135
	v_and_b32_e32 v135, 0xffff0000, v135
	v_add_f32_e32 v130, 1.0, v132
	v_pk_mul_f32 v[134:135], v[128:129], v[134:135] op_sel_hi:[0,1]
	v_rcp_f32_e32 v130, v130
	v_rcp_f32_e32 v131, v131
	v_lshlrev_b32_e32 v132, 16, v133
	v_and_b32_e32 v133, 0xffff0000, v133
	v_pk_mul_f32 v[134:135], v[60:61], v[134:135]
	v_mov_b32_e32 v189, v157
	v_pk_fma_f32 v[134:135], v[120:121], v[134:135], v[132:133]
	v_lshlrev_b32_e32 v132, 16, v138
	v_and_b32_e32 v133, 0xffff0000, v138
	v_mov_b32_dpp v189, v187 row_ror:8 row_mask:0xf bank_mask:0xf
	v_pk_mul_f32 v[132:133], v[128:129], v[132:133] op_sel_hi:[0,1]
	v_cndmask_b32_e64 v141, v189, v141, s[0:1]
	v_lshlrev_b32_e32 v120, 16, v183
	v_and_b32_e32 v121, 0xffff0000, v183
	v_pk_mul_f32 v[132:133], v[56:57], v[132:133]
	v_mov_b32_e32 v142, v157
	v_pk_fma_f32 v[120:121], v[130:131], v[132:133], v[120:121]
	v_lshlrev_b32_e32 v132, 16, v141
	v_and_b32_e32 v133, 0xffff0000, v141
	v_pk_mul_f32 v[132:133], v[128:129], v[132:133] op_sel_hi:[0,1]
	v_lshlrev_b32_e32 v130, 16, v190
	v_and_b32_e32 v131, 0xffff0000, v190
	v_pk_mul_f32 v[132:133], v[62:63], v[132:133]
	v_mov_b32_e32 v143, v157
	v_pk_fma_f32 v[130:131], v[122:123], v[132:133], v[130:131]
	v_lshlrev_b32_e32 v132, 16, v139
	v_and_b32_e32 v133, 0xffff0000, v139
	v_pk_mul_f32 v[132:133], v[128:129], v[132:133] op_sel_hi:[0,1]
	v_lshlrev_b32_e32 v122, 16, v188
	v_and_b32_e32 v123, 0xffff0000, v188
	v_pk_mul_f32 v[132:133], v[58:59], v[132:133]
	v_mov_b32_e32 v141, v157
	v_pk_fma_f32 v[122:123], v[126:127], v[132:133], v[122:123]
	v_mov_b32_e32 v126, v157
	v_mov_b32_e32 v127, v157
	v_mov_b32_e32 v185, v157
	v_mov_b32_dpp v126, v122 row_ror:8 row_mask:0xf bank_mask:0xf
	v_mov_b32_dpp v127, v123 row_ror:8 row_mask:0xf bank_mask:0xf
	v_mov_b32_dpp v142, v134 row_ror:8 row_mask:0xf bank_mask:0xf
	v_mov_b32_dpp v143, v135 row_ror:8 row_mask:0xf bank_mask:0xf
	v_mov_b32_e32 v138, v157
	v_mov_b32_e32 v183, v157
	v_mov_b32_dpp v141, v130 row_ror:8 row_mask:0xf bank_mask:0xf
	v_mov_b32_dpp v185, v131 row_ror:8 row_mask:0xf bank_mask:0xf
	v_cndmask_b32_e64 v133, v131, v127, s[0:1]
	v_cndmask_b32_e64 v132, v130, v126, s[0:1]
	v_lshlrev_b32_e32 v126, 16, v184
	v_and_b32_e32 v127, 0xffff0000, v184
	v_mov_b32_dpp v138, v120 row_ror:8 row_mask:0xf bank_mask:0xf
	v_mov_b32_dpp v183, v121 row_ror:8 row_mask:0xf bank_mask:0xf
	v_cndmask_b32_e64 v123, v185, v123, s[0:1]
	v_cndmask_b32_e64 v122, v141, v122, s[0:1]
	v_cndmask_b32_e64 v121, v143, v121, s[0:1]
	v_cndmask_b32_e64 v120, v142, v120, s[0:1]
	v_pk_mul_f32 v[126:127], v[128:129], v[126:127] op_sel_hi:[0,1]
	global_store_dwordx4 v[124:125], v[120:123], off
	v_pk_mul_f32 v[126:127], v[44:45], v[126:127]
	v_cndmask_b32_e64 v131, v135, v183, s[0:1]
	v_lshlrev_b32_e32 v122, 16, v136
	v_and_b32_e32 v123, 0xffff0000, v136
	v_pk_fma_f32 v[122:123], v[112:113], v[126:127], v[122:123]
	v_lshlrev_b32_e32 v126, 16, v173
	v_and_b32_e32 v127, 0xffff0000, v173
	v_pk_mul_f32 v[126:127], v[128:129], v[126:127] op_sel_hi:[0,1]
	v_lshlrev_b32_e32 v112, 16, v129
	v_and_b32_e32 v113, 0xffff0000, v129
; __device__ __forceinline__ float bflo(unsigned w) { return __uint_as_float(w << 16); }
; __device__ __forceinline__ float bfhi(unsigned w) { return __uint_as_float(w & 0xffff0000u); }
; __device__ __forceinline__ unsigned dpp_ror8(unsigned x) { return (unsigned)__builtin_amdgcn_update_dpp(0, (int)x, 0x128, 0xf, 0xf, false); }
;     __device__ __forceinline__ void operator()(const f32x4 (&acc)[2][2][4][2], const Unit& u, int wr, int wc, int fr, int fq) const {
;     ...
;         for (int ai = 0; ai < 2; ++ai)
; #pragma unroll
;             for (int m = 0; m < 4; ++m) { const int row = row0 + ai * HALF + m * 16; const float ri = __builtin_amdgcn_rsqf(sse[row] * (1.f / D) + EPS);
;                 u32x4 rr[2], ee[2]; load_pair_lines(R, D, row, fr, col0, rr[0], rr[1], 32); load_pair_lines(E, D, row, fr, col0, ee[0], ee[1], 32);
;                 float* orow = OUT + (size_t)(row - fr + (fr & 7)) * D + col0 + (lo ? 0 : 4);
; #pragma unroll
;                 for (int bj = 0; bj < 2; ++bj) { const u32x4 rw = rr[bj], ew = ee[bj];
;                     const float r[8] = {bflo(rw.x), bfhi(rw.x), bflo(rw.y), bfhi(rw.y), bflo(rw.z), bfhi(rw.z), bflo(rw.w), bfhi(rw.w)};
;                     const float e[8] = {bflo(ew.x), bfhi(ew.x), bflo(ew.y), bfhi(ew.y), bflo(ew.z), bfhi(ew.z), bflo(ew.w), bfhi(ew.w)};
;                     float o[8];
; #pragma unroll
;                     for (int j = 0; j < 8; ++j) { const float a = acc[ai][bj][m][j >> 2][j & 3]; const float gg = gv[bj][j >> 2][j & 3];
;                         o[j] = r[j] + e[j] * ri * gg * __builtin_amdgcn_rcpf(1.f + __builtin_amdgcn_exp2f(-a * LOG2E)); }
;                     f32x4 o1, o2;
; #pragma unroll
;                     for (int j = 0; j < 4; ++j) { const unsigned a = __float_as_uint(o[j]), b = __float_as_uint(o[4 + j]); const unsigned sa = dpp_ror8(a), sb = dpp_ror8(b);
;                         o1[j] = __uint_as_float(lo ? a : sb); o2[j] = __uint_as_float(lo ? sa : b); }
;                     *(f32x4*)(orow + 32 * bj) = o1; *(f32x4*)(orow + (size_t)8 * D + 32 * bj) = o2; } }
	v_pk_mul_f32 v[126:127], v[40:41], v[126:127]
	v_mov_b32_e32 v129, v157
	v_pk_fma_f32 v[112:113], v[116:117], v[126:127], v[112:113]
	v_lshlrev_b32_e32 v126, 16, v172
	v_and_b32_e32 v127, 0xffff0000, v172
	v_mov_b32_dpp v129, v112 row_ror:8 row_mask:0xf bank_mask:0xf
	v_pk_mul_f32 v[126:127], v[128:129], v[126:127] op_sel_hi:[0,1]
	v_lshlrev_b32_e32 v116, 16, v137
	v_and_b32_e32 v117, 0xffff0000, v137
	v_pk_mul_f32 v[126:127], v[46:47], v[126:127]
	v_add_co_u32_e32 v120, vcc, s45, v124
	v_pk_fma_f32 v[116:117], v[114:115], v[126:127], v[116:117]
	v_lshlrev_b32_e32 v126, 16, v140
	v_and_b32_e32 v127, 0xffff0000, v140
	v_cndmask_b32_e64 v130, v134, v138, s[0:1]
	v_addc_co_u32_e32 v121, vcc, 0, v125, vcc
	v_pk_mul_f32 v[126:127], v[128:129], v[126:127] op_sel_hi:[0,1]
	global_store_dwordx4 v[120:121], v[130:133], off
	v_mov_b32_e32 v134, v157
	v_lshlrev_b32_e32 v114, 16, v171
	v_mov_b32_e32 v130, v157
	v_mov_b32_e32 v131, v157
	v_mov_b32_e32 v133, v157
	v_and_b32_e32 v115, 0xffff0000, v171
	v_pk_mul_f32 v[126:127], v[42:43], v[126:127]
	v_mov_b32_dpp v130, v122 row_ror:8 row_mask:0xf bank_mask:0xf
	v_mov_b32_dpp v131, v123 row_ror:8 row_mask:0xf bank_mask:0xf
	v_mov_b32_e32 v132, v157
	v_mov_b32_dpp v133, v116 row_ror:8 row_mask:0xf bank_mask:0xf
	v_mov_b32_dpp v134, v117 row_ror:8 row_mask:0xf bank_mask:0xf
	v_pk_fma_f32 v[114:115], v[118:119], v[126:127], v[114:115]
	v_mov_b32_e32 v118, v157
	v_mov_b32_e32 v119, v157
	v_mov_b32_dpp v132, v113 row_ror:8 row_mask:0xf bank_mask:0xf
	v_mov_b32_dpp v118, v114 row_ror:8 row_mask:0xf bank_mask:0xf
	v_mov_b32_dpp v119, v115 row_ror:8 row_mask:0xf bank_mask:0xf
	v_cndmask_b32_e64 v115, v134, v115, s[0:1]
	v_cndmask_b32_e64 v114, v133, v114, s[0:1]
	v_cndmask_b32_e64 v113, v131, v113, s[0:1]
	v_cndmask_b32_e64 v112, v130, v112, s[0:1]
	v_cndmask_b32_e64 v119, v117, v119, s[0:1]
	v_cndmask_b32_e64 v118, v116, v118, s[0:1]
	v_cndmask_b32_e64 v117, v123, v132, s[0:1]
	v_cndmask_b32_e64 v116, v122, v129, s[0:1]
	global_store_dwordx4 v[124:125], v[112:115], off offset:128
	global_store_dwordx4 v[120:121], v[116:119], off offset:128
	v_mov_b32_e32 v137, v157
	v_or_b32_e32 v112, 32, v170
	v_ashrrev_i32_e32 v113, 31, v112
	v_lshl_add_u64 v[114:115], v[112:113], 2, s[6:7]
	v_sub_u32_e32 v112, v112, v174
	v_add_u32_e32 v130, v112, v176
	v_ashrrev_i32_e32 v131, 31, v130
	v_lshlrev_b64 v[112:113], 12, v[130:131]
	v_lshl_add_u64 v[126:127], v[112:113], 0, s[16:17]
	v_lshl_add_u64 v[118:119], s[8:9], 0, v[126:127]
	s_waitcnt vmcnt(4)
	s_nop 0
	v_mov_b32_e32 v132, v228
	v_lshl_add_u64 v[114:115], s[8:9], 0, v[112:113]
	v_lshl_add_u64 v[118:119], v[118:119], 0, v[164:165]
	v_lshl_add_u64 v[112:113], s[10:11], 0, v[112:113]
	v_lshl_add_u64 v[114:115], v[114:115], 0, v[164:165]
	v_mov_b64_e32 v[118:119], v[232:233]
	v_mov_b64_e32 v[120:121], v[234:235]
	v_lshl_add_u64 v[112:113], v[112:113], 0, v[164:165]
	v_mov_b64_e32 v[114:115], v[236:237]
	v_mov_b64_e32 v[116:117], v[238:239]
	v_mov_b32_e32 v138, v157
	v_mov_b64_e32 v[122:123], v[240:241]
	v_mov_b64_e32 v[124:125], v[242:243]
	v_lshl_add_u64 v[112:113], s[10:11], 0, v[126:127]
	v_lshl_add_u64 v[112:113], v[112:113], 0, v[164:165]
	v_mov_b64_e32 v[126:127], v[244:245]
	v_mov_b64_e32 v[128:129], v[246:247]
	s_nop 1
	v_or_b32_e32 v216, 48, v170
	v_ashrrev_i32_e32 v217, 31, v216
	v_lshl_add_u64 v[218:219], v[216:217], 2, s[6:7]
	v_sub_u32_e32 v216, v216, v174
	v_add_u32_e32 v224, v216, v176
	v_ashrrev_i32_e32 v225, 31, v224
	v_lshlrev_b64 v[216:217], 12, v[224:225]
	v_lshl_add_u64 v[222:223], v[216:217], 0, s[16:17]
	v_lshl_add_u64 v[220:221], s[8:9], 0, v[222:223]
	global_load_dword v228, v[218:219], off
	v_lshl_add_u64 v[218:219], s[8:9], 0, v[216:217]
	v_lshl_add_u64 v[220:221], v[220:221], 0, v[164:165]
	v_lshl_add_u64 v[216:217], s[10:11], 0, v[216:217]
	v_lshl_add_u64 v[218:219], v[218:219], 0, v[164:165]
	global_load_dwordx4 v[232:235], v[220:221], off
	v_lshl_add_u64 v[216:217], v[216:217], 0, v[164:165]
	global_load_dwordx4 v[236:239], v[218:219], off
	global_load_dwordx4 v[240:243], v[216:217], off
	v_lshl_add_u64 v[216:217], s[10:11], 0, v[222:223]
	v_lshl_add_u64 v[216:217], v[216:217], 0, v[164:165]
	global_load_dwordx4 v[244:247], v[216:217], off
	v_mov_b32_e32 v113, v157
	v_mov_b32_e32 v133, v157
	v_mov_b32_e32 v134, v157
	v_mov_b32_e32 v136, v157
	v_mov_b32_e32 v135, v157
	v_add_f32_e32 v105, 1.0, v105
	v_mul_f32_e32 v107, 0xbfb8aa3b, v107
	v_rcp_f32_e32 v105, v105
	v_exp_f32_e32 v106, v106
	v_exp_f32_e32 v107, v107
	v_mul_f32_e32 v110, 0xbfb8aa3b, v110
	v_mul_f32_e32 v111, 0xbfb8aa3b, v111
	v_exp_f32_e32 v110, v110
	v_exp_f32_e32 v111, v111
	v_add_f32_e32 v106, 1.0, v106
	v_add_f32_e32 v107, 1.0, v107
	v_rcp_f32_e32 v106, v106
	v_rcp_f32_e32 v107, v107
	v_add_f32_e32 v110, 1.0, v110
	v_add_f32_e32 v111, 1.0, v111
	v_mul_f32_e32 v96, 0xbfb8aa3b, v96
	v_mul_f32_e32 v97, 0xbfb8aa3b, v97
	v_rcp_f32_e32 v110, v110
	v_rcp_f32_e32 v111, v111
	v_exp_f32_e32 v96, v96
	v_exp_f32_e32 v97, v97
	v_mul_f32_e32 v100, 0xbfb8aa3b, v100
	v_mul_f32_e32 v101, 0xbfb8aa3b, v101
	v_exp_f32_e32 v100, v100
	v_exp_f32_e32 v101, v101
	v_add_f32_e32 v96, 1.0, v96
	v_add_f32_e32 v97, 1.0, v97
	v_rcp_f32_e32 v96, v96
	v_rcp_f32_e32 v97, v97
	v_mul_f32_e32 v98, 0xbfb8aa3b, v98
	v_mul_f32_e32 v99, 0xbfb8aa3b, v99
	v_add_f32_e32 v100, 1.0, v100
	v_add_f32_e32 v101, 1.0, v101
	v_exp_f32_e32 v98, v98
	v_exp_f32_e32 v99, v99
	v_rcp_f32_e32 v100, v100
	v_rcp_f32_e32 v101, v101
	v_mul_f32_e32 v102, 0xbfb8aa3b, v102
	v_mul_f32_e32 v103, 0xbfb8aa3b, v103
	v_exp_f32_e32 v102, v102
	v_exp_f32_e32 v103, v103
	v_add_f32_e32 v98, 1.0, v98
	v_add_f32_e32 v99, 1.0, v99
	v_rcp_f32_e32 v98, v98
; __device__ __forceinline__ float bflo(unsigned w) { return __uint_as_float(w << 16); }
; __device__ __forceinline__ float bfhi(unsigned w) { return __uint_as_float(w & 0xffff0000u); }
; __device__ __forceinline__ unsigned dpp_ror8(unsigned x) { return (unsigned)__builtin_amdgcn_update_dpp(0, (int)x, 0x128, 0xf, 0xf, false); }
;     __device__ __forceinline__ void operator()(const f32x4 (&acc)[2][2][4][2], const Unit& u, int wr, int wc, int fr, int fq) const {
;     ...
;         for (int ai = 0; ai < 2; ++ai)
; #pragma unroll
;             for (int m = 0; m < 4; ++m) { const int row = row0 + ai * HALF + m * 16; const float ri = __builtin_amdgcn_rsqf(sse[row] * (1.f / D) + EPS);
;                 u32x4 rr[2], ee[2]; load_pair_lines(R, D, row, fr, col0, rr[0], rr[1], 32); load_pair_lines(E, D, row, fr, col0, ee[0], ee[1], 32);
;                 float* orow = OUT + (size_t)(row - fr + (fr & 7)) * D + col0 + (lo ? 0 : 4);
; #pragma unroll
;                 for (int bj = 0; bj < 2; ++bj) { const u32x4 rw = rr[bj], ew = ee[bj];
;                     const float r[8] = {bflo(rw.x), bfhi(rw.x), bflo(rw.y), bfhi(rw.y), bflo(rw.z), bfhi(rw.z), bflo(rw.w), bfhi(rw.w)};
;                     const float e[8] = {bflo(ew.x), bfhi(ew.x), bflo(ew.y), bfhi(ew.y), bflo(ew.z), bfhi(ew.z), bflo(ew.w), bfhi(ew.w)};
;                     float o[8];
; #pragma unroll
;                     for (int j = 0; j < 8; ++j) { const float a = acc[ai][bj][m][j >> 2][j & 3]; const float gg = gv[bj][j >> 2][j & 3];
;                         o[j] = r[j] + e[j] * ri * gg * __builtin_amdgcn_rcpf(1.f + __builtin_amdgcn_exp2f(-a * LOG2E)); }
;                     f32x4 o1, o2;
; #pragma unroll
;                     for (int j = 0; j < 4; ++j) { const unsigned a = __float_as_uint(o[j]), b = __float_as_uint(o[4 + j]); const unsigned sa = dpp_ror8(a), sb = dpp_ror8(b);
;                         o1[j] = __uint_as_float(lo ? a : sb); o2[j] = __uint_as_float(lo ? sa : b); }
;                     *(f32x4*)(orow + 32 * bj) = o1; *(f32x4*)(orow + (size_t)8 * D + 32 * bj) = o2; } }
	v_rcp_f32_e32 v99, v99
	v_add_f32_e32 v102, 1.0, v102
	v_add_f32_e32 v103, 1.0, v103
	v_rcp_f32_e32 v102, v102
	v_rcp_f32_e32 v103, v103
	v_mul_f32_e32 v88, 0xbfb8aa3b, v88
	v_mul_f32_e32 v89, 0xbfb8aa3b, v89
	v_mul_f32_e32 v92, 0xbfb8aa3b, v92
	v_exp_f32_e32 v88, v88
	v_exp_f32_e32 v89, v89
	v_mul_f32_e32 v90, 0xbfb8aa3b, v90
	v_mul_f32_e32 v91, 0xbfb8aa3b, v91
	v_add_f32_e32 v88, 1.0, v88
	v_add_f32_e32 v89, 1.0, v89
	v_rcp_f32_e32 v88, v88
	v_rcp_f32_e32 v89, v89
	v_exp_f32_e32 v90, v90
	v_exp_f32_e32 v91, v91
	v_fmamk_f32 v112, v132, 0x3a000000, v182
	v_mov_b32_e32 v132, v157
	v_rsq_f32_e32 v112, v112
	v_mul_f32_e32 v94, 0xbfb8aa3b, v94
	v_mul_f32_e32 v95, 0xbfb8aa3b, v95
	v_mov_b32_dpp v137, v120 row_ror:8 row_mask:0xf bank_mask:0xf
	v_mov_b32_dpp v138, v121 row_ror:8 row_mask:0xf bank_mask:0xf
	v_mov_b32_dpp v113, v114 row_ror:8 row_mask:0xf bank_mask:0xf
	v_mov_b32_dpp v132, v115 row_ror:8 row_mask:0xf bank_mask:0xf
	v_mov_b32_dpp v133, v116 row_ror:8 row_mask:0xf bank_mask:0xf
	v_mov_b32_dpp v134, v117 row_ror:8 row_mask:0xf bank_mask:0xf
	v_mov_b32_dpp v136, v119 row_ror:8 row_mask:0xf bank_mask:0xf
	v_cndmask_b32_e64 v138, v138, v117, s[0:1]
	v_cndmask_b32_e64 v117, v137, v116, s[0:1]
	v_mov_b32_e32 v116, v157
	v_mov_b32_dpp v135, v118 row_ror:8 row_mask:0xf bank_mask:0xf
	v_cndmask_b32_e64 v136, v136, v115, s[0:1]
	v_cndmask_b32_e64 v132, v119, v132, s[0:1]
	v_cndmask_b32_e64 v121, v121, v134, s[0:1]
	v_cndmask_b32_e64 v113, v118, v113, s[0:1]
	v_mov_b32_e32 v115, v157
	v_mov_b32_dpp v116, v124 row_ror:8 row_mask:0xf bank_mask:0xf
	v_mov_b32_e32 v118, v157
	v_mov_b32_e32 v119, v157
	v_mov_b32_e32 v134, v157
	v_cndmask_b32_e64 v135, v135, v114, s[0:1]
	v_cndmask_b32_e64 v120, v120, v133, s[0:1]
	v_mov_b32_e32 v114, v157
	v_mov_b32_dpp v115, v123 row_ror:8 row_mask:0xf bank_mask:0xf
	v_mov_b32_dpp v118, v125 row_ror:8 row_mask:0xf bank_mask:0xf
	v_mov_b32_dpp v119, v126 row_ror:8 row_mask:0xf bank_mask:0xf
	v_mov_b32_e32 v133, v157
	v_mov_b32_dpp v134, v128 row_ror:8 row_mask:0xf bank_mask:0xf
	v_cndmask_b32_e64 v128, v128, v116, s[0:1]
	v_exp_f32_e32 v116, v108
	v_mul_f32_e32 v108, 0xbfb8aa3b, v109
	v_mov_b32_dpp v114, v122 row_ror:8 row_mask:0xf bank_mask:0xf
	v_mov_b32_dpp v133, v127 row_ror:8 row_mask:0xf bank_mask:0xf
	v_cndmask_b32_e64 v122, v119, v122, s[0:1]
	v_cndmask_b32_e64 v119, v134, v124, s[0:1]
	v_cndmask_b32_e64 v124, v127, v115, s[0:1]
	v_cndmask_b32_e64 v127, v129, v118, s[0:1]
	v_exp_f32_e32 v118, v108
	v_cndmask_b32_e64 v126, v126, v114, s[0:1]
	v_lshlrev_b64 v[114:115], 13, v[130:131]
	v_lshl_add_u64 v[114:115], s[4:5], 0, v[114:115]
	v_lshl_add_u64 v[114:115], v[114:115], 0, v[166:167]
	v_lshl_add_u64 v[108:109], v[114:115], 0, v[156:157]
	v_add_f32_e32 v115, 1.0, v118
	v_lshlrev_b32_e32 v118, 16, v119
	v_and_b32_e32 v119, 0xffff0000, v119
	v_add_f32_e32 v114, 1.0, v116
	v_pk_mul_f32 v[118:119], v[112:113], v[118:119] op_sel_hi:[0,1]
	v_rcp_f32_e32 v114, v114
	v_rcp_f32_e32 v115, v115
	v_lshlrev_b32_e32 v116, 16, v117
	v_and_b32_e32 v117, 0xffff0000, v117
	v_pk_mul_f32 v[118:119], v[60:61], v[118:119]
	v_mov_b32_e32 v137, v157
	v_pk_fma_f32 v[118:119], v[104:105], v[118:119], v[116:117]
	v_lshlrev_b32_e32 v116, 16, v122
	v_and_b32_e32 v117, 0xffff0000, v122
	v_mov_b32_dpp v137, v129 row_ror:8 row_mask:0xf bank_mask:0xf
	v_pk_mul_f32 v[116:117], v[112:113], v[116:117] op_sel_hi:[0,1]
	v_cndmask_b32_e64 v125, v137, v125, s[0:1]
	v_lshlrev_b32_e32 v104, 16, v135
	v_and_b32_e32 v105, 0xffff0000, v135
	v_pk_mul_f32 v[116:117], v[56:57], v[116:117]
	v_cndmask_b32_e64 v123, v133, v123, s[0:1]
	v_pk_fma_f32 v[104:105], v[114:115], v[116:117], v[104:105]
	v_lshlrev_b32_e32 v116, 16, v125
	v_and_b32_e32 v117, 0xffff0000, v125
	v_pk_mul_f32 v[116:117], v[112:113], v[116:117] op_sel_hi:[0,1]
	v_lshlrev_b32_e32 v114, 16, v138
	v_and_b32_e32 v115, 0xffff0000, v138
	v_pk_mul_f32 v[116:117], v[62:63], v[116:117]
	v_mov_b32_e32 v129, v157
	v_pk_fma_f32 v[114:115], v[106:107], v[116:117], v[114:115]
	v_lshlrev_b32_e32 v116, 16, v123
	v_and_b32_e32 v117, 0xffff0000, v123
	v_pk_mul_f32 v[116:117], v[112:113], v[116:117] op_sel_hi:[0,1]
	v_lshlrev_b32_e32 v106, 16, v136
	v_and_b32_e32 v107, 0xffff0000, v136
	v_pk_mul_f32 v[116:117], v[58:59], v[116:117]
	v_mov_b32_e32 v130, v157
	v_pk_fma_f32 v[106:107], v[110:111], v[116:117], v[106:107]
	v_mov_b32_e32 v110, v157
	v_mov_b32_e32 v111, v157
	v_mov_b32_e32 v125, v157
	v_mov_b32_e32 v133, v157
	v_mov_b32_dpp v110, v106 row_ror:8 row_mask:0xf bank_mask:0xf
	v_mov_b32_dpp v111, v107 row_ror:8 row_mask:0xf bank_mask:0xf
	v_mov_b32_dpp v129, v118 row_ror:8 row_mask:0xf bank_mask:0xf
	v_mov_b32_dpp v130, v119 row_ror:8 row_mask:0xf bank_mask:0xf
	v_mov_b32_e32 v122, v157
	v_mov_b32_e32 v131, v157
	v_mov_b32_dpp v125, v114 row_ror:8 row_mask:0xf bank_mask:0xf
	v_mov_b32_dpp v133, v115 row_ror:8 row_mask:0xf bank_mask:0xf
	v_cndmask_b32_e64 v117, v115, v111, s[0:1]
	v_cndmask_b32_e64 v116, v114, v110, s[0:1]
	v_lshlrev_b32_e32 v110, 16, v128
	v_and_b32_e32 v111, 0xffff0000, v128
	v_mov_b32_dpp v122, v104 row_ror:8 row_mask:0xf bank_mask:0xf
	v_mov_b32_dpp v131, v105 row_ror:8 row_mask:0xf bank_mask:0xf
	v_cndmask_b32_e64 v107, v133, v107, s[0:1]
	v_cndmask_b32_e64 v106, v125, v106, s[0:1]
	v_cndmask_b32_e64 v105, v130, v105, s[0:1]
	v_cndmask_b32_e64 v104, v129, v104, s[0:1]
	v_pk_mul_f32 v[110:111], v[112:113], v[110:111] op_sel_hi:[0,1]
	global_store_dwordx4 v[108:109], v[104:107], off
	v_pk_mul_f32 v[110:111], v[44:45], v[110:111]
	v_cndmask_b32_e64 v115, v119, v131, s[0:1]
	v_lshlrev_b32_e32 v106, 16, v120
	v_and_b32_e32 v107, 0xffff0000, v120
	v_pk_fma_f32 v[106:107], v[96:97], v[110:111], v[106:107]
; __device__ __forceinline__ float bflo(unsigned w) { return __uint_as_float(w << 16); }
; __device__ __forceinline__ float bfhi(unsigned w) { return __uint_as_float(w & 0xffff0000u); }
; __device__ __forceinline__ unsigned dpp_ror8(unsigned x) { return (unsigned)__builtin_amdgcn_update_dpp(0, (int)x, 0x128, 0xf, 0xf, false); }
;     __device__ __forceinline__ void operator()(const f32x4 (&acc)[2][2][4][2], const Unit& u, int wr, int wc, int fr, int fq) const {
;     ...
;         for (int ai = 0; ai < 2; ++ai)
; #pragma unroll
;             for (int m = 0; m < 4; ++m) { const int row = row0 + ai * HALF + m * 16; const float ri = __builtin_amdgcn_rsqf(sse[row] * (1.f / D) + EPS);
;                 u32x4 rr[2], ee[2]; load_pair_lines(R, D, row, fr, col0, rr[0], rr[1], 32); load_pair_lines(E, D, row, fr, col0, ee[0], ee[1], 32);
;                 float* orow = OUT + (size_t)(row - fr + (fr & 7)) * D + col0 + (lo ? 0 : 4);
; #pragma unroll
;                 for (int bj = 0; bj < 2; ++bj) { const u32x4 rw = rr[bj], ew = ee[bj];
;                     const float r[8] = {bflo(rw.x), bfhi(rw.x), bflo(rw.y), bfhi(rw.y), bflo(rw.z), bfhi(rw.z), bflo(rw.w), bfhi(rw.w)};
;                     const float e[8] = {bflo(ew.x), bfhi(ew.x), bflo(ew.y), bfhi(ew.y), bflo(ew.z), bfhi(ew.z), bflo(ew.w), bfhi(ew.w)};
;                     float o[8];
; #pragma unroll
;                     for (int j = 0; j < 8; ++j) { const float a = acc[ai][bj][m][j >> 2][j & 3]; const float gg = gv[bj][j >> 2][j & 3];
;                         o[j] = r[j] + e[j] * ri * gg * __builtin_amdgcn_rcpf(1.f + __builtin_amdgcn_exp2f(-a * LOG2E)); }
;                     f32x4 o1, o2;
; #pragma unroll
;                     for (int j = 0; j < 4; ++j) { const unsigned a = __float_as_uint(o[j]), b = __float_as_uint(o[4 + j]); const unsigned sa = dpp_ror8(a), sb = dpp_ror8(b);
;                         o1[j] = __uint_as_float(lo ? a : sb); o2[j] = __uint_as_float(lo ? sa : b); }
;                     *(f32x4*)(orow + 32 * bj) = o1; *(f32x4*)(orow + (size_t)8 * D + 32 * bj) = o2; } }
	v_lshlrev_b32_e32 v110, 16, v126
	v_and_b32_e32 v111, 0xffff0000, v126
	v_pk_mul_f32 v[110:111], v[112:113], v[110:111] op_sel_hi:[0,1]
	v_lshlrev_b32_e32 v96, 16, v113
	v_and_b32_e32 v97, 0xffff0000, v113
	v_pk_mul_f32 v[110:111], v[40:41], v[110:111]
	v_mov_b32_e32 v113, v157
	v_pk_fma_f32 v[96:97], v[100:101], v[110:111], v[96:97]
	v_lshlrev_b32_e32 v110, 16, v127
	v_and_b32_e32 v111, 0xffff0000, v127
	v_mov_b32_dpp v113, v96 row_ror:8 row_mask:0xf bank_mask:0xf
	v_pk_mul_f32 v[110:111], v[112:113], v[110:111] op_sel_hi:[0,1]
	v_lshlrev_b32_e32 v100, 16, v121
	v_and_b32_e32 v101, 0xffff0000, v121
	v_pk_mul_f32 v[110:111], v[46:47], v[110:111]
	v_add_co_u32_e32 v104, vcc, s45, v108
	v_pk_fma_f32 v[100:101], v[98:99], v[110:111], v[100:101]
	v_lshlrev_b32_e32 v110, 16, v124
	v_and_b32_e32 v111, 0xffff0000, v124
	v_cndmask_b32_e64 v114, v118, v122, s[0:1]
	v_addc_co_u32_e32 v105, vcc, 0, v109, vcc
	v_pk_mul_f32 v[110:111], v[112:113], v[110:111] op_sel_hi:[0,1]
	global_store_dwordx4 v[104:105], v[114:117], off
	v_mov_b32_e32 v118, v157
	v_lshlrev_b32_e32 v98, 16, v132
	v_mov_b32_e32 v114, v157
	v_mov_b32_e32 v115, v157
	v_mov_b32_e32 v117, v157
	v_and_b32_e32 v99, 0xffff0000, v132
	v_pk_mul_f32 v[110:111], v[42:43], v[110:111]
	v_mov_b32_dpp v114, v106 row_ror:8 row_mask:0xf bank_mask:0xf
	v_mov_b32_dpp v115, v107 row_ror:8 row_mask:0xf bank_mask:0xf
	v_mov_b32_e32 v116, v157
	v_mov_b32_dpp v117, v100 row_ror:8 row_mask:0xf bank_mask:0xf
	v_mov_b32_dpp v118, v101 row_ror:8 row_mask:0xf bank_mask:0xf
	v_pk_fma_f32 v[98:99], v[102:103], v[110:111], v[98:99]
	v_mov_b32_e32 v102, v157
	v_mov_b32_e32 v103, v157
	v_mov_b32_dpp v116, v97 row_ror:8 row_mask:0xf bank_mask:0xf
	v_mov_b32_dpp v102, v98 row_ror:8 row_mask:0xf bank_mask:0xf
	v_mov_b32_dpp v103, v99 row_ror:8 row_mask:0xf bank_mask:0xf
	v_cndmask_b32_e64 v99, v118, v99, s[0:1]
	v_cndmask_b32_e64 v98, v117, v98, s[0:1]
	v_cndmask_b32_e64 v97, v115, v97, s[0:1]
	v_cndmask_b32_e64 v96, v114, v96, s[0:1]
	v_cndmask_b32_e64 v103, v101, v103, s[0:1]
	v_cndmask_b32_e64 v102, v100, v102, s[0:1]
	v_cndmask_b32_e64 v101, v107, v116, s[0:1]
	v_cndmask_b32_e64 v100, v106, v113, s[0:1]
	global_store_dwordx4 v[108:109], v[96:99], off offset:128
	global_store_dwordx4 v[104:105], v[100:103], off offset:128
	v_mov_b32_e32 v121, v157
	v_or_b32_e32 v96, 48, v170
	v_ashrrev_i32_e32 v97, 31, v96
	v_lshl_add_u64 v[98:99], v[96:97], 2, s[6:7]
	v_sub_u32_e32 v96, v96, v174
	v_add_u32_e32 v114, v96, v176
	v_ashrrev_i32_e32 v115, 31, v114
	v_lshlrev_b64 v[96:97], 12, v[114:115]
	v_lshl_add_u64 v[110:111], v[96:97], 0, s[16:17]
	v_lshl_add_u64 v[102:103], s[8:9], 0, v[110:111]
	s_waitcnt vmcnt(4)
	s_nop 0
	v_mov_b32_e32 v116, v228
	v_lshl_add_u64 v[98:99], s[8:9], 0, v[96:97]
	v_lshl_add_u64 v[102:103], v[102:103], 0, v[164:165]
	v_lshl_add_u64 v[96:97], s[10:11], 0, v[96:97]
	v_lshl_add_u64 v[98:99], v[98:99], 0, v[164:165]
	v_mov_b64_e32 v[102:103], v[232:233]
	v_mov_b64_e32 v[104:105], v[234:235]
	v_lshl_add_u64 v[96:97], v[96:97], 0, v[164:165]
	v_mov_b64_e32 v[98:99], v[236:237]
	v_mov_b64_e32 v[100:101], v[238:239]
	v_mov_b32_e32 v122, v157
	v_mov_b64_e32 v[106:107], v[240:241]
	v_mov_b64_e32 v[108:109], v[242:243]
	v_lshl_add_u64 v[96:97], s[10:11], 0, v[110:111]
	v_lshl_add_u64 v[96:97], v[96:97], 0, v[164:165]
	v_mov_b64_e32 v[110:111], v[244:245]
	v_mov_b64_e32 v[112:113], v[246:247]
	s_nop 1
	global_load_dword v228, v[168:169], off offset:512
	v_sub_u32_e32 v217, v170, v174
	v_add_u32_e32 v217, v217, v176
	v_add_u32_e32 v226, 0x80, v217
	v_ashrrev_i32_e32 v227, 31, v226
	v_lshlrev_b64 v[222:223], 12, v[226:227]
	v_lshl_add_u64 v[224:225], v[222:223], 0, s[16:17]
	v_lshl_add_u64 v[218:219], s[8:9], 0, v[222:223]
	v_lshl_add_u64 v[220:221], s[8:9], 0, v[224:225]
	v_lshl_add_u64 v[218:219], v[218:219], 0, v[164:165]
	v_lshl_add_u64 v[220:221], v[220:221], 0, v[164:165]
	global_load_dwordx4 v[232:235], v[218:219], off
	v_lshl_add_u64 v[222:223], s[10:11], 0, v[222:223]
	global_load_dwordx4 v[236:239], v[220:221], off
	v_lshl_add_u64 v[222:223], v[222:223], 0, v[164:165]
	v_lshl_add_u64 v[224:225], s[10:11], 0, v[224:225]
	global_load_dwordx4 v[240:243], v[222:223], off
	v_lshl_add_u64 v[224:225], v[224:225], 0, v[164:165]
	global_load_dwordx4 v[244:247], v[224:225], off
	v_mov_b32_e32 v97, v157
	v_mov_b32_e32 v117, v157
	v_mov_b32_e32 v118, v157
	v_mov_b32_e32 v120, v157
	v_mov_b32_e32 v119, v157
	v_exp_f32_e32 v94, v94
	v_exp_f32_e32 v95, v95
	v_add_f32_e32 v90, 1.0, v90
	v_add_f32_e32 v91, 1.0, v91
	v_rcp_f32_e32 v90, v90
	v_rcp_f32_e32 v91, v91
	v_add_f32_e32 v94, 1.0, v94
	v_add_f32_e32 v95, 1.0, v95
	v_mul_f32_e32 v80, 0xbfb8aa3b, v80
	v_mul_f32_e32 v81, 0xbfb8aa3b, v81
	v_rcp_f32_e32 v94, v94
	v_rcp_f32_e32 v95, v95
	v_exp_f32_e32 v80, v80
	v_exp_f32_e32 v81, v81
	v_mul_f32_e32 v84, 0xbfb8aa3b, v84
	v_mul_f32_e32 v85, 0xbfb8aa3b, v85
	v_exp_f32_e32 v84, v84
	v_exp_f32_e32 v85, v85
	v_add_f32_e32 v80, 1.0, v80
	v_add_f32_e32 v81, 1.0, v81
	v_rcp_f32_e32 v80, v80
	v_rcp_f32_e32 v81, v81
	v_mul_f32_e32 v82, 0xbfb8aa3b, v82
	v_mul_f32_e32 v83, 0xbfb8aa3b, v83
	v_add_f32_e32 v84, 1.0, v84
	v_add_f32_e32 v85, 1.0, v85
	v_exp_f32_e32 v82, v82
	v_exp_f32_e32 v83, v83
	v_rcp_f32_e32 v84, v84
	v_rcp_f32_e32 v85, v85
	v_mul_f32_e32 v86, 0xbfb8aa3b, v86
	v_mul_f32_e32 v87, 0xbfb8aa3b, v87
	v_exp_f32_e32 v86, v86
	v_exp_f32_e32 v87, v87
	v_add_f32_e32 v82, 1.0, v82
	v_add_f32_e32 v83, 1.0, v83
	v_rcp_f32_e32 v82, v82
	v_rcp_f32_e32 v83, v83
	v_add_f32_e32 v86, 1.0, v86
	v_add_f32_e32 v87, 1.0, v87
	v_rcp_f32_e32 v86, v86
	v_rcp_f32_e32 v87, v87
	v_mul_f32_e32 v72, 0xbfb8aa3b, v72
	v_mul_f32_e32 v73, 0xbfb8aa3b, v73
; __device__ __forceinline__ float bflo(unsigned w) { return __uint_as_float(w << 16); }
; __device__ __forceinline__ float bfhi(unsigned w) { return __uint_as_float(w & 0xffff0000u); }
; __device__ __forceinline__ unsigned dpp_ror8(unsigned x) { return (unsigned)__builtin_amdgcn_update_dpp(0, (int)x, 0x128, 0xf, 0xf, false); }
;     __device__ __forceinline__ void operator()(const f32x4 (&acc)[2][2][4][2], const Unit& u, int wr, int wc, int fr, int fq) const {
;     ...
;         for (int ai = 0; ai < 2; ++ai)
; #pragma unroll
;             for (int m = 0; m < 4; ++m) { const int row = row0 + ai * HALF + m * 16; const float ri = __builtin_amdgcn_rsqf(sse[row] * (1.f / D) + EPS);
;                 u32x4 rr[2], ee[2]; load_pair_lines(R, D, row, fr, col0, rr[0], rr[1], 32); load_pair_lines(E, D, row, fr, col0, ee[0], ee[1], 32);
;                 float* orow = OUT + (size_t)(row - fr + (fr & 7)) * D + col0 + (lo ? 0 : 4);
; #pragma unroll
;                 for (int bj = 0; bj < 2; ++bj) { const u32x4 rw = rr[bj], ew = ee[bj];
;                     const float r[8] = {bflo(rw.x), bfhi(rw.x), bflo(rw.y), bfhi(rw.y), bflo(rw.z), bfhi(rw.z), bflo(rw.w), bfhi(rw.w)};
;                     const float e[8] = {bflo(ew.x), bfhi(ew.x), bflo(ew.y), bfhi(ew.y), bflo(ew.z), bfhi(ew.z), bflo(ew.w), bfhi(ew.w)};
;                     float o[8];
; #pragma unroll
;                     for (int j = 0; j < 8; ++j) { const float a = acc[ai][bj][m][j >> 2][j & 3]; const float gg = gv[bj][j >> 2][j & 3];
;                         o[j] = r[j] + e[j] * ri * gg * __builtin_amdgcn_rcpf(1.f + __builtin_amdgcn_exp2f(-a * LOG2E)); }
;                     f32x4 o1, o2;
; #pragma unroll
;                     for (int j = 0; j < 4; ++j) { const unsigned a = __float_as_uint(o[j]), b = __float_as_uint(o[4 + j]); const unsigned sa = dpp_ror8(a), sb = dpp_ror8(b);
;                         o1[j] = __uint_as_float(lo ? a : sb); o2[j] = __uint_as_float(lo ? sa : b); }
;                     *(f32x4*)(orow + 32 * bj) = o1; *(f32x4*)(orow + (size_t)8 * D + 32 * bj) = o2; } }
	v_mul_f32_e32 v76, 0xbfb8aa3b, v76
	v_exp_f32_e32 v72, v72
	v_exp_f32_e32 v73, v73
	v_mul_f32_e32 v74, 0xbfb8aa3b, v74
	v_mul_f32_e32 v75, 0xbfb8aa3b, v75
	v_add_f32_e32 v72, 1.0, v72
	v_add_f32_e32 v73, 1.0, v73
	v_rcp_f32_e32 v72, v72
	v_rcp_f32_e32 v73, v73
	v_exp_f32_e32 v74, v74
	v_exp_f32_e32 v75, v75
	v_mul_f32_e32 v78, 0xbfb8aa3b, v78
	v_mul_f32_e32 v79, 0xbfb8aa3b, v79
	v_exp_f32_e32 v78, v78
	v_exp_f32_e32 v79, v79
	v_add_f32_e32 v74, 1.0, v74
	v_add_f32_e32 v75, 1.0, v75
	v_rcp_f32_e32 v74, v74
	v_fmamk_f32 v96, v116, 0x3a000000, v182
	v_mov_b32_e32 v116, v157
	v_rsq_f32_e32 v96, v96
	v_rcp_f32_e32 v75, v75
	v_add_f32_e32 v78, 1.0, v78
	v_mov_b32_dpp v121, v104 row_ror:8 row_mask:0xf bank_mask:0xf
	v_mov_b32_dpp v122, v105 row_ror:8 row_mask:0xf bank_mask:0xf
	v_mov_b32_dpp v97, v98 row_ror:8 row_mask:0xf bank_mask:0xf
	v_mov_b32_dpp v116, v99 row_ror:8 row_mask:0xf bank_mask:0xf
	v_mov_b32_dpp v117, v100 row_ror:8 row_mask:0xf bank_mask:0xf
	v_mov_b32_dpp v118, v101 row_ror:8 row_mask:0xf bank_mask:0xf
	v_mov_b32_dpp v120, v103 row_ror:8 row_mask:0xf bank_mask:0xf
	v_cndmask_b32_e64 v122, v122, v101, s[0:1]
	v_cndmask_b32_e64 v101, v121, v100, s[0:1]
	v_mov_b32_e32 v100, v157
	v_mov_b32_dpp v119, v102 row_ror:8 row_mask:0xf bank_mask:0xf
	v_cndmask_b32_e64 v120, v120, v99, s[0:1]
	v_cndmask_b32_e64 v116, v103, v116, s[0:1]
	v_cndmask_b32_e64 v105, v105, v118, s[0:1]
	v_cndmask_b32_e64 v97, v102, v97, s[0:1]
	v_mov_b32_e32 v99, v157
	v_mov_b32_dpp v100, v108 row_ror:8 row_mask:0xf bank_mask:0xf
	v_mov_b32_e32 v102, v157
	v_mov_b32_e32 v103, v157
	v_mov_b32_e32 v118, v157
	v_cndmask_b32_e64 v119, v119, v98, s[0:1]
	v_cndmask_b32_e64 v104, v104, v117, s[0:1]
	v_mov_b32_e32 v98, v157
	v_mov_b32_dpp v99, v107 row_ror:8 row_mask:0xf bank_mask:0xf
	v_mov_b32_dpp v102, v109 row_ror:8 row_mask:0xf bank_mask:0xf
	v_mov_b32_dpp v103, v110 row_ror:8 row_mask:0xf bank_mask:0xf
	v_mov_b32_e32 v117, v157
	v_mov_b32_dpp v118, v112 row_ror:8 row_mask:0xf bank_mask:0xf
	v_cndmask_b32_e64 v112, v112, v100, s[0:1]
	v_exp_f32_e32 v100, v92
	v_mul_f32_e32 v92, 0xbfb8aa3b, v93
	v_mov_b32_dpp v98, v106 row_ror:8 row_mask:0xf bank_mask:0xf
	v_mov_b32_dpp v117, v111 row_ror:8 row_mask:0xf bank_mask:0xf
	v_cndmask_b32_e64 v106, v103, v106, s[0:1]
	v_cndmask_b32_e64 v103, v118, v108, s[0:1]
	v_cndmask_b32_e64 v108, v111, v99, s[0:1]
	v_cndmask_b32_e64 v111, v113, v102, s[0:1]
	v_exp_f32_e32 v102, v92
	v_cndmask_b32_e64 v110, v110, v98, s[0:1]
	v_lshlrev_b64 v[98:99], 13, v[114:115]
	v_lshl_add_u64 v[98:99], s[4:5], 0, v[98:99]
	v_lshl_add_u64 v[98:99], v[98:99], 0, v[166:167]
	v_lshl_add_u64 v[92:93], v[98:99], 0, v[156:157]
	v_add_f32_e32 v99, 1.0, v102
	v_lshlrev_b32_e32 v102, 16, v103
	v_and_b32_e32 v103, 0xffff0000, v103
	v_add_f32_e32 v98, 1.0, v100
	v_pk_mul_f32 v[102:103], v[96:97], v[102:103] op_sel_hi:[0,1]
	v_rcp_f32_e32 v98, v98
	v_rcp_f32_e32 v99, v99
	v_lshlrev_b32_e32 v100, 16, v101
	v_and_b32_e32 v101, 0xffff0000, v101
	v_pk_mul_f32 v[102:103], v[60:61], v[102:103]
	v_mov_b32_e32 v121, v157
	v_pk_fma_f32 v[102:103], v[88:89], v[102:103], v[100:101]
	v_lshlrev_b32_e32 v100, 16, v106
	v_and_b32_e32 v101, 0xffff0000, v106
	v_mov_b32_dpp v121, v113 row_ror:8 row_mask:0xf bank_mask:0xf
	v_pk_mul_f32 v[100:101], v[96:97], v[100:101] op_sel_hi:[0,1]
	v_cndmask_b32_e64 v109, v121, v109, s[0:1]
	v_lshlrev_b32_e32 v88, 16, v119
	v_and_b32_e32 v89, 0xffff0000, v119
	v_pk_mul_f32 v[100:101], v[56:57], v[100:101]
	v_cndmask_b32_e64 v107, v117, v107, s[0:1]
	v_pk_fma_f32 v[88:89], v[98:99], v[100:101], v[88:89]
	v_lshlrev_b32_e32 v100, 16, v109
	v_and_b32_e32 v101, 0xffff0000, v109
	v_pk_mul_f32 v[100:101], v[96:97], v[100:101] op_sel_hi:[0,1]
	v_lshlrev_b32_e32 v98, 16, v122
	v_and_b32_e32 v99, 0xffff0000, v122
	v_pk_mul_f32 v[100:101], v[62:63], v[100:101]
	v_mov_b32_e32 v113, v157
	v_pk_fma_f32 v[98:99], v[90:91], v[100:101], v[98:99]
	v_lshlrev_b32_e32 v100, 16, v107
	v_and_b32_e32 v101, 0xffff0000, v107
	v_pk_mul_f32 v[100:101], v[96:97], v[100:101] op_sel_hi:[0,1]
	v_lshlrev_b32_e32 v90, 16, v120
	v_and_b32_e32 v91, 0xffff0000, v120
	v_pk_mul_f32 v[100:101], v[58:59], v[100:101]
	v_mov_b32_e32 v114, v157
	v_pk_fma_f32 v[90:91], v[94:95], v[100:101], v[90:91]
	v_mov_b32_e32 v94, v157
	v_mov_b32_e32 v95, v157
	v_mov_b32_e32 v109, v157
	v_mov_b32_e32 v117, v157
	v_mov_b32_dpp v94, v90 row_ror:8 row_mask:0xf bank_mask:0xf
	v_mov_b32_dpp v95, v91 row_ror:8 row_mask:0xf bank_mask:0xf
	v_mov_b32_dpp v113, v102 row_ror:8 row_mask:0xf bank_mask:0xf
	v_mov_b32_dpp v114, v103 row_ror:8 row_mask:0xf bank_mask:0xf
	v_mov_b32_e32 v106, v157
	v_mov_b32_e32 v115, v157
	v_mov_b32_dpp v109, v98 row_ror:8 row_mask:0xf bank_mask:0xf
	v_mov_b32_dpp v117, v99 row_ror:8 row_mask:0xf bank_mask:0xf
	v_cndmask_b32_e64 v101, v99, v95, s[0:1]
	v_cndmask_b32_e64 v100, v98, v94, s[0:1]
	v_lshlrev_b32_e32 v94, 16, v112
	v_and_b32_e32 v95, 0xffff0000, v112
	v_mov_b32_dpp v106, v88 row_ror:8 row_mask:0xf bank_mask:0xf
	v_mov_b32_dpp v115, v89 row_ror:8 row_mask:0xf bank_mask:0xf
	v_cndmask_b32_e64 v91, v117, v91, s[0:1]
	v_cndmask_b32_e64 v90, v109, v90, s[0:1]
	v_cndmask_b32_e64 v89, v114, v89, s[0:1]
	v_cndmask_b32_e64 v88, v113, v88, s[0:1]
	v_pk_mul_f32 v[94:95], v[96:97], v[94:95] op_sel_hi:[0,1]
	global_store_dwordx4 v[92:93], v[88:91], off
	v_pk_mul_f32 v[94:95], v[44:45], v[94:95]
	v_cndmask_b32_e64 v99, v103, v115, s[0:1]
	v_lshlrev_b32_e32 v90, 16, v104
	v_and_b32_e32 v91, 0xffff0000, v104
	v_pk_fma_f32 v[90:91], v[80:81], v[94:95], v[90:91]
	v_lshlrev_b32_e32 v94, 16, v110
	v_and_b32_e32 v95, 0xffff0000, v110
	v_pk_mul_f32 v[94:95], v[96:97], v[94:95] op_sel_hi:[0,1]
; __device__ __forceinline__ float bflo(unsigned w) { return __uint_as_float(w << 16); }
; __device__ __forceinline__ float bfhi(unsigned w) { return __uint_as_float(w & 0xffff0000u); }
; __device__ __forceinline__ unsigned dpp_ror8(unsigned x) { return (unsigned)__builtin_amdgcn_update_dpp(0, (int)x, 0x128, 0xf, 0xf, false); }
;     __device__ __forceinline__ void operator()(const f32x4 (&acc)[2][2][4][2], const Unit& u, int wr, int wc, int fr, int fq) const {
;     ...
;         for (int ai = 0; ai < 2; ++ai)
; #pragma unroll
;             for (int m = 0; m < 4; ++m) { const int row = row0 + ai * HALF + m * 16; const float ri = __builtin_amdgcn_rsqf(sse[row] * (1.f / D) + EPS);
;                 u32x4 rr[2], ee[2]; load_pair_lines(R, D, row, fr, col0, rr[0], rr[1], 32); load_pair_lines(E, D, row, fr, col0, ee[0], ee[1], 32);
;                 float* orow = OUT + (size_t)(row - fr + (fr & 7)) * D + col0 + (lo ? 0 : 4);
; #pragma unroll
;                 for (int bj = 0; bj < 2; ++bj) { const u32x4 rw = rr[bj], ew = ee[bj];
;                     const float r[8] = {bflo(rw.x), bfhi(rw.x), bflo(rw.y), bfhi(rw.y), bflo(rw.z), bfhi(rw.z), bflo(rw.w), bfhi(rw.w)};
;                     const float e[8] = {bflo(ew.x), bfhi(ew.x), bflo(ew.y), bfhi(ew.y), bflo(ew.z), bfhi(ew.z), bflo(ew.w), bfhi(ew.w)};
;                     float o[8];
; #pragma unroll
;                     for (int j = 0; j < 8; ++j) { const float a = acc[ai][bj][m][j >> 2][j & 3]; const float gg = gv[bj][j >> 2][j & 3];
;                         o[j] = r[j] + e[j] * ri * gg * __builtin_amdgcn_rcpf(1.f + __builtin_amdgcn_exp2f(-a * LOG2E)); }
;                     f32x4 o1, o2;
; #pragma unroll
;                     for (int j = 0; j < 4; ++j) { const unsigned a = __float_as_uint(o[j]), b = __float_as_uint(o[4 + j]); const unsigned sa = dpp_ror8(a), sb = dpp_ror8(b);
;                         o1[j] = __uint_as_float(lo ? a : sb); o2[j] = __uint_as_float(lo ? sa : b); }
;                     *(f32x4*)(orow + 32 * bj) = o1; *(f32x4*)(orow + (size_t)8 * D + 32 * bj) = o2; } }
	v_lshlrev_b32_e32 v80, 16, v97
	v_and_b32_e32 v81, 0xffff0000, v97
	v_pk_mul_f32 v[94:95], v[40:41], v[94:95]
	v_mov_b32_e32 v97, v157
	v_pk_fma_f32 v[80:81], v[84:85], v[94:95], v[80:81]
	v_lshlrev_b32_e32 v94, 16, v111
	v_and_b32_e32 v95, 0xffff0000, v111
	v_mov_b32_dpp v97, v80 row_ror:8 row_mask:0xf bank_mask:0xf
	v_pk_mul_f32 v[94:95], v[96:97], v[94:95] op_sel_hi:[0,1]
	v_lshlrev_b32_e32 v84, 16, v105
	v_and_b32_e32 v85, 0xffff0000, v105
	v_pk_mul_f32 v[94:95], v[46:47], v[94:95]
	v_add_co_u32_e32 v88, vcc, s45, v92
	v_pk_fma_f32 v[84:85], v[82:83], v[94:95], v[84:85]
	v_lshlrev_b32_e32 v94, 16, v108
	v_and_b32_e32 v95, 0xffff0000, v108
	v_cndmask_b32_e64 v98, v102, v106, s[0:1]
	v_addc_co_u32_e32 v89, vcc, 0, v93, vcc
	v_pk_mul_f32 v[94:95], v[96:97], v[94:95] op_sel_hi:[0,1]
	global_store_dwordx4 v[88:89], v[98:101], off
	v_mov_b32_e32 v102, v157
	v_lshlrev_b32_e32 v82, 16, v116
	v_mov_b32_e32 v98, v157
	v_mov_b32_e32 v99, v157
	v_mov_b32_e32 v101, v157
	v_and_b32_e32 v83, 0xffff0000, v116
	v_pk_mul_f32 v[94:95], v[42:43], v[94:95]
	v_mov_b32_dpp v98, v90 row_ror:8 row_mask:0xf bank_mask:0xf
	v_mov_b32_dpp v99, v91 row_ror:8 row_mask:0xf bank_mask:0xf
	v_mov_b32_e32 v100, v157
	v_mov_b32_dpp v101, v84 row_ror:8 row_mask:0xf bank_mask:0xf
	v_mov_b32_dpp v102, v85 row_ror:8 row_mask:0xf bank_mask:0xf
	v_pk_fma_f32 v[82:83], v[86:87], v[94:95], v[82:83]
	v_mov_b32_e32 v86, v157
	v_mov_b32_e32 v87, v157
	v_mov_b32_dpp v100, v81 row_ror:8 row_mask:0xf bank_mask:0xf
	v_mov_b32_dpp v86, v82 row_ror:8 row_mask:0xf bank_mask:0xf
	v_mov_b32_dpp v87, v83 row_ror:8 row_mask:0xf bank_mask:0xf
	v_cndmask_b32_e64 v83, v102, v83, s[0:1]
	v_cndmask_b32_e64 v82, v101, v82, s[0:1]
	v_cndmask_b32_e64 v81, v99, v81, s[0:1]
	v_cndmask_b32_e64 v80, v98, v80, s[0:1]
	v_cndmask_b32_e64 v87, v85, v87, s[0:1]
	v_cndmask_b32_e64 v86, v84, v86, s[0:1]
	v_cndmask_b32_e64 v85, v91, v100, s[0:1]
	v_cndmask_b32_e64 v84, v90, v97, s[0:1]
	global_store_dwordx4 v[92:93], v[80:83], off offset:128
	global_store_dwordx4 v[88:89], v[84:87], off offset:128
	s_waitcnt vmcnt(4)
	s_nop 0
	v_mov_b32_e32 v80, v228
	v_sub_u32_e32 v81, v170, v174
	v_add_u32_e32 v81, v81, v176
	v_add_u32_e32 v98, 0x80, v81
	v_ashrrev_i32_e32 v99, 31, v98
	v_lshlrev_b64 v[90:91], 12, v[98:99]
	v_lshl_add_u64 v[94:95], v[90:91], 0, s[16:17]
	v_lshl_add_u64 v[82:83], s[8:9], 0, v[90:91]
	v_lshl_add_u64 v[86:87], s[8:9], 0, v[94:95]
	v_lshl_add_u64 v[82:83], v[82:83], 0, v[164:165]
	v_lshl_add_u64 v[86:87], v[86:87], 0, v[164:165]
	v_mov_b64_e32 v[82:83], v[232:233]
	v_mov_b64_e32 v[84:85], v[234:235]
	v_lshl_add_u64 v[90:91], s[10:11], 0, v[90:91]
	v_mov_b64_e32 v[86:87], v[236:237]
	v_mov_b64_e32 v[88:89], v[238:239]
	v_lshl_add_u64 v[90:91], v[90:91], 0, v[164:165]
	v_lshl_add_u64 v[94:95], s[10:11], 0, v[94:95]
	v_mov_b64_e32 v[90:91], v[240:241]
	v_mov_b64_e32 v[92:93], v[242:243]
	v_lshl_add_u64 v[94:95], v[94:95], 0, v[164:165]
	v_mov_b64_e32 v[94:95], v[244:245]
	v_mov_b64_e32 v[96:97], v[246:247]
	s_nop 1
	v_add_u32_e32 v222, 0x90, v81
	v_ashrrev_i32_e32 v223, 31, v222
	global_load_dword v228, v[168:169], off offset:576
	v_lshlrev_b64 v[216:217], 12, v[222:223]
	v_lshl_add_u64 v[224:225], v[216:217], 0, s[16:17]
	v_lshl_add_u64 v[220:221], s[8:9], 0, v[224:225]
	v_lshl_add_u64 v[218:219], s[8:9], 0, v[216:217]
	v_lshl_add_u64 v[220:221], v[220:221], 0, v[164:165]
	v_lshl_add_u64 v[216:217], s[10:11], 0, v[216:217]
	v_lshl_add_u64 v[218:219], v[218:219], 0, v[164:165]
	global_load_dwordx4 v[232:235], v[220:221], off
	v_lshl_add_u64 v[216:217], v[216:217], 0, v[164:165]
	global_load_dwordx4 v[236:239], v[218:219], off
	global_load_dwordx4 v[240:243], v[216:217], off
	v_lshl_add_u64 v[216:217], s[10:11], 0, v[224:225]
	v_lshl_add_u64 v[216:217], v[216:217], 0, v[164:165]
	global_load_dwordx4 v[244:247], v[216:217], off
	v_mov_b32_e32 v106, v157
	v_mov_b32_e32 v107, v157
	v_mov_b32_e32 v100, v157
	v_mov_b32_e32 v101, v157
	v_mov_b32_e32 v102, v157
	v_mov_b32_e32 v103, v157
	v_mov_b32_e32 v105, v157
	v_mov_b32_e32 v104, v157
	v_add_f32_e32 v79, 1.0, v79
	v_mul_f32_e32 v64, 0xbfb8aa3b, v64
	v_mul_f32_e32 v65, 0xbfb8aa3b, v65
	v_rcp_f32_e32 v78, v78
	v_rcp_f32_e32 v79, v79
	v_exp_f32_e32 v64, v64
	v_exp_f32_e32 v65, v65
	v_mul_f32_e32 v68, 0xbfb8aa3b, v68
	v_mul_f32_e32 v69, 0xbfb8aa3b, v69
	v_exp_f32_e32 v68, v68
	v_exp_f32_e32 v69, v69
	v_add_f32_e32 v64, 1.0, v64
	v_add_f32_e32 v65, 1.0, v65
	v_rcp_f32_e32 v64, v64
	v_mul_f32_e32 v66, 0xbfb8aa3b, v66
	v_mul_f32_e32 v67, 0xbfb8aa3b, v67
	v_rcp_f32_e32 v65, v65
	v_exp_f32_e32 v66, v66
	v_exp_f32_e32 v67, v67
	v_add_f32_e32 v68, 1.0, v68
	v_add_f32_e32 v69, 1.0, v69
	v_rcp_f32_e32 v68, v68
	v_mul_f32_e32 v70, 0xbfb8aa3b, v70
	v_mul_f32_e32 v71, 0xbfb8aa3b, v71
	v_rcp_f32_e32 v69, v69
	v_exp_f32_e32 v70, v70
	v_exp_f32_e32 v71, v71
	v_add_f32_e32 v66, 1.0, v66
	v_add_f32_e32 v67, 1.0, v67
	v_rcp_f32_e32 v66, v66
	v_rcp_f32_e32 v67, v67
	v_add_f32_e32 v70, 1.0, v70
	v_add_f32_e32 v71, 1.0, v71
	v_rcp_f32_e32 v70, v70
	v_rcp_f32_e32 v71, v71
	v_mul_f32_e32 v48, 0xbfb8aa3b, v48
	v_mul_f32_e32 v49, 0xbfb8aa3b, v49
	v_mul_f32_e32 v52, 0xbfb8aa3b, v52
	v_exp_f32_e32 v48, v48
	v_exp_f32_e32 v49, v49
	v_mul_f32_e32 v50, 0xbfb8aa3b, v50
	v_mul_f32_e32 v51, 0xbfb8aa3b, v51
	v_add_f32_e32 v48, 1.0, v48
	v_add_f32_e32 v49, 1.0, v49
	v_rcp_f32_e32 v48, v48
	v_rcp_f32_e32 v49, v49
	v_exp_f32_e32 v50, v50
	v_exp_f32_e32 v51, v51
	v_mul_f32_e32 v54, 0xbfb8aa3b, v54
	v_mul_f32_e32 v55, 0xbfb8aa3b, v55
	v_exp_f32_e32 v54, v54
	v_exp_f32_e32 v55, v55
	v_add_f32_e32 v50, 1.0, v50
	v_fmamk_f32 v80, v80, 0x3a000000, v182
	v_rsq_f32_e32 v80, v80
	v_add_f32_e32 v51, 1.0, v51
; __device__ __forceinline__ float bflo(unsigned w) { return __uint_as_float(w << 16); }
; __device__ __forceinline__ float bfhi(unsigned w) { return __uint_as_float(w & 0xffff0000u); }
; __device__ __forceinline__ unsigned dpp_ror8(unsigned x) { return (unsigned)__builtin_amdgcn_update_dpp(0, (int)x, 0x128, 0xf, 0xf, false); }
;     __device__ __forceinline__ void operator()(const f32x4 (&acc)[2][2][4][2], const Unit& u, int wr, int wc, int fr, int fq) const {
;     ...
;         for (int ai = 0; ai < 2; ++ai)
; #pragma unroll
;             for (int m = 0; m < 4; ++m) { const int row = row0 + ai * HALF + m * 16; const float ri = __builtin_amdgcn_rsqf(sse[row] * (1.f / D) + EPS);
;                 u32x4 rr[2], ee[2]; load_pair_lines(R, D, row, fr, col0, rr[0], rr[1], 32); load_pair_lines(E, D, row, fr, col0, ee[0], ee[1], 32);
;                 float* orow = OUT + (size_t)(row - fr + (fr & 7)) * D + col0 + (lo ? 0 : 4);
; #pragma unroll
;                 for (int bj = 0; bj < 2; ++bj) { const u32x4 rw = rr[bj], ew = ee[bj];
;                     const float r[8] = {bflo(rw.x), bfhi(rw.x), bflo(rw.y), bfhi(rw.y), bflo(rw.z), bfhi(rw.z), bflo(rw.w), bfhi(rw.w)};
;                     const float e[8] = {bflo(ew.x), bfhi(ew.x), bflo(ew.y), bfhi(ew.y), bflo(ew.z), bfhi(ew.z), bflo(ew.w), bfhi(ew.w)};
;                     float o[8];
; #pragma unroll
;                     for (int j = 0; j < 8; ++j) { const float a = acc[ai][bj][m][j >> 2][j & 3]; const float gg = gv[bj][j >> 2][j & 3];
;                         o[j] = r[j] + e[j] * ri * gg * __builtin_amdgcn_rcpf(1.f + __builtin_amdgcn_exp2f(-a * LOG2E)); }
;                     f32x4 o1, o2;
; #pragma unroll
;                     for (int j = 0; j < 4; ++j) { const unsigned a = __float_as_uint(o[j]), b = __float_as_uint(o[4 + j]); const unsigned sa = dpp_ror8(a), sb = dpp_ror8(b);
;                         o1[j] = __uint_as_float(lo ? a : sb); o2[j] = __uint_as_float(lo ? sa : b); }
;                     *(f32x4*)(orow + 32 * bj) = o1; *(f32x4*)(orow + (size_t)8 * D + 32 * bj) = o2; } }
	v_rcp_f32_e32 v50, v50
	v_rcp_f32_e32 v51, v51
	v_add_f32_e32 v54, 1.0, v54
	v_add_f32_e32 v55, 1.0, v55
	v_mul_f32_e32 v32, 0xbfb8aa3b, v32
	v_mul_f32_e32 v33, 0xbfb8aa3b, v33
	v_rcp_f32_e32 v54, v54
	v_rcp_f32_e32 v55, v55
	v_mov_b32_dpp v100, v82 row_ror:8 row_mask:0xf bank_mask:0xf
	v_mov_b32_dpp v101, v83 row_ror:8 row_mask:0xf bank_mask:0xf
	v_mov_b32_dpp v106, v88 row_ror:8 row_mask:0xf bank_mask:0xf
	v_mov_b32_dpp v107, v89 row_ror:8 row_mask:0xf bank_mask:0xf
	v_mov_b32_dpp v102, v84 row_ror:8 row_mask:0xf bank_mask:0xf
	v_mov_b32_dpp v103, v85 row_ror:8 row_mask:0xf bank_mask:0xf
	v_mov_b32_dpp v105, v87 row_ror:8 row_mask:0xf bank_mask:0xf
	v_cndmask_b32_e64 v107, v107, v85, s[0:1]
	v_cndmask_b32_e64 v85, v106, v84, s[0:1]
	v_mov_b32_e32 v84, v157
	v_mov_b32_dpp v104, v86 row_ror:8 row_mask:0xf bank_mask:0xf
	v_cndmask_b32_e64 v105, v105, v83, s[0:1]
	v_cndmask_b32_e64 v101, v87, v101, s[0:1]
	v_cndmask_b32_e64 v89, v89, v103, s[0:1]
	v_cndmask_b32_e64 v100, v86, v100, s[0:1]
	v_mov_b32_e32 v83, v157
	v_mov_b32_dpp v84, v92 row_ror:8 row_mask:0xf bank_mask:0xf
	v_mov_b32_e32 v86, v157
	v_mov_b32_e32 v87, v157
	v_mov_b32_e32 v103, v157
	v_cndmask_b32_e64 v104, v104, v82, s[0:1]
	v_cndmask_b32_e64 v88, v88, v102, s[0:1]
	v_mov_b32_e32 v82, v157
	v_mov_b32_dpp v83, v91 row_ror:8 row_mask:0xf bank_mask:0xf
	v_mov_b32_dpp v86, v93 row_ror:8 row_mask:0xf bank_mask:0xf
	v_mov_b32_dpp v87, v94 row_ror:8 row_mask:0xf bank_mask:0xf
	v_mov_b32_e32 v102, v157
	v_mov_b32_dpp v103, v96 row_ror:8 row_mask:0xf bank_mask:0xf
	v_cndmask_b32_e64 v96, v96, v84, s[0:1]
	v_exp_f32_e32 v84, v76
	v_mul_f32_e32 v76, 0xbfb8aa3b, v77
	v_mov_b32_dpp v82, v90 row_ror:8 row_mask:0xf bank_mask:0xf
	v_mov_b32_dpp v102, v95 row_ror:8 row_mask:0xf bank_mask:0xf
	v_cndmask_b32_e64 v90, v87, v90, s[0:1]
	v_cndmask_b32_e64 v87, v103, v92, s[0:1]
	v_cndmask_b32_e64 v92, v95, v83, s[0:1]
	v_cndmask_b32_e64 v95, v97, v86, s[0:1]
	v_exp_f32_e32 v86, v76
	v_cndmask_b32_e64 v94, v94, v82, s[0:1]
	v_lshlrev_b64 v[82:83], 13, v[98:99]
	v_lshl_add_u64 v[82:83], s[4:5], 0, v[82:83]
	v_lshl_add_u64 v[82:83], v[82:83], 0, v[166:167]
	v_lshl_add_u64 v[76:77], v[82:83], 0, v[156:157]
	v_add_f32_e32 v83, 1.0, v86
	v_lshlrev_b32_e32 v86, 16, v87
	v_and_b32_e32 v87, 0xffff0000, v87
	v_add_f32_e32 v82, 1.0, v84
	v_pk_mul_f32 v[86:87], v[80:81], v[86:87] op_sel_hi:[0,1]
	v_rcp_f32_e32 v82, v82
	v_rcp_f32_e32 v83, v83
	v_lshlrev_b32_e32 v84, 16, v85
	v_and_b32_e32 v85, 0xffff0000, v85
	v_pk_mul_f32 v[86:87], v[60:61], v[86:87]
	v_mov_b32_e32 v106, v157
	v_pk_fma_f32 v[86:87], v[72:73], v[86:87], v[84:85]
	v_lshlrev_b32_e32 v84, 16, v90
	v_and_b32_e32 v85, 0xffff0000, v90
	v_mov_b32_dpp v106, v97 row_ror:8 row_mask:0xf bank_mask:0xf
	v_pk_mul_f32 v[84:85], v[80:81], v[84:85] op_sel_hi:[0,1]
	v_cndmask_b32_e64 v93, v106, v93, s[0:1]
	v_lshlrev_b32_e32 v72, 16, v104
	v_and_b32_e32 v73, 0xffff0000, v104
	v_pk_mul_f32 v[84:85], v[56:57], v[84:85]
	v_cndmask_b32_e64 v91, v102, v91, s[0:1]
	v_pk_fma_f32 v[72:73], v[82:83], v[84:85], v[72:73]
	v_lshlrev_b32_e32 v84, 16, v93
	v_and_b32_e32 v85, 0xffff0000, v93
	v_pk_mul_f32 v[84:85], v[80:81], v[84:85] op_sel_hi:[0,1]
	v_lshlrev_b32_e32 v82, 16, v107
	v_and_b32_e32 v83, 0xffff0000, v107
	v_pk_mul_f32 v[84:85], v[62:63], v[84:85]
	v_mov_b32_e32 v97, v157
	v_pk_fma_f32 v[82:83], v[74:75], v[84:85], v[82:83]
	v_lshlrev_b32_e32 v84, 16, v91
	v_and_b32_e32 v85, 0xffff0000, v91
	v_pk_mul_f32 v[84:85], v[80:81], v[84:85] op_sel_hi:[0,1]
	v_lshlrev_b32_e32 v74, 16, v105
	v_and_b32_e32 v75, 0xffff0000, v105
	v_pk_mul_f32 v[84:85], v[58:59], v[84:85]
	v_mov_b32_e32 v98, v157
	v_pk_fma_f32 v[74:75], v[78:79], v[84:85], v[74:75]
	v_mov_b32_e32 v78, v157
	v_mov_b32_e32 v79, v157
	v_mov_b32_e32 v93, v157
	v_mov_b32_e32 v102, v157
	v_mov_b32_dpp v78, v74 row_ror:8 row_mask:0xf bank_mask:0xf
	v_mov_b32_dpp v79, v75 row_ror:8 row_mask:0xf bank_mask:0xf
	v_mov_b32_dpp v97, v86 row_ror:8 row_mask:0xf bank_mask:0xf
	v_mov_b32_dpp v98, v87 row_ror:8 row_mask:0xf bank_mask:0xf
	v_mov_b32_e32 v90, v157
	v_mov_b32_e32 v99, v157
	v_mov_b32_dpp v93, v82 row_ror:8 row_mask:0xf bank_mask:0xf
	v_mov_b32_dpp v102, v83 row_ror:8 row_mask:0xf bank_mask:0xf
	v_cndmask_b32_e64 v85, v83, v79, s[0:1]
	v_cndmask_b32_e64 v84, v82, v78, s[0:1]
	v_lshlrev_b32_e32 v78, 16, v96
	v_and_b32_e32 v79, 0xffff0000, v96
	v_mov_b32_dpp v90, v72 row_ror:8 row_mask:0xf bank_mask:0xf
	v_mov_b32_dpp v99, v73 row_ror:8 row_mask:0xf bank_mask:0xf
	v_cndmask_b32_e64 v75, v102, v75, s[0:1]
	v_cndmask_b32_e64 v74, v93, v74, s[0:1]
	v_cndmask_b32_e64 v73, v98, v73, s[0:1]
	v_cndmask_b32_e64 v72, v97, v72, s[0:1]
	v_pk_mul_f32 v[78:79], v[80:81], v[78:79] op_sel_hi:[0,1]
	global_store_dwordx4 v[76:77], v[72:75], off
	v_pk_mul_f32 v[78:79], v[44:45], v[78:79]
	v_cndmask_b32_e64 v83, v87, v99, s[0:1]
	v_lshlrev_b32_e32 v74, 16, v88
	v_and_b32_e32 v75, 0xffff0000, v88
	v_pk_fma_f32 v[74:75], v[64:65], v[78:79], v[74:75]
	v_lshlrev_b32_e32 v78, 16, v94
	v_and_b32_e32 v79, 0xffff0000, v94
	v_pk_mul_f32 v[78:79], v[80:81], v[78:79] op_sel_hi:[0,1]
	v_lshlrev_b32_e32 v64, 16, v100
	v_and_b32_e32 v65, 0xffff0000, v100
	v_pk_mul_f32 v[78:79], v[40:41], v[78:79]
	v_add_co_u32_e32 v72, vcc, s45, v76
	v_pk_fma_f32 v[64:65], v[68:69], v[78:79], v[64:65]
	v_lshlrev_b32_e32 v78, 16, v95
	v_and_b32_e32 v79, 0xffff0000, v95
	v_pk_mul_f32 v[78:79], v[80:81], v[78:79] op_sel_hi:[0,1]
	v_lshlrev_b32_e32 v68, 16, v89
	v_and_b32_e32 v69, 0xffff0000, v89
	v_pk_mul_f32 v[78:79], v[46:47], v[78:79]
	v_cndmask_b32_e64 v82, v86, v90, s[0:1]
	v_pk_fma_f32 v[68:69], v[66:67], v[78:79], v[68:69]
	v_lshlrev_b32_e32 v78, 16, v92
; __device__ __forceinline__ float bflo(unsigned w) { return __uint_as_float(w << 16); }
; __device__ __forceinline__ float bfhi(unsigned w) { return __uint_as_float(w & 0xffff0000u); }
; __device__ __forceinline__ unsigned dpp_ror8(unsigned x) { return (unsigned)__builtin_amdgcn_update_dpp(0, (int)x, 0x128, 0xf, 0xf, false); }
;     __device__ __forceinline__ void operator()(const f32x4 (&acc)[2][2][4][2], const Unit& u, int wr, int wc, int fr, int fq) const {
;     ...
;         for (int ai = 0; ai < 2; ++ai)
; #pragma unroll
;             for (int m = 0; m < 4; ++m) { const int row = row0 + ai * HALF + m * 16; const float ri = __builtin_amdgcn_rsqf(sse[row] * (1.f / D) + EPS);
;                 u32x4 rr[2], ee[2]; load_pair_lines(R, D, row, fr, col0, rr[0], rr[1], 32); load_pair_lines(E, D, row, fr, col0, ee[0], ee[1], 32);
;                 float* orow = OUT + (size_t)(row - fr + (fr & 7)) * D + col0 + (lo ? 0 : 4);
; #pragma unroll
;                 for (int bj = 0; bj < 2; ++bj) { const u32x4 rw = rr[bj], ew = ee[bj];
;                     const float r[8] = {bflo(rw.x), bfhi(rw.x), bflo(rw.y), bfhi(rw.y), bflo(rw.z), bfhi(rw.z), bflo(rw.w), bfhi(rw.w)};
;                     const float e[8] = {bflo(ew.x), bfhi(ew.x), bflo(ew.y), bfhi(ew.y), bflo(ew.z), bfhi(ew.z), bflo(ew.w), bfhi(ew.w)};
;                     float o[8];
; #pragma unroll
;                     for (int j = 0; j < 8; ++j) { const float a = acc[ai][bj][m][j >> 2][j & 3]; const float gg = gv[bj][j >> 2][j & 3];
;                         o[j] = r[j] + e[j] * ri * gg * __builtin_amdgcn_rcpf(1.f + __builtin_amdgcn_exp2f(-a * LOG2E)); }
;                     f32x4 o1, o2;
; #pragma unroll
;                     for (int j = 0; j < 4; ++j) { const unsigned a = __float_as_uint(o[j]), b = __float_as_uint(o[4 + j]); const unsigned sa = dpp_ror8(a), sb = dpp_ror8(b);
;                         o1[j] = __uint_as_float(lo ? a : sb); o2[j] = __uint_as_float(lo ? sa : b); }
;                     *(f32x4*)(orow + 32 * bj) = o1; *(f32x4*)(orow + (size_t)8 * D + 32 * bj) = o2; } }
	v_and_b32_e32 v79, 0xffff0000, v92
	v_addc_co_u32_e32 v73, vcc, 0, v77, vcc
	v_pk_mul_f32 v[78:79], v[80:81], v[78:79] op_sel_hi:[0,1]
	global_store_dwordx4 v[72:73], v[82:85], off
	v_mov_b32_e32 v86, v157
	v_mov_b32_e32 v87, v157
	v_mov_b32_e32 v82, v157
	v_mov_b32_e32 v83, v157
	v_lshlrev_b32_e32 v66, 16, v101
	v_and_b32_e32 v67, 0xffff0000, v101
	v_pk_mul_f32 v[78:79], v[42:43], v[78:79]
	v_mov_b32_dpp v82, v74 row_ror:8 row_mask:0xf bank_mask:0xf
	v_mov_b32_dpp v83, v75 row_ror:8 row_mask:0xf bank_mask:0xf
	v_mov_b32_e32 v84, v157
	v_mov_b32_e32 v85, v157
	v_mov_b32_dpp v86, v68 row_ror:8 row_mask:0xf bank_mask:0xf
	v_mov_b32_dpp v87, v69 row_ror:8 row_mask:0xf bank_mask:0xf
	v_pk_fma_f32 v[66:67], v[70:71], v[78:79], v[66:67]
	v_mov_b32_e32 v70, v157
	v_mov_b32_e32 v71, v157
	v_add_u32_e32 v78, 0x90, v81
	v_mov_b32_dpp v84, v64 row_ror:8 row_mask:0xf bank_mask:0xf
	v_mov_b32_dpp v85, v65 row_ror:8 row_mask:0xf bank_mask:0xf
	v_mov_b32_dpp v70, v66 row_ror:8 row_mask:0xf bank_mask:0xf
	v_mov_b32_dpp v71, v67 row_ror:8 row_mask:0xf bank_mask:0xf
	v_cndmask_b32_e64 v67, v87, v67, s[0:1]
	v_cndmask_b32_e64 v66, v86, v66, s[0:1]
	v_cndmask_b32_e64 v65, v83, v65, s[0:1]
	v_cndmask_b32_e64 v64, v82, v64, s[0:1]
	v_ashrrev_i32_e32 v79, 31, v78
	v_cndmask_b32_e64 v71, v69, v71, s[0:1]
	v_cndmask_b32_e64 v70, v68, v70, s[0:1]
	v_cndmask_b32_e64 v69, v75, v85, s[0:1]
	v_cndmask_b32_e64 v68, v74, v84, s[0:1]
	global_store_dwordx4 v[76:77], v[64:67], off offset:128
	global_store_dwordx4 v[72:73], v[68:71], off offset:128
	s_waitcnt vmcnt(4)
	s_nop 0
	v_mov_b32_e32 v80, v228
	v_lshlrev_b64 v[64:65], 12, v[78:79]
	v_lshl_add_u64 v[82:83], v[64:65], 0, s[16:17]
	v_lshl_add_u64 v[70:71], s[8:9], 0, v[82:83]
	v_lshl_add_u64 v[66:67], s[8:9], 0, v[64:65]
	v_lshl_add_u64 v[70:71], v[70:71], 0, v[164:165]
	v_lshl_add_u64 v[64:65], s[10:11], 0, v[64:65]
	v_lshl_add_u64 v[66:67], v[66:67], 0, v[164:165]
	v_mov_b64_e32 v[70:71], v[232:233]
	v_mov_b64_e32 v[72:73], v[234:235]
	v_lshl_add_u64 v[64:65], v[64:65], 0, v[164:165]
	v_mov_b64_e32 v[66:67], v[236:237]
	v_mov_b64_e32 v[68:69], v[238:239]
	v_mov_b32_e32 v90, v157
	v_mov_b64_e32 v[74:75], v[240:241]
	v_mov_b64_e32 v[76:77], v[242:243]
	v_lshl_add_u64 v[64:65], s[10:11], 0, v[82:83]
	v_lshl_add_u64 v[64:65], v[64:65], 0, v[164:165]
	v_mov_b64_e32 v[82:83], v[244:245]
	v_mov_b64_e32 v[84:85], v[246:247]
	s_nop 1
	global_load_dword v228, v[168:169], off offset:640
	v_add_u32_e32 v220, 0xa0, v81
	v_ashrrev_i32_e32 v221, 31, v220
	v_lshlrev_b64 v[216:217], 12, v[220:221]
	v_lshl_add_u64 v[224:225], v[216:217], 0, s[16:17]
	v_lshl_add_u64 v[222:223], s[8:9], 0, v[224:225]
	v_lshl_add_u64 v[218:219], s[8:9], 0, v[216:217]
	v_lshl_add_u64 v[222:223], v[222:223], 0, v[164:165]
	v_lshl_add_u64 v[216:217], s[10:11], 0, v[216:217]
	v_lshl_add_u64 v[218:219], v[218:219], 0, v[164:165]
	global_load_dwordx4 v[232:235], v[222:223], off
	v_lshl_add_u64 v[216:217], v[216:217], 0, v[164:165]
	global_load_dwordx4 v[236:239], v[218:219], off
	global_load_dwordx4 v[240:243], v[216:217], off
	v_lshl_add_u64 v[216:217], s[10:11], 0, v[224:225]
	v_lshl_add_u64 v[216:217], v[216:217], 0, v[164:165]
	global_load_dwordx4 v[244:247], v[216:217], off
	v_mov_b32_e32 v91, v157
	v_mov_b32_e32 v65, v157
	v_mov_b32_e32 v86, v157
	v_mov_b32_e32 v87, v157
	v_mov_b32_e32 v89, v157
	v_mov_b32_e32 v88, v157
	v_exp_f32_e32 v32, v32
	v_exp_f32_e32 v33, v33
	v_mul_f32_e32 v36, 0xbfb8aa3b, v36
	v_mul_f32_e32 v37, 0xbfb8aa3b, v37
	v_exp_f32_e32 v36, v36
	v_exp_f32_e32 v37, v37
	v_add_f32_e32 v32, 1.0, v32
	v_add_f32_e32 v33, 1.0, v33
	v_rcp_f32_e32 v32, v32
	v_rcp_f32_e32 v33, v33
	v_mul_f32_e32 v34, 0xbfb8aa3b, v34
	v_mul_f32_e32 v35, 0xbfb8aa3b, v35
	v_add_f32_e32 v36, 1.0, v36
	v_add_f32_e32 v37, 1.0, v37
	v_exp_f32_e32 v34, v34
	v_exp_f32_e32 v35, v35
	v_rcp_f32_e32 v36, v36
	v_rcp_f32_e32 v37, v37
	v_mul_f32_e32 v38, 0xbfb8aa3b, v38
	v_mul_f32_e32 v39, 0xbfb8aa3b, v39
	v_exp_f32_e32 v38, v38
	v_exp_f32_e32 v39, v39
	v_add_f32_e32 v34, 1.0, v34
	v_add_f32_e32 v35, 1.0, v35
	v_rcp_f32_e32 v34, v34
	v_rcp_f32_e32 v35, v35
	v_add_f32_e32 v38, 1.0, v38
	v_add_f32_e32 v39, 1.0, v39
	v_rcp_f32_e32 v38, v38
	v_rcp_f32_e32 v39, v39
	v_mul_f32_e32 v24, 0xbfb8aa3b, v24
	v_mul_f32_e32 v25, 0xbfb8aa3b, v25
	v_mul_f32_e32 v28, 0xbfb8aa3b, v28
	v_exp_f32_e32 v24, v24
	v_exp_f32_e32 v25, v25
	v_mul_f32_e32 v26, 0xbfb8aa3b, v26
	v_mul_f32_e32 v27, 0xbfb8aa3b, v27
	v_add_f32_e32 v24, 1.0, v24
	v_add_f32_e32 v25, 1.0, v25
	v_rcp_f32_e32 v24, v24
	v_rcp_f32_e32 v25, v25
	v_exp_f32_e32 v26, v26
	v_exp_f32_e32 v27, v27
	v_mul_f32_e32 v30, 0xbfb8aa3b, v30
	v_mul_f32_e32 v31, 0xbfb8aa3b, v31
	v_exp_f32_e32 v30, v30
	v_exp_f32_e32 v31, v31
	v_add_f32_e32 v26, 1.0, v26
	v_add_f32_e32 v27, 1.0, v27
	v_rcp_f32_e32 v26, v26
	v_rcp_f32_e32 v27, v27
	v_add_f32_e32 v30, 1.0, v30
	v_add_f32_e32 v31, 1.0, v31
	v_mul_f32_e32 v16, 0xbfb8aa3b, v16
	v_mul_f32_e32 v17, 0xbfb8aa3b, v17
	v_rcp_f32_e32 v30, v30
	v_rcp_f32_e32 v31, v31
	v_exp_f32_e32 v16, v16
	v_fmamk_f32 v64, v80, 0x3a000000, v182
	v_mov_b32_e32 v80, v157
	v_rsq_f32_e32 v64, v64
	v_exp_f32_e32 v17, v17
	v_mul_f32_e32 v20, 0xbfb8aa3b, v20
	v_mul_f32_e32 v21, 0xbfb8aa3b, v21
	v_exp_f32_e32 v20, v20
	v_exp_f32_e32 v21, v21
	v_mov_b32_dpp v90, v72 row_ror:8 row_mask:0xf bank_mask:0xf
	v_mov_b32_dpp v91, v73 row_ror:8 row_mask:0xf bank_mask:0xf
	v_mov_b32_dpp v65, v66 row_ror:8 row_mask:0xf bank_mask:0xf
	v_mov_b32_dpp v80, v67 row_ror:8 row_mask:0xf bank_mask:0xf
	v_mov_b32_dpp v86, v68 row_ror:8 row_mask:0xf bank_mask:0xf
	v_mov_b32_dpp v87, v69 row_ror:8 row_mask:0xf bank_mask:0xf
	v_mov_b32_dpp v89, v71 row_ror:8 row_mask:0xf bank_mask:0xf
; __device__ __forceinline__ float bflo(unsigned w) { return __uint_as_float(w << 16); }
; __device__ __forceinline__ float bfhi(unsigned w) { return __uint_as_float(w & 0xffff0000u); }
; __device__ __forceinline__ unsigned dpp_ror8(unsigned x) { return (unsigned)__builtin_amdgcn_update_dpp(0, (int)x, 0x128, 0xf, 0xf, false); }
;     __device__ __forceinline__ void operator()(const f32x4 (&acc)[2][2][4][2], const Unit& u, int wr, int wc, int fr, int fq) const {
;     ...
;         for (int ai = 0; ai < 2; ++ai)
; #pragma unroll
;             for (int m = 0; m < 4; ++m) { const int row = row0 + ai * HALF + m * 16; const float ri = __builtin_amdgcn_rsqf(sse[row] * (1.f / D) + EPS);
;                 u32x4 rr[2], ee[2]; load_pair_lines(R, D, row, fr, col0, rr[0], rr[1], 32); load_pair_lines(E, D, row, fr, col0, ee[0], ee[1], 32);
;                 float* orow = OUT + (size_t)(row - fr + (fr & 7)) * D + col0 + (lo ? 0 : 4);
; #pragma unroll
;                 for (int bj = 0; bj < 2; ++bj) { const u32x4 rw = rr[bj], ew = ee[bj];
;                     const float r[8] = {bflo(rw.x), bfhi(rw.x), bflo(rw.y), bfhi(rw.y), bflo(rw.z), bfhi(rw.z), bflo(rw.w), bfhi(rw.w)};
;                     const float e[8] = {bflo(ew.x), bfhi(ew.x), bflo(ew.y), bfhi(ew.y), bflo(ew.z), bfhi(ew.z), bflo(ew.w), bfhi(ew.w)};
;                     float o[8];
; #pragma unroll
;                     for (int j = 0; j < 8; ++j) { const float a = acc[ai][bj][m][j >> 2][j & 3]; const float gg = gv[bj][j >> 2][j & 3];
;                         o[j] = r[j] + e[j] * ri * gg * __builtin_amdgcn_rcpf(1.f + __builtin_amdgcn_exp2f(-a * LOG2E)); }
;                     f32x4 o1, o2;
; #pragma unroll
;                     for (int j = 0; j < 4; ++j) { const unsigned a = __float_as_uint(o[j]), b = __float_as_uint(o[4 + j]); const unsigned sa = dpp_ror8(a), sb = dpp_ror8(b);
;                         o1[j] = __uint_as_float(lo ? a : sb); o2[j] = __uint_as_float(lo ? sa : b); }
;                     *(f32x4*)(orow + 32 * bj) = o1; *(f32x4*)(orow + (size_t)8 * D + 32 * bj) = o2; } }
	v_cndmask_b32_e64 v91, v91, v69, s[0:1]
	v_cndmask_b32_e64 v69, v90, v68, s[0:1]
	v_mov_b32_e32 v68, v157
	v_mov_b32_dpp v88, v70 row_ror:8 row_mask:0xf bank_mask:0xf
	v_cndmask_b32_e64 v89, v89, v67, s[0:1]
	v_cndmask_b32_e64 v80, v71, v80, s[0:1]
	v_cndmask_b32_e64 v73, v73, v87, s[0:1]
	v_cndmask_b32_e64 v65, v70, v65, s[0:1]
	v_mov_b32_e32 v67, v157
	v_mov_b32_dpp v68, v76 row_ror:8 row_mask:0xf bank_mask:0xf
	v_mov_b32_e32 v70, v157
	v_mov_b32_e32 v71, v157
	v_mov_b32_e32 v87, v157
	v_cndmask_b32_e64 v88, v88, v66, s[0:1]
	v_cndmask_b32_e64 v72, v72, v86, s[0:1]
	v_mov_b32_e32 v66, v157
	v_mov_b32_dpp v67, v75 row_ror:8 row_mask:0xf bank_mask:0xf
	v_mov_b32_dpp v70, v77 row_ror:8 row_mask:0xf bank_mask:0xf
	v_mov_b32_dpp v71, v82 row_ror:8 row_mask:0xf bank_mask:0xf
	v_mov_b32_e32 v86, v157
	v_mov_b32_dpp v87, v84 row_ror:8 row_mask:0xf bank_mask:0xf
	v_cndmask_b32_e64 v84, v84, v68, s[0:1]
	v_exp_f32_e32 v68, v52
	v_mul_f32_e32 v52, 0xbfb8aa3b, v53
	v_mov_b32_dpp v66, v74 row_ror:8 row_mask:0xf bank_mask:0xf
	v_mov_b32_dpp v86, v83 row_ror:8 row_mask:0xf bank_mask:0xf
	v_cndmask_b32_e64 v74, v71, v74, s[0:1]
	v_cndmask_b32_e64 v71, v87, v76, s[0:1]
	v_cndmask_b32_e64 v76, v83, v67, s[0:1]
	v_cndmask_b32_e64 v83, v85, v70, s[0:1]
	v_exp_f32_e32 v70, v52
	v_cndmask_b32_e64 v82, v82, v66, s[0:1]
	v_lshlrev_b64 v[66:67], 13, v[78:79]
	v_lshl_add_u64 v[66:67], s[4:5], 0, v[66:67]
	v_lshl_add_u64 v[66:67], v[66:67], 0, v[166:167]
	v_lshl_add_u64 v[52:53], v[66:67], 0, v[156:157]
	v_add_f32_e32 v67, 1.0, v70
	v_lshlrev_b32_e32 v70, 16, v71
	v_and_b32_e32 v71, 0xffff0000, v71
	v_add_f32_e32 v66, 1.0, v68
	v_pk_mul_f32 v[70:71], v[64:65], v[70:71] op_sel_hi:[0,1]
	v_rcp_f32_e32 v66, v66
	v_rcp_f32_e32 v67, v67
	v_lshlrev_b32_e32 v68, 16, v69
	v_and_b32_e32 v69, 0xffff0000, v69
	v_pk_mul_f32 v[70:71], v[60:61], v[70:71]
	v_mov_b32_e32 v90, v157
	v_pk_fma_f32 v[70:71], v[48:49], v[70:71], v[68:69]
	v_lshlrev_b32_e32 v68, 16, v74
	v_and_b32_e32 v69, 0xffff0000, v74
	v_mov_b32_dpp v90, v85 row_ror:8 row_mask:0xf bank_mask:0xf
	v_pk_mul_f32 v[68:69], v[64:65], v[68:69] op_sel_hi:[0,1]
	v_cndmask_b32_e64 v77, v90, v77, s[0:1]
	v_lshlrev_b32_e32 v48, 16, v88
	v_and_b32_e32 v49, 0xffff0000, v88
	v_pk_mul_f32 v[68:69], v[56:57], v[68:69]
	v_cndmask_b32_e64 v75, v86, v75, s[0:1]
	v_pk_fma_f32 v[48:49], v[66:67], v[68:69], v[48:49]
	v_lshlrev_b32_e32 v68, 16, v77
	v_and_b32_e32 v69, 0xffff0000, v77
	v_pk_mul_f32 v[68:69], v[64:65], v[68:69] op_sel_hi:[0,1]
	v_lshlrev_b32_e32 v66, 16, v91
	v_and_b32_e32 v67, 0xffff0000, v91
	v_pk_mul_f32 v[68:69], v[62:63], v[68:69]
	v_mov_b32_e32 v78, v157
	v_pk_fma_f32 v[66:67], v[50:51], v[68:69], v[66:67]
	v_lshlrev_b32_e32 v68, 16, v75
	v_and_b32_e32 v69, 0xffff0000, v75
	v_pk_mul_f32 v[68:69], v[64:65], v[68:69] op_sel_hi:[0,1]
	v_lshlrev_b32_e32 v50, 16, v89
	v_and_b32_e32 v51, 0xffff0000, v89
	v_pk_mul_f32 v[68:69], v[58:59], v[68:69]
	v_mov_b32_e32 v79, v157
	v_pk_fma_f32 v[50:51], v[54:55], v[68:69], v[50:51]
	v_mov_b32_e32 v54, v157
	v_mov_b32_e32 v55, v157
	v_mov_b32_e32 v77, v157
	v_mov_b32_e32 v86, v157
	v_mov_b32_dpp v54, v50 row_ror:8 row_mask:0xf bank_mask:0xf
	v_mov_b32_dpp v55, v51 row_ror:8 row_mask:0xf bank_mask:0xf
	v_mov_b32_dpp v78, v70 row_ror:8 row_mask:0xf bank_mask:0xf
	v_mov_b32_dpp v79, v71 row_ror:8 row_mask:0xf bank_mask:0xf
	v_mov_b32_e32 v74, v157
	v_mov_b32_e32 v85, v157
	v_mov_b32_dpp v77, v66 row_ror:8 row_mask:0xf bank_mask:0xf
	v_mov_b32_dpp v86, v67 row_ror:8 row_mask:0xf bank_mask:0xf
	v_cndmask_b32_e64 v69, v67, v55, s[0:1]
	v_cndmask_b32_e64 v68, v66, v54, s[0:1]
	v_lshlrev_b32_e32 v54, 16, v84
	v_and_b32_e32 v55, 0xffff0000, v84
	v_mov_b32_dpp v74, v48 row_ror:8 row_mask:0xf bank_mask:0xf
	v_mov_b32_dpp v85, v49 row_ror:8 row_mask:0xf bank_mask:0xf
	v_cndmask_b32_e64 v51, v86, v51, s[0:1]
	v_cndmask_b32_e64 v50, v77, v50, s[0:1]
	v_cndmask_b32_e64 v49, v79, v49, s[0:1]
	v_cndmask_b32_e64 v48, v78, v48, s[0:1]
	v_pk_mul_f32 v[54:55], v[64:65], v[54:55] op_sel_hi:[0,1]
	global_store_dwordx4 v[52:53], v[48:51], off
	v_pk_mul_f32 v[54:55], v[44:45], v[54:55]
	v_cndmask_b32_e64 v67, v71, v85, s[0:1]
	v_lshlrev_b32_e32 v50, 16, v72
	v_and_b32_e32 v51, 0xffff0000, v72
	v_pk_fma_f32 v[50:51], v[32:33], v[54:55], v[50:51]
	v_lshlrev_b32_e32 v54, 16, v82
	v_and_b32_e32 v55, 0xffff0000, v82
	v_pk_mul_f32 v[54:55], v[64:65], v[54:55] op_sel_hi:[0,1]
	v_lshlrev_b32_e32 v32, 16, v65
	v_and_b32_e32 v33, 0xffff0000, v65
	v_pk_mul_f32 v[54:55], v[40:41], v[54:55]
	v_mov_b32_e32 v65, v157
	v_pk_fma_f32 v[32:33], v[36:37], v[54:55], v[32:33]
	v_lshlrev_b32_e32 v54, 16, v83
	v_and_b32_e32 v55, 0xffff0000, v83
	v_mov_b32_dpp v65, v32 row_ror:8 row_mask:0xf bank_mask:0xf
	v_pk_mul_f32 v[54:55], v[64:65], v[54:55] op_sel_hi:[0,1]
	v_lshlrev_b32_e32 v36, 16, v73
	v_and_b32_e32 v37, 0xffff0000, v73
	v_pk_mul_f32 v[54:55], v[46:47], v[54:55]
	v_add_co_u32_e32 v48, vcc, s45, v52
	v_pk_fma_f32 v[36:37], v[34:35], v[54:55], v[36:37]
	v_lshlrev_b32_e32 v54, 16, v76
	v_and_b32_e32 v55, 0xffff0000, v76
	v_pk_mul_f32 v[54:55], v[64:65], v[54:55] op_sel_hi:[0,1]
	v_cndmask_b32_e64 v66, v70, v74, s[0:1]
	v_addc_co_u32_e32 v49, vcc, 0, v53, vcc
	v_lshlrev_b32_e32 v34, 16, v80
	v_and_b32_e32 v35, 0xffff0000, v80
	v_pk_mul_f32 v[54:55], v[42:43], v[54:55]
	global_store_dwordx4 v[48:49], v[66:69], off
	v_mov_b32_e32 v70, v157
	v_pk_fma_f32 v[34:35], v[38:39], v[54:55], v[34:35]
	v_mov_b32_e32 v66, v157
	v_mov_b32_e32 v67, v157
	v_mov_b32_e32 v69, v157
	v_mov_b32_e32 v38, v157
	v_mov_b32_dpp v66, v50 row_ror:8 row_mask:0xf bank_mask:0xf
	v_mov_b32_dpp v67, v51 row_ror:8 row_mask:0xf bank_mask:0xf
	v_mov_b32_e32 v68, v157
	v_mov_b32_dpp v69, v36 row_ror:8 row_mask:0xf bank_mask:0xf
	v_mov_b32_dpp v70, v37 row_ror:8 row_mask:0xf bank_mask:0xf
	v_mov_b32_dpp v38, v34 row_ror:8 row_mask:0xf bank_mask:0xf
	v_mov_b32_e32 v39, v157
	v_mov_b32_dpp v68, v33 row_ror:8 row_mask:0xf bank_mask:0xf
	v_cndmask_b32_e64 v34, v69, v34, s[0:1]
	v_mov_b32_dpp v39, v35 row_ror:8 row_mask:0xf bank_mask:0xf
	v_cndmask_b32_e64 v35, v70, v35, s[0:1]
	v_cndmask_b32_e64 v33, v67, v33, s[0:1]
	v_cndmask_b32_e64 v32, v66, v32, s[0:1]
	v_cndmask_b32_e64 v38, v36, v38, s[0:1]
	v_cndmask_b32_e64 v39, v37, v39, s[0:1]
	v_cndmask_b32_e64 v37, v51, v68, s[0:1]
	v_cndmask_b32_e64 v36, v50, v65, s[0:1]
	global_store_dwordx4 v[52:53], v[32:35], off offset:128
	global_store_dwordx4 v[48:49], v[36:39], off offset:128
	s_waitcnt vmcnt(4)
; __device__ __forceinline__ float bflo(unsigned w) { return __uint_as_float(w << 16); }
; __device__ __forceinline__ float bfhi(unsigned w) { return __uint_as_float(w & 0xffff0000u); }
; __device__ __forceinline__ unsigned dpp_ror8(unsigned x) { return (unsigned)__builtin_amdgcn_update_dpp(0, (int)x, 0x128, 0xf, 0xf, false); }
;     __device__ __forceinline__ void operator()(const f32x4 (&acc)[2][2][4][2], const Unit& u, int wr, int wc, int fr, int fq) const {
;     ...
;         for (int ai = 0; ai < 2; ++ai)
; #pragma unroll
;             for (int m = 0; m < 4; ++m) { const int row = row0 + ai * HALF + m * 16; const float ri = __builtin_amdgcn_rsqf(sse[row] * (1.f / D) + EPS);
;                 u32x4 rr[2], ee[2]; load_pair_lines(R, D, row, fr, col0, rr[0], rr[1], 32); load_pair_lines(E, D, row, fr, col0, ee[0], ee[1], 32);
;                 float* orow = OUT + (size_t)(row - fr + (fr & 7)) * D + col0 + (lo ? 0 : 4);
; #pragma unroll
;                 for (int bj = 0; bj < 2; ++bj) { const u32x4 rw = rr[bj], ew = ee[bj];
;                     const float r[8] = {bflo(rw.x), bfhi(rw.x), bflo(rw.y), bfhi(rw.y), bflo(rw.z), bfhi(rw.z), bflo(rw.w), bfhi(rw.w)};
;                     const float e[8] = {bflo(ew.x), bfhi(ew.x), bflo(ew.y), bfhi(ew.y), bflo(ew.z), bfhi(ew.z), bflo(ew.w), bfhi(ew.w)};
;                     float o[8];
; #pragma unroll
;                     for (int j = 0; j < 8; ++j) { const float a = acc[ai][bj][m][j >> 2][j & 3]; const float gg = gv[bj][j >> 2][j & 3];
;                         o[j] = r[j] + e[j] * ri * gg * __builtin_amdgcn_rcpf(1.f + __builtin_amdgcn_exp2f(-a * LOG2E)); }
;                     f32x4 o1, o2;
; #pragma unroll
;                     for (int j = 0; j < 4; ++j) { const unsigned a = __float_as_uint(o[j]), b = __float_as_uint(o[4 + j]); const unsigned sa = dpp_ror8(a), sb = dpp_ror8(b);
;                         o1[j] = __uint_as_float(lo ? a : sb); o2[j] = __uint_as_float(lo ? sa : b); }
;                     *(f32x4*)(orow + 32 * bj) = o1; *(f32x4*)(orow + (size_t)8 * D + 32 * bj) = o2; } }
	s_nop 0
	v_mov_b32_e32 v68, v228
	v_mov_b32_e32 v73, v157
	v_add_u32_e32 v38, 0xa0, v81
	v_ashrrev_i32_e32 v39, 31, v38
	v_lshlrev_b64 v[32:33], 12, v[38:39]
	v_lshl_add_u64 v[64:65], v[32:33], 0, s[16:17]
	v_lshl_add_u64 v[48:49], s[8:9], 0, v[64:65]
	v_lshl_add_u64 v[34:35], s[8:9], 0, v[32:33]
	v_lshl_add_u64 v[48:49], v[48:49], 0, v[164:165]
	v_lshl_add_u64 v[32:33], s[10:11], 0, v[32:33]
	v_lshl_add_u64 v[34:35], v[34:35], 0, v[164:165]
	v_mov_b64_e32 v[48:49], v[232:233]
	v_mov_b64_e32 v[50:51], v[234:235]
	v_lshl_add_u64 v[32:33], v[32:33], 0, v[164:165]
	v_mov_b64_e32 v[34:35], v[236:237]
	v_mov_b64_e32 v[36:37], v[238:239]
	v_mov_b32_e32 v74, v157
	v_mov_b64_e32 v[52:53], v[240:241]
	v_mov_b64_e32 v[54:55], v[242:243]
	v_lshl_add_u64 v[32:33], s[10:11], 0, v[64:65]
	v_lshl_add_u64 v[32:33], v[32:33], 0, v[164:165]
	v_mov_b64_e32 v[64:65], v[244:245]
	v_mov_b64_e32 v[66:67], v[246:247]
	s_nop 1
	v_add_u32_e32 v224, 0xb0, v81
	v_ashrrev_i32_e32 v225, 31, v224
	global_load_dword v228, v[168:169], off offset:704
	v_lshlrev_b64 v[216:217], 12, v[224:225]
	v_lshl_add_u64 v[222:223], v[216:217], 0, s[16:17]
	v_lshl_add_u64 v[220:221], s[8:9], 0, v[222:223]
	v_lshl_add_u64 v[218:219], s[8:9], 0, v[216:217]
	v_lshl_add_u64 v[220:221], v[220:221], 0, v[164:165]
	v_lshl_add_u64 v[216:217], s[10:11], 0, v[216:217]
	v_lshl_add_u64 v[218:219], v[218:219], 0, v[164:165]
	global_load_dwordx4 v[232:235], v[220:221], off
	v_lshl_add_u64 v[216:217], v[216:217], 0, v[164:165]
	global_load_dwordx4 v[236:239], v[218:219], off
	global_load_dwordx4 v[240:243], v[216:217], off
	v_lshl_add_u64 v[216:217], s[10:11], 0, v[222:223]
	v_lshl_add_u64 v[216:217], v[216:217], 0, v[164:165]
	global_load_dwordx4 v[244:247], v[216:217], off
	v_mov_b32_e32 v69, v157
	v_mov_b32_e32 v70, v157
	v_mov_b32_e32 v71, v157
	v_mov_b32_e32 v72, v157
	v_mov_b32_e32 v33, v157
	v_add_f32_e32 v16, 1.0, v16
	v_add_f32_e32 v17, 1.0, v17
	v_rcp_f32_e32 v16, v16
	v_rcp_f32_e32 v17, v17
	v_mul_f32_e32 v18, 0xbfb8aa3b, v18
	v_mul_f32_e32 v19, 0xbfb8aa3b, v19
	v_add_f32_e32 v20, 1.0, v20
	v_add_f32_e32 v21, 1.0, v21
	v_exp_f32_e32 v18, v18
	v_exp_f32_e32 v19, v19
	v_rcp_f32_e32 v20, v20
	v_rcp_f32_e32 v21, v21
	v_mul_f32_e32 v22, 0xbfb8aa3b, v22
	v_mul_f32_e32 v23, 0xbfb8aa3b, v23
	v_exp_f32_e32 v22, v22
	v_exp_f32_e32 v23, v23
	v_add_f32_e32 v18, 1.0, v18
	v_add_f32_e32 v19, 1.0, v19
	v_rcp_f32_e32 v18, v18
	v_rcp_f32_e32 v19, v19
	v_add_f32_e32 v22, 1.0, v22
	v_add_f32_e32 v23, 1.0, v23
	v_rcp_f32_e32 v22, v22
	v_rcp_f32_e32 v23, v23
	v_mul_f32_e32 v8, 0xbfb8aa3b, v8
	v_mul_f32_e32 v9, 0xbfb8aa3b, v9
	v_mul_f32_e32 v12, 0xbfb8aa3b, v12
	v_exp_f32_e32 v8, v8
	v_exp_f32_e32 v9, v9
	v_mul_f32_e32 v10, 0xbfb8aa3b, v10
	v_mul_f32_e32 v11, 0xbfb8aa3b, v11
	v_add_f32_e32 v8, 1.0, v8
	v_add_f32_e32 v9, 1.0, v9
	v_rcp_f32_e32 v8, v8
	v_rcp_f32_e32 v9, v9
	v_exp_f32_e32 v10, v10
	v_exp_f32_e32 v11, v11
	v_mul_f32_e32 v14, 0xbfb8aa3b, v14
	v_mul_f32_e32 v15, 0xbfb8aa3b, v15
	v_exp_f32_e32 v14, v14
	v_exp_f32_e32 v15, v15
	v_add_f32_e32 v10, 1.0, v10
	v_add_f32_e32 v11, 1.0, v11
	v_rcp_f32_e32 v10, v10
	v_rcp_f32_e32 v11, v11
	v_add_f32_e32 v14, 1.0, v14
	v_add_f32_e32 v15, 1.0, v15
	v_mul_f32_e32 v0, 0xbfb8aa3b, v0
	v_mul_f32_e32 v1, 0xbfb8aa3b, v1
	v_rcp_f32_e32 v14, v14
	v_rcp_f32_e32 v15, v15
	v_exp_f32_e32 v0, v0
	v_exp_f32_e32 v1, v1
	v_mul_f32_e32 v4, 0xbfb8aa3b, v4
	v_mul_f32_e32 v5, 0xbfb8aa3b, v5
	v_exp_f32_e32 v4, v4
	v_fmamk_f32 v32, v68, 0x3a000000, v182
	v_mov_b32_e32 v68, v157
	v_rsq_f32_e32 v32, v32
	v_exp_f32_e32 v5, v5
	v_add_f32_e32 v0, 1.0, v0
	v_add_f32_e32 v1, 1.0, v1
	v_rcp_f32_e32 v0, v0
	v_rcp_f32_e32 v1, v1
	v_mul_f32_e32 v2, 0xbfb8aa3b, v2
	v_mul_f32_e32 v3, 0xbfb8aa3b, v3
	v_add_f32_e32 v4, 1.0, v4
	v_mov_b32_dpp v73, v50 row_ror:8 row_mask:0xf bank_mask:0xf
	v_mov_b32_dpp v74, v51 row_ror:8 row_mask:0xf bank_mask:0xf
	v_mov_b32_dpp v69, v36 row_ror:8 row_mask:0xf bank_mask:0xf
	v_mov_b32_dpp v70, v37 row_ror:8 row_mask:0xf bank_mask:0xf
	v_mov_b32_dpp v71, v48 row_ror:8 row_mask:0xf bank_mask:0xf
	v_mov_b32_dpp v72, v49 row_ror:8 row_mask:0xf bank_mask:0xf
	v_cndmask_b32_e64 v74, v74, v37, s[0:1]
	v_cndmask_b32_e64 v37, v73, v36, s[0:1]
	v_mov_b32_e32 v36, v157
	v_mov_b32_dpp v33, v34 row_ror:8 row_mask:0xf bank_mask:0xf
	v_mov_b32_dpp v68, v35 row_ror:8 row_mask:0xf bank_mask:0xf
	v_cndmask_b32_e64 v72, v72, v35, s[0:1]
	v_cndmask_b32_e64 v71, v71, v34, s[0:1]
	v_cndmask_b32_e64 v51, v51, v70, s[0:1]
	v_mov_b32_e32 v34, v157
	v_mov_b32_e32 v35, v157
	v_mov_b32_dpp v36, v54 row_ror:8 row_mask:0xf bank_mask:0xf
	v_mov_b32_e32 v70, v157
	v_cndmask_b32_e64 v49, v49, v68, s[0:1]
	v_cndmask_b32_e64 v33, v48, v33, s[0:1]
	v_cndmask_b32_e64 v48, v50, v69, s[0:1]
	v_mov_b32_dpp v34, v52 row_ror:8 row_mask:0xf bank_mask:0xf
	v_mov_b32_dpp v35, v53 row_ror:8 row_mask:0xf bank_mask:0xf
	v_mov_b32_e32 v68, v157
	v_mov_b32_e32 v69, v157
	v_mov_b32_dpp v70, v66 row_ror:8 row_mask:0xf bank_mask:0xf
	v_cndmask_b32_e64 v66, v66, v36, s[0:1]
	v_exp_f32_e32 v36, v28
	v_mul_f32_e32 v28, 0xbfb8aa3b, v29
	v_mov_b32_dpp v68, v64 row_ror:8 row_mask:0xf bank_mask:0xf
	v_mov_b32_dpp v69, v65 row_ror:8 row_mask:0xf bank_mask:0xf
	v_cndmask_b32_e64 v65, v65, v35, s[0:1]
	v_cndmask_b32_e64 v64, v64, v34, s[0:1]
	v_lshlrev_b64 v[34:35], 13, v[38:39]
	v_exp_f32_e32 v38, v28
	v_lshl_add_u64 v[34:35], s[4:5], 0, v[34:35]
	v_cndmask_b32_e64 v54, v70, v54, s[0:1]
	v_lshl_add_u64 v[34:35], v[34:35], 0, v[166:167]
	v_lshl_add_u64 v[28:29], v[34:35], 0, v[156:157]
	v_add_f32_e32 v35, 1.0, v38
	v_lshlrev_b32_e32 v38, 16, v54
	v_and_b32_e32 v39, 0xffff0000, v54
	v_add_f32_e32 v34, 1.0, v36
; __device__ __forceinline__ float bflo(unsigned w) { return __uint_as_float(w << 16); }
; __device__ __forceinline__ float bfhi(unsigned w) { return __uint_as_float(w & 0xffff0000u); }
; __device__ __forceinline__ unsigned dpp_ror8(unsigned x) { return (unsigned)__builtin_amdgcn_update_dpp(0, (int)x, 0x128, 0xf, 0xf, false); }
;     __device__ __forceinline__ void operator()(const f32x4 (&acc)[2][2][4][2], const Unit& u, int wr, int wc, int fr, int fq) const {
;     ...
;         for (int ai = 0; ai < 2; ++ai)
; #pragma unroll
;             for (int m = 0; m < 4; ++m) { const int row = row0 + ai * HALF + m * 16; const float ri = __builtin_amdgcn_rsqf(sse[row] * (1.f / D) + EPS);
;                 u32x4 rr[2], ee[2]; load_pair_lines(R, D, row, fr, col0, rr[0], rr[1], 32); load_pair_lines(E, D, row, fr, col0, ee[0], ee[1], 32);
;                 float* orow = OUT + (size_t)(row - fr + (fr & 7)) * D + col0 + (lo ? 0 : 4);
; #pragma unroll
;                 for (int bj = 0; bj < 2; ++bj) { const u32x4 rw = rr[bj], ew = ee[bj];
;                     const float r[8] = {bflo(rw.x), bfhi(rw.x), bflo(rw.y), bfhi(rw.y), bflo(rw.z), bfhi(rw.z), bflo(rw.w), bfhi(rw.w)};
;                     const float e[8] = {bflo(ew.x), bfhi(ew.x), bflo(ew.y), bfhi(ew.y), bflo(ew.z), bfhi(ew.z), bflo(ew.w), bfhi(ew.w)};
;                     float o[8];
; #pragma unroll
;                     for (int j = 0; j < 8; ++j) { const float a = acc[ai][bj][m][j >> 2][j & 3]; const float gg = gv[bj][j >> 2][j & 3];
;                         o[j] = r[j] + e[j] * ri * gg * __builtin_amdgcn_rcpf(1.f + __builtin_amdgcn_exp2f(-a * LOG2E)); }
;                     f32x4 o1, o2;
; #pragma unroll
;                     for (int j = 0; j < 4; ++j) { const unsigned a = __float_as_uint(o[j]), b = __float_as_uint(o[4 + j]); const unsigned sa = dpp_ror8(a), sb = dpp_ror8(b);
;                         o1[j] = __uint_as_float(lo ? a : sb); o2[j] = __uint_as_float(lo ? sa : b); }
;                     *(f32x4*)(orow + 32 * bj) = o1; *(f32x4*)(orow + (size_t)8 * D + 32 * bj) = o2; } }
	v_pk_mul_f32 v[38:39], v[32:33], v[38:39] op_sel_hi:[0,1]
	v_cndmask_b32_e64 v52, v68, v52, s[0:1]
	v_rcp_f32_e32 v34, v34
	v_rcp_f32_e32 v35, v35
	v_lshlrev_b32_e32 v36, 16, v37
	v_and_b32_e32 v37, 0xffff0000, v37
	v_pk_mul_f32 v[38:39], v[60:61], v[38:39]
	v_mov_b32_e32 v73, v157
	v_pk_fma_f32 v[38:39], v[24:25], v[38:39], v[36:37]
	v_lshlrev_b32_e32 v36, 16, v52
	v_and_b32_e32 v37, 0xffff0000, v52
	v_mov_b32_e32 v50, v157
	v_mov_b32_dpp v73, v67 row_ror:8 row_mask:0xf bank_mask:0xf
	v_pk_mul_f32 v[36:37], v[32:33], v[36:37] op_sel_hi:[0,1]
	v_mov_b32_dpp v50, v55 row_ror:8 row_mask:0xf bank_mask:0xf
	v_cndmask_b32_e64 v55, v73, v55, s[0:1]
	v_lshlrev_b32_e32 v24, 16, v71
	v_and_b32_e32 v25, 0xffff0000, v71
	v_pk_mul_f32 v[36:37], v[56:57], v[36:37]
	v_cndmask_b32_e64 v53, v69, v53, s[0:1]
	v_pk_fma_f32 v[24:25], v[34:35], v[36:37], v[24:25]
	v_lshlrev_b32_e32 v36, 16, v55
	v_and_b32_e32 v37, 0xffff0000, v55
	v_pk_mul_f32 v[36:37], v[32:33], v[36:37] op_sel_hi:[0,1]
	v_lshlrev_b32_e32 v34, 16, v74
	v_and_b32_e32 v35, 0xffff0000, v74
	v_pk_mul_f32 v[36:37], v[62:63], v[36:37]
	v_cndmask_b32_e64 v50, v67, v50, s[0:1]
	v_pk_fma_f32 v[34:35], v[26:27], v[36:37], v[34:35]
	v_lshlrev_b32_e32 v36, 16, v53
	v_and_b32_e32 v37, 0xffff0000, v53
	v_pk_mul_f32 v[36:37], v[32:33], v[36:37] op_sel_hi:[0,1]
	v_lshlrev_b32_e32 v26, 16, v72
	v_and_b32_e32 v27, 0xffff0000, v72
	v_pk_mul_f32 v[36:37], v[58:59], v[36:37]
	v_mov_b32_e32 v54, v157
	v_pk_fma_f32 v[26:27], v[30:31], v[36:37], v[26:27]
	v_mov_b32_e32 v30, v157
	v_mov_b32_e32 v31, v157
	v_mov_b32_e32 v67, v157
	v_mov_b32_e32 v55, v157
	v_mov_b32_e32 v69, v157
	v_mov_b32_dpp v30, v26 row_ror:8 row_mask:0xf bank_mask:0xf
	v_mov_b32_dpp v31, v27 row_ror:8 row_mask:0xf bank_mask:0xf
	v_mov_b32_dpp v54, v38 row_ror:8 row_mask:0xf bank_mask:0xf
	v_mov_b32_dpp v67, v39 row_ror:8 row_mask:0xf bank_mask:0xf
	v_mov_b32_e32 v52, v157
	v_mov_b32_e32 v68, v157
	v_mov_b32_dpp v55, v34 row_ror:8 row_mask:0xf bank_mask:0xf
	v_mov_b32_dpp v69, v35 row_ror:8 row_mask:0xf bank_mask:0xf
	v_cndmask_b32_e64 v37, v35, v31, s[0:1]
	v_cndmask_b32_e64 v36, v34, v30, s[0:1]
	v_lshlrev_b32_e32 v30, 16, v66
	v_and_b32_e32 v31, 0xffff0000, v66
	v_mov_b32_dpp v52, v24 row_ror:8 row_mask:0xf bank_mask:0xf
	v_mov_b32_dpp v68, v25 row_ror:8 row_mask:0xf bank_mask:0xf
	v_cndmask_b32_e64 v27, v69, v27, s[0:1]
	v_cndmask_b32_e64 v26, v55, v26, s[0:1]
	v_cndmask_b32_e64 v25, v67, v25, s[0:1]
	v_cndmask_b32_e64 v24, v54, v24, s[0:1]
	v_pk_mul_f32 v[30:31], v[32:33], v[30:31] op_sel_hi:[0,1]
	global_store_dwordx4 v[28:29], v[24:27], off
	v_pk_mul_f32 v[30:31], v[44:45], v[30:31]
	v_cndmask_b32_e64 v35, v39, v68, s[0:1]
	v_lshlrev_b32_e32 v26, 16, v48
	v_and_b32_e32 v27, 0xffff0000, v48
	v_pk_fma_f32 v[26:27], v[16:17], v[30:31], v[26:27]
	v_lshlrev_b32_e32 v30, 16, v64
	v_and_b32_e32 v31, 0xffff0000, v64
	v_pk_mul_f32 v[30:31], v[32:33], v[30:31] op_sel_hi:[0,1]
	v_lshlrev_b32_e32 v16, 16, v33
	v_and_b32_e32 v17, 0xffff0000, v33
	v_pk_mul_f32 v[30:31], v[40:41], v[30:31]
	v_mov_b32_e32 v33, v157
	v_pk_fma_f32 v[16:17], v[20:21], v[30:31], v[16:17]
	v_lshlrev_b32_e32 v30, 16, v50
	v_and_b32_e32 v31, 0xffff0000, v50
	v_mov_b32_dpp v33, v16 row_ror:8 row_mask:0xf bank_mask:0xf
	v_pk_mul_f32 v[30:31], v[32:33], v[30:31] op_sel_hi:[0,1]
	v_add_co_u32_e32 v24, vcc, s45, v28
	v_lshlrev_b32_e32 v20, 16, v51
	v_and_b32_e32 v21, 0xffff0000, v51
	v_pk_mul_f32 v[30:31], v[46:47], v[30:31]
	v_cndmask_b32_e64 v34, v38, v52, s[0:1]
	v_addc_co_u32_e32 v25, vcc, 0, v29, vcc
	v_pk_fma_f32 v[20:21], v[18:19], v[30:31], v[20:21]
	v_lshlrev_b32_e32 v30, 16, v65
	v_and_b32_e32 v31, 0xffff0000, v65
	global_store_dwordx4 v[24:25], v[34:37], off
	v_pk_mul_f32 v[30:31], v[32:33], v[30:31] op_sel_hi:[0,1]
	v_mov_b32_e32 v38, v157
	v_mov_b32_e32 v34, v157
	v_mov_b32_e32 v35, v157
	v_mov_b32_e32 v37, v157
	v_mov_b32_dpp v34, v26 row_ror:8 row_mask:0xf bank_mask:0xf
	v_lshlrev_b32_e32 v18, 16, v49
	v_and_b32_e32 v19, 0xffff0000, v49
	v_pk_mul_f32 v[30:31], v[42:43], v[30:31]
	v_mov_b32_dpp v35, v27 row_ror:8 row_mask:0xf bank_mask:0xf
	v_mov_b32_e32 v36, v157
	v_mov_b32_dpp v37, v20 row_ror:8 row_mask:0xf bank_mask:0xf
	v_mov_b32_dpp v38, v21 row_ror:8 row_mask:0xf bank_mask:0xf
	v_pk_fma_f32 v[18:19], v[22:23], v[30:31], v[18:19]
	v_mov_b32_e32 v22, v157
	v_mov_b32_e32 v23, v157
	v_cndmask_b32_e64 v16, v34, v16, s[0:1]
	v_add_u32_e32 v34, 0xb0, v81
	v_mov_b32_dpp v36, v17 row_ror:8 row_mask:0xf bank_mask:0xf
	v_mov_b32_dpp v22, v18 row_ror:8 row_mask:0xf bank_mask:0xf
	v_mov_b32_dpp v23, v19 row_ror:8 row_mask:0xf bank_mask:0xf
	v_cndmask_b32_e64 v19, v38, v19, s[0:1]
	v_cndmask_b32_e64 v18, v37, v18, s[0:1]
	v_cndmask_b32_e64 v17, v35, v17, s[0:1]
	v_ashrrev_i32_e32 v35, 31, v34
	v_cndmask_b32_e64 v23, v21, v23, s[0:1]
	v_cndmask_b32_e64 v22, v20, v22, s[0:1]
	v_cndmask_b32_e64 v21, v27, v36, s[0:1]
	v_cndmask_b32_e64 v20, v26, v33, s[0:1]
	global_store_dwordx4 v[28:29], v[16:19], off offset:128
	global_store_dwordx4 v[24:25], v[20:23], off offset:128
	s_waitcnt vmcnt(4)
; __device__ __forceinline__ float bflo(unsigned w) { return __uint_as_float(w << 16); }
; __device__ __forceinline__ float bfhi(unsigned w) { return __uint_as_float(w & 0xffff0000u); }
; __device__ __forceinline__ unsigned dpp_ror8(unsigned x) { return (unsigned)__builtin_amdgcn_update_dpp(0, (int)x, 0x128, 0xf, 0xf, false); }
;     __device__ __forceinline__ void operator()(const f32x4 (&acc)[2][2][4][2], const Unit& u, int wr, int wc, int fr, int fq) const {
;     ...
;         for (int ai = 0; ai < 2; ++ai)
; #pragma unroll
;             for (int m = 0; m < 4; ++m) { const int row = row0 + ai * HALF + m * 16; const float ri = __builtin_amdgcn_rsqf(sse[row] * (1.f / D) + EPS);
;                 u32x4 rr[2], ee[2]; load_pair_lines(R, D, row, fr, col0, rr[0], rr[1], 32); load_pair_lines(E, D, row, fr, col0, ee[0], ee[1], 32);
;                 float* orow = OUT + (size_t)(row - fr + (fr & 7)) * D + col0 + (lo ? 0 : 4);
; #pragma unroll
;                 for (int bj = 0; bj < 2; ++bj) { const u32x4 rw = rr[bj], ew = ee[bj];
;                     const float r[8] = {bflo(rw.x), bfhi(rw.x), bflo(rw.y), bfhi(rw.y), bflo(rw.z), bfhi(rw.z), bflo(rw.w), bfhi(rw.w)};
;                     const float e[8] = {bflo(ew.x), bfhi(ew.x), bflo(ew.y), bfhi(ew.y), bflo(ew.z), bfhi(ew.z), bflo(ew.w), bfhi(ew.w)};
;                     float o[8];
; #pragma unroll
;                     for (int j = 0; j < 8; ++j) { const float a = acc[ai][bj][m][j >> 2][j & 3]; const float gg = gv[bj][j >> 2][j & 3];
;                         o[j] = r[j] + e[j] * ri * gg * __builtin_amdgcn_rcpf(1.f + __builtin_amdgcn_exp2f(-a * LOG2E)); }
;                     f32x4 o1, o2;
; #pragma unroll
;                     for (int j = 0; j < 4; ++j) { const unsigned a = __float_as_uint(o[j]), b = __float_as_uint(o[4 + j]); const unsigned sa = dpp_ror8(a), sb = dpp_ror8(b);
;                         o1[j] = __uint_as_float(lo ? a : sb); o2[j] = __uint_as_float(lo ? sa : b); }
;                     *(f32x4*)(orow + 32 * bj) = o1; *(f32x4*)(orow + (size_t)8 * D + 32 * bj) = o2; } }
; template <class Epi>
; __device__ __forceinline__ void gemm_phase(LAS unsigned char* lds, const Gemm g, const StaticOrder& S, const Epi& E) {
;     ...
;         cur = nxt; cA = nA; cB = nB; ++ui;
	s_nop 0
	v_mov_b32_e32 v36, v228
	v_lshlrev_b64 v[16:17], 12, v[34:35]
	v_lshl_add_u64 v[30:31], v[16:17], 0, s[16:17]
	v_lshl_add_u64 v[22:23], s[8:9], 0, v[30:31]
	v_lshl_add_u64 v[18:19], s[8:9], 0, v[16:17]
	v_lshl_add_u64 v[22:23], v[22:23], 0, v[164:165]
	v_lshl_add_u64 v[16:17], s[10:11], 0, v[16:17]
	v_lshl_add_u64 v[18:19], v[18:19], 0, v[164:165]
	v_mov_b64_e32 v[22:23], v[232:233]
	v_mov_b64_e32 v[24:25], v[234:235]
	v_lshl_add_u64 v[16:17], v[16:17], 0, v[164:165]
	v_mov_b64_e32 v[18:19], v[236:237]
	v_mov_b64_e32 v[20:21], v[238:239]
	v_mov_b32_e32 v49, v157
	v_mov_b64_e32 v[26:27], v[240:241]
	v_mov_b64_e32 v[28:29], v[242:243]
	v_lshl_add_u64 v[16:17], s[10:11], 0, v[30:31]
	v_lshl_add_u64 v[16:17], v[16:17], 0, v[164:165]
	v_mov_b64_e32 v[30:31], v[244:245]
	v_mov_b64_e32 v[32:33], v[246:247]
	s_nop 1
	v_mov_b32_e32 v50, v157
	v_mov_b32_e32 v17, v157
	v_mov_b32_e32 v37, v157
	v_mov_b32_e32 v38, v157
	v_mov_b32_e32 v48, v157
	v_mov_b32_e32 v39, v157
	v_add_f32_e32 v5, 1.0, v5
	v_exp_f32_e32 v2, v2
	v_exp_f32_e32 v3, v3
	v_rcp_f32_e32 v4, v4
	v_rcp_f32_e32 v5, v5
	v_mul_f32_e32 v6, 0xbfb8aa3b, v6
	v_mul_f32_e32 v7, 0xbfb8aa3b, v7
	v_exp_f32_e32 v6, v6
	v_exp_f32_e32 v7, v7
	v_add_f32_e32 v2, 1.0, v2
	v_add_f32_e32 v3, 1.0, v3
	v_rcp_f32_e32 v2, v2
	v_rcp_f32_e32 v3, v3
	v_add_f32_e32 v6, 1.0, v6
	v_add_f32_e32 v7, 1.0, v7
	v_rcp_f32_e32 v6, v6
	v_rcp_f32_e32 v7, v7
	s_mov_b32 s53, s18
	s_mov_b32 s30, s22
	s_mov_b64 s[36:37], s[28:29]
	s_mov_b64 s[34:35], s[24:25]
	v_fmamk_f32 v16, v36, 0x3a000000, v182
	v_mov_b32_e32 v36, v157
	v_rsq_f32_e32 v16, v16
	v_mov_b32_dpp v49, v24 row_ror:8 row_mask:0xf bank_mask:0xf
	v_mov_b32_dpp v50, v25 row_ror:8 row_mask:0xf bank_mask:0xf
	v_mov_b32_dpp v17, v18 row_ror:8 row_mask:0xf bank_mask:0xf
	v_mov_b32_dpp v36, v19 row_ror:8 row_mask:0xf bank_mask:0xf
	v_mov_b32_dpp v37, v20 row_ror:8 row_mask:0xf bank_mask:0xf
	v_mov_b32_dpp v38, v21 row_ror:8 row_mask:0xf bank_mask:0xf
	v_mov_b32_dpp v48, v23 row_ror:8 row_mask:0xf bank_mask:0xf
	v_cndmask_b32_e64 v50, v50, v21, s[0:1]
	v_cndmask_b32_e64 v21, v49, v20, s[0:1]
	v_mov_b32_e32 v20, v157
	v_mov_b32_dpp v39, v22 row_ror:8 row_mask:0xf bank_mask:0xf
	v_cndmask_b32_e64 v48, v48, v19, s[0:1]
	v_cndmask_b32_e64 v36, v23, v36, s[0:1]
	v_cndmask_b32_e64 v25, v25, v38, s[0:1]
	v_cndmask_b32_e64 v17, v22, v17, s[0:1]
	v_mov_b32_e32 v19, v157
	v_mov_b32_dpp v20, v28 row_ror:8 row_mask:0xf bank_mask:0xf
	v_mov_b32_e32 v22, v157
	v_mov_b32_e32 v23, v157
	v_mov_b32_e32 v38, v157
	v_cndmask_b32_e64 v39, v39, v18, s[0:1]
	v_cndmask_b32_e64 v24, v24, v37, s[0:1]
	v_mov_b32_e32 v18, v157
	v_mov_b32_dpp v19, v27 row_ror:8 row_mask:0xf bank_mask:0xf
	v_mov_b32_dpp v22, v29 row_ror:8 row_mask:0xf bank_mask:0xf
	v_mov_b32_dpp v23, v30 row_ror:8 row_mask:0xf bank_mask:0xf
	v_mov_b32_e32 v37, v157
	v_mov_b32_dpp v38, v32 row_ror:8 row_mask:0xf bank_mask:0xf
	v_cndmask_b32_e64 v32, v32, v20, s[0:1]
	v_exp_f32_e32 v20, v12
	v_mul_f32_e32 v12, 0xbfb8aa3b, v13
	v_mov_b32_dpp v18, v26 row_ror:8 row_mask:0xf bank_mask:0xf
	v_mov_b32_dpp v37, v31 row_ror:8 row_mask:0xf bank_mask:0xf
	v_cndmask_b32_e64 v26, v23, v26, s[0:1]
	v_cndmask_b32_e64 v23, v38, v28, s[0:1]
	v_cndmask_b32_e64 v28, v31, v19, s[0:1]
	v_cndmask_b32_e64 v31, v33, v22, s[0:1]
	v_exp_f32_e32 v22, v12
	v_cndmask_b32_e64 v30, v30, v18, s[0:1]
	v_lshlrev_b64 v[18:19], 13, v[34:35]
	v_lshl_add_u64 v[18:19], s[4:5], 0, v[18:19]
	v_lshl_add_u64 v[18:19], v[18:19], 0, v[166:167]
	v_lshl_add_u64 v[12:13], v[18:19], 0, v[156:157]
	v_add_f32_e32 v19, 1.0, v22
	v_lshlrev_b32_e32 v22, 16, v23
	v_and_b32_e32 v23, 0xffff0000, v23
	v_add_f32_e32 v18, 1.0, v20
	v_pk_mul_f32 v[22:23], v[16:17], v[22:23] op_sel_hi:[0,1]
	v_rcp_f32_e32 v18, v18
	v_rcp_f32_e32 v19, v19
	v_lshlrev_b32_e32 v20, 16, v21
	v_and_b32_e32 v21, 0xffff0000, v21
	v_pk_mul_f32 v[22:23], v[60:61], v[22:23]
	v_mov_b32_e32 v49, v157
	v_pk_fma_f32 v[22:23], v[8:9], v[22:23], v[20:21]
	v_lshlrev_b32_e32 v20, 16, v26
	v_and_b32_e32 v21, 0xffff0000, v26
	v_mov_b32_dpp v49, v33 row_ror:8 row_mask:0xf bank_mask:0xf
	v_pk_mul_f32 v[20:21], v[16:17], v[20:21] op_sel_hi:[0,1]
	v_cndmask_b32_e64 v29, v49, v29, s[0:1]
	v_lshlrev_b32_e32 v8, 16, v39
	v_and_b32_e32 v9, 0xffff0000, v39
; __device__ __forceinline__ float bflo(unsigned w) { return __uint_as_float(w << 16); }
; __device__ __forceinline__ float bfhi(unsigned w) { return __uint_as_float(w & 0xffff0000u); }
; __device__ __forceinline__ unsigned dpp_ror8(unsigned x) { return (unsigned)__builtin_amdgcn_update_dpp(0, (int)x, 0x128, 0xf, 0xf, false); }
; #define PG8_WAIT_V(n) asm volatile("s_waitcnt vmcnt(" #n ")" ::: "memory")
; #define PG8_BAR __builtin_amdgcn_s_barrier()
;     __device__ __forceinline__ void operator()(const f32x4 (&acc)[2][2][4][2], const Unit& u, int wr, int wc, int fr, int fq) const {
;     ...
;                 for (int bj = 0; bj < 2; ++bj) { const u32x4 rw = rr[bj], ew = ee[bj];
;                     const float r[8] = {bflo(rw.x), bfhi(rw.x), bflo(rw.y), bfhi(rw.y), bflo(rw.z), bfhi(rw.z), bflo(rw.w), bfhi(rw.w)};
;                     const float e[8] = {bflo(ew.x), bfhi(ew.x), bflo(ew.y), bfhi(ew.y), bflo(ew.z), bfhi(ew.z), bflo(ew.w), bfhi(ew.w)};
;                     float o[8];
; #pragma unroll
;                     for (int j = 0; j < 8; ++j) { const float a = acc[ai][bj][m][j >> 2][j & 3]; const float gg = gv[bj][j >> 2][j & 3];
;                         o[j] = r[j] + e[j] * ri * gg * __builtin_amdgcn_rcpf(1.f + __builtin_amdgcn_exp2f(-a * LOG2E)); }
;                     f32x4 o1, o2;
; #pragma unroll
;                     for (int j = 0; j < 4; ++j) { const unsigned a = __float_as_uint(o[j]), b = __float_as_uint(o[4 + j]); const unsigned sa = dpp_ror8(a), sb = dpp_ror8(b);
;                         o1[j] = __uint_as_float(lo ? a : sb); o2[j] = __uint_as_float(lo ? sa : b); }
;                     *(f32x4*)(orow + 32 * bj) = o1; *(f32x4*)(orow + (size_t)8 * D + 32 * bj) = o2; } }
; template <class Epi>
; __device__ __forceinline__ void gemm_phase(LAS unsigned char* lds, const Gemm g, const StaticOrder& S, const Epi& E) {
;     ...
;         if (!has_next) break;
; #pragma unroll
;         for (int a = 0; a < 2; ++a)
; #pragma unroll
;             for (int b = 0; b < 2; ++b)
; #pragma unroll
;                 for (int m = 0; m < 4; ++m)
; #pragma unroll
;                     for (int n = 0; n < 2; ++n) acc[a][b][m][n] = (f32x4){0.f, 0.f, 0.f, 0.f};
;         cur = nxt; cA = nA; cB = nB; ++ui;
;     }
;     PG8_WAIT_V(0);
;     if (wr == 0) PG8_BAR;
;     PG8_BAR;
	v_pk_mul_f32 v[20:21], v[56:57], v[20:21]
	v_cndmask_b32_e64 v27, v37, v27, s[0:1]
	v_pk_fma_f32 v[8:9], v[18:19], v[20:21], v[8:9]
	v_lshlrev_b32_e32 v20, 16, v29
	v_and_b32_e32 v21, 0xffff0000, v29
	v_pk_mul_f32 v[20:21], v[16:17], v[20:21] op_sel_hi:[0,1]
	v_lshlrev_b32_e32 v18, 16, v50
	v_and_b32_e32 v19, 0xffff0000, v50
	v_pk_mul_f32 v[20:21], v[62:63], v[20:21]
	v_mov_b32_e32 v33, v157
	v_pk_fma_f32 v[18:19], v[10:11], v[20:21], v[18:19]
	v_lshlrev_b32_e32 v20, 16, v27
	v_and_b32_e32 v21, 0xffff0000, v27
	v_pk_mul_f32 v[20:21], v[16:17], v[20:21] op_sel_hi:[0,1]
	v_lshlrev_b32_e32 v10, 16, v48
	v_and_b32_e32 v11, 0xffff0000, v48
	v_pk_mul_f32 v[20:21], v[58:59], v[20:21]
	v_mov_b32_e32 v34, v157
	v_pk_fma_f32 v[10:11], v[14:15], v[20:21], v[10:11]
	v_mov_b32_e32 v14, v157
	v_mov_b32_e32 v15, v157
	v_mov_b32_e32 v29, v157
	v_mov_b32_e32 v37, v157
	v_mov_b32_dpp v14, v10 row_ror:8 row_mask:0xf bank_mask:0xf
	v_mov_b32_dpp v15, v11 row_ror:8 row_mask:0xf bank_mask:0xf
	v_mov_b32_dpp v33, v22 row_ror:8 row_mask:0xf bank_mask:0xf
	v_mov_b32_dpp v34, v23 row_ror:8 row_mask:0xf bank_mask:0xf
	v_mov_b32_e32 v26, v157
	v_mov_b32_e32 v35, v157
	v_mov_b32_dpp v29, v18 row_ror:8 row_mask:0xf bank_mask:0xf
	v_mov_b32_dpp v37, v19 row_ror:8 row_mask:0xf bank_mask:0xf
	v_cndmask_b32_e64 v21, v19, v15, s[0:1]
	v_cndmask_b32_e64 v20, v18, v14, s[0:1]
	v_lshlrev_b32_e32 v14, 16, v32
	v_and_b32_e32 v15, 0xffff0000, v32
	v_mov_b32_dpp v26, v8 row_ror:8 row_mask:0xf bank_mask:0xf
	v_mov_b32_dpp v35, v9 row_ror:8 row_mask:0xf bank_mask:0xf
	v_cndmask_b32_e64 v11, v37, v11, s[0:1]
	v_cndmask_b32_e64 v10, v29, v10, s[0:1]
	v_cndmask_b32_e64 v9, v34, v9, s[0:1]
	v_cndmask_b32_e64 v8, v33, v8, s[0:1]
	v_pk_mul_f32 v[14:15], v[16:17], v[14:15] op_sel_hi:[0,1]
	global_store_dwordx4 v[12:13], v[8:11], off
	v_pk_mul_f32 v[14:15], v[44:45], v[14:15]
	v_cndmask_b32_e64 v19, v23, v35, s[0:1]
	v_lshlrev_b32_e32 v10, 16, v24
	v_and_b32_e32 v11, 0xffff0000, v24
	v_pk_fma_f32 v[10:11], v[0:1], v[14:15], v[10:11]
	v_lshlrev_b32_e32 v14, 16, v30
	v_and_b32_e32 v15, 0xffff0000, v30
	v_pk_mul_f32 v[14:15], v[16:17], v[14:15] op_sel_hi:[0,1]
	v_lshlrev_b32_e32 v0, 16, v17
	v_and_b32_e32 v1, 0xffff0000, v17
	v_pk_mul_f32 v[14:15], v[40:41], v[14:15]
	v_mov_b32_e32 v17, v157
	v_pk_fma_f32 v[0:1], v[4:5], v[14:15], v[0:1]
	v_lshlrev_b32_e32 v14, 16, v31
	v_and_b32_e32 v15, 0xffff0000, v31
	v_mov_b32_dpp v17, v0 row_ror:8 row_mask:0xf bank_mask:0xf
	v_pk_mul_f32 v[14:15], v[16:17], v[14:15] op_sel_hi:[0,1]
	v_lshlrev_b32_e32 v4, 16, v25
	v_and_b32_e32 v5, 0xffff0000, v25
	v_pk_mul_f32 v[14:15], v[46:47], v[14:15]
	v_add_co_u32_e32 v8, vcc, s45, v12
	v_pk_fma_f32 v[4:5], v[2:3], v[14:15], v[4:5]
	v_lshlrev_b32_e32 v14, 16, v28
	v_and_b32_e32 v15, 0xffff0000, v28
	v_cndmask_b32_e64 v18, v22, v26, s[0:1]
	v_addc_co_u32_e32 v9, vcc, 0, v13, vcc
	v_pk_mul_f32 v[14:15], v[16:17], v[14:15] op_sel_hi:[0,1]
	global_store_dwordx4 v[8:9], v[18:21], off
	v_mov_b32_e32 v22, v157
	v_lshlrev_b32_e32 v2, 16, v36
	v_mov_b32_e32 v18, v157
	v_mov_b32_e32 v19, v157
	v_mov_b32_e32 v21, v157
	v_and_b32_e32 v3, 0xffff0000, v36
	v_pk_mul_f32 v[14:15], v[42:43], v[14:15]
	v_mov_b32_dpp v18, v10 row_ror:8 row_mask:0xf bank_mask:0xf
	v_mov_b32_dpp v19, v11 row_ror:8 row_mask:0xf bank_mask:0xf
	v_mov_b32_e32 v20, v157
	v_mov_b32_dpp v21, v4 row_ror:8 row_mask:0xf bank_mask:0xf
	v_mov_b32_dpp v22, v5 row_ror:8 row_mask:0xf bank_mask:0xf
	v_pk_fma_f32 v[2:3], v[6:7], v[14:15], v[2:3]
	v_mov_b32_e32 v6, v157
	v_mov_b32_e32 v7, v157
	v_mov_b32_dpp v20, v1 row_ror:8 row_mask:0xf bank_mask:0xf
	v_mov_b32_dpp v6, v2 row_ror:8 row_mask:0xf bank_mask:0xf
	v_mov_b32_dpp v7, v3 row_ror:8 row_mask:0xf bank_mask:0xf
	v_cndmask_b32_e64 v3, v22, v3, s[0:1]
	v_cndmask_b32_e64 v2, v21, v2, s[0:1]
	v_cndmask_b32_e64 v1, v19, v1, s[0:1]
	v_cndmask_b32_e64 v0, v18, v0, s[0:1]
	s_and_b64 vcc, exec, s[26:27]
	v_cndmask_b32_e64 v7, v5, v7, s[0:1]
	v_cndmask_b32_e64 v6, v4, v6, s[0:1]
	v_cndmask_b32_e64 v5, v11, v20, s[0:1]
	v_cndmask_b32_e64 v4, v10, v17, s[0:1]
	global_store_dwordx4 v[12:13], v[0:3], off offset:128
	global_store_dwordx4 v[8:9], v[4:7], off offset:128
	s_cbranch_vccz .LBB0_1595
	s_waitcnt vmcnt(0)
	s_cmpk_gt_u32 s3, 0xff
	s_cbranch_scc1 .LBB0_1607
	s_barrier
